# attention fast path: loop back edge rotated in front of the barrier for fast-to-fast tiles (latch, next-tile test and loop-top state decided before the barrier; after it the next slot's copy starts di
# speedup vs baseline: 1.0008x; 1.0008x over previous
.Latt_latchb_0:
	s_waitcnt lgkmcnt(0)
	s_cmp_eq_u32 s87, s43
	s_barrier
	s_cbranch_scc1 .LBB0_862

.Latt_vstep_0s0:
.Latt_cont_0s0:
	v_add_u32_e32 v205, 0xffff0000, v205
	v_add_u32_e32 v218, 0xffff0000, v218
	v_add_u32_e32 v219, 0xffff0000, v219
	v_add_u32_e32 v221, 0xffff0000, v221

.Latt_nr0_0s0:
	s_waitcnt lgkmcnt(3)
	v_mfma_f32_32x32x16_bf16 v[222:237], v[214:217], v[152:155], v[222:237]
	ds_read_b128 v[214:217], v200 offset:8192
	v_sub_f32_e32 v128, v128, v190
	v_exp_f32_e32 v128, v128
	v_sub_f32_e32 v129, v129, v190
	v_exp_f32_e32 v129, v129
	v_sub_f32_e32 v130, v130, v190
	s_waitcnt lgkmcnt(3)
	v_mfma_f32_32x32x16_bf16 v[222:237], v[238:241], v[156:159], v[222:237]
	ds_read_b128 v[238:241], v201 offset:8192
	v_add_f32_e32 v254, 0, v128
	v_exp_f32_e32 v130, v130
	v_sub_f32_e32 v131, v131, v190
	v_add_f32_e32 v254, v129, v254
	v_exp_f32_e32 v131, v131
	s_waitcnt lgkmcnt(3)
	v_mfma_f32_32x32x16_bf16 v[222:237], v[206:209], v[160:163], v[222:237]
	ds_read_b64_tr_b16 v[206:207], v205
	ds_read_b64_tr_b16 v[208:209], v205 offset:4096
	v_sub_f32_e32 v132, v132, v190
	v_add_f32_e32 v254, v130, v254
	v_exp_f32_e32 v132, v132
	v_sub_f32_e32 v133, v133, v190
	v_add_f32_e32 v254, v131, v254
	s_waitcnt lgkmcnt(4)
	v_mfma_f32_32x32x16_bf16 v[222:237], v[210:213], v[164:167], v[222:237]
	ds_read_b64_tr_b16 v[210:211], v218
	ds_read_b64_tr_b16 v[212:213], v218 offset:4096
	v_exp_f32_e32 v133, v133
	v_sub_f32_e32 v134, v134, v190
	v_add_f32_e32 v254, v132, v254
	v_exp_f32_e32 v134, v134
	s_waitcnt lgkmcnt(5)
	v_mfma_f32_32x32x16_bf16 v[222:237], v[214:217], v[168:171], v[222:237]
	ds_read_b64_tr_b16 v[214:215], v219
	ds_read_b64_tr_b16 v[216:217], v219 offset:4096
	v_sub_f32_e32 v135, v135, v190
	v_add_f32_e32 v254, v133, v254
	v_exp_f32_e32 v135, v135
	s_nop 0
	s_waitcnt lgkmcnt(6)
	v_mfma_f32_32x32x16_bf16 v[222:237], v[238:241], v[172:175], v[222:237]
	ds_read_b64_tr_b16 v[238:239], v221
	ds_read_b64_tr_b16 v[240:241], v221 offset:4096
	v_cvt_pk_bf16_f32 v242, v128, v129
	v_cvt_pk_bf16_f32 v243, v130, v131
	v_cvt_pk_bf16_f32 v244, v132, v133
	v_cvt_pk_bf16_f32 v245, v134, v135
	s_nop 1
	s_waitcnt lgkmcnt(6)
	v_mfma_f32_32x32x16_bf16 v[112:127], v[206:209], v[242:245], v[112:127]
	ds_read_b64_tr_b16 v[206:207], v205 offset:256
	ds_read_b64_tr_b16 v[208:209], v205 offset:4352
	v_sub_f32_e32 v136, v136, v190
	v_add_f32_e32 v254, v134, v254
	v_exp_f32_e32 v136, v136
	v_sub_f32_e32 v137, v137, v190
	v_add_f32_e32 v254, v135, v254
	s_waitcnt lgkmcnt(6)
	v_mfma_f32_32x32x16_bf16 v[96:111], v[210:213], v[242:245], v[96:111]
	ds_read_b64_tr_b16 v[210:211], v218 offset:256
	ds_read_b64_tr_b16 v[212:213], v218 offset:4352
	v_exp_f32_e32 v137, v137
	v_sub_f32_e32 v138, v138, v190
	v_add_f32_e32 v254, v136, v254
	v_exp_f32_e32 v138, v138
	v_sub_f32_e32 v139, v139, v190
	s_waitcnt lgkmcnt(6)
	v_mfma_f32_32x32x16_bf16 v[80:95], v[214:217], v[242:245], v[80:95]
	ds_read_b64_tr_b16 v[214:215], v219 offset:256
	ds_read_b64_tr_b16 v[216:217], v219 offset:4352
	v_add_f32_e32 v254, v137, v254
	v_exp_f32_e32 v139, v139
	v_sub_f32_e32 v140, v140, v190
	v_add_f32_e32 v254, v138, v254
	s_waitcnt lgkmcnt(6)
	v_mfma_f32_32x32x16_bf16 v[64:79], v[238:241], v[242:245], v[64:79]
	ds_read_b64_tr_b16 v[238:239], v221 offset:256
	ds_read_b64_tr_b16 v[240:241], v221 offset:4352
	v_exp_f32_e32 v140, v140
	v_sub_f32_e32 v141, v141, v190
	v_add_f32_e32 v254, v139, v254
	v_exp_f32_e32 v141, v141
	s_waitcnt lgkmcnt(6)
	v_mfma_f32_32x32x16_bf16 v[48:63], v[206:209], v[242:245], v[48:63]
	ds_read_b64_tr_b16 v[206:207], v205 offset:8192
	ds_read_b64_tr_b16 v[208:209], v205 offset:12288
	v_sub_f32_e32 v142, v142, v190
	v_add_f32_e32 v254, v140, v254
	v_exp_f32_e32 v142, v142
	v_sub_f32_e32 v143, v143, v190
	s_waitcnt lgkmcnt(6)
	v_mfma_f32_32x32x16_bf16 v[32:47], v[210:213], v[242:245], v[32:47]
	ds_read_b64_tr_b16 v[210:211], v218 offset:8192
	ds_read_b64_tr_b16 v[212:213], v218 offset:12288
	v_add_f32_e32 v254, v141, v254
	v_exp_f32_e32 v143, v143
	v_add_f32_e32 v254, v142, v254
	v_add_f32_e32 v254, v143, v254
	s_waitcnt lgkmcnt(6)
	v_mfma_f32_32x32x16_bf16 v[16:31], v[214:217], v[242:245], v[16:31]
	ds_read_b64_tr_b16 v[214:215], v219 offset:8192
	ds_read_b64_tr_b16 v[216:217], v219 offset:12288
	v_cvt_pk_bf16_f32 v250, v136, v137
	v_cvt_pk_bf16_f32 v251, v138, v139
	v_cvt_pk_bf16_f32 v252, v140, v141
	v_cvt_pk_bf16_f32 v253, v142, v143
	v_add_f32_e32 v202, v202, v254
	s_waitcnt lgkmcnt(6)
	v_mfma_f32_32x32x16_bf16 v[0:15], v[238:241], v[242:245], v[0:15]
	ds_read_b64_tr_b16 v[238:239], v221 offset:8192
	ds_read_b64_tr_b16 v[240:241], v221 offset:12288
	ds_read_b64_tr_b16 v[128:129], v205 offset:8448
	ds_read_b64_tr_b16 v[130:131], v205 offset:12544
	s_waitcnt lgkmcnt(8)
	v_mfma_f32_32x32x16_bf16 v[112:127], v[206:209], v[250:253], v[112:127]
	ds_read_b64_tr_b16 v[206:207], v218 offset:8448
	ds_read_b64_tr_b16 v[208:209], v218 offset:12544
	v_max3_f32 v246, v222, v223, v224
	v_max3_f32 v247, v225, v226, v227
	v_max3_f32 v246, v246, v228, v229
	v_max3_f32 v247, v247, v230, v231
	v_max3_f32 v246, v246, v232, v233
	s_waitcnt lgkmcnt(8)
	v_mfma_f32_32x32x16_bf16 v[96:111], v[210:213], v[250:253], v[96:111]
	ds_read_b64_tr_b16 v[210:211], v219 offset:8448
	ds_read_b64_tr_b16 v[212:213], v219 offset:12544
	v_max3_f32 v247, v247, v234, v235
	v_max3_f32 v246, v246, v236, v237
	v_max_f32_e32 v246, v246, v247
	v_mov_b32_e32 v247, v246
	v_add_f32_e32 v249, 0x41000000, v190
	s_waitcnt lgkmcnt(8)
	v_mfma_f32_32x32x16_bf16 v[80:95], v[214:217], v[250:253], v[80:95]
	ds_read_b64_tr_b16 v[214:215], v221 offset:8448
	ds_read_b64_tr_b16 v[216:217], v221 offset:12544
	s_nop 1
	v_permlane32_swap_b32_e32 v246, v247
	v_max_f32_e32 v246, v246, v247
	v_cmp_gt_f32_e32 vcc, v246, v249
	s_cbranch_vccnz .Latt_rs1_0s0
	s_waitcnt lgkmcnt(8)
	v_mfma_f32_32x32x16_bf16 v[64:79], v[238:241], v[250:253], v[64:79]
	ds_read_b64_tr_b16 v[238:239], v205 offset:16384
	ds_read_b64_tr_b16 v[240:241], v205 offset:20480
	v_sub_f32_e32 v222, v222, v190
	v_exp_f32_e32 v222, v222
	v_sub_f32_e32 v223, v223, v190
	v_exp_f32_e32 v223, v223
	v_sub_f32_e32 v224, v224, v190
	v_add_f32_e32 v254, 0, v222
	s_waitcnt lgkmcnt(8)
	v_mfma_f32_32x32x16_bf16 v[48:63], v[128:131], v[250:253], v[48:63]
	ds_read_b64_tr_b16 v[128:129], v218 offset:16384
	ds_read_b64_tr_b16 v[130:131], v218 offset:20480
	v_exp_f32_e32 v224, v224
	v_sub_f32_e32 v225, v225, v190
	v_add_f32_e32 v254, v223, v254
	v_exp_f32_e32 v225, v225
	v_sub_f32_e32 v226, v226, v190
	v_add_f32_e32 v254, v224, v254
	s_waitcnt lgkmcnt(8)
	v_mfma_f32_32x32x16_bf16 v[32:47], v[206:209], v[250:253], v[32:47]
	ds_read_b64_tr_b16 v[206:207], v219 offset:16384
	ds_read_b64_tr_b16 v[208:209], v219 offset:20480
	v_exp_f32_e32 v226, v226
	v_sub_f32_e32 v227, v227, v190
	v_add_f32_e32 v254, v225, v254
	v_exp_f32_e32 v227, v227
	v_sub_f32_e32 v228, v228, v190
	s_waitcnt lgkmcnt(8)
	v_mfma_f32_32x32x16_bf16 v[16:31], v[210:213], v[250:253], v[16:31]
	ds_read_b64_tr_b16 v[210:211], v221 offset:16384
	ds_read_b64_tr_b16 v[212:213], v221 offset:20480
	v_add_f32_e32 v254, v226, v254
	v_exp_f32_e32 v228, v228
	v_sub_f32_e32 v229, v229, v190
	v_add_f32_e32 v254, v227, v254
	v_exp_f32_e32 v229, v229
	s_waitcnt lgkmcnt(8)
	v_mfma_f32_32x32x16_bf16 v[0:15], v[214:217], v[250:253], v[0:15]
	ds_read_b64_tr_b16 v[214:215], v205 offset:16640
	ds_read_b64_tr_b16 v[216:217], v205 offset:20736
	s_nop 0
	v_cvt_pk_bf16_f32 v242, v222, v223
	v_cvt_pk_bf16_f32 v243, v224, v225
	v_cvt_pk_bf16_f32 v244, v226, v227
	v_cvt_pk_bf16_f32 v245, v228, v229
	s_nop 1
	s_waitcnt lgkmcnt(8)
	v_mfma_f32_32x32x16_bf16 v[112:127], v[238:241], v[242:245], v[112:127]
	ds_read_b64_tr_b16 v[238:239], v218 offset:16640
	ds_read_b64_tr_b16 v[240:241], v218 offset:20736
	v_sub_f32_e32 v230, v230, v190
	v_add_f32_e32 v254, v228, v254
	v_exp_f32_e32 v230, v230
	v_sub_f32_e32 v231, v231, v190
	v_add_f32_e32 v254, v229, v254
	s_waitcnt lgkmcnt(8)
	v_mfma_f32_32x32x16_bf16 v[96:111], v[128:131], v[242:245], v[96:111]
	ds_read_b64_tr_b16 v[128:129], v219 offset:16640
	ds_read_b64_tr_b16 v[130:131], v219 offset:20736
	v_exp_f32_e32 v231, v231
	v_sub_f32_e32 v232, v232, v190
	v_add_f32_e32 v254, v230, v254
	v_exp_f32_e32 v232, v232
	v_sub_f32_e32 v233, v233, v190
	s_waitcnt lgkmcnt(8)
	v_mfma_f32_32x32x16_bf16 v[80:95], v[206:209], v[242:245], v[80:95]
	ds_read_b64_tr_b16 v[206:207], v221 offset:16640
	ds_read_b64_tr_b16 v[208:209], v221 offset:20736
	v_add_f32_e32 v254, v231, v254
	v_exp_f32_e32 v233, v233
	v_sub_f32_e32 v234, v234, v190
	v_add_f32_e32 v254, v232, v254
	s_waitcnt lgkmcnt(8)
	v_mfma_f32_32x32x16_bf16 v[64:79], v[210:213], v[242:245], v[64:79]
	ds_read_b64_tr_b16 v[210:211], v205 offset:24576
	ds_read_b64_tr_b16 v[212:213], v205 offset:28672
	v_exp_f32_e32 v234, v234
	v_sub_f32_e32 v235, v235, v190
	v_add_f32_e32 v254, v233, v254
	v_exp_f32_e32 v235, v235
	s_waitcnt lgkmcnt(8)
	v_mfma_f32_32x32x16_bf16 v[48:63], v[214:217], v[242:245], v[48:63]
	ds_read_b64_tr_b16 v[214:215], v218 offset:24576
	ds_read_b64_tr_b16 v[216:217], v218 offset:28672
	v_sub_f32_e32 v236, v236, v190
	v_add_f32_e32 v254, v234, v254
	v_exp_f32_e32 v236, v236
	v_sub_f32_e32 v237, v237, v190
	s_waitcnt lgkmcnt(8)
	v_mfma_f32_32x32x16_bf16 v[32:47], v[238:241], v[242:245], v[32:47]
	ds_read_b64_tr_b16 v[238:239], v219 offset:24576
	ds_read_b64_tr_b16 v[240:241], v219 offset:28672
	v_add_f32_e32 v254, v235, v254
	v_exp_f32_e32 v237, v237
	v_add_f32_e32 v254, v236, v254
	v_add_f32_e32 v254, v237, v254
	s_waitcnt lgkmcnt(8)
	v_mfma_f32_32x32x16_bf16 v[16:31], v[128:131], v[242:245], v[16:31]
	ds_read_b64_tr_b16 v[128:129], v221 offset:24576
	ds_read_b64_tr_b16 v[130:131], v221 offset:28672
	v_cvt_pk_bf16_f32 v250, v230, v231
	v_cvt_pk_bf16_f32 v251, v232, v233
	v_cvt_pk_bf16_f32 v252, v234, v235
	v_cvt_pk_bf16_f32 v253, v236, v237
	v_add_f32_e32 v202, v202, v254
	s_waitcnt lgkmcnt(8)
	v_mfma_f32_32x32x16_bf16 v[0:15], v[206:209], v[242:245], v[0:15]
	ds_read_b64_tr_b16 v[206:207], v205 offset:24832
	ds_read_b64_tr_b16 v[208:209], v205 offset:28928
	s_waitcnt lgkmcnt(8)
	v_mfma_f32_32x32x16_bf16 v[112:127], v[210:213], v[250:253], v[112:127]
	ds_read_b64_tr_b16 v[210:211], v218 offset:24832
	ds_read_b64_tr_b16 v[212:213], v218 offset:28928
	s_waitcnt lgkmcnt(8)
	v_mfma_f32_32x32x16_bf16 v[96:111], v[214:217], v[250:253], v[96:111]
	ds_read_b64_tr_b16 v[214:215], v219 offset:24832
	ds_read_b64_tr_b16 v[216:217], v219 offset:28928
	s_waitcnt lgkmcnt(8)
	v_mfma_f32_32x32x16_bf16 v[80:95], v[238:241], v[250:253], v[80:95]
	ds_read_b64_tr_b16 v[238:239], v221 offset:24832
	ds_read_b64_tr_b16 v[240:241], v221 offset:28928
	s_waitcnt lgkmcnt(8)
	v_mfma_f32_32x32x16_bf16 v[64:79], v[128:131], v[250:253], v[64:79]
	s_waitcnt lgkmcnt(6)
	v_mfma_f32_32x32x16_bf16 v[48:63], v[206:209], v[250:253], v[48:63]
	s_waitcnt lgkmcnt(4)
	v_mfma_f32_32x32x16_bf16 v[32:47], v[210:213], v[250:253], v[32:47]
	s_waitcnt lgkmcnt(2)
	v_mfma_f32_32x32x16_bf16 v[16:31], v[214:217], v[250:253], v[16:31]
	s_waitcnt lgkmcnt(0)
	v_mfma_f32_32x32x16_bf16 v[0:15], v[238:241], v[250:253], v[0:15]
	ds_read_b128 v[206:209], v194 offset:16384
	ds_read_b128 v[210:213], v195 offset:16384
	ds_read_b128 v[214:217], v196 offset:16384
	ds_read_b128 v[238:241], v197 offset:16384
	ds_read_b128 v[242:245], v198 offset:16384
	ds_read_b128 v[250:253], v199 offset:16384
	ds_read_b128 v[222:225], v200 offset:16384
	ds_read_b128 v[226:229], v201 offset:16384
	s_waitcnt vmcnt(0)
	s_add_i32 s18, s88, 1
	s_cmp_lg_u32 s88, 2
	s_cselect_b32 s88, s18, 0
	s_add_i32 s43, s43, 64
	s_add_u32 s14, s14, 0x100000
	s_addc_u32 s15, s15, 0
	s_add_i32 s42, s42, 1
	s_add_i32 s100, s43, 63
	s_cmp_le_i32 s100, s83
	s_cbranch_scc0 .Latt_latchb_0
	s_cmp_ge_u32 s42, s82
	s_cselect_b64 s[18:19], -1, 0
	v_mov_b32_e32 v203, v176
	s_barrier
	s_branch .Latt_cont_0s1
.Latt_rs1_0s0:
	s_waitcnt lgkmcnt(8)
	v_mfma_f32_32x32x16_bf16 v[64:79], v[238:241], v[250:253], v[64:79]
	ds_read_b64_tr_b16 v[238:239], v205 offset:16384
	ds_read_b64_tr_b16 v[240:241], v205 offset:20480
	s_waitcnt lgkmcnt(8)
	v_mfma_f32_32x32x16_bf16 v[48:63], v[128:131], v[250:253], v[48:63]
	ds_read_b64_tr_b16 v[128:129], v218 offset:16384
	ds_read_b64_tr_b16 v[130:131], v218 offset:20480
	s_waitcnt lgkmcnt(8)
	v_mfma_f32_32x32x16_bf16 v[32:47], v[206:209], v[250:253], v[32:47]
	ds_read_b64_tr_b16 v[206:207], v219 offset:16384
	ds_read_b64_tr_b16 v[208:209], v219 offset:20480
	s_waitcnt lgkmcnt(8)
	v_mfma_f32_32x32x16_bf16 v[16:31], v[210:213], v[250:253], v[16:31]
	ds_read_b64_tr_b16 v[210:211], v221 offset:16384
	ds_read_b64_tr_b16 v[212:213], v221 offset:20480
	s_waitcnt lgkmcnt(8)
	v_mfma_f32_32x32x16_bf16 v[0:15], v[214:217], v[250:253], v[0:15]
	ds_read_b64_tr_b16 v[214:215], v205 offset:16640
	ds_read_b64_tr_b16 v[216:217], v205 offset:20736
	s_nop 11
	v_max_f32_e32 v246, v190, v246
	v_sub_f32_e32 v190, v190, v246
	v_exp_f32_e32 v190, v190
	s_nop 0
	v_pk_mul_f32 v[126:127], v[126:127], v[190:191] op_sel_hi:[1,0]
	v_pk_mul_f32 v[124:125], v[124:125], v[190:191] op_sel_hi:[1,0]
	v_pk_mul_f32 v[122:123], v[122:123], v[190:191] op_sel_hi:[1,0]
	v_pk_mul_f32 v[120:121], v[120:121], v[190:191] op_sel_hi:[1,0]
	v_pk_mul_f32 v[118:119], v[118:119], v[190:191] op_sel_hi:[1,0]
	v_pk_mul_f32 v[116:117], v[116:117], v[190:191] op_sel_hi:[1,0]
	v_pk_mul_f32 v[114:115], v[114:115], v[190:191] op_sel_hi:[1,0]
	v_pk_mul_f32 v[112:113], v[112:113], v[190:191] op_sel_hi:[1,0]
	v_pk_mul_f32 v[110:111], v[110:111], v[190:191] op_sel_hi:[1,0]
	v_pk_mul_f32 v[108:109], v[108:109], v[190:191] op_sel_hi:[1,0]
	v_pk_mul_f32 v[106:107], v[106:107], v[190:191] op_sel_hi:[1,0]
	v_pk_mul_f32 v[104:105], v[104:105], v[190:191] op_sel_hi:[1,0]
	v_pk_mul_f32 v[102:103], v[102:103], v[190:191] op_sel_hi:[1,0]
	v_pk_mul_f32 v[100:101], v[100:101], v[190:191] op_sel_hi:[1,0]
	v_pk_mul_f32 v[98:99], v[98:99], v[190:191] op_sel_hi:[1,0]
	v_pk_mul_f32 v[96:97], v[96:97], v[190:191] op_sel_hi:[1,0]
	v_pk_mul_f32 v[94:95], v[94:95], v[190:191] op_sel_hi:[1,0]
	v_pk_mul_f32 v[92:93], v[92:93], v[190:191] op_sel_hi:[1,0]
	v_pk_mul_f32 v[90:91], v[90:91], v[190:191] op_sel_hi:[1,0]
	v_pk_mul_f32 v[88:89], v[88:89], v[190:191] op_sel_hi:[1,0]
	v_pk_mul_f32 v[86:87], v[86:87], v[190:191] op_sel_hi:[1,0]
	v_pk_mul_f32 v[84:85], v[84:85], v[190:191] op_sel_hi:[1,0]
	v_pk_mul_f32 v[82:83], v[82:83], v[190:191] op_sel_hi:[1,0]
	v_pk_mul_f32 v[80:81], v[80:81], v[190:191] op_sel_hi:[1,0]
	v_pk_mul_f32 v[78:79], v[78:79], v[190:191] op_sel_hi:[1,0]
	v_pk_mul_f32 v[76:77], v[76:77], v[190:191] op_sel_hi:[1,0]
	v_pk_mul_f32 v[74:75], v[74:75], v[190:191] op_sel_hi:[1,0]
	v_pk_mul_f32 v[72:73], v[72:73], v[190:191] op_sel_hi:[1,0]
	v_pk_mul_f32 v[70:71], v[70:71], v[190:191] op_sel_hi:[1,0]
	v_pk_mul_f32 v[68:69], v[68:69], v[190:191] op_sel_hi:[1,0]
	v_pk_mul_f32 v[66:67], v[66:67], v[190:191] op_sel_hi:[1,0]
	v_pk_mul_f32 v[64:65], v[64:65], v[190:191] op_sel_hi:[1,0]
	v_pk_mul_f32 v[62:63], v[62:63], v[190:191] op_sel_hi:[1,0]
	v_pk_mul_f32 v[60:61], v[60:61], v[190:191] op_sel_hi:[1,0]
	v_pk_mul_f32 v[58:59], v[58:59], v[190:191] op_sel_hi:[1,0]
	v_pk_mul_f32 v[56:57], v[56:57], v[190:191] op_sel_hi:[1,0]
	v_pk_mul_f32 v[54:55], v[54:55], v[190:191] op_sel_hi:[1,0]
	v_pk_mul_f32 v[52:53], v[52:53], v[190:191] op_sel_hi:[1,0]
	v_pk_mul_f32 v[50:51], v[50:51], v[190:191] op_sel_hi:[1,0]
	v_pk_mul_f32 v[48:49], v[48:49], v[190:191] op_sel_hi:[1,0]
	v_pk_mul_f32 v[46:47], v[46:47], v[190:191] op_sel_hi:[1,0]
	v_pk_mul_f32 v[44:45], v[44:45], v[190:191] op_sel_hi:[1,0]
	v_pk_mul_f32 v[42:43], v[42:43], v[190:191] op_sel_hi:[1,0]
	v_pk_mul_f32 v[40:41], v[40:41], v[190:191] op_sel_hi:[1,0]
	v_pk_mul_f32 v[38:39], v[38:39], v[190:191] op_sel_hi:[1,0]
	v_pk_mul_f32 v[36:37], v[36:37], v[190:191] op_sel_hi:[1,0]
	v_pk_mul_f32 v[34:35], v[34:35], v[190:191] op_sel_hi:[1,0]
	v_pk_mul_f32 v[32:33], v[32:33], v[190:191] op_sel_hi:[1,0]
	v_pk_mul_f32 v[30:31], v[30:31], v[190:191] op_sel_hi:[1,0]
	v_pk_mul_f32 v[28:29], v[28:29], v[190:191] op_sel_hi:[1,0]
	v_pk_mul_f32 v[26:27], v[26:27], v[190:191] op_sel_hi:[1,0]
	v_pk_mul_f32 v[24:25], v[24:25], v[190:191] op_sel_hi:[1,0]
	v_pk_mul_f32 v[22:23], v[22:23], v[190:191] op_sel_hi:[1,0]
	v_pk_mul_f32 v[20:21], v[20:21], v[190:191] op_sel_hi:[1,0]
	v_pk_mul_f32 v[18:19], v[18:19], v[190:191] op_sel_hi:[1,0]
	v_pk_mul_f32 v[16:17], v[16:17], v[190:191] op_sel_hi:[1,0]
	v_pk_mul_f32 v[14:15], v[14:15], v[190:191] op_sel_hi:[1,0]
	v_pk_mul_f32 v[12:13], v[12:13], v[190:191] op_sel_hi:[1,0]
	v_pk_mul_f32 v[10:11], v[10:11], v[190:191] op_sel_hi:[1,0]
	v_pk_mul_f32 v[8:9], v[8:9], v[190:191] op_sel_hi:[1,0]
	v_pk_mul_f32 v[6:7], v[6:7], v[190:191] op_sel_hi:[1,0]
	v_pk_mul_f32 v[4:5], v[4:5], v[190:191] op_sel_hi:[1,0]
	v_pk_mul_f32 v[2:3], v[2:3], v[190:191] op_sel_hi:[1,0]
	v_pk_mul_f32 v[0:1], v[0:1], v[190:191] op_sel_hi:[1,0]
	v_mul_f32_e32 v202, v202, v190
	v_mov_b32_e32 v190, v246
	v_sub_f32_e32 v222, v222, v190
	v_exp_f32_e32 v222, v222
	v_sub_f32_e32 v223, v223, v190
	v_exp_f32_e32 v223, v223
	v_sub_f32_e32 v224, v224, v190
	v_add_f32_e32 v254, 0, v222
	v_exp_f32_e32 v224, v224
	v_sub_f32_e32 v225, v225, v190
	v_add_f32_e32 v254, v223, v254
	v_exp_f32_e32 v225, v225
	v_sub_f32_e32 v226, v226, v190
	v_add_f32_e32 v254, v224, v254
	v_exp_f32_e32 v226, v226
	v_sub_f32_e32 v227, v227, v190
	v_add_f32_e32 v254, v225, v254
	v_exp_f32_e32 v227, v227
	v_sub_f32_e32 v228, v228, v190
	v_add_f32_e32 v254, v226, v254
	v_exp_f32_e32 v228, v228
	v_sub_f32_e32 v229, v229, v190
	v_add_f32_e32 v254, v227, v254
	v_exp_f32_e32 v229, v229
	v_sub_f32_e32 v230, v230, v190
	v_add_f32_e32 v254, v228, v254
	v_exp_f32_e32 v230, v230
	v_sub_f32_e32 v231, v231, v190
	v_add_f32_e32 v254, v229, v254
	v_exp_f32_e32 v231, v231
	v_sub_f32_e32 v232, v232, v190
	v_add_f32_e32 v254, v230, v254
	v_exp_f32_e32 v232, v232
	v_sub_f32_e32 v233, v233, v190
	v_add_f32_e32 v254, v231, v254
	v_exp_f32_e32 v233, v233
	v_sub_f32_e32 v234, v234, v190
	v_add_f32_e32 v254, v232, v254
	v_exp_f32_e32 v234, v234
	v_sub_f32_e32 v235, v235, v190
	v_add_f32_e32 v254, v233, v254
	v_exp_f32_e32 v235, v235
	v_sub_f32_e32 v236, v236, v190
	v_add_f32_e32 v254, v234, v254
	v_exp_f32_e32 v236, v236
	v_sub_f32_e32 v237, v237, v190
	v_add_f32_e32 v254, v235, v254
	v_exp_f32_e32 v237, v237
	v_add_f32_e32 v254, v236, v254
	v_add_f32_e32 v254, v237, v254
	v_cvt_pk_bf16_f32 v242, v222, v223
	v_cvt_pk_bf16_f32 v243, v224, v225
	v_cvt_pk_bf16_f32 v244, v226, v227
	v_cvt_pk_bf16_f32 v245, v228, v229
	v_cvt_pk_bf16_f32 v250, v230, v231
	v_cvt_pk_bf16_f32 v251, v232, v233
	v_cvt_pk_bf16_f32 v252, v234, v235
	v_cvt_pk_bf16_f32 v253, v236, v237
	v_add_f32_e32 v202, v202, v254
	s_nop 1
	s_waitcnt lgkmcnt(8)
	v_mfma_f32_32x32x16_bf16 v[112:127], v[238:241], v[242:245], v[112:127]
	ds_read_b64_tr_b16 v[238:239], v218 offset:16640
	ds_read_b64_tr_b16 v[240:241], v218 offset:20736
	s_waitcnt lgkmcnt(8)
	v_mfma_f32_32x32x16_bf16 v[96:111], v[128:131], v[242:245], v[96:111]
	ds_read_b64_tr_b16 v[222:223], v219 offset:16640
	ds_read_b64_tr_b16 v[224:225], v219 offset:20736
	s_waitcnt lgkmcnt(8)
	v_mfma_f32_32x32x16_bf16 v[80:95], v[206:209], v[242:245], v[80:95]
	ds_read_b64_tr_b16 v[206:207], v221 offset:16640
	ds_read_b64_tr_b16 v[208:209], v221 offset:20736
	s_waitcnt lgkmcnt(8)
	v_mfma_f32_32x32x16_bf16 v[64:79], v[210:213], v[242:245], v[64:79]
	ds_read_b64_tr_b16 v[210:211], v205 offset:24576
	ds_read_b64_tr_b16 v[212:213], v205 offset:28672
	s_waitcnt lgkmcnt(8)
	v_mfma_f32_32x32x16_bf16 v[48:63], v[214:217], v[242:245], v[48:63]
	ds_read_b64_tr_b16 v[214:215], v218 offset:24576
	ds_read_b64_tr_b16 v[216:217], v218 offset:28672
	s_waitcnt lgkmcnt(8)
	v_mfma_f32_32x32x16_bf16 v[32:47], v[238:241], v[242:245], v[32:47]
	ds_read_b64_tr_b16 v[238:239], v219 offset:24576
	ds_read_b64_tr_b16 v[240:241], v219 offset:28672
	s_waitcnt lgkmcnt(8)
	v_mfma_f32_32x32x16_bf16 v[16:31], v[222:225], v[242:245], v[16:31]
	ds_read_b64_tr_b16 v[222:223], v221 offset:24576
	ds_read_b64_tr_b16 v[224:225], v221 offset:28672
	s_waitcnt lgkmcnt(8)
	v_mfma_f32_32x32x16_bf16 v[0:15], v[206:209], v[242:245], v[0:15]
	ds_read_b64_tr_b16 v[206:207], v205 offset:24832
	ds_read_b64_tr_b16 v[208:209], v205 offset:28928
	s_waitcnt lgkmcnt(8)
	v_mfma_f32_32x32x16_bf16 v[112:127], v[210:213], v[250:253], v[112:127]
	ds_read_b64_tr_b16 v[210:211], v218 offset:24832
	ds_read_b64_tr_b16 v[212:213], v218 offset:28928
	s_waitcnt lgkmcnt(8)
	v_mfma_f32_32x32x16_bf16 v[96:111], v[214:217], v[250:253], v[96:111]
	ds_read_b64_tr_b16 v[214:215], v219 offset:24832
	ds_read_b64_tr_b16 v[216:217], v219 offset:28928
	s_waitcnt lgkmcnt(8)
	v_mfma_f32_32x32x16_bf16 v[80:95], v[238:241], v[250:253], v[80:95]
	ds_read_b64_tr_b16 v[238:239], v221 offset:24832
	ds_read_b64_tr_b16 v[240:241], v221 offset:28928
	s_waitcnt lgkmcnt(8)
	v_mfma_f32_32x32x16_bf16 v[64:79], v[222:225], v[250:253], v[64:79]
	s_waitcnt lgkmcnt(6)
	v_mfma_f32_32x32x16_bf16 v[48:63], v[206:209], v[250:253], v[48:63]
	s_waitcnt lgkmcnt(4)
	v_mfma_f32_32x32x16_bf16 v[32:47], v[210:213], v[250:253], v[32:47]
	s_waitcnt lgkmcnt(2)
	v_mfma_f32_32x32x16_bf16 v[16:31], v[214:217], v[250:253], v[16:31]
	s_waitcnt lgkmcnt(0)
	v_mfma_f32_32x32x16_bf16 v[0:15], v[238:241], v[250:253], v[0:15]
	ds_read_b128 v[206:209], v194 offset:16384
	ds_read_b128 v[210:213], v195 offset:16384
	ds_read_b128 v[214:217], v196 offset:16384
	ds_read_b128 v[238:241], v197 offset:16384
	ds_read_b128 v[242:245], v198 offset:16384
	ds_read_b128 v[250:253], v199 offset:16384
	ds_read_b128 v[222:225], v200 offset:16384
	ds_read_b128 v[226:229], v201 offset:16384
	s_waitcnt vmcnt(0)
	s_add_i32 s18, s88, 1
	s_cmp_lg_u32 s88, 2
	s_cselect_b32 s88, s18, 0
	s_add_i32 s43, s43, 64
	s_add_u32 s14, s14, 0x100000
	s_addc_u32 s15, s15, 0
	s_add_i32 s42, s42, 1
	s_add_i32 s100, s43, 63
	s_cmp_le_i32 s100, s83
	s_cbranch_scc0 .Latt_latchb_0
	s_cmp_ge_u32 s42, s82
	s_cselect_b64 s[18:19], -1, 0
	v_mov_b32_e32 v203, v176
	s_barrier
	s_branch .Latt_cont_0s1
.Latt_slow_0s0:
.Latt_slot1_0:
.Latt_cont_0s1:
	v_add_u32_e32 v205, 0x8000, v205
	v_add_u32_e32 v218, 0x8000, v218
	v_add_u32_e32 v219, 0x8000, v219
	v_add_u32_e32 v221, 0x8000, v221
	s_waitcnt lgkmcnt(7)
	v_mfma_f32_32x32x16_bf16 v[128:143], v[206:209], v[144:147], 0
	ds_read_b128 v[206:209], v194 offset:24576
	s_cmp_lg_u64 s[18:19], 0
	s_cbranch_scc1 .Latt_nd0_0s1
	s_sub_i32 s100, s88, 1
	s_cmp_eq_u32 s88, 0
	s_cselect_b32 s100, 2, s100
	s_lshl_b32 s101, s100, 14
	s_add_i32 m0, s85, s101
	s_nop 0
	global_load_lds_dwordx4 v178, s[14:15]

.Latt_nr0_0s1:
	s_waitcnt lgkmcnt(3)
	v_mfma_f32_32x32x16_bf16 v[222:237], v[214:217], v[152:155], v[222:237]
	ds_read_b128 v[214:217], v200 offset:24576
	v_sub_f32_e32 v128, v128, v190
	v_exp_f32_e32 v128, v128
	v_sub_f32_e32 v129, v129, v190
	v_exp_f32_e32 v129, v129
	v_sub_f32_e32 v130, v130, v190
	s_waitcnt lgkmcnt(3)
	v_mfma_f32_32x32x16_bf16 v[222:237], v[238:241], v[156:159], v[222:237]
	ds_read_b128 v[238:241], v201 offset:24576
	v_add_f32_e32 v254, 0, v128
	v_exp_f32_e32 v130, v130
	v_sub_f32_e32 v131, v131, v190
	v_add_f32_e32 v254, v129, v254
	v_exp_f32_e32 v131, v131
	s_waitcnt lgkmcnt(3)
	v_mfma_f32_32x32x16_bf16 v[222:237], v[206:209], v[160:163], v[222:237]
	ds_read_b64_tr_b16 v[206:207], v205
	ds_read_b64_tr_b16 v[208:209], v205 offset:4096
	v_sub_f32_e32 v132, v132, v190
	v_add_f32_e32 v254, v130, v254
	v_exp_f32_e32 v132, v132
	v_sub_f32_e32 v133, v133, v190
	v_add_f32_e32 v254, v131, v254
	s_waitcnt lgkmcnt(4)
	v_mfma_f32_32x32x16_bf16 v[222:237], v[210:213], v[164:167], v[222:237]
	ds_read_b64_tr_b16 v[210:211], v218
	ds_read_b64_tr_b16 v[212:213], v218 offset:4096
	v_exp_f32_e32 v133, v133
	v_sub_f32_e32 v134, v134, v190
	v_add_f32_e32 v254, v132, v254
	v_exp_f32_e32 v134, v134
	s_waitcnt lgkmcnt(5)
	v_mfma_f32_32x32x16_bf16 v[222:237], v[214:217], v[168:171], v[222:237]
	ds_read_b64_tr_b16 v[214:215], v219
	ds_read_b64_tr_b16 v[216:217], v219 offset:4096
	v_sub_f32_e32 v135, v135, v190
	v_add_f32_e32 v254, v133, v254
	v_exp_f32_e32 v135, v135
	s_nop 0
	s_waitcnt lgkmcnt(6)
	v_mfma_f32_32x32x16_bf16 v[222:237], v[238:241], v[172:175], v[222:237]
	ds_read_b64_tr_b16 v[238:239], v221
	ds_read_b64_tr_b16 v[240:241], v221 offset:4096
	v_cvt_pk_bf16_f32 v242, v128, v129
	v_cvt_pk_bf16_f32 v243, v130, v131
	v_cvt_pk_bf16_f32 v244, v132, v133
	v_cvt_pk_bf16_f32 v245, v134, v135
	s_nop 1
	s_waitcnt lgkmcnt(6)
	v_mfma_f32_32x32x16_bf16 v[112:127], v[206:209], v[242:245], v[112:127]
	ds_read_b64_tr_b16 v[206:207], v205 offset:256
	ds_read_b64_tr_b16 v[208:209], v205 offset:4352
	v_sub_f32_e32 v136, v136, v190
	v_add_f32_e32 v254, v134, v254
	v_exp_f32_e32 v136, v136
	v_sub_f32_e32 v137, v137, v190
	v_add_f32_e32 v254, v135, v254
	s_waitcnt lgkmcnt(6)
	v_mfma_f32_32x32x16_bf16 v[96:111], v[210:213], v[242:245], v[96:111]
	ds_read_b64_tr_b16 v[210:211], v218 offset:256
	ds_read_b64_tr_b16 v[212:213], v218 offset:4352
	v_exp_f32_e32 v137, v137
	v_sub_f32_e32 v138, v138, v190
	v_add_f32_e32 v254, v136, v254
	v_exp_f32_e32 v138, v138
	v_sub_f32_e32 v139, v139, v190
	s_waitcnt lgkmcnt(6)
	v_mfma_f32_32x32x16_bf16 v[80:95], v[214:217], v[242:245], v[80:95]
	ds_read_b64_tr_b16 v[214:215], v219 offset:256
	ds_read_b64_tr_b16 v[216:217], v219 offset:4352
	v_add_f32_e32 v254, v137, v254
	v_exp_f32_e32 v139, v139
	v_sub_f32_e32 v140, v140, v190
	v_add_f32_e32 v254, v138, v254
	s_waitcnt lgkmcnt(6)
	v_mfma_f32_32x32x16_bf16 v[64:79], v[238:241], v[242:245], v[64:79]
	ds_read_b64_tr_b16 v[238:239], v221 offset:256
	ds_read_b64_tr_b16 v[240:241], v221 offset:4352
	v_exp_f32_e32 v140, v140
	v_sub_f32_e32 v141, v141, v190
	v_add_f32_e32 v254, v139, v254
	v_exp_f32_e32 v141, v141
	s_waitcnt lgkmcnt(6)
	v_mfma_f32_32x32x16_bf16 v[48:63], v[206:209], v[242:245], v[48:63]
	ds_read_b64_tr_b16 v[206:207], v205 offset:8192
	ds_read_b64_tr_b16 v[208:209], v205 offset:12288
	v_sub_f32_e32 v142, v142, v190
	v_add_f32_e32 v254, v140, v254
	v_exp_f32_e32 v142, v142
	v_sub_f32_e32 v143, v143, v190
	s_waitcnt lgkmcnt(6)
	v_mfma_f32_32x32x16_bf16 v[32:47], v[210:213], v[242:245], v[32:47]
	ds_read_b64_tr_b16 v[210:211], v218 offset:8192
	ds_read_b64_tr_b16 v[212:213], v218 offset:12288
	v_add_f32_e32 v254, v141, v254
	v_exp_f32_e32 v143, v143
	v_add_f32_e32 v254, v142, v254
	v_add_f32_e32 v254, v143, v254
	s_waitcnt lgkmcnt(6)
	v_mfma_f32_32x32x16_bf16 v[16:31], v[214:217], v[242:245], v[16:31]
	ds_read_b64_tr_b16 v[214:215], v219 offset:8192
	ds_read_b64_tr_b16 v[216:217], v219 offset:12288
	v_cvt_pk_bf16_f32 v250, v136, v137
	v_cvt_pk_bf16_f32 v251, v138, v139
	v_cvt_pk_bf16_f32 v252, v140, v141
	v_cvt_pk_bf16_f32 v253, v142, v143
	v_add_f32_e32 v202, v202, v254
	s_waitcnt lgkmcnt(6)
	v_mfma_f32_32x32x16_bf16 v[0:15], v[238:241], v[242:245], v[0:15]
	ds_read_b64_tr_b16 v[238:239], v221 offset:8192
	ds_read_b64_tr_b16 v[240:241], v221 offset:12288
	ds_read_b64_tr_b16 v[128:129], v205 offset:8448
	ds_read_b64_tr_b16 v[130:131], v205 offset:12544
	s_waitcnt lgkmcnt(8)
	v_mfma_f32_32x32x16_bf16 v[112:127], v[206:209], v[250:253], v[112:127]
	ds_read_b64_tr_b16 v[206:207], v218 offset:8448
	ds_read_b64_tr_b16 v[208:209], v218 offset:12544
	v_max3_f32 v246, v222, v223, v224
	v_max3_f32 v247, v225, v226, v227
	v_max3_f32 v246, v246, v228, v229
	v_max3_f32 v247, v247, v230, v231
	v_max3_f32 v246, v246, v232, v233
	s_waitcnt lgkmcnt(8)
	v_mfma_f32_32x32x16_bf16 v[96:111], v[210:213], v[250:253], v[96:111]
	ds_read_b64_tr_b16 v[210:211], v219 offset:8448
	ds_read_b64_tr_b16 v[212:213], v219 offset:12544
	v_max3_f32 v247, v247, v234, v235
	v_max3_f32 v246, v246, v236, v237
	v_max_f32_e32 v246, v246, v247
	v_mov_b32_e32 v247, v246
	v_add_f32_e32 v249, 0x41000000, v190
	s_waitcnt lgkmcnt(8)
	v_mfma_f32_32x32x16_bf16 v[80:95], v[214:217], v[250:253], v[80:95]
	ds_read_b64_tr_b16 v[214:215], v221 offset:8448
	ds_read_b64_tr_b16 v[216:217], v221 offset:12544
	s_nop 1
	v_permlane32_swap_b32_e32 v246, v247
	v_max_f32_e32 v246, v246, v247
	v_cmp_gt_f32_e32 vcc, v246, v249
	s_cbranch_vccnz .Latt_rs1_0s1
	s_waitcnt lgkmcnt(8)
	v_mfma_f32_32x32x16_bf16 v[64:79], v[238:241], v[250:253], v[64:79]
	ds_read_b64_tr_b16 v[238:239], v205 offset:16384
	ds_read_b64_tr_b16 v[240:241], v205 offset:20480
	v_sub_f32_e32 v222, v222, v190
	v_exp_f32_e32 v222, v222
	v_sub_f32_e32 v223, v223, v190
	v_exp_f32_e32 v223, v223
	v_sub_f32_e32 v224, v224, v190
	v_add_f32_e32 v254, 0, v222
	s_waitcnt lgkmcnt(8)
	v_mfma_f32_32x32x16_bf16 v[48:63], v[128:131], v[250:253], v[48:63]
	ds_read_b64_tr_b16 v[128:129], v218 offset:16384
	ds_read_b64_tr_b16 v[130:131], v218 offset:20480
	v_exp_f32_e32 v224, v224
	v_sub_f32_e32 v225, v225, v190
	v_add_f32_e32 v254, v223, v254
	v_exp_f32_e32 v225, v225
	v_sub_f32_e32 v226, v226, v190
	v_add_f32_e32 v254, v224, v254
	s_waitcnt lgkmcnt(8)
	v_mfma_f32_32x32x16_bf16 v[32:47], v[206:209], v[250:253], v[32:47]
	ds_read_b64_tr_b16 v[206:207], v219 offset:16384
	ds_read_b64_tr_b16 v[208:209], v219 offset:20480
	v_exp_f32_e32 v226, v226
	v_sub_f32_e32 v227, v227, v190
	v_add_f32_e32 v254, v225, v254
	v_exp_f32_e32 v227, v227
	v_sub_f32_e32 v228, v228, v190
	s_waitcnt lgkmcnt(8)
	v_mfma_f32_32x32x16_bf16 v[16:31], v[210:213], v[250:253], v[16:31]
	ds_read_b64_tr_b16 v[210:211], v221 offset:16384
	ds_read_b64_tr_b16 v[212:213], v221 offset:20480
	v_add_f32_e32 v254, v226, v254
	v_exp_f32_e32 v228, v228
	v_sub_f32_e32 v229, v229, v190
	v_add_f32_e32 v254, v227, v254
	v_exp_f32_e32 v229, v229
	s_waitcnt lgkmcnt(8)
	v_mfma_f32_32x32x16_bf16 v[0:15], v[214:217], v[250:253], v[0:15]
	ds_read_b64_tr_b16 v[214:215], v205 offset:16640
	ds_read_b64_tr_b16 v[216:217], v205 offset:20736
	s_nop 0
	v_cvt_pk_bf16_f32 v242, v222, v223
	v_cvt_pk_bf16_f32 v243, v224, v225
	v_cvt_pk_bf16_f32 v244, v226, v227
	v_cvt_pk_bf16_f32 v245, v228, v229
	s_nop 1
	s_waitcnt lgkmcnt(8)
	v_mfma_f32_32x32x16_bf16 v[112:127], v[238:241], v[242:245], v[112:127]
	ds_read_b64_tr_b16 v[238:239], v218 offset:16640
	ds_read_b64_tr_b16 v[240:241], v218 offset:20736
	v_sub_f32_e32 v230, v230, v190
	v_add_f32_e32 v254, v228, v254
	v_exp_f32_e32 v230, v230
	v_sub_f32_e32 v231, v231, v190
	v_add_f32_e32 v254, v229, v254
	s_waitcnt lgkmcnt(8)
	v_mfma_f32_32x32x16_bf16 v[96:111], v[128:131], v[242:245], v[96:111]
	ds_read_b64_tr_b16 v[128:129], v219 offset:16640
	ds_read_b64_tr_b16 v[130:131], v219 offset:20736
	v_exp_f32_e32 v231, v231
	v_sub_f32_e32 v232, v232, v190
	v_add_f32_e32 v254, v230, v254
	v_exp_f32_e32 v232, v232
	v_sub_f32_e32 v233, v233, v190
	s_waitcnt lgkmcnt(8)
	v_mfma_f32_32x32x16_bf16 v[80:95], v[206:209], v[242:245], v[80:95]
	ds_read_b64_tr_b16 v[206:207], v221 offset:16640
	ds_read_b64_tr_b16 v[208:209], v221 offset:20736
	v_add_f32_e32 v254, v231, v254
	v_exp_f32_e32 v233, v233
	v_sub_f32_e32 v234, v234, v190
	v_add_f32_e32 v254, v232, v254
	s_waitcnt lgkmcnt(8)
	v_mfma_f32_32x32x16_bf16 v[64:79], v[210:213], v[242:245], v[64:79]
	ds_read_b64_tr_b16 v[210:211], v205 offset:24576
	ds_read_b64_tr_b16 v[212:213], v205 offset:28672
	v_exp_f32_e32 v234, v234
	v_sub_f32_e32 v235, v235, v190
	v_add_f32_e32 v254, v233, v254
	v_exp_f32_e32 v235, v235
	s_waitcnt lgkmcnt(8)
	v_mfma_f32_32x32x16_bf16 v[48:63], v[214:217], v[242:245], v[48:63]
	ds_read_b64_tr_b16 v[214:215], v218 offset:24576
	ds_read_b64_tr_b16 v[216:217], v218 offset:28672
	v_sub_f32_e32 v236, v236, v190
	v_add_f32_e32 v254, v234, v254
	v_exp_f32_e32 v236, v236
	v_sub_f32_e32 v237, v237, v190
	s_waitcnt lgkmcnt(8)
	v_mfma_f32_32x32x16_bf16 v[32:47], v[238:241], v[242:245], v[32:47]
	ds_read_b64_tr_b16 v[238:239], v219 offset:24576
	ds_read_b64_tr_b16 v[240:241], v219 offset:28672
	v_add_f32_e32 v254, v235, v254
	v_exp_f32_e32 v237, v237
	v_add_f32_e32 v254, v236, v254
	v_add_f32_e32 v254, v237, v254
	s_waitcnt lgkmcnt(8)
	v_mfma_f32_32x32x16_bf16 v[16:31], v[128:131], v[242:245], v[16:31]
	ds_read_b64_tr_b16 v[128:129], v221 offset:24576
	ds_read_b64_tr_b16 v[130:131], v221 offset:28672
	v_cvt_pk_bf16_f32 v250, v230, v231
	v_cvt_pk_bf16_f32 v251, v232, v233
	v_cvt_pk_bf16_f32 v252, v234, v235
	v_cvt_pk_bf16_f32 v253, v236, v237
	v_add_f32_e32 v202, v202, v254
	s_waitcnt lgkmcnt(8)
	v_mfma_f32_32x32x16_bf16 v[0:15], v[206:209], v[242:245], v[0:15]
	ds_read_b64_tr_b16 v[206:207], v205 offset:24832
	ds_read_b64_tr_b16 v[208:209], v205 offset:28928
	s_waitcnt lgkmcnt(8)
	v_mfma_f32_32x32x16_bf16 v[112:127], v[210:213], v[250:253], v[112:127]
	ds_read_b64_tr_b16 v[210:211], v218 offset:24832
	ds_read_b64_tr_b16 v[212:213], v218 offset:28928
	s_waitcnt lgkmcnt(8)
	v_mfma_f32_32x32x16_bf16 v[96:111], v[214:217], v[250:253], v[96:111]
	ds_read_b64_tr_b16 v[214:215], v219 offset:24832
	ds_read_b64_tr_b16 v[216:217], v219 offset:28928
	s_waitcnt lgkmcnt(8)
	v_mfma_f32_32x32x16_bf16 v[80:95], v[238:241], v[250:253], v[80:95]
	ds_read_b64_tr_b16 v[238:239], v221 offset:24832
	ds_read_b64_tr_b16 v[240:241], v221 offset:28928
	s_waitcnt lgkmcnt(8)
	v_mfma_f32_32x32x16_bf16 v[64:79], v[128:131], v[250:253], v[64:79]
	s_waitcnt lgkmcnt(6)
	v_mfma_f32_32x32x16_bf16 v[48:63], v[206:209], v[250:253], v[48:63]
	s_waitcnt lgkmcnt(4)
	v_mfma_f32_32x32x16_bf16 v[32:47], v[210:213], v[250:253], v[32:47]
	s_waitcnt lgkmcnt(2)
	v_mfma_f32_32x32x16_bf16 v[16:31], v[214:217], v[250:253], v[16:31]
	s_waitcnt lgkmcnt(0)
	v_mfma_f32_32x32x16_bf16 v[0:15], v[238:241], v[250:253], v[0:15]
	ds_read_b128 v[206:209], v194 offset:32768
	ds_read_b128 v[210:213], v195 offset:32768
	ds_read_b128 v[214:217], v196 offset:32768
	ds_read_b128 v[238:241], v197 offset:32768
	ds_read_b128 v[242:245], v198 offset:32768
	ds_read_b128 v[250:253], v199 offset:32768
	ds_read_b128 v[222:225], v200 offset:32768
	ds_read_b128 v[226:229], v201 offset:32768
	s_waitcnt vmcnt(0)
	s_add_i32 s18, s88, 1
	s_cmp_lg_u32 s88, 2
	s_cselect_b32 s88, s18, 0
	s_add_i32 s43, s43, 64
	s_add_u32 s14, s14, 0x100000
	s_addc_u32 s15, s15, 0
	s_add_i32 s42, s42, 1
	s_add_i32 s100, s43, 63
	s_cmp_le_i32 s100, s83
	s_cbranch_scc0 .Latt_latchb_0
	s_cmp_ge_u32 s42, s82
	s_cselect_b64 s[18:19], -1, 0
	v_mov_b32_e32 v203, v176
	s_barrier
	s_branch .Latt_cont_0s2
.Latt_rs1_0s1:
	s_waitcnt lgkmcnt(8)
	v_mfma_f32_32x32x16_bf16 v[64:79], v[238:241], v[250:253], v[64:79]
	ds_read_b64_tr_b16 v[238:239], v205 offset:16384
	ds_read_b64_tr_b16 v[240:241], v205 offset:20480
	s_waitcnt lgkmcnt(8)
	v_mfma_f32_32x32x16_bf16 v[48:63], v[128:131], v[250:253], v[48:63]
	ds_read_b64_tr_b16 v[128:129], v218 offset:16384
	ds_read_b64_tr_b16 v[130:131], v218 offset:20480
	s_waitcnt lgkmcnt(8)
	v_mfma_f32_32x32x16_bf16 v[32:47], v[206:209], v[250:253], v[32:47]
	ds_read_b64_tr_b16 v[206:207], v219 offset:16384
	ds_read_b64_tr_b16 v[208:209], v219 offset:20480
	s_waitcnt lgkmcnt(8)
	v_mfma_f32_32x32x16_bf16 v[16:31], v[210:213], v[250:253], v[16:31]
	ds_read_b64_tr_b16 v[210:211], v221 offset:16384
	ds_read_b64_tr_b16 v[212:213], v221 offset:20480
	s_waitcnt lgkmcnt(8)
	v_mfma_f32_32x32x16_bf16 v[0:15], v[214:217], v[250:253], v[0:15]
	ds_read_b64_tr_b16 v[214:215], v205 offset:16640
	ds_read_b64_tr_b16 v[216:217], v205 offset:20736
	s_nop 11
	v_max_f32_e32 v246, v190, v246
	v_sub_f32_e32 v190, v190, v246
	v_exp_f32_e32 v190, v190
	s_nop 0
	v_pk_mul_f32 v[126:127], v[126:127], v[190:191] op_sel_hi:[1,0]
	v_pk_mul_f32 v[124:125], v[124:125], v[190:191] op_sel_hi:[1,0]
	v_pk_mul_f32 v[122:123], v[122:123], v[190:191] op_sel_hi:[1,0]
	v_pk_mul_f32 v[120:121], v[120:121], v[190:191] op_sel_hi:[1,0]
	v_pk_mul_f32 v[118:119], v[118:119], v[190:191] op_sel_hi:[1,0]
	v_pk_mul_f32 v[116:117], v[116:117], v[190:191] op_sel_hi:[1,0]
	v_pk_mul_f32 v[114:115], v[114:115], v[190:191] op_sel_hi:[1,0]
	v_pk_mul_f32 v[112:113], v[112:113], v[190:191] op_sel_hi:[1,0]
	v_pk_mul_f32 v[110:111], v[110:111], v[190:191] op_sel_hi:[1,0]
	v_pk_mul_f32 v[108:109], v[108:109], v[190:191] op_sel_hi:[1,0]
	v_pk_mul_f32 v[106:107], v[106:107], v[190:191] op_sel_hi:[1,0]
	v_pk_mul_f32 v[104:105], v[104:105], v[190:191] op_sel_hi:[1,0]
	v_pk_mul_f32 v[102:103], v[102:103], v[190:191] op_sel_hi:[1,0]
	v_pk_mul_f32 v[100:101], v[100:101], v[190:191] op_sel_hi:[1,0]
	v_pk_mul_f32 v[98:99], v[98:99], v[190:191] op_sel_hi:[1,0]
	v_pk_mul_f32 v[96:97], v[96:97], v[190:191] op_sel_hi:[1,0]
	v_pk_mul_f32 v[94:95], v[94:95], v[190:191] op_sel_hi:[1,0]
	v_pk_mul_f32 v[92:93], v[92:93], v[190:191] op_sel_hi:[1,0]
	v_pk_mul_f32 v[90:91], v[90:91], v[190:191] op_sel_hi:[1,0]
	v_pk_mul_f32 v[88:89], v[88:89], v[190:191] op_sel_hi:[1,0]
	v_pk_mul_f32 v[86:87], v[86:87], v[190:191] op_sel_hi:[1,0]
	v_pk_mul_f32 v[84:85], v[84:85], v[190:191] op_sel_hi:[1,0]
	v_pk_mul_f32 v[82:83], v[82:83], v[190:191] op_sel_hi:[1,0]
	v_pk_mul_f32 v[80:81], v[80:81], v[190:191] op_sel_hi:[1,0]
	v_pk_mul_f32 v[78:79], v[78:79], v[190:191] op_sel_hi:[1,0]
	v_pk_mul_f32 v[76:77], v[76:77], v[190:191] op_sel_hi:[1,0]
	v_pk_mul_f32 v[74:75], v[74:75], v[190:191] op_sel_hi:[1,0]
	v_pk_mul_f32 v[72:73], v[72:73], v[190:191] op_sel_hi:[1,0]
	v_pk_mul_f32 v[70:71], v[70:71], v[190:191] op_sel_hi:[1,0]
	v_pk_mul_f32 v[68:69], v[68:69], v[190:191] op_sel_hi:[1,0]
	v_pk_mul_f32 v[66:67], v[66:67], v[190:191] op_sel_hi:[1,0]
	v_pk_mul_f32 v[64:65], v[64:65], v[190:191] op_sel_hi:[1,0]
	v_pk_mul_f32 v[62:63], v[62:63], v[190:191] op_sel_hi:[1,0]
	v_pk_mul_f32 v[60:61], v[60:61], v[190:191] op_sel_hi:[1,0]
	v_pk_mul_f32 v[58:59], v[58:59], v[190:191] op_sel_hi:[1,0]
	v_pk_mul_f32 v[56:57], v[56:57], v[190:191] op_sel_hi:[1,0]
	v_pk_mul_f32 v[54:55], v[54:55], v[190:191] op_sel_hi:[1,0]
	v_pk_mul_f32 v[52:53], v[52:53], v[190:191] op_sel_hi:[1,0]
	v_pk_mul_f32 v[50:51], v[50:51], v[190:191] op_sel_hi:[1,0]
	v_pk_mul_f32 v[48:49], v[48:49], v[190:191] op_sel_hi:[1,0]
	v_pk_mul_f32 v[46:47], v[46:47], v[190:191] op_sel_hi:[1,0]
	v_pk_mul_f32 v[44:45], v[44:45], v[190:191] op_sel_hi:[1,0]
	v_pk_mul_f32 v[42:43], v[42:43], v[190:191] op_sel_hi:[1,0]
	v_pk_mul_f32 v[40:41], v[40:41], v[190:191] op_sel_hi:[1,0]
	v_pk_mul_f32 v[38:39], v[38:39], v[190:191] op_sel_hi:[1,0]
	v_pk_mul_f32 v[36:37], v[36:37], v[190:191] op_sel_hi:[1,0]
	v_pk_mul_f32 v[34:35], v[34:35], v[190:191] op_sel_hi:[1,0]
	v_pk_mul_f32 v[32:33], v[32:33], v[190:191] op_sel_hi:[1,0]
	v_pk_mul_f32 v[30:31], v[30:31], v[190:191] op_sel_hi:[1,0]
	v_pk_mul_f32 v[28:29], v[28:29], v[190:191] op_sel_hi:[1,0]
	v_pk_mul_f32 v[26:27], v[26:27], v[190:191] op_sel_hi:[1,0]
	v_pk_mul_f32 v[24:25], v[24:25], v[190:191] op_sel_hi:[1,0]
	v_pk_mul_f32 v[22:23], v[22:23], v[190:191] op_sel_hi:[1,0]
	v_pk_mul_f32 v[20:21], v[20:21], v[190:191] op_sel_hi:[1,0]
	v_pk_mul_f32 v[18:19], v[18:19], v[190:191] op_sel_hi:[1,0]
	v_pk_mul_f32 v[16:17], v[16:17], v[190:191] op_sel_hi:[1,0]
	v_pk_mul_f32 v[14:15], v[14:15], v[190:191] op_sel_hi:[1,0]
	v_pk_mul_f32 v[12:13], v[12:13], v[190:191] op_sel_hi:[1,0]
	v_pk_mul_f32 v[10:11], v[10:11], v[190:191] op_sel_hi:[1,0]
	v_pk_mul_f32 v[8:9], v[8:9], v[190:191] op_sel_hi:[1,0]
	v_pk_mul_f32 v[6:7], v[6:7], v[190:191] op_sel_hi:[1,0]
	v_pk_mul_f32 v[4:5], v[4:5], v[190:191] op_sel_hi:[1,0]
	v_pk_mul_f32 v[2:3], v[2:3], v[190:191] op_sel_hi:[1,0]
	v_pk_mul_f32 v[0:1], v[0:1], v[190:191] op_sel_hi:[1,0]
	v_mul_f32_e32 v202, v202, v190
	v_mov_b32_e32 v190, v246
	v_sub_f32_e32 v222, v222, v190
	v_exp_f32_e32 v222, v222
	v_sub_f32_e32 v223, v223, v190
	v_exp_f32_e32 v223, v223
	v_sub_f32_e32 v224, v224, v190
	v_add_f32_e32 v254, 0, v222
	v_exp_f32_e32 v224, v224
	v_sub_f32_e32 v225, v225, v190
	v_add_f32_e32 v254, v223, v254
	v_exp_f32_e32 v225, v225
	v_sub_f32_e32 v226, v226, v190
	v_add_f32_e32 v254, v224, v254
	v_exp_f32_e32 v226, v226
	v_sub_f32_e32 v227, v227, v190
	v_add_f32_e32 v254, v225, v254
	v_exp_f32_e32 v227, v227
	v_sub_f32_e32 v228, v228, v190
	v_add_f32_e32 v254, v226, v254
	v_exp_f32_e32 v228, v228
	v_sub_f32_e32 v229, v229, v190
	v_add_f32_e32 v254, v227, v254
	v_exp_f32_e32 v229, v229
	v_sub_f32_e32 v230, v230, v190
	v_add_f32_e32 v254, v228, v254
	v_exp_f32_e32 v230, v230
	v_sub_f32_e32 v231, v231, v190
	v_add_f32_e32 v254, v229, v254
	v_exp_f32_e32 v231, v231
	v_sub_f32_e32 v232, v232, v190
	v_add_f32_e32 v254, v230, v254
	v_exp_f32_e32 v232, v232
	v_sub_f32_e32 v233, v233, v190
	v_add_f32_e32 v254, v231, v254
	v_exp_f32_e32 v233, v233
	v_sub_f32_e32 v234, v234, v190
	v_add_f32_e32 v254, v232, v254
	v_exp_f32_e32 v234, v234
	v_sub_f32_e32 v235, v235, v190
	v_add_f32_e32 v254, v233, v254
	v_exp_f32_e32 v235, v235
	v_sub_f32_e32 v236, v236, v190
	v_add_f32_e32 v254, v234, v254
	v_exp_f32_e32 v236, v236
	v_sub_f32_e32 v237, v237, v190
	v_add_f32_e32 v254, v235, v254
	v_exp_f32_e32 v237, v237
	v_add_f32_e32 v254, v236, v254
	v_add_f32_e32 v254, v237, v254
	v_cvt_pk_bf16_f32 v242, v222, v223
	v_cvt_pk_bf16_f32 v243, v224, v225
	v_cvt_pk_bf16_f32 v244, v226, v227
	v_cvt_pk_bf16_f32 v245, v228, v229
	v_cvt_pk_bf16_f32 v250, v230, v231
	v_cvt_pk_bf16_f32 v251, v232, v233
	v_cvt_pk_bf16_f32 v252, v234, v235
	v_cvt_pk_bf16_f32 v253, v236, v237
	v_add_f32_e32 v202, v202, v254
	s_nop 1
	s_waitcnt lgkmcnt(8)
	v_mfma_f32_32x32x16_bf16 v[112:127], v[238:241], v[242:245], v[112:127]
	ds_read_b64_tr_b16 v[238:239], v218 offset:16640
	ds_read_b64_tr_b16 v[240:241], v218 offset:20736
	s_waitcnt lgkmcnt(8)
	v_mfma_f32_32x32x16_bf16 v[96:111], v[128:131], v[242:245], v[96:111]
	ds_read_b64_tr_b16 v[222:223], v219 offset:16640
	ds_read_b64_tr_b16 v[224:225], v219 offset:20736
	s_waitcnt lgkmcnt(8)
	v_mfma_f32_32x32x16_bf16 v[80:95], v[206:209], v[242:245], v[80:95]
	ds_read_b64_tr_b16 v[206:207], v221 offset:16640
	ds_read_b64_tr_b16 v[208:209], v221 offset:20736
	s_waitcnt lgkmcnt(8)
	v_mfma_f32_32x32x16_bf16 v[64:79], v[210:213], v[242:245], v[64:79]
	ds_read_b64_tr_b16 v[210:211], v205 offset:24576
	ds_read_b64_tr_b16 v[212:213], v205 offset:28672
	s_waitcnt lgkmcnt(8)
	v_mfma_f32_32x32x16_bf16 v[48:63], v[214:217], v[242:245], v[48:63]
	ds_read_b64_tr_b16 v[214:215], v218 offset:24576
	ds_read_b64_tr_b16 v[216:217], v218 offset:28672
	s_waitcnt lgkmcnt(8)
	v_mfma_f32_32x32x16_bf16 v[32:47], v[238:241], v[242:245], v[32:47]
	ds_read_b64_tr_b16 v[238:239], v219 offset:24576
	ds_read_b64_tr_b16 v[240:241], v219 offset:28672
	s_waitcnt lgkmcnt(8)
	v_mfma_f32_32x32x16_bf16 v[16:31], v[222:225], v[242:245], v[16:31]
	ds_read_b64_tr_b16 v[222:223], v221 offset:24576
	ds_read_b64_tr_b16 v[224:225], v221 offset:28672
	s_waitcnt lgkmcnt(8)
	v_mfma_f32_32x32x16_bf16 v[0:15], v[206:209], v[242:245], v[0:15]
	ds_read_b64_tr_b16 v[206:207], v205 offset:24832
	ds_read_b64_tr_b16 v[208:209], v205 offset:28928
	s_waitcnt lgkmcnt(8)
	v_mfma_f32_32x32x16_bf16 v[112:127], v[210:213], v[250:253], v[112:127]
	ds_read_b64_tr_b16 v[210:211], v218 offset:24832
	ds_read_b64_tr_b16 v[212:213], v218 offset:28928
	s_waitcnt lgkmcnt(8)
	v_mfma_f32_32x32x16_bf16 v[96:111], v[214:217], v[250:253], v[96:111]
	ds_read_b64_tr_b16 v[214:215], v219 offset:24832
	ds_read_b64_tr_b16 v[216:217], v219 offset:28928
	s_waitcnt lgkmcnt(8)
	v_mfma_f32_32x32x16_bf16 v[80:95], v[238:241], v[250:253], v[80:95]
	ds_read_b64_tr_b16 v[238:239], v221 offset:24832
	ds_read_b64_tr_b16 v[240:241], v221 offset:28928
	s_waitcnt lgkmcnt(8)
	v_mfma_f32_32x32x16_bf16 v[64:79], v[222:225], v[250:253], v[64:79]
	s_waitcnt lgkmcnt(6)
	v_mfma_f32_32x32x16_bf16 v[48:63], v[206:209], v[250:253], v[48:63]
	s_waitcnt lgkmcnt(4)
	v_mfma_f32_32x32x16_bf16 v[32:47], v[210:213], v[250:253], v[32:47]
	s_waitcnt lgkmcnt(2)
	v_mfma_f32_32x32x16_bf16 v[16:31], v[214:217], v[250:253], v[16:31]
	s_waitcnt lgkmcnt(0)
	v_mfma_f32_32x32x16_bf16 v[0:15], v[238:241], v[250:253], v[0:15]
	ds_read_b128 v[206:209], v194 offset:32768
	ds_read_b128 v[210:213], v195 offset:32768
	ds_read_b128 v[214:217], v196 offset:32768
	ds_read_b128 v[238:241], v197 offset:32768
	ds_read_b128 v[242:245], v198 offset:32768
	ds_read_b128 v[250:253], v199 offset:32768
	ds_read_b128 v[222:225], v200 offset:32768
	ds_read_b128 v[226:229], v201 offset:32768
	s_waitcnt vmcnt(0)
	s_add_i32 s18, s88, 1
	s_cmp_lg_u32 s88, 2
	s_cselect_b32 s88, s18, 0
	s_add_i32 s43, s43, 64
	s_add_u32 s14, s14, 0x100000
	s_addc_u32 s15, s15, 0
	s_add_i32 s42, s42, 1
	s_add_i32 s100, s43, 63
	s_cmp_le_i32 s100, s83
	s_cbranch_scc0 .Latt_latchb_0
	s_cmp_ge_u32 s42, s82
	s_cselect_b64 s[18:19], -1, 0
	v_mov_b32_e32 v203, v176
	s_barrier
	s_branch .Latt_cont_0s2
.Latt_slow_0s1:
.Latt_slot2_0:
.Latt_cont_0s2:
	v_add_u32_e32 v205, 0x8000, v205
	v_add_u32_e32 v218, 0x8000, v218
	v_add_u32_e32 v219, 0x8000, v219
	v_add_u32_e32 v221, 0x8000, v221
	s_waitcnt lgkmcnt(7)
	v_mfma_f32_32x32x16_bf16 v[128:143], v[206:209], v[144:147], 0
	ds_read_b128 v[206:209], v194 offset:40960
	s_cmp_lg_u64 s[18:19], 0
	s_cbranch_scc1 .Latt_nd0_0s2
	s_sub_i32 s100, s88, 1
	s_cmp_eq_u32 s88, 0
	s_cselect_b32 s100, 2, s100
	s_lshl_b32 s101, s100, 14
	s_add_i32 m0, s85, s101
	s_nop 0
	global_load_lds_dwordx4 v178, s[14:15]

.Latt_nr0_0s2:
	s_waitcnt lgkmcnt(3)
	v_mfma_f32_32x32x16_bf16 v[222:237], v[214:217], v[152:155], v[222:237]
	ds_read_b128 v[214:217], v200 offset:40960
	v_sub_f32_e32 v128, v128, v190
	v_exp_f32_e32 v128, v128
	v_sub_f32_e32 v129, v129, v190
	v_exp_f32_e32 v129, v129
	v_sub_f32_e32 v130, v130, v190
	s_waitcnt lgkmcnt(3)
	v_mfma_f32_32x32x16_bf16 v[222:237], v[238:241], v[156:159], v[222:237]
	ds_read_b128 v[238:241], v201 offset:40960
	v_add_f32_e32 v254, 0, v128
	v_exp_f32_e32 v130, v130
	v_sub_f32_e32 v131, v131, v190
	v_add_f32_e32 v254, v129, v254
	v_exp_f32_e32 v131, v131
	s_waitcnt lgkmcnt(3)
	v_mfma_f32_32x32x16_bf16 v[222:237], v[206:209], v[160:163], v[222:237]
	ds_read_b64_tr_b16 v[206:207], v205
	ds_read_b64_tr_b16 v[208:209], v205 offset:4096
	v_sub_f32_e32 v132, v132, v190
	v_add_f32_e32 v254, v130, v254
	v_exp_f32_e32 v132, v132
	v_sub_f32_e32 v133, v133, v190
	v_add_f32_e32 v254, v131, v254
	s_waitcnt lgkmcnt(4)
	v_mfma_f32_32x32x16_bf16 v[222:237], v[210:213], v[164:167], v[222:237]
	ds_read_b64_tr_b16 v[210:211], v218
	ds_read_b64_tr_b16 v[212:213], v218 offset:4096
	v_exp_f32_e32 v133, v133
	v_sub_f32_e32 v134, v134, v190
	v_add_f32_e32 v254, v132, v254
	v_exp_f32_e32 v134, v134
	s_waitcnt lgkmcnt(5)
	v_mfma_f32_32x32x16_bf16 v[222:237], v[214:217], v[168:171], v[222:237]
	ds_read_b64_tr_b16 v[214:215], v219
	ds_read_b64_tr_b16 v[216:217], v219 offset:4096
	v_sub_f32_e32 v135, v135, v190
	v_add_f32_e32 v254, v133, v254
	v_exp_f32_e32 v135, v135
	s_nop 0
	s_waitcnt lgkmcnt(6)
	v_mfma_f32_32x32x16_bf16 v[222:237], v[238:241], v[172:175], v[222:237]
	ds_read_b64_tr_b16 v[238:239], v221
	ds_read_b64_tr_b16 v[240:241], v221 offset:4096
	v_cvt_pk_bf16_f32 v242, v128, v129
	v_cvt_pk_bf16_f32 v243, v130, v131
	v_cvt_pk_bf16_f32 v244, v132, v133
	v_cvt_pk_bf16_f32 v245, v134, v135
	s_nop 1
	s_waitcnt lgkmcnt(6)
	v_mfma_f32_32x32x16_bf16 v[112:127], v[206:209], v[242:245], v[112:127]
	ds_read_b64_tr_b16 v[206:207], v205 offset:256
	ds_read_b64_tr_b16 v[208:209], v205 offset:4352
	v_sub_f32_e32 v136, v136, v190
	v_add_f32_e32 v254, v134, v254
	v_exp_f32_e32 v136, v136
	v_sub_f32_e32 v137, v137, v190
	v_add_f32_e32 v254, v135, v254
	s_waitcnt lgkmcnt(6)
	v_mfma_f32_32x32x16_bf16 v[96:111], v[210:213], v[242:245], v[96:111]
	ds_read_b64_tr_b16 v[210:211], v218 offset:256
	ds_read_b64_tr_b16 v[212:213], v218 offset:4352
	v_exp_f32_e32 v137, v137
	v_sub_f32_e32 v138, v138, v190
	v_add_f32_e32 v254, v136, v254
	v_exp_f32_e32 v138, v138
	v_sub_f32_e32 v139, v139, v190
	s_waitcnt lgkmcnt(6)
	v_mfma_f32_32x32x16_bf16 v[80:95], v[214:217], v[242:245], v[80:95]
	ds_read_b64_tr_b16 v[214:215], v219 offset:256
	ds_read_b64_tr_b16 v[216:217], v219 offset:4352
	v_add_f32_e32 v254, v137, v254
	v_exp_f32_e32 v139, v139
	v_sub_f32_e32 v140, v140, v190
	v_add_f32_e32 v254, v138, v254
	s_waitcnt lgkmcnt(6)
	v_mfma_f32_32x32x16_bf16 v[64:79], v[238:241], v[242:245], v[64:79]
	ds_read_b64_tr_b16 v[238:239], v221 offset:256
	ds_read_b64_tr_b16 v[240:241], v221 offset:4352
	v_exp_f32_e32 v140, v140
	v_sub_f32_e32 v141, v141, v190
	v_add_f32_e32 v254, v139, v254
	v_exp_f32_e32 v141, v141
	s_waitcnt lgkmcnt(6)
	v_mfma_f32_32x32x16_bf16 v[48:63], v[206:209], v[242:245], v[48:63]
	ds_read_b64_tr_b16 v[206:207], v205 offset:8192
	ds_read_b64_tr_b16 v[208:209], v205 offset:12288
	v_sub_f32_e32 v142, v142, v190
	v_add_f32_e32 v254, v140, v254
	v_exp_f32_e32 v142, v142
	v_sub_f32_e32 v143, v143, v190
	s_waitcnt lgkmcnt(6)
	v_mfma_f32_32x32x16_bf16 v[32:47], v[210:213], v[242:245], v[32:47]
	ds_read_b64_tr_b16 v[210:211], v218 offset:8192
	ds_read_b64_tr_b16 v[212:213], v218 offset:12288
	v_add_f32_e32 v254, v141, v254
	v_exp_f32_e32 v143, v143
	v_add_f32_e32 v254, v142, v254
	v_add_f32_e32 v254, v143, v254
	s_waitcnt lgkmcnt(6)
	v_mfma_f32_32x32x16_bf16 v[16:31], v[214:217], v[242:245], v[16:31]
	ds_read_b64_tr_b16 v[214:215], v219 offset:8192
	ds_read_b64_tr_b16 v[216:217], v219 offset:12288
	v_cvt_pk_bf16_f32 v250, v136, v137
	v_cvt_pk_bf16_f32 v251, v138, v139
	v_cvt_pk_bf16_f32 v252, v140, v141
	v_cvt_pk_bf16_f32 v253, v142, v143
	v_add_f32_e32 v202, v202, v254
	s_waitcnt lgkmcnt(6)
	v_mfma_f32_32x32x16_bf16 v[0:15], v[238:241], v[242:245], v[0:15]
	ds_read_b64_tr_b16 v[238:239], v221 offset:8192
	ds_read_b64_tr_b16 v[240:241], v221 offset:12288
	ds_read_b64_tr_b16 v[128:129], v205 offset:8448
	ds_read_b64_tr_b16 v[130:131], v205 offset:12544
	s_waitcnt lgkmcnt(8)
	v_mfma_f32_32x32x16_bf16 v[112:127], v[206:209], v[250:253], v[112:127]
	ds_read_b64_tr_b16 v[206:207], v218 offset:8448
	ds_read_b64_tr_b16 v[208:209], v218 offset:12544
	v_max3_f32 v246, v222, v223, v224
	v_max3_f32 v247, v225, v226, v227
	v_max3_f32 v246, v246, v228, v229
	v_max3_f32 v247, v247, v230, v231
	v_max3_f32 v246, v246, v232, v233
	s_waitcnt lgkmcnt(8)
	v_mfma_f32_32x32x16_bf16 v[96:111], v[210:213], v[250:253], v[96:111]
	ds_read_b64_tr_b16 v[210:211], v219 offset:8448
	ds_read_b64_tr_b16 v[212:213], v219 offset:12544
	v_max3_f32 v247, v247, v234, v235
	v_max3_f32 v246, v246, v236, v237
	v_max_f32_e32 v246, v246, v247
	v_mov_b32_e32 v247, v246
	v_add_f32_e32 v249, 0x41000000, v190
	s_waitcnt lgkmcnt(8)
	v_mfma_f32_32x32x16_bf16 v[80:95], v[214:217], v[250:253], v[80:95]
	ds_read_b64_tr_b16 v[214:215], v221 offset:8448
	ds_read_b64_tr_b16 v[216:217], v221 offset:12544
	s_nop 1
	v_permlane32_swap_b32_e32 v246, v247
	v_max_f32_e32 v246, v246, v247
	v_cmp_gt_f32_e32 vcc, v246, v249
	s_cbranch_vccnz .Latt_rs1_0s2
	s_waitcnt lgkmcnt(8)
	v_mfma_f32_32x32x16_bf16 v[64:79], v[238:241], v[250:253], v[64:79]
	ds_read_b64_tr_b16 v[238:239], v205 offset:16384
	ds_read_b64_tr_b16 v[240:241], v205 offset:20480
	v_sub_f32_e32 v222, v222, v190
	v_exp_f32_e32 v222, v222
	v_sub_f32_e32 v223, v223, v190
	v_exp_f32_e32 v223, v223
	v_sub_f32_e32 v224, v224, v190
	v_add_f32_e32 v254, 0, v222
	s_waitcnt lgkmcnt(8)
	v_mfma_f32_32x32x16_bf16 v[48:63], v[128:131], v[250:253], v[48:63]
	ds_read_b64_tr_b16 v[128:129], v218 offset:16384
	ds_read_b64_tr_b16 v[130:131], v218 offset:20480
	v_exp_f32_e32 v224, v224
	v_sub_f32_e32 v225, v225, v190
	v_add_f32_e32 v254, v223, v254
	v_exp_f32_e32 v225, v225
	v_sub_f32_e32 v226, v226, v190
	v_add_f32_e32 v254, v224, v254
	s_waitcnt lgkmcnt(8)
	v_mfma_f32_32x32x16_bf16 v[32:47], v[206:209], v[250:253], v[32:47]
	ds_read_b64_tr_b16 v[206:207], v219 offset:16384
	ds_read_b64_tr_b16 v[208:209], v219 offset:20480
	v_exp_f32_e32 v226, v226
	v_sub_f32_e32 v227, v227, v190
	v_add_f32_e32 v254, v225, v254
	v_exp_f32_e32 v227, v227
	v_sub_f32_e32 v228, v228, v190
	s_waitcnt lgkmcnt(8)
	v_mfma_f32_32x32x16_bf16 v[16:31], v[210:213], v[250:253], v[16:31]
	ds_read_b64_tr_b16 v[210:211], v221 offset:16384
	ds_read_b64_tr_b16 v[212:213], v221 offset:20480
	v_add_f32_e32 v254, v226, v254
	v_exp_f32_e32 v228, v228
	v_sub_f32_e32 v229, v229, v190
	v_add_f32_e32 v254, v227, v254
	v_exp_f32_e32 v229, v229
	s_waitcnt lgkmcnt(8)
	v_mfma_f32_32x32x16_bf16 v[0:15], v[214:217], v[250:253], v[0:15]
	ds_read_b64_tr_b16 v[214:215], v205 offset:16640
	ds_read_b64_tr_b16 v[216:217], v205 offset:20736
	s_nop 0
	v_cvt_pk_bf16_f32 v242, v222, v223
	v_cvt_pk_bf16_f32 v243, v224, v225
	v_cvt_pk_bf16_f32 v244, v226, v227
	v_cvt_pk_bf16_f32 v245, v228, v229
	s_nop 1
	s_waitcnt lgkmcnt(8)
	v_mfma_f32_32x32x16_bf16 v[112:127], v[238:241], v[242:245], v[112:127]
	ds_read_b64_tr_b16 v[238:239], v218 offset:16640
	ds_read_b64_tr_b16 v[240:241], v218 offset:20736
	v_sub_f32_e32 v230, v230, v190
	v_add_f32_e32 v254, v228, v254
	v_exp_f32_e32 v230, v230
	v_sub_f32_e32 v231, v231, v190
	v_add_f32_e32 v254, v229, v254
	s_waitcnt lgkmcnt(8)
	v_mfma_f32_32x32x16_bf16 v[96:111], v[128:131], v[242:245], v[96:111]
	ds_read_b64_tr_b16 v[128:129], v219 offset:16640
	ds_read_b64_tr_b16 v[130:131], v219 offset:20736
	v_exp_f32_e32 v231, v231
	v_sub_f32_e32 v232, v232, v190
	v_add_f32_e32 v254, v230, v254
	v_exp_f32_e32 v232, v232
	v_sub_f32_e32 v233, v233, v190
	s_waitcnt lgkmcnt(8)
	v_mfma_f32_32x32x16_bf16 v[80:95], v[206:209], v[242:245], v[80:95]
	ds_read_b64_tr_b16 v[206:207], v221 offset:16640
	ds_read_b64_tr_b16 v[208:209], v221 offset:20736
	v_add_f32_e32 v254, v231, v254
	v_exp_f32_e32 v233, v233
	v_sub_f32_e32 v234, v234, v190
	v_add_f32_e32 v254, v232, v254
	s_waitcnt lgkmcnt(8)
	v_mfma_f32_32x32x16_bf16 v[64:79], v[210:213], v[242:245], v[64:79]
	ds_read_b64_tr_b16 v[210:211], v205 offset:24576
	ds_read_b64_tr_b16 v[212:213], v205 offset:28672
	v_exp_f32_e32 v234, v234
	v_sub_f32_e32 v235, v235, v190
	v_add_f32_e32 v254, v233, v254
	v_exp_f32_e32 v235, v235
	s_waitcnt lgkmcnt(8)
	v_mfma_f32_32x32x16_bf16 v[48:63], v[214:217], v[242:245], v[48:63]
	ds_read_b64_tr_b16 v[214:215], v218 offset:24576
	ds_read_b64_tr_b16 v[216:217], v218 offset:28672
	v_sub_f32_e32 v236, v236, v190
	v_add_f32_e32 v254, v234, v254
	v_exp_f32_e32 v236, v236
	v_sub_f32_e32 v237, v237, v190
	s_waitcnt lgkmcnt(8)
	v_mfma_f32_32x32x16_bf16 v[32:47], v[238:241], v[242:245], v[32:47]
	ds_read_b64_tr_b16 v[238:239], v219 offset:24576
	ds_read_b64_tr_b16 v[240:241], v219 offset:28672
	v_add_f32_e32 v254, v235, v254
	v_exp_f32_e32 v237, v237
	v_add_f32_e32 v254, v236, v254
	v_add_f32_e32 v254, v237, v254
	s_waitcnt lgkmcnt(8)
	v_mfma_f32_32x32x16_bf16 v[16:31], v[128:131], v[242:245], v[16:31]
	ds_read_b64_tr_b16 v[128:129], v221 offset:24576
	ds_read_b64_tr_b16 v[130:131], v221 offset:28672
	v_cvt_pk_bf16_f32 v250, v230, v231
	v_cvt_pk_bf16_f32 v251, v232, v233
	v_cvt_pk_bf16_f32 v252, v234, v235
	v_cvt_pk_bf16_f32 v253, v236, v237
	v_add_f32_e32 v202, v202, v254
	s_waitcnt lgkmcnt(8)
	v_mfma_f32_32x32x16_bf16 v[0:15], v[206:209], v[242:245], v[0:15]
	ds_read_b64_tr_b16 v[206:207], v205 offset:24832
	ds_read_b64_tr_b16 v[208:209], v205 offset:28928
	s_waitcnt lgkmcnt(8)
	v_mfma_f32_32x32x16_bf16 v[112:127], v[210:213], v[250:253], v[112:127]
	ds_read_b64_tr_b16 v[210:211], v218 offset:24832
	ds_read_b64_tr_b16 v[212:213], v218 offset:28928
	s_waitcnt lgkmcnt(8)
	v_mfma_f32_32x32x16_bf16 v[96:111], v[214:217], v[250:253], v[96:111]
	ds_read_b64_tr_b16 v[214:215], v219 offset:24832
	ds_read_b64_tr_b16 v[216:217], v219 offset:28928
	s_waitcnt lgkmcnt(8)
	v_mfma_f32_32x32x16_bf16 v[80:95], v[238:241], v[250:253], v[80:95]
	ds_read_b64_tr_b16 v[238:239], v221 offset:24832
	ds_read_b64_tr_b16 v[240:241], v221 offset:28928
	s_waitcnt lgkmcnt(8)
	v_mfma_f32_32x32x16_bf16 v[64:79], v[128:131], v[250:253], v[64:79]
	s_waitcnt lgkmcnt(6)
	v_mfma_f32_32x32x16_bf16 v[48:63], v[206:209], v[250:253], v[48:63]
	s_waitcnt lgkmcnt(4)
	v_mfma_f32_32x32x16_bf16 v[32:47], v[210:213], v[250:253], v[32:47]
	s_waitcnt lgkmcnt(2)
	v_mfma_f32_32x32x16_bf16 v[16:31], v[214:217], v[250:253], v[16:31]
	s_waitcnt lgkmcnt(0)
	v_mfma_f32_32x32x16_bf16 v[0:15], v[238:241], v[250:253], v[0:15]
	ds_read_b128 v[206:209], v194
	ds_read_b128 v[210:213], v195
	ds_read_b128 v[214:217], v196
	ds_read_b128 v[238:241], v197
	ds_read_b128 v[242:245], v198
	ds_read_b128 v[250:253], v199
	ds_read_b128 v[222:225], v200
	ds_read_b128 v[226:229], v201
	s_waitcnt vmcnt(0)
	s_add_i32 s18, s88, 1
	s_cmp_lg_u32 s88, 2
	s_cselect_b32 s88, s18, 0
	s_add_i32 s43, s43, 64
	s_add_u32 s14, s14, 0x100000
	s_addc_u32 s15, s15, 0
	s_add_i32 s42, s42, 1
	s_add_i32 s100, s43, 63
	s_cmp_le_i32 s100, s83
	s_cbranch_scc0 .Latt_latchb_0
	s_cmp_ge_u32 s42, s82
	s_cselect_b64 s[18:19], -1, 0
	v_mov_b32_e32 v203, v176
	s_barrier
	s_branch .Latt_cont_0s0
.Latt_rs1_0s2:
	s_waitcnt lgkmcnt(8)
	v_mfma_f32_32x32x16_bf16 v[64:79], v[238:241], v[250:253], v[64:79]
	ds_read_b64_tr_b16 v[238:239], v205 offset:16384
	ds_read_b64_tr_b16 v[240:241], v205 offset:20480
	s_waitcnt lgkmcnt(8)
	v_mfma_f32_32x32x16_bf16 v[48:63], v[128:131], v[250:253], v[48:63]
	ds_read_b64_tr_b16 v[128:129], v218 offset:16384
	ds_read_b64_tr_b16 v[130:131], v218 offset:20480
	s_waitcnt lgkmcnt(8)
	v_mfma_f32_32x32x16_bf16 v[32:47], v[206:209], v[250:253], v[32:47]
	ds_read_b64_tr_b16 v[206:207], v219 offset:16384
	ds_read_b64_tr_b16 v[208:209], v219 offset:20480
	s_waitcnt lgkmcnt(8)
	v_mfma_f32_32x32x16_bf16 v[16:31], v[210:213], v[250:253], v[16:31]
	ds_read_b64_tr_b16 v[210:211], v221 offset:16384
	ds_read_b64_tr_b16 v[212:213], v221 offset:20480
	s_waitcnt lgkmcnt(8)
	v_mfma_f32_32x32x16_bf16 v[0:15], v[214:217], v[250:253], v[0:15]
	ds_read_b64_tr_b16 v[214:215], v205 offset:16640
	ds_read_b64_tr_b16 v[216:217], v205 offset:20736
	s_nop 11
	v_max_f32_e32 v246, v190, v246
	v_sub_f32_e32 v190, v190, v246
	v_exp_f32_e32 v190, v190
	s_nop 0
	v_pk_mul_f32 v[126:127], v[126:127], v[190:191] op_sel_hi:[1,0]
	v_pk_mul_f32 v[124:125], v[124:125], v[190:191] op_sel_hi:[1,0]
	v_pk_mul_f32 v[122:123], v[122:123], v[190:191] op_sel_hi:[1,0]
	v_pk_mul_f32 v[120:121], v[120:121], v[190:191] op_sel_hi:[1,0]
	v_pk_mul_f32 v[118:119], v[118:119], v[190:191] op_sel_hi:[1,0]
	v_pk_mul_f32 v[116:117], v[116:117], v[190:191] op_sel_hi:[1,0]
	v_pk_mul_f32 v[114:115], v[114:115], v[190:191] op_sel_hi:[1,0]
	v_pk_mul_f32 v[112:113], v[112:113], v[190:191] op_sel_hi:[1,0]
	v_pk_mul_f32 v[110:111], v[110:111], v[190:191] op_sel_hi:[1,0]
	v_pk_mul_f32 v[108:109], v[108:109], v[190:191] op_sel_hi:[1,0]
	v_pk_mul_f32 v[106:107], v[106:107], v[190:191] op_sel_hi:[1,0]
	v_pk_mul_f32 v[104:105], v[104:105], v[190:191] op_sel_hi:[1,0]
	v_pk_mul_f32 v[102:103], v[102:103], v[190:191] op_sel_hi:[1,0]
	v_pk_mul_f32 v[100:101], v[100:101], v[190:191] op_sel_hi:[1,0]
	v_pk_mul_f32 v[98:99], v[98:99], v[190:191] op_sel_hi:[1,0]
	v_pk_mul_f32 v[96:97], v[96:97], v[190:191] op_sel_hi:[1,0]
	v_pk_mul_f32 v[94:95], v[94:95], v[190:191] op_sel_hi:[1,0]
	v_pk_mul_f32 v[92:93], v[92:93], v[190:191] op_sel_hi:[1,0]
	v_pk_mul_f32 v[90:91], v[90:91], v[190:191] op_sel_hi:[1,0]
	v_pk_mul_f32 v[88:89], v[88:89], v[190:191] op_sel_hi:[1,0]
	v_pk_mul_f32 v[86:87], v[86:87], v[190:191] op_sel_hi:[1,0]
	v_pk_mul_f32 v[84:85], v[84:85], v[190:191] op_sel_hi:[1,0]
	v_pk_mul_f32 v[82:83], v[82:83], v[190:191] op_sel_hi:[1,0]
	v_pk_mul_f32 v[80:81], v[80:81], v[190:191] op_sel_hi:[1,0]
	v_pk_mul_f32 v[78:79], v[78:79], v[190:191] op_sel_hi:[1,0]
	v_pk_mul_f32 v[76:77], v[76:77], v[190:191] op_sel_hi:[1,0]
	v_pk_mul_f32 v[74:75], v[74:75], v[190:191] op_sel_hi:[1,0]
	v_pk_mul_f32 v[72:73], v[72:73], v[190:191] op_sel_hi:[1,0]
	v_pk_mul_f32 v[70:71], v[70:71], v[190:191] op_sel_hi:[1,0]
	v_pk_mul_f32 v[68:69], v[68:69], v[190:191] op_sel_hi:[1,0]
	v_pk_mul_f32 v[66:67], v[66:67], v[190:191] op_sel_hi:[1,0]
	v_pk_mul_f32 v[64:65], v[64:65], v[190:191] op_sel_hi:[1,0]
	v_pk_mul_f32 v[62:63], v[62:63], v[190:191] op_sel_hi:[1,0]
	v_pk_mul_f32 v[60:61], v[60:61], v[190:191] op_sel_hi:[1,0]
	v_pk_mul_f32 v[58:59], v[58:59], v[190:191] op_sel_hi:[1,0]
	v_pk_mul_f32 v[56:57], v[56:57], v[190:191] op_sel_hi:[1,0]
	v_pk_mul_f32 v[54:55], v[54:55], v[190:191] op_sel_hi:[1,0]
	v_pk_mul_f32 v[52:53], v[52:53], v[190:191] op_sel_hi:[1,0]
	v_pk_mul_f32 v[50:51], v[50:51], v[190:191] op_sel_hi:[1,0]
	v_pk_mul_f32 v[48:49], v[48:49], v[190:191] op_sel_hi:[1,0]
	v_pk_mul_f32 v[46:47], v[46:47], v[190:191] op_sel_hi:[1,0]
	v_pk_mul_f32 v[44:45], v[44:45], v[190:191] op_sel_hi:[1,0]
	v_pk_mul_f32 v[42:43], v[42:43], v[190:191] op_sel_hi:[1,0]
	v_pk_mul_f32 v[40:41], v[40:41], v[190:191] op_sel_hi:[1,0]
	v_pk_mul_f32 v[38:39], v[38:39], v[190:191] op_sel_hi:[1,0]
	v_pk_mul_f32 v[36:37], v[36:37], v[190:191] op_sel_hi:[1,0]
	v_pk_mul_f32 v[34:35], v[34:35], v[190:191] op_sel_hi:[1,0]
	v_pk_mul_f32 v[32:33], v[32:33], v[190:191] op_sel_hi:[1,0]
	v_pk_mul_f32 v[30:31], v[30:31], v[190:191] op_sel_hi:[1,0]
	v_pk_mul_f32 v[28:29], v[28:29], v[190:191] op_sel_hi:[1,0]
	v_pk_mul_f32 v[26:27], v[26:27], v[190:191] op_sel_hi:[1,0]
	v_pk_mul_f32 v[24:25], v[24:25], v[190:191] op_sel_hi:[1,0]
	v_pk_mul_f32 v[22:23], v[22:23], v[190:191] op_sel_hi:[1,0]
	v_pk_mul_f32 v[20:21], v[20:21], v[190:191] op_sel_hi:[1,0]
	v_pk_mul_f32 v[18:19], v[18:19], v[190:191] op_sel_hi:[1,0]
	v_pk_mul_f32 v[16:17], v[16:17], v[190:191] op_sel_hi:[1,0]
	v_pk_mul_f32 v[14:15], v[14:15], v[190:191] op_sel_hi:[1,0]
	v_pk_mul_f32 v[12:13], v[12:13], v[190:191] op_sel_hi:[1,0]
	v_pk_mul_f32 v[10:11], v[10:11], v[190:191] op_sel_hi:[1,0]
	v_pk_mul_f32 v[8:9], v[8:9], v[190:191] op_sel_hi:[1,0]
	v_pk_mul_f32 v[6:7], v[6:7], v[190:191] op_sel_hi:[1,0]
	v_pk_mul_f32 v[4:5], v[4:5], v[190:191] op_sel_hi:[1,0]
	v_pk_mul_f32 v[2:3], v[2:3], v[190:191] op_sel_hi:[1,0]
	v_pk_mul_f32 v[0:1], v[0:1], v[190:191] op_sel_hi:[1,0]
	v_mul_f32_e32 v202, v202, v190
	v_mov_b32_e32 v190, v246
	v_sub_f32_e32 v222, v222, v190
	v_exp_f32_e32 v222, v222
	v_sub_f32_e32 v223, v223, v190
	v_exp_f32_e32 v223, v223
	v_sub_f32_e32 v224, v224, v190
	v_add_f32_e32 v254, 0, v222
	v_exp_f32_e32 v224, v224
	v_sub_f32_e32 v225, v225, v190
	v_add_f32_e32 v254, v223, v254
	v_exp_f32_e32 v225, v225
	v_sub_f32_e32 v226, v226, v190
	v_add_f32_e32 v254, v224, v254
	v_exp_f32_e32 v226, v226
	v_sub_f32_e32 v227, v227, v190
	v_add_f32_e32 v254, v225, v254
	v_exp_f32_e32 v227, v227
	v_sub_f32_e32 v228, v228, v190
	v_add_f32_e32 v254, v226, v254
	v_exp_f32_e32 v228, v228
	v_sub_f32_e32 v229, v229, v190
	v_add_f32_e32 v254, v227, v254
	v_exp_f32_e32 v229, v229
	v_sub_f32_e32 v230, v230, v190
	v_add_f32_e32 v254, v228, v254
	v_exp_f32_e32 v230, v230
	v_sub_f32_e32 v231, v231, v190
	v_add_f32_e32 v254, v229, v254
	v_exp_f32_e32 v231, v231
	v_sub_f32_e32 v232, v232, v190
	v_add_f32_e32 v254, v230, v254
	v_exp_f32_e32 v232, v232
	v_sub_f32_e32 v233, v233, v190
	v_add_f32_e32 v254, v231, v254
	v_exp_f32_e32 v233, v233
	v_sub_f32_e32 v234, v234, v190
	v_add_f32_e32 v254, v232, v254
	v_exp_f32_e32 v234, v234
	v_sub_f32_e32 v235, v235, v190
	v_add_f32_e32 v254, v233, v254
	v_exp_f32_e32 v235, v235
	v_sub_f32_e32 v236, v236, v190
	v_add_f32_e32 v254, v234, v254
	v_exp_f32_e32 v236, v236
	v_sub_f32_e32 v237, v237, v190
	v_add_f32_e32 v254, v235, v254
	v_exp_f32_e32 v237, v237
	v_add_f32_e32 v254, v236, v254
	v_add_f32_e32 v254, v237, v254
	v_cvt_pk_bf16_f32 v242, v222, v223
	v_cvt_pk_bf16_f32 v243, v224, v225
	v_cvt_pk_bf16_f32 v244, v226, v227
	v_cvt_pk_bf16_f32 v245, v228, v229
	v_cvt_pk_bf16_f32 v250, v230, v231
	v_cvt_pk_bf16_f32 v251, v232, v233
	v_cvt_pk_bf16_f32 v252, v234, v235
	v_cvt_pk_bf16_f32 v253, v236, v237
	v_add_f32_e32 v202, v202, v254
	s_nop 1
	s_waitcnt lgkmcnt(8)
	v_mfma_f32_32x32x16_bf16 v[112:127], v[238:241], v[242:245], v[112:127]
	ds_read_b64_tr_b16 v[238:239], v218 offset:16640
	ds_read_b64_tr_b16 v[240:241], v218 offset:20736
	s_waitcnt lgkmcnt(8)
	v_mfma_f32_32x32x16_bf16 v[96:111], v[128:131], v[242:245], v[96:111]
	ds_read_b64_tr_b16 v[222:223], v219 offset:16640
	ds_read_b64_tr_b16 v[224:225], v219 offset:20736
	s_waitcnt lgkmcnt(8)
	v_mfma_f32_32x32x16_bf16 v[80:95], v[206:209], v[242:245], v[80:95]
	ds_read_b64_tr_b16 v[206:207], v221 offset:16640
	ds_read_b64_tr_b16 v[208:209], v221 offset:20736
	s_waitcnt lgkmcnt(8)
	v_mfma_f32_32x32x16_bf16 v[64:79], v[210:213], v[242:245], v[64:79]
	ds_read_b64_tr_b16 v[210:211], v205 offset:24576
	ds_read_b64_tr_b16 v[212:213], v205 offset:28672
	s_waitcnt lgkmcnt(8)
	v_mfma_f32_32x32x16_bf16 v[48:63], v[214:217], v[242:245], v[48:63]
	ds_read_b64_tr_b16 v[214:215], v218 offset:24576
	ds_read_b64_tr_b16 v[216:217], v218 offset:28672
	s_waitcnt lgkmcnt(8)
	v_mfma_f32_32x32x16_bf16 v[32:47], v[238:241], v[242:245], v[32:47]
	ds_read_b64_tr_b16 v[238:239], v219 offset:24576
	ds_read_b64_tr_b16 v[240:241], v219 offset:28672
	s_waitcnt lgkmcnt(8)
	v_mfma_f32_32x32x16_bf16 v[16:31], v[222:225], v[242:245], v[16:31]
	ds_read_b64_tr_b16 v[222:223], v221 offset:24576
	ds_read_b64_tr_b16 v[224:225], v221 offset:28672
	s_waitcnt lgkmcnt(8)
	v_mfma_f32_32x32x16_bf16 v[0:15], v[206:209], v[242:245], v[0:15]
	ds_read_b64_tr_b16 v[206:207], v205 offset:24832
	ds_read_b64_tr_b16 v[208:209], v205 offset:28928
	s_waitcnt lgkmcnt(8)
	v_mfma_f32_32x32x16_bf16 v[112:127], v[210:213], v[250:253], v[112:127]
	ds_read_b64_tr_b16 v[210:211], v218 offset:24832
	ds_read_b64_tr_b16 v[212:213], v218 offset:28928
	s_waitcnt lgkmcnt(8)
	v_mfma_f32_32x32x16_bf16 v[96:111], v[214:217], v[250:253], v[96:111]
	ds_read_b64_tr_b16 v[214:215], v219 offset:24832
	ds_read_b64_tr_b16 v[216:217], v219 offset:28928
	s_waitcnt lgkmcnt(8)
	v_mfma_f32_32x32x16_bf16 v[80:95], v[238:241], v[250:253], v[80:95]
	ds_read_b64_tr_b16 v[238:239], v221 offset:24832
	ds_read_b64_tr_b16 v[240:241], v221 offset:28928
	s_waitcnt lgkmcnt(8)
	v_mfma_f32_32x32x16_bf16 v[64:79], v[222:225], v[250:253], v[64:79]
	s_waitcnt lgkmcnt(6)
	v_mfma_f32_32x32x16_bf16 v[48:63], v[206:209], v[250:253], v[48:63]
	s_waitcnt lgkmcnt(4)
	v_mfma_f32_32x32x16_bf16 v[32:47], v[210:213], v[250:253], v[32:47]
	s_waitcnt lgkmcnt(2)
	v_mfma_f32_32x32x16_bf16 v[16:31], v[214:217], v[250:253], v[16:31]
	s_waitcnt lgkmcnt(0)
	v_mfma_f32_32x32x16_bf16 v[0:15], v[238:241], v[250:253], v[0:15]
	ds_read_b128 v[206:209], v194
	ds_read_b128 v[210:213], v195
	ds_read_b128 v[214:217], v196
	ds_read_b128 v[238:241], v197
	ds_read_b128 v[242:245], v198
	ds_read_b128 v[250:253], v199
	ds_read_b128 v[222:225], v200
	ds_read_b128 v[226:229], v201
	s_waitcnt vmcnt(0)
	s_add_i32 s18, s88, 1
	s_cmp_lg_u32 s88, 2
	s_cselect_b32 s88, s18, 0
	s_add_i32 s43, s43, 64
	s_add_u32 s14, s14, 0x100000
	s_addc_u32 s15, s15, 0
	s_add_i32 s42, s42, 1
	s_add_i32 s100, s43, 63
	s_cmp_le_i32 s100, s83
	s_cbranch_scc0 .Latt_latchb_0
	s_cmp_ge_u32 s42, s82
	s_cselect_b64 s[18:19], -1, 0
	v_mov_b32_e32 v203, v176
	s_barrier
	s_branch .Latt_cont_0s0

.Latt_latchb_1:
	s_waitcnt lgkmcnt(0)
	s_cmp_lg_u32 s87, s4
	s_barrier
	s_cbranch_scc0 .LBB0_881

.Latt_nr0_1s0:
	s_waitcnt lgkmcnt(3)
	v_mfma_f32_32x32x16_bf16 v[222:237], v[214:217], v[152:155], v[222:237]
	ds_read_b128 v[214:217], v202 offset:8192
	v_sub_f32_e32 v128, v128, v190
	v_exp_f32_e32 v128, v128
	v_sub_f32_e32 v129, v129, v190
	v_exp_f32_e32 v129, v129
	v_sub_f32_e32 v130, v130, v190
	s_waitcnt lgkmcnt(3)
	v_mfma_f32_32x32x16_bf16 v[222:237], v[238:241], v[156:159], v[222:237]
	ds_read_b128 v[238:241], v203 offset:8192
	v_add_f32_e32 v254, 0, v128
	v_exp_f32_e32 v130, v130
	v_sub_f32_e32 v131, v131, v190
	v_add_f32_e32 v254, v129, v254
	v_exp_f32_e32 v131, v131
	s_waitcnt lgkmcnt(3)
	v_mfma_f32_32x32x16_bf16 v[222:237], v[206:209], v[160:163], v[222:237]
	ds_read_b64_tr_b16 v[206:207], v205
	ds_read_b64_tr_b16 v[208:209], v205 offset:4096
	v_sub_f32_e32 v132, v132, v190
	v_add_f32_e32 v254, v130, v254
	v_exp_f32_e32 v132, v132
	v_sub_f32_e32 v133, v133, v190
	v_add_f32_e32 v254, v131, v254
	s_waitcnt lgkmcnt(4)
	v_mfma_f32_32x32x16_bf16 v[222:237], v[210:213], v[164:167], v[222:237]
	ds_read_b64_tr_b16 v[210:211], v218
	ds_read_b64_tr_b16 v[212:213], v218 offset:4096
	v_exp_f32_e32 v133, v133
	v_sub_f32_e32 v134, v134, v190
	v_add_f32_e32 v254, v132, v254
	v_exp_f32_e32 v134, v134
	s_waitcnt lgkmcnt(5)
	v_mfma_f32_32x32x16_bf16 v[222:237], v[214:217], v[168:171], v[222:237]
	ds_read_b64_tr_b16 v[214:215], v219
	ds_read_b64_tr_b16 v[216:217], v219 offset:4096
	v_sub_f32_e32 v135, v135, v190
	v_add_f32_e32 v254, v133, v254
	v_exp_f32_e32 v135, v135
	s_nop 0
	s_waitcnt lgkmcnt(6)
	v_mfma_f32_32x32x16_bf16 v[222:237], v[238:241], v[172:175], v[222:237]
	ds_read_b64_tr_b16 v[238:239], v221
	ds_read_b64_tr_b16 v[240:241], v221 offset:4096
	v_cvt_pk_bf16_f32 v242, v128, v129
	v_cvt_pk_bf16_f32 v243, v130, v131
	v_cvt_pk_bf16_f32 v244, v132, v133
	v_cvt_pk_bf16_f32 v245, v134, v135
	s_nop 1
	s_waitcnt lgkmcnt(6)
	v_mfma_f32_32x32x16_bf16 v[112:127], v[206:209], v[242:245], v[112:127]
	ds_read_b64_tr_b16 v[206:207], v205 offset:256
	ds_read_b64_tr_b16 v[208:209], v205 offset:4352
	v_sub_f32_e32 v136, v136, v190
	v_add_f32_e32 v254, v134, v254
	v_exp_f32_e32 v136, v136
	v_sub_f32_e32 v137, v137, v190
	v_add_f32_e32 v254, v135, v254
	s_waitcnt lgkmcnt(6)
	v_mfma_f32_32x32x16_bf16 v[96:111], v[210:213], v[242:245], v[96:111]
	ds_read_b64_tr_b16 v[210:211], v218 offset:256
	ds_read_b64_tr_b16 v[212:213], v218 offset:4352
	v_exp_f32_e32 v137, v137
	v_sub_f32_e32 v138, v138, v190
	v_add_f32_e32 v254, v136, v254
	v_exp_f32_e32 v138, v138
	v_sub_f32_e32 v139, v139, v190
	s_waitcnt lgkmcnt(6)
	v_mfma_f32_32x32x16_bf16 v[80:95], v[214:217], v[242:245], v[80:95]
	ds_read_b64_tr_b16 v[214:215], v219 offset:256
	ds_read_b64_tr_b16 v[216:217], v219 offset:4352
	v_add_f32_e32 v254, v137, v254
	v_exp_f32_e32 v139, v139
	v_sub_f32_e32 v140, v140, v190
	v_add_f32_e32 v254, v138, v254
	s_waitcnt lgkmcnt(6)
	v_mfma_f32_32x32x16_bf16 v[64:79], v[238:241], v[242:245], v[64:79]
	ds_read_b64_tr_b16 v[238:239], v221 offset:256
	ds_read_b64_tr_b16 v[240:241], v221 offset:4352
	v_exp_f32_e32 v140, v140
	v_sub_f32_e32 v141, v141, v190
	v_add_f32_e32 v254, v139, v254
	v_exp_f32_e32 v141, v141
	s_waitcnt lgkmcnt(6)
	v_mfma_f32_32x32x16_bf16 v[48:63], v[206:209], v[242:245], v[48:63]
	ds_read_b64_tr_b16 v[206:207], v205 offset:8192
	ds_read_b64_tr_b16 v[208:209], v205 offset:12288
	v_sub_f32_e32 v142, v142, v190
	v_add_f32_e32 v254, v140, v254
	v_exp_f32_e32 v142, v142
	v_sub_f32_e32 v143, v143, v190
	s_waitcnt lgkmcnt(6)
	v_mfma_f32_32x32x16_bf16 v[32:47], v[210:213], v[242:245], v[32:47]
	ds_read_b64_tr_b16 v[210:211], v218 offset:8192
	ds_read_b64_tr_b16 v[212:213], v218 offset:12288
	v_add_f32_e32 v254, v141, v254
	v_exp_f32_e32 v143, v143
	v_add_f32_e32 v254, v142, v254
	v_add_f32_e32 v254, v143, v254
	s_waitcnt lgkmcnt(6)
	v_mfma_f32_32x32x16_bf16 v[16:31], v[214:217], v[242:245], v[16:31]
	ds_read_b64_tr_b16 v[214:215], v219 offset:8192
	ds_read_b64_tr_b16 v[216:217], v219 offset:12288
	v_cvt_pk_bf16_f32 v250, v136, v137
	v_cvt_pk_bf16_f32 v251, v138, v139
	v_cvt_pk_bf16_f32 v252, v140, v141
	v_cvt_pk_bf16_f32 v253, v142, v143
	v_add_f32_e32 v195, v195, v254
	s_waitcnt lgkmcnt(6)
	v_mfma_f32_32x32x16_bf16 v[0:15], v[238:241], v[242:245], v[0:15]
	ds_read_b64_tr_b16 v[238:239], v221 offset:8192
	ds_read_b64_tr_b16 v[240:241], v221 offset:12288
	ds_read_b64_tr_b16 v[128:129], v205 offset:8448
	ds_read_b64_tr_b16 v[130:131], v205 offset:12544
	s_waitcnt lgkmcnt(8)
	v_mfma_f32_32x32x16_bf16 v[112:127], v[206:209], v[250:253], v[112:127]
	ds_read_b64_tr_b16 v[206:207], v218 offset:8448
	ds_read_b64_tr_b16 v[208:209], v218 offset:12544
	v_max3_f32 v246, v222, v223, v224
	v_max3_f32 v247, v225, v226, v227
	v_max3_f32 v246, v246, v228, v229
	v_max3_f32 v247, v247, v230, v231
	v_max3_f32 v246, v246, v232, v233
	s_waitcnt lgkmcnt(8)
	v_mfma_f32_32x32x16_bf16 v[96:111], v[210:213], v[250:253], v[96:111]
	ds_read_b64_tr_b16 v[210:211], v219 offset:8448
	ds_read_b64_tr_b16 v[212:213], v219 offset:12544
	v_max3_f32 v247, v247, v234, v235
	v_max3_f32 v246, v246, v236, v237
	v_max_f32_e32 v246, v246, v247
	v_mov_b32_e32 v247, v246
	v_add_f32_e32 v249, 0x41000000, v190
	s_waitcnt lgkmcnt(8)
	v_mfma_f32_32x32x16_bf16 v[80:95], v[214:217], v[250:253], v[80:95]
	ds_read_b64_tr_b16 v[214:215], v221 offset:8448
	ds_read_b64_tr_b16 v[216:217], v221 offset:12544
	s_nop 1
	v_permlane32_swap_b32_e32 v246, v247
	v_max_f32_e32 v246, v246, v247
	v_cmp_gt_f32_e32 vcc, v246, v249
	s_cbranch_vccnz .Latt_rs1_1s0
	s_waitcnt lgkmcnt(8)
	v_mfma_f32_32x32x16_bf16 v[64:79], v[238:241], v[250:253], v[64:79]
	ds_read_b64_tr_b16 v[238:239], v205 offset:16384
	ds_read_b64_tr_b16 v[240:241], v205 offset:20480
	v_sub_f32_e32 v222, v222, v190
	v_exp_f32_e32 v222, v222
	v_sub_f32_e32 v223, v223, v190
	v_exp_f32_e32 v223, v223
	v_sub_f32_e32 v224, v224, v190
	v_add_f32_e32 v254, 0, v222
	s_waitcnt lgkmcnt(8)
	v_mfma_f32_32x32x16_bf16 v[48:63], v[128:131], v[250:253], v[48:63]
	ds_read_b64_tr_b16 v[128:129], v218 offset:16384
	ds_read_b64_tr_b16 v[130:131], v218 offset:20480
	v_exp_f32_e32 v224, v224
	v_sub_f32_e32 v225, v225, v190
	v_add_f32_e32 v254, v223, v254
	v_exp_f32_e32 v225, v225
	v_sub_f32_e32 v226, v226, v190
	v_add_f32_e32 v254, v224, v254
	s_waitcnt lgkmcnt(8)
	v_mfma_f32_32x32x16_bf16 v[32:47], v[206:209], v[250:253], v[32:47]
	ds_read_b64_tr_b16 v[206:207], v219 offset:16384
	ds_read_b64_tr_b16 v[208:209], v219 offset:20480
	v_exp_f32_e32 v226, v226
	v_sub_f32_e32 v227, v227, v190
	v_add_f32_e32 v254, v225, v254
	v_exp_f32_e32 v227, v227
	v_sub_f32_e32 v228, v228, v190
	s_waitcnt lgkmcnt(8)
	v_mfma_f32_32x32x16_bf16 v[16:31], v[210:213], v[250:253], v[16:31]
	ds_read_b64_tr_b16 v[210:211], v221 offset:16384
	ds_read_b64_tr_b16 v[212:213], v221 offset:20480
	v_add_f32_e32 v254, v226, v254
	v_exp_f32_e32 v228, v228
	v_sub_f32_e32 v229, v229, v190
	v_add_f32_e32 v254, v227, v254
	v_exp_f32_e32 v229, v229
	s_waitcnt lgkmcnt(8)
	v_mfma_f32_32x32x16_bf16 v[0:15], v[214:217], v[250:253], v[0:15]
	ds_read_b64_tr_b16 v[214:215], v205 offset:16640
	ds_read_b64_tr_b16 v[216:217], v205 offset:20736
	s_nop 0
	v_cvt_pk_bf16_f32 v242, v222, v223
	v_cvt_pk_bf16_f32 v243, v224, v225
	v_cvt_pk_bf16_f32 v244, v226, v227
	v_cvt_pk_bf16_f32 v245, v228, v229
	s_nop 1
	s_waitcnt lgkmcnt(8)
	v_mfma_f32_32x32x16_bf16 v[112:127], v[238:241], v[242:245], v[112:127]
	ds_read_b64_tr_b16 v[238:239], v218 offset:16640
	ds_read_b64_tr_b16 v[240:241], v218 offset:20736
	v_sub_f32_e32 v230, v230, v190
	v_add_f32_e32 v254, v228, v254
	v_exp_f32_e32 v230, v230
	v_sub_f32_e32 v231, v231, v190
	v_add_f32_e32 v254, v229, v254
	s_waitcnt lgkmcnt(8)
	v_mfma_f32_32x32x16_bf16 v[96:111], v[128:131], v[242:245], v[96:111]
	ds_read_b64_tr_b16 v[128:129], v219 offset:16640
	ds_read_b64_tr_b16 v[130:131], v219 offset:20736
	v_exp_f32_e32 v231, v231
	v_sub_f32_e32 v232, v232, v190
	v_add_f32_e32 v254, v230, v254
	v_exp_f32_e32 v232, v232
	v_sub_f32_e32 v233, v233, v190
	s_waitcnt lgkmcnt(8)
	v_mfma_f32_32x32x16_bf16 v[80:95], v[206:209], v[242:245], v[80:95]
	ds_read_b64_tr_b16 v[206:207], v221 offset:16640
	ds_read_b64_tr_b16 v[208:209], v221 offset:20736
	v_add_f32_e32 v254, v231, v254
	v_exp_f32_e32 v233, v233
	v_sub_f32_e32 v234, v234, v190
	v_add_f32_e32 v254, v232, v254
	s_waitcnt lgkmcnt(8)
	v_mfma_f32_32x32x16_bf16 v[64:79], v[210:213], v[242:245], v[64:79]
	ds_read_b64_tr_b16 v[210:211], v205 offset:24576
	ds_read_b64_tr_b16 v[212:213], v205 offset:28672
	v_exp_f32_e32 v234, v234
	v_sub_f32_e32 v235, v235, v190
	v_add_f32_e32 v254, v233, v254
	v_exp_f32_e32 v235, v235
	s_waitcnt lgkmcnt(8)
	v_mfma_f32_32x32x16_bf16 v[48:63], v[214:217], v[242:245], v[48:63]
	ds_read_b64_tr_b16 v[214:215], v218 offset:24576
	ds_read_b64_tr_b16 v[216:217], v218 offset:28672
	v_sub_f32_e32 v236, v236, v190
	v_add_f32_e32 v254, v234, v254
	v_exp_f32_e32 v236, v236
	v_sub_f32_e32 v237, v237, v190
	s_waitcnt lgkmcnt(8)
	v_mfma_f32_32x32x16_bf16 v[32:47], v[238:241], v[242:245], v[32:47]
	ds_read_b64_tr_b16 v[238:239], v219 offset:24576
	ds_read_b64_tr_b16 v[240:241], v219 offset:28672
	v_add_f32_e32 v254, v235, v254
	v_exp_f32_e32 v237, v237
	v_add_f32_e32 v254, v236, v254
	v_add_f32_e32 v254, v237, v254
	s_waitcnt lgkmcnt(8)
	v_mfma_f32_32x32x16_bf16 v[16:31], v[128:131], v[242:245], v[16:31]
	ds_read_b64_tr_b16 v[128:129], v221 offset:24576
	ds_read_b64_tr_b16 v[130:131], v221 offset:28672
	v_cvt_pk_bf16_f32 v250, v230, v231
	v_cvt_pk_bf16_f32 v251, v232, v233
	v_cvt_pk_bf16_f32 v252, v234, v235
	v_cvt_pk_bf16_f32 v253, v236, v237
	v_add_f32_e32 v195, v195, v254
	s_waitcnt lgkmcnt(8)
	v_mfma_f32_32x32x16_bf16 v[0:15], v[206:209], v[242:245], v[0:15]
	ds_read_b64_tr_b16 v[206:207], v205 offset:24832
	ds_read_b64_tr_b16 v[208:209], v205 offset:28928
	s_waitcnt lgkmcnt(8)
	v_mfma_f32_32x32x16_bf16 v[112:127], v[210:213], v[250:253], v[112:127]
	ds_read_b64_tr_b16 v[210:211], v218 offset:24832
	ds_read_b64_tr_b16 v[212:213], v218 offset:28928
	s_waitcnt lgkmcnt(8)
	v_mfma_f32_32x32x16_bf16 v[96:111], v[214:217], v[250:253], v[96:111]
	ds_read_b64_tr_b16 v[214:215], v219 offset:24832
	ds_read_b64_tr_b16 v[216:217], v219 offset:28928
	s_waitcnt lgkmcnt(8)
	v_mfma_f32_32x32x16_bf16 v[80:95], v[238:241], v[250:253], v[80:95]
	ds_read_b64_tr_b16 v[238:239], v221 offset:24832
	ds_read_b64_tr_b16 v[240:241], v221 offset:28928
	s_waitcnt lgkmcnt(8)
	v_mfma_f32_32x32x16_bf16 v[64:79], v[128:131], v[250:253], v[64:79]
	s_waitcnt lgkmcnt(6)
	v_mfma_f32_32x32x16_bf16 v[48:63], v[206:209], v[250:253], v[48:63]
	s_waitcnt lgkmcnt(4)
	v_mfma_f32_32x32x16_bf16 v[32:47], v[210:213], v[250:253], v[32:47]
	s_waitcnt lgkmcnt(2)
	v_mfma_f32_32x32x16_bf16 v[16:31], v[214:217], v[250:253], v[16:31]
	s_waitcnt lgkmcnt(0)
	v_mfma_f32_32x32x16_bf16 v[0:15], v[238:241], v[250:253], v[0:15]
	ds_read_b128 v[206:209], v196 offset:16384
	ds_read_b128 v[210:213], v197 offset:16384
	ds_read_b128 v[214:217], v198 offset:16384
	ds_read_b128 v[238:241], v199 offset:16384
	ds_read_b128 v[242:245], v200 offset:16384
	ds_read_b128 v[250:253], v201 offset:16384
	ds_read_b128 v[222:225], v202 offset:16384
	ds_read_b128 v[226:229], v203 offset:16384
	s_waitcnt vmcnt(0)
	s_add_i32 s18, s33, 1
	s_cmp_lg_u32 s33, 2
	s_cselect_b32 s33, s18, 0
	s_add_i32 s4, s4, 64
	s_add_u32 s12, s12, 0x100000
	s_addc_u32 s13, s13, 0
	s_add_i32 s88, s88, 1
	s_add_i32 s100, s4, 63
	s_cmp_le_i32 s100, s83
	s_cbranch_scc0 .Latt_latchb_1
	s_cmp_ge_u32 s88, s82
	s_cselect_b64 s[18:19], -1, 0
	v_mov_b32_e32 v204, v176
	s_barrier
	s_branch .Latt_cont_1s1
.Latt_rs1_1s0:
	s_waitcnt lgkmcnt(8)
	v_mfma_f32_32x32x16_bf16 v[64:79], v[238:241], v[250:253], v[64:79]
	ds_read_b64_tr_b16 v[238:239], v205 offset:16384
	ds_read_b64_tr_b16 v[240:241], v205 offset:20480
	s_waitcnt lgkmcnt(8)
	v_mfma_f32_32x32x16_bf16 v[48:63], v[128:131], v[250:253], v[48:63]
	ds_read_b64_tr_b16 v[128:129], v218 offset:16384
	ds_read_b64_tr_b16 v[130:131], v218 offset:20480
	s_waitcnt lgkmcnt(8)
	v_mfma_f32_32x32x16_bf16 v[32:47], v[206:209], v[250:253], v[32:47]
	ds_read_b64_tr_b16 v[206:207], v219 offset:16384
	ds_read_b64_tr_b16 v[208:209], v219 offset:20480
	s_waitcnt lgkmcnt(8)
	v_mfma_f32_32x32x16_bf16 v[16:31], v[210:213], v[250:253], v[16:31]
	ds_read_b64_tr_b16 v[210:211], v221 offset:16384
	ds_read_b64_tr_b16 v[212:213], v221 offset:20480
	s_waitcnt lgkmcnt(8)
	v_mfma_f32_32x32x16_bf16 v[0:15], v[214:217], v[250:253], v[0:15]
	ds_read_b64_tr_b16 v[214:215], v205 offset:16640
	ds_read_b64_tr_b16 v[216:217], v205 offset:20736
	s_nop 11
	v_max_f32_e32 v246, v190, v246
	v_sub_f32_e32 v190, v190, v246
	v_exp_f32_e32 v190, v190
	s_nop 0
	v_pk_mul_f32 v[126:127], v[126:127], v[190:191] op_sel_hi:[1,0]
	v_pk_mul_f32 v[124:125], v[124:125], v[190:191] op_sel_hi:[1,0]
	v_pk_mul_f32 v[122:123], v[122:123], v[190:191] op_sel_hi:[1,0]
	v_pk_mul_f32 v[120:121], v[120:121], v[190:191] op_sel_hi:[1,0]
	v_pk_mul_f32 v[118:119], v[118:119], v[190:191] op_sel_hi:[1,0]
	v_pk_mul_f32 v[116:117], v[116:117], v[190:191] op_sel_hi:[1,0]
	v_pk_mul_f32 v[114:115], v[114:115], v[190:191] op_sel_hi:[1,0]
	v_pk_mul_f32 v[112:113], v[112:113], v[190:191] op_sel_hi:[1,0]
	v_pk_mul_f32 v[110:111], v[110:111], v[190:191] op_sel_hi:[1,0]
	v_pk_mul_f32 v[108:109], v[108:109], v[190:191] op_sel_hi:[1,0]
	v_pk_mul_f32 v[106:107], v[106:107], v[190:191] op_sel_hi:[1,0]
	v_pk_mul_f32 v[104:105], v[104:105], v[190:191] op_sel_hi:[1,0]
	v_pk_mul_f32 v[102:103], v[102:103], v[190:191] op_sel_hi:[1,0]
	v_pk_mul_f32 v[100:101], v[100:101], v[190:191] op_sel_hi:[1,0]
	v_pk_mul_f32 v[98:99], v[98:99], v[190:191] op_sel_hi:[1,0]
	v_pk_mul_f32 v[96:97], v[96:97], v[190:191] op_sel_hi:[1,0]
	v_pk_mul_f32 v[94:95], v[94:95], v[190:191] op_sel_hi:[1,0]
	v_pk_mul_f32 v[92:93], v[92:93], v[190:191] op_sel_hi:[1,0]
	v_pk_mul_f32 v[90:91], v[90:91], v[190:191] op_sel_hi:[1,0]
	v_pk_mul_f32 v[88:89], v[88:89], v[190:191] op_sel_hi:[1,0]
	v_pk_mul_f32 v[86:87], v[86:87], v[190:191] op_sel_hi:[1,0]
	v_pk_mul_f32 v[84:85], v[84:85], v[190:191] op_sel_hi:[1,0]
	v_pk_mul_f32 v[82:83], v[82:83], v[190:191] op_sel_hi:[1,0]
	v_pk_mul_f32 v[80:81], v[80:81], v[190:191] op_sel_hi:[1,0]
	v_pk_mul_f32 v[78:79], v[78:79], v[190:191] op_sel_hi:[1,0]
	v_pk_mul_f32 v[76:77], v[76:77], v[190:191] op_sel_hi:[1,0]
	v_pk_mul_f32 v[74:75], v[74:75], v[190:191] op_sel_hi:[1,0]
	v_pk_mul_f32 v[72:73], v[72:73], v[190:191] op_sel_hi:[1,0]
	v_pk_mul_f32 v[70:71], v[70:71], v[190:191] op_sel_hi:[1,0]
	v_pk_mul_f32 v[68:69], v[68:69], v[190:191] op_sel_hi:[1,0]
	v_pk_mul_f32 v[66:67], v[66:67], v[190:191] op_sel_hi:[1,0]
	v_pk_mul_f32 v[64:65], v[64:65], v[190:191] op_sel_hi:[1,0]
	v_pk_mul_f32 v[62:63], v[62:63], v[190:191] op_sel_hi:[1,0]
	v_pk_mul_f32 v[60:61], v[60:61], v[190:191] op_sel_hi:[1,0]
	v_pk_mul_f32 v[58:59], v[58:59], v[190:191] op_sel_hi:[1,0]
	v_pk_mul_f32 v[56:57], v[56:57], v[190:191] op_sel_hi:[1,0]
	v_pk_mul_f32 v[54:55], v[54:55], v[190:191] op_sel_hi:[1,0]
	v_pk_mul_f32 v[52:53], v[52:53], v[190:191] op_sel_hi:[1,0]
	v_pk_mul_f32 v[50:51], v[50:51], v[190:191] op_sel_hi:[1,0]
	v_pk_mul_f32 v[48:49], v[48:49], v[190:191] op_sel_hi:[1,0]
	v_pk_mul_f32 v[46:47], v[46:47], v[190:191] op_sel_hi:[1,0]
	v_pk_mul_f32 v[44:45], v[44:45], v[190:191] op_sel_hi:[1,0]
	v_pk_mul_f32 v[42:43], v[42:43], v[190:191] op_sel_hi:[1,0]
	v_pk_mul_f32 v[40:41], v[40:41], v[190:191] op_sel_hi:[1,0]
	v_pk_mul_f32 v[38:39], v[38:39], v[190:191] op_sel_hi:[1,0]
	v_pk_mul_f32 v[36:37], v[36:37], v[190:191] op_sel_hi:[1,0]
	v_pk_mul_f32 v[34:35], v[34:35], v[190:191] op_sel_hi:[1,0]
	v_pk_mul_f32 v[32:33], v[32:33], v[190:191] op_sel_hi:[1,0]
	v_pk_mul_f32 v[30:31], v[30:31], v[190:191] op_sel_hi:[1,0]
	v_pk_mul_f32 v[28:29], v[28:29], v[190:191] op_sel_hi:[1,0]
	v_pk_mul_f32 v[26:27], v[26:27], v[190:191] op_sel_hi:[1,0]
	v_pk_mul_f32 v[24:25], v[24:25], v[190:191] op_sel_hi:[1,0]
	v_pk_mul_f32 v[22:23], v[22:23], v[190:191] op_sel_hi:[1,0]
	v_pk_mul_f32 v[20:21], v[20:21], v[190:191] op_sel_hi:[1,0]
	v_pk_mul_f32 v[18:19], v[18:19], v[190:191] op_sel_hi:[1,0]
	v_pk_mul_f32 v[16:17], v[16:17], v[190:191] op_sel_hi:[1,0]
	v_pk_mul_f32 v[14:15], v[14:15], v[190:191] op_sel_hi:[1,0]
	v_pk_mul_f32 v[12:13], v[12:13], v[190:191] op_sel_hi:[1,0]
	v_pk_mul_f32 v[10:11], v[10:11], v[190:191] op_sel_hi:[1,0]
	v_pk_mul_f32 v[8:9], v[8:9], v[190:191] op_sel_hi:[1,0]
	v_pk_mul_f32 v[6:7], v[6:7], v[190:191] op_sel_hi:[1,0]
	v_pk_mul_f32 v[4:5], v[4:5], v[190:191] op_sel_hi:[1,0]
	v_pk_mul_f32 v[2:3], v[2:3], v[190:191] op_sel_hi:[1,0]
	v_pk_mul_f32 v[0:1], v[0:1], v[190:191] op_sel_hi:[1,0]
	v_mul_f32_e32 v195, v195, v190
	v_mov_b32_e32 v190, v246
	v_sub_f32_e32 v222, v222, v190
	v_exp_f32_e32 v222, v222
	v_sub_f32_e32 v223, v223, v190
	v_exp_f32_e32 v223, v223
	v_sub_f32_e32 v224, v224, v190
	v_add_f32_e32 v254, 0, v222
	v_exp_f32_e32 v224, v224
	v_sub_f32_e32 v225, v225, v190
	v_add_f32_e32 v254, v223, v254
	v_exp_f32_e32 v225, v225
	v_sub_f32_e32 v226, v226, v190
	v_add_f32_e32 v254, v224, v254
	v_exp_f32_e32 v226, v226
	v_sub_f32_e32 v227, v227, v190
	v_add_f32_e32 v254, v225, v254
	v_exp_f32_e32 v227, v227
	v_sub_f32_e32 v228, v228, v190
	v_add_f32_e32 v254, v226, v254
	v_exp_f32_e32 v228, v228
	v_sub_f32_e32 v229, v229, v190
	v_add_f32_e32 v254, v227, v254
	v_exp_f32_e32 v229, v229
	v_sub_f32_e32 v230, v230, v190
	v_add_f32_e32 v254, v228, v254
	v_exp_f32_e32 v230, v230
	v_sub_f32_e32 v231, v231, v190
	v_add_f32_e32 v254, v229, v254
	v_exp_f32_e32 v231, v231
	v_sub_f32_e32 v232, v232, v190
	v_add_f32_e32 v254, v230, v254
	v_exp_f32_e32 v232, v232
	v_sub_f32_e32 v233, v233, v190
	v_add_f32_e32 v254, v231, v254
	v_exp_f32_e32 v233, v233
	v_sub_f32_e32 v234, v234, v190
	v_add_f32_e32 v254, v232, v254
	v_exp_f32_e32 v234, v234
	v_sub_f32_e32 v235, v235, v190
	v_add_f32_e32 v254, v233, v254
	v_exp_f32_e32 v235, v235
	v_sub_f32_e32 v236, v236, v190
	v_add_f32_e32 v254, v234, v254
	v_exp_f32_e32 v236, v236
	v_sub_f32_e32 v237, v237, v190
	v_add_f32_e32 v254, v235, v254
	v_exp_f32_e32 v237, v237
	v_add_f32_e32 v254, v236, v254
	v_add_f32_e32 v254, v237, v254
	v_cvt_pk_bf16_f32 v242, v222, v223
	v_cvt_pk_bf16_f32 v243, v224, v225
	v_cvt_pk_bf16_f32 v244, v226, v227
	v_cvt_pk_bf16_f32 v245, v228, v229
	v_cvt_pk_bf16_f32 v250, v230, v231
	v_cvt_pk_bf16_f32 v251, v232, v233
	v_cvt_pk_bf16_f32 v252, v234, v235
	v_cvt_pk_bf16_f32 v253, v236, v237
	v_add_f32_e32 v195, v195, v254
	s_nop 1
	s_waitcnt lgkmcnt(8)
	v_mfma_f32_32x32x16_bf16 v[112:127], v[238:241], v[242:245], v[112:127]
	ds_read_b64_tr_b16 v[238:239], v218 offset:16640
	ds_read_b64_tr_b16 v[240:241], v218 offset:20736
	s_waitcnt lgkmcnt(8)
	v_mfma_f32_32x32x16_bf16 v[96:111], v[128:131], v[242:245], v[96:111]
	ds_read_b64_tr_b16 v[222:223], v219 offset:16640
	ds_read_b64_tr_b16 v[224:225], v219 offset:20736
	s_waitcnt lgkmcnt(8)
	v_mfma_f32_32x32x16_bf16 v[80:95], v[206:209], v[242:245], v[80:95]
	ds_read_b64_tr_b16 v[206:207], v221 offset:16640
	ds_read_b64_tr_b16 v[208:209], v221 offset:20736
	s_waitcnt lgkmcnt(8)
	v_mfma_f32_32x32x16_bf16 v[64:79], v[210:213], v[242:245], v[64:79]
	ds_read_b64_tr_b16 v[210:211], v205 offset:24576
	ds_read_b64_tr_b16 v[212:213], v205 offset:28672
	s_waitcnt lgkmcnt(8)
	v_mfma_f32_32x32x16_bf16 v[48:63], v[214:217], v[242:245], v[48:63]
	ds_read_b64_tr_b16 v[214:215], v218 offset:24576
	ds_read_b64_tr_b16 v[216:217], v218 offset:28672
	s_waitcnt lgkmcnt(8)
	v_mfma_f32_32x32x16_bf16 v[32:47], v[238:241], v[242:245], v[32:47]
	ds_read_b64_tr_b16 v[238:239], v219 offset:24576
	ds_read_b64_tr_b16 v[240:241], v219 offset:28672
	s_waitcnt lgkmcnt(8)
	v_mfma_f32_32x32x16_bf16 v[16:31], v[222:225], v[242:245], v[16:31]
	ds_read_b64_tr_b16 v[222:223], v221 offset:24576
	ds_read_b64_tr_b16 v[224:225], v221 offset:28672
	s_waitcnt lgkmcnt(8)
	v_mfma_f32_32x32x16_bf16 v[0:15], v[206:209], v[242:245], v[0:15]
	ds_read_b64_tr_b16 v[206:207], v205 offset:24832
	ds_read_b64_tr_b16 v[208:209], v205 offset:28928
	s_waitcnt lgkmcnt(8)
	v_mfma_f32_32x32x16_bf16 v[112:127], v[210:213], v[250:253], v[112:127]
	ds_read_b64_tr_b16 v[210:211], v218 offset:24832
	ds_read_b64_tr_b16 v[212:213], v218 offset:28928
	s_waitcnt lgkmcnt(8)
	v_mfma_f32_32x32x16_bf16 v[96:111], v[214:217], v[250:253], v[96:111]
	ds_read_b64_tr_b16 v[214:215], v219 offset:24832
	ds_read_b64_tr_b16 v[216:217], v219 offset:28928
	s_waitcnt lgkmcnt(8)
	v_mfma_f32_32x32x16_bf16 v[80:95], v[238:241], v[250:253], v[80:95]
	ds_read_b64_tr_b16 v[238:239], v221 offset:24832
	ds_read_b64_tr_b16 v[240:241], v221 offset:28928
	s_waitcnt lgkmcnt(8)
	v_mfma_f32_32x32x16_bf16 v[64:79], v[222:225], v[250:253], v[64:79]
	s_waitcnt lgkmcnt(6)
	v_mfma_f32_32x32x16_bf16 v[48:63], v[206:209], v[250:253], v[48:63]
	s_waitcnt lgkmcnt(4)
	v_mfma_f32_32x32x16_bf16 v[32:47], v[210:213], v[250:253], v[32:47]
	s_waitcnt lgkmcnt(2)
	v_mfma_f32_32x32x16_bf16 v[16:31], v[214:217], v[250:253], v[16:31]
	s_waitcnt lgkmcnt(0)
	v_mfma_f32_32x32x16_bf16 v[0:15], v[238:241], v[250:253], v[0:15]
	ds_read_b128 v[206:209], v196 offset:16384
	ds_read_b128 v[210:213], v197 offset:16384
	ds_read_b128 v[214:217], v198 offset:16384
	ds_read_b128 v[238:241], v199 offset:16384
	ds_read_b128 v[242:245], v200 offset:16384
	ds_read_b128 v[250:253], v201 offset:16384
	ds_read_b128 v[222:225], v202 offset:16384
	ds_read_b128 v[226:229], v203 offset:16384
	s_waitcnt vmcnt(0)
	s_add_i32 s18, s33, 1
	s_cmp_lg_u32 s33, 2
	s_cselect_b32 s33, s18, 0
	s_add_i32 s4, s4, 64
	s_add_u32 s12, s12, 0x100000
	s_addc_u32 s13, s13, 0
	s_add_i32 s88, s88, 1
	s_add_i32 s100, s4, 63
	s_cmp_le_i32 s100, s83
	s_cbranch_scc0 .Latt_latchb_1
	s_cmp_ge_u32 s88, s82
	s_cselect_b64 s[18:19], -1, 0
	v_mov_b32_e32 v204, v176
	s_barrier
	s_branch .Latt_cont_1s1
.Latt_slow_1s0:
.Latt_slot1_1:
.Latt_cont_1s1:
	v_add_u32_e32 v205, 0x8000, v205
	v_add_u32_e32 v218, 0x8000, v218
	v_add_u32_e32 v219, 0x8000, v219
	v_add_u32_e32 v221, 0x8000, v221
	s_waitcnt lgkmcnt(7)
	v_mfma_f32_32x32x16_bf16 v[128:143], v[206:209], v[144:147], 0
	ds_read_b128 v[206:209], v196 offset:24576
	s_cmp_lg_u64 s[18:19], 0
	s_cbranch_scc1 .Latt_nd0_1s1
	s_sub_i32 s100, s33, 1
	s_cmp_eq_u32 s33, 0
	s_cselect_b32 s100, 2, s100
	s_lshl_b32 s101, s100, 14
	s_add_i32 m0, s85, s101
	s_nop 0
	global_load_lds_dwordx4 v178, s[12:13]

.Latt_nr0_1s1:
	s_waitcnt lgkmcnt(3)
	v_mfma_f32_32x32x16_bf16 v[222:237], v[214:217], v[152:155], v[222:237]
	ds_read_b128 v[214:217], v202 offset:24576
	v_sub_f32_e32 v128, v128, v190
	v_exp_f32_e32 v128, v128
	v_sub_f32_e32 v129, v129, v190
	v_exp_f32_e32 v129, v129
	v_sub_f32_e32 v130, v130, v190
	s_waitcnt lgkmcnt(3)
	v_mfma_f32_32x32x16_bf16 v[222:237], v[238:241], v[156:159], v[222:237]
	ds_read_b128 v[238:241], v203 offset:24576
	v_add_f32_e32 v254, 0, v128
	v_exp_f32_e32 v130, v130
	v_sub_f32_e32 v131, v131, v190
	v_add_f32_e32 v254, v129, v254
	v_exp_f32_e32 v131, v131
	s_waitcnt lgkmcnt(3)
	v_mfma_f32_32x32x16_bf16 v[222:237], v[206:209], v[160:163], v[222:237]
	ds_read_b64_tr_b16 v[206:207], v205
	ds_read_b64_tr_b16 v[208:209], v205 offset:4096
	v_sub_f32_e32 v132, v132, v190
	v_add_f32_e32 v254, v130, v254
	v_exp_f32_e32 v132, v132
	v_sub_f32_e32 v133, v133, v190
	v_add_f32_e32 v254, v131, v254
	s_waitcnt lgkmcnt(4)
	v_mfma_f32_32x32x16_bf16 v[222:237], v[210:213], v[164:167], v[222:237]
	ds_read_b64_tr_b16 v[210:211], v218
	ds_read_b64_tr_b16 v[212:213], v218 offset:4096
	v_exp_f32_e32 v133, v133
	v_sub_f32_e32 v134, v134, v190
	v_add_f32_e32 v254, v132, v254
	v_exp_f32_e32 v134, v134
	s_waitcnt lgkmcnt(5)
	v_mfma_f32_32x32x16_bf16 v[222:237], v[214:217], v[168:171], v[222:237]
	ds_read_b64_tr_b16 v[214:215], v219
	ds_read_b64_tr_b16 v[216:217], v219 offset:4096
	v_sub_f32_e32 v135, v135, v190
	v_add_f32_e32 v254, v133, v254
	v_exp_f32_e32 v135, v135
	s_nop 0
	s_waitcnt lgkmcnt(6)
	v_mfma_f32_32x32x16_bf16 v[222:237], v[238:241], v[172:175], v[222:237]
	ds_read_b64_tr_b16 v[238:239], v221
	ds_read_b64_tr_b16 v[240:241], v221 offset:4096
	v_cvt_pk_bf16_f32 v242, v128, v129
	v_cvt_pk_bf16_f32 v243, v130, v131
	v_cvt_pk_bf16_f32 v244, v132, v133
	v_cvt_pk_bf16_f32 v245, v134, v135
	s_nop 1
	s_waitcnt lgkmcnt(6)
	v_mfma_f32_32x32x16_bf16 v[112:127], v[206:209], v[242:245], v[112:127]
	ds_read_b64_tr_b16 v[206:207], v205 offset:256
	ds_read_b64_tr_b16 v[208:209], v205 offset:4352
	v_sub_f32_e32 v136, v136, v190
	v_add_f32_e32 v254, v134, v254
	v_exp_f32_e32 v136, v136
	v_sub_f32_e32 v137, v137, v190
	v_add_f32_e32 v254, v135, v254
	s_waitcnt lgkmcnt(6)
	v_mfma_f32_32x32x16_bf16 v[96:111], v[210:213], v[242:245], v[96:111]
	ds_read_b64_tr_b16 v[210:211], v218 offset:256
	ds_read_b64_tr_b16 v[212:213], v218 offset:4352
	v_exp_f32_e32 v137, v137
	v_sub_f32_e32 v138, v138, v190
	v_add_f32_e32 v254, v136, v254
	v_exp_f32_e32 v138, v138
	v_sub_f32_e32 v139, v139, v190
	s_waitcnt lgkmcnt(6)
	v_mfma_f32_32x32x16_bf16 v[80:95], v[214:217], v[242:245], v[80:95]
	ds_read_b64_tr_b16 v[214:215], v219 offset:256
	ds_read_b64_tr_b16 v[216:217], v219 offset:4352
	v_add_f32_e32 v254, v137, v254
	v_exp_f32_e32 v139, v139
	v_sub_f32_e32 v140, v140, v190
	v_add_f32_e32 v254, v138, v254
	s_waitcnt lgkmcnt(6)
	v_mfma_f32_32x32x16_bf16 v[64:79], v[238:241], v[242:245], v[64:79]
	ds_read_b64_tr_b16 v[238:239], v221 offset:256
	ds_read_b64_tr_b16 v[240:241], v221 offset:4352
	v_exp_f32_e32 v140, v140
	v_sub_f32_e32 v141, v141, v190
	v_add_f32_e32 v254, v139, v254
	v_exp_f32_e32 v141, v141
	s_waitcnt lgkmcnt(6)
	v_mfma_f32_32x32x16_bf16 v[48:63], v[206:209], v[242:245], v[48:63]
	ds_read_b64_tr_b16 v[206:207], v205 offset:8192
	ds_read_b64_tr_b16 v[208:209], v205 offset:12288
	v_sub_f32_e32 v142, v142, v190
	v_add_f32_e32 v254, v140, v254
	v_exp_f32_e32 v142, v142
	v_sub_f32_e32 v143, v143, v190
	s_waitcnt lgkmcnt(6)
	v_mfma_f32_32x32x16_bf16 v[32:47], v[210:213], v[242:245], v[32:47]
	ds_read_b64_tr_b16 v[210:211], v218 offset:8192
	ds_read_b64_tr_b16 v[212:213], v218 offset:12288
	v_add_f32_e32 v254, v141, v254
	v_exp_f32_e32 v143, v143
	v_add_f32_e32 v254, v142, v254
	v_add_f32_e32 v254, v143, v254
	s_waitcnt lgkmcnt(6)
	v_mfma_f32_32x32x16_bf16 v[16:31], v[214:217], v[242:245], v[16:31]
	ds_read_b64_tr_b16 v[214:215], v219 offset:8192
	ds_read_b64_tr_b16 v[216:217], v219 offset:12288
	v_cvt_pk_bf16_f32 v250, v136, v137
	v_cvt_pk_bf16_f32 v251, v138, v139
	v_cvt_pk_bf16_f32 v252, v140, v141
	v_cvt_pk_bf16_f32 v253, v142, v143
	v_add_f32_e32 v195, v195, v254
	s_waitcnt lgkmcnt(6)
	v_mfma_f32_32x32x16_bf16 v[0:15], v[238:241], v[242:245], v[0:15]
	ds_read_b64_tr_b16 v[238:239], v221 offset:8192
	ds_read_b64_tr_b16 v[240:241], v221 offset:12288
	ds_read_b64_tr_b16 v[128:129], v205 offset:8448
	ds_read_b64_tr_b16 v[130:131], v205 offset:12544
	s_waitcnt lgkmcnt(8)
	v_mfma_f32_32x32x16_bf16 v[112:127], v[206:209], v[250:253], v[112:127]
	ds_read_b64_tr_b16 v[206:207], v218 offset:8448
	ds_read_b64_tr_b16 v[208:209], v218 offset:12544
	v_max3_f32 v246, v222, v223, v224
	v_max3_f32 v247, v225, v226, v227
	v_max3_f32 v246, v246, v228, v229
	v_max3_f32 v247, v247, v230, v231
	v_max3_f32 v246, v246, v232, v233
	s_waitcnt lgkmcnt(8)
	v_mfma_f32_32x32x16_bf16 v[96:111], v[210:213], v[250:253], v[96:111]
	ds_read_b64_tr_b16 v[210:211], v219 offset:8448
	ds_read_b64_tr_b16 v[212:213], v219 offset:12544
	v_max3_f32 v247, v247, v234, v235
	v_max3_f32 v246, v246, v236, v237
	v_max_f32_e32 v246, v246, v247
	v_mov_b32_e32 v247, v246
	v_add_f32_e32 v249, 0x41000000, v190
	s_waitcnt lgkmcnt(8)
	v_mfma_f32_32x32x16_bf16 v[80:95], v[214:217], v[250:253], v[80:95]
	ds_read_b64_tr_b16 v[214:215], v221 offset:8448
	ds_read_b64_tr_b16 v[216:217], v221 offset:12544
	s_nop 1
	v_permlane32_swap_b32_e32 v246, v247
	v_max_f32_e32 v246, v246, v247
	v_cmp_gt_f32_e32 vcc, v246, v249
	s_cbranch_vccnz .Latt_rs1_1s1
	s_waitcnt lgkmcnt(8)
	v_mfma_f32_32x32x16_bf16 v[64:79], v[238:241], v[250:253], v[64:79]
	ds_read_b64_tr_b16 v[238:239], v205 offset:16384
	ds_read_b64_tr_b16 v[240:241], v205 offset:20480
	v_sub_f32_e32 v222, v222, v190
	v_exp_f32_e32 v222, v222
	v_sub_f32_e32 v223, v223, v190
	v_exp_f32_e32 v223, v223
	v_sub_f32_e32 v224, v224, v190
	v_add_f32_e32 v254, 0, v222
	s_waitcnt lgkmcnt(8)
	v_mfma_f32_32x32x16_bf16 v[48:63], v[128:131], v[250:253], v[48:63]
	ds_read_b64_tr_b16 v[128:129], v218 offset:16384
	ds_read_b64_tr_b16 v[130:131], v218 offset:20480
	v_exp_f32_e32 v224, v224
	v_sub_f32_e32 v225, v225, v190
	v_add_f32_e32 v254, v223, v254
	v_exp_f32_e32 v225, v225
	v_sub_f32_e32 v226, v226, v190
	v_add_f32_e32 v254, v224, v254
	s_waitcnt lgkmcnt(8)
	v_mfma_f32_32x32x16_bf16 v[32:47], v[206:209], v[250:253], v[32:47]
	ds_read_b64_tr_b16 v[206:207], v219 offset:16384
	ds_read_b64_tr_b16 v[208:209], v219 offset:20480
	v_exp_f32_e32 v226, v226
	v_sub_f32_e32 v227, v227, v190
	v_add_f32_e32 v254, v225, v254
	v_exp_f32_e32 v227, v227
	v_sub_f32_e32 v228, v228, v190
	s_waitcnt lgkmcnt(8)
	v_mfma_f32_32x32x16_bf16 v[16:31], v[210:213], v[250:253], v[16:31]
	ds_read_b64_tr_b16 v[210:211], v221 offset:16384
	ds_read_b64_tr_b16 v[212:213], v221 offset:20480
	v_add_f32_e32 v254, v226, v254
	v_exp_f32_e32 v228, v228
	v_sub_f32_e32 v229, v229, v190
	v_add_f32_e32 v254, v227, v254
	v_exp_f32_e32 v229, v229
	s_waitcnt lgkmcnt(8)
	v_mfma_f32_32x32x16_bf16 v[0:15], v[214:217], v[250:253], v[0:15]
	ds_read_b64_tr_b16 v[214:215], v205 offset:16640
	ds_read_b64_tr_b16 v[216:217], v205 offset:20736
	s_nop 0
	v_cvt_pk_bf16_f32 v242, v222, v223
	v_cvt_pk_bf16_f32 v243, v224, v225
	v_cvt_pk_bf16_f32 v244, v226, v227
	v_cvt_pk_bf16_f32 v245, v228, v229
	s_nop 1
	s_waitcnt lgkmcnt(8)
	v_mfma_f32_32x32x16_bf16 v[112:127], v[238:241], v[242:245], v[112:127]
	ds_read_b64_tr_b16 v[238:239], v218 offset:16640
	ds_read_b64_tr_b16 v[240:241], v218 offset:20736
	v_sub_f32_e32 v230, v230, v190
	v_add_f32_e32 v254, v228, v254
	v_exp_f32_e32 v230, v230
	v_sub_f32_e32 v231, v231, v190
	v_add_f32_e32 v254, v229, v254
	s_waitcnt lgkmcnt(8)
	v_mfma_f32_32x32x16_bf16 v[96:111], v[128:131], v[242:245], v[96:111]
	ds_read_b64_tr_b16 v[128:129], v219 offset:16640
	ds_read_b64_tr_b16 v[130:131], v219 offset:20736
	v_exp_f32_e32 v231, v231
	v_sub_f32_e32 v232, v232, v190
	v_add_f32_e32 v254, v230, v254
	v_exp_f32_e32 v232, v232
	v_sub_f32_e32 v233, v233, v190
	s_waitcnt lgkmcnt(8)
	v_mfma_f32_32x32x16_bf16 v[80:95], v[206:209], v[242:245], v[80:95]
	ds_read_b64_tr_b16 v[206:207], v221 offset:16640
	ds_read_b64_tr_b16 v[208:209], v221 offset:20736
	v_add_f32_e32 v254, v231, v254
	v_exp_f32_e32 v233, v233
	v_sub_f32_e32 v234, v234, v190
	v_add_f32_e32 v254, v232, v254
	s_waitcnt lgkmcnt(8)
	v_mfma_f32_32x32x16_bf16 v[64:79], v[210:213], v[242:245], v[64:79]
	ds_read_b64_tr_b16 v[210:211], v205 offset:24576
	ds_read_b64_tr_b16 v[212:213], v205 offset:28672
	v_exp_f32_e32 v234, v234
	v_sub_f32_e32 v235, v235, v190
	v_add_f32_e32 v254, v233, v254
	v_exp_f32_e32 v235, v235
	s_waitcnt lgkmcnt(8)
	v_mfma_f32_32x32x16_bf16 v[48:63], v[214:217], v[242:245], v[48:63]
	ds_read_b64_tr_b16 v[214:215], v218 offset:24576
	ds_read_b64_tr_b16 v[216:217], v218 offset:28672
	v_sub_f32_e32 v236, v236, v190
	v_add_f32_e32 v254, v234, v254
	v_exp_f32_e32 v236, v236
	v_sub_f32_e32 v237, v237, v190
	s_waitcnt lgkmcnt(8)
	v_mfma_f32_32x32x16_bf16 v[32:47], v[238:241], v[242:245], v[32:47]
	ds_read_b64_tr_b16 v[238:239], v219 offset:24576
	ds_read_b64_tr_b16 v[240:241], v219 offset:28672
	v_add_f32_e32 v254, v235, v254
	v_exp_f32_e32 v237, v237
	v_add_f32_e32 v254, v236, v254
	v_add_f32_e32 v254, v237, v254
	s_waitcnt lgkmcnt(8)
	v_mfma_f32_32x32x16_bf16 v[16:31], v[128:131], v[242:245], v[16:31]
	ds_read_b64_tr_b16 v[128:129], v221 offset:24576
	ds_read_b64_tr_b16 v[130:131], v221 offset:28672
	v_cvt_pk_bf16_f32 v250, v230, v231
	v_cvt_pk_bf16_f32 v251, v232, v233
	v_cvt_pk_bf16_f32 v252, v234, v235
	v_cvt_pk_bf16_f32 v253, v236, v237
	v_add_f32_e32 v195, v195, v254
	s_waitcnt lgkmcnt(8)
	v_mfma_f32_32x32x16_bf16 v[0:15], v[206:209], v[242:245], v[0:15]
	ds_read_b64_tr_b16 v[206:207], v205 offset:24832
	ds_read_b64_tr_b16 v[208:209], v205 offset:28928
	s_waitcnt lgkmcnt(8)
	v_mfma_f32_32x32x16_bf16 v[112:127], v[210:213], v[250:253], v[112:127]
	ds_read_b64_tr_b16 v[210:211], v218 offset:24832
	ds_read_b64_tr_b16 v[212:213], v218 offset:28928
	s_waitcnt lgkmcnt(8)
	v_mfma_f32_32x32x16_bf16 v[96:111], v[214:217], v[250:253], v[96:111]
	ds_read_b64_tr_b16 v[214:215], v219 offset:24832
	ds_read_b64_tr_b16 v[216:217], v219 offset:28928
	s_waitcnt lgkmcnt(8)
	v_mfma_f32_32x32x16_bf16 v[80:95], v[238:241], v[250:253], v[80:95]
	ds_read_b64_tr_b16 v[238:239], v221 offset:24832
	ds_read_b64_tr_b16 v[240:241], v221 offset:28928
	s_waitcnt lgkmcnt(8)
	v_mfma_f32_32x32x16_bf16 v[64:79], v[128:131], v[250:253], v[64:79]
	s_waitcnt lgkmcnt(6)
	v_mfma_f32_32x32x16_bf16 v[48:63], v[206:209], v[250:253], v[48:63]
	s_waitcnt lgkmcnt(4)
	v_mfma_f32_32x32x16_bf16 v[32:47], v[210:213], v[250:253], v[32:47]
	s_waitcnt lgkmcnt(2)
	v_mfma_f32_32x32x16_bf16 v[16:31], v[214:217], v[250:253], v[16:31]
	s_waitcnt lgkmcnt(0)
	v_mfma_f32_32x32x16_bf16 v[0:15], v[238:241], v[250:253], v[0:15]
	ds_read_b128 v[206:209], v196 offset:32768
	ds_read_b128 v[210:213], v197 offset:32768
	ds_read_b128 v[214:217], v198 offset:32768
	ds_read_b128 v[238:241], v199 offset:32768
	ds_read_b128 v[242:245], v200 offset:32768
	ds_read_b128 v[250:253], v201 offset:32768
	ds_read_b128 v[222:225], v202 offset:32768
	ds_read_b128 v[226:229], v203 offset:32768
	s_waitcnt vmcnt(0)
	s_add_i32 s18, s33, 1
	s_cmp_lg_u32 s33, 2
	s_cselect_b32 s33, s18, 0
	s_add_i32 s4, s4, 64
	s_add_u32 s12, s12, 0x100000
	s_addc_u32 s13, s13, 0
	s_add_i32 s88, s88, 1
	s_add_i32 s100, s4, 63
	s_cmp_le_i32 s100, s83
	s_cbranch_scc0 .Latt_latchb_1
	s_cmp_ge_u32 s88, s82
	s_cselect_b64 s[18:19], -1, 0
	v_mov_b32_e32 v204, v176
	s_barrier
	s_branch .Latt_cont_1s2
.Latt_rs1_1s1:
	s_waitcnt lgkmcnt(8)
	v_mfma_f32_32x32x16_bf16 v[64:79], v[238:241], v[250:253], v[64:79]
	ds_read_b64_tr_b16 v[238:239], v205 offset:16384
	ds_read_b64_tr_b16 v[240:241], v205 offset:20480
	s_waitcnt lgkmcnt(8)
	v_mfma_f32_32x32x16_bf16 v[48:63], v[128:131], v[250:253], v[48:63]
	ds_read_b64_tr_b16 v[128:129], v218 offset:16384
	ds_read_b64_tr_b16 v[130:131], v218 offset:20480
	s_waitcnt lgkmcnt(8)
	v_mfma_f32_32x32x16_bf16 v[32:47], v[206:209], v[250:253], v[32:47]
	ds_read_b64_tr_b16 v[206:207], v219 offset:16384
	ds_read_b64_tr_b16 v[208:209], v219 offset:20480
	s_waitcnt lgkmcnt(8)
	v_mfma_f32_32x32x16_bf16 v[16:31], v[210:213], v[250:253], v[16:31]
	ds_read_b64_tr_b16 v[210:211], v221 offset:16384
	ds_read_b64_tr_b16 v[212:213], v221 offset:20480
	s_waitcnt lgkmcnt(8)
	v_mfma_f32_32x32x16_bf16 v[0:15], v[214:217], v[250:253], v[0:15]
	ds_read_b64_tr_b16 v[214:215], v205 offset:16640
	ds_read_b64_tr_b16 v[216:217], v205 offset:20736
	s_nop 11
	v_max_f32_e32 v246, v190, v246
	v_sub_f32_e32 v190, v190, v246
	v_exp_f32_e32 v190, v190
	s_nop 0
	v_pk_mul_f32 v[126:127], v[126:127], v[190:191] op_sel_hi:[1,0]
	v_pk_mul_f32 v[124:125], v[124:125], v[190:191] op_sel_hi:[1,0]
	v_pk_mul_f32 v[122:123], v[122:123], v[190:191] op_sel_hi:[1,0]
	v_pk_mul_f32 v[120:121], v[120:121], v[190:191] op_sel_hi:[1,0]
	v_pk_mul_f32 v[118:119], v[118:119], v[190:191] op_sel_hi:[1,0]
	v_pk_mul_f32 v[116:117], v[116:117], v[190:191] op_sel_hi:[1,0]
	v_pk_mul_f32 v[114:115], v[114:115], v[190:191] op_sel_hi:[1,0]
	v_pk_mul_f32 v[112:113], v[112:113], v[190:191] op_sel_hi:[1,0]
	v_pk_mul_f32 v[110:111], v[110:111], v[190:191] op_sel_hi:[1,0]
	v_pk_mul_f32 v[108:109], v[108:109], v[190:191] op_sel_hi:[1,0]
	v_pk_mul_f32 v[106:107], v[106:107], v[190:191] op_sel_hi:[1,0]
	v_pk_mul_f32 v[104:105], v[104:105], v[190:191] op_sel_hi:[1,0]
	v_pk_mul_f32 v[102:103], v[102:103], v[190:191] op_sel_hi:[1,0]
	v_pk_mul_f32 v[100:101], v[100:101], v[190:191] op_sel_hi:[1,0]
	v_pk_mul_f32 v[98:99], v[98:99], v[190:191] op_sel_hi:[1,0]
	v_pk_mul_f32 v[96:97], v[96:97], v[190:191] op_sel_hi:[1,0]
	v_pk_mul_f32 v[94:95], v[94:95], v[190:191] op_sel_hi:[1,0]
	v_pk_mul_f32 v[92:93], v[92:93], v[190:191] op_sel_hi:[1,0]
	v_pk_mul_f32 v[90:91], v[90:91], v[190:191] op_sel_hi:[1,0]
	v_pk_mul_f32 v[88:89], v[88:89], v[190:191] op_sel_hi:[1,0]
	v_pk_mul_f32 v[86:87], v[86:87], v[190:191] op_sel_hi:[1,0]
	v_pk_mul_f32 v[84:85], v[84:85], v[190:191] op_sel_hi:[1,0]
	v_pk_mul_f32 v[82:83], v[82:83], v[190:191] op_sel_hi:[1,0]
	v_pk_mul_f32 v[80:81], v[80:81], v[190:191] op_sel_hi:[1,0]
	v_pk_mul_f32 v[78:79], v[78:79], v[190:191] op_sel_hi:[1,0]
	v_pk_mul_f32 v[76:77], v[76:77], v[190:191] op_sel_hi:[1,0]
	v_pk_mul_f32 v[74:75], v[74:75], v[190:191] op_sel_hi:[1,0]
	v_pk_mul_f32 v[72:73], v[72:73], v[190:191] op_sel_hi:[1,0]
	v_pk_mul_f32 v[70:71], v[70:71], v[190:191] op_sel_hi:[1,0]
	v_pk_mul_f32 v[68:69], v[68:69], v[190:191] op_sel_hi:[1,0]
	v_pk_mul_f32 v[66:67], v[66:67], v[190:191] op_sel_hi:[1,0]
	v_pk_mul_f32 v[64:65], v[64:65], v[190:191] op_sel_hi:[1,0]
	v_pk_mul_f32 v[62:63], v[62:63], v[190:191] op_sel_hi:[1,0]
	v_pk_mul_f32 v[60:61], v[60:61], v[190:191] op_sel_hi:[1,0]
	v_pk_mul_f32 v[58:59], v[58:59], v[190:191] op_sel_hi:[1,0]
	v_pk_mul_f32 v[56:57], v[56:57], v[190:191] op_sel_hi:[1,0]
	v_pk_mul_f32 v[54:55], v[54:55], v[190:191] op_sel_hi:[1,0]
	v_pk_mul_f32 v[52:53], v[52:53], v[190:191] op_sel_hi:[1,0]
	v_pk_mul_f32 v[50:51], v[50:51], v[190:191] op_sel_hi:[1,0]
	v_pk_mul_f32 v[48:49], v[48:49], v[190:191] op_sel_hi:[1,0]
	v_pk_mul_f32 v[46:47], v[46:47], v[190:191] op_sel_hi:[1,0]
	v_pk_mul_f32 v[44:45], v[44:45], v[190:191] op_sel_hi:[1,0]
	v_pk_mul_f32 v[42:43], v[42:43], v[190:191] op_sel_hi:[1,0]
	v_pk_mul_f32 v[40:41], v[40:41], v[190:191] op_sel_hi:[1,0]
	v_pk_mul_f32 v[38:39], v[38:39], v[190:191] op_sel_hi:[1,0]
	v_pk_mul_f32 v[36:37], v[36:37], v[190:191] op_sel_hi:[1,0]
	v_pk_mul_f32 v[34:35], v[34:35], v[190:191] op_sel_hi:[1,0]
	v_pk_mul_f32 v[32:33], v[32:33], v[190:191] op_sel_hi:[1,0]
	v_pk_mul_f32 v[30:31], v[30:31], v[190:191] op_sel_hi:[1,0]
	v_pk_mul_f32 v[28:29], v[28:29], v[190:191] op_sel_hi:[1,0]
	v_pk_mul_f32 v[26:27], v[26:27], v[190:191] op_sel_hi:[1,0]
	v_pk_mul_f32 v[24:25], v[24:25], v[190:191] op_sel_hi:[1,0]
	v_pk_mul_f32 v[22:23], v[22:23], v[190:191] op_sel_hi:[1,0]
	v_pk_mul_f32 v[20:21], v[20:21], v[190:191] op_sel_hi:[1,0]
	v_pk_mul_f32 v[18:19], v[18:19], v[190:191] op_sel_hi:[1,0]
	v_pk_mul_f32 v[16:17], v[16:17], v[190:191] op_sel_hi:[1,0]
	v_pk_mul_f32 v[14:15], v[14:15], v[190:191] op_sel_hi:[1,0]
	v_pk_mul_f32 v[12:13], v[12:13], v[190:191] op_sel_hi:[1,0]
	v_pk_mul_f32 v[10:11], v[10:11], v[190:191] op_sel_hi:[1,0]
	v_pk_mul_f32 v[8:9], v[8:9], v[190:191] op_sel_hi:[1,0]
	v_pk_mul_f32 v[6:7], v[6:7], v[190:191] op_sel_hi:[1,0]
	v_pk_mul_f32 v[4:5], v[4:5], v[190:191] op_sel_hi:[1,0]
	v_pk_mul_f32 v[2:3], v[2:3], v[190:191] op_sel_hi:[1,0]
	v_pk_mul_f32 v[0:1], v[0:1], v[190:191] op_sel_hi:[1,0]
	v_mul_f32_e32 v195, v195, v190
	v_mov_b32_e32 v190, v246
	v_sub_f32_e32 v222, v222, v190
	v_exp_f32_e32 v222, v222
	v_sub_f32_e32 v223, v223, v190
	v_exp_f32_e32 v223, v223
	v_sub_f32_e32 v224, v224, v190
	v_add_f32_e32 v254, 0, v222
	v_exp_f32_e32 v224, v224
	v_sub_f32_e32 v225, v225, v190
	v_add_f32_e32 v254, v223, v254
	v_exp_f32_e32 v225, v225
	v_sub_f32_e32 v226, v226, v190
	v_add_f32_e32 v254, v224, v254
	v_exp_f32_e32 v226, v226
	v_sub_f32_e32 v227, v227, v190
	v_add_f32_e32 v254, v225, v254
	v_exp_f32_e32 v227, v227
	v_sub_f32_e32 v228, v228, v190
	v_add_f32_e32 v254, v226, v254
	v_exp_f32_e32 v228, v228
	v_sub_f32_e32 v229, v229, v190
	v_add_f32_e32 v254, v227, v254
	v_exp_f32_e32 v229, v229
	v_sub_f32_e32 v230, v230, v190
	v_add_f32_e32 v254, v228, v254
	v_exp_f32_e32 v230, v230
	v_sub_f32_e32 v231, v231, v190
	v_add_f32_e32 v254, v229, v254
	v_exp_f32_e32 v231, v231
	v_sub_f32_e32 v232, v232, v190
	v_add_f32_e32 v254, v230, v254
	v_exp_f32_e32 v232, v232
	v_sub_f32_e32 v233, v233, v190
	v_add_f32_e32 v254, v231, v254
	v_exp_f32_e32 v233, v233
	v_sub_f32_e32 v234, v234, v190
	v_add_f32_e32 v254, v232, v254
	v_exp_f32_e32 v234, v234
	v_sub_f32_e32 v235, v235, v190
	v_add_f32_e32 v254, v233, v254
	v_exp_f32_e32 v235, v235
	v_sub_f32_e32 v236, v236, v190
	v_add_f32_e32 v254, v234, v254
	v_exp_f32_e32 v236, v236
	v_sub_f32_e32 v237, v237, v190
	v_add_f32_e32 v254, v235, v254
	v_exp_f32_e32 v237, v237
	v_add_f32_e32 v254, v236, v254
	v_add_f32_e32 v254, v237, v254
	v_cvt_pk_bf16_f32 v242, v222, v223
	v_cvt_pk_bf16_f32 v243, v224, v225
	v_cvt_pk_bf16_f32 v244, v226, v227
	v_cvt_pk_bf16_f32 v245, v228, v229
	v_cvt_pk_bf16_f32 v250, v230, v231
	v_cvt_pk_bf16_f32 v251, v232, v233
	v_cvt_pk_bf16_f32 v252, v234, v235
	v_cvt_pk_bf16_f32 v253, v236, v237
	v_add_f32_e32 v195, v195, v254
	s_nop 1
	s_waitcnt lgkmcnt(8)
	v_mfma_f32_32x32x16_bf16 v[112:127], v[238:241], v[242:245], v[112:127]
	ds_read_b64_tr_b16 v[238:239], v218 offset:16640
	ds_read_b64_tr_b16 v[240:241], v218 offset:20736
	s_waitcnt lgkmcnt(8)
	v_mfma_f32_32x32x16_bf16 v[96:111], v[128:131], v[242:245], v[96:111]
	ds_read_b64_tr_b16 v[222:223], v219 offset:16640
	ds_read_b64_tr_b16 v[224:225], v219 offset:20736
	s_waitcnt lgkmcnt(8)
	v_mfma_f32_32x32x16_bf16 v[80:95], v[206:209], v[242:245], v[80:95]
	ds_read_b64_tr_b16 v[206:207], v221 offset:16640
	ds_read_b64_tr_b16 v[208:209], v221 offset:20736
	s_waitcnt lgkmcnt(8)
	v_mfma_f32_32x32x16_bf16 v[64:79], v[210:213], v[242:245], v[64:79]
	ds_read_b64_tr_b16 v[210:211], v205 offset:24576
	ds_read_b64_tr_b16 v[212:213], v205 offset:28672
	s_waitcnt lgkmcnt(8)
	v_mfma_f32_32x32x16_bf16 v[48:63], v[214:217], v[242:245], v[48:63]
	ds_read_b64_tr_b16 v[214:215], v218 offset:24576
	ds_read_b64_tr_b16 v[216:217], v218 offset:28672
	s_waitcnt lgkmcnt(8)
	v_mfma_f32_32x32x16_bf16 v[32:47], v[238:241], v[242:245], v[32:47]
	ds_read_b64_tr_b16 v[238:239], v219 offset:24576
	ds_read_b64_tr_b16 v[240:241], v219 offset:28672
	s_waitcnt lgkmcnt(8)
	v_mfma_f32_32x32x16_bf16 v[16:31], v[222:225], v[242:245], v[16:31]
	ds_read_b64_tr_b16 v[222:223], v221 offset:24576
	ds_read_b64_tr_b16 v[224:225], v221 offset:28672
	s_waitcnt lgkmcnt(8)
	v_mfma_f32_32x32x16_bf16 v[0:15], v[206:209], v[242:245], v[0:15]
	ds_read_b64_tr_b16 v[206:207], v205 offset:24832
	ds_read_b64_tr_b16 v[208:209], v205 offset:28928
	s_waitcnt lgkmcnt(8)
	v_mfma_f32_32x32x16_bf16 v[112:127], v[210:213], v[250:253], v[112:127]
	ds_read_b64_tr_b16 v[210:211], v218 offset:24832
	ds_read_b64_tr_b16 v[212:213], v218 offset:28928
	s_waitcnt lgkmcnt(8)
	v_mfma_f32_32x32x16_bf16 v[96:111], v[214:217], v[250:253], v[96:111]
	ds_read_b64_tr_b16 v[214:215], v219 offset:24832
	ds_read_b64_tr_b16 v[216:217], v219 offset:28928
	s_waitcnt lgkmcnt(8)
	v_mfma_f32_32x32x16_bf16 v[80:95], v[238:241], v[250:253], v[80:95]
	ds_read_b64_tr_b16 v[238:239], v221 offset:24832
	ds_read_b64_tr_b16 v[240:241], v221 offset:28928
	s_waitcnt lgkmcnt(8)
	v_mfma_f32_32x32x16_bf16 v[64:79], v[222:225], v[250:253], v[64:79]
	s_waitcnt lgkmcnt(6)
	v_mfma_f32_32x32x16_bf16 v[48:63], v[206:209], v[250:253], v[48:63]
	s_waitcnt lgkmcnt(4)
	v_mfma_f32_32x32x16_bf16 v[32:47], v[210:213], v[250:253], v[32:47]
	s_waitcnt lgkmcnt(2)
	v_mfma_f32_32x32x16_bf16 v[16:31], v[214:217], v[250:253], v[16:31]
	s_waitcnt lgkmcnt(0)
	v_mfma_f32_32x32x16_bf16 v[0:15], v[238:241], v[250:253], v[0:15]
	ds_read_b128 v[206:209], v196 offset:32768
	ds_read_b128 v[210:213], v197 offset:32768
	ds_read_b128 v[214:217], v198 offset:32768
	ds_read_b128 v[238:241], v199 offset:32768
	ds_read_b128 v[242:245], v200 offset:32768
	ds_read_b128 v[250:253], v201 offset:32768
	ds_read_b128 v[222:225], v202 offset:32768
	ds_read_b128 v[226:229], v203 offset:32768
	s_waitcnt vmcnt(0)
	s_add_i32 s18, s33, 1
	s_cmp_lg_u32 s33, 2
	s_cselect_b32 s33, s18, 0
	s_add_i32 s4, s4, 64
	s_add_u32 s12, s12, 0x100000
	s_addc_u32 s13, s13, 0
	s_add_i32 s88, s88, 1
	s_add_i32 s100, s4, 63
	s_cmp_le_i32 s100, s83
	s_cbranch_scc0 .Latt_latchb_1
	s_cmp_ge_u32 s88, s82
	s_cselect_b64 s[18:19], -1, 0
	v_mov_b32_e32 v204, v176
	s_barrier
	s_branch .Latt_cont_1s2
.Latt_slow_1s1:
.Latt_slot2_1:
.Latt_cont_1s2:
	v_add_u32_e32 v205, 0x8000, v205
	v_add_u32_e32 v218, 0x8000, v218
	v_add_u32_e32 v219, 0x8000, v219
	v_add_u32_e32 v221, 0x8000, v221
	s_waitcnt lgkmcnt(7)
	v_mfma_f32_32x32x16_bf16 v[128:143], v[206:209], v[144:147], 0
	ds_read_b128 v[206:209], v196 offset:40960
	s_cmp_lg_u64 s[18:19], 0
	s_cbranch_scc1 .Latt_nd0_1s2
	s_sub_i32 s100, s33, 1
	s_cmp_eq_u32 s33, 0
	s_cselect_b32 s100, 2, s100
	s_lshl_b32 s101, s100, 14
	s_add_i32 m0, s85, s101
	s_nop 0
	global_load_lds_dwordx4 v178, s[12:13]

.Latt_nr0_1s2:
	s_waitcnt lgkmcnt(3)
	v_mfma_f32_32x32x16_bf16 v[222:237], v[214:217], v[152:155], v[222:237]
	ds_read_b128 v[214:217], v202 offset:40960
	v_sub_f32_e32 v128, v128, v190
	v_exp_f32_e32 v128, v128
	v_sub_f32_e32 v129, v129, v190
	v_exp_f32_e32 v129, v129
	v_sub_f32_e32 v130, v130, v190
	s_waitcnt lgkmcnt(3)
	v_mfma_f32_32x32x16_bf16 v[222:237], v[238:241], v[156:159], v[222:237]
	ds_read_b128 v[238:241], v203 offset:40960
	v_add_f32_e32 v254, 0, v128
	v_exp_f32_e32 v130, v130
	v_sub_f32_e32 v131, v131, v190
	v_add_f32_e32 v254, v129, v254
	v_exp_f32_e32 v131, v131
	s_waitcnt lgkmcnt(3)
	v_mfma_f32_32x32x16_bf16 v[222:237], v[206:209], v[160:163], v[222:237]
	ds_read_b64_tr_b16 v[206:207], v205
	ds_read_b64_tr_b16 v[208:209], v205 offset:4096
	v_sub_f32_e32 v132, v132, v190
	v_add_f32_e32 v254, v130, v254
	v_exp_f32_e32 v132, v132
	v_sub_f32_e32 v133, v133, v190
	v_add_f32_e32 v254, v131, v254
	s_waitcnt lgkmcnt(4)
	v_mfma_f32_32x32x16_bf16 v[222:237], v[210:213], v[164:167], v[222:237]
	ds_read_b64_tr_b16 v[210:211], v218
	ds_read_b64_tr_b16 v[212:213], v218 offset:4096
	v_exp_f32_e32 v133, v133
	v_sub_f32_e32 v134, v134, v190
	v_add_f32_e32 v254, v132, v254
	v_exp_f32_e32 v134, v134
	s_waitcnt lgkmcnt(5)
	v_mfma_f32_32x32x16_bf16 v[222:237], v[214:217], v[168:171], v[222:237]
	ds_read_b64_tr_b16 v[214:215], v219
	ds_read_b64_tr_b16 v[216:217], v219 offset:4096
	v_sub_f32_e32 v135, v135, v190
	v_add_f32_e32 v254, v133, v254
	v_exp_f32_e32 v135, v135
	s_nop 0
	s_waitcnt lgkmcnt(6)
	v_mfma_f32_32x32x16_bf16 v[222:237], v[238:241], v[172:175], v[222:237]
	ds_read_b64_tr_b16 v[238:239], v221
	ds_read_b64_tr_b16 v[240:241], v221 offset:4096
	v_cvt_pk_bf16_f32 v242, v128, v129
	v_cvt_pk_bf16_f32 v243, v130, v131
	v_cvt_pk_bf16_f32 v244, v132, v133
	v_cvt_pk_bf16_f32 v245, v134, v135
	s_nop 1
	s_waitcnt lgkmcnt(6)
	v_mfma_f32_32x32x16_bf16 v[112:127], v[206:209], v[242:245], v[112:127]
	ds_read_b64_tr_b16 v[206:207], v205 offset:256
	ds_read_b64_tr_b16 v[208:209], v205 offset:4352
	v_sub_f32_e32 v136, v136, v190
	v_add_f32_e32 v254, v134, v254
	v_exp_f32_e32 v136, v136
	v_sub_f32_e32 v137, v137, v190
	v_add_f32_e32 v254, v135, v254
	s_waitcnt lgkmcnt(6)
	v_mfma_f32_32x32x16_bf16 v[96:111], v[210:213], v[242:245], v[96:111]
	ds_read_b64_tr_b16 v[210:211], v218 offset:256
	ds_read_b64_tr_b16 v[212:213], v218 offset:4352
	v_exp_f32_e32 v137, v137
	v_sub_f32_e32 v138, v138, v190
	v_add_f32_e32 v254, v136, v254
	v_exp_f32_e32 v138, v138
	v_sub_f32_e32 v139, v139, v190
	s_waitcnt lgkmcnt(6)
	v_mfma_f32_32x32x16_bf16 v[80:95], v[214:217], v[242:245], v[80:95]
	ds_read_b64_tr_b16 v[214:215], v219 offset:256
	ds_read_b64_tr_b16 v[216:217], v219 offset:4352
	v_add_f32_e32 v254, v137, v254
	v_exp_f32_e32 v139, v139
	v_sub_f32_e32 v140, v140, v190
	v_add_f32_e32 v254, v138, v254
	s_waitcnt lgkmcnt(6)
	v_mfma_f32_32x32x16_bf16 v[64:79], v[238:241], v[242:245], v[64:79]
	ds_read_b64_tr_b16 v[238:239], v221 offset:256
	ds_read_b64_tr_b16 v[240:241], v221 offset:4352
	v_exp_f32_e32 v140, v140
	v_sub_f32_e32 v141, v141, v190
	v_add_f32_e32 v254, v139, v254
	v_exp_f32_e32 v141, v141
	s_waitcnt lgkmcnt(6)
	v_mfma_f32_32x32x16_bf16 v[48:63], v[206:209], v[242:245], v[48:63]
	ds_read_b64_tr_b16 v[206:207], v205 offset:8192
	ds_read_b64_tr_b16 v[208:209], v205 offset:12288
	v_sub_f32_e32 v142, v142, v190
	v_add_f32_e32 v254, v140, v254
	v_exp_f32_e32 v142, v142
	v_sub_f32_e32 v143, v143, v190
	s_waitcnt lgkmcnt(6)
	v_mfma_f32_32x32x16_bf16 v[32:47], v[210:213], v[242:245], v[32:47]
	ds_read_b64_tr_b16 v[210:211], v218 offset:8192
	ds_read_b64_tr_b16 v[212:213], v218 offset:12288
	v_add_f32_e32 v254, v141, v254
	v_exp_f32_e32 v143, v143
	v_add_f32_e32 v254, v142, v254
	v_add_f32_e32 v254, v143, v254
	s_waitcnt lgkmcnt(6)
	v_mfma_f32_32x32x16_bf16 v[16:31], v[214:217], v[242:245], v[16:31]
	ds_read_b64_tr_b16 v[214:215], v219 offset:8192
	ds_read_b64_tr_b16 v[216:217], v219 offset:12288
	v_cvt_pk_bf16_f32 v250, v136, v137
	v_cvt_pk_bf16_f32 v251, v138, v139
	v_cvt_pk_bf16_f32 v252, v140, v141
	v_cvt_pk_bf16_f32 v253, v142, v143
	v_add_f32_e32 v195, v195, v254
	s_waitcnt lgkmcnt(6)
	v_mfma_f32_32x32x16_bf16 v[0:15], v[238:241], v[242:245], v[0:15]
	ds_read_b64_tr_b16 v[238:239], v221 offset:8192
	ds_read_b64_tr_b16 v[240:241], v221 offset:12288
	ds_read_b64_tr_b16 v[128:129], v205 offset:8448
	ds_read_b64_tr_b16 v[130:131], v205 offset:12544
	s_waitcnt lgkmcnt(8)
	v_mfma_f32_32x32x16_bf16 v[112:127], v[206:209], v[250:253], v[112:127]
	ds_read_b64_tr_b16 v[206:207], v218 offset:8448
	ds_read_b64_tr_b16 v[208:209], v218 offset:12544
	v_max3_f32 v246, v222, v223, v224
	v_max3_f32 v247, v225, v226, v227
	v_max3_f32 v246, v246, v228, v229
	v_max3_f32 v247, v247, v230, v231
	v_max3_f32 v246, v246, v232, v233
	s_waitcnt lgkmcnt(8)
	v_mfma_f32_32x32x16_bf16 v[96:111], v[210:213], v[250:253], v[96:111]
	ds_read_b64_tr_b16 v[210:211], v219 offset:8448
	ds_read_b64_tr_b16 v[212:213], v219 offset:12544
	v_max3_f32 v247, v247, v234, v235
	v_max3_f32 v246, v246, v236, v237
	v_max_f32_e32 v246, v246, v247
	v_mov_b32_e32 v247, v246
	v_add_f32_e32 v249, 0x41000000, v190
	s_waitcnt lgkmcnt(8)
	v_mfma_f32_32x32x16_bf16 v[80:95], v[214:217], v[250:253], v[80:95]
	ds_read_b64_tr_b16 v[214:215], v221 offset:8448
	ds_read_b64_tr_b16 v[216:217], v221 offset:12544
	s_nop 1
	v_permlane32_swap_b32_e32 v246, v247
	v_max_f32_e32 v246, v246, v247
	v_cmp_gt_f32_e32 vcc, v246, v249
	s_cbranch_vccnz .Latt_rs1_1s2
	s_waitcnt lgkmcnt(8)
	v_mfma_f32_32x32x16_bf16 v[64:79], v[238:241], v[250:253], v[64:79]
	ds_read_b64_tr_b16 v[238:239], v205 offset:16384
	ds_read_b64_tr_b16 v[240:241], v205 offset:20480
	v_sub_f32_e32 v222, v222, v190
	v_exp_f32_e32 v222, v222
	v_sub_f32_e32 v223, v223, v190
	v_exp_f32_e32 v223, v223
	v_sub_f32_e32 v224, v224, v190
	v_add_f32_e32 v254, 0, v222
	s_waitcnt lgkmcnt(8)
	v_mfma_f32_32x32x16_bf16 v[48:63], v[128:131], v[250:253], v[48:63]
	ds_read_b64_tr_b16 v[128:129], v218 offset:16384
	ds_read_b64_tr_b16 v[130:131], v218 offset:20480
	v_exp_f32_e32 v224, v224
	v_sub_f32_e32 v225, v225, v190
	v_add_f32_e32 v254, v223, v254
	v_exp_f32_e32 v225, v225
	v_sub_f32_e32 v226, v226, v190
	v_add_f32_e32 v254, v224, v254
	s_waitcnt lgkmcnt(8)
	v_mfma_f32_32x32x16_bf16 v[32:47], v[206:209], v[250:253], v[32:47]
	ds_read_b64_tr_b16 v[206:207], v219 offset:16384
	ds_read_b64_tr_b16 v[208:209], v219 offset:20480
	v_exp_f32_e32 v226, v226
	v_sub_f32_e32 v227, v227, v190
	v_add_f32_e32 v254, v225, v254
	v_exp_f32_e32 v227, v227
	v_sub_f32_e32 v228, v228, v190
	s_waitcnt lgkmcnt(8)
	v_mfma_f32_32x32x16_bf16 v[16:31], v[210:213], v[250:253], v[16:31]
	ds_read_b64_tr_b16 v[210:211], v221 offset:16384
	ds_read_b64_tr_b16 v[212:213], v221 offset:20480
	v_add_f32_e32 v254, v226, v254
	v_exp_f32_e32 v228, v228
	v_sub_f32_e32 v229, v229, v190
	v_add_f32_e32 v254, v227, v254
	v_exp_f32_e32 v229, v229
	s_waitcnt lgkmcnt(8)
	v_mfma_f32_32x32x16_bf16 v[0:15], v[214:217], v[250:253], v[0:15]
	ds_read_b64_tr_b16 v[214:215], v205 offset:16640
	ds_read_b64_tr_b16 v[216:217], v205 offset:20736
	s_nop 0
	v_cvt_pk_bf16_f32 v242, v222, v223
	v_cvt_pk_bf16_f32 v243, v224, v225
	v_cvt_pk_bf16_f32 v244, v226, v227
	v_cvt_pk_bf16_f32 v245, v228, v229
	s_nop 1
	s_waitcnt lgkmcnt(8)
	v_mfma_f32_32x32x16_bf16 v[112:127], v[238:241], v[242:245], v[112:127]
	ds_read_b64_tr_b16 v[238:239], v218 offset:16640
	ds_read_b64_tr_b16 v[240:241], v218 offset:20736
	v_sub_f32_e32 v230, v230, v190
	v_add_f32_e32 v254, v228, v254
	v_exp_f32_e32 v230, v230
	v_sub_f32_e32 v231, v231, v190
	v_add_f32_e32 v254, v229, v254
	s_waitcnt lgkmcnt(8)
	v_mfma_f32_32x32x16_bf16 v[96:111], v[128:131], v[242:245], v[96:111]
	ds_read_b64_tr_b16 v[128:129], v219 offset:16640
	ds_read_b64_tr_b16 v[130:131], v219 offset:20736
	v_exp_f32_e32 v231, v231
	v_sub_f32_e32 v232, v232, v190
	v_add_f32_e32 v254, v230, v254
	v_exp_f32_e32 v232, v232
	v_sub_f32_e32 v233, v233, v190
	s_waitcnt lgkmcnt(8)
	v_mfma_f32_32x32x16_bf16 v[80:95], v[206:209], v[242:245], v[80:95]
	ds_read_b64_tr_b16 v[206:207], v221 offset:16640
	ds_read_b64_tr_b16 v[208:209], v221 offset:20736
	v_add_f32_e32 v254, v231, v254
	v_exp_f32_e32 v233, v233
	v_sub_f32_e32 v234, v234, v190
	v_add_f32_e32 v254, v232, v254
	s_waitcnt lgkmcnt(8)
	v_mfma_f32_32x32x16_bf16 v[64:79], v[210:213], v[242:245], v[64:79]
	ds_read_b64_tr_b16 v[210:211], v205 offset:24576
	ds_read_b64_tr_b16 v[212:213], v205 offset:28672
	v_exp_f32_e32 v234, v234
	v_sub_f32_e32 v235, v235, v190
	v_add_f32_e32 v254, v233, v254
	v_exp_f32_e32 v235, v235
	s_waitcnt lgkmcnt(8)
	v_mfma_f32_32x32x16_bf16 v[48:63], v[214:217], v[242:245], v[48:63]
	ds_read_b64_tr_b16 v[214:215], v218 offset:24576
	ds_read_b64_tr_b16 v[216:217], v218 offset:28672
	v_sub_f32_e32 v236, v236, v190
	v_add_f32_e32 v254, v234, v254
	v_exp_f32_e32 v236, v236
	v_sub_f32_e32 v237, v237, v190
	s_waitcnt lgkmcnt(8)
	v_mfma_f32_32x32x16_bf16 v[32:47], v[238:241], v[242:245], v[32:47]
	ds_read_b64_tr_b16 v[238:239], v219 offset:24576
	ds_read_b64_tr_b16 v[240:241], v219 offset:28672
	v_add_f32_e32 v254, v235, v254
	v_exp_f32_e32 v237, v237
	v_add_f32_e32 v254, v236, v254
	v_add_f32_e32 v254, v237, v254
	s_waitcnt lgkmcnt(8)
	v_mfma_f32_32x32x16_bf16 v[16:31], v[128:131], v[242:245], v[16:31]
	ds_read_b64_tr_b16 v[128:129], v221 offset:24576
	ds_read_b64_tr_b16 v[130:131], v221 offset:28672
	v_cvt_pk_bf16_f32 v250, v230, v231
	v_cvt_pk_bf16_f32 v251, v232, v233
	v_cvt_pk_bf16_f32 v252, v234, v235
	v_cvt_pk_bf16_f32 v253, v236, v237
	v_add_f32_e32 v195, v195, v254
	s_waitcnt lgkmcnt(8)
	v_mfma_f32_32x32x16_bf16 v[0:15], v[206:209], v[242:245], v[0:15]
	ds_read_b64_tr_b16 v[206:207], v205 offset:24832
	ds_read_b64_tr_b16 v[208:209], v205 offset:28928
	s_waitcnt lgkmcnt(8)
	v_mfma_f32_32x32x16_bf16 v[112:127], v[210:213], v[250:253], v[112:127]
	ds_read_b64_tr_b16 v[210:211], v218 offset:24832
	ds_read_b64_tr_b16 v[212:213], v218 offset:28928
	s_waitcnt lgkmcnt(8)
	v_mfma_f32_32x32x16_bf16 v[96:111], v[214:217], v[250:253], v[96:111]
	ds_read_b64_tr_b16 v[214:215], v219 offset:24832
	ds_read_b64_tr_b16 v[216:217], v219 offset:28928
	s_waitcnt lgkmcnt(8)
	v_mfma_f32_32x32x16_bf16 v[80:95], v[238:241], v[250:253], v[80:95]
	ds_read_b64_tr_b16 v[238:239], v221 offset:24832
	ds_read_b64_tr_b16 v[240:241], v221 offset:28928
	s_waitcnt lgkmcnt(8)
	v_mfma_f32_32x32x16_bf16 v[64:79], v[128:131], v[250:253], v[64:79]
	s_waitcnt lgkmcnt(6)
	v_mfma_f32_32x32x16_bf16 v[48:63], v[206:209], v[250:253], v[48:63]
	s_waitcnt lgkmcnt(4)
	v_mfma_f32_32x32x16_bf16 v[32:47], v[210:213], v[250:253], v[32:47]
	s_waitcnt lgkmcnt(2)
	v_mfma_f32_32x32x16_bf16 v[16:31], v[214:217], v[250:253], v[16:31]
	s_waitcnt lgkmcnt(0)
	v_mfma_f32_32x32x16_bf16 v[0:15], v[238:241], v[250:253], v[0:15]
	ds_read_b128 v[206:209], v196
	ds_read_b128 v[210:213], v197
	ds_read_b128 v[214:217], v198
	ds_read_b128 v[238:241], v199
	ds_read_b128 v[242:245], v200
	ds_read_b128 v[250:253], v201
	ds_read_b128 v[222:225], v202
	ds_read_b128 v[226:229], v203
	s_waitcnt vmcnt(0)
	s_add_i32 s18, s33, 1
	s_cmp_lg_u32 s33, 2
	s_cselect_b32 s33, s18, 0
	s_add_i32 s4, s4, 64
	s_add_u32 s12, s12, 0x100000
	s_addc_u32 s13, s13, 0
	s_add_i32 s88, s88, 1
	s_add_i32 s100, s4, 63
	s_cmp_le_i32 s100, s83
	s_cbranch_scc0 .Latt_latchb_1
	s_cmp_ge_u32 s88, s82
	s_cselect_b64 s[18:19], -1, 0
	v_mov_b32_e32 v204, v176
	s_barrier
	s_branch .Latt_cont_1s0
.Latt_rs1_1s2:
	s_waitcnt lgkmcnt(8)
	v_mfma_f32_32x32x16_bf16 v[64:79], v[238:241], v[250:253], v[64:79]
	ds_read_b64_tr_b16 v[238:239], v205 offset:16384
	ds_read_b64_tr_b16 v[240:241], v205 offset:20480
	s_waitcnt lgkmcnt(8)
	v_mfma_f32_32x32x16_bf16 v[48:63], v[128:131], v[250:253], v[48:63]
	ds_read_b64_tr_b16 v[128:129], v218 offset:16384
	ds_read_b64_tr_b16 v[130:131], v218 offset:20480
	s_waitcnt lgkmcnt(8)
	v_mfma_f32_32x32x16_bf16 v[32:47], v[206:209], v[250:253], v[32:47]
	ds_read_b64_tr_b16 v[206:207], v219 offset:16384
	ds_read_b64_tr_b16 v[208:209], v219 offset:20480
	s_waitcnt lgkmcnt(8)
	v_mfma_f32_32x32x16_bf16 v[16:31], v[210:213], v[250:253], v[16:31]
	ds_read_b64_tr_b16 v[210:211], v221 offset:16384
	ds_read_b64_tr_b16 v[212:213], v221 offset:20480
	s_waitcnt lgkmcnt(8)
	v_mfma_f32_32x32x16_bf16 v[0:15], v[214:217], v[250:253], v[0:15]
	ds_read_b64_tr_b16 v[214:215], v205 offset:16640
	ds_read_b64_tr_b16 v[216:217], v205 offset:20736
	s_nop 11
	v_max_f32_e32 v246, v190, v246
	v_sub_f32_e32 v190, v190, v246
	v_exp_f32_e32 v190, v190
	s_nop 0
	v_pk_mul_f32 v[126:127], v[126:127], v[190:191] op_sel_hi:[1,0]
	v_pk_mul_f32 v[124:125], v[124:125], v[190:191] op_sel_hi:[1,0]
	v_pk_mul_f32 v[122:123], v[122:123], v[190:191] op_sel_hi:[1,0]
	v_pk_mul_f32 v[120:121], v[120:121], v[190:191] op_sel_hi:[1,0]
	v_pk_mul_f32 v[118:119], v[118:119], v[190:191] op_sel_hi:[1,0]
	v_pk_mul_f32 v[116:117], v[116:117], v[190:191] op_sel_hi:[1,0]
	v_pk_mul_f32 v[114:115], v[114:115], v[190:191] op_sel_hi:[1,0]
	v_pk_mul_f32 v[112:113], v[112:113], v[190:191] op_sel_hi:[1,0]
	v_pk_mul_f32 v[110:111], v[110:111], v[190:191] op_sel_hi:[1,0]
	v_pk_mul_f32 v[108:109], v[108:109], v[190:191] op_sel_hi:[1,0]
	v_pk_mul_f32 v[106:107], v[106:107], v[190:191] op_sel_hi:[1,0]
	v_pk_mul_f32 v[104:105], v[104:105], v[190:191] op_sel_hi:[1,0]
	v_pk_mul_f32 v[102:103], v[102:103], v[190:191] op_sel_hi:[1,0]
	v_pk_mul_f32 v[100:101], v[100:101], v[190:191] op_sel_hi:[1,0]
	v_pk_mul_f32 v[98:99], v[98:99], v[190:191] op_sel_hi:[1,0]
	v_pk_mul_f32 v[96:97], v[96:97], v[190:191] op_sel_hi:[1,0]
	v_pk_mul_f32 v[94:95], v[94:95], v[190:191] op_sel_hi:[1,0]
	v_pk_mul_f32 v[92:93], v[92:93], v[190:191] op_sel_hi:[1,0]
	v_pk_mul_f32 v[90:91], v[90:91], v[190:191] op_sel_hi:[1,0]
	v_pk_mul_f32 v[88:89], v[88:89], v[190:191] op_sel_hi:[1,0]
	v_pk_mul_f32 v[86:87], v[86:87], v[190:191] op_sel_hi:[1,0]
	v_pk_mul_f32 v[84:85], v[84:85], v[190:191] op_sel_hi:[1,0]
	v_pk_mul_f32 v[82:83], v[82:83], v[190:191] op_sel_hi:[1,0]
	v_pk_mul_f32 v[80:81], v[80:81], v[190:191] op_sel_hi:[1,0]
	v_pk_mul_f32 v[78:79], v[78:79], v[190:191] op_sel_hi:[1,0]
	v_pk_mul_f32 v[76:77], v[76:77], v[190:191] op_sel_hi:[1,0]
	v_pk_mul_f32 v[74:75], v[74:75], v[190:191] op_sel_hi:[1,0]
	v_pk_mul_f32 v[72:73], v[72:73], v[190:191] op_sel_hi:[1,0]
	v_pk_mul_f32 v[70:71], v[70:71], v[190:191] op_sel_hi:[1,0]
	v_pk_mul_f32 v[68:69], v[68:69], v[190:191] op_sel_hi:[1,0]
	v_pk_mul_f32 v[66:67], v[66:67], v[190:191] op_sel_hi:[1,0]
	v_pk_mul_f32 v[64:65], v[64:65], v[190:191] op_sel_hi:[1,0]
	v_pk_mul_f32 v[62:63], v[62:63], v[190:191] op_sel_hi:[1,0]
	v_pk_mul_f32 v[60:61], v[60:61], v[190:191] op_sel_hi:[1,0]
	v_pk_mul_f32 v[58:59], v[58:59], v[190:191] op_sel_hi:[1,0]
	v_pk_mul_f32 v[56:57], v[56:57], v[190:191] op_sel_hi:[1,0]
	v_pk_mul_f32 v[54:55], v[54:55], v[190:191] op_sel_hi:[1,0]
	v_pk_mul_f32 v[52:53], v[52:53], v[190:191] op_sel_hi:[1,0]
	v_pk_mul_f32 v[50:51], v[50:51], v[190:191] op_sel_hi:[1,0]
	v_pk_mul_f32 v[48:49], v[48:49], v[190:191] op_sel_hi:[1,0]
	v_pk_mul_f32 v[46:47], v[46:47], v[190:191] op_sel_hi:[1,0]
	v_pk_mul_f32 v[44:45], v[44:45], v[190:191] op_sel_hi:[1,0]
	v_pk_mul_f32 v[42:43], v[42:43], v[190:191] op_sel_hi:[1,0]
	v_pk_mul_f32 v[40:41], v[40:41], v[190:191] op_sel_hi:[1,0]
	v_pk_mul_f32 v[38:39], v[38:39], v[190:191] op_sel_hi:[1,0]
	v_pk_mul_f32 v[36:37], v[36:37], v[190:191] op_sel_hi:[1,0]
	v_pk_mul_f32 v[34:35], v[34:35], v[190:191] op_sel_hi:[1,0]
	v_pk_mul_f32 v[32:33], v[32:33], v[190:191] op_sel_hi:[1,0]
	v_pk_mul_f32 v[30:31], v[30:31], v[190:191] op_sel_hi:[1,0]
	v_pk_mul_f32 v[28:29], v[28:29], v[190:191] op_sel_hi:[1,0]
	v_pk_mul_f32 v[26:27], v[26:27], v[190:191] op_sel_hi:[1,0]
	v_pk_mul_f32 v[24:25], v[24:25], v[190:191] op_sel_hi:[1,0]
	v_pk_mul_f32 v[22:23], v[22:23], v[190:191] op_sel_hi:[1,0]
	v_pk_mul_f32 v[20:21], v[20:21], v[190:191] op_sel_hi:[1,0]
	v_pk_mul_f32 v[18:19], v[18:19], v[190:191] op_sel_hi:[1,0]
	v_pk_mul_f32 v[16:17], v[16:17], v[190:191] op_sel_hi:[1,0]
	v_pk_mul_f32 v[14:15], v[14:15], v[190:191] op_sel_hi:[1,0]
	v_pk_mul_f32 v[12:13], v[12:13], v[190:191] op_sel_hi:[1,0]
	v_pk_mul_f32 v[10:11], v[10:11], v[190:191] op_sel_hi:[1,0]
	v_pk_mul_f32 v[8:9], v[8:9], v[190:191] op_sel_hi:[1,0]
	v_pk_mul_f32 v[6:7], v[6:7], v[190:191] op_sel_hi:[1,0]
	v_pk_mul_f32 v[4:5], v[4:5], v[190:191] op_sel_hi:[1,0]
	v_pk_mul_f32 v[2:3], v[2:3], v[190:191] op_sel_hi:[1,0]
	v_pk_mul_f32 v[0:1], v[0:1], v[190:191] op_sel_hi:[1,0]
	v_mul_f32_e32 v195, v195, v190
	v_mov_b32_e32 v190, v246
	v_sub_f32_e32 v222, v222, v190
	v_exp_f32_e32 v222, v222
	v_sub_f32_e32 v223, v223, v190
	v_exp_f32_e32 v223, v223
	v_sub_f32_e32 v224, v224, v190
	v_add_f32_e32 v254, 0, v222
	v_exp_f32_e32 v224, v224
	v_sub_f32_e32 v225, v225, v190
	v_add_f32_e32 v254, v223, v254
	v_exp_f32_e32 v225, v225
	v_sub_f32_e32 v226, v226, v190
	v_add_f32_e32 v254, v224, v254
	v_exp_f32_e32 v226, v226
	v_sub_f32_e32 v227, v227, v190
	v_add_f32_e32 v254, v225, v254
	v_exp_f32_e32 v227, v227
	v_sub_f32_e32 v228, v228, v190
	v_add_f32_e32 v254, v226, v254
	v_exp_f32_e32 v228, v228
	v_sub_f32_e32 v229, v229, v190
	v_add_f32_e32 v254, v227, v254
	v_exp_f32_e32 v229, v229
	v_sub_f32_e32 v230, v230, v190
	v_add_f32_e32 v254, v228, v254
	v_exp_f32_e32 v230, v230
	v_sub_f32_e32 v231, v231, v190
	v_add_f32_e32 v254, v229, v254
	v_exp_f32_e32 v231, v231
	v_sub_f32_e32 v232, v232, v190
	v_add_f32_e32 v254, v230, v254
	v_exp_f32_e32 v232, v232
	v_sub_f32_e32 v233, v233, v190
	v_add_f32_e32 v254, v231, v254
	v_exp_f32_e32 v233, v233
	v_sub_f32_e32 v234, v234, v190
	v_add_f32_e32 v254, v232, v254
	v_exp_f32_e32 v234, v234
	v_sub_f32_e32 v235, v235, v190
	v_add_f32_e32 v254, v233, v254
	v_exp_f32_e32 v235, v235
	v_sub_f32_e32 v236, v236, v190
	v_add_f32_e32 v254, v234, v254
	v_exp_f32_e32 v236, v236
	v_sub_f32_e32 v237, v237, v190
	v_add_f32_e32 v254, v235, v254
	v_exp_f32_e32 v237, v237
	v_add_f32_e32 v254, v236, v254
	v_add_f32_e32 v254, v237, v254
	v_cvt_pk_bf16_f32 v242, v222, v223
	v_cvt_pk_bf16_f32 v243, v224, v225
	v_cvt_pk_bf16_f32 v244, v226, v227
	v_cvt_pk_bf16_f32 v245, v228, v229
	v_cvt_pk_bf16_f32 v250, v230, v231
	v_cvt_pk_bf16_f32 v251, v232, v233
	v_cvt_pk_bf16_f32 v252, v234, v235
	v_cvt_pk_bf16_f32 v253, v236, v237
	v_add_f32_e32 v195, v195, v254
	s_nop 1
	s_waitcnt lgkmcnt(8)
	v_mfma_f32_32x32x16_bf16 v[112:127], v[238:241], v[242:245], v[112:127]
	ds_read_b64_tr_b16 v[238:239], v218 offset:16640
	ds_read_b64_tr_b16 v[240:241], v218 offset:20736
	s_waitcnt lgkmcnt(8)
	v_mfma_f32_32x32x16_bf16 v[96:111], v[128:131], v[242:245], v[96:111]
	ds_read_b64_tr_b16 v[222:223], v219 offset:16640
	ds_read_b64_tr_b16 v[224:225], v219 offset:20736
	s_waitcnt lgkmcnt(8)
	v_mfma_f32_32x32x16_bf16 v[80:95], v[206:209], v[242:245], v[80:95]
	ds_read_b64_tr_b16 v[206:207], v221 offset:16640
	ds_read_b64_tr_b16 v[208:209], v221 offset:20736
	s_waitcnt lgkmcnt(8)
	v_mfma_f32_32x32x16_bf16 v[64:79], v[210:213], v[242:245], v[64:79]
	ds_read_b64_tr_b16 v[210:211], v205 offset:24576
	ds_read_b64_tr_b16 v[212:213], v205 offset:28672
	s_waitcnt lgkmcnt(8)
	v_mfma_f32_32x32x16_bf16 v[48:63], v[214:217], v[242:245], v[48:63]
	ds_read_b64_tr_b16 v[214:215], v218 offset:24576
	ds_read_b64_tr_b16 v[216:217], v218 offset:28672
	s_waitcnt lgkmcnt(8)
	v_mfma_f32_32x32x16_bf16 v[32:47], v[238:241], v[242:245], v[32:47]
	ds_read_b64_tr_b16 v[238:239], v219 offset:24576
	ds_read_b64_tr_b16 v[240:241], v219 offset:28672
	s_waitcnt lgkmcnt(8)
	v_mfma_f32_32x32x16_bf16 v[16:31], v[222:225], v[242:245], v[16:31]
	ds_read_b64_tr_b16 v[222:223], v221 offset:24576
	ds_read_b64_tr_b16 v[224:225], v221 offset:28672
	s_waitcnt lgkmcnt(8)
	v_mfma_f32_32x32x16_bf16 v[0:15], v[206:209], v[242:245], v[0:15]
	ds_read_b64_tr_b16 v[206:207], v205 offset:24832
	ds_read_b64_tr_b16 v[208:209], v205 offset:28928
	s_waitcnt lgkmcnt(8)
	v_mfma_f32_32x32x16_bf16 v[112:127], v[210:213], v[250:253], v[112:127]
	ds_read_b64_tr_b16 v[210:211], v218 offset:24832
	ds_read_b64_tr_b16 v[212:213], v218 offset:28928
	s_waitcnt lgkmcnt(8)
	v_mfma_f32_32x32x16_bf16 v[96:111], v[214:217], v[250:253], v[96:111]
	ds_read_b64_tr_b16 v[214:215], v219 offset:24832
	ds_read_b64_tr_b16 v[216:217], v219 offset:28928
	s_waitcnt lgkmcnt(8)
	v_mfma_f32_32x32x16_bf16 v[80:95], v[238:241], v[250:253], v[80:95]
	ds_read_b64_tr_b16 v[238:239], v221 offset:24832
	ds_read_b64_tr_b16 v[240:241], v221 offset:28928
	s_waitcnt lgkmcnt(8)
	v_mfma_f32_32x32x16_bf16 v[64:79], v[222:225], v[250:253], v[64:79]
	s_waitcnt lgkmcnt(6)
	v_mfma_f32_32x32x16_bf16 v[48:63], v[206:209], v[250:253], v[48:63]
	s_waitcnt lgkmcnt(4)
	v_mfma_f32_32x32x16_bf16 v[32:47], v[210:213], v[250:253], v[32:47]
	s_waitcnt lgkmcnt(2)
	v_mfma_f32_32x32x16_bf16 v[16:31], v[214:217], v[250:253], v[16:31]
	s_waitcnt lgkmcnt(0)
	v_mfma_f32_32x32x16_bf16 v[0:15], v[238:241], v[250:253], v[0:15]
	ds_read_b128 v[206:209], v196
	ds_read_b128 v[210:213], v197
	ds_read_b128 v[214:217], v198
	ds_read_b128 v[238:241], v199
	ds_read_b128 v[242:245], v200
	ds_read_b128 v[250:253], v201
	ds_read_b128 v[222:225], v202
	ds_read_b128 v[226:229], v203
	s_waitcnt vmcnt(0)
	s_add_i32 s18, s33, 1
	s_cmp_lg_u32 s33, 2
	s_cselect_b32 s33, s18, 0
	s_add_i32 s4, s4, 64
	s_add_u32 s12, s12, 0x100000
	s_addc_u32 s13, s13, 0
	s_add_i32 s88, s88, 1
	s_add_i32 s100, s4, 63
	s_cmp_le_i32 s100, s83
	s_cbranch_scc0 .Latt_latchb_1
	s_cmp_ge_u32 s88, s82
	s_cselect_b64 s[18:19], -1, 0
	v_mov_b32_e32 v204, v176
	s_barrier
	s_branch .Latt_cont_1s0

.Latt_latchb_2:
	s_waitcnt lgkmcnt(0)
	s_cmp_eq_u32 s79, s84
	s_barrier
	s_cbranch_scc1 .LBB0_900

.Latt_nr0_2s0:
	s_waitcnt lgkmcnt(3)
	v_mfma_f32_32x32x16_bf16 v[222:237], v[214:217], v[152:155], v[222:237]
	ds_read_b128 v[214:217], v201 offset:8192
	v_sub_f32_e32 v128, v128, v190
	v_exp_f32_e32 v128, v128
	v_sub_f32_e32 v129, v129, v190
	v_exp_f32_e32 v129, v129
	v_sub_f32_e32 v130, v130, v190
	s_waitcnt lgkmcnt(3)
	v_mfma_f32_32x32x16_bf16 v[222:237], v[238:241], v[156:159], v[222:237]
	ds_read_b128 v[238:241], v202 offset:8192
	v_add_f32_e32 v254, 0, v128
	v_exp_f32_e32 v130, v130
	v_sub_f32_e32 v131, v131, v190
	v_add_f32_e32 v254, v129, v254
	v_exp_f32_e32 v131, v131
	s_waitcnt lgkmcnt(3)
	v_mfma_f32_32x32x16_bf16 v[222:237], v[206:209], v[160:163], v[222:237]
	ds_read_b64_tr_b16 v[206:207], v205
	ds_read_b64_tr_b16 v[208:209], v205 offset:4096
	v_sub_f32_e32 v132, v132, v190
	v_add_f32_e32 v254, v130, v254
	v_exp_f32_e32 v132, v132
	v_sub_f32_e32 v133, v133, v190
	v_add_f32_e32 v254, v131, v254
	s_waitcnt lgkmcnt(4)
	v_mfma_f32_32x32x16_bf16 v[222:237], v[210:213], v[164:167], v[222:237]
	ds_read_b64_tr_b16 v[210:211], v218
	ds_read_b64_tr_b16 v[212:213], v218 offset:4096
	v_exp_f32_e32 v133, v133
	v_sub_f32_e32 v134, v134, v190
	v_add_f32_e32 v254, v132, v254
	v_exp_f32_e32 v134, v134
	s_waitcnt lgkmcnt(5)
	v_mfma_f32_32x32x16_bf16 v[222:237], v[214:217], v[168:171], v[222:237]
	ds_read_b64_tr_b16 v[214:215], v219
	ds_read_b64_tr_b16 v[216:217], v219 offset:4096
	v_sub_f32_e32 v135, v135, v190
	v_add_f32_e32 v254, v133, v254
	v_exp_f32_e32 v135, v135
	s_nop 0
	s_waitcnt lgkmcnt(6)
	v_mfma_f32_32x32x16_bf16 v[222:237], v[238:241], v[172:175], v[222:237]
	ds_read_b64_tr_b16 v[238:239], v221
	ds_read_b64_tr_b16 v[240:241], v221 offset:4096
	v_cvt_pk_bf16_f32 v242, v128, v129
	v_cvt_pk_bf16_f32 v243, v130, v131
	v_cvt_pk_bf16_f32 v244, v132, v133
	v_cvt_pk_bf16_f32 v245, v134, v135
	s_nop 1
	s_waitcnt lgkmcnt(6)
	v_mfma_f32_32x32x16_bf16 v[112:127], v[206:209], v[242:245], v[112:127]
	ds_read_b64_tr_b16 v[206:207], v205 offset:256
	ds_read_b64_tr_b16 v[208:209], v205 offset:4352
	v_sub_f32_e32 v136, v136, v190
	v_add_f32_e32 v254, v134, v254
	v_exp_f32_e32 v136, v136
	v_sub_f32_e32 v137, v137, v190
	v_add_f32_e32 v254, v135, v254
	s_waitcnt lgkmcnt(6)
	v_mfma_f32_32x32x16_bf16 v[96:111], v[210:213], v[242:245], v[96:111]
	ds_read_b64_tr_b16 v[210:211], v218 offset:256
	ds_read_b64_tr_b16 v[212:213], v218 offset:4352
	v_exp_f32_e32 v137, v137
	v_sub_f32_e32 v138, v138, v190
	v_add_f32_e32 v254, v136, v254
	v_exp_f32_e32 v138, v138
	v_sub_f32_e32 v139, v139, v190
	s_waitcnt lgkmcnt(6)
	v_mfma_f32_32x32x16_bf16 v[80:95], v[214:217], v[242:245], v[80:95]
	ds_read_b64_tr_b16 v[214:215], v219 offset:256
	ds_read_b64_tr_b16 v[216:217], v219 offset:4352
	v_add_f32_e32 v254, v137, v254
	v_exp_f32_e32 v139, v139
	v_sub_f32_e32 v140, v140, v190
	v_add_f32_e32 v254, v138, v254
	s_waitcnt lgkmcnt(6)
	v_mfma_f32_32x32x16_bf16 v[64:79], v[238:241], v[242:245], v[64:79]
	ds_read_b64_tr_b16 v[238:239], v221 offset:256
	ds_read_b64_tr_b16 v[240:241], v221 offset:4352
	v_exp_f32_e32 v140, v140
	v_sub_f32_e32 v141, v141, v190
	v_add_f32_e32 v254, v139, v254
	v_exp_f32_e32 v141, v141
	s_waitcnt lgkmcnt(6)
	v_mfma_f32_32x32x16_bf16 v[48:63], v[206:209], v[242:245], v[48:63]
	ds_read_b64_tr_b16 v[206:207], v205 offset:8192
	ds_read_b64_tr_b16 v[208:209], v205 offset:12288
	v_sub_f32_e32 v142, v142, v190
	v_add_f32_e32 v254, v140, v254
	v_exp_f32_e32 v142, v142
	v_sub_f32_e32 v143, v143, v190
	s_waitcnt lgkmcnt(6)
	v_mfma_f32_32x32x16_bf16 v[32:47], v[210:213], v[242:245], v[32:47]
	ds_read_b64_tr_b16 v[210:211], v218 offset:8192
	ds_read_b64_tr_b16 v[212:213], v218 offset:12288
	v_add_f32_e32 v254, v141, v254
	v_exp_f32_e32 v143, v143
	v_add_f32_e32 v254, v142, v254
	v_add_f32_e32 v254, v143, v254
	s_waitcnt lgkmcnt(6)
	v_mfma_f32_32x32x16_bf16 v[16:31], v[214:217], v[242:245], v[16:31]
	ds_read_b64_tr_b16 v[214:215], v219 offset:8192
	ds_read_b64_tr_b16 v[216:217], v219 offset:12288
	v_cvt_pk_bf16_f32 v250, v136, v137
	v_cvt_pk_bf16_f32 v251, v138, v139
	v_cvt_pk_bf16_f32 v252, v140, v141
	v_cvt_pk_bf16_f32 v253, v142, v143
	v_add_f32_e32 v203, v203, v254
	s_waitcnt lgkmcnt(6)
	v_mfma_f32_32x32x16_bf16 v[0:15], v[238:241], v[242:245], v[0:15]
	ds_read_b64_tr_b16 v[238:239], v221 offset:8192
	ds_read_b64_tr_b16 v[240:241], v221 offset:12288
	ds_read_b64_tr_b16 v[128:129], v205 offset:8448
	ds_read_b64_tr_b16 v[130:131], v205 offset:12544
	s_waitcnt lgkmcnt(8)
	v_mfma_f32_32x32x16_bf16 v[112:127], v[206:209], v[250:253], v[112:127]
	ds_read_b64_tr_b16 v[206:207], v218 offset:8448
	ds_read_b64_tr_b16 v[208:209], v218 offset:12544
	v_max3_f32 v246, v222, v223, v224
	v_max3_f32 v247, v225, v226, v227
	v_max3_f32 v246, v246, v228, v229
	v_max3_f32 v247, v247, v230, v231
	v_max3_f32 v246, v246, v232, v233
	s_waitcnt lgkmcnt(8)
	v_mfma_f32_32x32x16_bf16 v[96:111], v[210:213], v[250:253], v[96:111]
	ds_read_b64_tr_b16 v[210:211], v219 offset:8448
	ds_read_b64_tr_b16 v[212:213], v219 offset:12544
	v_max3_f32 v247, v247, v234, v235
	v_max3_f32 v246, v246, v236, v237
	v_max_f32_e32 v246, v246, v247
	v_mov_b32_e32 v247, v246
	v_add_f32_e32 v249, 0x41000000, v190
	s_waitcnt lgkmcnt(8)
	v_mfma_f32_32x32x16_bf16 v[80:95], v[214:217], v[250:253], v[80:95]
	ds_read_b64_tr_b16 v[214:215], v221 offset:8448
	ds_read_b64_tr_b16 v[216:217], v221 offset:12544
	s_nop 1
	v_permlane32_swap_b32_e32 v246, v247
	v_max_f32_e32 v246, v246, v247
	v_cmp_gt_f32_e32 vcc, v246, v249
	s_cbranch_vccnz .Latt_rs1_2s0
	s_waitcnt lgkmcnt(8)
	v_mfma_f32_32x32x16_bf16 v[64:79], v[238:241], v[250:253], v[64:79]
	ds_read_b64_tr_b16 v[238:239], v205 offset:16384
	ds_read_b64_tr_b16 v[240:241], v205 offset:20480
	v_sub_f32_e32 v222, v222, v190
	v_exp_f32_e32 v222, v222
	v_sub_f32_e32 v223, v223, v190
	v_exp_f32_e32 v223, v223
	v_sub_f32_e32 v224, v224, v190
	v_add_f32_e32 v254, 0, v222
	s_waitcnt lgkmcnt(8)
	v_mfma_f32_32x32x16_bf16 v[48:63], v[128:131], v[250:253], v[48:63]
	ds_read_b64_tr_b16 v[128:129], v218 offset:16384
	ds_read_b64_tr_b16 v[130:131], v218 offset:20480
	v_exp_f32_e32 v224, v224
	v_sub_f32_e32 v225, v225, v190
	v_add_f32_e32 v254, v223, v254
	v_exp_f32_e32 v225, v225
	v_sub_f32_e32 v226, v226, v190
	v_add_f32_e32 v254, v224, v254
	s_waitcnt lgkmcnt(8)
	v_mfma_f32_32x32x16_bf16 v[32:47], v[206:209], v[250:253], v[32:47]
	ds_read_b64_tr_b16 v[206:207], v219 offset:16384
	ds_read_b64_tr_b16 v[208:209], v219 offset:20480
	v_exp_f32_e32 v226, v226
	v_sub_f32_e32 v227, v227, v190
	v_add_f32_e32 v254, v225, v254
	v_exp_f32_e32 v227, v227
	v_sub_f32_e32 v228, v228, v190
	s_waitcnt lgkmcnt(8)
	v_mfma_f32_32x32x16_bf16 v[16:31], v[210:213], v[250:253], v[16:31]
	ds_read_b64_tr_b16 v[210:211], v221 offset:16384
	ds_read_b64_tr_b16 v[212:213], v221 offset:20480
	v_add_f32_e32 v254, v226, v254
	v_exp_f32_e32 v228, v228
	v_sub_f32_e32 v229, v229, v190
	v_add_f32_e32 v254, v227, v254
	v_exp_f32_e32 v229, v229
	s_waitcnt lgkmcnt(8)
	v_mfma_f32_32x32x16_bf16 v[0:15], v[214:217], v[250:253], v[0:15]
	ds_read_b64_tr_b16 v[214:215], v205 offset:16640
	ds_read_b64_tr_b16 v[216:217], v205 offset:20736
	s_nop 0
	v_cvt_pk_bf16_f32 v242, v222, v223
	v_cvt_pk_bf16_f32 v243, v224, v225
	v_cvt_pk_bf16_f32 v244, v226, v227
	v_cvt_pk_bf16_f32 v245, v228, v229
	s_nop 1
	s_waitcnt lgkmcnt(8)
	v_mfma_f32_32x32x16_bf16 v[112:127], v[238:241], v[242:245], v[112:127]
	ds_read_b64_tr_b16 v[238:239], v218 offset:16640
	ds_read_b64_tr_b16 v[240:241], v218 offset:20736
	v_sub_f32_e32 v230, v230, v190
	v_add_f32_e32 v254, v228, v254
	v_exp_f32_e32 v230, v230
	v_sub_f32_e32 v231, v231, v190
	v_add_f32_e32 v254, v229, v254
	s_waitcnt lgkmcnt(8)
	v_mfma_f32_32x32x16_bf16 v[96:111], v[128:131], v[242:245], v[96:111]
	ds_read_b64_tr_b16 v[128:129], v219 offset:16640
	ds_read_b64_tr_b16 v[130:131], v219 offset:20736
	v_exp_f32_e32 v231, v231
	v_sub_f32_e32 v232, v232, v190
	v_add_f32_e32 v254, v230, v254
	v_exp_f32_e32 v232, v232
	v_sub_f32_e32 v233, v233, v190
	s_waitcnt lgkmcnt(8)
	v_mfma_f32_32x32x16_bf16 v[80:95], v[206:209], v[242:245], v[80:95]
	ds_read_b64_tr_b16 v[206:207], v221 offset:16640
	ds_read_b64_tr_b16 v[208:209], v221 offset:20736
	v_add_f32_e32 v254, v231, v254
	v_exp_f32_e32 v233, v233
	v_sub_f32_e32 v234, v234, v190
	v_add_f32_e32 v254, v232, v254
	s_waitcnt lgkmcnt(8)
	v_mfma_f32_32x32x16_bf16 v[64:79], v[210:213], v[242:245], v[64:79]
	ds_read_b64_tr_b16 v[210:211], v205 offset:24576
	ds_read_b64_tr_b16 v[212:213], v205 offset:28672
	v_exp_f32_e32 v234, v234
	v_sub_f32_e32 v235, v235, v190
	v_add_f32_e32 v254, v233, v254
	v_exp_f32_e32 v235, v235
	s_waitcnt lgkmcnt(8)
	v_mfma_f32_32x32x16_bf16 v[48:63], v[214:217], v[242:245], v[48:63]
	ds_read_b64_tr_b16 v[214:215], v218 offset:24576
	ds_read_b64_tr_b16 v[216:217], v218 offset:28672
	v_sub_f32_e32 v236, v236, v190
	v_add_f32_e32 v254, v234, v254
	v_exp_f32_e32 v236, v236
	v_sub_f32_e32 v237, v237, v190
	s_waitcnt lgkmcnt(8)
	v_mfma_f32_32x32x16_bf16 v[32:47], v[238:241], v[242:245], v[32:47]
	ds_read_b64_tr_b16 v[238:239], v219 offset:24576
	ds_read_b64_tr_b16 v[240:241], v219 offset:28672
	v_add_f32_e32 v254, v235, v254
	v_exp_f32_e32 v237, v237
	v_add_f32_e32 v254, v236, v254
	v_add_f32_e32 v254, v237, v254
	s_waitcnt lgkmcnt(8)
	v_mfma_f32_32x32x16_bf16 v[16:31], v[128:131], v[242:245], v[16:31]
	ds_read_b64_tr_b16 v[128:129], v221 offset:24576
	ds_read_b64_tr_b16 v[130:131], v221 offset:28672
	v_cvt_pk_bf16_f32 v250, v230, v231
	v_cvt_pk_bf16_f32 v251, v232, v233
	v_cvt_pk_bf16_f32 v252, v234, v235
	v_cvt_pk_bf16_f32 v253, v236, v237
	v_add_f32_e32 v203, v203, v254
	s_waitcnt lgkmcnt(8)
	v_mfma_f32_32x32x16_bf16 v[0:15], v[206:209], v[242:245], v[0:15]
	ds_read_b64_tr_b16 v[206:207], v205 offset:24832
	ds_read_b64_tr_b16 v[208:209], v205 offset:28928
	s_waitcnt lgkmcnt(8)
	v_mfma_f32_32x32x16_bf16 v[112:127], v[210:213], v[250:253], v[112:127]
	ds_read_b64_tr_b16 v[210:211], v218 offset:24832
	ds_read_b64_tr_b16 v[212:213], v218 offset:28928
	s_waitcnt lgkmcnt(8)
	v_mfma_f32_32x32x16_bf16 v[96:111], v[214:217], v[250:253], v[96:111]
	ds_read_b64_tr_b16 v[214:215], v219 offset:24832
	ds_read_b64_tr_b16 v[216:217], v219 offset:28928
	s_waitcnt lgkmcnt(8)
	v_mfma_f32_32x32x16_bf16 v[80:95], v[238:241], v[250:253], v[80:95]
	ds_read_b64_tr_b16 v[238:239], v221 offset:24832
	ds_read_b64_tr_b16 v[240:241], v221 offset:28928
	s_waitcnt lgkmcnt(8)
	v_mfma_f32_32x32x16_bf16 v[64:79], v[128:131], v[250:253], v[64:79]
	s_waitcnt lgkmcnt(6)
	v_mfma_f32_32x32x16_bf16 v[48:63], v[206:209], v[250:253], v[48:63]
	s_waitcnt lgkmcnt(4)
	v_mfma_f32_32x32x16_bf16 v[32:47], v[210:213], v[250:253], v[32:47]
	s_waitcnt lgkmcnt(2)
	v_mfma_f32_32x32x16_bf16 v[16:31], v[214:217], v[250:253], v[16:31]
	s_waitcnt lgkmcnt(0)
	v_mfma_f32_32x32x16_bf16 v[0:15], v[238:241], v[250:253], v[0:15]
	ds_read_b128 v[206:209], v195 offset:16384
	ds_read_b128 v[210:213], v196 offset:16384
	ds_read_b128 v[214:217], v197 offset:16384
	ds_read_b128 v[238:241], v198 offset:16384
	ds_read_b128 v[242:245], v199 offset:16384
	ds_read_b128 v[250:253], v200 offset:16384
	ds_read_b128 v[222:225], v201 offset:16384
	ds_read_b128 v[226:229], v202 offset:16384
	s_waitcnt vmcnt(0)
	s_add_i32 s12, s38, 1
	s_cmp_lg_u32 s38, 2
	s_cselect_b32 s38, s12, 0
	s_add_i32 s84, s84, 64
	s_add_u32 s22, s22, 0x100000
	s_addc_u32 s23, s23, 0
	s_add_i32 s85, s85, 1
	s_add_i32 s100, s84, 63
	s_cmp_le_i32 s100, s80
	s_cbranch_scc0 .Latt_latchb_2
	s_cmp_ge_u32 s85, s78
	s_cselect_b64 s[12:13], -1, 0
	v_mov_b32_e32 v204, v176
	s_barrier
	s_branch .Latt_cont_2s1
.Latt_rs1_2s0:
	s_waitcnt lgkmcnt(8)
	v_mfma_f32_32x32x16_bf16 v[64:79], v[238:241], v[250:253], v[64:79]
	ds_read_b64_tr_b16 v[238:239], v205 offset:16384
	ds_read_b64_tr_b16 v[240:241], v205 offset:20480
	s_waitcnt lgkmcnt(8)
	v_mfma_f32_32x32x16_bf16 v[48:63], v[128:131], v[250:253], v[48:63]
	ds_read_b64_tr_b16 v[128:129], v218 offset:16384
	ds_read_b64_tr_b16 v[130:131], v218 offset:20480
	s_waitcnt lgkmcnt(8)
	v_mfma_f32_32x32x16_bf16 v[32:47], v[206:209], v[250:253], v[32:47]
	ds_read_b64_tr_b16 v[206:207], v219 offset:16384
	ds_read_b64_tr_b16 v[208:209], v219 offset:20480
	s_waitcnt lgkmcnt(8)
	v_mfma_f32_32x32x16_bf16 v[16:31], v[210:213], v[250:253], v[16:31]
	ds_read_b64_tr_b16 v[210:211], v221 offset:16384
	ds_read_b64_tr_b16 v[212:213], v221 offset:20480
	s_waitcnt lgkmcnt(8)
	v_mfma_f32_32x32x16_bf16 v[0:15], v[214:217], v[250:253], v[0:15]
	ds_read_b64_tr_b16 v[214:215], v205 offset:16640
	ds_read_b64_tr_b16 v[216:217], v205 offset:20736
	s_nop 11
	v_max_f32_e32 v246, v190, v246
	v_sub_f32_e32 v190, v190, v246
	v_exp_f32_e32 v190, v190
	s_nop 0
	v_pk_mul_f32 v[126:127], v[126:127], v[190:191] op_sel_hi:[1,0]
	v_pk_mul_f32 v[124:125], v[124:125], v[190:191] op_sel_hi:[1,0]
	v_pk_mul_f32 v[122:123], v[122:123], v[190:191] op_sel_hi:[1,0]
	v_pk_mul_f32 v[120:121], v[120:121], v[190:191] op_sel_hi:[1,0]
	v_pk_mul_f32 v[118:119], v[118:119], v[190:191] op_sel_hi:[1,0]
	v_pk_mul_f32 v[116:117], v[116:117], v[190:191] op_sel_hi:[1,0]
	v_pk_mul_f32 v[114:115], v[114:115], v[190:191] op_sel_hi:[1,0]
	v_pk_mul_f32 v[112:113], v[112:113], v[190:191] op_sel_hi:[1,0]
	v_pk_mul_f32 v[110:111], v[110:111], v[190:191] op_sel_hi:[1,0]
	v_pk_mul_f32 v[108:109], v[108:109], v[190:191] op_sel_hi:[1,0]
	v_pk_mul_f32 v[106:107], v[106:107], v[190:191] op_sel_hi:[1,0]
	v_pk_mul_f32 v[104:105], v[104:105], v[190:191] op_sel_hi:[1,0]
	v_pk_mul_f32 v[102:103], v[102:103], v[190:191] op_sel_hi:[1,0]
	v_pk_mul_f32 v[100:101], v[100:101], v[190:191] op_sel_hi:[1,0]
	v_pk_mul_f32 v[98:99], v[98:99], v[190:191] op_sel_hi:[1,0]
	v_pk_mul_f32 v[96:97], v[96:97], v[190:191] op_sel_hi:[1,0]
	v_pk_mul_f32 v[94:95], v[94:95], v[190:191] op_sel_hi:[1,0]
	v_pk_mul_f32 v[92:93], v[92:93], v[190:191] op_sel_hi:[1,0]
	v_pk_mul_f32 v[90:91], v[90:91], v[190:191] op_sel_hi:[1,0]
	v_pk_mul_f32 v[88:89], v[88:89], v[190:191] op_sel_hi:[1,0]
	v_pk_mul_f32 v[86:87], v[86:87], v[190:191] op_sel_hi:[1,0]
	v_pk_mul_f32 v[84:85], v[84:85], v[190:191] op_sel_hi:[1,0]
	v_pk_mul_f32 v[82:83], v[82:83], v[190:191] op_sel_hi:[1,0]
	v_pk_mul_f32 v[80:81], v[80:81], v[190:191] op_sel_hi:[1,0]
	v_pk_mul_f32 v[78:79], v[78:79], v[190:191] op_sel_hi:[1,0]
	v_pk_mul_f32 v[76:77], v[76:77], v[190:191] op_sel_hi:[1,0]
	v_pk_mul_f32 v[74:75], v[74:75], v[190:191] op_sel_hi:[1,0]
	v_pk_mul_f32 v[72:73], v[72:73], v[190:191] op_sel_hi:[1,0]
	v_pk_mul_f32 v[70:71], v[70:71], v[190:191] op_sel_hi:[1,0]
	v_pk_mul_f32 v[68:69], v[68:69], v[190:191] op_sel_hi:[1,0]
	v_pk_mul_f32 v[66:67], v[66:67], v[190:191] op_sel_hi:[1,0]
	v_pk_mul_f32 v[64:65], v[64:65], v[190:191] op_sel_hi:[1,0]
	v_pk_mul_f32 v[62:63], v[62:63], v[190:191] op_sel_hi:[1,0]
	v_pk_mul_f32 v[60:61], v[60:61], v[190:191] op_sel_hi:[1,0]
	v_pk_mul_f32 v[58:59], v[58:59], v[190:191] op_sel_hi:[1,0]
	v_pk_mul_f32 v[56:57], v[56:57], v[190:191] op_sel_hi:[1,0]
	v_pk_mul_f32 v[54:55], v[54:55], v[190:191] op_sel_hi:[1,0]
	v_pk_mul_f32 v[52:53], v[52:53], v[190:191] op_sel_hi:[1,0]
	v_pk_mul_f32 v[50:51], v[50:51], v[190:191] op_sel_hi:[1,0]
	v_pk_mul_f32 v[48:49], v[48:49], v[190:191] op_sel_hi:[1,0]
	v_pk_mul_f32 v[46:47], v[46:47], v[190:191] op_sel_hi:[1,0]
	v_pk_mul_f32 v[44:45], v[44:45], v[190:191] op_sel_hi:[1,0]
	v_pk_mul_f32 v[42:43], v[42:43], v[190:191] op_sel_hi:[1,0]
	v_pk_mul_f32 v[40:41], v[40:41], v[190:191] op_sel_hi:[1,0]
	v_pk_mul_f32 v[38:39], v[38:39], v[190:191] op_sel_hi:[1,0]
	v_pk_mul_f32 v[36:37], v[36:37], v[190:191] op_sel_hi:[1,0]
	v_pk_mul_f32 v[34:35], v[34:35], v[190:191] op_sel_hi:[1,0]
	v_pk_mul_f32 v[32:33], v[32:33], v[190:191] op_sel_hi:[1,0]
	v_pk_mul_f32 v[30:31], v[30:31], v[190:191] op_sel_hi:[1,0]
	v_pk_mul_f32 v[28:29], v[28:29], v[190:191] op_sel_hi:[1,0]
	v_pk_mul_f32 v[26:27], v[26:27], v[190:191] op_sel_hi:[1,0]
	v_pk_mul_f32 v[24:25], v[24:25], v[190:191] op_sel_hi:[1,0]
	v_pk_mul_f32 v[22:23], v[22:23], v[190:191] op_sel_hi:[1,0]
	v_pk_mul_f32 v[20:21], v[20:21], v[190:191] op_sel_hi:[1,0]
	v_pk_mul_f32 v[18:19], v[18:19], v[190:191] op_sel_hi:[1,0]
	v_pk_mul_f32 v[16:17], v[16:17], v[190:191] op_sel_hi:[1,0]
	v_pk_mul_f32 v[14:15], v[14:15], v[190:191] op_sel_hi:[1,0]
	v_pk_mul_f32 v[12:13], v[12:13], v[190:191] op_sel_hi:[1,0]
	v_pk_mul_f32 v[10:11], v[10:11], v[190:191] op_sel_hi:[1,0]
	v_pk_mul_f32 v[8:9], v[8:9], v[190:191] op_sel_hi:[1,0]
	v_pk_mul_f32 v[6:7], v[6:7], v[190:191] op_sel_hi:[1,0]
	v_pk_mul_f32 v[4:5], v[4:5], v[190:191] op_sel_hi:[1,0]
	v_pk_mul_f32 v[2:3], v[2:3], v[190:191] op_sel_hi:[1,0]
	v_pk_mul_f32 v[0:1], v[0:1], v[190:191] op_sel_hi:[1,0]
	v_mul_f32_e32 v203, v203, v190
	v_mov_b32_e32 v190, v246
	v_sub_f32_e32 v222, v222, v190
	v_exp_f32_e32 v222, v222
	v_sub_f32_e32 v223, v223, v190
	v_exp_f32_e32 v223, v223
	v_sub_f32_e32 v224, v224, v190
	v_add_f32_e32 v254, 0, v222
	v_exp_f32_e32 v224, v224
	v_sub_f32_e32 v225, v225, v190
	v_add_f32_e32 v254, v223, v254
	v_exp_f32_e32 v225, v225
	v_sub_f32_e32 v226, v226, v190
	v_add_f32_e32 v254, v224, v254
	v_exp_f32_e32 v226, v226
	v_sub_f32_e32 v227, v227, v190
	v_add_f32_e32 v254, v225, v254
	v_exp_f32_e32 v227, v227
	v_sub_f32_e32 v228, v228, v190
	v_add_f32_e32 v254, v226, v254
	v_exp_f32_e32 v228, v228
	v_sub_f32_e32 v229, v229, v190
	v_add_f32_e32 v254, v227, v254
	v_exp_f32_e32 v229, v229
	v_sub_f32_e32 v230, v230, v190
	v_add_f32_e32 v254, v228, v254
	v_exp_f32_e32 v230, v230
	v_sub_f32_e32 v231, v231, v190
	v_add_f32_e32 v254, v229, v254
	v_exp_f32_e32 v231, v231
	v_sub_f32_e32 v232, v232, v190
	v_add_f32_e32 v254, v230, v254
	v_exp_f32_e32 v232, v232
	v_sub_f32_e32 v233, v233, v190
	v_add_f32_e32 v254, v231, v254
	v_exp_f32_e32 v233, v233
	v_sub_f32_e32 v234, v234, v190
	v_add_f32_e32 v254, v232, v254
	v_exp_f32_e32 v234, v234
	v_sub_f32_e32 v235, v235, v190
	v_add_f32_e32 v254, v233, v254
	v_exp_f32_e32 v235, v235
	v_sub_f32_e32 v236, v236, v190
	v_add_f32_e32 v254, v234, v254
	v_exp_f32_e32 v236, v236
	v_sub_f32_e32 v237, v237, v190
	v_add_f32_e32 v254, v235, v254
	v_exp_f32_e32 v237, v237
	v_add_f32_e32 v254, v236, v254
	v_add_f32_e32 v254, v237, v254
	v_cvt_pk_bf16_f32 v242, v222, v223
	v_cvt_pk_bf16_f32 v243, v224, v225
	v_cvt_pk_bf16_f32 v244, v226, v227
	v_cvt_pk_bf16_f32 v245, v228, v229
	v_cvt_pk_bf16_f32 v250, v230, v231
	v_cvt_pk_bf16_f32 v251, v232, v233
	v_cvt_pk_bf16_f32 v252, v234, v235
	v_cvt_pk_bf16_f32 v253, v236, v237
	v_add_f32_e32 v203, v203, v254
	s_nop 1
	s_waitcnt lgkmcnt(8)
	v_mfma_f32_32x32x16_bf16 v[112:127], v[238:241], v[242:245], v[112:127]
	ds_read_b64_tr_b16 v[238:239], v218 offset:16640
	ds_read_b64_tr_b16 v[240:241], v218 offset:20736
	s_waitcnt lgkmcnt(8)
	v_mfma_f32_32x32x16_bf16 v[96:111], v[128:131], v[242:245], v[96:111]
	ds_read_b64_tr_b16 v[222:223], v219 offset:16640
	ds_read_b64_tr_b16 v[224:225], v219 offset:20736
	s_waitcnt lgkmcnt(8)
	v_mfma_f32_32x32x16_bf16 v[80:95], v[206:209], v[242:245], v[80:95]
	ds_read_b64_tr_b16 v[206:207], v221 offset:16640
	ds_read_b64_tr_b16 v[208:209], v221 offset:20736
	s_waitcnt lgkmcnt(8)
	v_mfma_f32_32x32x16_bf16 v[64:79], v[210:213], v[242:245], v[64:79]
	ds_read_b64_tr_b16 v[210:211], v205 offset:24576
	ds_read_b64_tr_b16 v[212:213], v205 offset:28672
	s_waitcnt lgkmcnt(8)
	v_mfma_f32_32x32x16_bf16 v[48:63], v[214:217], v[242:245], v[48:63]
	ds_read_b64_tr_b16 v[214:215], v218 offset:24576
	ds_read_b64_tr_b16 v[216:217], v218 offset:28672
	s_waitcnt lgkmcnt(8)
	v_mfma_f32_32x32x16_bf16 v[32:47], v[238:241], v[242:245], v[32:47]
	ds_read_b64_tr_b16 v[238:239], v219 offset:24576
	ds_read_b64_tr_b16 v[240:241], v219 offset:28672
	s_waitcnt lgkmcnt(8)
	v_mfma_f32_32x32x16_bf16 v[16:31], v[222:225], v[242:245], v[16:31]
	ds_read_b64_tr_b16 v[222:223], v221 offset:24576
	ds_read_b64_tr_b16 v[224:225], v221 offset:28672
	s_waitcnt lgkmcnt(8)
	v_mfma_f32_32x32x16_bf16 v[0:15], v[206:209], v[242:245], v[0:15]
	ds_read_b64_tr_b16 v[206:207], v205 offset:24832
	ds_read_b64_tr_b16 v[208:209], v205 offset:28928
	s_waitcnt lgkmcnt(8)
	v_mfma_f32_32x32x16_bf16 v[112:127], v[210:213], v[250:253], v[112:127]
	ds_read_b64_tr_b16 v[210:211], v218 offset:24832
	ds_read_b64_tr_b16 v[212:213], v218 offset:28928
	s_waitcnt lgkmcnt(8)
	v_mfma_f32_32x32x16_bf16 v[96:111], v[214:217], v[250:253], v[96:111]
	ds_read_b64_tr_b16 v[214:215], v219 offset:24832
	ds_read_b64_tr_b16 v[216:217], v219 offset:28928
	s_waitcnt lgkmcnt(8)
	v_mfma_f32_32x32x16_bf16 v[80:95], v[238:241], v[250:253], v[80:95]
	ds_read_b64_tr_b16 v[238:239], v221 offset:24832
	ds_read_b64_tr_b16 v[240:241], v221 offset:28928
	s_waitcnt lgkmcnt(8)
	v_mfma_f32_32x32x16_bf16 v[64:79], v[222:225], v[250:253], v[64:79]
	s_waitcnt lgkmcnt(6)
	v_mfma_f32_32x32x16_bf16 v[48:63], v[206:209], v[250:253], v[48:63]
	s_waitcnt lgkmcnt(4)
	v_mfma_f32_32x32x16_bf16 v[32:47], v[210:213], v[250:253], v[32:47]
	s_waitcnt lgkmcnt(2)
	v_mfma_f32_32x32x16_bf16 v[16:31], v[214:217], v[250:253], v[16:31]
	s_waitcnt lgkmcnt(0)
	v_mfma_f32_32x32x16_bf16 v[0:15], v[238:241], v[250:253], v[0:15]
	ds_read_b128 v[206:209], v195 offset:16384
	ds_read_b128 v[210:213], v196 offset:16384
	ds_read_b128 v[214:217], v197 offset:16384
	ds_read_b128 v[238:241], v198 offset:16384
	ds_read_b128 v[242:245], v199 offset:16384
	ds_read_b128 v[250:253], v200 offset:16384
	ds_read_b128 v[222:225], v201 offset:16384
	ds_read_b128 v[226:229], v202 offset:16384
	s_waitcnt vmcnt(0)
	s_add_i32 s12, s38, 1
	s_cmp_lg_u32 s38, 2
	s_cselect_b32 s38, s12, 0
	s_add_i32 s84, s84, 64
	s_add_u32 s22, s22, 0x100000
	s_addc_u32 s23, s23, 0
	s_add_i32 s85, s85, 1
	s_add_i32 s100, s84, 63
	s_cmp_le_i32 s100, s80
	s_cbranch_scc0 .Latt_latchb_2
	s_cmp_ge_u32 s85, s78
	s_cselect_b64 s[12:13], -1, 0
	v_mov_b32_e32 v204, v176
	s_barrier
	s_branch .Latt_cont_2s1
.Latt_slow_2s0:
.Latt_slot1_2:
.Latt_cont_2s1:
	v_add_u32_e32 v205, 0x8000, v205
	v_add_u32_e32 v218, 0x8000, v218
	v_add_u32_e32 v219, 0x8000, v219
	v_add_u32_e32 v221, 0x8000, v221
	s_waitcnt lgkmcnt(7)
	v_mfma_f32_32x32x16_bf16 v[128:143], v[206:209], v[144:147], 0
	ds_read_b128 v[206:209], v195 offset:24576
	s_cmp_lg_u64 s[12:13], 0
	s_cbranch_scc1 .Latt_nd0_2s1
	s_sub_i32 s100, s38, 1
	s_cmp_eq_u32 s38, 0
	s_cselect_b32 s100, 2, s100
	s_lshl_b32 s101, s100, 14
	s_add_i32 m0, s40, s101
	s_nop 0
	global_load_lds_dwordx4 v178, s[22:23]

.Latt_nr0_2s1:
	s_waitcnt lgkmcnt(3)
	v_mfma_f32_32x32x16_bf16 v[222:237], v[214:217], v[152:155], v[222:237]
	ds_read_b128 v[214:217], v201 offset:24576
	v_sub_f32_e32 v128, v128, v190
	v_exp_f32_e32 v128, v128
	v_sub_f32_e32 v129, v129, v190
	v_exp_f32_e32 v129, v129
	v_sub_f32_e32 v130, v130, v190
	s_waitcnt lgkmcnt(3)
	v_mfma_f32_32x32x16_bf16 v[222:237], v[238:241], v[156:159], v[222:237]
	ds_read_b128 v[238:241], v202 offset:24576
	v_add_f32_e32 v254, 0, v128
	v_exp_f32_e32 v130, v130
	v_sub_f32_e32 v131, v131, v190
	v_add_f32_e32 v254, v129, v254
	v_exp_f32_e32 v131, v131
	s_waitcnt lgkmcnt(3)
	v_mfma_f32_32x32x16_bf16 v[222:237], v[206:209], v[160:163], v[222:237]
	ds_read_b64_tr_b16 v[206:207], v205
	ds_read_b64_tr_b16 v[208:209], v205 offset:4096
	v_sub_f32_e32 v132, v132, v190
	v_add_f32_e32 v254, v130, v254
	v_exp_f32_e32 v132, v132
	v_sub_f32_e32 v133, v133, v190
	v_add_f32_e32 v254, v131, v254
	s_waitcnt lgkmcnt(4)
	v_mfma_f32_32x32x16_bf16 v[222:237], v[210:213], v[164:167], v[222:237]
	ds_read_b64_tr_b16 v[210:211], v218
	ds_read_b64_tr_b16 v[212:213], v218 offset:4096
	v_exp_f32_e32 v133, v133
	v_sub_f32_e32 v134, v134, v190
	v_add_f32_e32 v254, v132, v254
	v_exp_f32_e32 v134, v134
	s_waitcnt lgkmcnt(5)
	v_mfma_f32_32x32x16_bf16 v[222:237], v[214:217], v[168:171], v[222:237]
	ds_read_b64_tr_b16 v[214:215], v219
	ds_read_b64_tr_b16 v[216:217], v219 offset:4096
	v_sub_f32_e32 v135, v135, v190
	v_add_f32_e32 v254, v133, v254
	v_exp_f32_e32 v135, v135
	s_nop 0
	s_waitcnt lgkmcnt(6)
	v_mfma_f32_32x32x16_bf16 v[222:237], v[238:241], v[172:175], v[222:237]
	ds_read_b64_tr_b16 v[238:239], v221
	ds_read_b64_tr_b16 v[240:241], v221 offset:4096
	v_cvt_pk_bf16_f32 v242, v128, v129
	v_cvt_pk_bf16_f32 v243, v130, v131
	v_cvt_pk_bf16_f32 v244, v132, v133
	v_cvt_pk_bf16_f32 v245, v134, v135
	s_nop 1
	s_waitcnt lgkmcnt(6)
	v_mfma_f32_32x32x16_bf16 v[112:127], v[206:209], v[242:245], v[112:127]
	ds_read_b64_tr_b16 v[206:207], v205 offset:256
	ds_read_b64_tr_b16 v[208:209], v205 offset:4352
	v_sub_f32_e32 v136, v136, v190
	v_add_f32_e32 v254, v134, v254
	v_exp_f32_e32 v136, v136
	v_sub_f32_e32 v137, v137, v190
	v_add_f32_e32 v254, v135, v254
	s_waitcnt lgkmcnt(6)
	v_mfma_f32_32x32x16_bf16 v[96:111], v[210:213], v[242:245], v[96:111]
	ds_read_b64_tr_b16 v[210:211], v218 offset:256
	ds_read_b64_tr_b16 v[212:213], v218 offset:4352
	v_exp_f32_e32 v137, v137
	v_sub_f32_e32 v138, v138, v190
	v_add_f32_e32 v254, v136, v254
	v_exp_f32_e32 v138, v138
	v_sub_f32_e32 v139, v139, v190
	s_waitcnt lgkmcnt(6)
	v_mfma_f32_32x32x16_bf16 v[80:95], v[214:217], v[242:245], v[80:95]
	ds_read_b64_tr_b16 v[214:215], v219 offset:256
	ds_read_b64_tr_b16 v[216:217], v219 offset:4352
	v_add_f32_e32 v254, v137, v254
	v_exp_f32_e32 v139, v139
	v_sub_f32_e32 v140, v140, v190
	v_add_f32_e32 v254, v138, v254
	s_waitcnt lgkmcnt(6)
	v_mfma_f32_32x32x16_bf16 v[64:79], v[238:241], v[242:245], v[64:79]
	ds_read_b64_tr_b16 v[238:239], v221 offset:256
	ds_read_b64_tr_b16 v[240:241], v221 offset:4352
	v_exp_f32_e32 v140, v140
	v_sub_f32_e32 v141, v141, v190
	v_add_f32_e32 v254, v139, v254
	v_exp_f32_e32 v141, v141
	s_waitcnt lgkmcnt(6)
	v_mfma_f32_32x32x16_bf16 v[48:63], v[206:209], v[242:245], v[48:63]
	ds_read_b64_tr_b16 v[206:207], v205 offset:8192
	ds_read_b64_tr_b16 v[208:209], v205 offset:12288
	v_sub_f32_e32 v142, v142, v190
	v_add_f32_e32 v254, v140, v254
	v_exp_f32_e32 v142, v142
	v_sub_f32_e32 v143, v143, v190
	s_waitcnt lgkmcnt(6)
	v_mfma_f32_32x32x16_bf16 v[32:47], v[210:213], v[242:245], v[32:47]
	ds_read_b64_tr_b16 v[210:211], v218 offset:8192
	ds_read_b64_tr_b16 v[212:213], v218 offset:12288
	v_add_f32_e32 v254, v141, v254
	v_exp_f32_e32 v143, v143
	v_add_f32_e32 v254, v142, v254
	v_add_f32_e32 v254, v143, v254
	s_waitcnt lgkmcnt(6)
	v_mfma_f32_32x32x16_bf16 v[16:31], v[214:217], v[242:245], v[16:31]
	ds_read_b64_tr_b16 v[214:215], v219 offset:8192
	ds_read_b64_tr_b16 v[216:217], v219 offset:12288
	v_cvt_pk_bf16_f32 v250, v136, v137
	v_cvt_pk_bf16_f32 v251, v138, v139
	v_cvt_pk_bf16_f32 v252, v140, v141
	v_cvt_pk_bf16_f32 v253, v142, v143
	v_add_f32_e32 v203, v203, v254
	s_waitcnt lgkmcnt(6)
	v_mfma_f32_32x32x16_bf16 v[0:15], v[238:241], v[242:245], v[0:15]
	ds_read_b64_tr_b16 v[238:239], v221 offset:8192
	ds_read_b64_tr_b16 v[240:241], v221 offset:12288
	ds_read_b64_tr_b16 v[128:129], v205 offset:8448
	ds_read_b64_tr_b16 v[130:131], v205 offset:12544
	s_waitcnt lgkmcnt(8)
	v_mfma_f32_32x32x16_bf16 v[112:127], v[206:209], v[250:253], v[112:127]
	ds_read_b64_tr_b16 v[206:207], v218 offset:8448
	ds_read_b64_tr_b16 v[208:209], v218 offset:12544
	v_max3_f32 v246, v222, v223, v224
	v_max3_f32 v247, v225, v226, v227
	v_max3_f32 v246, v246, v228, v229
	v_max3_f32 v247, v247, v230, v231
	v_max3_f32 v246, v246, v232, v233
	s_waitcnt lgkmcnt(8)
	v_mfma_f32_32x32x16_bf16 v[96:111], v[210:213], v[250:253], v[96:111]
	ds_read_b64_tr_b16 v[210:211], v219 offset:8448
	ds_read_b64_tr_b16 v[212:213], v219 offset:12544
	v_max3_f32 v247, v247, v234, v235
	v_max3_f32 v246, v246, v236, v237
	v_max_f32_e32 v246, v246, v247
	v_mov_b32_e32 v247, v246
	v_add_f32_e32 v249, 0x41000000, v190
	s_waitcnt lgkmcnt(8)
	v_mfma_f32_32x32x16_bf16 v[80:95], v[214:217], v[250:253], v[80:95]
	ds_read_b64_tr_b16 v[214:215], v221 offset:8448
	ds_read_b64_tr_b16 v[216:217], v221 offset:12544
	s_nop 1
	v_permlane32_swap_b32_e32 v246, v247
	v_max_f32_e32 v246, v246, v247
	v_cmp_gt_f32_e32 vcc, v246, v249
	s_cbranch_vccnz .Latt_rs1_2s1
	s_waitcnt lgkmcnt(8)
	v_mfma_f32_32x32x16_bf16 v[64:79], v[238:241], v[250:253], v[64:79]
	ds_read_b64_tr_b16 v[238:239], v205 offset:16384
	ds_read_b64_tr_b16 v[240:241], v205 offset:20480
	v_sub_f32_e32 v222, v222, v190
	v_exp_f32_e32 v222, v222
	v_sub_f32_e32 v223, v223, v190
	v_exp_f32_e32 v223, v223
	v_sub_f32_e32 v224, v224, v190
	v_add_f32_e32 v254, 0, v222
	s_waitcnt lgkmcnt(8)
	v_mfma_f32_32x32x16_bf16 v[48:63], v[128:131], v[250:253], v[48:63]
	ds_read_b64_tr_b16 v[128:129], v218 offset:16384
	ds_read_b64_tr_b16 v[130:131], v218 offset:20480
	v_exp_f32_e32 v224, v224
	v_sub_f32_e32 v225, v225, v190
	v_add_f32_e32 v254, v223, v254
	v_exp_f32_e32 v225, v225
	v_sub_f32_e32 v226, v226, v190
	v_add_f32_e32 v254, v224, v254
	s_waitcnt lgkmcnt(8)
	v_mfma_f32_32x32x16_bf16 v[32:47], v[206:209], v[250:253], v[32:47]
	ds_read_b64_tr_b16 v[206:207], v219 offset:16384
	ds_read_b64_tr_b16 v[208:209], v219 offset:20480
	v_exp_f32_e32 v226, v226
	v_sub_f32_e32 v227, v227, v190
	v_add_f32_e32 v254, v225, v254
	v_exp_f32_e32 v227, v227
	v_sub_f32_e32 v228, v228, v190
	s_waitcnt lgkmcnt(8)
	v_mfma_f32_32x32x16_bf16 v[16:31], v[210:213], v[250:253], v[16:31]
	ds_read_b64_tr_b16 v[210:211], v221 offset:16384
	ds_read_b64_tr_b16 v[212:213], v221 offset:20480
	v_add_f32_e32 v254, v226, v254
	v_exp_f32_e32 v228, v228
	v_sub_f32_e32 v229, v229, v190
	v_add_f32_e32 v254, v227, v254
	v_exp_f32_e32 v229, v229
	s_waitcnt lgkmcnt(8)
	v_mfma_f32_32x32x16_bf16 v[0:15], v[214:217], v[250:253], v[0:15]
	ds_read_b64_tr_b16 v[214:215], v205 offset:16640
	ds_read_b64_tr_b16 v[216:217], v205 offset:20736
	s_nop 0
	v_cvt_pk_bf16_f32 v242, v222, v223
	v_cvt_pk_bf16_f32 v243, v224, v225
	v_cvt_pk_bf16_f32 v244, v226, v227
	v_cvt_pk_bf16_f32 v245, v228, v229
	s_nop 1
	s_waitcnt lgkmcnt(8)
	v_mfma_f32_32x32x16_bf16 v[112:127], v[238:241], v[242:245], v[112:127]
	ds_read_b64_tr_b16 v[238:239], v218 offset:16640
	ds_read_b64_tr_b16 v[240:241], v218 offset:20736
	v_sub_f32_e32 v230, v230, v190
	v_add_f32_e32 v254, v228, v254
	v_exp_f32_e32 v230, v230
	v_sub_f32_e32 v231, v231, v190
	v_add_f32_e32 v254, v229, v254
	s_waitcnt lgkmcnt(8)
	v_mfma_f32_32x32x16_bf16 v[96:111], v[128:131], v[242:245], v[96:111]
	ds_read_b64_tr_b16 v[128:129], v219 offset:16640
	ds_read_b64_tr_b16 v[130:131], v219 offset:20736
	v_exp_f32_e32 v231, v231
	v_sub_f32_e32 v232, v232, v190
	v_add_f32_e32 v254, v230, v254
	v_exp_f32_e32 v232, v232
	v_sub_f32_e32 v233, v233, v190
	s_waitcnt lgkmcnt(8)
	v_mfma_f32_32x32x16_bf16 v[80:95], v[206:209], v[242:245], v[80:95]
	ds_read_b64_tr_b16 v[206:207], v221 offset:16640
	ds_read_b64_tr_b16 v[208:209], v221 offset:20736
	v_add_f32_e32 v254, v231, v254
	v_exp_f32_e32 v233, v233
	v_sub_f32_e32 v234, v234, v190
	v_add_f32_e32 v254, v232, v254
	s_waitcnt lgkmcnt(8)
	v_mfma_f32_32x32x16_bf16 v[64:79], v[210:213], v[242:245], v[64:79]
	ds_read_b64_tr_b16 v[210:211], v205 offset:24576
	ds_read_b64_tr_b16 v[212:213], v205 offset:28672
	v_exp_f32_e32 v234, v234
	v_sub_f32_e32 v235, v235, v190
	v_add_f32_e32 v254, v233, v254
	v_exp_f32_e32 v235, v235
	s_waitcnt lgkmcnt(8)
	v_mfma_f32_32x32x16_bf16 v[48:63], v[214:217], v[242:245], v[48:63]
	ds_read_b64_tr_b16 v[214:215], v218 offset:24576
	ds_read_b64_tr_b16 v[216:217], v218 offset:28672
	v_sub_f32_e32 v236, v236, v190
	v_add_f32_e32 v254, v234, v254
	v_exp_f32_e32 v236, v236
	v_sub_f32_e32 v237, v237, v190
	s_waitcnt lgkmcnt(8)
	v_mfma_f32_32x32x16_bf16 v[32:47], v[238:241], v[242:245], v[32:47]
	ds_read_b64_tr_b16 v[238:239], v219 offset:24576
	ds_read_b64_tr_b16 v[240:241], v219 offset:28672
	v_add_f32_e32 v254, v235, v254
	v_exp_f32_e32 v237, v237
	v_add_f32_e32 v254, v236, v254
	v_add_f32_e32 v254, v237, v254
	s_waitcnt lgkmcnt(8)
	v_mfma_f32_32x32x16_bf16 v[16:31], v[128:131], v[242:245], v[16:31]
	ds_read_b64_tr_b16 v[128:129], v221 offset:24576
	ds_read_b64_tr_b16 v[130:131], v221 offset:28672
	v_cvt_pk_bf16_f32 v250, v230, v231
	v_cvt_pk_bf16_f32 v251, v232, v233
	v_cvt_pk_bf16_f32 v252, v234, v235
	v_cvt_pk_bf16_f32 v253, v236, v237
	v_add_f32_e32 v203, v203, v254
	s_waitcnt lgkmcnt(8)
	v_mfma_f32_32x32x16_bf16 v[0:15], v[206:209], v[242:245], v[0:15]
	ds_read_b64_tr_b16 v[206:207], v205 offset:24832
	ds_read_b64_tr_b16 v[208:209], v205 offset:28928
	s_waitcnt lgkmcnt(8)
	v_mfma_f32_32x32x16_bf16 v[112:127], v[210:213], v[250:253], v[112:127]
	ds_read_b64_tr_b16 v[210:211], v218 offset:24832
	ds_read_b64_tr_b16 v[212:213], v218 offset:28928
	s_waitcnt lgkmcnt(8)
	v_mfma_f32_32x32x16_bf16 v[96:111], v[214:217], v[250:253], v[96:111]
	ds_read_b64_tr_b16 v[214:215], v219 offset:24832
	ds_read_b64_tr_b16 v[216:217], v219 offset:28928
	s_waitcnt lgkmcnt(8)
	v_mfma_f32_32x32x16_bf16 v[80:95], v[238:241], v[250:253], v[80:95]
	ds_read_b64_tr_b16 v[238:239], v221 offset:24832
	ds_read_b64_tr_b16 v[240:241], v221 offset:28928
	s_waitcnt lgkmcnt(8)
	v_mfma_f32_32x32x16_bf16 v[64:79], v[128:131], v[250:253], v[64:79]
	s_waitcnt lgkmcnt(6)
	v_mfma_f32_32x32x16_bf16 v[48:63], v[206:209], v[250:253], v[48:63]
	s_waitcnt lgkmcnt(4)
	v_mfma_f32_32x32x16_bf16 v[32:47], v[210:213], v[250:253], v[32:47]
	s_waitcnt lgkmcnt(2)
	v_mfma_f32_32x32x16_bf16 v[16:31], v[214:217], v[250:253], v[16:31]
	s_waitcnt lgkmcnt(0)
	v_mfma_f32_32x32x16_bf16 v[0:15], v[238:241], v[250:253], v[0:15]
	ds_read_b128 v[206:209], v195 offset:32768
	ds_read_b128 v[210:213], v196 offset:32768
	ds_read_b128 v[214:217], v197 offset:32768
	ds_read_b128 v[238:241], v198 offset:32768
	ds_read_b128 v[242:245], v199 offset:32768
	ds_read_b128 v[250:253], v200 offset:32768
	ds_read_b128 v[222:225], v201 offset:32768
	ds_read_b128 v[226:229], v202 offset:32768
	s_waitcnt vmcnt(0)
	s_add_i32 s12, s38, 1
	s_cmp_lg_u32 s38, 2
	s_cselect_b32 s38, s12, 0
	s_add_i32 s84, s84, 64
	s_add_u32 s22, s22, 0x100000
	s_addc_u32 s23, s23, 0
	s_add_i32 s85, s85, 1
	s_add_i32 s100, s84, 63
	s_cmp_le_i32 s100, s80
	s_cbranch_scc0 .Latt_latchb_2
	s_cmp_ge_u32 s85, s78
	s_cselect_b64 s[12:13], -1, 0
	v_mov_b32_e32 v204, v176
	s_barrier
	s_branch .Latt_cont_2s2
.Latt_rs1_2s1:
	s_waitcnt lgkmcnt(8)
	v_mfma_f32_32x32x16_bf16 v[64:79], v[238:241], v[250:253], v[64:79]
	ds_read_b64_tr_b16 v[238:239], v205 offset:16384
	ds_read_b64_tr_b16 v[240:241], v205 offset:20480
	s_waitcnt lgkmcnt(8)
	v_mfma_f32_32x32x16_bf16 v[48:63], v[128:131], v[250:253], v[48:63]
	ds_read_b64_tr_b16 v[128:129], v218 offset:16384
	ds_read_b64_tr_b16 v[130:131], v218 offset:20480
	s_waitcnt lgkmcnt(8)
	v_mfma_f32_32x32x16_bf16 v[32:47], v[206:209], v[250:253], v[32:47]
	ds_read_b64_tr_b16 v[206:207], v219 offset:16384
	ds_read_b64_tr_b16 v[208:209], v219 offset:20480
	s_waitcnt lgkmcnt(8)
	v_mfma_f32_32x32x16_bf16 v[16:31], v[210:213], v[250:253], v[16:31]
	ds_read_b64_tr_b16 v[210:211], v221 offset:16384
	ds_read_b64_tr_b16 v[212:213], v221 offset:20480
	s_waitcnt lgkmcnt(8)
	v_mfma_f32_32x32x16_bf16 v[0:15], v[214:217], v[250:253], v[0:15]
	ds_read_b64_tr_b16 v[214:215], v205 offset:16640
	ds_read_b64_tr_b16 v[216:217], v205 offset:20736
	s_nop 11
	v_max_f32_e32 v246, v190, v246
	v_sub_f32_e32 v190, v190, v246
	v_exp_f32_e32 v190, v190
	s_nop 0
	v_pk_mul_f32 v[126:127], v[126:127], v[190:191] op_sel_hi:[1,0]
	v_pk_mul_f32 v[124:125], v[124:125], v[190:191] op_sel_hi:[1,0]
	v_pk_mul_f32 v[122:123], v[122:123], v[190:191] op_sel_hi:[1,0]
	v_pk_mul_f32 v[120:121], v[120:121], v[190:191] op_sel_hi:[1,0]
	v_pk_mul_f32 v[118:119], v[118:119], v[190:191] op_sel_hi:[1,0]
	v_pk_mul_f32 v[116:117], v[116:117], v[190:191] op_sel_hi:[1,0]
	v_pk_mul_f32 v[114:115], v[114:115], v[190:191] op_sel_hi:[1,0]
	v_pk_mul_f32 v[112:113], v[112:113], v[190:191] op_sel_hi:[1,0]
	v_pk_mul_f32 v[110:111], v[110:111], v[190:191] op_sel_hi:[1,0]
	v_pk_mul_f32 v[108:109], v[108:109], v[190:191] op_sel_hi:[1,0]
	v_pk_mul_f32 v[106:107], v[106:107], v[190:191] op_sel_hi:[1,0]
	v_pk_mul_f32 v[104:105], v[104:105], v[190:191] op_sel_hi:[1,0]
	v_pk_mul_f32 v[102:103], v[102:103], v[190:191] op_sel_hi:[1,0]
	v_pk_mul_f32 v[100:101], v[100:101], v[190:191] op_sel_hi:[1,0]
	v_pk_mul_f32 v[98:99], v[98:99], v[190:191] op_sel_hi:[1,0]
	v_pk_mul_f32 v[96:97], v[96:97], v[190:191] op_sel_hi:[1,0]
	v_pk_mul_f32 v[94:95], v[94:95], v[190:191] op_sel_hi:[1,0]
	v_pk_mul_f32 v[92:93], v[92:93], v[190:191] op_sel_hi:[1,0]
	v_pk_mul_f32 v[90:91], v[90:91], v[190:191] op_sel_hi:[1,0]
	v_pk_mul_f32 v[88:89], v[88:89], v[190:191] op_sel_hi:[1,0]
	v_pk_mul_f32 v[86:87], v[86:87], v[190:191] op_sel_hi:[1,0]
	v_pk_mul_f32 v[84:85], v[84:85], v[190:191] op_sel_hi:[1,0]
	v_pk_mul_f32 v[82:83], v[82:83], v[190:191] op_sel_hi:[1,0]
	v_pk_mul_f32 v[80:81], v[80:81], v[190:191] op_sel_hi:[1,0]
	v_pk_mul_f32 v[78:79], v[78:79], v[190:191] op_sel_hi:[1,0]
	v_pk_mul_f32 v[76:77], v[76:77], v[190:191] op_sel_hi:[1,0]
	v_pk_mul_f32 v[74:75], v[74:75], v[190:191] op_sel_hi:[1,0]
	v_pk_mul_f32 v[72:73], v[72:73], v[190:191] op_sel_hi:[1,0]
	v_pk_mul_f32 v[70:71], v[70:71], v[190:191] op_sel_hi:[1,0]
	v_pk_mul_f32 v[68:69], v[68:69], v[190:191] op_sel_hi:[1,0]
	v_pk_mul_f32 v[66:67], v[66:67], v[190:191] op_sel_hi:[1,0]
	v_pk_mul_f32 v[64:65], v[64:65], v[190:191] op_sel_hi:[1,0]
	v_pk_mul_f32 v[62:63], v[62:63], v[190:191] op_sel_hi:[1,0]
	v_pk_mul_f32 v[60:61], v[60:61], v[190:191] op_sel_hi:[1,0]
	v_pk_mul_f32 v[58:59], v[58:59], v[190:191] op_sel_hi:[1,0]
	v_pk_mul_f32 v[56:57], v[56:57], v[190:191] op_sel_hi:[1,0]
	v_pk_mul_f32 v[54:55], v[54:55], v[190:191] op_sel_hi:[1,0]
	v_pk_mul_f32 v[52:53], v[52:53], v[190:191] op_sel_hi:[1,0]
	v_pk_mul_f32 v[50:51], v[50:51], v[190:191] op_sel_hi:[1,0]
	v_pk_mul_f32 v[48:49], v[48:49], v[190:191] op_sel_hi:[1,0]
	v_pk_mul_f32 v[46:47], v[46:47], v[190:191] op_sel_hi:[1,0]
	v_pk_mul_f32 v[44:45], v[44:45], v[190:191] op_sel_hi:[1,0]
	v_pk_mul_f32 v[42:43], v[42:43], v[190:191] op_sel_hi:[1,0]
	v_pk_mul_f32 v[40:41], v[40:41], v[190:191] op_sel_hi:[1,0]
	v_pk_mul_f32 v[38:39], v[38:39], v[190:191] op_sel_hi:[1,0]
	v_pk_mul_f32 v[36:37], v[36:37], v[190:191] op_sel_hi:[1,0]
	v_pk_mul_f32 v[34:35], v[34:35], v[190:191] op_sel_hi:[1,0]
	v_pk_mul_f32 v[32:33], v[32:33], v[190:191] op_sel_hi:[1,0]
	v_pk_mul_f32 v[30:31], v[30:31], v[190:191] op_sel_hi:[1,0]
	v_pk_mul_f32 v[28:29], v[28:29], v[190:191] op_sel_hi:[1,0]
	v_pk_mul_f32 v[26:27], v[26:27], v[190:191] op_sel_hi:[1,0]
	v_pk_mul_f32 v[24:25], v[24:25], v[190:191] op_sel_hi:[1,0]
	v_pk_mul_f32 v[22:23], v[22:23], v[190:191] op_sel_hi:[1,0]
	v_pk_mul_f32 v[20:21], v[20:21], v[190:191] op_sel_hi:[1,0]
	v_pk_mul_f32 v[18:19], v[18:19], v[190:191] op_sel_hi:[1,0]
	v_pk_mul_f32 v[16:17], v[16:17], v[190:191] op_sel_hi:[1,0]
	v_pk_mul_f32 v[14:15], v[14:15], v[190:191] op_sel_hi:[1,0]
	v_pk_mul_f32 v[12:13], v[12:13], v[190:191] op_sel_hi:[1,0]
	v_pk_mul_f32 v[10:11], v[10:11], v[190:191] op_sel_hi:[1,0]
	v_pk_mul_f32 v[8:9], v[8:9], v[190:191] op_sel_hi:[1,0]
	v_pk_mul_f32 v[6:7], v[6:7], v[190:191] op_sel_hi:[1,0]
	v_pk_mul_f32 v[4:5], v[4:5], v[190:191] op_sel_hi:[1,0]
	v_pk_mul_f32 v[2:3], v[2:3], v[190:191] op_sel_hi:[1,0]
	v_pk_mul_f32 v[0:1], v[0:1], v[190:191] op_sel_hi:[1,0]
	v_mul_f32_e32 v203, v203, v190
	v_mov_b32_e32 v190, v246
	v_sub_f32_e32 v222, v222, v190
	v_exp_f32_e32 v222, v222
	v_sub_f32_e32 v223, v223, v190
	v_exp_f32_e32 v223, v223
	v_sub_f32_e32 v224, v224, v190
	v_add_f32_e32 v254, 0, v222
	v_exp_f32_e32 v224, v224
	v_sub_f32_e32 v225, v225, v190
	v_add_f32_e32 v254, v223, v254
	v_exp_f32_e32 v225, v225
	v_sub_f32_e32 v226, v226, v190
	v_add_f32_e32 v254, v224, v254
	v_exp_f32_e32 v226, v226
	v_sub_f32_e32 v227, v227, v190
	v_add_f32_e32 v254, v225, v254
	v_exp_f32_e32 v227, v227
	v_sub_f32_e32 v228, v228, v190
	v_add_f32_e32 v254, v226, v254
	v_exp_f32_e32 v228, v228
	v_sub_f32_e32 v229, v229, v190
	v_add_f32_e32 v254, v227, v254
	v_exp_f32_e32 v229, v229
	v_sub_f32_e32 v230, v230, v190
	v_add_f32_e32 v254, v228, v254
	v_exp_f32_e32 v230, v230
	v_sub_f32_e32 v231, v231, v190
	v_add_f32_e32 v254, v229, v254
	v_exp_f32_e32 v231, v231
	v_sub_f32_e32 v232, v232, v190
	v_add_f32_e32 v254, v230, v254
	v_exp_f32_e32 v232, v232
	v_sub_f32_e32 v233, v233, v190
	v_add_f32_e32 v254, v231, v254
	v_exp_f32_e32 v233, v233
	v_sub_f32_e32 v234, v234, v190
	v_add_f32_e32 v254, v232, v254
	v_exp_f32_e32 v234, v234
	v_sub_f32_e32 v235, v235, v190
	v_add_f32_e32 v254, v233, v254
	v_exp_f32_e32 v235, v235
	v_sub_f32_e32 v236, v236, v190
	v_add_f32_e32 v254, v234, v254
	v_exp_f32_e32 v236, v236
	v_sub_f32_e32 v237, v237, v190
	v_add_f32_e32 v254, v235, v254
	v_exp_f32_e32 v237, v237
	v_add_f32_e32 v254, v236, v254
	v_add_f32_e32 v254, v237, v254
	v_cvt_pk_bf16_f32 v242, v222, v223
	v_cvt_pk_bf16_f32 v243, v224, v225
	v_cvt_pk_bf16_f32 v244, v226, v227
	v_cvt_pk_bf16_f32 v245, v228, v229
	v_cvt_pk_bf16_f32 v250, v230, v231
	v_cvt_pk_bf16_f32 v251, v232, v233
	v_cvt_pk_bf16_f32 v252, v234, v235
	v_cvt_pk_bf16_f32 v253, v236, v237
	v_add_f32_e32 v203, v203, v254
	s_nop 1
	s_waitcnt lgkmcnt(8)
	v_mfma_f32_32x32x16_bf16 v[112:127], v[238:241], v[242:245], v[112:127]
	ds_read_b64_tr_b16 v[238:239], v218 offset:16640
	ds_read_b64_tr_b16 v[240:241], v218 offset:20736
	s_waitcnt lgkmcnt(8)
	v_mfma_f32_32x32x16_bf16 v[96:111], v[128:131], v[242:245], v[96:111]
	ds_read_b64_tr_b16 v[222:223], v219 offset:16640
	ds_read_b64_tr_b16 v[224:225], v219 offset:20736
	s_waitcnt lgkmcnt(8)
	v_mfma_f32_32x32x16_bf16 v[80:95], v[206:209], v[242:245], v[80:95]
	ds_read_b64_tr_b16 v[206:207], v221 offset:16640
	ds_read_b64_tr_b16 v[208:209], v221 offset:20736
	s_waitcnt lgkmcnt(8)
	v_mfma_f32_32x32x16_bf16 v[64:79], v[210:213], v[242:245], v[64:79]
	ds_read_b64_tr_b16 v[210:211], v205 offset:24576
	ds_read_b64_tr_b16 v[212:213], v205 offset:28672
	s_waitcnt lgkmcnt(8)
	v_mfma_f32_32x32x16_bf16 v[48:63], v[214:217], v[242:245], v[48:63]
	ds_read_b64_tr_b16 v[214:215], v218 offset:24576
	ds_read_b64_tr_b16 v[216:217], v218 offset:28672
	s_waitcnt lgkmcnt(8)
	v_mfma_f32_32x32x16_bf16 v[32:47], v[238:241], v[242:245], v[32:47]
	ds_read_b64_tr_b16 v[238:239], v219 offset:24576
	ds_read_b64_tr_b16 v[240:241], v219 offset:28672
	s_waitcnt lgkmcnt(8)
	v_mfma_f32_32x32x16_bf16 v[16:31], v[222:225], v[242:245], v[16:31]
	ds_read_b64_tr_b16 v[222:223], v221 offset:24576
	ds_read_b64_tr_b16 v[224:225], v221 offset:28672
	s_waitcnt lgkmcnt(8)
	v_mfma_f32_32x32x16_bf16 v[0:15], v[206:209], v[242:245], v[0:15]
	ds_read_b64_tr_b16 v[206:207], v205 offset:24832
	ds_read_b64_tr_b16 v[208:209], v205 offset:28928
	s_waitcnt lgkmcnt(8)
	v_mfma_f32_32x32x16_bf16 v[112:127], v[210:213], v[250:253], v[112:127]
	ds_read_b64_tr_b16 v[210:211], v218 offset:24832
	ds_read_b64_tr_b16 v[212:213], v218 offset:28928
	s_waitcnt lgkmcnt(8)
	v_mfma_f32_32x32x16_bf16 v[96:111], v[214:217], v[250:253], v[96:111]
	ds_read_b64_tr_b16 v[214:215], v219 offset:24832
	ds_read_b64_tr_b16 v[216:217], v219 offset:28928
	s_waitcnt lgkmcnt(8)
	v_mfma_f32_32x32x16_bf16 v[80:95], v[238:241], v[250:253], v[80:95]
	ds_read_b64_tr_b16 v[238:239], v221 offset:24832
	ds_read_b64_tr_b16 v[240:241], v221 offset:28928
	s_waitcnt lgkmcnt(8)
	v_mfma_f32_32x32x16_bf16 v[64:79], v[222:225], v[250:253], v[64:79]
	s_waitcnt lgkmcnt(6)
	v_mfma_f32_32x32x16_bf16 v[48:63], v[206:209], v[250:253], v[48:63]
	s_waitcnt lgkmcnt(4)
	v_mfma_f32_32x32x16_bf16 v[32:47], v[210:213], v[250:253], v[32:47]
	s_waitcnt lgkmcnt(2)
	v_mfma_f32_32x32x16_bf16 v[16:31], v[214:217], v[250:253], v[16:31]
	s_waitcnt lgkmcnt(0)
	v_mfma_f32_32x32x16_bf16 v[0:15], v[238:241], v[250:253], v[0:15]
	ds_read_b128 v[206:209], v195 offset:32768
	ds_read_b128 v[210:213], v196 offset:32768
	ds_read_b128 v[214:217], v197 offset:32768
	ds_read_b128 v[238:241], v198 offset:32768
	ds_read_b128 v[242:245], v199 offset:32768
	ds_read_b128 v[250:253], v200 offset:32768
	ds_read_b128 v[222:225], v201 offset:32768
	ds_read_b128 v[226:229], v202 offset:32768
	s_waitcnt vmcnt(0)
	s_add_i32 s12, s38, 1
	s_cmp_lg_u32 s38, 2
	s_cselect_b32 s38, s12, 0
	s_add_i32 s84, s84, 64
	s_add_u32 s22, s22, 0x100000
	s_addc_u32 s23, s23, 0
	s_add_i32 s85, s85, 1
	s_add_i32 s100, s84, 63
	s_cmp_le_i32 s100, s80
	s_cbranch_scc0 .Latt_latchb_2
	s_cmp_ge_u32 s85, s78
	s_cselect_b64 s[12:13], -1, 0
	v_mov_b32_e32 v204, v176
	s_barrier
	s_branch .Latt_cont_2s2
.Latt_slow_2s1:
.Latt_slot2_2:
.Latt_cont_2s2:
	v_add_u32_e32 v205, 0x8000, v205
	v_add_u32_e32 v218, 0x8000, v218
	v_add_u32_e32 v219, 0x8000, v219
	v_add_u32_e32 v221, 0x8000, v221
	s_waitcnt lgkmcnt(7)
	v_mfma_f32_32x32x16_bf16 v[128:143], v[206:209], v[144:147], 0
	ds_read_b128 v[206:209], v195 offset:40960
	s_cmp_lg_u64 s[12:13], 0
	s_cbranch_scc1 .Latt_nd0_2s2
	s_sub_i32 s100, s38, 1
	s_cmp_eq_u32 s38, 0
	s_cselect_b32 s100, 2, s100
	s_lshl_b32 s101, s100, 14
	s_add_i32 m0, s40, s101
	s_nop 0
	global_load_lds_dwordx4 v178, s[22:23]

.Latt_nr0_2s2:
	s_waitcnt lgkmcnt(3)
	v_mfma_f32_32x32x16_bf16 v[222:237], v[214:217], v[152:155], v[222:237]
	ds_read_b128 v[214:217], v201 offset:40960
	v_sub_f32_e32 v128, v128, v190
	v_exp_f32_e32 v128, v128
	v_sub_f32_e32 v129, v129, v190
	v_exp_f32_e32 v129, v129
	v_sub_f32_e32 v130, v130, v190
	s_waitcnt lgkmcnt(3)
	v_mfma_f32_32x32x16_bf16 v[222:237], v[238:241], v[156:159], v[222:237]
	ds_read_b128 v[238:241], v202 offset:40960
	v_add_f32_e32 v254, 0, v128
	v_exp_f32_e32 v130, v130
	v_sub_f32_e32 v131, v131, v190
	v_add_f32_e32 v254, v129, v254
	v_exp_f32_e32 v131, v131
	s_waitcnt lgkmcnt(3)
	v_mfma_f32_32x32x16_bf16 v[222:237], v[206:209], v[160:163], v[222:237]
	ds_read_b64_tr_b16 v[206:207], v205
	ds_read_b64_tr_b16 v[208:209], v205 offset:4096
	v_sub_f32_e32 v132, v132, v190
	v_add_f32_e32 v254, v130, v254
	v_exp_f32_e32 v132, v132
	v_sub_f32_e32 v133, v133, v190
	v_add_f32_e32 v254, v131, v254
	s_waitcnt lgkmcnt(4)
	v_mfma_f32_32x32x16_bf16 v[222:237], v[210:213], v[164:167], v[222:237]
	ds_read_b64_tr_b16 v[210:211], v218
	ds_read_b64_tr_b16 v[212:213], v218 offset:4096
	v_exp_f32_e32 v133, v133
	v_sub_f32_e32 v134, v134, v190
	v_add_f32_e32 v254, v132, v254
	v_exp_f32_e32 v134, v134
	s_waitcnt lgkmcnt(5)
	v_mfma_f32_32x32x16_bf16 v[222:237], v[214:217], v[168:171], v[222:237]
	ds_read_b64_tr_b16 v[214:215], v219
	ds_read_b64_tr_b16 v[216:217], v219 offset:4096
	v_sub_f32_e32 v135, v135, v190
	v_add_f32_e32 v254, v133, v254
	v_exp_f32_e32 v135, v135
	s_nop 0
	s_waitcnt lgkmcnt(6)
	v_mfma_f32_32x32x16_bf16 v[222:237], v[238:241], v[172:175], v[222:237]
	ds_read_b64_tr_b16 v[238:239], v221
	ds_read_b64_tr_b16 v[240:241], v221 offset:4096
	v_cvt_pk_bf16_f32 v242, v128, v129
	v_cvt_pk_bf16_f32 v243, v130, v131
	v_cvt_pk_bf16_f32 v244, v132, v133
	v_cvt_pk_bf16_f32 v245, v134, v135
	s_nop 1
	s_waitcnt lgkmcnt(6)
	v_mfma_f32_32x32x16_bf16 v[112:127], v[206:209], v[242:245], v[112:127]
	ds_read_b64_tr_b16 v[206:207], v205 offset:256
	ds_read_b64_tr_b16 v[208:209], v205 offset:4352
	v_sub_f32_e32 v136, v136, v190
	v_add_f32_e32 v254, v134, v254
	v_exp_f32_e32 v136, v136
	v_sub_f32_e32 v137, v137, v190
	v_add_f32_e32 v254, v135, v254
	s_waitcnt lgkmcnt(6)
	v_mfma_f32_32x32x16_bf16 v[96:111], v[210:213], v[242:245], v[96:111]
	ds_read_b64_tr_b16 v[210:211], v218 offset:256
	ds_read_b64_tr_b16 v[212:213], v218 offset:4352
	v_exp_f32_e32 v137, v137
	v_sub_f32_e32 v138, v138, v190
	v_add_f32_e32 v254, v136, v254
	v_exp_f32_e32 v138, v138
	v_sub_f32_e32 v139, v139, v190
	s_waitcnt lgkmcnt(6)
	v_mfma_f32_32x32x16_bf16 v[80:95], v[214:217], v[242:245], v[80:95]
	ds_read_b64_tr_b16 v[214:215], v219 offset:256
	ds_read_b64_tr_b16 v[216:217], v219 offset:4352
	v_add_f32_e32 v254, v137, v254
	v_exp_f32_e32 v139, v139
	v_sub_f32_e32 v140, v140, v190
	v_add_f32_e32 v254, v138, v254
	s_waitcnt lgkmcnt(6)
	v_mfma_f32_32x32x16_bf16 v[64:79], v[238:241], v[242:245], v[64:79]
	ds_read_b64_tr_b16 v[238:239], v221 offset:256
	ds_read_b64_tr_b16 v[240:241], v221 offset:4352
	v_exp_f32_e32 v140, v140
	v_sub_f32_e32 v141, v141, v190
	v_add_f32_e32 v254, v139, v254
	v_exp_f32_e32 v141, v141
	s_waitcnt lgkmcnt(6)
	v_mfma_f32_32x32x16_bf16 v[48:63], v[206:209], v[242:245], v[48:63]
	ds_read_b64_tr_b16 v[206:207], v205 offset:8192
	ds_read_b64_tr_b16 v[208:209], v205 offset:12288
	v_sub_f32_e32 v142, v142, v190
	v_add_f32_e32 v254, v140, v254
	v_exp_f32_e32 v142, v142
	v_sub_f32_e32 v143, v143, v190
	s_waitcnt lgkmcnt(6)
	v_mfma_f32_32x32x16_bf16 v[32:47], v[210:213], v[242:245], v[32:47]
	ds_read_b64_tr_b16 v[210:211], v218 offset:8192
	ds_read_b64_tr_b16 v[212:213], v218 offset:12288
	v_add_f32_e32 v254, v141, v254
	v_exp_f32_e32 v143, v143
	v_add_f32_e32 v254, v142, v254
	v_add_f32_e32 v254, v143, v254
	s_waitcnt lgkmcnt(6)
	v_mfma_f32_32x32x16_bf16 v[16:31], v[214:217], v[242:245], v[16:31]
	ds_read_b64_tr_b16 v[214:215], v219 offset:8192
	ds_read_b64_tr_b16 v[216:217], v219 offset:12288
	v_cvt_pk_bf16_f32 v250, v136, v137
	v_cvt_pk_bf16_f32 v251, v138, v139
	v_cvt_pk_bf16_f32 v252, v140, v141
	v_cvt_pk_bf16_f32 v253, v142, v143
	v_add_f32_e32 v203, v203, v254
	s_waitcnt lgkmcnt(6)
	v_mfma_f32_32x32x16_bf16 v[0:15], v[238:241], v[242:245], v[0:15]
	ds_read_b64_tr_b16 v[238:239], v221 offset:8192
	ds_read_b64_tr_b16 v[240:241], v221 offset:12288
	ds_read_b64_tr_b16 v[128:129], v205 offset:8448
	ds_read_b64_tr_b16 v[130:131], v205 offset:12544
	s_waitcnt lgkmcnt(8)
	v_mfma_f32_32x32x16_bf16 v[112:127], v[206:209], v[250:253], v[112:127]
	ds_read_b64_tr_b16 v[206:207], v218 offset:8448
	ds_read_b64_tr_b16 v[208:209], v218 offset:12544
	v_max3_f32 v246, v222, v223, v224
	v_max3_f32 v247, v225, v226, v227
	v_max3_f32 v246, v246, v228, v229
	v_max3_f32 v247, v247, v230, v231
	v_max3_f32 v246, v246, v232, v233
	s_waitcnt lgkmcnt(8)
	v_mfma_f32_32x32x16_bf16 v[96:111], v[210:213], v[250:253], v[96:111]
	ds_read_b64_tr_b16 v[210:211], v219 offset:8448
	ds_read_b64_tr_b16 v[212:213], v219 offset:12544
	v_max3_f32 v247, v247, v234, v235
	v_max3_f32 v246, v246, v236, v237
	v_max_f32_e32 v246, v246, v247
	v_mov_b32_e32 v247, v246
	v_add_f32_e32 v249, 0x41000000, v190
	s_waitcnt lgkmcnt(8)
	v_mfma_f32_32x32x16_bf16 v[80:95], v[214:217], v[250:253], v[80:95]
	ds_read_b64_tr_b16 v[214:215], v221 offset:8448
	ds_read_b64_tr_b16 v[216:217], v221 offset:12544
	s_nop 1
	v_permlane32_swap_b32_e32 v246, v247
	v_max_f32_e32 v246, v246, v247
	v_cmp_gt_f32_e32 vcc, v246, v249
	s_cbranch_vccnz .Latt_rs1_2s2
	s_waitcnt lgkmcnt(8)
	v_mfma_f32_32x32x16_bf16 v[64:79], v[238:241], v[250:253], v[64:79]
	ds_read_b64_tr_b16 v[238:239], v205 offset:16384
	ds_read_b64_tr_b16 v[240:241], v205 offset:20480
	v_sub_f32_e32 v222, v222, v190
	v_exp_f32_e32 v222, v222
	v_sub_f32_e32 v223, v223, v190
	v_exp_f32_e32 v223, v223
	v_sub_f32_e32 v224, v224, v190
	v_add_f32_e32 v254, 0, v222
	s_waitcnt lgkmcnt(8)
	v_mfma_f32_32x32x16_bf16 v[48:63], v[128:131], v[250:253], v[48:63]
	ds_read_b64_tr_b16 v[128:129], v218 offset:16384
	ds_read_b64_tr_b16 v[130:131], v218 offset:20480
	v_exp_f32_e32 v224, v224
	v_sub_f32_e32 v225, v225, v190
	v_add_f32_e32 v254, v223, v254
	v_exp_f32_e32 v225, v225
	v_sub_f32_e32 v226, v226, v190
	v_add_f32_e32 v254, v224, v254
	s_waitcnt lgkmcnt(8)
	v_mfma_f32_32x32x16_bf16 v[32:47], v[206:209], v[250:253], v[32:47]
	ds_read_b64_tr_b16 v[206:207], v219 offset:16384
	ds_read_b64_tr_b16 v[208:209], v219 offset:20480
	v_exp_f32_e32 v226, v226
	v_sub_f32_e32 v227, v227, v190
	v_add_f32_e32 v254, v225, v254
	v_exp_f32_e32 v227, v227
	v_sub_f32_e32 v228, v228, v190
	s_waitcnt lgkmcnt(8)
	v_mfma_f32_32x32x16_bf16 v[16:31], v[210:213], v[250:253], v[16:31]
	ds_read_b64_tr_b16 v[210:211], v221 offset:16384
	ds_read_b64_tr_b16 v[212:213], v221 offset:20480
	v_add_f32_e32 v254, v226, v254
	v_exp_f32_e32 v228, v228
	v_sub_f32_e32 v229, v229, v190
	v_add_f32_e32 v254, v227, v254
	v_exp_f32_e32 v229, v229
	s_waitcnt lgkmcnt(8)
	v_mfma_f32_32x32x16_bf16 v[0:15], v[214:217], v[250:253], v[0:15]
	ds_read_b64_tr_b16 v[214:215], v205 offset:16640
	ds_read_b64_tr_b16 v[216:217], v205 offset:20736
	s_nop 0
	v_cvt_pk_bf16_f32 v242, v222, v223
	v_cvt_pk_bf16_f32 v243, v224, v225
	v_cvt_pk_bf16_f32 v244, v226, v227
	v_cvt_pk_bf16_f32 v245, v228, v229
	s_nop 1
	s_waitcnt lgkmcnt(8)
	v_mfma_f32_32x32x16_bf16 v[112:127], v[238:241], v[242:245], v[112:127]
	ds_read_b64_tr_b16 v[238:239], v218 offset:16640
	ds_read_b64_tr_b16 v[240:241], v218 offset:20736
	v_sub_f32_e32 v230, v230, v190
	v_add_f32_e32 v254, v228, v254
	v_exp_f32_e32 v230, v230
	v_sub_f32_e32 v231, v231, v190
	v_add_f32_e32 v254, v229, v254
	s_waitcnt lgkmcnt(8)
	v_mfma_f32_32x32x16_bf16 v[96:111], v[128:131], v[242:245], v[96:111]
	ds_read_b64_tr_b16 v[128:129], v219 offset:16640
	ds_read_b64_tr_b16 v[130:131], v219 offset:20736
	v_exp_f32_e32 v231, v231
	v_sub_f32_e32 v232, v232, v190
	v_add_f32_e32 v254, v230, v254
	v_exp_f32_e32 v232, v232
	v_sub_f32_e32 v233, v233, v190
	s_waitcnt lgkmcnt(8)
	v_mfma_f32_32x32x16_bf16 v[80:95], v[206:209], v[242:245], v[80:95]
	ds_read_b64_tr_b16 v[206:207], v221 offset:16640
	ds_read_b64_tr_b16 v[208:209], v221 offset:20736
	v_add_f32_e32 v254, v231, v254
	v_exp_f32_e32 v233, v233
	v_sub_f32_e32 v234, v234, v190
	v_add_f32_e32 v254, v232, v254
	s_waitcnt lgkmcnt(8)
	v_mfma_f32_32x32x16_bf16 v[64:79], v[210:213], v[242:245], v[64:79]
	ds_read_b64_tr_b16 v[210:211], v205 offset:24576
	ds_read_b64_tr_b16 v[212:213], v205 offset:28672
	v_exp_f32_e32 v234, v234
	v_sub_f32_e32 v235, v235, v190
	v_add_f32_e32 v254, v233, v254
	v_exp_f32_e32 v235, v235
	s_waitcnt lgkmcnt(8)
	v_mfma_f32_32x32x16_bf16 v[48:63], v[214:217], v[242:245], v[48:63]
	ds_read_b64_tr_b16 v[214:215], v218 offset:24576
	ds_read_b64_tr_b16 v[216:217], v218 offset:28672
	v_sub_f32_e32 v236, v236, v190
	v_add_f32_e32 v254, v234, v254
	v_exp_f32_e32 v236, v236
	v_sub_f32_e32 v237, v237, v190
	s_waitcnt lgkmcnt(8)
	v_mfma_f32_32x32x16_bf16 v[32:47], v[238:241], v[242:245], v[32:47]
	ds_read_b64_tr_b16 v[238:239], v219 offset:24576
	ds_read_b64_tr_b16 v[240:241], v219 offset:28672
	v_add_f32_e32 v254, v235, v254
	v_exp_f32_e32 v237, v237
	v_add_f32_e32 v254, v236, v254
	v_add_f32_e32 v254, v237, v254
	s_waitcnt lgkmcnt(8)
	v_mfma_f32_32x32x16_bf16 v[16:31], v[128:131], v[242:245], v[16:31]
	ds_read_b64_tr_b16 v[128:129], v221 offset:24576
	ds_read_b64_tr_b16 v[130:131], v221 offset:28672
	v_cvt_pk_bf16_f32 v250, v230, v231
	v_cvt_pk_bf16_f32 v251, v232, v233
	v_cvt_pk_bf16_f32 v252, v234, v235
	v_cvt_pk_bf16_f32 v253, v236, v237
	v_add_f32_e32 v203, v203, v254
	s_waitcnt lgkmcnt(8)
	v_mfma_f32_32x32x16_bf16 v[0:15], v[206:209], v[242:245], v[0:15]
	ds_read_b64_tr_b16 v[206:207], v205 offset:24832
	ds_read_b64_tr_b16 v[208:209], v205 offset:28928
	s_waitcnt lgkmcnt(8)
	v_mfma_f32_32x32x16_bf16 v[112:127], v[210:213], v[250:253], v[112:127]
	ds_read_b64_tr_b16 v[210:211], v218 offset:24832
	ds_read_b64_tr_b16 v[212:213], v218 offset:28928
	s_waitcnt lgkmcnt(8)
	v_mfma_f32_32x32x16_bf16 v[96:111], v[214:217], v[250:253], v[96:111]
	ds_read_b64_tr_b16 v[214:215], v219 offset:24832
	ds_read_b64_tr_b16 v[216:217], v219 offset:28928
	s_waitcnt lgkmcnt(8)
	v_mfma_f32_32x32x16_bf16 v[80:95], v[238:241], v[250:253], v[80:95]
	ds_read_b64_tr_b16 v[238:239], v221 offset:24832
	ds_read_b64_tr_b16 v[240:241], v221 offset:28928
	s_waitcnt lgkmcnt(8)
	v_mfma_f32_32x32x16_bf16 v[64:79], v[128:131], v[250:253], v[64:79]
	s_waitcnt lgkmcnt(6)
	v_mfma_f32_32x32x16_bf16 v[48:63], v[206:209], v[250:253], v[48:63]
	s_waitcnt lgkmcnt(4)
	v_mfma_f32_32x32x16_bf16 v[32:47], v[210:213], v[250:253], v[32:47]
	s_waitcnt lgkmcnt(2)
	v_mfma_f32_32x32x16_bf16 v[16:31], v[214:217], v[250:253], v[16:31]
	s_waitcnt lgkmcnt(0)
	v_mfma_f32_32x32x16_bf16 v[0:15], v[238:241], v[250:253], v[0:15]
	ds_read_b128 v[206:209], v195
	ds_read_b128 v[210:213], v196
	ds_read_b128 v[214:217], v197
	ds_read_b128 v[238:241], v198
	ds_read_b128 v[242:245], v199
	ds_read_b128 v[250:253], v200
	ds_read_b128 v[222:225], v201
	ds_read_b128 v[226:229], v202
	s_waitcnt vmcnt(0)
	s_add_i32 s12, s38, 1
	s_cmp_lg_u32 s38, 2
	s_cselect_b32 s38, s12, 0
	s_add_i32 s84, s84, 64
	s_add_u32 s22, s22, 0x100000
	s_addc_u32 s23, s23, 0
	s_add_i32 s85, s85, 1
	s_add_i32 s100, s84, 63
	s_cmp_le_i32 s100, s80
	s_cbranch_scc0 .Latt_latchb_2
	s_cmp_ge_u32 s85, s78
	s_cselect_b64 s[12:13], -1, 0
	v_mov_b32_e32 v204, v176
	s_barrier
	s_branch .Latt_cont_2s0
.Latt_rs1_2s2:
	s_waitcnt lgkmcnt(8)
	v_mfma_f32_32x32x16_bf16 v[64:79], v[238:241], v[250:253], v[64:79]
	ds_read_b64_tr_b16 v[238:239], v205 offset:16384
	ds_read_b64_tr_b16 v[240:241], v205 offset:20480
	s_waitcnt lgkmcnt(8)
	v_mfma_f32_32x32x16_bf16 v[48:63], v[128:131], v[250:253], v[48:63]
	ds_read_b64_tr_b16 v[128:129], v218 offset:16384
	ds_read_b64_tr_b16 v[130:131], v218 offset:20480
	s_waitcnt lgkmcnt(8)
	v_mfma_f32_32x32x16_bf16 v[32:47], v[206:209], v[250:253], v[32:47]
	ds_read_b64_tr_b16 v[206:207], v219 offset:16384
	ds_read_b64_tr_b16 v[208:209], v219 offset:20480
	s_waitcnt lgkmcnt(8)
	v_mfma_f32_32x32x16_bf16 v[16:31], v[210:213], v[250:253], v[16:31]
	ds_read_b64_tr_b16 v[210:211], v221 offset:16384
	ds_read_b64_tr_b16 v[212:213], v221 offset:20480
	s_waitcnt lgkmcnt(8)
	v_mfma_f32_32x32x16_bf16 v[0:15], v[214:217], v[250:253], v[0:15]
	ds_read_b64_tr_b16 v[214:215], v205 offset:16640
	ds_read_b64_tr_b16 v[216:217], v205 offset:20736
	s_nop 11
	v_max_f32_e32 v246, v190, v246
	v_sub_f32_e32 v190, v190, v246
	v_exp_f32_e32 v190, v190
	s_nop 0
	v_pk_mul_f32 v[126:127], v[126:127], v[190:191] op_sel_hi:[1,0]
	v_pk_mul_f32 v[124:125], v[124:125], v[190:191] op_sel_hi:[1,0]
	v_pk_mul_f32 v[122:123], v[122:123], v[190:191] op_sel_hi:[1,0]
	v_pk_mul_f32 v[120:121], v[120:121], v[190:191] op_sel_hi:[1,0]
	v_pk_mul_f32 v[118:119], v[118:119], v[190:191] op_sel_hi:[1,0]
	v_pk_mul_f32 v[116:117], v[116:117], v[190:191] op_sel_hi:[1,0]
	v_pk_mul_f32 v[114:115], v[114:115], v[190:191] op_sel_hi:[1,0]
	v_pk_mul_f32 v[112:113], v[112:113], v[190:191] op_sel_hi:[1,0]
	v_pk_mul_f32 v[110:111], v[110:111], v[190:191] op_sel_hi:[1,0]
	v_pk_mul_f32 v[108:109], v[108:109], v[190:191] op_sel_hi:[1,0]
	v_pk_mul_f32 v[106:107], v[106:107], v[190:191] op_sel_hi:[1,0]
	v_pk_mul_f32 v[104:105], v[104:105], v[190:191] op_sel_hi:[1,0]
	v_pk_mul_f32 v[102:103], v[102:103], v[190:191] op_sel_hi:[1,0]
	v_pk_mul_f32 v[100:101], v[100:101], v[190:191] op_sel_hi:[1,0]
	v_pk_mul_f32 v[98:99], v[98:99], v[190:191] op_sel_hi:[1,0]
	v_pk_mul_f32 v[96:97], v[96:97], v[190:191] op_sel_hi:[1,0]
	v_pk_mul_f32 v[94:95], v[94:95], v[190:191] op_sel_hi:[1,0]
	v_pk_mul_f32 v[92:93], v[92:93], v[190:191] op_sel_hi:[1,0]
	v_pk_mul_f32 v[90:91], v[90:91], v[190:191] op_sel_hi:[1,0]
	v_pk_mul_f32 v[88:89], v[88:89], v[190:191] op_sel_hi:[1,0]
	v_pk_mul_f32 v[86:87], v[86:87], v[190:191] op_sel_hi:[1,0]
	v_pk_mul_f32 v[84:85], v[84:85], v[190:191] op_sel_hi:[1,0]
	v_pk_mul_f32 v[82:83], v[82:83], v[190:191] op_sel_hi:[1,0]
	v_pk_mul_f32 v[80:81], v[80:81], v[190:191] op_sel_hi:[1,0]
	v_pk_mul_f32 v[78:79], v[78:79], v[190:191] op_sel_hi:[1,0]
	v_pk_mul_f32 v[76:77], v[76:77], v[190:191] op_sel_hi:[1,0]
	v_pk_mul_f32 v[74:75], v[74:75], v[190:191] op_sel_hi:[1,0]
	v_pk_mul_f32 v[72:73], v[72:73], v[190:191] op_sel_hi:[1,0]
	v_pk_mul_f32 v[70:71], v[70:71], v[190:191] op_sel_hi:[1,0]
	v_pk_mul_f32 v[68:69], v[68:69], v[190:191] op_sel_hi:[1,0]
	v_pk_mul_f32 v[66:67], v[66:67], v[190:191] op_sel_hi:[1,0]
	v_pk_mul_f32 v[64:65], v[64:65], v[190:191] op_sel_hi:[1,0]
	v_pk_mul_f32 v[62:63], v[62:63], v[190:191] op_sel_hi:[1,0]
	v_pk_mul_f32 v[60:61], v[60:61], v[190:191] op_sel_hi:[1,0]
	v_pk_mul_f32 v[58:59], v[58:59], v[190:191] op_sel_hi:[1,0]
	v_pk_mul_f32 v[56:57], v[56:57], v[190:191] op_sel_hi:[1,0]
	v_pk_mul_f32 v[54:55], v[54:55], v[190:191] op_sel_hi:[1,0]
	v_pk_mul_f32 v[52:53], v[52:53], v[190:191] op_sel_hi:[1,0]
	v_pk_mul_f32 v[50:51], v[50:51], v[190:191] op_sel_hi:[1,0]
	v_pk_mul_f32 v[48:49], v[48:49], v[190:191] op_sel_hi:[1,0]
	v_pk_mul_f32 v[46:47], v[46:47], v[190:191] op_sel_hi:[1,0]
	v_pk_mul_f32 v[44:45], v[44:45], v[190:191] op_sel_hi:[1,0]
	v_pk_mul_f32 v[42:43], v[42:43], v[190:191] op_sel_hi:[1,0]
	v_pk_mul_f32 v[40:41], v[40:41], v[190:191] op_sel_hi:[1,0]
	v_pk_mul_f32 v[38:39], v[38:39], v[190:191] op_sel_hi:[1,0]
	v_pk_mul_f32 v[36:37], v[36:37], v[190:191] op_sel_hi:[1,0]
	v_pk_mul_f32 v[34:35], v[34:35], v[190:191] op_sel_hi:[1,0]
	v_pk_mul_f32 v[32:33], v[32:33], v[190:191] op_sel_hi:[1,0]
	v_pk_mul_f32 v[30:31], v[30:31], v[190:191] op_sel_hi:[1,0]
	v_pk_mul_f32 v[28:29], v[28:29], v[190:191] op_sel_hi:[1,0]
	v_pk_mul_f32 v[26:27], v[26:27], v[190:191] op_sel_hi:[1,0]
	v_pk_mul_f32 v[24:25], v[24:25], v[190:191] op_sel_hi:[1,0]
	v_pk_mul_f32 v[22:23], v[22:23], v[190:191] op_sel_hi:[1,0]
	v_pk_mul_f32 v[20:21], v[20:21], v[190:191] op_sel_hi:[1,0]
	v_pk_mul_f32 v[18:19], v[18:19], v[190:191] op_sel_hi:[1,0]
	v_pk_mul_f32 v[16:17], v[16:17], v[190:191] op_sel_hi:[1,0]
	v_pk_mul_f32 v[14:15], v[14:15], v[190:191] op_sel_hi:[1,0]
	v_pk_mul_f32 v[12:13], v[12:13], v[190:191] op_sel_hi:[1,0]
	v_pk_mul_f32 v[10:11], v[10:11], v[190:191] op_sel_hi:[1,0]
	v_pk_mul_f32 v[8:9], v[8:9], v[190:191] op_sel_hi:[1,0]
	v_pk_mul_f32 v[6:7], v[6:7], v[190:191] op_sel_hi:[1,0]
	v_pk_mul_f32 v[4:5], v[4:5], v[190:191] op_sel_hi:[1,0]
	v_pk_mul_f32 v[2:3], v[2:3], v[190:191] op_sel_hi:[1,0]
	v_pk_mul_f32 v[0:1], v[0:1], v[190:191] op_sel_hi:[1,0]
	v_mul_f32_e32 v203, v203, v190
	v_mov_b32_e32 v190, v246
	v_sub_f32_e32 v222, v222, v190
	v_exp_f32_e32 v222, v222
	v_sub_f32_e32 v223, v223, v190
	v_exp_f32_e32 v223, v223
	v_sub_f32_e32 v224, v224, v190
	v_add_f32_e32 v254, 0, v222
	v_exp_f32_e32 v224, v224
	v_sub_f32_e32 v225, v225, v190
	v_add_f32_e32 v254, v223, v254
	v_exp_f32_e32 v225, v225
	v_sub_f32_e32 v226, v226, v190
	v_add_f32_e32 v254, v224, v254
	v_exp_f32_e32 v226, v226
	v_sub_f32_e32 v227, v227, v190
	v_add_f32_e32 v254, v225, v254
	v_exp_f32_e32 v227, v227
	v_sub_f32_e32 v228, v228, v190
	v_add_f32_e32 v254, v226, v254
	v_exp_f32_e32 v228, v228
	v_sub_f32_e32 v229, v229, v190
	v_add_f32_e32 v254, v227, v254
	v_exp_f32_e32 v229, v229
	v_sub_f32_e32 v230, v230, v190
	v_add_f32_e32 v254, v228, v254
	v_exp_f32_e32 v230, v230
	v_sub_f32_e32 v231, v231, v190
	v_add_f32_e32 v254, v229, v254
	v_exp_f32_e32 v231, v231
	v_sub_f32_e32 v232, v232, v190
	v_add_f32_e32 v254, v230, v254
	v_exp_f32_e32 v232, v232
	v_sub_f32_e32 v233, v233, v190
	v_add_f32_e32 v254, v231, v254
	v_exp_f32_e32 v233, v233
	v_sub_f32_e32 v234, v234, v190
	v_add_f32_e32 v254, v232, v254
	v_exp_f32_e32 v234, v234
	v_sub_f32_e32 v235, v235, v190
	v_add_f32_e32 v254, v233, v254
	v_exp_f32_e32 v235, v235
	v_sub_f32_e32 v236, v236, v190
	v_add_f32_e32 v254, v234, v254
	v_exp_f32_e32 v236, v236
	v_sub_f32_e32 v237, v237, v190
	v_add_f32_e32 v254, v235, v254
	v_exp_f32_e32 v237, v237
	v_add_f32_e32 v254, v236, v254
	v_add_f32_e32 v254, v237, v254
	v_cvt_pk_bf16_f32 v242, v222, v223
	v_cvt_pk_bf16_f32 v243, v224, v225
	v_cvt_pk_bf16_f32 v244, v226, v227
	v_cvt_pk_bf16_f32 v245, v228, v229
	v_cvt_pk_bf16_f32 v250, v230, v231
	v_cvt_pk_bf16_f32 v251, v232, v233
	v_cvt_pk_bf16_f32 v252, v234, v235
	v_cvt_pk_bf16_f32 v253, v236, v237
	v_add_f32_e32 v203, v203, v254
	s_nop 1
	s_waitcnt lgkmcnt(8)
	v_mfma_f32_32x32x16_bf16 v[112:127], v[238:241], v[242:245], v[112:127]
	ds_read_b64_tr_b16 v[238:239], v218 offset:16640
	ds_read_b64_tr_b16 v[240:241], v218 offset:20736
	s_waitcnt lgkmcnt(8)
	v_mfma_f32_32x32x16_bf16 v[96:111], v[128:131], v[242:245], v[96:111]
	ds_read_b64_tr_b16 v[222:223], v219 offset:16640
	ds_read_b64_tr_b16 v[224:225], v219 offset:20736
	s_waitcnt lgkmcnt(8)
	v_mfma_f32_32x32x16_bf16 v[80:95], v[206:209], v[242:245], v[80:95]
	ds_read_b64_tr_b16 v[206:207], v221 offset:16640
	ds_read_b64_tr_b16 v[208:209], v221 offset:20736
	s_waitcnt lgkmcnt(8)
	v_mfma_f32_32x32x16_bf16 v[64:79], v[210:213], v[242:245], v[64:79]
	ds_read_b64_tr_b16 v[210:211], v205 offset:24576
	ds_read_b64_tr_b16 v[212:213], v205 offset:28672
	s_waitcnt lgkmcnt(8)
	v_mfma_f32_32x32x16_bf16 v[48:63], v[214:217], v[242:245], v[48:63]
	ds_read_b64_tr_b16 v[214:215], v218 offset:24576
	ds_read_b64_tr_b16 v[216:217], v218 offset:28672
	s_waitcnt lgkmcnt(8)
	v_mfma_f32_32x32x16_bf16 v[32:47], v[238:241], v[242:245], v[32:47]
	ds_read_b64_tr_b16 v[238:239], v219 offset:24576
	ds_read_b64_tr_b16 v[240:241], v219 offset:28672
	s_waitcnt lgkmcnt(8)
	v_mfma_f32_32x32x16_bf16 v[16:31], v[222:225], v[242:245], v[16:31]
	ds_read_b64_tr_b16 v[222:223], v221 offset:24576
	ds_read_b64_tr_b16 v[224:225], v221 offset:28672
	s_waitcnt lgkmcnt(8)
	v_mfma_f32_32x32x16_bf16 v[0:15], v[206:209], v[242:245], v[0:15]
	ds_read_b64_tr_b16 v[206:207], v205 offset:24832
	ds_read_b64_tr_b16 v[208:209], v205 offset:28928
	s_waitcnt lgkmcnt(8)
	v_mfma_f32_32x32x16_bf16 v[112:127], v[210:213], v[250:253], v[112:127]
	ds_read_b64_tr_b16 v[210:211], v218 offset:24832
	ds_read_b64_tr_b16 v[212:213], v218 offset:28928
	s_waitcnt lgkmcnt(8)
	v_mfma_f32_32x32x16_bf16 v[96:111], v[214:217], v[250:253], v[96:111]
	ds_read_b64_tr_b16 v[214:215], v219 offset:24832
	ds_read_b64_tr_b16 v[216:217], v219 offset:28928
	s_waitcnt lgkmcnt(8)
	v_mfma_f32_32x32x16_bf16 v[80:95], v[238:241], v[250:253], v[80:95]
	ds_read_b64_tr_b16 v[238:239], v221 offset:24832
	ds_read_b64_tr_b16 v[240:241], v221 offset:28928
	s_waitcnt lgkmcnt(8)
	v_mfma_f32_32x32x16_bf16 v[64:79], v[222:225], v[250:253], v[64:79]
	s_waitcnt lgkmcnt(6)
	v_mfma_f32_32x32x16_bf16 v[48:63], v[206:209], v[250:253], v[48:63]
	s_waitcnt lgkmcnt(4)
	v_mfma_f32_32x32x16_bf16 v[32:47], v[210:213], v[250:253], v[32:47]
	s_waitcnt lgkmcnt(2)
	v_mfma_f32_32x32x16_bf16 v[16:31], v[214:217], v[250:253], v[16:31]
	s_waitcnt lgkmcnt(0)
	v_mfma_f32_32x32x16_bf16 v[0:15], v[238:241], v[250:253], v[0:15]
	ds_read_b128 v[206:209], v195
	ds_read_b128 v[210:213], v196
	ds_read_b128 v[214:217], v197
	ds_read_b128 v[238:241], v198
	ds_read_b128 v[242:245], v199
	ds_read_b128 v[250:253], v200
	ds_read_b128 v[222:225], v201
	ds_read_b128 v[226:229], v202
	s_waitcnt vmcnt(0)
	s_add_i32 s12, s38, 1
	s_cmp_lg_u32 s38, 2
	s_cselect_b32 s38, s12, 0
	s_add_i32 s84, s84, 64
	s_add_u32 s22, s22, 0x100000
	s_addc_u32 s23, s23, 0
	s_add_i32 s85, s85, 1
	s_add_i32 s100, s84, 63
	s_cmp_le_i32 s100, s80
	s_cbranch_scc0 .Latt_latchb_2
	s_cmp_ge_u32 s85, s78
	s_cselect_b64 s[12:13], -1, 0
	v_mov_b32_e32 v204, v176
	s_barrier
	s_branch .Latt_cont_2s0

.Latt_latchb_3:
	s_waitcnt lgkmcnt(0)
	s_cmp_lg_u32 s79, s14
	s_barrier
	s_cbranch_scc0 .LBB0_842

.Latt_nr0_3s0:
	s_waitcnt lgkmcnt(3)
	v_mfma_f32_32x32x16_bf16 v[222:237], v[214:217], v[152:155], v[222:237]
	ds_read_b128 v[214:217], v202 offset:8192
	v_sub_f32_e32 v128, v128, v190
	v_exp_f32_e32 v128, v128
	v_sub_f32_e32 v129, v129, v190
	v_exp_f32_e32 v129, v129
	v_sub_f32_e32 v130, v130, v190
	s_waitcnt lgkmcnt(3)
	v_mfma_f32_32x32x16_bf16 v[222:237], v[238:241], v[156:159], v[222:237]
	ds_read_b128 v[238:241], v203 offset:8192
	v_add_f32_e32 v254, 0, v128
	v_exp_f32_e32 v130, v130
	v_sub_f32_e32 v131, v131, v190
	v_add_f32_e32 v254, v129, v254
	v_exp_f32_e32 v131, v131
	s_waitcnt lgkmcnt(3)
	v_mfma_f32_32x32x16_bf16 v[222:237], v[206:209], v[160:163], v[222:237]
	ds_read_b64_tr_b16 v[206:207], v205
	ds_read_b64_tr_b16 v[208:209], v205 offset:4096
	v_sub_f32_e32 v132, v132, v190
	v_add_f32_e32 v254, v130, v254
	v_exp_f32_e32 v132, v132
	v_sub_f32_e32 v133, v133, v190
	v_add_f32_e32 v254, v131, v254
	s_waitcnt lgkmcnt(4)
	v_mfma_f32_32x32x16_bf16 v[222:237], v[210:213], v[164:167], v[222:237]
	ds_read_b64_tr_b16 v[210:211], v218
	ds_read_b64_tr_b16 v[212:213], v218 offset:4096
	v_exp_f32_e32 v133, v133
	v_sub_f32_e32 v134, v134, v190
	v_add_f32_e32 v254, v132, v254
	v_exp_f32_e32 v134, v134
	s_waitcnt lgkmcnt(5)
	v_mfma_f32_32x32x16_bf16 v[222:237], v[214:217], v[168:171], v[222:237]
	ds_read_b64_tr_b16 v[214:215], v219
	ds_read_b64_tr_b16 v[216:217], v219 offset:4096
	v_sub_f32_e32 v135, v135, v190
	v_add_f32_e32 v254, v133, v254
	v_exp_f32_e32 v135, v135
	s_nop 0
	s_waitcnt lgkmcnt(6)
	v_mfma_f32_32x32x16_bf16 v[222:237], v[238:241], v[172:175], v[222:237]
	ds_read_b64_tr_b16 v[238:239], v221
	ds_read_b64_tr_b16 v[240:241], v221 offset:4096
	v_cvt_pk_bf16_f32 v242, v128, v129
	v_cvt_pk_bf16_f32 v243, v130, v131
	v_cvt_pk_bf16_f32 v244, v132, v133
	v_cvt_pk_bf16_f32 v245, v134, v135
	s_nop 1
	s_waitcnt lgkmcnt(6)
	v_mfma_f32_32x32x16_bf16 v[112:127], v[206:209], v[242:245], v[112:127]
	ds_read_b64_tr_b16 v[206:207], v205 offset:256
	ds_read_b64_tr_b16 v[208:209], v205 offset:4352
	v_sub_f32_e32 v136, v136, v190
	v_add_f32_e32 v254, v134, v254
	v_exp_f32_e32 v136, v136
	v_sub_f32_e32 v137, v137, v190
	v_add_f32_e32 v254, v135, v254
	s_waitcnt lgkmcnt(6)
	v_mfma_f32_32x32x16_bf16 v[96:111], v[210:213], v[242:245], v[96:111]
	ds_read_b64_tr_b16 v[210:211], v218 offset:256
	ds_read_b64_tr_b16 v[212:213], v218 offset:4352
	v_exp_f32_e32 v137, v137
	v_sub_f32_e32 v138, v138, v190
	v_add_f32_e32 v254, v136, v254
	v_exp_f32_e32 v138, v138
	v_sub_f32_e32 v139, v139, v190
	s_waitcnt lgkmcnt(6)
	v_mfma_f32_32x32x16_bf16 v[80:95], v[214:217], v[242:245], v[80:95]
	ds_read_b64_tr_b16 v[214:215], v219 offset:256
	ds_read_b64_tr_b16 v[216:217], v219 offset:4352
	v_add_f32_e32 v254, v137, v254
	v_exp_f32_e32 v139, v139
	v_sub_f32_e32 v140, v140, v190
	v_add_f32_e32 v254, v138, v254
	s_waitcnt lgkmcnt(6)
	v_mfma_f32_32x32x16_bf16 v[64:79], v[238:241], v[242:245], v[64:79]
	ds_read_b64_tr_b16 v[238:239], v221 offset:256
	ds_read_b64_tr_b16 v[240:241], v221 offset:4352
	v_exp_f32_e32 v140, v140
	v_sub_f32_e32 v141, v141, v190
	v_add_f32_e32 v254, v139, v254
	v_exp_f32_e32 v141, v141
	s_waitcnt lgkmcnt(6)
	v_mfma_f32_32x32x16_bf16 v[48:63], v[206:209], v[242:245], v[48:63]
	ds_read_b64_tr_b16 v[206:207], v205 offset:8192
	ds_read_b64_tr_b16 v[208:209], v205 offset:12288
	v_sub_f32_e32 v142, v142, v190
	v_add_f32_e32 v254, v140, v254
	v_exp_f32_e32 v142, v142
	v_sub_f32_e32 v143, v143, v190
	s_waitcnt lgkmcnt(6)
	v_mfma_f32_32x32x16_bf16 v[32:47], v[210:213], v[242:245], v[32:47]
	ds_read_b64_tr_b16 v[210:211], v218 offset:8192
	ds_read_b64_tr_b16 v[212:213], v218 offset:12288
	v_add_f32_e32 v254, v141, v254
	v_exp_f32_e32 v143, v143
	v_add_f32_e32 v254, v142, v254
	v_add_f32_e32 v254, v143, v254
	s_waitcnt lgkmcnt(6)
	v_mfma_f32_32x32x16_bf16 v[16:31], v[214:217], v[242:245], v[16:31]
	ds_read_b64_tr_b16 v[214:215], v219 offset:8192
	ds_read_b64_tr_b16 v[216:217], v219 offset:12288
	v_cvt_pk_bf16_f32 v250, v136, v137
	v_cvt_pk_bf16_f32 v251, v138, v139
	v_cvt_pk_bf16_f32 v252, v140, v141
	v_cvt_pk_bf16_f32 v253, v142, v143
	v_add_f32_e32 v195, v195, v254
	s_waitcnt lgkmcnt(6)
	v_mfma_f32_32x32x16_bf16 v[0:15], v[238:241], v[242:245], v[0:15]
	ds_read_b64_tr_b16 v[238:239], v221 offset:8192
	ds_read_b64_tr_b16 v[240:241], v221 offset:12288
	ds_read_b64_tr_b16 v[128:129], v205 offset:8448
	ds_read_b64_tr_b16 v[130:131], v205 offset:12544
	s_waitcnt lgkmcnt(8)
	v_mfma_f32_32x32x16_bf16 v[112:127], v[206:209], v[250:253], v[112:127]
	ds_read_b64_tr_b16 v[206:207], v218 offset:8448
	ds_read_b64_tr_b16 v[208:209], v218 offset:12544
	v_max3_f32 v246, v222, v223, v224
	v_max3_f32 v247, v225, v226, v227
	v_max3_f32 v246, v246, v228, v229
	v_max3_f32 v247, v247, v230, v231
	v_max3_f32 v246, v246, v232, v233
	s_waitcnt lgkmcnt(8)
	v_mfma_f32_32x32x16_bf16 v[96:111], v[210:213], v[250:253], v[96:111]
	ds_read_b64_tr_b16 v[210:211], v219 offset:8448
	ds_read_b64_tr_b16 v[212:213], v219 offset:12544
	v_max3_f32 v247, v247, v234, v235
	v_max3_f32 v246, v246, v236, v237
	v_max_f32_e32 v246, v246, v247
	v_mov_b32_e32 v247, v246
	v_add_f32_e32 v249, 0x41000000, v190
	s_waitcnt lgkmcnt(8)
	v_mfma_f32_32x32x16_bf16 v[80:95], v[214:217], v[250:253], v[80:95]
	ds_read_b64_tr_b16 v[214:215], v221 offset:8448
	ds_read_b64_tr_b16 v[216:217], v221 offset:12544
	s_nop 1
	v_permlane32_swap_b32_e32 v246, v247
	v_max_f32_e32 v246, v246, v247
	v_cmp_gt_f32_e32 vcc, v246, v249
	s_cbranch_vccnz .Latt_rs1_3s0
	s_waitcnt lgkmcnt(8)
	v_mfma_f32_32x32x16_bf16 v[64:79], v[238:241], v[250:253], v[64:79]
	ds_read_b64_tr_b16 v[238:239], v205 offset:16384
	ds_read_b64_tr_b16 v[240:241], v205 offset:20480
	v_sub_f32_e32 v222, v222, v190
	v_exp_f32_e32 v222, v222
	v_sub_f32_e32 v223, v223, v190
	v_exp_f32_e32 v223, v223
	v_sub_f32_e32 v224, v224, v190
	v_add_f32_e32 v254, 0, v222
	s_waitcnt lgkmcnt(8)
	v_mfma_f32_32x32x16_bf16 v[48:63], v[128:131], v[250:253], v[48:63]
	ds_read_b64_tr_b16 v[128:129], v218 offset:16384
	ds_read_b64_tr_b16 v[130:131], v218 offset:20480
	v_exp_f32_e32 v224, v224
	v_sub_f32_e32 v225, v225, v190
	v_add_f32_e32 v254, v223, v254
	v_exp_f32_e32 v225, v225
	v_sub_f32_e32 v226, v226, v190
	v_add_f32_e32 v254, v224, v254
	s_waitcnt lgkmcnt(8)
	v_mfma_f32_32x32x16_bf16 v[32:47], v[206:209], v[250:253], v[32:47]
	ds_read_b64_tr_b16 v[206:207], v219 offset:16384
	ds_read_b64_tr_b16 v[208:209], v219 offset:20480
	v_exp_f32_e32 v226, v226
	v_sub_f32_e32 v227, v227, v190
	v_add_f32_e32 v254, v225, v254
	v_exp_f32_e32 v227, v227
	v_sub_f32_e32 v228, v228, v190
	s_waitcnt lgkmcnt(8)
	v_mfma_f32_32x32x16_bf16 v[16:31], v[210:213], v[250:253], v[16:31]
	ds_read_b64_tr_b16 v[210:211], v221 offset:16384
	ds_read_b64_tr_b16 v[212:213], v221 offset:20480
	v_add_f32_e32 v254, v226, v254
	v_exp_f32_e32 v228, v228
	v_sub_f32_e32 v229, v229, v190
	v_add_f32_e32 v254, v227, v254
	v_exp_f32_e32 v229, v229
	s_waitcnt lgkmcnt(8)
	v_mfma_f32_32x32x16_bf16 v[0:15], v[214:217], v[250:253], v[0:15]
	ds_read_b64_tr_b16 v[214:215], v205 offset:16640
	ds_read_b64_tr_b16 v[216:217], v205 offset:20736
	s_nop 0
	v_cvt_pk_bf16_f32 v242, v222, v223
	v_cvt_pk_bf16_f32 v243, v224, v225
	v_cvt_pk_bf16_f32 v244, v226, v227
	v_cvt_pk_bf16_f32 v245, v228, v229
	s_nop 1
	s_waitcnt lgkmcnt(8)
	v_mfma_f32_32x32x16_bf16 v[112:127], v[238:241], v[242:245], v[112:127]
	ds_read_b64_tr_b16 v[238:239], v218 offset:16640
	ds_read_b64_tr_b16 v[240:241], v218 offset:20736
	v_sub_f32_e32 v230, v230, v190
	v_add_f32_e32 v254, v228, v254
	v_exp_f32_e32 v230, v230
	v_sub_f32_e32 v231, v231, v190
	v_add_f32_e32 v254, v229, v254
	s_waitcnt lgkmcnt(8)
	v_mfma_f32_32x32x16_bf16 v[96:111], v[128:131], v[242:245], v[96:111]
	ds_read_b64_tr_b16 v[128:129], v219 offset:16640
	ds_read_b64_tr_b16 v[130:131], v219 offset:20736
	v_exp_f32_e32 v231, v231
	v_sub_f32_e32 v232, v232, v190
	v_add_f32_e32 v254, v230, v254
	v_exp_f32_e32 v232, v232
	v_sub_f32_e32 v233, v233, v190
	s_waitcnt lgkmcnt(8)
	v_mfma_f32_32x32x16_bf16 v[80:95], v[206:209], v[242:245], v[80:95]
	ds_read_b64_tr_b16 v[206:207], v221 offset:16640
	ds_read_b64_tr_b16 v[208:209], v221 offset:20736
	v_add_f32_e32 v254, v231, v254
	v_exp_f32_e32 v233, v233
	v_sub_f32_e32 v234, v234, v190
	v_add_f32_e32 v254, v232, v254
	s_waitcnt lgkmcnt(8)
	v_mfma_f32_32x32x16_bf16 v[64:79], v[210:213], v[242:245], v[64:79]
	ds_read_b64_tr_b16 v[210:211], v205 offset:24576
	ds_read_b64_tr_b16 v[212:213], v205 offset:28672
	v_exp_f32_e32 v234, v234
	v_sub_f32_e32 v235, v235, v190
	v_add_f32_e32 v254, v233, v254
	v_exp_f32_e32 v235, v235
	s_waitcnt lgkmcnt(8)
	v_mfma_f32_32x32x16_bf16 v[48:63], v[214:217], v[242:245], v[48:63]
	ds_read_b64_tr_b16 v[214:215], v218 offset:24576
	ds_read_b64_tr_b16 v[216:217], v218 offset:28672
	v_sub_f32_e32 v236, v236, v190
	v_add_f32_e32 v254, v234, v254
	v_exp_f32_e32 v236, v236
	v_sub_f32_e32 v237, v237, v190
	s_waitcnt lgkmcnt(8)
	v_mfma_f32_32x32x16_bf16 v[32:47], v[238:241], v[242:245], v[32:47]
	ds_read_b64_tr_b16 v[238:239], v219 offset:24576
	ds_read_b64_tr_b16 v[240:241], v219 offset:28672
	v_add_f32_e32 v254, v235, v254
	v_exp_f32_e32 v237, v237
	v_add_f32_e32 v254, v236, v254
	v_add_f32_e32 v254, v237, v254
	s_waitcnt lgkmcnt(8)
	v_mfma_f32_32x32x16_bf16 v[16:31], v[128:131], v[242:245], v[16:31]
	ds_read_b64_tr_b16 v[128:129], v221 offset:24576
	ds_read_b64_tr_b16 v[130:131], v221 offset:28672
	v_cvt_pk_bf16_f32 v250, v230, v231
	v_cvt_pk_bf16_f32 v251, v232, v233
	v_cvt_pk_bf16_f32 v252, v234, v235
	v_cvt_pk_bf16_f32 v253, v236, v237
	v_add_f32_e32 v195, v195, v254
	s_waitcnt lgkmcnt(8)
	v_mfma_f32_32x32x16_bf16 v[0:15], v[206:209], v[242:245], v[0:15]
	ds_read_b64_tr_b16 v[206:207], v205 offset:24832
	ds_read_b64_tr_b16 v[208:209], v205 offset:28928
	s_waitcnt lgkmcnt(8)
	v_mfma_f32_32x32x16_bf16 v[112:127], v[210:213], v[250:253], v[112:127]
	ds_read_b64_tr_b16 v[210:211], v218 offset:24832
	ds_read_b64_tr_b16 v[212:213], v218 offset:28928
	s_waitcnt lgkmcnt(8)
	v_mfma_f32_32x32x16_bf16 v[96:111], v[214:217], v[250:253], v[96:111]
	ds_read_b64_tr_b16 v[214:215], v219 offset:24832
	ds_read_b64_tr_b16 v[216:217], v219 offset:28928
	s_waitcnt lgkmcnt(8)
	v_mfma_f32_32x32x16_bf16 v[80:95], v[238:241], v[250:253], v[80:95]
	ds_read_b64_tr_b16 v[238:239], v221 offset:24832
	ds_read_b64_tr_b16 v[240:241], v221 offset:28928
	s_waitcnt lgkmcnt(8)
	v_mfma_f32_32x32x16_bf16 v[64:79], v[128:131], v[250:253], v[64:79]
	s_waitcnt lgkmcnt(6)
	v_mfma_f32_32x32x16_bf16 v[48:63], v[206:209], v[250:253], v[48:63]
	s_waitcnt lgkmcnt(4)
	v_mfma_f32_32x32x16_bf16 v[32:47], v[210:213], v[250:253], v[32:47]
	s_waitcnt lgkmcnt(2)
	v_mfma_f32_32x32x16_bf16 v[16:31], v[214:217], v[250:253], v[16:31]
	s_waitcnt lgkmcnt(0)
	v_mfma_f32_32x32x16_bf16 v[0:15], v[238:241], v[250:253], v[0:15]
	ds_read_b128 v[206:209], v196 offset:16384
	ds_read_b128 v[210:213], v197 offset:16384
	ds_read_b128 v[214:217], v198 offset:16384
	ds_read_b128 v[238:241], v199 offset:16384
	ds_read_b128 v[242:245], v200 offset:16384
	ds_read_b128 v[250:253], v201 offset:16384
	ds_read_b128 v[222:225], v202 offset:16384
	ds_read_b128 v[226:229], v203 offset:16384
	s_waitcnt vmcnt(0)
	s_add_i32 s8, s11, 1
	s_cmp_lg_u32 s11, 2
	s_cselect_b32 s11, s8, 0
	s_add_i32 s14, s14, 64
	s_add_u32 s34, s34, 0x100000
	s_addc_u32 s35, s35, 0
	s_add_i32 s10, s10, 1
	s_add_i32 s100, s14, 63
	s_cmp_le_i32 s100, s80
	s_cbranch_scc0 .Latt_latchb_3
	s_cmp_ge_u32 s10, s78
	s_cselect_b64 s[8:9], -1, 0
	v_mov_b32_e32 v204, v176
	s_barrier
	s_branch .Latt_cont_3s1
.Latt_rs1_3s0:
	s_waitcnt lgkmcnt(8)
	v_mfma_f32_32x32x16_bf16 v[64:79], v[238:241], v[250:253], v[64:79]
	ds_read_b64_tr_b16 v[238:239], v205 offset:16384
	ds_read_b64_tr_b16 v[240:241], v205 offset:20480
	s_waitcnt lgkmcnt(8)
	v_mfma_f32_32x32x16_bf16 v[48:63], v[128:131], v[250:253], v[48:63]
	ds_read_b64_tr_b16 v[128:129], v218 offset:16384
	ds_read_b64_tr_b16 v[130:131], v218 offset:20480
	s_waitcnt lgkmcnt(8)
	v_mfma_f32_32x32x16_bf16 v[32:47], v[206:209], v[250:253], v[32:47]
	ds_read_b64_tr_b16 v[206:207], v219 offset:16384
	ds_read_b64_tr_b16 v[208:209], v219 offset:20480
	s_waitcnt lgkmcnt(8)
	v_mfma_f32_32x32x16_bf16 v[16:31], v[210:213], v[250:253], v[16:31]
	ds_read_b64_tr_b16 v[210:211], v221 offset:16384
	ds_read_b64_tr_b16 v[212:213], v221 offset:20480
	s_waitcnt lgkmcnt(8)
	v_mfma_f32_32x32x16_bf16 v[0:15], v[214:217], v[250:253], v[0:15]
	ds_read_b64_tr_b16 v[214:215], v205 offset:16640
	ds_read_b64_tr_b16 v[216:217], v205 offset:20736
	s_nop 11
	v_max_f32_e32 v246, v190, v246
	v_sub_f32_e32 v190, v190, v246
	v_exp_f32_e32 v190, v190
	s_nop 0
	v_pk_mul_f32 v[126:127], v[126:127], v[190:191] op_sel_hi:[1,0]
	v_pk_mul_f32 v[124:125], v[124:125], v[190:191] op_sel_hi:[1,0]
	v_pk_mul_f32 v[122:123], v[122:123], v[190:191] op_sel_hi:[1,0]
	v_pk_mul_f32 v[120:121], v[120:121], v[190:191] op_sel_hi:[1,0]
	v_pk_mul_f32 v[118:119], v[118:119], v[190:191] op_sel_hi:[1,0]
	v_pk_mul_f32 v[116:117], v[116:117], v[190:191] op_sel_hi:[1,0]
	v_pk_mul_f32 v[114:115], v[114:115], v[190:191] op_sel_hi:[1,0]
	v_pk_mul_f32 v[112:113], v[112:113], v[190:191] op_sel_hi:[1,0]
	v_pk_mul_f32 v[110:111], v[110:111], v[190:191] op_sel_hi:[1,0]
	v_pk_mul_f32 v[108:109], v[108:109], v[190:191] op_sel_hi:[1,0]
	v_pk_mul_f32 v[106:107], v[106:107], v[190:191] op_sel_hi:[1,0]
	v_pk_mul_f32 v[104:105], v[104:105], v[190:191] op_sel_hi:[1,0]
	v_pk_mul_f32 v[102:103], v[102:103], v[190:191] op_sel_hi:[1,0]
	v_pk_mul_f32 v[100:101], v[100:101], v[190:191] op_sel_hi:[1,0]
	v_pk_mul_f32 v[98:99], v[98:99], v[190:191] op_sel_hi:[1,0]
	v_pk_mul_f32 v[96:97], v[96:97], v[190:191] op_sel_hi:[1,0]
	v_pk_mul_f32 v[94:95], v[94:95], v[190:191] op_sel_hi:[1,0]
	v_pk_mul_f32 v[92:93], v[92:93], v[190:191] op_sel_hi:[1,0]
	v_pk_mul_f32 v[90:91], v[90:91], v[190:191] op_sel_hi:[1,0]
	v_pk_mul_f32 v[88:89], v[88:89], v[190:191] op_sel_hi:[1,0]
	v_pk_mul_f32 v[86:87], v[86:87], v[190:191] op_sel_hi:[1,0]
	v_pk_mul_f32 v[84:85], v[84:85], v[190:191] op_sel_hi:[1,0]
	v_pk_mul_f32 v[82:83], v[82:83], v[190:191] op_sel_hi:[1,0]
	v_pk_mul_f32 v[80:81], v[80:81], v[190:191] op_sel_hi:[1,0]
	v_pk_mul_f32 v[78:79], v[78:79], v[190:191] op_sel_hi:[1,0]
	v_pk_mul_f32 v[76:77], v[76:77], v[190:191] op_sel_hi:[1,0]
	v_pk_mul_f32 v[74:75], v[74:75], v[190:191] op_sel_hi:[1,0]
	v_pk_mul_f32 v[72:73], v[72:73], v[190:191] op_sel_hi:[1,0]
	v_pk_mul_f32 v[70:71], v[70:71], v[190:191] op_sel_hi:[1,0]
	v_pk_mul_f32 v[68:69], v[68:69], v[190:191] op_sel_hi:[1,0]
	v_pk_mul_f32 v[66:67], v[66:67], v[190:191] op_sel_hi:[1,0]
	v_pk_mul_f32 v[64:65], v[64:65], v[190:191] op_sel_hi:[1,0]
	v_pk_mul_f32 v[62:63], v[62:63], v[190:191] op_sel_hi:[1,0]
	v_pk_mul_f32 v[60:61], v[60:61], v[190:191] op_sel_hi:[1,0]
	v_pk_mul_f32 v[58:59], v[58:59], v[190:191] op_sel_hi:[1,0]
	v_pk_mul_f32 v[56:57], v[56:57], v[190:191] op_sel_hi:[1,0]
	v_pk_mul_f32 v[54:55], v[54:55], v[190:191] op_sel_hi:[1,0]
	v_pk_mul_f32 v[52:53], v[52:53], v[190:191] op_sel_hi:[1,0]
	v_pk_mul_f32 v[50:51], v[50:51], v[190:191] op_sel_hi:[1,0]
	v_pk_mul_f32 v[48:49], v[48:49], v[190:191] op_sel_hi:[1,0]
	v_pk_mul_f32 v[46:47], v[46:47], v[190:191] op_sel_hi:[1,0]
	v_pk_mul_f32 v[44:45], v[44:45], v[190:191] op_sel_hi:[1,0]
	v_pk_mul_f32 v[42:43], v[42:43], v[190:191] op_sel_hi:[1,0]
	v_pk_mul_f32 v[40:41], v[40:41], v[190:191] op_sel_hi:[1,0]
	v_pk_mul_f32 v[38:39], v[38:39], v[190:191] op_sel_hi:[1,0]
	v_pk_mul_f32 v[36:37], v[36:37], v[190:191] op_sel_hi:[1,0]
	v_pk_mul_f32 v[34:35], v[34:35], v[190:191] op_sel_hi:[1,0]
	v_pk_mul_f32 v[32:33], v[32:33], v[190:191] op_sel_hi:[1,0]
	v_pk_mul_f32 v[30:31], v[30:31], v[190:191] op_sel_hi:[1,0]
	v_pk_mul_f32 v[28:29], v[28:29], v[190:191] op_sel_hi:[1,0]
	v_pk_mul_f32 v[26:27], v[26:27], v[190:191] op_sel_hi:[1,0]
	v_pk_mul_f32 v[24:25], v[24:25], v[190:191] op_sel_hi:[1,0]
	v_pk_mul_f32 v[22:23], v[22:23], v[190:191] op_sel_hi:[1,0]
	v_pk_mul_f32 v[20:21], v[20:21], v[190:191] op_sel_hi:[1,0]
	v_pk_mul_f32 v[18:19], v[18:19], v[190:191] op_sel_hi:[1,0]
	v_pk_mul_f32 v[16:17], v[16:17], v[190:191] op_sel_hi:[1,0]
	v_pk_mul_f32 v[14:15], v[14:15], v[190:191] op_sel_hi:[1,0]
	v_pk_mul_f32 v[12:13], v[12:13], v[190:191] op_sel_hi:[1,0]
	v_pk_mul_f32 v[10:11], v[10:11], v[190:191] op_sel_hi:[1,0]
	v_pk_mul_f32 v[8:9], v[8:9], v[190:191] op_sel_hi:[1,0]
	v_pk_mul_f32 v[6:7], v[6:7], v[190:191] op_sel_hi:[1,0]
	v_pk_mul_f32 v[4:5], v[4:5], v[190:191] op_sel_hi:[1,0]
	v_pk_mul_f32 v[2:3], v[2:3], v[190:191] op_sel_hi:[1,0]
	v_pk_mul_f32 v[0:1], v[0:1], v[190:191] op_sel_hi:[1,0]
	v_mul_f32_e32 v195, v195, v190
	v_mov_b32_e32 v190, v246
	v_sub_f32_e32 v222, v222, v190
	v_exp_f32_e32 v222, v222
	v_sub_f32_e32 v223, v223, v190
	v_exp_f32_e32 v223, v223
	v_sub_f32_e32 v224, v224, v190
	v_add_f32_e32 v254, 0, v222
	v_exp_f32_e32 v224, v224
	v_sub_f32_e32 v225, v225, v190
	v_add_f32_e32 v254, v223, v254
	v_exp_f32_e32 v225, v225
	v_sub_f32_e32 v226, v226, v190
	v_add_f32_e32 v254, v224, v254
	v_exp_f32_e32 v226, v226
	v_sub_f32_e32 v227, v227, v190
	v_add_f32_e32 v254, v225, v254
	v_exp_f32_e32 v227, v227
	v_sub_f32_e32 v228, v228, v190
	v_add_f32_e32 v254, v226, v254
	v_exp_f32_e32 v228, v228
	v_sub_f32_e32 v229, v229, v190
	v_add_f32_e32 v254, v227, v254
	v_exp_f32_e32 v229, v229
	v_sub_f32_e32 v230, v230, v190
	v_add_f32_e32 v254, v228, v254
	v_exp_f32_e32 v230, v230
	v_sub_f32_e32 v231, v231, v190
	v_add_f32_e32 v254, v229, v254
	v_exp_f32_e32 v231, v231
	v_sub_f32_e32 v232, v232, v190
	v_add_f32_e32 v254, v230, v254
	v_exp_f32_e32 v232, v232
	v_sub_f32_e32 v233, v233, v190
	v_add_f32_e32 v254, v231, v254
	v_exp_f32_e32 v233, v233
	v_sub_f32_e32 v234, v234, v190
	v_add_f32_e32 v254, v232, v254
	v_exp_f32_e32 v234, v234
	v_sub_f32_e32 v235, v235, v190
	v_add_f32_e32 v254, v233, v254
	v_exp_f32_e32 v235, v235
	v_sub_f32_e32 v236, v236, v190
	v_add_f32_e32 v254, v234, v254
	v_exp_f32_e32 v236, v236
	v_sub_f32_e32 v237, v237, v190
	v_add_f32_e32 v254, v235, v254
	v_exp_f32_e32 v237, v237
	v_add_f32_e32 v254, v236, v254
	v_add_f32_e32 v254, v237, v254
	v_cvt_pk_bf16_f32 v242, v222, v223
	v_cvt_pk_bf16_f32 v243, v224, v225
	v_cvt_pk_bf16_f32 v244, v226, v227
	v_cvt_pk_bf16_f32 v245, v228, v229
	v_cvt_pk_bf16_f32 v250, v230, v231
	v_cvt_pk_bf16_f32 v251, v232, v233
	v_cvt_pk_bf16_f32 v252, v234, v235
	v_cvt_pk_bf16_f32 v253, v236, v237
	v_add_f32_e32 v195, v195, v254
	s_nop 1
	s_waitcnt lgkmcnt(8)
	v_mfma_f32_32x32x16_bf16 v[112:127], v[238:241], v[242:245], v[112:127]
	ds_read_b64_tr_b16 v[238:239], v218 offset:16640
	ds_read_b64_tr_b16 v[240:241], v218 offset:20736
	s_waitcnt lgkmcnt(8)
	v_mfma_f32_32x32x16_bf16 v[96:111], v[128:131], v[242:245], v[96:111]
	ds_read_b64_tr_b16 v[222:223], v219 offset:16640
	ds_read_b64_tr_b16 v[224:225], v219 offset:20736
	s_waitcnt lgkmcnt(8)
	v_mfma_f32_32x32x16_bf16 v[80:95], v[206:209], v[242:245], v[80:95]
	ds_read_b64_tr_b16 v[206:207], v221 offset:16640
	ds_read_b64_tr_b16 v[208:209], v221 offset:20736
	s_waitcnt lgkmcnt(8)
	v_mfma_f32_32x32x16_bf16 v[64:79], v[210:213], v[242:245], v[64:79]
	ds_read_b64_tr_b16 v[210:211], v205 offset:24576
	ds_read_b64_tr_b16 v[212:213], v205 offset:28672
	s_waitcnt lgkmcnt(8)
	v_mfma_f32_32x32x16_bf16 v[48:63], v[214:217], v[242:245], v[48:63]
	ds_read_b64_tr_b16 v[214:215], v218 offset:24576
	ds_read_b64_tr_b16 v[216:217], v218 offset:28672
	s_waitcnt lgkmcnt(8)
	v_mfma_f32_32x32x16_bf16 v[32:47], v[238:241], v[242:245], v[32:47]
	ds_read_b64_tr_b16 v[238:239], v219 offset:24576
	ds_read_b64_tr_b16 v[240:241], v219 offset:28672
	s_waitcnt lgkmcnt(8)
	v_mfma_f32_32x32x16_bf16 v[16:31], v[222:225], v[242:245], v[16:31]
	ds_read_b64_tr_b16 v[222:223], v221 offset:24576
	ds_read_b64_tr_b16 v[224:225], v221 offset:28672
	s_waitcnt lgkmcnt(8)
	v_mfma_f32_32x32x16_bf16 v[0:15], v[206:209], v[242:245], v[0:15]
	ds_read_b64_tr_b16 v[206:207], v205 offset:24832
	ds_read_b64_tr_b16 v[208:209], v205 offset:28928
	s_waitcnt lgkmcnt(8)
	v_mfma_f32_32x32x16_bf16 v[112:127], v[210:213], v[250:253], v[112:127]
	ds_read_b64_tr_b16 v[210:211], v218 offset:24832
	ds_read_b64_tr_b16 v[212:213], v218 offset:28928
	s_waitcnt lgkmcnt(8)
	v_mfma_f32_32x32x16_bf16 v[96:111], v[214:217], v[250:253], v[96:111]
	ds_read_b64_tr_b16 v[214:215], v219 offset:24832
	ds_read_b64_tr_b16 v[216:217], v219 offset:28928
	s_waitcnt lgkmcnt(8)
	v_mfma_f32_32x32x16_bf16 v[80:95], v[238:241], v[250:253], v[80:95]
	ds_read_b64_tr_b16 v[238:239], v221 offset:24832
	ds_read_b64_tr_b16 v[240:241], v221 offset:28928
	s_waitcnt lgkmcnt(8)
	v_mfma_f32_32x32x16_bf16 v[64:79], v[222:225], v[250:253], v[64:79]
	s_waitcnt lgkmcnt(6)
	v_mfma_f32_32x32x16_bf16 v[48:63], v[206:209], v[250:253], v[48:63]
	s_waitcnt lgkmcnt(4)
	v_mfma_f32_32x32x16_bf16 v[32:47], v[210:213], v[250:253], v[32:47]
	s_waitcnt lgkmcnt(2)
	v_mfma_f32_32x32x16_bf16 v[16:31], v[214:217], v[250:253], v[16:31]
	s_waitcnt lgkmcnt(0)
	v_mfma_f32_32x32x16_bf16 v[0:15], v[238:241], v[250:253], v[0:15]
	ds_read_b128 v[206:209], v196 offset:16384
	ds_read_b128 v[210:213], v197 offset:16384
	ds_read_b128 v[214:217], v198 offset:16384
	ds_read_b128 v[238:241], v199 offset:16384
	ds_read_b128 v[242:245], v200 offset:16384
	ds_read_b128 v[250:253], v201 offset:16384
	ds_read_b128 v[222:225], v202 offset:16384
	ds_read_b128 v[226:229], v203 offset:16384
	s_waitcnt vmcnt(0)
	s_add_i32 s8, s11, 1
	s_cmp_lg_u32 s11, 2
	s_cselect_b32 s11, s8, 0
	s_add_i32 s14, s14, 64
	s_add_u32 s34, s34, 0x100000
	s_addc_u32 s35, s35, 0
	s_add_i32 s10, s10, 1
	s_add_i32 s100, s14, 63
	s_cmp_le_i32 s100, s80
	s_cbranch_scc0 .Latt_latchb_3
	s_cmp_ge_u32 s10, s78
	s_cselect_b64 s[8:9], -1, 0
	v_mov_b32_e32 v204, v176
	s_barrier
	s_branch .Latt_cont_3s1
.Latt_slow_3s0:
.Latt_slot1_3:
.Latt_cont_3s1:
	v_add_u32_e32 v205, 0x8000, v205
	v_add_u32_e32 v218, 0x8000, v218
	v_add_u32_e32 v219, 0x8000, v219
	v_add_u32_e32 v221, 0x8000, v221
	s_waitcnt lgkmcnt(7)
	v_mfma_f32_32x32x16_bf16 v[128:143], v[206:209], v[144:147], 0
	ds_read_b128 v[206:209], v196 offset:24576
	s_cmp_lg_u64 s[8:9], 0
	s_cbranch_scc1 .Latt_nd0_3s1
	s_sub_i32 s100, s11, 1
	s_cmp_eq_u32 s11, 0
	s_cselect_b32 s100, 2, s100
	s_lshl_b32 s101, s100, 14
	s_add_i32 m0, s40, s101
	s_nop 0
	global_load_lds_dwordx4 v178, s[34:35]

.Latt_nr0_3s1:
	s_waitcnt lgkmcnt(3)
	v_mfma_f32_32x32x16_bf16 v[222:237], v[214:217], v[152:155], v[222:237]
	ds_read_b128 v[214:217], v202 offset:24576
	v_sub_f32_e32 v128, v128, v190
	v_exp_f32_e32 v128, v128
	v_sub_f32_e32 v129, v129, v190
	v_exp_f32_e32 v129, v129
	v_sub_f32_e32 v130, v130, v190
	s_waitcnt lgkmcnt(3)
	v_mfma_f32_32x32x16_bf16 v[222:237], v[238:241], v[156:159], v[222:237]
	ds_read_b128 v[238:241], v203 offset:24576
	v_add_f32_e32 v254, 0, v128
	v_exp_f32_e32 v130, v130
	v_sub_f32_e32 v131, v131, v190
	v_add_f32_e32 v254, v129, v254
	v_exp_f32_e32 v131, v131
	s_waitcnt lgkmcnt(3)
	v_mfma_f32_32x32x16_bf16 v[222:237], v[206:209], v[160:163], v[222:237]
	ds_read_b64_tr_b16 v[206:207], v205
	ds_read_b64_tr_b16 v[208:209], v205 offset:4096
	v_sub_f32_e32 v132, v132, v190
	v_add_f32_e32 v254, v130, v254
	v_exp_f32_e32 v132, v132
	v_sub_f32_e32 v133, v133, v190
	v_add_f32_e32 v254, v131, v254
	s_waitcnt lgkmcnt(4)
	v_mfma_f32_32x32x16_bf16 v[222:237], v[210:213], v[164:167], v[222:237]
	ds_read_b64_tr_b16 v[210:211], v218
	ds_read_b64_tr_b16 v[212:213], v218 offset:4096
	v_exp_f32_e32 v133, v133
	v_sub_f32_e32 v134, v134, v190
	v_add_f32_e32 v254, v132, v254
	v_exp_f32_e32 v134, v134
	s_waitcnt lgkmcnt(5)
	v_mfma_f32_32x32x16_bf16 v[222:237], v[214:217], v[168:171], v[222:237]
	ds_read_b64_tr_b16 v[214:215], v219
	ds_read_b64_tr_b16 v[216:217], v219 offset:4096
	v_sub_f32_e32 v135, v135, v190
	v_add_f32_e32 v254, v133, v254
	v_exp_f32_e32 v135, v135
	s_nop 0
	s_waitcnt lgkmcnt(6)
	v_mfma_f32_32x32x16_bf16 v[222:237], v[238:241], v[172:175], v[222:237]
	ds_read_b64_tr_b16 v[238:239], v221
	ds_read_b64_tr_b16 v[240:241], v221 offset:4096
	v_cvt_pk_bf16_f32 v242, v128, v129
	v_cvt_pk_bf16_f32 v243, v130, v131
	v_cvt_pk_bf16_f32 v244, v132, v133
	v_cvt_pk_bf16_f32 v245, v134, v135
	s_nop 1
	s_waitcnt lgkmcnt(6)
	v_mfma_f32_32x32x16_bf16 v[112:127], v[206:209], v[242:245], v[112:127]
	ds_read_b64_tr_b16 v[206:207], v205 offset:256
	ds_read_b64_tr_b16 v[208:209], v205 offset:4352
	v_sub_f32_e32 v136, v136, v190
	v_add_f32_e32 v254, v134, v254
	v_exp_f32_e32 v136, v136
	v_sub_f32_e32 v137, v137, v190
	v_add_f32_e32 v254, v135, v254
	s_waitcnt lgkmcnt(6)
	v_mfma_f32_32x32x16_bf16 v[96:111], v[210:213], v[242:245], v[96:111]
	ds_read_b64_tr_b16 v[210:211], v218 offset:256
	ds_read_b64_tr_b16 v[212:213], v218 offset:4352
	v_exp_f32_e32 v137, v137
	v_sub_f32_e32 v138, v138, v190
	v_add_f32_e32 v254, v136, v254
	v_exp_f32_e32 v138, v138
	v_sub_f32_e32 v139, v139, v190
	s_waitcnt lgkmcnt(6)
	v_mfma_f32_32x32x16_bf16 v[80:95], v[214:217], v[242:245], v[80:95]
	ds_read_b64_tr_b16 v[214:215], v219 offset:256
	ds_read_b64_tr_b16 v[216:217], v219 offset:4352
	v_add_f32_e32 v254, v137, v254
	v_exp_f32_e32 v139, v139
	v_sub_f32_e32 v140, v140, v190
	v_add_f32_e32 v254, v138, v254
	s_waitcnt lgkmcnt(6)
	v_mfma_f32_32x32x16_bf16 v[64:79], v[238:241], v[242:245], v[64:79]
	ds_read_b64_tr_b16 v[238:239], v221 offset:256
	ds_read_b64_tr_b16 v[240:241], v221 offset:4352
	v_exp_f32_e32 v140, v140
	v_sub_f32_e32 v141, v141, v190
	v_add_f32_e32 v254, v139, v254
	v_exp_f32_e32 v141, v141
	s_waitcnt lgkmcnt(6)
	v_mfma_f32_32x32x16_bf16 v[48:63], v[206:209], v[242:245], v[48:63]
	ds_read_b64_tr_b16 v[206:207], v205 offset:8192
	ds_read_b64_tr_b16 v[208:209], v205 offset:12288
	v_sub_f32_e32 v142, v142, v190
	v_add_f32_e32 v254, v140, v254
	v_exp_f32_e32 v142, v142
	v_sub_f32_e32 v143, v143, v190
	s_waitcnt lgkmcnt(6)
	v_mfma_f32_32x32x16_bf16 v[32:47], v[210:213], v[242:245], v[32:47]
	ds_read_b64_tr_b16 v[210:211], v218 offset:8192
	ds_read_b64_tr_b16 v[212:213], v218 offset:12288
	v_add_f32_e32 v254, v141, v254
	v_exp_f32_e32 v143, v143
	v_add_f32_e32 v254, v142, v254
	v_add_f32_e32 v254, v143, v254
	s_waitcnt lgkmcnt(6)
	v_mfma_f32_32x32x16_bf16 v[16:31], v[214:217], v[242:245], v[16:31]
	ds_read_b64_tr_b16 v[214:215], v219 offset:8192
	ds_read_b64_tr_b16 v[216:217], v219 offset:12288
	v_cvt_pk_bf16_f32 v250, v136, v137
	v_cvt_pk_bf16_f32 v251, v138, v139
	v_cvt_pk_bf16_f32 v252, v140, v141
	v_cvt_pk_bf16_f32 v253, v142, v143
	v_add_f32_e32 v195, v195, v254
	s_waitcnt lgkmcnt(6)
	v_mfma_f32_32x32x16_bf16 v[0:15], v[238:241], v[242:245], v[0:15]
	ds_read_b64_tr_b16 v[238:239], v221 offset:8192
	ds_read_b64_tr_b16 v[240:241], v221 offset:12288
	ds_read_b64_tr_b16 v[128:129], v205 offset:8448
	ds_read_b64_tr_b16 v[130:131], v205 offset:12544
	s_waitcnt lgkmcnt(8)
	v_mfma_f32_32x32x16_bf16 v[112:127], v[206:209], v[250:253], v[112:127]
	ds_read_b64_tr_b16 v[206:207], v218 offset:8448
	ds_read_b64_tr_b16 v[208:209], v218 offset:12544
	v_max3_f32 v246, v222, v223, v224
	v_max3_f32 v247, v225, v226, v227
	v_max3_f32 v246, v246, v228, v229
	v_max3_f32 v247, v247, v230, v231
	v_max3_f32 v246, v246, v232, v233
	s_waitcnt lgkmcnt(8)
	v_mfma_f32_32x32x16_bf16 v[96:111], v[210:213], v[250:253], v[96:111]
	ds_read_b64_tr_b16 v[210:211], v219 offset:8448
	ds_read_b64_tr_b16 v[212:213], v219 offset:12544
	v_max3_f32 v247, v247, v234, v235
	v_max3_f32 v246, v246, v236, v237
	v_max_f32_e32 v246, v246, v247
	v_mov_b32_e32 v247, v246
	v_add_f32_e32 v249, 0x41000000, v190
	s_waitcnt lgkmcnt(8)
	v_mfma_f32_32x32x16_bf16 v[80:95], v[214:217], v[250:253], v[80:95]
	ds_read_b64_tr_b16 v[214:215], v221 offset:8448
	ds_read_b64_tr_b16 v[216:217], v221 offset:12544
	s_nop 1
	v_permlane32_swap_b32_e32 v246, v247
	v_max_f32_e32 v246, v246, v247
	v_cmp_gt_f32_e32 vcc, v246, v249
	s_cbranch_vccnz .Latt_rs1_3s1
	s_waitcnt lgkmcnt(8)
	v_mfma_f32_32x32x16_bf16 v[64:79], v[238:241], v[250:253], v[64:79]
	ds_read_b64_tr_b16 v[238:239], v205 offset:16384
	ds_read_b64_tr_b16 v[240:241], v205 offset:20480
	v_sub_f32_e32 v222, v222, v190
	v_exp_f32_e32 v222, v222
	v_sub_f32_e32 v223, v223, v190
	v_exp_f32_e32 v223, v223
	v_sub_f32_e32 v224, v224, v190
	v_add_f32_e32 v254, 0, v222
	s_waitcnt lgkmcnt(8)
	v_mfma_f32_32x32x16_bf16 v[48:63], v[128:131], v[250:253], v[48:63]
	ds_read_b64_tr_b16 v[128:129], v218 offset:16384
	ds_read_b64_tr_b16 v[130:131], v218 offset:20480
	v_exp_f32_e32 v224, v224
	v_sub_f32_e32 v225, v225, v190
	v_add_f32_e32 v254, v223, v254
	v_exp_f32_e32 v225, v225
	v_sub_f32_e32 v226, v226, v190
	v_add_f32_e32 v254, v224, v254
	s_waitcnt lgkmcnt(8)
	v_mfma_f32_32x32x16_bf16 v[32:47], v[206:209], v[250:253], v[32:47]
	ds_read_b64_tr_b16 v[206:207], v219 offset:16384
	ds_read_b64_tr_b16 v[208:209], v219 offset:20480
	v_exp_f32_e32 v226, v226
	v_sub_f32_e32 v227, v227, v190
	v_add_f32_e32 v254, v225, v254
	v_exp_f32_e32 v227, v227
	v_sub_f32_e32 v228, v228, v190
	s_waitcnt lgkmcnt(8)
	v_mfma_f32_32x32x16_bf16 v[16:31], v[210:213], v[250:253], v[16:31]
	ds_read_b64_tr_b16 v[210:211], v221 offset:16384
	ds_read_b64_tr_b16 v[212:213], v221 offset:20480
	v_add_f32_e32 v254, v226, v254
	v_exp_f32_e32 v228, v228
	v_sub_f32_e32 v229, v229, v190
	v_add_f32_e32 v254, v227, v254
	v_exp_f32_e32 v229, v229
	s_waitcnt lgkmcnt(8)
	v_mfma_f32_32x32x16_bf16 v[0:15], v[214:217], v[250:253], v[0:15]
	ds_read_b64_tr_b16 v[214:215], v205 offset:16640
	ds_read_b64_tr_b16 v[216:217], v205 offset:20736
	s_nop 0
	v_cvt_pk_bf16_f32 v242, v222, v223
	v_cvt_pk_bf16_f32 v243, v224, v225
	v_cvt_pk_bf16_f32 v244, v226, v227
	v_cvt_pk_bf16_f32 v245, v228, v229
	s_nop 1
	s_waitcnt lgkmcnt(8)
	v_mfma_f32_32x32x16_bf16 v[112:127], v[238:241], v[242:245], v[112:127]
	ds_read_b64_tr_b16 v[238:239], v218 offset:16640
	ds_read_b64_tr_b16 v[240:241], v218 offset:20736
	v_sub_f32_e32 v230, v230, v190
	v_add_f32_e32 v254, v228, v254
	v_exp_f32_e32 v230, v230
	v_sub_f32_e32 v231, v231, v190
	v_add_f32_e32 v254, v229, v254
	s_waitcnt lgkmcnt(8)
	v_mfma_f32_32x32x16_bf16 v[96:111], v[128:131], v[242:245], v[96:111]
	ds_read_b64_tr_b16 v[128:129], v219 offset:16640
	ds_read_b64_tr_b16 v[130:131], v219 offset:20736
	v_exp_f32_e32 v231, v231
	v_sub_f32_e32 v232, v232, v190
	v_add_f32_e32 v254, v230, v254
	v_exp_f32_e32 v232, v232
	v_sub_f32_e32 v233, v233, v190
	s_waitcnt lgkmcnt(8)
	v_mfma_f32_32x32x16_bf16 v[80:95], v[206:209], v[242:245], v[80:95]
	ds_read_b64_tr_b16 v[206:207], v221 offset:16640
	ds_read_b64_tr_b16 v[208:209], v221 offset:20736
	v_add_f32_e32 v254, v231, v254
	v_exp_f32_e32 v233, v233
	v_sub_f32_e32 v234, v234, v190
	v_add_f32_e32 v254, v232, v254
	s_waitcnt lgkmcnt(8)
	v_mfma_f32_32x32x16_bf16 v[64:79], v[210:213], v[242:245], v[64:79]
	ds_read_b64_tr_b16 v[210:211], v205 offset:24576
	ds_read_b64_tr_b16 v[212:213], v205 offset:28672
	v_exp_f32_e32 v234, v234
	v_sub_f32_e32 v235, v235, v190
	v_add_f32_e32 v254, v233, v254
	v_exp_f32_e32 v235, v235
	s_waitcnt lgkmcnt(8)
	v_mfma_f32_32x32x16_bf16 v[48:63], v[214:217], v[242:245], v[48:63]
	ds_read_b64_tr_b16 v[214:215], v218 offset:24576
	ds_read_b64_tr_b16 v[216:217], v218 offset:28672
	v_sub_f32_e32 v236, v236, v190
	v_add_f32_e32 v254, v234, v254
	v_exp_f32_e32 v236, v236
	v_sub_f32_e32 v237, v237, v190
	s_waitcnt lgkmcnt(8)
	v_mfma_f32_32x32x16_bf16 v[32:47], v[238:241], v[242:245], v[32:47]
	ds_read_b64_tr_b16 v[238:239], v219 offset:24576
	ds_read_b64_tr_b16 v[240:241], v219 offset:28672
	v_add_f32_e32 v254, v235, v254
	v_exp_f32_e32 v237, v237
	v_add_f32_e32 v254, v236, v254
	v_add_f32_e32 v254, v237, v254
	s_waitcnt lgkmcnt(8)
	v_mfma_f32_32x32x16_bf16 v[16:31], v[128:131], v[242:245], v[16:31]
	ds_read_b64_tr_b16 v[128:129], v221 offset:24576
	ds_read_b64_tr_b16 v[130:131], v221 offset:28672
	v_cvt_pk_bf16_f32 v250, v230, v231
	v_cvt_pk_bf16_f32 v251, v232, v233
	v_cvt_pk_bf16_f32 v252, v234, v235
	v_cvt_pk_bf16_f32 v253, v236, v237
	v_add_f32_e32 v195, v195, v254
	s_waitcnt lgkmcnt(8)
	v_mfma_f32_32x32x16_bf16 v[0:15], v[206:209], v[242:245], v[0:15]
	ds_read_b64_tr_b16 v[206:207], v205 offset:24832
	ds_read_b64_tr_b16 v[208:209], v205 offset:28928
	s_waitcnt lgkmcnt(8)
	v_mfma_f32_32x32x16_bf16 v[112:127], v[210:213], v[250:253], v[112:127]
	ds_read_b64_tr_b16 v[210:211], v218 offset:24832
	ds_read_b64_tr_b16 v[212:213], v218 offset:28928
	s_waitcnt lgkmcnt(8)
	v_mfma_f32_32x32x16_bf16 v[96:111], v[214:217], v[250:253], v[96:111]
	ds_read_b64_tr_b16 v[214:215], v219 offset:24832
	ds_read_b64_tr_b16 v[216:217], v219 offset:28928
	s_waitcnt lgkmcnt(8)
	v_mfma_f32_32x32x16_bf16 v[80:95], v[238:241], v[250:253], v[80:95]
	ds_read_b64_tr_b16 v[238:239], v221 offset:24832
	ds_read_b64_tr_b16 v[240:241], v221 offset:28928
	s_waitcnt lgkmcnt(8)
	v_mfma_f32_32x32x16_bf16 v[64:79], v[128:131], v[250:253], v[64:79]
	s_waitcnt lgkmcnt(6)
	v_mfma_f32_32x32x16_bf16 v[48:63], v[206:209], v[250:253], v[48:63]
	s_waitcnt lgkmcnt(4)
	v_mfma_f32_32x32x16_bf16 v[32:47], v[210:213], v[250:253], v[32:47]
	s_waitcnt lgkmcnt(2)
	v_mfma_f32_32x32x16_bf16 v[16:31], v[214:217], v[250:253], v[16:31]
	s_waitcnt lgkmcnt(0)
	v_mfma_f32_32x32x16_bf16 v[0:15], v[238:241], v[250:253], v[0:15]
	ds_read_b128 v[206:209], v196 offset:32768
	ds_read_b128 v[210:213], v197 offset:32768
	ds_read_b128 v[214:217], v198 offset:32768
	ds_read_b128 v[238:241], v199 offset:32768
	ds_read_b128 v[242:245], v200 offset:32768
	ds_read_b128 v[250:253], v201 offset:32768
	ds_read_b128 v[222:225], v202 offset:32768
	ds_read_b128 v[226:229], v203 offset:32768
	s_waitcnt vmcnt(0)
	s_add_i32 s8, s11, 1
	s_cmp_lg_u32 s11, 2
	s_cselect_b32 s11, s8, 0
	s_add_i32 s14, s14, 64
	s_add_u32 s34, s34, 0x100000
	s_addc_u32 s35, s35, 0
	s_add_i32 s10, s10, 1
	s_add_i32 s100, s14, 63
	s_cmp_le_i32 s100, s80
	s_cbranch_scc0 .Latt_latchb_3
	s_cmp_ge_u32 s10, s78
	s_cselect_b64 s[8:9], -1, 0
	v_mov_b32_e32 v204, v176
	s_barrier
	s_branch .Latt_cont_3s2
.Latt_rs1_3s1:
	s_waitcnt lgkmcnt(8)
	v_mfma_f32_32x32x16_bf16 v[64:79], v[238:241], v[250:253], v[64:79]
	ds_read_b64_tr_b16 v[238:239], v205 offset:16384
	ds_read_b64_tr_b16 v[240:241], v205 offset:20480
	s_waitcnt lgkmcnt(8)
	v_mfma_f32_32x32x16_bf16 v[48:63], v[128:131], v[250:253], v[48:63]
	ds_read_b64_tr_b16 v[128:129], v218 offset:16384
	ds_read_b64_tr_b16 v[130:131], v218 offset:20480
	s_waitcnt lgkmcnt(8)
	v_mfma_f32_32x32x16_bf16 v[32:47], v[206:209], v[250:253], v[32:47]
	ds_read_b64_tr_b16 v[206:207], v219 offset:16384
	ds_read_b64_tr_b16 v[208:209], v219 offset:20480
	s_waitcnt lgkmcnt(8)
	v_mfma_f32_32x32x16_bf16 v[16:31], v[210:213], v[250:253], v[16:31]
	ds_read_b64_tr_b16 v[210:211], v221 offset:16384
	ds_read_b64_tr_b16 v[212:213], v221 offset:20480
	s_waitcnt lgkmcnt(8)
	v_mfma_f32_32x32x16_bf16 v[0:15], v[214:217], v[250:253], v[0:15]
	ds_read_b64_tr_b16 v[214:215], v205 offset:16640
	ds_read_b64_tr_b16 v[216:217], v205 offset:20736
	s_nop 11
	v_max_f32_e32 v246, v190, v246
	v_sub_f32_e32 v190, v190, v246
	v_exp_f32_e32 v190, v190
	s_nop 0
	v_pk_mul_f32 v[126:127], v[126:127], v[190:191] op_sel_hi:[1,0]
	v_pk_mul_f32 v[124:125], v[124:125], v[190:191] op_sel_hi:[1,0]
	v_pk_mul_f32 v[122:123], v[122:123], v[190:191] op_sel_hi:[1,0]
	v_pk_mul_f32 v[120:121], v[120:121], v[190:191] op_sel_hi:[1,0]
	v_pk_mul_f32 v[118:119], v[118:119], v[190:191] op_sel_hi:[1,0]
	v_pk_mul_f32 v[116:117], v[116:117], v[190:191] op_sel_hi:[1,0]
	v_pk_mul_f32 v[114:115], v[114:115], v[190:191] op_sel_hi:[1,0]
	v_pk_mul_f32 v[112:113], v[112:113], v[190:191] op_sel_hi:[1,0]
	v_pk_mul_f32 v[110:111], v[110:111], v[190:191] op_sel_hi:[1,0]
	v_pk_mul_f32 v[108:109], v[108:109], v[190:191] op_sel_hi:[1,0]
	v_pk_mul_f32 v[106:107], v[106:107], v[190:191] op_sel_hi:[1,0]
	v_pk_mul_f32 v[104:105], v[104:105], v[190:191] op_sel_hi:[1,0]
	v_pk_mul_f32 v[102:103], v[102:103], v[190:191] op_sel_hi:[1,0]
	v_pk_mul_f32 v[100:101], v[100:101], v[190:191] op_sel_hi:[1,0]
	v_pk_mul_f32 v[98:99], v[98:99], v[190:191] op_sel_hi:[1,0]
	v_pk_mul_f32 v[96:97], v[96:97], v[190:191] op_sel_hi:[1,0]
	v_pk_mul_f32 v[94:95], v[94:95], v[190:191] op_sel_hi:[1,0]
	v_pk_mul_f32 v[92:93], v[92:93], v[190:191] op_sel_hi:[1,0]
	v_pk_mul_f32 v[90:91], v[90:91], v[190:191] op_sel_hi:[1,0]
	v_pk_mul_f32 v[88:89], v[88:89], v[190:191] op_sel_hi:[1,0]
	v_pk_mul_f32 v[86:87], v[86:87], v[190:191] op_sel_hi:[1,0]
	v_pk_mul_f32 v[84:85], v[84:85], v[190:191] op_sel_hi:[1,0]
	v_pk_mul_f32 v[82:83], v[82:83], v[190:191] op_sel_hi:[1,0]
	v_pk_mul_f32 v[80:81], v[80:81], v[190:191] op_sel_hi:[1,0]
	v_pk_mul_f32 v[78:79], v[78:79], v[190:191] op_sel_hi:[1,0]
	v_pk_mul_f32 v[76:77], v[76:77], v[190:191] op_sel_hi:[1,0]
	v_pk_mul_f32 v[74:75], v[74:75], v[190:191] op_sel_hi:[1,0]
	v_pk_mul_f32 v[72:73], v[72:73], v[190:191] op_sel_hi:[1,0]
	v_pk_mul_f32 v[70:71], v[70:71], v[190:191] op_sel_hi:[1,0]
	v_pk_mul_f32 v[68:69], v[68:69], v[190:191] op_sel_hi:[1,0]
	v_pk_mul_f32 v[66:67], v[66:67], v[190:191] op_sel_hi:[1,0]
	v_pk_mul_f32 v[64:65], v[64:65], v[190:191] op_sel_hi:[1,0]
	v_pk_mul_f32 v[62:63], v[62:63], v[190:191] op_sel_hi:[1,0]
	v_pk_mul_f32 v[60:61], v[60:61], v[190:191] op_sel_hi:[1,0]
	v_pk_mul_f32 v[58:59], v[58:59], v[190:191] op_sel_hi:[1,0]
	v_pk_mul_f32 v[56:57], v[56:57], v[190:191] op_sel_hi:[1,0]
	v_pk_mul_f32 v[54:55], v[54:55], v[190:191] op_sel_hi:[1,0]
	v_pk_mul_f32 v[52:53], v[52:53], v[190:191] op_sel_hi:[1,0]
	v_pk_mul_f32 v[50:51], v[50:51], v[190:191] op_sel_hi:[1,0]
	v_pk_mul_f32 v[48:49], v[48:49], v[190:191] op_sel_hi:[1,0]
	v_pk_mul_f32 v[46:47], v[46:47], v[190:191] op_sel_hi:[1,0]
	v_pk_mul_f32 v[44:45], v[44:45], v[190:191] op_sel_hi:[1,0]
	v_pk_mul_f32 v[42:43], v[42:43], v[190:191] op_sel_hi:[1,0]
	v_pk_mul_f32 v[40:41], v[40:41], v[190:191] op_sel_hi:[1,0]
	v_pk_mul_f32 v[38:39], v[38:39], v[190:191] op_sel_hi:[1,0]
	v_pk_mul_f32 v[36:37], v[36:37], v[190:191] op_sel_hi:[1,0]
	v_pk_mul_f32 v[34:35], v[34:35], v[190:191] op_sel_hi:[1,0]
	v_pk_mul_f32 v[32:33], v[32:33], v[190:191] op_sel_hi:[1,0]
	v_pk_mul_f32 v[30:31], v[30:31], v[190:191] op_sel_hi:[1,0]
	v_pk_mul_f32 v[28:29], v[28:29], v[190:191] op_sel_hi:[1,0]
	v_pk_mul_f32 v[26:27], v[26:27], v[190:191] op_sel_hi:[1,0]
	v_pk_mul_f32 v[24:25], v[24:25], v[190:191] op_sel_hi:[1,0]
	v_pk_mul_f32 v[22:23], v[22:23], v[190:191] op_sel_hi:[1,0]
	v_pk_mul_f32 v[20:21], v[20:21], v[190:191] op_sel_hi:[1,0]
	v_pk_mul_f32 v[18:19], v[18:19], v[190:191] op_sel_hi:[1,0]
	v_pk_mul_f32 v[16:17], v[16:17], v[190:191] op_sel_hi:[1,0]
	v_pk_mul_f32 v[14:15], v[14:15], v[190:191] op_sel_hi:[1,0]
	v_pk_mul_f32 v[12:13], v[12:13], v[190:191] op_sel_hi:[1,0]
	v_pk_mul_f32 v[10:11], v[10:11], v[190:191] op_sel_hi:[1,0]
	v_pk_mul_f32 v[8:9], v[8:9], v[190:191] op_sel_hi:[1,0]
	v_pk_mul_f32 v[6:7], v[6:7], v[190:191] op_sel_hi:[1,0]
	v_pk_mul_f32 v[4:5], v[4:5], v[190:191] op_sel_hi:[1,0]
	v_pk_mul_f32 v[2:3], v[2:3], v[190:191] op_sel_hi:[1,0]
	v_pk_mul_f32 v[0:1], v[0:1], v[190:191] op_sel_hi:[1,0]
	v_mul_f32_e32 v195, v195, v190
	v_mov_b32_e32 v190, v246
	v_sub_f32_e32 v222, v222, v190
	v_exp_f32_e32 v222, v222
	v_sub_f32_e32 v223, v223, v190
	v_exp_f32_e32 v223, v223
	v_sub_f32_e32 v224, v224, v190
	v_add_f32_e32 v254, 0, v222
	v_exp_f32_e32 v224, v224
	v_sub_f32_e32 v225, v225, v190
	v_add_f32_e32 v254, v223, v254
	v_exp_f32_e32 v225, v225
	v_sub_f32_e32 v226, v226, v190
	v_add_f32_e32 v254, v224, v254
	v_exp_f32_e32 v226, v226
	v_sub_f32_e32 v227, v227, v190
	v_add_f32_e32 v254, v225, v254
	v_exp_f32_e32 v227, v227
	v_sub_f32_e32 v228, v228, v190
	v_add_f32_e32 v254, v226, v254
	v_exp_f32_e32 v228, v228
	v_sub_f32_e32 v229, v229, v190
	v_add_f32_e32 v254, v227, v254
	v_exp_f32_e32 v229, v229
	v_sub_f32_e32 v230, v230, v190
	v_add_f32_e32 v254, v228, v254
	v_exp_f32_e32 v230, v230
	v_sub_f32_e32 v231, v231, v190
	v_add_f32_e32 v254, v229, v254
	v_exp_f32_e32 v231, v231
	v_sub_f32_e32 v232, v232, v190
	v_add_f32_e32 v254, v230, v254
	v_exp_f32_e32 v232, v232
	v_sub_f32_e32 v233, v233, v190
	v_add_f32_e32 v254, v231, v254
	v_exp_f32_e32 v233, v233
	v_sub_f32_e32 v234, v234, v190
	v_add_f32_e32 v254, v232, v254
	v_exp_f32_e32 v234, v234
	v_sub_f32_e32 v235, v235, v190
	v_add_f32_e32 v254, v233, v254
	v_exp_f32_e32 v235, v235
	v_sub_f32_e32 v236, v236, v190
	v_add_f32_e32 v254, v234, v254
	v_exp_f32_e32 v236, v236
	v_sub_f32_e32 v237, v237, v190
	v_add_f32_e32 v254, v235, v254
	v_exp_f32_e32 v237, v237
	v_add_f32_e32 v254, v236, v254
	v_add_f32_e32 v254, v237, v254
	v_cvt_pk_bf16_f32 v242, v222, v223
	v_cvt_pk_bf16_f32 v243, v224, v225
	v_cvt_pk_bf16_f32 v244, v226, v227
	v_cvt_pk_bf16_f32 v245, v228, v229
	v_cvt_pk_bf16_f32 v250, v230, v231
	v_cvt_pk_bf16_f32 v251, v232, v233
	v_cvt_pk_bf16_f32 v252, v234, v235
	v_cvt_pk_bf16_f32 v253, v236, v237
	v_add_f32_e32 v195, v195, v254
	s_nop 1
	s_waitcnt lgkmcnt(8)
	v_mfma_f32_32x32x16_bf16 v[112:127], v[238:241], v[242:245], v[112:127]
	ds_read_b64_tr_b16 v[238:239], v218 offset:16640
	ds_read_b64_tr_b16 v[240:241], v218 offset:20736
	s_waitcnt lgkmcnt(8)
	v_mfma_f32_32x32x16_bf16 v[96:111], v[128:131], v[242:245], v[96:111]
	ds_read_b64_tr_b16 v[222:223], v219 offset:16640
	ds_read_b64_tr_b16 v[224:225], v219 offset:20736
	s_waitcnt lgkmcnt(8)
	v_mfma_f32_32x32x16_bf16 v[80:95], v[206:209], v[242:245], v[80:95]
	ds_read_b64_tr_b16 v[206:207], v221 offset:16640
	ds_read_b64_tr_b16 v[208:209], v221 offset:20736
	s_waitcnt lgkmcnt(8)
	v_mfma_f32_32x32x16_bf16 v[64:79], v[210:213], v[242:245], v[64:79]
	ds_read_b64_tr_b16 v[210:211], v205 offset:24576
	ds_read_b64_tr_b16 v[212:213], v205 offset:28672
	s_waitcnt lgkmcnt(8)
	v_mfma_f32_32x32x16_bf16 v[48:63], v[214:217], v[242:245], v[48:63]
	ds_read_b64_tr_b16 v[214:215], v218 offset:24576
	ds_read_b64_tr_b16 v[216:217], v218 offset:28672
	s_waitcnt lgkmcnt(8)
	v_mfma_f32_32x32x16_bf16 v[32:47], v[238:241], v[242:245], v[32:47]
	ds_read_b64_tr_b16 v[238:239], v219 offset:24576
	ds_read_b64_tr_b16 v[240:241], v219 offset:28672
	s_waitcnt lgkmcnt(8)
	v_mfma_f32_32x32x16_bf16 v[16:31], v[222:225], v[242:245], v[16:31]
	ds_read_b64_tr_b16 v[222:223], v221 offset:24576
	ds_read_b64_tr_b16 v[224:225], v221 offset:28672
	s_waitcnt lgkmcnt(8)
	v_mfma_f32_32x32x16_bf16 v[0:15], v[206:209], v[242:245], v[0:15]
	ds_read_b64_tr_b16 v[206:207], v205 offset:24832
	ds_read_b64_tr_b16 v[208:209], v205 offset:28928
	s_waitcnt lgkmcnt(8)
	v_mfma_f32_32x32x16_bf16 v[112:127], v[210:213], v[250:253], v[112:127]
	ds_read_b64_tr_b16 v[210:211], v218 offset:24832
	ds_read_b64_tr_b16 v[212:213], v218 offset:28928
	s_waitcnt lgkmcnt(8)
	v_mfma_f32_32x32x16_bf16 v[96:111], v[214:217], v[250:253], v[96:111]
	ds_read_b64_tr_b16 v[214:215], v219 offset:24832
	ds_read_b64_tr_b16 v[216:217], v219 offset:28928
	s_waitcnt lgkmcnt(8)
	v_mfma_f32_32x32x16_bf16 v[80:95], v[238:241], v[250:253], v[80:95]
	ds_read_b64_tr_b16 v[238:239], v221 offset:24832
	ds_read_b64_tr_b16 v[240:241], v221 offset:28928
	s_waitcnt lgkmcnt(8)
	v_mfma_f32_32x32x16_bf16 v[64:79], v[222:225], v[250:253], v[64:79]
	s_waitcnt lgkmcnt(6)
	v_mfma_f32_32x32x16_bf16 v[48:63], v[206:209], v[250:253], v[48:63]
	s_waitcnt lgkmcnt(4)
	v_mfma_f32_32x32x16_bf16 v[32:47], v[210:213], v[250:253], v[32:47]
	s_waitcnt lgkmcnt(2)
	v_mfma_f32_32x32x16_bf16 v[16:31], v[214:217], v[250:253], v[16:31]
	s_waitcnt lgkmcnt(0)
	v_mfma_f32_32x32x16_bf16 v[0:15], v[238:241], v[250:253], v[0:15]
	ds_read_b128 v[206:209], v196 offset:32768
	ds_read_b128 v[210:213], v197 offset:32768
	ds_read_b128 v[214:217], v198 offset:32768
	ds_read_b128 v[238:241], v199 offset:32768
	ds_read_b128 v[242:245], v200 offset:32768
	ds_read_b128 v[250:253], v201 offset:32768
	ds_read_b128 v[222:225], v202 offset:32768
	ds_read_b128 v[226:229], v203 offset:32768
	s_waitcnt vmcnt(0)
	s_add_i32 s8, s11, 1
	s_cmp_lg_u32 s11, 2
	s_cselect_b32 s11, s8, 0
	s_add_i32 s14, s14, 64
	s_add_u32 s34, s34, 0x100000
	s_addc_u32 s35, s35, 0
	s_add_i32 s10, s10, 1
	s_add_i32 s100, s14, 63
	s_cmp_le_i32 s100, s80
	s_cbranch_scc0 .Latt_latchb_3
	s_cmp_ge_u32 s10, s78
	s_cselect_b64 s[8:9], -1, 0
	v_mov_b32_e32 v204, v176
	s_barrier
	s_branch .Latt_cont_3s2
.Latt_slow_3s1:
.Latt_slot2_3:
.Latt_cont_3s2:
	v_add_u32_e32 v205, 0x8000, v205
	v_add_u32_e32 v218, 0x8000, v218
	v_add_u32_e32 v219, 0x8000, v219
	v_add_u32_e32 v221, 0x8000, v221
	s_waitcnt lgkmcnt(7)
	v_mfma_f32_32x32x16_bf16 v[128:143], v[206:209], v[144:147], 0
	ds_read_b128 v[206:209], v196 offset:40960
	s_cmp_lg_u64 s[8:9], 0
	s_cbranch_scc1 .Latt_nd0_3s2
	s_sub_i32 s100, s11, 1
	s_cmp_eq_u32 s11, 0
	s_cselect_b32 s100, 2, s100
	s_lshl_b32 s101, s100, 14
	s_add_i32 m0, s40, s101
	s_nop 0
	global_load_lds_dwordx4 v178, s[34:35]

.Latt_nr0_3s2:
	s_waitcnt lgkmcnt(3)
	v_mfma_f32_32x32x16_bf16 v[222:237], v[214:217], v[152:155], v[222:237]
	ds_read_b128 v[214:217], v202 offset:40960
	v_sub_f32_e32 v128, v128, v190
	v_exp_f32_e32 v128, v128
	v_sub_f32_e32 v129, v129, v190
	v_exp_f32_e32 v129, v129
	v_sub_f32_e32 v130, v130, v190
	s_waitcnt lgkmcnt(3)
	v_mfma_f32_32x32x16_bf16 v[222:237], v[238:241], v[156:159], v[222:237]
	ds_read_b128 v[238:241], v203 offset:40960
	v_add_f32_e32 v254, 0, v128
	v_exp_f32_e32 v130, v130
	v_sub_f32_e32 v131, v131, v190
	v_add_f32_e32 v254, v129, v254
	v_exp_f32_e32 v131, v131
	s_waitcnt lgkmcnt(3)
	v_mfma_f32_32x32x16_bf16 v[222:237], v[206:209], v[160:163], v[222:237]
	ds_read_b64_tr_b16 v[206:207], v205
	ds_read_b64_tr_b16 v[208:209], v205 offset:4096
	v_sub_f32_e32 v132, v132, v190
	v_add_f32_e32 v254, v130, v254
	v_exp_f32_e32 v132, v132
	v_sub_f32_e32 v133, v133, v190
	v_add_f32_e32 v254, v131, v254
	s_waitcnt lgkmcnt(4)
	v_mfma_f32_32x32x16_bf16 v[222:237], v[210:213], v[164:167], v[222:237]
	ds_read_b64_tr_b16 v[210:211], v218
	ds_read_b64_tr_b16 v[212:213], v218 offset:4096
	v_exp_f32_e32 v133, v133
	v_sub_f32_e32 v134, v134, v190
	v_add_f32_e32 v254, v132, v254
	v_exp_f32_e32 v134, v134
	s_waitcnt lgkmcnt(5)
	v_mfma_f32_32x32x16_bf16 v[222:237], v[214:217], v[168:171], v[222:237]
	ds_read_b64_tr_b16 v[214:215], v219
	ds_read_b64_tr_b16 v[216:217], v219 offset:4096
	v_sub_f32_e32 v135, v135, v190
	v_add_f32_e32 v254, v133, v254
	v_exp_f32_e32 v135, v135
	s_nop 0
	s_waitcnt lgkmcnt(6)
	v_mfma_f32_32x32x16_bf16 v[222:237], v[238:241], v[172:175], v[222:237]
	ds_read_b64_tr_b16 v[238:239], v221
	ds_read_b64_tr_b16 v[240:241], v221 offset:4096
	v_cvt_pk_bf16_f32 v242, v128, v129
	v_cvt_pk_bf16_f32 v243, v130, v131
	v_cvt_pk_bf16_f32 v244, v132, v133
	v_cvt_pk_bf16_f32 v245, v134, v135
	s_nop 1
	s_waitcnt lgkmcnt(6)
	v_mfma_f32_32x32x16_bf16 v[112:127], v[206:209], v[242:245], v[112:127]
	ds_read_b64_tr_b16 v[206:207], v205 offset:256
	ds_read_b64_tr_b16 v[208:209], v205 offset:4352
	v_sub_f32_e32 v136, v136, v190
	v_add_f32_e32 v254, v134, v254
	v_exp_f32_e32 v136, v136
	v_sub_f32_e32 v137, v137, v190
	v_add_f32_e32 v254, v135, v254
	s_waitcnt lgkmcnt(6)
	v_mfma_f32_32x32x16_bf16 v[96:111], v[210:213], v[242:245], v[96:111]
	ds_read_b64_tr_b16 v[210:211], v218 offset:256
	ds_read_b64_tr_b16 v[212:213], v218 offset:4352
	v_exp_f32_e32 v137, v137
	v_sub_f32_e32 v138, v138, v190
	v_add_f32_e32 v254, v136, v254
	v_exp_f32_e32 v138, v138
	v_sub_f32_e32 v139, v139, v190
	s_waitcnt lgkmcnt(6)
	v_mfma_f32_32x32x16_bf16 v[80:95], v[214:217], v[242:245], v[80:95]
	ds_read_b64_tr_b16 v[214:215], v219 offset:256
	ds_read_b64_tr_b16 v[216:217], v219 offset:4352
	v_add_f32_e32 v254, v137, v254
	v_exp_f32_e32 v139, v139
	v_sub_f32_e32 v140, v140, v190
	v_add_f32_e32 v254, v138, v254
	s_waitcnt lgkmcnt(6)
	v_mfma_f32_32x32x16_bf16 v[64:79], v[238:241], v[242:245], v[64:79]
	ds_read_b64_tr_b16 v[238:239], v221 offset:256
	ds_read_b64_tr_b16 v[240:241], v221 offset:4352
	v_exp_f32_e32 v140, v140
	v_sub_f32_e32 v141, v141, v190
	v_add_f32_e32 v254, v139, v254
	v_exp_f32_e32 v141, v141
	s_waitcnt lgkmcnt(6)
	v_mfma_f32_32x32x16_bf16 v[48:63], v[206:209], v[242:245], v[48:63]
	ds_read_b64_tr_b16 v[206:207], v205 offset:8192
	ds_read_b64_tr_b16 v[208:209], v205 offset:12288
	v_sub_f32_e32 v142, v142, v190
	v_add_f32_e32 v254, v140, v254
	v_exp_f32_e32 v142, v142
	v_sub_f32_e32 v143, v143, v190
	s_waitcnt lgkmcnt(6)
	v_mfma_f32_32x32x16_bf16 v[32:47], v[210:213], v[242:245], v[32:47]
	ds_read_b64_tr_b16 v[210:211], v218 offset:8192
	ds_read_b64_tr_b16 v[212:213], v218 offset:12288
	v_add_f32_e32 v254, v141, v254
	v_exp_f32_e32 v143, v143
	v_add_f32_e32 v254, v142, v254
	v_add_f32_e32 v254, v143, v254
	s_waitcnt lgkmcnt(6)
	v_mfma_f32_32x32x16_bf16 v[16:31], v[214:217], v[242:245], v[16:31]
	ds_read_b64_tr_b16 v[214:215], v219 offset:8192
	ds_read_b64_tr_b16 v[216:217], v219 offset:12288
	v_cvt_pk_bf16_f32 v250, v136, v137
	v_cvt_pk_bf16_f32 v251, v138, v139
	v_cvt_pk_bf16_f32 v252, v140, v141
	v_cvt_pk_bf16_f32 v253, v142, v143
	v_add_f32_e32 v195, v195, v254
	s_waitcnt lgkmcnt(6)
	v_mfma_f32_32x32x16_bf16 v[0:15], v[238:241], v[242:245], v[0:15]
	ds_read_b64_tr_b16 v[238:239], v221 offset:8192
	ds_read_b64_tr_b16 v[240:241], v221 offset:12288
	ds_read_b64_tr_b16 v[128:129], v205 offset:8448
	ds_read_b64_tr_b16 v[130:131], v205 offset:12544
	s_waitcnt lgkmcnt(8)
	v_mfma_f32_32x32x16_bf16 v[112:127], v[206:209], v[250:253], v[112:127]
	ds_read_b64_tr_b16 v[206:207], v218 offset:8448
	ds_read_b64_tr_b16 v[208:209], v218 offset:12544
	v_max3_f32 v246, v222, v223, v224
	v_max3_f32 v247, v225, v226, v227
	v_max3_f32 v246, v246, v228, v229
	v_max3_f32 v247, v247, v230, v231
	v_max3_f32 v246, v246, v232, v233
	s_waitcnt lgkmcnt(8)
	v_mfma_f32_32x32x16_bf16 v[96:111], v[210:213], v[250:253], v[96:111]
	ds_read_b64_tr_b16 v[210:211], v219 offset:8448
	ds_read_b64_tr_b16 v[212:213], v219 offset:12544
	v_max3_f32 v247, v247, v234, v235
	v_max3_f32 v246, v246, v236, v237
	v_max_f32_e32 v246, v246, v247
	v_mov_b32_e32 v247, v246
	v_add_f32_e32 v249, 0x41000000, v190
	s_waitcnt lgkmcnt(8)
	v_mfma_f32_32x32x16_bf16 v[80:95], v[214:217], v[250:253], v[80:95]
	ds_read_b64_tr_b16 v[214:215], v221 offset:8448
	ds_read_b64_tr_b16 v[216:217], v221 offset:12544
	s_nop 1
	v_permlane32_swap_b32_e32 v246, v247
	v_max_f32_e32 v246, v246, v247
	v_cmp_gt_f32_e32 vcc, v246, v249
	s_cbranch_vccnz .Latt_rs1_3s2
	s_waitcnt lgkmcnt(8)
	v_mfma_f32_32x32x16_bf16 v[64:79], v[238:241], v[250:253], v[64:79]
	ds_read_b64_tr_b16 v[238:239], v205 offset:16384
	ds_read_b64_tr_b16 v[240:241], v205 offset:20480
	v_sub_f32_e32 v222, v222, v190
	v_exp_f32_e32 v222, v222
	v_sub_f32_e32 v223, v223, v190
	v_exp_f32_e32 v223, v223
	v_sub_f32_e32 v224, v224, v190
	v_add_f32_e32 v254, 0, v222
	s_waitcnt lgkmcnt(8)
	v_mfma_f32_32x32x16_bf16 v[48:63], v[128:131], v[250:253], v[48:63]
	ds_read_b64_tr_b16 v[128:129], v218 offset:16384
	ds_read_b64_tr_b16 v[130:131], v218 offset:20480
	v_exp_f32_e32 v224, v224
	v_sub_f32_e32 v225, v225, v190
	v_add_f32_e32 v254, v223, v254
	v_exp_f32_e32 v225, v225
	v_sub_f32_e32 v226, v226, v190
	v_add_f32_e32 v254, v224, v254
	s_waitcnt lgkmcnt(8)
	v_mfma_f32_32x32x16_bf16 v[32:47], v[206:209], v[250:253], v[32:47]
	ds_read_b64_tr_b16 v[206:207], v219 offset:16384
	ds_read_b64_tr_b16 v[208:209], v219 offset:20480
	v_exp_f32_e32 v226, v226
	v_sub_f32_e32 v227, v227, v190
	v_add_f32_e32 v254, v225, v254
	v_exp_f32_e32 v227, v227
	v_sub_f32_e32 v228, v228, v190
	s_waitcnt lgkmcnt(8)
	v_mfma_f32_32x32x16_bf16 v[16:31], v[210:213], v[250:253], v[16:31]
	ds_read_b64_tr_b16 v[210:211], v221 offset:16384
	ds_read_b64_tr_b16 v[212:213], v221 offset:20480
	v_add_f32_e32 v254, v226, v254
	v_exp_f32_e32 v228, v228
	v_sub_f32_e32 v229, v229, v190
	v_add_f32_e32 v254, v227, v254
	v_exp_f32_e32 v229, v229
	s_waitcnt lgkmcnt(8)
	v_mfma_f32_32x32x16_bf16 v[0:15], v[214:217], v[250:253], v[0:15]
	ds_read_b64_tr_b16 v[214:215], v205 offset:16640
	ds_read_b64_tr_b16 v[216:217], v205 offset:20736
	s_nop 0
	v_cvt_pk_bf16_f32 v242, v222, v223
	v_cvt_pk_bf16_f32 v243, v224, v225
	v_cvt_pk_bf16_f32 v244, v226, v227
	v_cvt_pk_bf16_f32 v245, v228, v229
	s_nop 1
	s_waitcnt lgkmcnt(8)
	v_mfma_f32_32x32x16_bf16 v[112:127], v[238:241], v[242:245], v[112:127]
	ds_read_b64_tr_b16 v[238:239], v218 offset:16640
	ds_read_b64_tr_b16 v[240:241], v218 offset:20736
	v_sub_f32_e32 v230, v230, v190
	v_add_f32_e32 v254, v228, v254
	v_exp_f32_e32 v230, v230
	v_sub_f32_e32 v231, v231, v190
	v_add_f32_e32 v254, v229, v254
	s_waitcnt lgkmcnt(8)
	v_mfma_f32_32x32x16_bf16 v[96:111], v[128:131], v[242:245], v[96:111]
	ds_read_b64_tr_b16 v[128:129], v219 offset:16640
	ds_read_b64_tr_b16 v[130:131], v219 offset:20736
	v_exp_f32_e32 v231, v231
	v_sub_f32_e32 v232, v232, v190
	v_add_f32_e32 v254, v230, v254
	v_exp_f32_e32 v232, v232
	v_sub_f32_e32 v233, v233, v190
	s_waitcnt lgkmcnt(8)
	v_mfma_f32_32x32x16_bf16 v[80:95], v[206:209], v[242:245], v[80:95]
	ds_read_b64_tr_b16 v[206:207], v221 offset:16640
	ds_read_b64_tr_b16 v[208:209], v221 offset:20736
	v_add_f32_e32 v254, v231, v254
	v_exp_f32_e32 v233, v233
	v_sub_f32_e32 v234, v234, v190
	v_add_f32_e32 v254, v232, v254
	s_waitcnt lgkmcnt(8)
	v_mfma_f32_32x32x16_bf16 v[64:79], v[210:213], v[242:245], v[64:79]
	ds_read_b64_tr_b16 v[210:211], v205 offset:24576
	ds_read_b64_tr_b16 v[212:213], v205 offset:28672
	v_exp_f32_e32 v234, v234
	v_sub_f32_e32 v235, v235, v190
	v_add_f32_e32 v254, v233, v254
	v_exp_f32_e32 v235, v235
	s_waitcnt lgkmcnt(8)
	v_mfma_f32_32x32x16_bf16 v[48:63], v[214:217], v[242:245], v[48:63]
	ds_read_b64_tr_b16 v[214:215], v218 offset:24576
	ds_read_b64_tr_b16 v[216:217], v218 offset:28672
	v_sub_f32_e32 v236, v236, v190
	v_add_f32_e32 v254, v234, v254
	v_exp_f32_e32 v236, v236
	v_sub_f32_e32 v237, v237, v190
	s_waitcnt lgkmcnt(8)
	v_mfma_f32_32x32x16_bf16 v[32:47], v[238:241], v[242:245], v[32:47]
	ds_read_b64_tr_b16 v[238:239], v219 offset:24576
	ds_read_b64_tr_b16 v[240:241], v219 offset:28672
	v_add_f32_e32 v254, v235, v254
	v_exp_f32_e32 v237, v237
	v_add_f32_e32 v254, v236, v254
	v_add_f32_e32 v254, v237, v254
	s_waitcnt lgkmcnt(8)
	v_mfma_f32_32x32x16_bf16 v[16:31], v[128:131], v[242:245], v[16:31]
	ds_read_b64_tr_b16 v[128:129], v221 offset:24576
	ds_read_b64_tr_b16 v[130:131], v221 offset:28672
	v_cvt_pk_bf16_f32 v250, v230, v231
	v_cvt_pk_bf16_f32 v251, v232, v233
	v_cvt_pk_bf16_f32 v252, v234, v235
	v_cvt_pk_bf16_f32 v253, v236, v237
	v_add_f32_e32 v195, v195, v254
	s_waitcnt lgkmcnt(8)
	v_mfma_f32_32x32x16_bf16 v[0:15], v[206:209], v[242:245], v[0:15]
	ds_read_b64_tr_b16 v[206:207], v205 offset:24832
	ds_read_b64_tr_b16 v[208:209], v205 offset:28928
	s_waitcnt lgkmcnt(8)
	v_mfma_f32_32x32x16_bf16 v[112:127], v[210:213], v[250:253], v[112:127]
	ds_read_b64_tr_b16 v[210:211], v218 offset:24832
	ds_read_b64_tr_b16 v[212:213], v218 offset:28928
	s_waitcnt lgkmcnt(8)
	v_mfma_f32_32x32x16_bf16 v[96:111], v[214:217], v[250:253], v[96:111]
	ds_read_b64_tr_b16 v[214:215], v219 offset:24832
	ds_read_b64_tr_b16 v[216:217], v219 offset:28928
	s_waitcnt lgkmcnt(8)
	v_mfma_f32_32x32x16_bf16 v[80:95], v[238:241], v[250:253], v[80:95]
	ds_read_b64_tr_b16 v[238:239], v221 offset:24832
	ds_read_b64_tr_b16 v[240:241], v221 offset:28928
	s_waitcnt lgkmcnt(8)
	v_mfma_f32_32x32x16_bf16 v[64:79], v[128:131], v[250:253], v[64:79]
	s_waitcnt lgkmcnt(6)
	v_mfma_f32_32x32x16_bf16 v[48:63], v[206:209], v[250:253], v[48:63]
	s_waitcnt lgkmcnt(4)
	v_mfma_f32_32x32x16_bf16 v[32:47], v[210:213], v[250:253], v[32:47]
	s_waitcnt lgkmcnt(2)
	v_mfma_f32_32x32x16_bf16 v[16:31], v[214:217], v[250:253], v[16:31]
	s_waitcnt lgkmcnt(0)
	v_mfma_f32_32x32x16_bf16 v[0:15], v[238:241], v[250:253], v[0:15]
	ds_read_b128 v[206:209], v196
	ds_read_b128 v[210:213], v197
	ds_read_b128 v[214:217], v198
	ds_read_b128 v[238:241], v199
	ds_read_b128 v[242:245], v200
	ds_read_b128 v[250:253], v201
	ds_read_b128 v[222:225], v202
	ds_read_b128 v[226:229], v203
	s_waitcnt vmcnt(0)
	s_add_i32 s8, s11, 1
	s_cmp_lg_u32 s11, 2
	s_cselect_b32 s11, s8, 0
	s_add_i32 s14, s14, 64
	s_add_u32 s34, s34, 0x100000
	s_addc_u32 s35, s35, 0
	s_add_i32 s10, s10, 1
	s_add_i32 s100, s14, 63
	s_cmp_le_i32 s100, s80
	s_cbranch_scc0 .Latt_latchb_3
	s_cmp_ge_u32 s10, s78
	s_cselect_b64 s[8:9], -1, 0
	v_mov_b32_e32 v204, v176
	s_barrier
	s_branch .Latt_cont_3s0
.Latt_rs1_3s2:
	s_waitcnt lgkmcnt(8)
	v_mfma_f32_32x32x16_bf16 v[64:79], v[238:241], v[250:253], v[64:79]
	ds_read_b64_tr_b16 v[238:239], v205 offset:16384
	ds_read_b64_tr_b16 v[240:241], v205 offset:20480
	s_waitcnt lgkmcnt(8)
	v_mfma_f32_32x32x16_bf16 v[48:63], v[128:131], v[250:253], v[48:63]
	ds_read_b64_tr_b16 v[128:129], v218 offset:16384
	ds_read_b64_tr_b16 v[130:131], v218 offset:20480
	s_waitcnt lgkmcnt(8)
	v_mfma_f32_32x32x16_bf16 v[32:47], v[206:209], v[250:253], v[32:47]
	ds_read_b64_tr_b16 v[206:207], v219 offset:16384
	ds_read_b64_tr_b16 v[208:209], v219 offset:20480
	s_waitcnt lgkmcnt(8)
	v_mfma_f32_32x32x16_bf16 v[16:31], v[210:213], v[250:253], v[16:31]
	ds_read_b64_tr_b16 v[210:211], v221 offset:16384
	ds_read_b64_tr_b16 v[212:213], v221 offset:20480
	s_waitcnt lgkmcnt(8)
	v_mfma_f32_32x32x16_bf16 v[0:15], v[214:217], v[250:253], v[0:15]
	ds_read_b64_tr_b16 v[214:215], v205 offset:16640
	ds_read_b64_tr_b16 v[216:217], v205 offset:20736
	s_nop 11
	v_max_f32_e32 v246, v190, v246
	v_sub_f32_e32 v190, v190, v246
	v_exp_f32_e32 v190, v190
	s_nop 0
	v_pk_mul_f32 v[126:127], v[126:127], v[190:191] op_sel_hi:[1,0]
	v_pk_mul_f32 v[124:125], v[124:125], v[190:191] op_sel_hi:[1,0]
	v_pk_mul_f32 v[122:123], v[122:123], v[190:191] op_sel_hi:[1,0]
	v_pk_mul_f32 v[120:121], v[120:121], v[190:191] op_sel_hi:[1,0]
	v_pk_mul_f32 v[118:119], v[118:119], v[190:191] op_sel_hi:[1,0]
	v_pk_mul_f32 v[116:117], v[116:117], v[190:191] op_sel_hi:[1,0]
	v_pk_mul_f32 v[114:115], v[114:115], v[190:191] op_sel_hi:[1,0]
	v_pk_mul_f32 v[112:113], v[112:113], v[190:191] op_sel_hi:[1,0]
	v_pk_mul_f32 v[110:111], v[110:111], v[190:191] op_sel_hi:[1,0]
	v_pk_mul_f32 v[108:109], v[108:109], v[190:191] op_sel_hi:[1,0]
	v_pk_mul_f32 v[106:107], v[106:107], v[190:191] op_sel_hi:[1,0]
	v_pk_mul_f32 v[104:105], v[104:105], v[190:191] op_sel_hi:[1,0]
	v_pk_mul_f32 v[102:103], v[102:103], v[190:191] op_sel_hi:[1,0]
	v_pk_mul_f32 v[100:101], v[100:101], v[190:191] op_sel_hi:[1,0]
	v_pk_mul_f32 v[98:99], v[98:99], v[190:191] op_sel_hi:[1,0]
	v_pk_mul_f32 v[96:97], v[96:97], v[190:191] op_sel_hi:[1,0]
	v_pk_mul_f32 v[94:95], v[94:95], v[190:191] op_sel_hi:[1,0]
	v_pk_mul_f32 v[92:93], v[92:93], v[190:191] op_sel_hi:[1,0]
	v_pk_mul_f32 v[90:91], v[90:91], v[190:191] op_sel_hi:[1,0]
	v_pk_mul_f32 v[88:89], v[88:89], v[190:191] op_sel_hi:[1,0]
	v_pk_mul_f32 v[86:87], v[86:87], v[190:191] op_sel_hi:[1,0]
	v_pk_mul_f32 v[84:85], v[84:85], v[190:191] op_sel_hi:[1,0]
	v_pk_mul_f32 v[82:83], v[82:83], v[190:191] op_sel_hi:[1,0]
	v_pk_mul_f32 v[80:81], v[80:81], v[190:191] op_sel_hi:[1,0]
	v_pk_mul_f32 v[78:79], v[78:79], v[190:191] op_sel_hi:[1,0]
	v_pk_mul_f32 v[76:77], v[76:77], v[190:191] op_sel_hi:[1,0]
	v_pk_mul_f32 v[74:75], v[74:75], v[190:191] op_sel_hi:[1,0]
	v_pk_mul_f32 v[72:73], v[72:73], v[190:191] op_sel_hi:[1,0]
	v_pk_mul_f32 v[70:71], v[70:71], v[190:191] op_sel_hi:[1,0]
	v_pk_mul_f32 v[68:69], v[68:69], v[190:191] op_sel_hi:[1,0]
	v_pk_mul_f32 v[66:67], v[66:67], v[190:191] op_sel_hi:[1,0]
	v_pk_mul_f32 v[64:65], v[64:65], v[190:191] op_sel_hi:[1,0]
	v_pk_mul_f32 v[62:63], v[62:63], v[190:191] op_sel_hi:[1,0]
	v_pk_mul_f32 v[60:61], v[60:61], v[190:191] op_sel_hi:[1,0]
	v_pk_mul_f32 v[58:59], v[58:59], v[190:191] op_sel_hi:[1,0]
	v_pk_mul_f32 v[56:57], v[56:57], v[190:191] op_sel_hi:[1,0]
	v_pk_mul_f32 v[54:55], v[54:55], v[190:191] op_sel_hi:[1,0]
	v_pk_mul_f32 v[52:53], v[52:53], v[190:191] op_sel_hi:[1,0]
	v_pk_mul_f32 v[50:51], v[50:51], v[190:191] op_sel_hi:[1,0]
	v_pk_mul_f32 v[48:49], v[48:49], v[190:191] op_sel_hi:[1,0]
	v_pk_mul_f32 v[46:47], v[46:47], v[190:191] op_sel_hi:[1,0]
	v_pk_mul_f32 v[44:45], v[44:45], v[190:191] op_sel_hi:[1,0]
	v_pk_mul_f32 v[42:43], v[42:43], v[190:191] op_sel_hi:[1,0]
	v_pk_mul_f32 v[40:41], v[40:41], v[190:191] op_sel_hi:[1,0]
	v_pk_mul_f32 v[38:39], v[38:39], v[190:191] op_sel_hi:[1,0]
	v_pk_mul_f32 v[36:37], v[36:37], v[190:191] op_sel_hi:[1,0]
	v_pk_mul_f32 v[34:35], v[34:35], v[190:191] op_sel_hi:[1,0]
	v_pk_mul_f32 v[32:33], v[32:33], v[190:191] op_sel_hi:[1,0]
	v_pk_mul_f32 v[30:31], v[30:31], v[190:191] op_sel_hi:[1,0]
	v_pk_mul_f32 v[28:29], v[28:29], v[190:191] op_sel_hi:[1,0]
	v_pk_mul_f32 v[26:27], v[26:27], v[190:191] op_sel_hi:[1,0]
	v_pk_mul_f32 v[24:25], v[24:25], v[190:191] op_sel_hi:[1,0]
	v_pk_mul_f32 v[22:23], v[22:23], v[190:191] op_sel_hi:[1,0]
	v_pk_mul_f32 v[20:21], v[20:21], v[190:191] op_sel_hi:[1,0]
	v_pk_mul_f32 v[18:19], v[18:19], v[190:191] op_sel_hi:[1,0]
	v_pk_mul_f32 v[16:17], v[16:17], v[190:191] op_sel_hi:[1,0]
	v_pk_mul_f32 v[14:15], v[14:15], v[190:191] op_sel_hi:[1,0]
	v_pk_mul_f32 v[12:13], v[12:13], v[190:191] op_sel_hi:[1,0]
	v_pk_mul_f32 v[10:11], v[10:11], v[190:191] op_sel_hi:[1,0]
	v_pk_mul_f32 v[8:9], v[8:9], v[190:191] op_sel_hi:[1,0]
	v_pk_mul_f32 v[6:7], v[6:7], v[190:191] op_sel_hi:[1,0]
	v_pk_mul_f32 v[4:5], v[4:5], v[190:191] op_sel_hi:[1,0]
	v_pk_mul_f32 v[2:3], v[2:3], v[190:191] op_sel_hi:[1,0]
	v_pk_mul_f32 v[0:1], v[0:1], v[190:191] op_sel_hi:[1,0]
	v_mul_f32_e32 v195, v195, v190
	v_mov_b32_e32 v190, v246
	v_sub_f32_e32 v222, v222, v190
	v_exp_f32_e32 v222, v222
	v_sub_f32_e32 v223, v223, v190
	v_exp_f32_e32 v223, v223
	v_sub_f32_e32 v224, v224, v190
	v_add_f32_e32 v254, 0, v222
	v_exp_f32_e32 v224, v224
	v_sub_f32_e32 v225, v225, v190
	v_add_f32_e32 v254, v223, v254
	v_exp_f32_e32 v225, v225
	v_sub_f32_e32 v226, v226, v190
	v_add_f32_e32 v254, v224, v254
	v_exp_f32_e32 v226, v226
	v_sub_f32_e32 v227, v227, v190
	v_add_f32_e32 v254, v225, v254
	v_exp_f32_e32 v227, v227
	v_sub_f32_e32 v228, v228, v190
	v_add_f32_e32 v254, v226, v254
	v_exp_f32_e32 v228, v228
	v_sub_f32_e32 v229, v229, v190
	v_add_f32_e32 v254, v227, v254
	v_exp_f32_e32 v229, v229
	v_sub_f32_e32 v230, v230, v190
	v_add_f32_e32 v254, v228, v254
	v_exp_f32_e32 v230, v230
	v_sub_f32_e32 v231, v231, v190
	v_add_f32_e32 v254, v229, v254
	v_exp_f32_e32 v231, v231
	v_sub_f32_e32 v232, v232, v190
	v_add_f32_e32 v254, v230, v254
	v_exp_f32_e32 v232, v232
	v_sub_f32_e32 v233, v233, v190
	v_add_f32_e32 v254, v231, v254
	v_exp_f32_e32 v233, v233
	v_sub_f32_e32 v234, v234, v190
	v_add_f32_e32 v254, v232, v254
	v_exp_f32_e32 v234, v234
	v_sub_f32_e32 v235, v235, v190
	v_add_f32_e32 v254, v233, v254
	v_exp_f32_e32 v235, v235
	v_sub_f32_e32 v236, v236, v190
	v_add_f32_e32 v254, v234, v254
	v_exp_f32_e32 v236, v236
	v_sub_f32_e32 v237, v237, v190
	v_add_f32_e32 v254, v235, v254
	v_exp_f32_e32 v237, v237
	v_add_f32_e32 v254, v236, v254
	v_add_f32_e32 v254, v237, v254
	v_cvt_pk_bf16_f32 v242, v222, v223
	v_cvt_pk_bf16_f32 v243, v224, v225
	v_cvt_pk_bf16_f32 v244, v226, v227
	v_cvt_pk_bf16_f32 v245, v228, v229
	v_cvt_pk_bf16_f32 v250, v230, v231
	v_cvt_pk_bf16_f32 v251, v232, v233
	v_cvt_pk_bf16_f32 v252, v234, v235
	v_cvt_pk_bf16_f32 v253, v236, v237
	v_add_f32_e32 v195, v195, v254
	s_nop 1
	s_waitcnt lgkmcnt(8)
	v_mfma_f32_32x32x16_bf16 v[112:127], v[238:241], v[242:245], v[112:127]
	ds_read_b64_tr_b16 v[238:239], v218 offset:16640
	ds_read_b64_tr_b16 v[240:241], v218 offset:20736
	s_waitcnt lgkmcnt(8)
	v_mfma_f32_32x32x16_bf16 v[96:111], v[128:131], v[242:245], v[96:111]
	ds_read_b64_tr_b16 v[222:223], v219 offset:16640
	ds_read_b64_tr_b16 v[224:225], v219 offset:20736
	s_waitcnt lgkmcnt(8)
	v_mfma_f32_32x32x16_bf16 v[80:95], v[206:209], v[242:245], v[80:95]
	ds_read_b64_tr_b16 v[206:207], v221 offset:16640
	ds_read_b64_tr_b16 v[208:209], v221 offset:20736
	s_waitcnt lgkmcnt(8)
	v_mfma_f32_32x32x16_bf16 v[64:79], v[210:213], v[242:245], v[64:79]
	ds_read_b64_tr_b16 v[210:211], v205 offset:24576
	ds_read_b64_tr_b16 v[212:213], v205 offset:28672
	s_waitcnt lgkmcnt(8)
	v_mfma_f32_32x32x16_bf16 v[48:63], v[214:217], v[242:245], v[48:63]
	ds_read_b64_tr_b16 v[214:215], v218 offset:24576
	ds_read_b64_tr_b16 v[216:217], v218 offset:28672
	s_waitcnt lgkmcnt(8)
	v_mfma_f32_32x32x16_bf16 v[32:47], v[238:241], v[242:245], v[32:47]
	ds_read_b64_tr_b16 v[238:239], v219 offset:24576
	ds_read_b64_tr_b16 v[240:241], v219 offset:28672
	s_waitcnt lgkmcnt(8)
	v_mfma_f32_32x32x16_bf16 v[16:31], v[222:225], v[242:245], v[16:31]
	ds_read_b64_tr_b16 v[222:223], v221 offset:24576
	ds_read_b64_tr_b16 v[224:225], v221 offset:28672
	s_waitcnt lgkmcnt(8)
	v_mfma_f32_32x32x16_bf16 v[0:15], v[206:209], v[242:245], v[0:15]
	ds_read_b64_tr_b16 v[206:207], v205 offset:24832
	ds_read_b64_tr_b16 v[208:209], v205 offset:28928
	s_waitcnt lgkmcnt(8)
	v_mfma_f32_32x32x16_bf16 v[112:127], v[210:213], v[250:253], v[112:127]
	ds_read_b64_tr_b16 v[210:211], v218 offset:24832
	ds_read_b64_tr_b16 v[212:213], v218 offset:28928
	s_waitcnt lgkmcnt(8)
	v_mfma_f32_32x32x16_bf16 v[96:111], v[214:217], v[250:253], v[96:111]
	ds_read_b64_tr_b16 v[214:215], v219 offset:24832
	ds_read_b64_tr_b16 v[216:217], v219 offset:28928
	s_waitcnt lgkmcnt(8)
	v_mfma_f32_32x32x16_bf16 v[80:95], v[238:241], v[250:253], v[80:95]
	ds_read_b64_tr_b16 v[238:239], v221 offset:24832
	ds_read_b64_tr_b16 v[240:241], v221 offset:28928
	s_waitcnt lgkmcnt(8)
	v_mfma_f32_32x32x16_bf16 v[64:79], v[222:225], v[250:253], v[64:79]
	s_waitcnt lgkmcnt(6)
	v_mfma_f32_32x32x16_bf16 v[48:63], v[206:209], v[250:253], v[48:63]
	s_waitcnt lgkmcnt(4)
	v_mfma_f32_32x32x16_bf16 v[32:47], v[210:213], v[250:253], v[32:47]
	s_waitcnt lgkmcnt(2)
	v_mfma_f32_32x32x16_bf16 v[16:31], v[214:217], v[250:253], v[16:31]
	s_waitcnt lgkmcnt(0)
	v_mfma_f32_32x32x16_bf16 v[0:15], v[238:241], v[250:253], v[0:15]
	ds_read_b128 v[206:209], v196
	ds_read_b128 v[210:213], v197
	ds_read_b128 v[214:217], v198
	ds_read_b128 v[238:241], v199
	ds_read_b128 v[242:245], v200
	ds_read_b128 v[250:253], v201
	ds_read_b128 v[222:225], v202
	ds_read_b128 v[226:229], v203
	s_waitcnt vmcnt(0)
	s_add_i32 s8, s11, 1
	s_cmp_lg_u32 s11, 2
	s_cselect_b32 s11, s8, 0
	s_add_i32 s14, s14, 64
	s_add_u32 s34, s34, 0x100000
	s_addc_u32 s35, s35, 0
	s_add_i32 s10, s10, 1
	s_add_i32 s100, s14, 63
	s_cmp_le_i32 s100, s80
	s_cbranch_scc0 .Latt_latchb_3
	s_cmp_ge_u32 s10, s78
	s_cselect_b64 s[8:9], -1, 0
	v_mov_b32_e32 v204, v176
	s_barrier
	s_branch .Latt_cont_3s0

.Latt_latchb_4:
	s_waitcnt lgkmcnt(0)
	s_cmp_eq_u32 s75, s39
	s_barrier
	s_cbranch_scc1 .LBB0_1816

.Latt_nr0_4s0:
	s_waitcnt lgkmcnt(3)
	v_mfma_f32_32x32x16_bf16 v[222:237], v[214:217], v[152:155], v[222:237]
	ds_read_b128 v[214:217], v200 offset:8192
	v_sub_f32_e32 v128, v128, v190
	v_exp_f32_e32 v128, v128
	v_sub_f32_e32 v129, v129, v190
	v_exp_f32_e32 v129, v129
	v_sub_f32_e32 v130, v130, v190
	s_waitcnt lgkmcnt(3)
	v_mfma_f32_32x32x16_bf16 v[222:237], v[238:241], v[156:159], v[222:237]
	ds_read_b128 v[238:241], v201 offset:8192
	v_add_f32_e32 v254, 0, v128
	v_exp_f32_e32 v130, v130
	v_sub_f32_e32 v131, v131, v190
	v_add_f32_e32 v254, v129, v254
	v_exp_f32_e32 v131, v131
	s_waitcnt lgkmcnt(3)
	v_mfma_f32_32x32x16_bf16 v[222:237], v[206:209], v[160:163], v[222:237]
	ds_read_b64_tr_b16 v[206:207], v205
	ds_read_b64_tr_b16 v[208:209], v205 offset:4096
	v_sub_f32_e32 v132, v132, v190
	v_add_f32_e32 v254, v130, v254
	v_exp_f32_e32 v132, v132
	v_sub_f32_e32 v133, v133, v190
	v_add_f32_e32 v254, v131, v254
	s_waitcnt lgkmcnt(4)
	v_mfma_f32_32x32x16_bf16 v[222:237], v[210:213], v[164:167], v[222:237]
	ds_read_b64_tr_b16 v[210:211], v218
	ds_read_b64_tr_b16 v[212:213], v218 offset:4096
	v_exp_f32_e32 v133, v133
	v_sub_f32_e32 v134, v134, v190
	v_add_f32_e32 v254, v132, v254
	v_exp_f32_e32 v134, v134
	s_waitcnt lgkmcnt(5)
	v_mfma_f32_32x32x16_bf16 v[222:237], v[214:217], v[168:171], v[222:237]
	ds_read_b64_tr_b16 v[214:215], v219
	ds_read_b64_tr_b16 v[216:217], v219 offset:4096
	v_sub_f32_e32 v135, v135, v190
	v_add_f32_e32 v254, v133, v254
	v_exp_f32_e32 v135, v135
	s_nop 0
	s_waitcnt lgkmcnt(6)
	v_mfma_f32_32x32x16_bf16 v[222:237], v[238:241], v[172:175], v[222:237]
	ds_read_b64_tr_b16 v[238:239], v221
	ds_read_b64_tr_b16 v[240:241], v221 offset:4096
	v_cvt_pk_bf16_f32 v242, v128, v129
	v_cvt_pk_bf16_f32 v243, v130, v131
	v_cvt_pk_bf16_f32 v244, v132, v133
	v_cvt_pk_bf16_f32 v245, v134, v135
	s_nop 1
	s_waitcnt lgkmcnt(6)
	v_mfma_f32_32x32x16_bf16 v[112:127], v[206:209], v[242:245], v[112:127]
	ds_read_b64_tr_b16 v[206:207], v205 offset:256
	ds_read_b64_tr_b16 v[208:209], v205 offset:4352
	v_sub_f32_e32 v136, v136, v190
	v_add_f32_e32 v254, v134, v254
	v_exp_f32_e32 v136, v136
	v_sub_f32_e32 v137, v137, v190
	v_add_f32_e32 v254, v135, v254
	s_waitcnt lgkmcnt(6)
	v_mfma_f32_32x32x16_bf16 v[96:111], v[210:213], v[242:245], v[96:111]
	ds_read_b64_tr_b16 v[210:211], v218 offset:256
	ds_read_b64_tr_b16 v[212:213], v218 offset:4352
	v_exp_f32_e32 v137, v137
	v_sub_f32_e32 v138, v138, v190
	v_add_f32_e32 v254, v136, v254
	v_exp_f32_e32 v138, v138
	v_sub_f32_e32 v139, v139, v190
	s_waitcnt lgkmcnt(6)
	v_mfma_f32_32x32x16_bf16 v[80:95], v[214:217], v[242:245], v[80:95]
	ds_read_b64_tr_b16 v[214:215], v219 offset:256
	ds_read_b64_tr_b16 v[216:217], v219 offset:4352
	v_add_f32_e32 v254, v137, v254
	v_exp_f32_e32 v139, v139
	v_sub_f32_e32 v140, v140, v190
	v_add_f32_e32 v254, v138, v254
	s_waitcnt lgkmcnt(6)
	v_mfma_f32_32x32x16_bf16 v[64:79], v[238:241], v[242:245], v[64:79]
	ds_read_b64_tr_b16 v[238:239], v221 offset:256
	ds_read_b64_tr_b16 v[240:241], v221 offset:4352
	v_exp_f32_e32 v140, v140
	v_sub_f32_e32 v141, v141, v190
	v_add_f32_e32 v254, v139, v254
	v_exp_f32_e32 v141, v141
	s_waitcnt lgkmcnt(6)
	v_mfma_f32_32x32x16_bf16 v[48:63], v[206:209], v[242:245], v[48:63]
	ds_read_b64_tr_b16 v[206:207], v205 offset:8192
	ds_read_b64_tr_b16 v[208:209], v205 offset:12288
	v_sub_f32_e32 v142, v142, v190
	v_add_f32_e32 v254, v140, v254
	v_exp_f32_e32 v142, v142
	v_sub_f32_e32 v143, v143, v190
	s_waitcnt lgkmcnt(6)
	v_mfma_f32_32x32x16_bf16 v[32:47], v[210:213], v[242:245], v[32:47]
	ds_read_b64_tr_b16 v[210:211], v218 offset:8192
	ds_read_b64_tr_b16 v[212:213], v218 offset:12288
	v_add_f32_e32 v254, v141, v254
	v_exp_f32_e32 v143, v143
	v_add_f32_e32 v254, v142, v254
	v_add_f32_e32 v254, v143, v254
	s_waitcnt lgkmcnt(6)
	v_mfma_f32_32x32x16_bf16 v[16:31], v[214:217], v[242:245], v[16:31]
	ds_read_b64_tr_b16 v[214:215], v219 offset:8192
	ds_read_b64_tr_b16 v[216:217], v219 offset:12288
	v_cvt_pk_bf16_f32 v250, v136, v137
	v_cvt_pk_bf16_f32 v251, v138, v139
	v_cvt_pk_bf16_f32 v252, v140, v141
	v_cvt_pk_bf16_f32 v253, v142, v143
	v_add_f32_e32 v202, v202, v254
	s_waitcnt lgkmcnt(6)
	v_mfma_f32_32x32x16_bf16 v[0:15], v[238:241], v[242:245], v[0:15]
	ds_read_b64_tr_b16 v[238:239], v221 offset:8192
	ds_read_b64_tr_b16 v[240:241], v221 offset:12288
	ds_read_b64_tr_b16 v[128:129], v205 offset:8448
	ds_read_b64_tr_b16 v[130:131], v205 offset:12544
	s_waitcnt lgkmcnt(8)
	v_mfma_f32_32x32x16_bf16 v[112:127], v[206:209], v[250:253], v[112:127]
	ds_read_b64_tr_b16 v[206:207], v218 offset:8448
	ds_read_b64_tr_b16 v[208:209], v218 offset:12544
	v_max3_f32 v246, v222, v223, v224
	v_max3_f32 v247, v225, v226, v227
	v_max3_f32 v246, v246, v228, v229
	v_max3_f32 v247, v247, v230, v231
	v_max3_f32 v246, v246, v232, v233
	s_waitcnt lgkmcnt(8)
	v_mfma_f32_32x32x16_bf16 v[96:111], v[210:213], v[250:253], v[96:111]
	ds_read_b64_tr_b16 v[210:211], v219 offset:8448
	ds_read_b64_tr_b16 v[212:213], v219 offset:12544
	v_max3_f32 v247, v247, v234, v235
	v_max3_f32 v246, v246, v236, v237
	v_max_f32_e32 v246, v246, v247
	v_mov_b32_e32 v247, v246
	v_add_f32_e32 v249, 0x41000000, v190
	s_waitcnt lgkmcnt(8)
	v_mfma_f32_32x32x16_bf16 v[80:95], v[214:217], v[250:253], v[80:95]
	ds_read_b64_tr_b16 v[214:215], v221 offset:8448
	ds_read_b64_tr_b16 v[216:217], v221 offset:12544
	s_nop 1
	v_permlane32_swap_b32_e32 v246, v247
	v_max_f32_e32 v246, v246, v247
	v_cmp_gt_f32_e32 vcc, v246, v249
	s_cbranch_vccnz .Latt_rs1_4s0
	s_waitcnt lgkmcnt(8)
	v_mfma_f32_32x32x16_bf16 v[64:79], v[238:241], v[250:253], v[64:79]
	ds_read_b64_tr_b16 v[238:239], v205 offset:16384
	ds_read_b64_tr_b16 v[240:241], v205 offset:20480
	v_sub_f32_e32 v222, v222, v190
	v_exp_f32_e32 v222, v222
	v_sub_f32_e32 v223, v223, v190
	v_exp_f32_e32 v223, v223
	v_sub_f32_e32 v224, v224, v190
	v_add_f32_e32 v254, 0, v222
	s_waitcnt lgkmcnt(8)
	v_mfma_f32_32x32x16_bf16 v[48:63], v[128:131], v[250:253], v[48:63]
	ds_read_b64_tr_b16 v[128:129], v218 offset:16384
	ds_read_b64_tr_b16 v[130:131], v218 offset:20480
	v_exp_f32_e32 v224, v224
	v_sub_f32_e32 v225, v225, v190
	v_add_f32_e32 v254, v223, v254
	v_exp_f32_e32 v225, v225
	v_sub_f32_e32 v226, v226, v190
	v_add_f32_e32 v254, v224, v254
	s_waitcnt lgkmcnt(8)
	v_mfma_f32_32x32x16_bf16 v[32:47], v[206:209], v[250:253], v[32:47]
	ds_read_b64_tr_b16 v[206:207], v219 offset:16384
	ds_read_b64_tr_b16 v[208:209], v219 offset:20480
	v_exp_f32_e32 v226, v226
	v_sub_f32_e32 v227, v227, v190
	v_add_f32_e32 v254, v225, v254
	v_exp_f32_e32 v227, v227
	v_sub_f32_e32 v228, v228, v190
	s_waitcnt lgkmcnt(8)
	v_mfma_f32_32x32x16_bf16 v[16:31], v[210:213], v[250:253], v[16:31]
	ds_read_b64_tr_b16 v[210:211], v221 offset:16384
	ds_read_b64_tr_b16 v[212:213], v221 offset:20480
	v_add_f32_e32 v254, v226, v254
	v_exp_f32_e32 v228, v228
	v_sub_f32_e32 v229, v229, v190
	v_add_f32_e32 v254, v227, v254
	v_exp_f32_e32 v229, v229
	s_waitcnt lgkmcnt(8)
	v_mfma_f32_32x32x16_bf16 v[0:15], v[214:217], v[250:253], v[0:15]
	ds_read_b64_tr_b16 v[214:215], v205 offset:16640
	ds_read_b64_tr_b16 v[216:217], v205 offset:20736
	s_nop 0
	v_cvt_pk_bf16_f32 v242, v222, v223
	v_cvt_pk_bf16_f32 v243, v224, v225
	v_cvt_pk_bf16_f32 v244, v226, v227
	v_cvt_pk_bf16_f32 v245, v228, v229
	s_nop 1
	s_waitcnt lgkmcnt(8)
	v_mfma_f32_32x32x16_bf16 v[112:127], v[238:241], v[242:245], v[112:127]
	ds_read_b64_tr_b16 v[238:239], v218 offset:16640
	ds_read_b64_tr_b16 v[240:241], v218 offset:20736
	v_sub_f32_e32 v230, v230, v190
	v_add_f32_e32 v254, v228, v254
	v_exp_f32_e32 v230, v230
	v_sub_f32_e32 v231, v231, v190
	v_add_f32_e32 v254, v229, v254
	s_waitcnt lgkmcnt(8)
	v_mfma_f32_32x32x16_bf16 v[96:111], v[128:131], v[242:245], v[96:111]
	ds_read_b64_tr_b16 v[128:129], v219 offset:16640
	ds_read_b64_tr_b16 v[130:131], v219 offset:20736
	v_exp_f32_e32 v231, v231
	v_sub_f32_e32 v232, v232, v190
	v_add_f32_e32 v254, v230, v254
	v_exp_f32_e32 v232, v232
	v_sub_f32_e32 v233, v233, v190
	s_waitcnt lgkmcnt(8)
	v_mfma_f32_32x32x16_bf16 v[80:95], v[206:209], v[242:245], v[80:95]
	ds_read_b64_tr_b16 v[206:207], v221 offset:16640
	ds_read_b64_tr_b16 v[208:209], v221 offset:20736
	v_add_f32_e32 v254, v231, v254
	v_exp_f32_e32 v233, v233
	v_sub_f32_e32 v234, v234, v190
	v_add_f32_e32 v254, v232, v254
	s_waitcnt lgkmcnt(8)
	v_mfma_f32_32x32x16_bf16 v[64:79], v[210:213], v[242:245], v[64:79]
	ds_read_b64_tr_b16 v[210:211], v205 offset:24576
	ds_read_b64_tr_b16 v[212:213], v205 offset:28672
	v_exp_f32_e32 v234, v234
	v_sub_f32_e32 v235, v235, v190
	v_add_f32_e32 v254, v233, v254
	v_exp_f32_e32 v235, v235
	s_waitcnt lgkmcnt(8)
	v_mfma_f32_32x32x16_bf16 v[48:63], v[214:217], v[242:245], v[48:63]
	ds_read_b64_tr_b16 v[214:215], v218 offset:24576
	ds_read_b64_tr_b16 v[216:217], v218 offset:28672
	v_sub_f32_e32 v236, v236, v190
	v_add_f32_e32 v254, v234, v254
	v_exp_f32_e32 v236, v236
	v_sub_f32_e32 v237, v237, v190
	s_waitcnt lgkmcnt(8)
	v_mfma_f32_32x32x16_bf16 v[32:47], v[238:241], v[242:245], v[32:47]
	ds_read_b64_tr_b16 v[238:239], v219 offset:24576
	ds_read_b64_tr_b16 v[240:241], v219 offset:28672
	v_add_f32_e32 v254, v235, v254
	v_exp_f32_e32 v237, v237
	v_add_f32_e32 v254, v236, v254
	v_add_f32_e32 v254, v237, v254
	s_waitcnt lgkmcnt(8)
	v_mfma_f32_32x32x16_bf16 v[16:31], v[128:131], v[242:245], v[16:31]
	ds_read_b64_tr_b16 v[128:129], v221 offset:24576
	ds_read_b64_tr_b16 v[130:131], v221 offset:28672
	v_cvt_pk_bf16_f32 v250, v230, v231
	v_cvt_pk_bf16_f32 v251, v232, v233
	v_cvt_pk_bf16_f32 v252, v234, v235
	v_cvt_pk_bf16_f32 v253, v236, v237
	v_add_f32_e32 v202, v202, v254
	s_waitcnt lgkmcnt(8)
	v_mfma_f32_32x32x16_bf16 v[0:15], v[206:209], v[242:245], v[0:15]
	ds_read_b64_tr_b16 v[206:207], v205 offset:24832
	ds_read_b64_tr_b16 v[208:209], v205 offset:28928
	s_waitcnt lgkmcnt(8)
	v_mfma_f32_32x32x16_bf16 v[112:127], v[210:213], v[250:253], v[112:127]
	ds_read_b64_tr_b16 v[210:211], v218 offset:24832
	ds_read_b64_tr_b16 v[212:213], v218 offset:28928
	s_waitcnt lgkmcnt(8)
	v_mfma_f32_32x32x16_bf16 v[96:111], v[214:217], v[250:253], v[96:111]
	ds_read_b64_tr_b16 v[214:215], v219 offset:24832
	ds_read_b64_tr_b16 v[216:217], v219 offset:28928
	s_waitcnt lgkmcnt(8)
	v_mfma_f32_32x32x16_bf16 v[80:95], v[238:241], v[250:253], v[80:95]
	ds_read_b64_tr_b16 v[238:239], v221 offset:24832
	ds_read_b64_tr_b16 v[240:241], v221 offset:28928
	s_waitcnt lgkmcnt(8)
	v_mfma_f32_32x32x16_bf16 v[64:79], v[128:131], v[250:253], v[64:79]
	s_waitcnt lgkmcnt(6)
	v_mfma_f32_32x32x16_bf16 v[48:63], v[206:209], v[250:253], v[48:63]
	s_waitcnt lgkmcnt(4)
	v_mfma_f32_32x32x16_bf16 v[32:47], v[210:213], v[250:253], v[32:47]
	s_waitcnt lgkmcnt(2)
	v_mfma_f32_32x32x16_bf16 v[16:31], v[214:217], v[250:253], v[16:31]
	s_waitcnt lgkmcnt(0)
	v_mfma_f32_32x32x16_bf16 v[0:15], v[238:241], v[250:253], v[0:15]
	ds_read_b128 v[206:209], v194 offset:16384
	ds_read_b128 v[210:213], v195 offset:16384
	ds_read_b128 v[214:217], v196 offset:16384
	ds_read_b128 v[238:241], v197 offset:16384
	ds_read_b128 v[242:245], v198 offset:16384
	ds_read_b128 v[250:253], v199 offset:16384
	ds_read_b128 v[222:225], v200 offset:16384
	ds_read_b128 v[226:229], v201 offset:16384
	s_waitcnt vmcnt(0)
	s_add_i32 s18, s76, 1
	s_cmp_lg_u32 s76, 2
	s_cselect_b32 s76, s18, 0
	s_add_i32 s39, s39, 64
	s_add_u32 s14, s14, 0x100000
	s_addc_u32 s15, s15, 0
	s_add_i32 s38, s38, 1
	s_add_i32 s100, s39, 63
	s_cmp_le_i32 s100, s71
	s_cbranch_scc0 .Latt_latchb_4
	s_cmp_ge_u32 s38, s70
	s_cselect_b64 s[18:19], -1, 0
	v_mov_b32_e32 v203, v176
	s_barrier
	s_branch .Latt_cont_4s1
.Latt_rs1_4s0:
	s_waitcnt lgkmcnt(8)
	v_mfma_f32_32x32x16_bf16 v[64:79], v[238:241], v[250:253], v[64:79]
	ds_read_b64_tr_b16 v[238:239], v205 offset:16384
	ds_read_b64_tr_b16 v[240:241], v205 offset:20480
	s_waitcnt lgkmcnt(8)
	v_mfma_f32_32x32x16_bf16 v[48:63], v[128:131], v[250:253], v[48:63]
	ds_read_b64_tr_b16 v[128:129], v218 offset:16384
	ds_read_b64_tr_b16 v[130:131], v218 offset:20480
	s_waitcnt lgkmcnt(8)
	v_mfma_f32_32x32x16_bf16 v[32:47], v[206:209], v[250:253], v[32:47]
	ds_read_b64_tr_b16 v[206:207], v219 offset:16384
	ds_read_b64_tr_b16 v[208:209], v219 offset:20480
	s_waitcnt lgkmcnt(8)
	v_mfma_f32_32x32x16_bf16 v[16:31], v[210:213], v[250:253], v[16:31]
	ds_read_b64_tr_b16 v[210:211], v221 offset:16384
	ds_read_b64_tr_b16 v[212:213], v221 offset:20480
	s_waitcnt lgkmcnt(8)
	v_mfma_f32_32x32x16_bf16 v[0:15], v[214:217], v[250:253], v[0:15]
	ds_read_b64_tr_b16 v[214:215], v205 offset:16640
	ds_read_b64_tr_b16 v[216:217], v205 offset:20736
	s_nop 11
	v_max_f32_e32 v246, v190, v246
	v_sub_f32_e32 v190, v190, v246
	v_exp_f32_e32 v190, v190
	s_nop 0
	v_pk_mul_f32 v[126:127], v[126:127], v[190:191] op_sel_hi:[1,0]
	v_pk_mul_f32 v[124:125], v[124:125], v[190:191] op_sel_hi:[1,0]
	v_pk_mul_f32 v[122:123], v[122:123], v[190:191] op_sel_hi:[1,0]
	v_pk_mul_f32 v[120:121], v[120:121], v[190:191] op_sel_hi:[1,0]
	v_pk_mul_f32 v[118:119], v[118:119], v[190:191] op_sel_hi:[1,0]
	v_pk_mul_f32 v[116:117], v[116:117], v[190:191] op_sel_hi:[1,0]
	v_pk_mul_f32 v[114:115], v[114:115], v[190:191] op_sel_hi:[1,0]
	v_pk_mul_f32 v[112:113], v[112:113], v[190:191] op_sel_hi:[1,0]
	v_pk_mul_f32 v[110:111], v[110:111], v[190:191] op_sel_hi:[1,0]
	v_pk_mul_f32 v[108:109], v[108:109], v[190:191] op_sel_hi:[1,0]
	v_pk_mul_f32 v[106:107], v[106:107], v[190:191] op_sel_hi:[1,0]
	v_pk_mul_f32 v[104:105], v[104:105], v[190:191] op_sel_hi:[1,0]
	v_pk_mul_f32 v[102:103], v[102:103], v[190:191] op_sel_hi:[1,0]
	v_pk_mul_f32 v[100:101], v[100:101], v[190:191] op_sel_hi:[1,0]
	v_pk_mul_f32 v[98:99], v[98:99], v[190:191] op_sel_hi:[1,0]
	v_pk_mul_f32 v[96:97], v[96:97], v[190:191] op_sel_hi:[1,0]
	v_pk_mul_f32 v[94:95], v[94:95], v[190:191] op_sel_hi:[1,0]
	v_pk_mul_f32 v[92:93], v[92:93], v[190:191] op_sel_hi:[1,0]
	v_pk_mul_f32 v[90:91], v[90:91], v[190:191] op_sel_hi:[1,0]
	v_pk_mul_f32 v[88:89], v[88:89], v[190:191] op_sel_hi:[1,0]
	v_pk_mul_f32 v[86:87], v[86:87], v[190:191] op_sel_hi:[1,0]
	v_pk_mul_f32 v[84:85], v[84:85], v[190:191] op_sel_hi:[1,0]
	v_pk_mul_f32 v[82:83], v[82:83], v[190:191] op_sel_hi:[1,0]
	v_pk_mul_f32 v[80:81], v[80:81], v[190:191] op_sel_hi:[1,0]
	v_pk_mul_f32 v[78:79], v[78:79], v[190:191] op_sel_hi:[1,0]
	v_pk_mul_f32 v[76:77], v[76:77], v[190:191] op_sel_hi:[1,0]
	v_pk_mul_f32 v[74:75], v[74:75], v[190:191] op_sel_hi:[1,0]
	v_pk_mul_f32 v[72:73], v[72:73], v[190:191] op_sel_hi:[1,0]
	v_pk_mul_f32 v[70:71], v[70:71], v[190:191] op_sel_hi:[1,0]
	v_pk_mul_f32 v[68:69], v[68:69], v[190:191] op_sel_hi:[1,0]
	v_pk_mul_f32 v[66:67], v[66:67], v[190:191] op_sel_hi:[1,0]
	v_pk_mul_f32 v[64:65], v[64:65], v[190:191] op_sel_hi:[1,0]
	v_pk_mul_f32 v[62:63], v[62:63], v[190:191] op_sel_hi:[1,0]
	v_pk_mul_f32 v[60:61], v[60:61], v[190:191] op_sel_hi:[1,0]
	v_pk_mul_f32 v[58:59], v[58:59], v[190:191] op_sel_hi:[1,0]
	v_pk_mul_f32 v[56:57], v[56:57], v[190:191] op_sel_hi:[1,0]
	v_pk_mul_f32 v[54:55], v[54:55], v[190:191] op_sel_hi:[1,0]
	v_pk_mul_f32 v[52:53], v[52:53], v[190:191] op_sel_hi:[1,0]
	v_pk_mul_f32 v[50:51], v[50:51], v[190:191] op_sel_hi:[1,0]
	v_pk_mul_f32 v[48:49], v[48:49], v[190:191] op_sel_hi:[1,0]
	v_pk_mul_f32 v[46:47], v[46:47], v[190:191] op_sel_hi:[1,0]
	v_pk_mul_f32 v[44:45], v[44:45], v[190:191] op_sel_hi:[1,0]
	v_pk_mul_f32 v[42:43], v[42:43], v[190:191] op_sel_hi:[1,0]
	v_pk_mul_f32 v[40:41], v[40:41], v[190:191] op_sel_hi:[1,0]
	v_pk_mul_f32 v[38:39], v[38:39], v[190:191] op_sel_hi:[1,0]
	v_pk_mul_f32 v[36:37], v[36:37], v[190:191] op_sel_hi:[1,0]
	v_pk_mul_f32 v[34:35], v[34:35], v[190:191] op_sel_hi:[1,0]
	v_pk_mul_f32 v[32:33], v[32:33], v[190:191] op_sel_hi:[1,0]
	v_pk_mul_f32 v[30:31], v[30:31], v[190:191] op_sel_hi:[1,0]
	v_pk_mul_f32 v[28:29], v[28:29], v[190:191] op_sel_hi:[1,0]
	v_pk_mul_f32 v[26:27], v[26:27], v[190:191] op_sel_hi:[1,0]
	v_pk_mul_f32 v[24:25], v[24:25], v[190:191] op_sel_hi:[1,0]
	v_pk_mul_f32 v[22:23], v[22:23], v[190:191] op_sel_hi:[1,0]
	v_pk_mul_f32 v[20:21], v[20:21], v[190:191] op_sel_hi:[1,0]
	v_pk_mul_f32 v[18:19], v[18:19], v[190:191] op_sel_hi:[1,0]
	v_pk_mul_f32 v[16:17], v[16:17], v[190:191] op_sel_hi:[1,0]
	v_pk_mul_f32 v[14:15], v[14:15], v[190:191] op_sel_hi:[1,0]
	v_pk_mul_f32 v[12:13], v[12:13], v[190:191] op_sel_hi:[1,0]
	v_pk_mul_f32 v[10:11], v[10:11], v[190:191] op_sel_hi:[1,0]
	v_pk_mul_f32 v[8:9], v[8:9], v[190:191] op_sel_hi:[1,0]
	v_pk_mul_f32 v[6:7], v[6:7], v[190:191] op_sel_hi:[1,0]
	v_pk_mul_f32 v[4:5], v[4:5], v[190:191] op_sel_hi:[1,0]
	v_pk_mul_f32 v[2:3], v[2:3], v[190:191] op_sel_hi:[1,0]
	v_pk_mul_f32 v[0:1], v[0:1], v[190:191] op_sel_hi:[1,0]
	v_mul_f32_e32 v202, v202, v190
	v_mov_b32_e32 v190, v246
	v_sub_f32_e32 v222, v222, v190
	v_exp_f32_e32 v222, v222
	v_sub_f32_e32 v223, v223, v190
	v_exp_f32_e32 v223, v223
	v_sub_f32_e32 v224, v224, v190
	v_add_f32_e32 v254, 0, v222
	v_exp_f32_e32 v224, v224
	v_sub_f32_e32 v225, v225, v190
	v_add_f32_e32 v254, v223, v254
	v_exp_f32_e32 v225, v225
	v_sub_f32_e32 v226, v226, v190
	v_add_f32_e32 v254, v224, v254
	v_exp_f32_e32 v226, v226
	v_sub_f32_e32 v227, v227, v190
	v_add_f32_e32 v254, v225, v254
	v_exp_f32_e32 v227, v227
	v_sub_f32_e32 v228, v228, v190
	v_add_f32_e32 v254, v226, v254
	v_exp_f32_e32 v228, v228
	v_sub_f32_e32 v229, v229, v190
	v_add_f32_e32 v254, v227, v254
	v_exp_f32_e32 v229, v229
	v_sub_f32_e32 v230, v230, v190
	v_add_f32_e32 v254, v228, v254
	v_exp_f32_e32 v230, v230
	v_sub_f32_e32 v231, v231, v190
	v_add_f32_e32 v254, v229, v254
	v_exp_f32_e32 v231, v231
	v_sub_f32_e32 v232, v232, v190
	v_add_f32_e32 v254, v230, v254
	v_exp_f32_e32 v232, v232
	v_sub_f32_e32 v233, v233, v190
	v_add_f32_e32 v254, v231, v254
	v_exp_f32_e32 v233, v233
	v_sub_f32_e32 v234, v234, v190
	v_add_f32_e32 v254, v232, v254
	v_exp_f32_e32 v234, v234
	v_sub_f32_e32 v235, v235, v190
	v_add_f32_e32 v254, v233, v254
	v_exp_f32_e32 v235, v235
	v_sub_f32_e32 v236, v236, v190
	v_add_f32_e32 v254, v234, v254
	v_exp_f32_e32 v236, v236
	v_sub_f32_e32 v237, v237, v190
	v_add_f32_e32 v254, v235, v254
	v_exp_f32_e32 v237, v237
	v_add_f32_e32 v254, v236, v254
	v_add_f32_e32 v254, v237, v254
	v_cvt_pk_bf16_f32 v242, v222, v223
	v_cvt_pk_bf16_f32 v243, v224, v225
	v_cvt_pk_bf16_f32 v244, v226, v227
	v_cvt_pk_bf16_f32 v245, v228, v229
	v_cvt_pk_bf16_f32 v250, v230, v231
	v_cvt_pk_bf16_f32 v251, v232, v233
	v_cvt_pk_bf16_f32 v252, v234, v235
	v_cvt_pk_bf16_f32 v253, v236, v237
	v_add_f32_e32 v202, v202, v254
	s_nop 1
	s_waitcnt lgkmcnt(8)
	v_mfma_f32_32x32x16_bf16 v[112:127], v[238:241], v[242:245], v[112:127]
	ds_read_b64_tr_b16 v[238:239], v218 offset:16640
	ds_read_b64_tr_b16 v[240:241], v218 offset:20736
	s_waitcnt lgkmcnt(8)
	v_mfma_f32_32x32x16_bf16 v[96:111], v[128:131], v[242:245], v[96:111]
	ds_read_b64_tr_b16 v[222:223], v219 offset:16640
	ds_read_b64_tr_b16 v[224:225], v219 offset:20736
	s_waitcnt lgkmcnt(8)
	v_mfma_f32_32x32x16_bf16 v[80:95], v[206:209], v[242:245], v[80:95]
	ds_read_b64_tr_b16 v[206:207], v221 offset:16640
	ds_read_b64_tr_b16 v[208:209], v221 offset:20736
	s_waitcnt lgkmcnt(8)
	v_mfma_f32_32x32x16_bf16 v[64:79], v[210:213], v[242:245], v[64:79]
	ds_read_b64_tr_b16 v[210:211], v205 offset:24576
	ds_read_b64_tr_b16 v[212:213], v205 offset:28672
	s_waitcnt lgkmcnt(8)
	v_mfma_f32_32x32x16_bf16 v[48:63], v[214:217], v[242:245], v[48:63]
	ds_read_b64_tr_b16 v[214:215], v218 offset:24576
	ds_read_b64_tr_b16 v[216:217], v218 offset:28672
	s_waitcnt lgkmcnt(8)
	v_mfma_f32_32x32x16_bf16 v[32:47], v[238:241], v[242:245], v[32:47]
	ds_read_b64_tr_b16 v[238:239], v219 offset:24576
	ds_read_b64_tr_b16 v[240:241], v219 offset:28672
	s_waitcnt lgkmcnt(8)
	v_mfma_f32_32x32x16_bf16 v[16:31], v[222:225], v[242:245], v[16:31]
	ds_read_b64_tr_b16 v[222:223], v221 offset:24576
	ds_read_b64_tr_b16 v[224:225], v221 offset:28672
	s_waitcnt lgkmcnt(8)
	v_mfma_f32_32x32x16_bf16 v[0:15], v[206:209], v[242:245], v[0:15]
	ds_read_b64_tr_b16 v[206:207], v205 offset:24832
	ds_read_b64_tr_b16 v[208:209], v205 offset:28928
	s_waitcnt lgkmcnt(8)
	v_mfma_f32_32x32x16_bf16 v[112:127], v[210:213], v[250:253], v[112:127]
	ds_read_b64_tr_b16 v[210:211], v218 offset:24832
	ds_read_b64_tr_b16 v[212:213], v218 offset:28928
	s_waitcnt lgkmcnt(8)
	v_mfma_f32_32x32x16_bf16 v[96:111], v[214:217], v[250:253], v[96:111]
	ds_read_b64_tr_b16 v[214:215], v219 offset:24832
	ds_read_b64_tr_b16 v[216:217], v219 offset:28928
	s_waitcnt lgkmcnt(8)
	v_mfma_f32_32x32x16_bf16 v[80:95], v[238:241], v[250:253], v[80:95]
	ds_read_b64_tr_b16 v[238:239], v221 offset:24832
	ds_read_b64_tr_b16 v[240:241], v221 offset:28928
	s_waitcnt lgkmcnt(8)
	v_mfma_f32_32x32x16_bf16 v[64:79], v[222:225], v[250:253], v[64:79]
	s_waitcnt lgkmcnt(6)
	v_mfma_f32_32x32x16_bf16 v[48:63], v[206:209], v[250:253], v[48:63]
	s_waitcnt lgkmcnt(4)
	v_mfma_f32_32x32x16_bf16 v[32:47], v[210:213], v[250:253], v[32:47]
	s_waitcnt lgkmcnt(2)
	v_mfma_f32_32x32x16_bf16 v[16:31], v[214:217], v[250:253], v[16:31]
	s_waitcnt lgkmcnt(0)
	v_mfma_f32_32x32x16_bf16 v[0:15], v[238:241], v[250:253], v[0:15]
	ds_read_b128 v[206:209], v194 offset:16384
	ds_read_b128 v[210:213], v195 offset:16384
	ds_read_b128 v[214:217], v196 offset:16384
	ds_read_b128 v[238:241], v197 offset:16384
	ds_read_b128 v[242:245], v198 offset:16384
	ds_read_b128 v[250:253], v199 offset:16384
	ds_read_b128 v[222:225], v200 offset:16384
	ds_read_b128 v[226:229], v201 offset:16384
	s_waitcnt vmcnt(0)
	s_add_i32 s18, s76, 1
	s_cmp_lg_u32 s76, 2
	s_cselect_b32 s76, s18, 0
	s_add_i32 s39, s39, 64
	s_add_u32 s14, s14, 0x100000
	s_addc_u32 s15, s15, 0
	s_add_i32 s38, s38, 1
	s_add_i32 s100, s39, 63
	s_cmp_le_i32 s100, s71
	s_cbranch_scc0 .Latt_latchb_4
	s_cmp_ge_u32 s38, s70
	s_cselect_b64 s[18:19], -1, 0
	v_mov_b32_e32 v203, v176
	s_barrier
	s_branch .Latt_cont_4s1
.Latt_slow_4s0:
.Latt_slot1_4:
.Latt_cont_4s1:
	v_add_u32_e32 v205, 0x8000, v205
	v_add_u32_e32 v218, 0x8000, v218
	v_add_u32_e32 v219, 0x8000, v219
	v_add_u32_e32 v221, 0x8000, v221
	s_waitcnt lgkmcnt(7)
	v_mfma_f32_32x32x16_bf16 v[128:143], v[206:209], v[144:147], 0
	ds_read_b128 v[206:209], v194 offset:24576
	s_cmp_lg_u64 s[18:19], 0
	s_cbranch_scc1 .Latt_nd0_4s1
	s_sub_i32 s100, s76, 1
	s_cmp_eq_u32 s76, 0
	s_cselect_b32 s100, 2, s100
	s_lshl_b32 s101, s100, 14
	s_add_i32 m0, s73, s101
	s_nop 0
	global_load_lds_dwordx4 v178, s[14:15]

.Latt_nr0_4s1:
	s_waitcnt lgkmcnt(3)
	v_mfma_f32_32x32x16_bf16 v[222:237], v[214:217], v[152:155], v[222:237]
	ds_read_b128 v[214:217], v200 offset:24576
	v_sub_f32_e32 v128, v128, v190
	v_exp_f32_e32 v128, v128
	v_sub_f32_e32 v129, v129, v190
	v_exp_f32_e32 v129, v129
	v_sub_f32_e32 v130, v130, v190
	s_waitcnt lgkmcnt(3)
	v_mfma_f32_32x32x16_bf16 v[222:237], v[238:241], v[156:159], v[222:237]
	ds_read_b128 v[238:241], v201 offset:24576
	v_add_f32_e32 v254, 0, v128
	v_exp_f32_e32 v130, v130
	v_sub_f32_e32 v131, v131, v190
	v_add_f32_e32 v254, v129, v254
	v_exp_f32_e32 v131, v131
	s_waitcnt lgkmcnt(3)
	v_mfma_f32_32x32x16_bf16 v[222:237], v[206:209], v[160:163], v[222:237]
	ds_read_b64_tr_b16 v[206:207], v205
	ds_read_b64_tr_b16 v[208:209], v205 offset:4096
	v_sub_f32_e32 v132, v132, v190
	v_add_f32_e32 v254, v130, v254
	v_exp_f32_e32 v132, v132
	v_sub_f32_e32 v133, v133, v190
	v_add_f32_e32 v254, v131, v254
	s_waitcnt lgkmcnt(4)
	v_mfma_f32_32x32x16_bf16 v[222:237], v[210:213], v[164:167], v[222:237]
	ds_read_b64_tr_b16 v[210:211], v218
	ds_read_b64_tr_b16 v[212:213], v218 offset:4096
	v_exp_f32_e32 v133, v133
	v_sub_f32_e32 v134, v134, v190
	v_add_f32_e32 v254, v132, v254
	v_exp_f32_e32 v134, v134
	s_waitcnt lgkmcnt(5)
	v_mfma_f32_32x32x16_bf16 v[222:237], v[214:217], v[168:171], v[222:237]
	ds_read_b64_tr_b16 v[214:215], v219
	ds_read_b64_tr_b16 v[216:217], v219 offset:4096
	v_sub_f32_e32 v135, v135, v190
	v_add_f32_e32 v254, v133, v254
	v_exp_f32_e32 v135, v135
	s_nop 0
	s_waitcnt lgkmcnt(6)
	v_mfma_f32_32x32x16_bf16 v[222:237], v[238:241], v[172:175], v[222:237]
	ds_read_b64_tr_b16 v[238:239], v221
	ds_read_b64_tr_b16 v[240:241], v221 offset:4096
	v_cvt_pk_bf16_f32 v242, v128, v129
	v_cvt_pk_bf16_f32 v243, v130, v131
	v_cvt_pk_bf16_f32 v244, v132, v133
	v_cvt_pk_bf16_f32 v245, v134, v135
	s_nop 1
	s_waitcnt lgkmcnt(6)
	v_mfma_f32_32x32x16_bf16 v[112:127], v[206:209], v[242:245], v[112:127]
	ds_read_b64_tr_b16 v[206:207], v205 offset:256
	ds_read_b64_tr_b16 v[208:209], v205 offset:4352
	v_sub_f32_e32 v136, v136, v190
	v_add_f32_e32 v254, v134, v254
	v_exp_f32_e32 v136, v136
	v_sub_f32_e32 v137, v137, v190
	v_add_f32_e32 v254, v135, v254
	s_waitcnt lgkmcnt(6)
	v_mfma_f32_32x32x16_bf16 v[96:111], v[210:213], v[242:245], v[96:111]
	ds_read_b64_tr_b16 v[210:211], v218 offset:256
	ds_read_b64_tr_b16 v[212:213], v218 offset:4352
	v_exp_f32_e32 v137, v137
	v_sub_f32_e32 v138, v138, v190
	v_add_f32_e32 v254, v136, v254
	v_exp_f32_e32 v138, v138
	v_sub_f32_e32 v139, v139, v190
	s_waitcnt lgkmcnt(6)
	v_mfma_f32_32x32x16_bf16 v[80:95], v[214:217], v[242:245], v[80:95]
	ds_read_b64_tr_b16 v[214:215], v219 offset:256
	ds_read_b64_tr_b16 v[216:217], v219 offset:4352
	v_add_f32_e32 v254, v137, v254
	v_exp_f32_e32 v139, v139
	v_sub_f32_e32 v140, v140, v190
	v_add_f32_e32 v254, v138, v254
	s_waitcnt lgkmcnt(6)
	v_mfma_f32_32x32x16_bf16 v[64:79], v[238:241], v[242:245], v[64:79]
	ds_read_b64_tr_b16 v[238:239], v221 offset:256
	ds_read_b64_tr_b16 v[240:241], v221 offset:4352
	v_exp_f32_e32 v140, v140
	v_sub_f32_e32 v141, v141, v190
	v_add_f32_e32 v254, v139, v254
	v_exp_f32_e32 v141, v141
	s_waitcnt lgkmcnt(6)
	v_mfma_f32_32x32x16_bf16 v[48:63], v[206:209], v[242:245], v[48:63]
	ds_read_b64_tr_b16 v[206:207], v205 offset:8192
	ds_read_b64_tr_b16 v[208:209], v205 offset:12288
	v_sub_f32_e32 v142, v142, v190
	v_add_f32_e32 v254, v140, v254
	v_exp_f32_e32 v142, v142
	v_sub_f32_e32 v143, v143, v190
	s_waitcnt lgkmcnt(6)
	v_mfma_f32_32x32x16_bf16 v[32:47], v[210:213], v[242:245], v[32:47]
	ds_read_b64_tr_b16 v[210:211], v218 offset:8192
	ds_read_b64_tr_b16 v[212:213], v218 offset:12288
	v_add_f32_e32 v254, v141, v254
	v_exp_f32_e32 v143, v143
	v_add_f32_e32 v254, v142, v254
	v_add_f32_e32 v254, v143, v254
	s_waitcnt lgkmcnt(6)
	v_mfma_f32_32x32x16_bf16 v[16:31], v[214:217], v[242:245], v[16:31]
	ds_read_b64_tr_b16 v[214:215], v219 offset:8192
	ds_read_b64_tr_b16 v[216:217], v219 offset:12288
	v_cvt_pk_bf16_f32 v250, v136, v137
	v_cvt_pk_bf16_f32 v251, v138, v139
	v_cvt_pk_bf16_f32 v252, v140, v141
	v_cvt_pk_bf16_f32 v253, v142, v143
	v_add_f32_e32 v202, v202, v254
	s_waitcnt lgkmcnt(6)
	v_mfma_f32_32x32x16_bf16 v[0:15], v[238:241], v[242:245], v[0:15]
	ds_read_b64_tr_b16 v[238:239], v221 offset:8192
	ds_read_b64_tr_b16 v[240:241], v221 offset:12288
	ds_read_b64_tr_b16 v[128:129], v205 offset:8448
	ds_read_b64_tr_b16 v[130:131], v205 offset:12544
	s_waitcnt lgkmcnt(8)
	v_mfma_f32_32x32x16_bf16 v[112:127], v[206:209], v[250:253], v[112:127]
	ds_read_b64_tr_b16 v[206:207], v218 offset:8448
	ds_read_b64_tr_b16 v[208:209], v218 offset:12544
	v_max3_f32 v246, v222, v223, v224
	v_max3_f32 v247, v225, v226, v227
	v_max3_f32 v246, v246, v228, v229
	v_max3_f32 v247, v247, v230, v231
	v_max3_f32 v246, v246, v232, v233
	s_waitcnt lgkmcnt(8)
	v_mfma_f32_32x32x16_bf16 v[96:111], v[210:213], v[250:253], v[96:111]
	ds_read_b64_tr_b16 v[210:211], v219 offset:8448
	ds_read_b64_tr_b16 v[212:213], v219 offset:12544
	v_max3_f32 v247, v247, v234, v235
	v_max3_f32 v246, v246, v236, v237
	v_max_f32_e32 v246, v246, v247
	v_mov_b32_e32 v247, v246
	v_add_f32_e32 v249, 0x41000000, v190
	s_waitcnt lgkmcnt(8)
	v_mfma_f32_32x32x16_bf16 v[80:95], v[214:217], v[250:253], v[80:95]
	ds_read_b64_tr_b16 v[214:215], v221 offset:8448
	ds_read_b64_tr_b16 v[216:217], v221 offset:12544
	s_nop 1
	v_permlane32_swap_b32_e32 v246, v247
	v_max_f32_e32 v246, v246, v247
	v_cmp_gt_f32_e32 vcc, v246, v249
	s_cbranch_vccnz .Latt_rs1_4s1
	s_waitcnt lgkmcnt(8)
	v_mfma_f32_32x32x16_bf16 v[64:79], v[238:241], v[250:253], v[64:79]
	ds_read_b64_tr_b16 v[238:239], v205 offset:16384
	ds_read_b64_tr_b16 v[240:241], v205 offset:20480
	v_sub_f32_e32 v222, v222, v190
	v_exp_f32_e32 v222, v222
	v_sub_f32_e32 v223, v223, v190
	v_exp_f32_e32 v223, v223
	v_sub_f32_e32 v224, v224, v190
	v_add_f32_e32 v254, 0, v222
	s_waitcnt lgkmcnt(8)
	v_mfma_f32_32x32x16_bf16 v[48:63], v[128:131], v[250:253], v[48:63]
	ds_read_b64_tr_b16 v[128:129], v218 offset:16384
	ds_read_b64_tr_b16 v[130:131], v218 offset:20480
	v_exp_f32_e32 v224, v224
	v_sub_f32_e32 v225, v225, v190
	v_add_f32_e32 v254, v223, v254
	v_exp_f32_e32 v225, v225
	v_sub_f32_e32 v226, v226, v190
	v_add_f32_e32 v254, v224, v254
	s_waitcnt lgkmcnt(8)
	v_mfma_f32_32x32x16_bf16 v[32:47], v[206:209], v[250:253], v[32:47]
	ds_read_b64_tr_b16 v[206:207], v219 offset:16384
	ds_read_b64_tr_b16 v[208:209], v219 offset:20480
	v_exp_f32_e32 v226, v226
	v_sub_f32_e32 v227, v227, v190
	v_add_f32_e32 v254, v225, v254
	v_exp_f32_e32 v227, v227
	v_sub_f32_e32 v228, v228, v190
	s_waitcnt lgkmcnt(8)
	v_mfma_f32_32x32x16_bf16 v[16:31], v[210:213], v[250:253], v[16:31]
	ds_read_b64_tr_b16 v[210:211], v221 offset:16384
	ds_read_b64_tr_b16 v[212:213], v221 offset:20480
	v_add_f32_e32 v254, v226, v254
	v_exp_f32_e32 v228, v228
	v_sub_f32_e32 v229, v229, v190
	v_add_f32_e32 v254, v227, v254
	v_exp_f32_e32 v229, v229
	s_waitcnt lgkmcnt(8)
	v_mfma_f32_32x32x16_bf16 v[0:15], v[214:217], v[250:253], v[0:15]
	ds_read_b64_tr_b16 v[214:215], v205 offset:16640
	ds_read_b64_tr_b16 v[216:217], v205 offset:20736
	s_nop 0
	v_cvt_pk_bf16_f32 v242, v222, v223
	v_cvt_pk_bf16_f32 v243, v224, v225
	v_cvt_pk_bf16_f32 v244, v226, v227
	v_cvt_pk_bf16_f32 v245, v228, v229
	s_nop 1
	s_waitcnt lgkmcnt(8)
	v_mfma_f32_32x32x16_bf16 v[112:127], v[238:241], v[242:245], v[112:127]
	ds_read_b64_tr_b16 v[238:239], v218 offset:16640
	ds_read_b64_tr_b16 v[240:241], v218 offset:20736
	v_sub_f32_e32 v230, v230, v190
	v_add_f32_e32 v254, v228, v254
	v_exp_f32_e32 v230, v230
	v_sub_f32_e32 v231, v231, v190
	v_add_f32_e32 v254, v229, v254
	s_waitcnt lgkmcnt(8)
	v_mfma_f32_32x32x16_bf16 v[96:111], v[128:131], v[242:245], v[96:111]
	ds_read_b64_tr_b16 v[128:129], v219 offset:16640
	ds_read_b64_tr_b16 v[130:131], v219 offset:20736
	v_exp_f32_e32 v231, v231
	v_sub_f32_e32 v232, v232, v190
	v_add_f32_e32 v254, v230, v254
	v_exp_f32_e32 v232, v232
	v_sub_f32_e32 v233, v233, v190
	s_waitcnt lgkmcnt(8)
	v_mfma_f32_32x32x16_bf16 v[80:95], v[206:209], v[242:245], v[80:95]
	ds_read_b64_tr_b16 v[206:207], v221 offset:16640
	ds_read_b64_tr_b16 v[208:209], v221 offset:20736
	v_add_f32_e32 v254, v231, v254
	v_exp_f32_e32 v233, v233
	v_sub_f32_e32 v234, v234, v190
	v_add_f32_e32 v254, v232, v254
	s_waitcnt lgkmcnt(8)
	v_mfma_f32_32x32x16_bf16 v[64:79], v[210:213], v[242:245], v[64:79]
	ds_read_b64_tr_b16 v[210:211], v205 offset:24576
	ds_read_b64_tr_b16 v[212:213], v205 offset:28672
	v_exp_f32_e32 v234, v234
	v_sub_f32_e32 v235, v235, v190
	v_add_f32_e32 v254, v233, v254
	v_exp_f32_e32 v235, v235
	s_waitcnt lgkmcnt(8)
	v_mfma_f32_32x32x16_bf16 v[48:63], v[214:217], v[242:245], v[48:63]
	ds_read_b64_tr_b16 v[214:215], v218 offset:24576
	ds_read_b64_tr_b16 v[216:217], v218 offset:28672
	v_sub_f32_e32 v236, v236, v190
	v_add_f32_e32 v254, v234, v254
	v_exp_f32_e32 v236, v236
	v_sub_f32_e32 v237, v237, v190
	s_waitcnt lgkmcnt(8)
	v_mfma_f32_32x32x16_bf16 v[32:47], v[238:241], v[242:245], v[32:47]
	ds_read_b64_tr_b16 v[238:239], v219 offset:24576
	ds_read_b64_tr_b16 v[240:241], v219 offset:28672
	v_add_f32_e32 v254, v235, v254
	v_exp_f32_e32 v237, v237
	v_add_f32_e32 v254, v236, v254
	v_add_f32_e32 v254, v237, v254
	s_waitcnt lgkmcnt(8)
	v_mfma_f32_32x32x16_bf16 v[16:31], v[128:131], v[242:245], v[16:31]
	ds_read_b64_tr_b16 v[128:129], v221 offset:24576
	ds_read_b64_tr_b16 v[130:131], v221 offset:28672
	v_cvt_pk_bf16_f32 v250, v230, v231
	v_cvt_pk_bf16_f32 v251, v232, v233
	v_cvt_pk_bf16_f32 v252, v234, v235
	v_cvt_pk_bf16_f32 v253, v236, v237
	v_add_f32_e32 v202, v202, v254
	s_waitcnt lgkmcnt(8)
	v_mfma_f32_32x32x16_bf16 v[0:15], v[206:209], v[242:245], v[0:15]
	ds_read_b64_tr_b16 v[206:207], v205 offset:24832
	ds_read_b64_tr_b16 v[208:209], v205 offset:28928
	s_waitcnt lgkmcnt(8)
	v_mfma_f32_32x32x16_bf16 v[112:127], v[210:213], v[250:253], v[112:127]
	ds_read_b64_tr_b16 v[210:211], v218 offset:24832
	ds_read_b64_tr_b16 v[212:213], v218 offset:28928
	s_waitcnt lgkmcnt(8)
	v_mfma_f32_32x32x16_bf16 v[96:111], v[214:217], v[250:253], v[96:111]
	ds_read_b64_tr_b16 v[214:215], v219 offset:24832
	ds_read_b64_tr_b16 v[216:217], v219 offset:28928
	s_waitcnt lgkmcnt(8)
	v_mfma_f32_32x32x16_bf16 v[80:95], v[238:241], v[250:253], v[80:95]
	ds_read_b64_tr_b16 v[238:239], v221 offset:24832
	ds_read_b64_tr_b16 v[240:241], v221 offset:28928
	s_waitcnt lgkmcnt(8)
	v_mfma_f32_32x32x16_bf16 v[64:79], v[128:131], v[250:253], v[64:79]
	s_waitcnt lgkmcnt(6)
	v_mfma_f32_32x32x16_bf16 v[48:63], v[206:209], v[250:253], v[48:63]
	s_waitcnt lgkmcnt(4)
	v_mfma_f32_32x32x16_bf16 v[32:47], v[210:213], v[250:253], v[32:47]
	s_waitcnt lgkmcnt(2)
	v_mfma_f32_32x32x16_bf16 v[16:31], v[214:217], v[250:253], v[16:31]
	s_waitcnt lgkmcnt(0)
	v_mfma_f32_32x32x16_bf16 v[0:15], v[238:241], v[250:253], v[0:15]
	ds_read_b128 v[206:209], v194 offset:32768
	ds_read_b128 v[210:213], v195 offset:32768
	ds_read_b128 v[214:217], v196 offset:32768
	ds_read_b128 v[238:241], v197 offset:32768
	ds_read_b128 v[242:245], v198 offset:32768
	ds_read_b128 v[250:253], v199 offset:32768
	ds_read_b128 v[222:225], v200 offset:32768
	ds_read_b128 v[226:229], v201 offset:32768
	s_waitcnt vmcnt(0)
	s_add_i32 s18, s76, 1
	s_cmp_lg_u32 s76, 2
	s_cselect_b32 s76, s18, 0
	s_add_i32 s39, s39, 64
	s_add_u32 s14, s14, 0x100000
	s_addc_u32 s15, s15, 0
	s_add_i32 s38, s38, 1
	s_add_i32 s100, s39, 63
	s_cmp_le_i32 s100, s71
	s_cbranch_scc0 .Latt_latchb_4
	s_cmp_ge_u32 s38, s70
	s_cselect_b64 s[18:19], -1, 0
	v_mov_b32_e32 v203, v176
	s_barrier
	s_branch .Latt_cont_4s2
.Latt_rs1_4s1:
	s_waitcnt lgkmcnt(8)
	v_mfma_f32_32x32x16_bf16 v[64:79], v[238:241], v[250:253], v[64:79]
	ds_read_b64_tr_b16 v[238:239], v205 offset:16384
	ds_read_b64_tr_b16 v[240:241], v205 offset:20480
	s_waitcnt lgkmcnt(8)
	v_mfma_f32_32x32x16_bf16 v[48:63], v[128:131], v[250:253], v[48:63]
	ds_read_b64_tr_b16 v[128:129], v218 offset:16384
	ds_read_b64_tr_b16 v[130:131], v218 offset:20480
	s_waitcnt lgkmcnt(8)
	v_mfma_f32_32x32x16_bf16 v[32:47], v[206:209], v[250:253], v[32:47]
	ds_read_b64_tr_b16 v[206:207], v219 offset:16384
	ds_read_b64_tr_b16 v[208:209], v219 offset:20480
	s_waitcnt lgkmcnt(8)
	v_mfma_f32_32x32x16_bf16 v[16:31], v[210:213], v[250:253], v[16:31]
	ds_read_b64_tr_b16 v[210:211], v221 offset:16384
	ds_read_b64_tr_b16 v[212:213], v221 offset:20480
	s_waitcnt lgkmcnt(8)
	v_mfma_f32_32x32x16_bf16 v[0:15], v[214:217], v[250:253], v[0:15]
	ds_read_b64_tr_b16 v[214:215], v205 offset:16640
	ds_read_b64_tr_b16 v[216:217], v205 offset:20736
	s_nop 11
	v_max_f32_e32 v246, v190, v246
	v_sub_f32_e32 v190, v190, v246
	v_exp_f32_e32 v190, v190
	s_nop 0
	v_pk_mul_f32 v[126:127], v[126:127], v[190:191] op_sel_hi:[1,0]
	v_pk_mul_f32 v[124:125], v[124:125], v[190:191] op_sel_hi:[1,0]
	v_pk_mul_f32 v[122:123], v[122:123], v[190:191] op_sel_hi:[1,0]
	v_pk_mul_f32 v[120:121], v[120:121], v[190:191] op_sel_hi:[1,0]
	v_pk_mul_f32 v[118:119], v[118:119], v[190:191] op_sel_hi:[1,0]
	v_pk_mul_f32 v[116:117], v[116:117], v[190:191] op_sel_hi:[1,0]
	v_pk_mul_f32 v[114:115], v[114:115], v[190:191] op_sel_hi:[1,0]
	v_pk_mul_f32 v[112:113], v[112:113], v[190:191] op_sel_hi:[1,0]
	v_pk_mul_f32 v[110:111], v[110:111], v[190:191] op_sel_hi:[1,0]
	v_pk_mul_f32 v[108:109], v[108:109], v[190:191] op_sel_hi:[1,0]
	v_pk_mul_f32 v[106:107], v[106:107], v[190:191] op_sel_hi:[1,0]
	v_pk_mul_f32 v[104:105], v[104:105], v[190:191] op_sel_hi:[1,0]
	v_pk_mul_f32 v[102:103], v[102:103], v[190:191] op_sel_hi:[1,0]
	v_pk_mul_f32 v[100:101], v[100:101], v[190:191] op_sel_hi:[1,0]
	v_pk_mul_f32 v[98:99], v[98:99], v[190:191] op_sel_hi:[1,0]
	v_pk_mul_f32 v[96:97], v[96:97], v[190:191] op_sel_hi:[1,0]
	v_pk_mul_f32 v[94:95], v[94:95], v[190:191] op_sel_hi:[1,0]
	v_pk_mul_f32 v[92:93], v[92:93], v[190:191] op_sel_hi:[1,0]
	v_pk_mul_f32 v[90:91], v[90:91], v[190:191] op_sel_hi:[1,0]
	v_pk_mul_f32 v[88:89], v[88:89], v[190:191] op_sel_hi:[1,0]
	v_pk_mul_f32 v[86:87], v[86:87], v[190:191] op_sel_hi:[1,0]
	v_pk_mul_f32 v[84:85], v[84:85], v[190:191] op_sel_hi:[1,0]
	v_pk_mul_f32 v[82:83], v[82:83], v[190:191] op_sel_hi:[1,0]
	v_pk_mul_f32 v[80:81], v[80:81], v[190:191] op_sel_hi:[1,0]
	v_pk_mul_f32 v[78:79], v[78:79], v[190:191] op_sel_hi:[1,0]
	v_pk_mul_f32 v[76:77], v[76:77], v[190:191] op_sel_hi:[1,0]
	v_pk_mul_f32 v[74:75], v[74:75], v[190:191] op_sel_hi:[1,0]
	v_pk_mul_f32 v[72:73], v[72:73], v[190:191] op_sel_hi:[1,0]
	v_pk_mul_f32 v[70:71], v[70:71], v[190:191] op_sel_hi:[1,0]
	v_pk_mul_f32 v[68:69], v[68:69], v[190:191] op_sel_hi:[1,0]
	v_pk_mul_f32 v[66:67], v[66:67], v[190:191] op_sel_hi:[1,0]
	v_pk_mul_f32 v[64:65], v[64:65], v[190:191] op_sel_hi:[1,0]
	v_pk_mul_f32 v[62:63], v[62:63], v[190:191] op_sel_hi:[1,0]
	v_pk_mul_f32 v[60:61], v[60:61], v[190:191] op_sel_hi:[1,0]
	v_pk_mul_f32 v[58:59], v[58:59], v[190:191] op_sel_hi:[1,0]
	v_pk_mul_f32 v[56:57], v[56:57], v[190:191] op_sel_hi:[1,0]
	v_pk_mul_f32 v[54:55], v[54:55], v[190:191] op_sel_hi:[1,0]
	v_pk_mul_f32 v[52:53], v[52:53], v[190:191] op_sel_hi:[1,0]
	v_pk_mul_f32 v[50:51], v[50:51], v[190:191] op_sel_hi:[1,0]
	v_pk_mul_f32 v[48:49], v[48:49], v[190:191] op_sel_hi:[1,0]
	v_pk_mul_f32 v[46:47], v[46:47], v[190:191] op_sel_hi:[1,0]
	v_pk_mul_f32 v[44:45], v[44:45], v[190:191] op_sel_hi:[1,0]
	v_pk_mul_f32 v[42:43], v[42:43], v[190:191] op_sel_hi:[1,0]
	v_pk_mul_f32 v[40:41], v[40:41], v[190:191] op_sel_hi:[1,0]
	v_pk_mul_f32 v[38:39], v[38:39], v[190:191] op_sel_hi:[1,0]
	v_pk_mul_f32 v[36:37], v[36:37], v[190:191] op_sel_hi:[1,0]
	v_pk_mul_f32 v[34:35], v[34:35], v[190:191] op_sel_hi:[1,0]
	v_pk_mul_f32 v[32:33], v[32:33], v[190:191] op_sel_hi:[1,0]
	v_pk_mul_f32 v[30:31], v[30:31], v[190:191] op_sel_hi:[1,0]
	v_pk_mul_f32 v[28:29], v[28:29], v[190:191] op_sel_hi:[1,0]
	v_pk_mul_f32 v[26:27], v[26:27], v[190:191] op_sel_hi:[1,0]
	v_pk_mul_f32 v[24:25], v[24:25], v[190:191] op_sel_hi:[1,0]
	v_pk_mul_f32 v[22:23], v[22:23], v[190:191] op_sel_hi:[1,0]
	v_pk_mul_f32 v[20:21], v[20:21], v[190:191] op_sel_hi:[1,0]
	v_pk_mul_f32 v[18:19], v[18:19], v[190:191] op_sel_hi:[1,0]
	v_pk_mul_f32 v[16:17], v[16:17], v[190:191] op_sel_hi:[1,0]
	v_pk_mul_f32 v[14:15], v[14:15], v[190:191] op_sel_hi:[1,0]
	v_pk_mul_f32 v[12:13], v[12:13], v[190:191] op_sel_hi:[1,0]
	v_pk_mul_f32 v[10:11], v[10:11], v[190:191] op_sel_hi:[1,0]
	v_pk_mul_f32 v[8:9], v[8:9], v[190:191] op_sel_hi:[1,0]
	v_pk_mul_f32 v[6:7], v[6:7], v[190:191] op_sel_hi:[1,0]
	v_pk_mul_f32 v[4:5], v[4:5], v[190:191] op_sel_hi:[1,0]
	v_pk_mul_f32 v[2:3], v[2:3], v[190:191] op_sel_hi:[1,0]
	v_pk_mul_f32 v[0:1], v[0:1], v[190:191] op_sel_hi:[1,0]
	v_mul_f32_e32 v202, v202, v190
	v_mov_b32_e32 v190, v246
	v_sub_f32_e32 v222, v222, v190
	v_exp_f32_e32 v222, v222
	v_sub_f32_e32 v223, v223, v190
	v_exp_f32_e32 v223, v223
	v_sub_f32_e32 v224, v224, v190
	v_add_f32_e32 v254, 0, v222
	v_exp_f32_e32 v224, v224
	v_sub_f32_e32 v225, v225, v190
	v_add_f32_e32 v254, v223, v254
	v_exp_f32_e32 v225, v225
	v_sub_f32_e32 v226, v226, v190
	v_add_f32_e32 v254, v224, v254
	v_exp_f32_e32 v226, v226
	v_sub_f32_e32 v227, v227, v190
	v_add_f32_e32 v254, v225, v254
	v_exp_f32_e32 v227, v227
	v_sub_f32_e32 v228, v228, v190
	v_add_f32_e32 v254, v226, v254
	v_exp_f32_e32 v228, v228
	v_sub_f32_e32 v229, v229, v190
	v_add_f32_e32 v254, v227, v254
	v_exp_f32_e32 v229, v229
	v_sub_f32_e32 v230, v230, v190
	v_add_f32_e32 v254, v228, v254
	v_exp_f32_e32 v230, v230
	v_sub_f32_e32 v231, v231, v190
	v_add_f32_e32 v254, v229, v254
	v_exp_f32_e32 v231, v231
	v_sub_f32_e32 v232, v232, v190
	v_add_f32_e32 v254, v230, v254
	v_exp_f32_e32 v232, v232
	v_sub_f32_e32 v233, v233, v190
	v_add_f32_e32 v254, v231, v254
	v_exp_f32_e32 v233, v233
	v_sub_f32_e32 v234, v234, v190
	v_add_f32_e32 v254, v232, v254
	v_exp_f32_e32 v234, v234
	v_sub_f32_e32 v235, v235, v190
	v_add_f32_e32 v254, v233, v254
	v_exp_f32_e32 v235, v235
	v_sub_f32_e32 v236, v236, v190
	v_add_f32_e32 v254, v234, v254
	v_exp_f32_e32 v236, v236
	v_sub_f32_e32 v237, v237, v190
	v_add_f32_e32 v254, v235, v254
	v_exp_f32_e32 v237, v237
	v_add_f32_e32 v254, v236, v254
	v_add_f32_e32 v254, v237, v254
	v_cvt_pk_bf16_f32 v242, v222, v223
	v_cvt_pk_bf16_f32 v243, v224, v225
	v_cvt_pk_bf16_f32 v244, v226, v227
	v_cvt_pk_bf16_f32 v245, v228, v229
	v_cvt_pk_bf16_f32 v250, v230, v231
	v_cvt_pk_bf16_f32 v251, v232, v233
	v_cvt_pk_bf16_f32 v252, v234, v235
	v_cvt_pk_bf16_f32 v253, v236, v237
	v_add_f32_e32 v202, v202, v254
	s_nop 1
	s_waitcnt lgkmcnt(8)
	v_mfma_f32_32x32x16_bf16 v[112:127], v[238:241], v[242:245], v[112:127]
	ds_read_b64_tr_b16 v[238:239], v218 offset:16640
	ds_read_b64_tr_b16 v[240:241], v218 offset:20736
	s_waitcnt lgkmcnt(8)
	v_mfma_f32_32x32x16_bf16 v[96:111], v[128:131], v[242:245], v[96:111]
	ds_read_b64_tr_b16 v[222:223], v219 offset:16640
	ds_read_b64_tr_b16 v[224:225], v219 offset:20736
	s_waitcnt lgkmcnt(8)
	v_mfma_f32_32x32x16_bf16 v[80:95], v[206:209], v[242:245], v[80:95]
	ds_read_b64_tr_b16 v[206:207], v221 offset:16640
	ds_read_b64_tr_b16 v[208:209], v221 offset:20736
	s_waitcnt lgkmcnt(8)
	v_mfma_f32_32x32x16_bf16 v[64:79], v[210:213], v[242:245], v[64:79]
	ds_read_b64_tr_b16 v[210:211], v205 offset:24576
	ds_read_b64_tr_b16 v[212:213], v205 offset:28672
	s_waitcnt lgkmcnt(8)
	v_mfma_f32_32x32x16_bf16 v[48:63], v[214:217], v[242:245], v[48:63]
	ds_read_b64_tr_b16 v[214:215], v218 offset:24576
	ds_read_b64_tr_b16 v[216:217], v218 offset:28672
	s_waitcnt lgkmcnt(8)
	v_mfma_f32_32x32x16_bf16 v[32:47], v[238:241], v[242:245], v[32:47]
	ds_read_b64_tr_b16 v[238:239], v219 offset:24576
	ds_read_b64_tr_b16 v[240:241], v219 offset:28672
	s_waitcnt lgkmcnt(8)
	v_mfma_f32_32x32x16_bf16 v[16:31], v[222:225], v[242:245], v[16:31]
	ds_read_b64_tr_b16 v[222:223], v221 offset:24576
	ds_read_b64_tr_b16 v[224:225], v221 offset:28672
	s_waitcnt lgkmcnt(8)
	v_mfma_f32_32x32x16_bf16 v[0:15], v[206:209], v[242:245], v[0:15]
	ds_read_b64_tr_b16 v[206:207], v205 offset:24832
	ds_read_b64_tr_b16 v[208:209], v205 offset:28928
	s_waitcnt lgkmcnt(8)
	v_mfma_f32_32x32x16_bf16 v[112:127], v[210:213], v[250:253], v[112:127]
	ds_read_b64_tr_b16 v[210:211], v218 offset:24832
	ds_read_b64_tr_b16 v[212:213], v218 offset:28928
	s_waitcnt lgkmcnt(8)
	v_mfma_f32_32x32x16_bf16 v[96:111], v[214:217], v[250:253], v[96:111]
	ds_read_b64_tr_b16 v[214:215], v219 offset:24832
	ds_read_b64_tr_b16 v[216:217], v219 offset:28928
	s_waitcnt lgkmcnt(8)
	v_mfma_f32_32x32x16_bf16 v[80:95], v[238:241], v[250:253], v[80:95]
	ds_read_b64_tr_b16 v[238:239], v221 offset:24832
	ds_read_b64_tr_b16 v[240:241], v221 offset:28928
	s_waitcnt lgkmcnt(8)
	v_mfma_f32_32x32x16_bf16 v[64:79], v[222:225], v[250:253], v[64:79]
	s_waitcnt lgkmcnt(6)
	v_mfma_f32_32x32x16_bf16 v[48:63], v[206:209], v[250:253], v[48:63]
	s_waitcnt lgkmcnt(4)
	v_mfma_f32_32x32x16_bf16 v[32:47], v[210:213], v[250:253], v[32:47]
	s_waitcnt lgkmcnt(2)
	v_mfma_f32_32x32x16_bf16 v[16:31], v[214:217], v[250:253], v[16:31]
	s_waitcnt lgkmcnt(0)
	v_mfma_f32_32x32x16_bf16 v[0:15], v[238:241], v[250:253], v[0:15]
	ds_read_b128 v[206:209], v194 offset:32768
	ds_read_b128 v[210:213], v195 offset:32768
	ds_read_b128 v[214:217], v196 offset:32768
	ds_read_b128 v[238:241], v197 offset:32768
	ds_read_b128 v[242:245], v198 offset:32768
	ds_read_b128 v[250:253], v199 offset:32768
	ds_read_b128 v[222:225], v200 offset:32768
	ds_read_b128 v[226:229], v201 offset:32768
	s_waitcnt vmcnt(0)
	s_add_i32 s18, s76, 1
	s_cmp_lg_u32 s76, 2
	s_cselect_b32 s76, s18, 0
	s_add_i32 s39, s39, 64
	s_add_u32 s14, s14, 0x100000
	s_addc_u32 s15, s15, 0
	s_add_i32 s38, s38, 1
	s_add_i32 s100, s39, 63
	s_cmp_le_i32 s100, s71
	s_cbranch_scc0 .Latt_latchb_4
	s_cmp_ge_u32 s38, s70
	s_cselect_b64 s[18:19], -1, 0
	v_mov_b32_e32 v203, v176
	s_barrier
	s_branch .Latt_cont_4s2
.Latt_slow_4s1:
.Latt_slot2_4:
.Latt_cont_4s2:
	v_add_u32_e32 v205, 0x8000, v205
	v_add_u32_e32 v218, 0x8000, v218
	v_add_u32_e32 v219, 0x8000, v219
	v_add_u32_e32 v221, 0x8000, v221
	s_waitcnt lgkmcnt(7)
	v_mfma_f32_32x32x16_bf16 v[128:143], v[206:209], v[144:147], 0
	ds_read_b128 v[206:209], v194 offset:40960
	s_cmp_lg_u64 s[18:19], 0
	s_cbranch_scc1 .Latt_nd0_4s2
	s_sub_i32 s100, s76, 1
	s_cmp_eq_u32 s76, 0
	s_cselect_b32 s100, 2, s100
	s_lshl_b32 s101, s100, 14
	s_add_i32 m0, s73, s101
	s_nop 0
	global_load_lds_dwordx4 v178, s[14:15]

.Latt_nr0_4s2:
	s_waitcnt lgkmcnt(3)
	v_mfma_f32_32x32x16_bf16 v[222:237], v[214:217], v[152:155], v[222:237]
	ds_read_b128 v[214:217], v200 offset:40960
	v_sub_f32_e32 v128, v128, v190
	v_exp_f32_e32 v128, v128
	v_sub_f32_e32 v129, v129, v190
	v_exp_f32_e32 v129, v129
	v_sub_f32_e32 v130, v130, v190
	s_waitcnt lgkmcnt(3)
	v_mfma_f32_32x32x16_bf16 v[222:237], v[238:241], v[156:159], v[222:237]
	ds_read_b128 v[238:241], v201 offset:40960
	v_add_f32_e32 v254, 0, v128
	v_exp_f32_e32 v130, v130
	v_sub_f32_e32 v131, v131, v190
	v_add_f32_e32 v254, v129, v254
	v_exp_f32_e32 v131, v131
	s_waitcnt lgkmcnt(3)
	v_mfma_f32_32x32x16_bf16 v[222:237], v[206:209], v[160:163], v[222:237]
	ds_read_b64_tr_b16 v[206:207], v205
	ds_read_b64_tr_b16 v[208:209], v205 offset:4096
	v_sub_f32_e32 v132, v132, v190
	v_add_f32_e32 v254, v130, v254
	v_exp_f32_e32 v132, v132
	v_sub_f32_e32 v133, v133, v190
	v_add_f32_e32 v254, v131, v254
	s_waitcnt lgkmcnt(4)
	v_mfma_f32_32x32x16_bf16 v[222:237], v[210:213], v[164:167], v[222:237]
	ds_read_b64_tr_b16 v[210:211], v218
	ds_read_b64_tr_b16 v[212:213], v218 offset:4096
	v_exp_f32_e32 v133, v133
	v_sub_f32_e32 v134, v134, v190
	v_add_f32_e32 v254, v132, v254
	v_exp_f32_e32 v134, v134
	s_waitcnt lgkmcnt(5)
	v_mfma_f32_32x32x16_bf16 v[222:237], v[214:217], v[168:171], v[222:237]
	ds_read_b64_tr_b16 v[214:215], v219
	ds_read_b64_tr_b16 v[216:217], v219 offset:4096
	v_sub_f32_e32 v135, v135, v190
	v_add_f32_e32 v254, v133, v254
	v_exp_f32_e32 v135, v135
	s_nop 0
	s_waitcnt lgkmcnt(6)
	v_mfma_f32_32x32x16_bf16 v[222:237], v[238:241], v[172:175], v[222:237]
	ds_read_b64_tr_b16 v[238:239], v221
	ds_read_b64_tr_b16 v[240:241], v221 offset:4096
	v_cvt_pk_bf16_f32 v242, v128, v129
	v_cvt_pk_bf16_f32 v243, v130, v131
	v_cvt_pk_bf16_f32 v244, v132, v133
	v_cvt_pk_bf16_f32 v245, v134, v135
	s_nop 1
	s_waitcnt lgkmcnt(6)
	v_mfma_f32_32x32x16_bf16 v[112:127], v[206:209], v[242:245], v[112:127]
	ds_read_b64_tr_b16 v[206:207], v205 offset:256
	ds_read_b64_tr_b16 v[208:209], v205 offset:4352
	v_sub_f32_e32 v136, v136, v190
	v_add_f32_e32 v254, v134, v254
	v_exp_f32_e32 v136, v136
	v_sub_f32_e32 v137, v137, v190
	v_add_f32_e32 v254, v135, v254
	s_waitcnt lgkmcnt(6)
	v_mfma_f32_32x32x16_bf16 v[96:111], v[210:213], v[242:245], v[96:111]
	ds_read_b64_tr_b16 v[210:211], v218 offset:256
	ds_read_b64_tr_b16 v[212:213], v218 offset:4352
	v_exp_f32_e32 v137, v137
	v_sub_f32_e32 v138, v138, v190
	v_add_f32_e32 v254, v136, v254
	v_exp_f32_e32 v138, v138
	v_sub_f32_e32 v139, v139, v190
	s_waitcnt lgkmcnt(6)
	v_mfma_f32_32x32x16_bf16 v[80:95], v[214:217], v[242:245], v[80:95]
	ds_read_b64_tr_b16 v[214:215], v219 offset:256
	ds_read_b64_tr_b16 v[216:217], v219 offset:4352
	v_add_f32_e32 v254, v137, v254
	v_exp_f32_e32 v139, v139
	v_sub_f32_e32 v140, v140, v190
	v_add_f32_e32 v254, v138, v254
	s_waitcnt lgkmcnt(6)
	v_mfma_f32_32x32x16_bf16 v[64:79], v[238:241], v[242:245], v[64:79]
	ds_read_b64_tr_b16 v[238:239], v221 offset:256
	ds_read_b64_tr_b16 v[240:241], v221 offset:4352
	v_exp_f32_e32 v140, v140
	v_sub_f32_e32 v141, v141, v190
	v_add_f32_e32 v254, v139, v254
	v_exp_f32_e32 v141, v141
	s_waitcnt lgkmcnt(6)
	v_mfma_f32_32x32x16_bf16 v[48:63], v[206:209], v[242:245], v[48:63]
	ds_read_b64_tr_b16 v[206:207], v205 offset:8192
	ds_read_b64_tr_b16 v[208:209], v205 offset:12288
	v_sub_f32_e32 v142, v142, v190
	v_add_f32_e32 v254, v140, v254
	v_exp_f32_e32 v142, v142
	v_sub_f32_e32 v143, v143, v190
	s_waitcnt lgkmcnt(6)
	v_mfma_f32_32x32x16_bf16 v[32:47], v[210:213], v[242:245], v[32:47]
	ds_read_b64_tr_b16 v[210:211], v218 offset:8192
	ds_read_b64_tr_b16 v[212:213], v218 offset:12288
	v_add_f32_e32 v254, v141, v254
	v_exp_f32_e32 v143, v143
	v_add_f32_e32 v254, v142, v254
	v_add_f32_e32 v254, v143, v254
	s_waitcnt lgkmcnt(6)
	v_mfma_f32_32x32x16_bf16 v[16:31], v[214:217], v[242:245], v[16:31]
	ds_read_b64_tr_b16 v[214:215], v219 offset:8192
	ds_read_b64_tr_b16 v[216:217], v219 offset:12288
	v_cvt_pk_bf16_f32 v250, v136, v137
	v_cvt_pk_bf16_f32 v251, v138, v139
	v_cvt_pk_bf16_f32 v252, v140, v141
	v_cvt_pk_bf16_f32 v253, v142, v143
	v_add_f32_e32 v202, v202, v254
	s_waitcnt lgkmcnt(6)
	v_mfma_f32_32x32x16_bf16 v[0:15], v[238:241], v[242:245], v[0:15]
	ds_read_b64_tr_b16 v[238:239], v221 offset:8192
	ds_read_b64_tr_b16 v[240:241], v221 offset:12288
	ds_read_b64_tr_b16 v[128:129], v205 offset:8448
	ds_read_b64_tr_b16 v[130:131], v205 offset:12544
	s_waitcnt lgkmcnt(8)
	v_mfma_f32_32x32x16_bf16 v[112:127], v[206:209], v[250:253], v[112:127]
	ds_read_b64_tr_b16 v[206:207], v218 offset:8448
	ds_read_b64_tr_b16 v[208:209], v218 offset:12544
	v_max3_f32 v246, v222, v223, v224
	v_max3_f32 v247, v225, v226, v227
	v_max3_f32 v246, v246, v228, v229
	v_max3_f32 v247, v247, v230, v231
	v_max3_f32 v246, v246, v232, v233
	s_waitcnt lgkmcnt(8)
	v_mfma_f32_32x32x16_bf16 v[96:111], v[210:213], v[250:253], v[96:111]
	ds_read_b64_tr_b16 v[210:211], v219 offset:8448
	ds_read_b64_tr_b16 v[212:213], v219 offset:12544
	v_max3_f32 v247, v247, v234, v235
	v_max3_f32 v246, v246, v236, v237
	v_max_f32_e32 v246, v246, v247
	v_mov_b32_e32 v247, v246
	v_add_f32_e32 v249, 0x41000000, v190
	s_waitcnt lgkmcnt(8)
	v_mfma_f32_32x32x16_bf16 v[80:95], v[214:217], v[250:253], v[80:95]
	ds_read_b64_tr_b16 v[214:215], v221 offset:8448
	ds_read_b64_tr_b16 v[216:217], v221 offset:12544
	s_nop 1
	v_permlane32_swap_b32_e32 v246, v247
	v_max_f32_e32 v246, v246, v247
	v_cmp_gt_f32_e32 vcc, v246, v249
	s_cbranch_vccnz .Latt_rs1_4s2
	s_waitcnt lgkmcnt(8)
	v_mfma_f32_32x32x16_bf16 v[64:79], v[238:241], v[250:253], v[64:79]
	ds_read_b64_tr_b16 v[238:239], v205 offset:16384
	ds_read_b64_tr_b16 v[240:241], v205 offset:20480
	v_sub_f32_e32 v222, v222, v190
	v_exp_f32_e32 v222, v222
	v_sub_f32_e32 v223, v223, v190
	v_exp_f32_e32 v223, v223
	v_sub_f32_e32 v224, v224, v190
	v_add_f32_e32 v254, 0, v222
	s_waitcnt lgkmcnt(8)
	v_mfma_f32_32x32x16_bf16 v[48:63], v[128:131], v[250:253], v[48:63]
	ds_read_b64_tr_b16 v[128:129], v218 offset:16384
	ds_read_b64_tr_b16 v[130:131], v218 offset:20480
	v_exp_f32_e32 v224, v224
	v_sub_f32_e32 v225, v225, v190
	v_add_f32_e32 v254, v223, v254
	v_exp_f32_e32 v225, v225
	v_sub_f32_e32 v226, v226, v190
	v_add_f32_e32 v254, v224, v254
	s_waitcnt lgkmcnt(8)
	v_mfma_f32_32x32x16_bf16 v[32:47], v[206:209], v[250:253], v[32:47]
	ds_read_b64_tr_b16 v[206:207], v219 offset:16384
	ds_read_b64_tr_b16 v[208:209], v219 offset:20480
	v_exp_f32_e32 v226, v226
	v_sub_f32_e32 v227, v227, v190
	v_add_f32_e32 v254, v225, v254
	v_exp_f32_e32 v227, v227
	v_sub_f32_e32 v228, v228, v190
	s_waitcnt lgkmcnt(8)
	v_mfma_f32_32x32x16_bf16 v[16:31], v[210:213], v[250:253], v[16:31]
	ds_read_b64_tr_b16 v[210:211], v221 offset:16384
	ds_read_b64_tr_b16 v[212:213], v221 offset:20480
	v_add_f32_e32 v254, v226, v254
	v_exp_f32_e32 v228, v228
	v_sub_f32_e32 v229, v229, v190
	v_add_f32_e32 v254, v227, v254
	v_exp_f32_e32 v229, v229
	s_waitcnt lgkmcnt(8)
	v_mfma_f32_32x32x16_bf16 v[0:15], v[214:217], v[250:253], v[0:15]
	ds_read_b64_tr_b16 v[214:215], v205 offset:16640
	ds_read_b64_tr_b16 v[216:217], v205 offset:20736
	s_nop 0
	v_cvt_pk_bf16_f32 v242, v222, v223
	v_cvt_pk_bf16_f32 v243, v224, v225
	v_cvt_pk_bf16_f32 v244, v226, v227
	v_cvt_pk_bf16_f32 v245, v228, v229
	s_nop 1
	s_waitcnt lgkmcnt(8)
	v_mfma_f32_32x32x16_bf16 v[112:127], v[238:241], v[242:245], v[112:127]
	ds_read_b64_tr_b16 v[238:239], v218 offset:16640
	ds_read_b64_tr_b16 v[240:241], v218 offset:20736
	v_sub_f32_e32 v230, v230, v190
	v_add_f32_e32 v254, v228, v254
	v_exp_f32_e32 v230, v230
	v_sub_f32_e32 v231, v231, v190
	v_add_f32_e32 v254, v229, v254
	s_waitcnt lgkmcnt(8)
	v_mfma_f32_32x32x16_bf16 v[96:111], v[128:131], v[242:245], v[96:111]
	ds_read_b64_tr_b16 v[128:129], v219 offset:16640
	ds_read_b64_tr_b16 v[130:131], v219 offset:20736
	v_exp_f32_e32 v231, v231
	v_sub_f32_e32 v232, v232, v190
	v_add_f32_e32 v254, v230, v254
	v_exp_f32_e32 v232, v232
	v_sub_f32_e32 v233, v233, v190
	s_waitcnt lgkmcnt(8)
	v_mfma_f32_32x32x16_bf16 v[80:95], v[206:209], v[242:245], v[80:95]
	ds_read_b64_tr_b16 v[206:207], v221 offset:16640
	ds_read_b64_tr_b16 v[208:209], v221 offset:20736
	v_add_f32_e32 v254, v231, v254
	v_exp_f32_e32 v233, v233
	v_sub_f32_e32 v234, v234, v190
	v_add_f32_e32 v254, v232, v254
	s_waitcnt lgkmcnt(8)
	v_mfma_f32_32x32x16_bf16 v[64:79], v[210:213], v[242:245], v[64:79]
	ds_read_b64_tr_b16 v[210:211], v205 offset:24576
	ds_read_b64_tr_b16 v[212:213], v205 offset:28672
	v_exp_f32_e32 v234, v234
	v_sub_f32_e32 v235, v235, v190
	v_add_f32_e32 v254, v233, v254
	v_exp_f32_e32 v235, v235
	s_waitcnt lgkmcnt(8)
	v_mfma_f32_32x32x16_bf16 v[48:63], v[214:217], v[242:245], v[48:63]
	ds_read_b64_tr_b16 v[214:215], v218 offset:24576
	ds_read_b64_tr_b16 v[216:217], v218 offset:28672
	v_sub_f32_e32 v236, v236, v190
	v_add_f32_e32 v254, v234, v254
	v_exp_f32_e32 v236, v236
	v_sub_f32_e32 v237, v237, v190
	s_waitcnt lgkmcnt(8)
	v_mfma_f32_32x32x16_bf16 v[32:47], v[238:241], v[242:245], v[32:47]
	ds_read_b64_tr_b16 v[238:239], v219 offset:24576
	ds_read_b64_tr_b16 v[240:241], v219 offset:28672
	v_add_f32_e32 v254, v235, v254
	v_exp_f32_e32 v237, v237
	v_add_f32_e32 v254, v236, v254
	v_add_f32_e32 v254, v237, v254
	s_waitcnt lgkmcnt(8)
	v_mfma_f32_32x32x16_bf16 v[16:31], v[128:131], v[242:245], v[16:31]
	ds_read_b64_tr_b16 v[128:129], v221 offset:24576
	ds_read_b64_tr_b16 v[130:131], v221 offset:28672
	v_cvt_pk_bf16_f32 v250, v230, v231
	v_cvt_pk_bf16_f32 v251, v232, v233
	v_cvt_pk_bf16_f32 v252, v234, v235
	v_cvt_pk_bf16_f32 v253, v236, v237
	v_add_f32_e32 v202, v202, v254
	s_waitcnt lgkmcnt(8)
	v_mfma_f32_32x32x16_bf16 v[0:15], v[206:209], v[242:245], v[0:15]
	ds_read_b64_tr_b16 v[206:207], v205 offset:24832
	ds_read_b64_tr_b16 v[208:209], v205 offset:28928
	s_waitcnt lgkmcnt(8)
	v_mfma_f32_32x32x16_bf16 v[112:127], v[210:213], v[250:253], v[112:127]
	ds_read_b64_tr_b16 v[210:211], v218 offset:24832
	ds_read_b64_tr_b16 v[212:213], v218 offset:28928
	s_waitcnt lgkmcnt(8)
	v_mfma_f32_32x32x16_bf16 v[96:111], v[214:217], v[250:253], v[96:111]
	ds_read_b64_tr_b16 v[214:215], v219 offset:24832
	ds_read_b64_tr_b16 v[216:217], v219 offset:28928
	s_waitcnt lgkmcnt(8)
	v_mfma_f32_32x32x16_bf16 v[80:95], v[238:241], v[250:253], v[80:95]
	ds_read_b64_tr_b16 v[238:239], v221 offset:24832
	ds_read_b64_tr_b16 v[240:241], v221 offset:28928
	s_waitcnt lgkmcnt(8)
	v_mfma_f32_32x32x16_bf16 v[64:79], v[128:131], v[250:253], v[64:79]
	s_waitcnt lgkmcnt(6)
	v_mfma_f32_32x32x16_bf16 v[48:63], v[206:209], v[250:253], v[48:63]
	s_waitcnt lgkmcnt(4)
	v_mfma_f32_32x32x16_bf16 v[32:47], v[210:213], v[250:253], v[32:47]
	s_waitcnt lgkmcnt(2)
	v_mfma_f32_32x32x16_bf16 v[16:31], v[214:217], v[250:253], v[16:31]
	s_waitcnt lgkmcnt(0)
	v_mfma_f32_32x32x16_bf16 v[0:15], v[238:241], v[250:253], v[0:15]
	ds_read_b128 v[206:209], v194
	ds_read_b128 v[210:213], v195
	ds_read_b128 v[214:217], v196
	ds_read_b128 v[238:241], v197
	ds_read_b128 v[242:245], v198
	ds_read_b128 v[250:253], v199
	ds_read_b128 v[222:225], v200
	ds_read_b128 v[226:229], v201
	s_waitcnt vmcnt(0)
	s_add_i32 s18, s76, 1
	s_cmp_lg_u32 s76, 2
	s_cselect_b32 s76, s18, 0
	s_add_i32 s39, s39, 64
	s_add_u32 s14, s14, 0x100000
	s_addc_u32 s15, s15, 0
	s_add_i32 s38, s38, 1
	s_add_i32 s100, s39, 63
	s_cmp_le_i32 s100, s71
	s_cbranch_scc0 .Latt_latchb_4
	s_cmp_ge_u32 s38, s70
	s_cselect_b64 s[18:19], -1, 0
	v_mov_b32_e32 v203, v176
	s_barrier
	s_branch .Latt_cont_4s0
.Latt_rs1_4s2:
	s_waitcnt lgkmcnt(8)
	v_mfma_f32_32x32x16_bf16 v[64:79], v[238:241], v[250:253], v[64:79]
	ds_read_b64_tr_b16 v[238:239], v205 offset:16384
	ds_read_b64_tr_b16 v[240:241], v205 offset:20480
	s_waitcnt lgkmcnt(8)
	v_mfma_f32_32x32x16_bf16 v[48:63], v[128:131], v[250:253], v[48:63]
	ds_read_b64_tr_b16 v[128:129], v218 offset:16384
	ds_read_b64_tr_b16 v[130:131], v218 offset:20480
	s_waitcnt lgkmcnt(8)
	v_mfma_f32_32x32x16_bf16 v[32:47], v[206:209], v[250:253], v[32:47]
	ds_read_b64_tr_b16 v[206:207], v219 offset:16384
	ds_read_b64_tr_b16 v[208:209], v219 offset:20480
	s_waitcnt lgkmcnt(8)
	v_mfma_f32_32x32x16_bf16 v[16:31], v[210:213], v[250:253], v[16:31]
	ds_read_b64_tr_b16 v[210:211], v221 offset:16384
	ds_read_b64_tr_b16 v[212:213], v221 offset:20480
	s_waitcnt lgkmcnt(8)
	v_mfma_f32_32x32x16_bf16 v[0:15], v[214:217], v[250:253], v[0:15]
	ds_read_b64_tr_b16 v[214:215], v205 offset:16640
	ds_read_b64_tr_b16 v[216:217], v205 offset:20736
	s_nop 11
	v_max_f32_e32 v246, v190, v246
	v_sub_f32_e32 v190, v190, v246
	v_exp_f32_e32 v190, v190
	s_nop 0
	v_pk_mul_f32 v[126:127], v[126:127], v[190:191] op_sel_hi:[1,0]
	v_pk_mul_f32 v[124:125], v[124:125], v[190:191] op_sel_hi:[1,0]
	v_pk_mul_f32 v[122:123], v[122:123], v[190:191] op_sel_hi:[1,0]
	v_pk_mul_f32 v[120:121], v[120:121], v[190:191] op_sel_hi:[1,0]
	v_pk_mul_f32 v[118:119], v[118:119], v[190:191] op_sel_hi:[1,0]
	v_pk_mul_f32 v[116:117], v[116:117], v[190:191] op_sel_hi:[1,0]
	v_pk_mul_f32 v[114:115], v[114:115], v[190:191] op_sel_hi:[1,0]
	v_pk_mul_f32 v[112:113], v[112:113], v[190:191] op_sel_hi:[1,0]
	v_pk_mul_f32 v[110:111], v[110:111], v[190:191] op_sel_hi:[1,0]
	v_pk_mul_f32 v[108:109], v[108:109], v[190:191] op_sel_hi:[1,0]
	v_pk_mul_f32 v[106:107], v[106:107], v[190:191] op_sel_hi:[1,0]
	v_pk_mul_f32 v[104:105], v[104:105], v[190:191] op_sel_hi:[1,0]
	v_pk_mul_f32 v[102:103], v[102:103], v[190:191] op_sel_hi:[1,0]
	v_pk_mul_f32 v[100:101], v[100:101], v[190:191] op_sel_hi:[1,0]
	v_pk_mul_f32 v[98:99], v[98:99], v[190:191] op_sel_hi:[1,0]
	v_pk_mul_f32 v[96:97], v[96:97], v[190:191] op_sel_hi:[1,0]
	v_pk_mul_f32 v[94:95], v[94:95], v[190:191] op_sel_hi:[1,0]
	v_pk_mul_f32 v[92:93], v[92:93], v[190:191] op_sel_hi:[1,0]
	v_pk_mul_f32 v[90:91], v[90:91], v[190:191] op_sel_hi:[1,0]
	v_pk_mul_f32 v[88:89], v[88:89], v[190:191] op_sel_hi:[1,0]
	v_pk_mul_f32 v[86:87], v[86:87], v[190:191] op_sel_hi:[1,0]
	v_pk_mul_f32 v[84:85], v[84:85], v[190:191] op_sel_hi:[1,0]
	v_pk_mul_f32 v[82:83], v[82:83], v[190:191] op_sel_hi:[1,0]
	v_pk_mul_f32 v[80:81], v[80:81], v[190:191] op_sel_hi:[1,0]
	v_pk_mul_f32 v[78:79], v[78:79], v[190:191] op_sel_hi:[1,0]
	v_pk_mul_f32 v[76:77], v[76:77], v[190:191] op_sel_hi:[1,0]
	v_pk_mul_f32 v[74:75], v[74:75], v[190:191] op_sel_hi:[1,0]
	v_pk_mul_f32 v[72:73], v[72:73], v[190:191] op_sel_hi:[1,0]
	v_pk_mul_f32 v[70:71], v[70:71], v[190:191] op_sel_hi:[1,0]
	v_pk_mul_f32 v[68:69], v[68:69], v[190:191] op_sel_hi:[1,0]
	v_pk_mul_f32 v[66:67], v[66:67], v[190:191] op_sel_hi:[1,0]
	v_pk_mul_f32 v[64:65], v[64:65], v[190:191] op_sel_hi:[1,0]
	v_pk_mul_f32 v[62:63], v[62:63], v[190:191] op_sel_hi:[1,0]
	v_pk_mul_f32 v[60:61], v[60:61], v[190:191] op_sel_hi:[1,0]
	v_pk_mul_f32 v[58:59], v[58:59], v[190:191] op_sel_hi:[1,0]
	v_pk_mul_f32 v[56:57], v[56:57], v[190:191] op_sel_hi:[1,0]
	v_pk_mul_f32 v[54:55], v[54:55], v[190:191] op_sel_hi:[1,0]
	v_pk_mul_f32 v[52:53], v[52:53], v[190:191] op_sel_hi:[1,0]
	v_pk_mul_f32 v[50:51], v[50:51], v[190:191] op_sel_hi:[1,0]
	v_pk_mul_f32 v[48:49], v[48:49], v[190:191] op_sel_hi:[1,0]
	v_pk_mul_f32 v[46:47], v[46:47], v[190:191] op_sel_hi:[1,0]
	v_pk_mul_f32 v[44:45], v[44:45], v[190:191] op_sel_hi:[1,0]
	v_pk_mul_f32 v[42:43], v[42:43], v[190:191] op_sel_hi:[1,0]
	v_pk_mul_f32 v[40:41], v[40:41], v[190:191] op_sel_hi:[1,0]
	v_pk_mul_f32 v[38:39], v[38:39], v[190:191] op_sel_hi:[1,0]
	v_pk_mul_f32 v[36:37], v[36:37], v[190:191] op_sel_hi:[1,0]
	v_pk_mul_f32 v[34:35], v[34:35], v[190:191] op_sel_hi:[1,0]
	v_pk_mul_f32 v[32:33], v[32:33], v[190:191] op_sel_hi:[1,0]
	v_pk_mul_f32 v[30:31], v[30:31], v[190:191] op_sel_hi:[1,0]
	v_pk_mul_f32 v[28:29], v[28:29], v[190:191] op_sel_hi:[1,0]
	v_pk_mul_f32 v[26:27], v[26:27], v[190:191] op_sel_hi:[1,0]
	v_pk_mul_f32 v[24:25], v[24:25], v[190:191] op_sel_hi:[1,0]
	v_pk_mul_f32 v[22:23], v[22:23], v[190:191] op_sel_hi:[1,0]
	v_pk_mul_f32 v[20:21], v[20:21], v[190:191] op_sel_hi:[1,0]
	v_pk_mul_f32 v[18:19], v[18:19], v[190:191] op_sel_hi:[1,0]
	v_pk_mul_f32 v[16:17], v[16:17], v[190:191] op_sel_hi:[1,0]
	v_pk_mul_f32 v[14:15], v[14:15], v[190:191] op_sel_hi:[1,0]
	v_pk_mul_f32 v[12:13], v[12:13], v[190:191] op_sel_hi:[1,0]
	v_pk_mul_f32 v[10:11], v[10:11], v[190:191] op_sel_hi:[1,0]
	v_pk_mul_f32 v[8:9], v[8:9], v[190:191] op_sel_hi:[1,0]
	v_pk_mul_f32 v[6:7], v[6:7], v[190:191] op_sel_hi:[1,0]
	v_pk_mul_f32 v[4:5], v[4:5], v[190:191] op_sel_hi:[1,0]
	v_pk_mul_f32 v[2:3], v[2:3], v[190:191] op_sel_hi:[1,0]
	v_pk_mul_f32 v[0:1], v[0:1], v[190:191] op_sel_hi:[1,0]
	v_mul_f32_e32 v202, v202, v190
	v_mov_b32_e32 v190, v246
	v_sub_f32_e32 v222, v222, v190
	v_exp_f32_e32 v222, v222
	v_sub_f32_e32 v223, v223, v190
	v_exp_f32_e32 v223, v223
	v_sub_f32_e32 v224, v224, v190
	v_add_f32_e32 v254, 0, v222
	v_exp_f32_e32 v224, v224
	v_sub_f32_e32 v225, v225, v190
	v_add_f32_e32 v254, v223, v254
	v_exp_f32_e32 v225, v225
	v_sub_f32_e32 v226, v226, v190
	v_add_f32_e32 v254, v224, v254
	v_exp_f32_e32 v226, v226
	v_sub_f32_e32 v227, v227, v190
	v_add_f32_e32 v254, v225, v254
	v_exp_f32_e32 v227, v227
	v_sub_f32_e32 v228, v228, v190
	v_add_f32_e32 v254, v226, v254
	v_exp_f32_e32 v228, v228
	v_sub_f32_e32 v229, v229, v190
	v_add_f32_e32 v254, v227, v254
	v_exp_f32_e32 v229, v229
	v_sub_f32_e32 v230, v230, v190
	v_add_f32_e32 v254, v228, v254
	v_exp_f32_e32 v230, v230
	v_sub_f32_e32 v231, v231, v190
	v_add_f32_e32 v254, v229, v254
	v_exp_f32_e32 v231, v231
	v_sub_f32_e32 v232, v232, v190
	v_add_f32_e32 v254, v230, v254
	v_exp_f32_e32 v232, v232
	v_sub_f32_e32 v233, v233, v190
	v_add_f32_e32 v254, v231, v254
	v_exp_f32_e32 v233, v233
	v_sub_f32_e32 v234, v234, v190
	v_add_f32_e32 v254, v232, v254
	v_exp_f32_e32 v234, v234
	v_sub_f32_e32 v235, v235, v190
	v_add_f32_e32 v254, v233, v254
	v_exp_f32_e32 v235, v235
	v_sub_f32_e32 v236, v236, v190
	v_add_f32_e32 v254, v234, v254
	v_exp_f32_e32 v236, v236
	v_sub_f32_e32 v237, v237, v190
	v_add_f32_e32 v254, v235, v254
	v_exp_f32_e32 v237, v237
	v_add_f32_e32 v254, v236, v254
	v_add_f32_e32 v254, v237, v254
	v_cvt_pk_bf16_f32 v242, v222, v223
	v_cvt_pk_bf16_f32 v243, v224, v225
	v_cvt_pk_bf16_f32 v244, v226, v227
	v_cvt_pk_bf16_f32 v245, v228, v229
	v_cvt_pk_bf16_f32 v250, v230, v231
	v_cvt_pk_bf16_f32 v251, v232, v233
	v_cvt_pk_bf16_f32 v252, v234, v235
	v_cvt_pk_bf16_f32 v253, v236, v237
	v_add_f32_e32 v202, v202, v254
	s_nop 1
	s_waitcnt lgkmcnt(8)
	v_mfma_f32_32x32x16_bf16 v[112:127], v[238:241], v[242:245], v[112:127]
	ds_read_b64_tr_b16 v[238:239], v218 offset:16640
	ds_read_b64_tr_b16 v[240:241], v218 offset:20736
	s_waitcnt lgkmcnt(8)
	v_mfma_f32_32x32x16_bf16 v[96:111], v[128:131], v[242:245], v[96:111]
	ds_read_b64_tr_b16 v[222:223], v219 offset:16640
	ds_read_b64_tr_b16 v[224:225], v219 offset:20736
	s_waitcnt lgkmcnt(8)
	v_mfma_f32_32x32x16_bf16 v[80:95], v[206:209], v[242:245], v[80:95]
	ds_read_b64_tr_b16 v[206:207], v221 offset:16640
	ds_read_b64_tr_b16 v[208:209], v221 offset:20736
	s_waitcnt lgkmcnt(8)
	v_mfma_f32_32x32x16_bf16 v[64:79], v[210:213], v[242:245], v[64:79]
	ds_read_b64_tr_b16 v[210:211], v205 offset:24576
	ds_read_b64_tr_b16 v[212:213], v205 offset:28672
	s_waitcnt lgkmcnt(8)
	v_mfma_f32_32x32x16_bf16 v[48:63], v[214:217], v[242:245], v[48:63]
	ds_read_b64_tr_b16 v[214:215], v218 offset:24576
	ds_read_b64_tr_b16 v[216:217], v218 offset:28672
	s_waitcnt lgkmcnt(8)
	v_mfma_f32_32x32x16_bf16 v[32:47], v[238:241], v[242:245], v[32:47]
	ds_read_b64_tr_b16 v[238:239], v219 offset:24576
	ds_read_b64_tr_b16 v[240:241], v219 offset:28672
	s_waitcnt lgkmcnt(8)
	v_mfma_f32_32x32x16_bf16 v[16:31], v[222:225], v[242:245], v[16:31]
	ds_read_b64_tr_b16 v[222:223], v221 offset:24576
	ds_read_b64_tr_b16 v[224:225], v221 offset:28672
	s_waitcnt lgkmcnt(8)
	v_mfma_f32_32x32x16_bf16 v[0:15], v[206:209], v[242:245], v[0:15]
	ds_read_b64_tr_b16 v[206:207], v205 offset:24832
	ds_read_b64_tr_b16 v[208:209], v205 offset:28928
	s_waitcnt lgkmcnt(8)
	v_mfma_f32_32x32x16_bf16 v[112:127], v[210:213], v[250:253], v[112:127]
	ds_read_b64_tr_b16 v[210:211], v218 offset:24832
	ds_read_b64_tr_b16 v[212:213], v218 offset:28928
	s_waitcnt lgkmcnt(8)
	v_mfma_f32_32x32x16_bf16 v[96:111], v[214:217], v[250:253], v[96:111]
	ds_read_b64_tr_b16 v[214:215], v219 offset:24832
	ds_read_b64_tr_b16 v[216:217], v219 offset:28928
	s_waitcnt lgkmcnt(8)
	v_mfma_f32_32x32x16_bf16 v[80:95], v[238:241], v[250:253], v[80:95]
	ds_read_b64_tr_b16 v[238:239], v221 offset:24832
	ds_read_b64_tr_b16 v[240:241], v221 offset:28928
	s_waitcnt lgkmcnt(8)
	v_mfma_f32_32x32x16_bf16 v[64:79], v[222:225], v[250:253], v[64:79]
	s_waitcnt lgkmcnt(6)
	v_mfma_f32_32x32x16_bf16 v[48:63], v[206:209], v[250:253], v[48:63]
	s_waitcnt lgkmcnt(4)
	v_mfma_f32_32x32x16_bf16 v[32:47], v[210:213], v[250:253], v[32:47]
	s_waitcnt lgkmcnt(2)
	v_mfma_f32_32x32x16_bf16 v[16:31], v[214:217], v[250:253], v[16:31]
	s_waitcnt lgkmcnt(0)
	v_mfma_f32_32x32x16_bf16 v[0:15], v[238:241], v[250:253], v[0:15]
	ds_read_b128 v[206:209], v194
	ds_read_b128 v[210:213], v195
	ds_read_b128 v[214:217], v196
	ds_read_b128 v[238:241], v197
	ds_read_b128 v[242:245], v198
	ds_read_b128 v[250:253], v199
	ds_read_b128 v[222:225], v200
	ds_read_b128 v[226:229], v201
	s_waitcnt vmcnt(0)
	s_add_i32 s18, s76, 1
	s_cmp_lg_u32 s76, 2
	s_cselect_b32 s76, s18, 0
	s_add_i32 s39, s39, 64
	s_add_u32 s14, s14, 0x100000
	s_addc_u32 s15, s15, 0
	s_add_i32 s38, s38, 1
	s_add_i32 s100, s39, 63
	s_cmp_le_i32 s100, s71
	s_cbranch_scc0 .Latt_latchb_4
	s_cmp_ge_u32 s38, s70
	s_cselect_b64 s[18:19], -1, 0
	v_mov_b32_e32 v203, v176
	s_barrier
	s_branch .Latt_cont_4s0

.Latt_latchb_5:
	s_waitcnt lgkmcnt(0)
	s_cmp_lg_u32 s75, s4
	s_barrier
	s_cbranch_scc0 .LBB0_1835

.Latt_nr0_5s0:
	s_waitcnt lgkmcnt(3)
	v_mfma_f32_32x32x16_bf16 v[222:237], v[214:217], v[152:155], v[222:237]
	ds_read_b128 v[214:217], v202 offset:8192
	v_sub_f32_e32 v128, v128, v190
	v_exp_f32_e32 v128, v128
	v_sub_f32_e32 v129, v129, v190
	v_exp_f32_e32 v129, v129
	v_sub_f32_e32 v130, v130, v190
	s_waitcnt lgkmcnt(3)
	v_mfma_f32_32x32x16_bf16 v[222:237], v[238:241], v[156:159], v[222:237]
	ds_read_b128 v[238:241], v203 offset:8192
	v_add_f32_e32 v254, 0, v128
	v_exp_f32_e32 v130, v130
	v_sub_f32_e32 v131, v131, v190
	v_add_f32_e32 v254, v129, v254
	v_exp_f32_e32 v131, v131
	s_waitcnt lgkmcnt(3)
	v_mfma_f32_32x32x16_bf16 v[222:237], v[206:209], v[160:163], v[222:237]
	ds_read_b64_tr_b16 v[206:207], v205
	ds_read_b64_tr_b16 v[208:209], v205 offset:4096
	v_sub_f32_e32 v132, v132, v190
	v_add_f32_e32 v254, v130, v254
	v_exp_f32_e32 v132, v132
	v_sub_f32_e32 v133, v133, v190
	v_add_f32_e32 v254, v131, v254
	s_waitcnt lgkmcnt(4)
	v_mfma_f32_32x32x16_bf16 v[222:237], v[210:213], v[164:167], v[222:237]
	ds_read_b64_tr_b16 v[210:211], v218
	ds_read_b64_tr_b16 v[212:213], v218 offset:4096
	v_exp_f32_e32 v133, v133
	v_sub_f32_e32 v134, v134, v190
	v_add_f32_e32 v254, v132, v254
	v_exp_f32_e32 v134, v134
	s_waitcnt lgkmcnt(5)
	v_mfma_f32_32x32x16_bf16 v[222:237], v[214:217], v[168:171], v[222:237]
	ds_read_b64_tr_b16 v[214:215], v219
	ds_read_b64_tr_b16 v[216:217], v219 offset:4096
	v_sub_f32_e32 v135, v135, v190
	v_add_f32_e32 v254, v133, v254
	v_exp_f32_e32 v135, v135
	s_nop 0
	s_waitcnt lgkmcnt(6)
	v_mfma_f32_32x32x16_bf16 v[222:237], v[238:241], v[172:175], v[222:237]
	ds_read_b64_tr_b16 v[238:239], v221
	ds_read_b64_tr_b16 v[240:241], v221 offset:4096
	v_cvt_pk_bf16_f32 v242, v128, v129
	v_cvt_pk_bf16_f32 v243, v130, v131
	v_cvt_pk_bf16_f32 v244, v132, v133
	v_cvt_pk_bf16_f32 v245, v134, v135
	s_nop 1
	s_waitcnt lgkmcnt(6)
	v_mfma_f32_32x32x16_bf16 v[112:127], v[206:209], v[242:245], v[112:127]
	ds_read_b64_tr_b16 v[206:207], v205 offset:256
	ds_read_b64_tr_b16 v[208:209], v205 offset:4352
	v_sub_f32_e32 v136, v136, v190
	v_add_f32_e32 v254, v134, v254
	v_exp_f32_e32 v136, v136
	v_sub_f32_e32 v137, v137, v190
	v_add_f32_e32 v254, v135, v254
	s_waitcnt lgkmcnt(6)
	v_mfma_f32_32x32x16_bf16 v[96:111], v[210:213], v[242:245], v[96:111]
	ds_read_b64_tr_b16 v[210:211], v218 offset:256
	ds_read_b64_tr_b16 v[212:213], v218 offset:4352
	v_exp_f32_e32 v137, v137
	v_sub_f32_e32 v138, v138, v190
	v_add_f32_e32 v254, v136, v254
	v_exp_f32_e32 v138, v138
	v_sub_f32_e32 v139, v139, v190
	s_waitcnt lgkmcnt(6)
	v_mfma_f32_32x32x16_bf16 v[80:95], v[214:217], v[242:245], v[80:95]
	ds_read_b64_tr_b16 v[214:215], v219 offset:256
	ds_read_b64_tr_b16 v[216:217], v219 offset:4352
	v_add_f32_e32 v254, v137, v254
	v_exp_f32_e32 v139, v139
	v_sub_f32_e32 v140, v140, v190
	v_add_f32_e32 v254, v138, v254
	s_waitcnt lgkmcnt(6)
	v_mfma_f32_32x32x16_bf16 v[64:79], v[238:241], v[242:245], v[64:79]
	ds_read_b64_tr_b16 v[238:239], v221 offset:256
	ds_read_b64_tr_b16 v[240:241], v221 offset:4352
	v_exp_f32_e32 v140, v140
	v_sub_f32_e32 v141, v141, v190
	v_add_f32_e32 v254, v139, v254
	v_exp_f32_e32 v141, v141
	s_waitcnt lgkmcnt(6)
	v_mfma_f32_32x32x16_bf16 v[48:63], v[206:209], v[242:245], v[48:63]
	ds_read_b64_tr_b16 v[206:207], v205 offset:8192
	ds_read_b64_tr_b16 v[208:209], v205 offset:12288
	v_sub_f32_e32 v142, v142, v190
	v_add_f32_e32 v254, v140, v254
	v_exp_f32_e32 v142, v142
	v_sub_f32_e32 v143, v143, v190
	s_waitcnt lgkmcnt(6)
	v_mfma_f32_32x32x16_bf16 v[32:47], v[210:213], v[242:245], v[32:47]
	ds_read_b64_tr_b16 v[210:211], v218 offset:8192
	ds_read_b64_tr_b16 v[212:213], v218 offset:12288
	v_add_f32_e32 v254, v141, v254
	v_exp_f32_e32 v143, v143
	v_add_f32_e32 v254, v142, v254
	v_add_f32_e32 v254, v143, v254
	s_waitcnt lgkmcnt(6)
	v_mfma_f32_32x32x16_bf16 v[16:31], v[214:217], v[242:245], v[16:31]
	ds_read_b64_tr_b16 v[214:215], v219 offset:8192
	ds_read_b64_tr_b16 v[216:217], v219 offset:12288
	v_cvt_pk_bf16_f32 v250, v136, v137
	v_cvt_pk_bf16_f32 v251, v138, v139
	v_cvt_pk_bf16_f32 v252, v140, v141
	v_cvt_pk_bf16_f32 v253, v142, v143
	v_add_f32_e32 v195, v195, v254
	s_waitcnt lgkmcnt(6)
	v_mfma_f32_32x32x16_bf16 v[0:15], v[238:241], v[242:245], v[0:15]
	ds_read_b64_tr_b16 v[238:239], v221 offset:8192
	ds_read_b64_tr_b16 v[240:241], v221 offset:12288
	ds_read_b64_tr_b16 v[128:129], v205 offset:8448
	ds_read_b64_tr_b16 v[130:131], v205 offset:12544
	s_waitcnt lgkmcnt(8)
	v_mfma_f32_32x32x16_bf16 v[112:127], v[206:209], v[250:253], v[112:127]
	ds_read_b64_tr_b16 v[206:207], v218 offset:8448
	ds_read_b64_tr_b16 v[208:209], v218 offset:12544
	v_max3_f32 v246, v222, v223, v224
	v_max3_f32 v247, v225, v226, v227
	v_max3_f32 v246, v246, v228, v229
	v_max3_f32 v247, v247, v230, v231
	v_max3_f32 v246, v246, v232, v233
	s_waitcnt lgkmcnt(8)
	v_mfma_f32_32x32x16_bf16 v[96:111], v[210:213], v[250:253], v[96:111]
	ds_read_b64_tr_b16 v[210:211], v219 offset:8448
	ds_read_b64_tr_b16 v[212:213], v219 offset:12544
	v_max3_f32 v247, v247, v234, v235
	v_max3_f32 v246, v246, v236, v237
	v_max_f32_e32 v246, v246, v247
	v_mov_b32_e32 v247, v246
	v_add_f32_e32 v249, 0x41000000, v190
	s_waitcnt lgkmcnt(8)
	v_mfma_f32_32x32x16_bf16 v[80:95], v[214:217], v[250:253], v[80:95]
	ds_read_b64_tr_b16 v[214:215], v221 offset:8448
	ds_read_b64_tr_b16 v[216:217], v221 offset:12544
	s_nop 1
	v_permlane32_swap_b32_e32 v246, v247
	v_max_f32_e32 v246, v246, v247
	v_cmp_gt_f32_e32 vcc, v246, v249
	s_cbranch_vccnz .Latt_rs1_5s0
	s_waitcnt lgkmcnt(8)
	v_mfma_f32_32x32x16_bf16 v[64:79], v[238:241], v[250:253], v[64:79]
	ds_read_b64_tr_b16 v[238:239], v205 offset:16384
	ds_read_b64_tr_b16 v[240:241], v205 offset:20480
	v_sub_f32_e32 v222, v222, v190
	v_exp_f32_e32 v222, v222
	v_sub_f32_e32 v223, v223, v190
	v_exp_f32_e32 v223, v223
	v_sub_f32_e32 v224, v224, v190
	v_add_f32_e32 v254, 0, v222
	s_waitcnt lgkmcnt(8)
	v_mfma_f32_32x32x16_bf16 v[48:63], v[128:131], v[250:253], v[48:63]
	ds_read_b64_tr_b16 v[128:129], v218 offset:16384
	ds_read_b64_tr_b16 v[130:131], v218 offset:20480
	v_exp_f32_e32 v224, v224
	v_sub_f32_e32 v225, v225, v190
	v_add_f32_e32 v254, v223, v254
	v_exp_f32_e32 v225, v225
	v_sub_f32_e32 v226, v226, v190
	v_add_f32_e32 v254, v224, v254
	s_waitcnt lgkmcnt(8)
	v_mfma_f32_32x32x16_bf16 v[32:47], v[206:209], v[250:253], v[32:47]
	ds_read_b64_tr_b16 v[206:207], v219 offset:16384
	ds_read_b64_tr_b16 v[208:209], v219 offset:20480
	v_exp_f32_e32 v226, v226
	v_sub_f32_e32 v227, v227, v190
	v_add_f32_e32 v254, v225, v254
	v_exp_f32_e32 v227, v227
	v_sub_f32_e32 v228, v228, v190
	s_waitcnt lgkmcnt(8)
	v_mfma_f32_32x32x16_bf16 v[16:31], v[210:213], v[250:253], v[16:31]
	ds_read_b64_tr_b16 v[210:211], v221 offset:16384
	ds_read_b64_tr_b16 v[212:213], v221 offset:20480
	v_add_f32_e32 v254, v226, v254
	v_exp_f32_e32 v228, v228
	v_sub_f32_e32 v229, v229, v190
	v_add_f32_e32 v254, v227, v254
	v_exp_f32_e32 v229, v229
	s_waitcnt lgkmcnt(8)
	v_mfma_f32_32x32x16_bf16 v[0:15], v[214:217], v[250:253], v[0:15]
	ds_read_b64_tr_b16 v[214:215], v205 offset:16640
	ds_read_b64_tr_b16 v[216:217], v205 offset:20736
	s_nop 0
	v_cvt_pk_bf16_f32 v242, v222, v223
	v_cvt_pk_bf16_f32 v243, v224, v225
	v_cvt_pk_bf16_f32 v244, v226, v227
	v_cvt_pk_bf16_f32 v245, v228, v229
	s_nop 1
	s_waitcnt lgkmcnt(8)
	v_mfma_f32_32x32x16_bf16 v[112:127], v[238:241], v[242:245], v[112:127]
	ds_read_b64_tr_b16 v[238:239], v218 offset:16640
	ds_read_b64_tr_b16 v[240:241], v218 offset:20736
	v_sub_f32_e32 v230, v230, v190
	v_add_f32_e32 v254, v228, v254
	v_exp_f32_e32 v230, v230
	v_sub_f32_e32 v231, v231, v190
	v_add_f32_e32 v254, v229, v254
	s_waitcnt lgkmcnt(8)
	v_mfma_f32_32x32x16_bf16 v[96:111], v[128:131], v[242:245], v[96:111]
	ds_read_b64_tr_b16 v[128:129], v219 offset:16640
	ds_read_b64_tr_b16 v[130:131], v219 offset:20736
	v_exp_f32_e32 v231, v231
	v_sub_f32_e32 v232, v232, v190
	v_add_f32_e32 v254, v230, v254
	v_exp_f32_e32 v232, v232
	v_sub_f32_e32 v233, v233, v190
	s_waitcnt lgkmcnt(8)
	v_mfma_f32_32x32x16_bf16 v[80:95], v[206:209], v[242:245], v[80:95]
	ds_read_b64_tr_b16 v[206:207], v221 offset:16640
	ds_read_b64_tr_b16 v[208:209], v221 offset:20736
	v_add_f32_e32 v254, v231, v254
	v_exp_f32_e32 v233, v233
	v_sub_f32_e32 v234, v234, v190
	v_add_f32_e32 v254, v232, v254
	s_waitcnt lgkmcnt(8)
	v_mfma_f32_32x32x16_bf16 v[64:79], v[210:213], v[242:245], v[64:79]
	ds_read_b64_tr_b16 v[210:211], v205 offset:24576
	ds_read_b64_tr_b16 v[212:213], v205 offset:28672
	v_exp_f32_e32 v234, v234
	v_sub_f32_e32 v235, v235, v190
	v_add_f32_e32 v254, v233, v254
	v_exp_f32_e32 v235, v235
	s_waitcnt lgkmcnt(8)
	v_mfma_f32_32x32x16_bf16 v[48:63], v[214:217], v[242:245], v[48:63]
	ds_read_b64_tr_b16 v[214:215], v218 offset:24576
	ds_read_b64_tr_b16 v[216:217], v218 offset:28672
	v_sub_f32_e32 v236, v236, v190
	v_add_f32_e32 v254, v234, v254
	v_exp_f32_e32 v236, v236
	v_sub_f32_e32 v237, v237, v190
	s_waitcnt lgkmcnt(8)
	v_mfma_f32_32x32x16_bf16 v[32:47], v[238:241], v[242:245], v[32:47]
	ds_read_b64_tr_b16 v[238:239], v219 offset:24576
	ds_read_b64_tr_b16 v[240:241], v219 offset:28672
	v_add_f32_e32 v254, v235, v254
	v_exp_f32_e32 v237, v237
	v_add_f32_e32 v254, v236, v254
	v_add_f32_e32 v254, v237, v254
	s_waitcnt lgkmcnt(8)
	v_mfma_f32_32x32x16_bf16 v[16:31], v[128:131], v[242:245], v[16:31]
	ds_read_b64_tr_b16 v[128:129], v221 offset:24576
	ds_read_b64_tr_b16 v[130:131], v221 offset:28672
	v_cvt_pk_bf16_f32 v250, v230, v231
	v_cvt_pk_bf16_f32 v251, v232, v233
	v_cvt_pk_bf16_f32 v252, v234, v235
	v_cvt_pk_bf16_f32 v253, v236, v237
	v_add_f32_e32 v195, v195, v254
	s_waitcnt lgkmcnt(8)
	v_mfma_f32_32x32x16_bf16 v[0:15], v[206:209], v[242:245], v[0:15]
	ds_read_b64_tr_b16 v[206:207], v205 offset:24832
	ds_read_b64_tr_b16 v[208:209], v205 offset:28928
	s_waitcnt lgkmcnt(8)
	v_mfma_f32_32x32x16_bf16 v[112:127], v[210:213], v[250:253], v[112:127]
	ds_read_b64_tr_b16 v[210:211], v218 offset:24832
	ds_read_b64_tr_b16 v[212:213], v218 offset:28928
	s_waitcnt lgkmcnt(8)
	v_mfma_f32_32x32x16_bf16 v[96:111], v[214:217], v[250:253], v[96:111]
	ds_read_b64_tr_b16 v[214:215], v219 offset:24832
	ds_read_b64_tr_b16 v[216:217], v219 offset:28928
	s_waitcnt lgkmcnt(8)
	v_mfma_f32_32x32x16_bf16 v[80:95], v[238:241], v[250:253], v[80:95]
	ds_read_b64_tr_b16 v[238:239], v221 offset:24832
	ds_read_b64_tr_b16 v[240:241], v221 offset:28928
	s_waitcnt lgkmcnt(8)
	v_mfma_f32_32x32x16_bf16 v[64:79], v[128:131], v[250:253], v[64:79]
	s_waitcnt lgkmcnt(6)
	v_mfma_f32_32x32x16_bf16 v[48:63], v[206:209], v[250:253], v[48:63]
	s_waitcnt lgkmcnt(4)
	v_mfma_f32_32x32x16_bf16 v[32:47], v[210:213], v[250:253], v[32:47]
	s_waitcnt lgkmcnt(2)
	v_mfma_f32_32x32x16_bf16 v[16:31], v[214:217], v[250:253], v[16:31]
	s_waitcnt lgkmcnt(0)
	v_mfma_f32_32x32x16_bf16 v[0:15], v[238:241], v[250:253], v[0:15]
	ds_read_b128 v[206:209], v196 offset:16384
	ds_read_b128 v[210:213], v197 offset:16384
	ds_read_b128 v[214:217], v198 offset:16384
	ds_read_b128 v[238:241], v199 offset:16384
	ds_read_b128 v[242:245], v200 offset:16384
	ds_read_b128 v[250:253], v201 offset:16384
	ds_read_b128 v[222:225], v202 offset:16384
	ds_read_b128 v[226:229], v203 offset:16384
	s_waitcnt vmcnt(0)
	s_add_i32 s18, s33, 1
	s_cmp_lg_u32 s33, 2
	s_cselect_b32 s33, s18, 0
	s_add_i32 s4, s4, 64
	s_add_u32 s12, s12, 0x100000
	s_addc_u32 s13, s13, 0
	s_add_i32 s76, s76, 1
	s_add_i32 s100, s4, 63
	s_cmp_le_i32 s100, s71
	s_cbranch_scc0 .Latt_latchb_5
	s_cmp_ge_u32 s76, s70
	s_cselect_b64 s[18:19], -1, 0
	v_mov_b32_e32 v204, v176
	s_barrier
	s_branch .Latt_cont_5s1
.Latt_rs1_5s0:
	s_waitcnt lgkmcnt(8)
	v_mfma_f32_32x32x16_bf16 v[64:79], v[238:241], v[250:253], v[64:79]
	ds_read_b64_tr_b16 v[238:239], v205 offset:16384
	ds_read_b64_tr_b16 v[240:241], v205 offset:20480
	s_waitcnt lgkmcnt(8)
	v_mfma_f32_32x32x16_bf16 v[48:63], v[128:131], v[250:253], v[48:63]
	ds_read_b64_tr_b16 v[128:129], v218 offset:16384
	ds_read_b64_tr_b16 v[130:131], v218 offset:20480
	s_waitcnt lgkmcnt(8)
	v_mfma_f32_32x32x16_bf16 v[32:47], v[206:209], v[250:253], v[32:47]
	ds_read_b64_tr_b16 v[206:207], v219 offset:16384
	ds_read_b64_tr_b16 v[208:209], v219 offset:20480
	s_waitcnt lgkmcnt(8)
	v_mfma_f32_32x32x16_bf16 v[16:31], v[210:213], v[250:253], v[16:31]
	ds_read_b64_tr_b16 v[210:211], v221 offset:16384
	ds_read_b64_tr_b16 v[212:213], v221 offset:20480
	s_waitcnt lgkmcnt(8)
	v_mfma_f32_32x32x16_bf16 v[0:15], v[214:217], v[250:253], v[0:15]
	ds_read_b64_tr_b16 v[214:215], v205 offset:16640
	ds_read_b64_tr_b16 v[216:217], v205 offset:20736
	s_nop 11
	v_max_f32_e32 v246, v190, v246
	v_sub_f32_e32 v190, v190, v246
	v_exp_f32_e32 v190, v190
	s_nop 0
	v_pk_mul_f32 v[126:127], v[126:127], v[190:191] op_sel_hi:[1,0]
	v_pk_mul_f32 v[124:125], v[124:125], v[190:191] op_sel_hi:[1,0]
	v_pk_mul_f32 v[122:123], v[122:123], v[190:191] op_sel_hi:[1,0]
	v_pk_mul_f32 v[120:121], v[120:121], v[190:191] op_sel_hi:[1,0]
	v_pk_mul_f32 v[118:119], v[118:119], v[190:191] op_sel_hi:[1,0]
	v_pk_mul_f32 v[116:117], v[116:117], v[190:191] op_sel_hi:[1,0]
	v_pk_mul_f32 v[114:115], v[114:115], v[190:191] op_sel_hi:[1,0]
	v_pk_mul_f32 v[112:113], v[112:113], v[190:191] op_sel_hi:[1,0]
	v_pk_mul_f32 v[110:111], v[110:111], v[190:191] op_sel_hi:[1,0]
	v_pk_mul_f32 v[108:109], v[108:109], v[190:191] op_sel_hi:[1,0]
	v_pk_mul_f32 v[106:107], v[106:107], v[190:191] op_sel_hi:[1,0]
	v_pk_mul_f32 v[104:105], v[104:105], v[190:191] op_sel_hi:[1,0]
	v_pk_mul_f32 v[102:103], v[102:103], v[190:191] op_sel_hi:[1,0]
	v_pk_mul_f32 v[100:101], v[100:101], v[190:191] op_sel_hi:[1,0]
	v_pk_mul_f32 v[98:99], v[98:99], v[190:191] op_sel_hi:[1,0]
	v_pk_mul_f32 v[96:97], v[96:97], v[190:191] op_sel_hi:[1,0]
	v_pk_mul_f32 v[94:95], v[94:95], v[190:191] op_sel_hi:[1,0]
	v_pk_mul_f32 v[92:93], v[92:93], v[190:191] op_sel_hi:[1,0]
	v_pk_mul_f32 v[90:91], v[90:91], v[190:191] op_sel_hi:[1,0]
	v_pk_mul_f32 v[88:89], v[88:89], v[190:191] op_sel_hi:[1,0]
	v_pk_mul_f32 v[86:87], v[86:87], v[190:191] op_sel_hi:[1,0]
	v_pk_mul_f32 v[84:85], v[84:85], v[190:191] op_sel_hi:[1,0]
	v_pk_mul_f32 v[82:83], v[82:83], v[190:191] op_sel_hi:[1,0]
	v_pk_mul_f32 v[80:81], v[80:81], v[190:191] op_sel_hi:[1,0]
	v_pk_mul_f32 v[78:79], v[78:79], v[190:191] op_sel_hi:[1,0]
	v_pk_mul_f32 v[76:77], v[76:77], v[190:191] op_sel_hi:[1,0]
	v_pk_mul_f32 v[74:75], v[74:75], v[190:191] op_sel_hi:[1,0]
	v_pk_mul_f32 v[72:73], v[72:73], v[190:191] op_sel_hi:[1,0]
	v_pk_mul_f32 v[70:71], v[70:71], v[190:191] op_sel_hi:[1,0]
	v_pk_mul_f32 v[68:69], v[68:69], v[190:191] op_sel_hi:[1,0]
	v_pk_mul_f32 v[66:67], v[66:67], v[190:191] op_sel_hi:[1,0]
	v_pk_mul_f32 v[64:65], v[64:65], v[190:191] op_sel_hi:[1,0]
	v_pk_mul_f32 v[62:63], v[62:63], v[190:191] op_sel_hi:[1,0]
	v_pk_mul_f32 v[60:61], v[60:61], v[190:191] op_sel_hi:[1,0]
	v_pk_mul_f32 v[58:59], v[58:59], v[190:191] op_sel_hi:[1,0]
	v_pk_mul_f32 v[56:57], v[56:57], v[190:191] op_sel_hi:[1,0]
	v_pk_mul_f32 v[54:55], v[54:55], v[190:191] op_sel_hi:[1,0]
	v_pk_mul_f32 v[52:53], v[52:53], v[190:191] op_sel_hi:[1,0]
	v_pk_mul_f32 v[50:51], v[50:51], v[190:191] op_sel_hi:[1,0]
	v_pk_mul_f32 v[48:49], v[48:49], v[190:191] op_sel_hi:[1,0]
	v_pk_mul_f32 v[46:47], v[46:47], v[190:191] op_sel_hi:[1,0]
	v_pk_mul_f32 v[44:45], v[44:45], v[190:191] op_sel_hi:[1,0]
	v_pk_mul_f32 v[42:43], v[42:43], v[190:191] op_sel_hi:[1,0]
	v_pk_mul_f32 v[40:41], v[40:41], v[190:191] op_sel_hi:[1,0]
	v_pk_mul_f32 v[38:39], v[38:39], v[190:191] op_sel_hi:[1,0]
	v_pk_mul_f32 v[36:37], v[36:37], v[190:191] op_sel_hi:[1,0]
	v_pk_mul_f32 v[34:35], v[34:35], v[190:191] op_sel_hi:[1,0]
	v_pk_mul_f32 v[32:33], v[32:33], v[190:191] op_sel_hi:[1,0]
	v_pk_mul_f32 v[30:31], v[30:31], v[190:191] op_sel_hi:[1,0]
	v_pk_mul_f32 v[28:29], v[28:29], v[190:191] op_sel_hi:[1,0]
	v_pk_mul_f32 v[26:27], v[26:27], v[190:191] op_sel_hi:[1,0]
	v_pk_mul_f32 v[24:25], v[24:25], v[190:191] op_sel_hi:[1,0]
	v_pk_mul_f32 v[22:23], v[22:23], v[190:191] op_sel_hi:[1,0]
	v_pk_mul_f32 v[20:21], v[20:21], v[190:191] op_sel_hi:[1,0]
	v_pk_mul_f32 v[18:19], v[18:19], v[190:191] op_sel_hi:[1,0]
	v_pk_mul_f32 v[16:17], v[16:17], v[190:191] op_sel_hi:[1,0]
	v_pk_mul_f32 v[14:15], v[14:15], v[190:191] op_sel_hi:[1,0]
	v_pk_mul_f32 v[12:13], v[12:13], v[190:191] op_sel_hi:[1,0]
	v_pk_mul_f32 v[10:11], v[10:11], v[190:191] op_sel_hi:[1,0]
	v_pk_mul_f32 v[8:9], v[8:9], v[190:191] op_sel_hi:[1,0]
	v_pk_mul_f32 v[6:7], v[6:7], v[190:191] op_sel_hi:[1,0]
	v_pk_mul_f32 v[4:5], v[4:5], v[190:191] op_sel_hi:[1,0]
	v_pk_mul_f32 v[2:3], v[2:3], v[190:191] op_sel_hi:[1,0]
	v_pk_mul_f32 v[0:1], v[0:1], v[190:191] op_sel_hi:[1,0]
	v_mul_f32_e32 v195, v195, v190
	v_mov_b32_e32 v190, v246
	v_sub_f32_e32 v222, v222, v190
	v_exp_f32_e32 v222, v222
	v_sub_f32_e32 v223, v223, v190
	v_exp_f32_e32 v223, v223
	v_sub_f32_e32 v224, v224, v190
	v_add_f32_e32 v254, 0, v222
	v_exp_f32_e32 v224, v224
	v_sub_f32_e32 v225, v225, v190
	v_add_f32_e32 v254, v223, v254
	v_exp_f32_e32 v225, v225
	v_sub_f32_e32 v226, v226, v190
	v_add_f32_e32 v254, v224, v254
	v_exp_f32_e32 v226, v226
	v_sub_f32_e32 v227, v227, v190
	v_add_f32_e32 v254, v225, v254
	v_exp_f32_e32 v227, v227
	v_sub_f32_e32 v228, v228, v190
	v_add_f32_e32 v254, v226, v254
	v_exp_f32_e32 v228, v228
	v_sub_f32_e32 v229, v229, v190
	v_add_f32_e32 v254, v227, v254
	v_exp_f32_e32 v229, v229
	v_sub_f32_e32 v230, v230, v190
	v_add_f32_e32 v254, v228, v254
	v_exp_f32_e32 v230, v230
	v_sub_f32_e32 v231, v231, v190
	v_add_f32_e32 v254, v229, v254
	v_exp_f32_e32 v231, v231
	v_sub_f32_e32 v232, v232, v190
	v_add_f32_e32 v254, v230, v254
	v_exp_f32_e32 v232, v232
	v_sub_f32_e32 v233, v233, v190
	v_add_f32_e32 v254, v231, v254
	v_exp_f32_e32 v233, v233
	v_sub_f32_e32 v234, v234, v190
	v_add_f32_e32 v254, v232, v254
	v_exp_f32_e32 v234, v234
	v_sub_f32_e32 v235, v235, v190
	v_add_f32_e32 v254, v233, v254
	v_exp_f32_e32 v235, v235
	v_sub_f32_e32 v236, v236, v190
	v_add_f32_e32 v254, v234, v254
	v_exp_f32_e32 v236, v236
	v_sub_f32_e32 v237, v237, v190
	v_add_f32_e32 v254, v235, v254
	v_exp_f32_e32 v237, v237
	v_add_f32_e32 v254, v236, v254
	v_add_f32_e32 v254, v237, v254
	v_cvt_pk_bf16_f32 v242, v222, v223
	v_cvt_pk_bf16_f32 v243, v224, v225
	v_cvt_pk_bf16_f32 v244, v226, v227
	v_cvt_pk_bf16_f32 v245, v228, v229
	v_cvt_pk_bf16_f32 v250, v230, v231
	v_cvt_pk_bf16_f32 v251, v232, v233
	v_cvt_pk_bf16_f32 v252, v234, v235
	v_cvt_pk_bf16_f32 v253, v236, v237
	v_add_f32_e32 v195, v195, v254
	s_nop 1
	s_waitcnt lgkmcnt(8)
	v_mfma_f32_32x32x16_bf16 v[112:127], v[238:241], v[242:245], v[112:127]
	ds_read_b64_tr_b16 v[238:239], v218 offset:16640
	ds_read_b64_tr_b16 v[240:241], v218 offset:20736
	s_waitcnt lgkmcnt(8)
	v_mfma_f32_32x32x16_bf16 v[96:111], v[128:131], v[242:245], v[96:111]
	ds_read_b64_tr_b16 v[222:223], v219 offset:16640
	ds_read_b64_tr_b16 v[224:225], v219 offset:20736
	s_waitcnt lgkmcnt(8)
	v_mfma_f32_32x32x16_bf16 v[80:95], v[206:209], v[242:245], v[80:95]
	ds_read_b64_tr_b16 v[206:207], v221 offset:16640
	ds_read_b64_tr_b16 v[208:209], v221 offset:20736
	s_waitcnt lgkmcnt(8)
	v_mfma_f32_32x32x16_bf16 v[64:79], v[210:213], v[242:245], v[64:79]
	ds_read_b64_tr_b16 v[210:211], v205 offset:24576
	ds_read_b64_tr_b16 v[212:213], v205 offset:28672
	s_waitcnt lgkmcnt(8)
	v_mfma_f32_32x32x16_bf16 v[48:63], v[214:217], v[242:245], v[48:63]
	ds_read_b64_tr_b16 v[214:215], v218 offset:24576
	ds_read_b64_tr_b16 v[216:217], v218 offset:28672
	s_waitcnt lgkmcnt(8)
	v_mfma_f32_32x32x16_bf16 v[32:47], v[238:241], v[242:245], v[32:47]
	ds_read_b64_tr_b16 v[238:239], v219 offset:24576
	ds_read_b64_tr_b16 v[240:241], v219 offset:28672
	s_waitcnt lgkmcnt(8)
	v_mfma_f32_32x32x16_bf16 v[16:31], v[222:225], v[242:245], v[16:31]
	ds_read_b64_tr_b16 v[222:223], v221 offset:24576
	ds_read_b64_tr_b16 v[224:225], v221 offset:28672
	s_waitcnt lgkmcnt(8)
	v_mfma_f32_32x32x16_bf16 v[0:15], v[206:209], v[242:245], v[0:15]
	ds_read_b64_tr_b16 v[206:207], v205 offset:24832
	ds_read_b64_tr_b16 v[208:209], v205 offset:28928
	s_waitcnt lgkmcnt(8)
	v_mfma_f32_32x32x16_bf16 v[112:127], v[210:213], v[250:253], v[112:127]
	ds_read_b64_tr_b16 v[210:211], v218 offset:24832
	ds_read_b64_tr_b16 v[212:213], v218 offset:28928
	s_waitcnt lgkmcnt(8)
	v_mfma_f32_32x32x16_bf16 v[96:111], v[214:217], v[250:253], v[96:111]
	ds_read_b64_tr_b16 v[214:215], v219 offset:24832
	ds_read_b64_tr_b16 v[216:217], v219 offset:28928
	s_waitcnt lgkmcnt(8)
	v_mfma_f32_32x32x16_bf16 v[80:95], v[238:241], v[250:253], v[80:95]
	ds_read_b64_tr_b16 v[238:239], v221 offset:24832
	ds_read_b64_tr_b16 v[240:241], v221 offset:28928
	s_waitcnt lgkmcnt(8)
	v_mfma_f32_32x32x16_bf16 v[64:79], v[222:225], v[250:253], v[64:79]
	s_waitcnt lgkmcnt(6)
	v_mfma_f32_32x32x16_bf16 v[48:63], v[206:209], v[250:253], v[48:63]
	s_waitcnt lgkmcnt(4)
	v_mfma_f32_32x32x16_bf16 v[32:47], v[210:213], v[250:253], v[32:47]
	s_waitcnt lgkmcnt(2)
	v_mfma_f32_32x32x16_bf16 v[16:31], v[214:217], v[250:253], v[16:31]
	s_waitcnt lgkmcnt(0)
	v_mfma_f32_32x32x16_bf16 v[0:15], v[238:241], v[250:253], v[0:15]
	ds_read_b128 v[206:209], v196 offset:16384
	ds_read_b128 v[210:213], v197 offset:16384
	ds_read_b128 v[214:217], v198 offset:16384
	ds_read_b128 v[238:241], v199 offset:16384
	ds_read_b128 v[242:245], v200 offset:16384
	ds_read_b128 v[250:253], v201 offset:16384
	ds_read_b128 v[222:225], v202 offset:16384
	ds_read_b128 v[226:229], v203 offset:16384
	s_waitcnt vmcnt(0)
	s_add_i32 s18, s33, 1
	s_cmp_lg_u32 s33, 2
	s_cselect_b32 s33, s18, 0
	s_add_i32 s4, s4, 64
	s_add_u32 s12, s12, 0x100000
	s_addc_u32 s13, s13, 0
	s_add_i32 s76, s76, 1
	s_add_i32 s100, s4, 63
	s_cmp_le_i32 s100, s71
	s_cbranch_scc0 .Latt_latchb_5
	s_cmp_ge_u32 s76, s70
	s_cselect_b64 s[18:19], -1, 0
	v_mov_b32_e32 v204, v176
	s_barrier
	s_branch .Latt_cont_5s1
.Latt_slow_5s0:
.Latt_slot1_5:
.Latt_cont_5s1:
	v_add_u32_e32 v205, 0x8000, v205
	v_add_u32_e32 v218, 0x8000, v218
	v_add_u32_e32 v219, 0x8000, v219
	v_add_u32_e32 v221, 0x8000, v221
	s_waitcnt lgkmcnt(7)
	v_mfma_f32_32x32x16_bf16 v[128:143], v[206:209], v[144:147], 0
	ds_read_b128 v[206:209], v196 offset:24576
	s_cmp_lg_u64 s[18:19], 0
	s_cbranch_scc1 .Latt_nd0_5s1
	s_sub_i32 s100, s33, 1
	s_cmp_eq_u32 s33, 0
	s_cselect_b32 s100, 2, s100
	s_lshl_b32 s101, s100, 14
	s_add_i32 m0, s73, s101
	s_nop 0
	global_load_lds_dwordx4 v178, s[12:13]

.Latt_nr0_5s1:
	s_waitcnt lgkmcnt(3)
	v_mfma_f32_32x32x16_bf16 v[222:237], v[214:217], v[152:155], v[222:237]
	ds_read_b128 v[214:217], v202 offset:24576
	v_sub_f32_e32 v128, v128, v190
	v_exp_f32_e32 v128, v128
	v_sub_f32_e32 v129, v129, v190
	v_exp_f32_e32 v129, v129
	v_sub_f32_e32 v130, v130, v190
	s_waitcnt lgkmcnt(3)
	v_mfma_f32_32x32x16_bf16 v[222:237], v[238:241], v[156:159], v[222:237]
	ds_read_b128 v[238:241], v203 offset:24576
	v_add_f32_e32 v254, 0, v128
	v_exp_f32_e32 v130, v130
	v_sub_f32_e32 v131, v131, v190
	v_add_f32_e32 v254, v129, v254
	v_exp_f32_e32 v131, v131
	s_waitcnt lgkmcnt(3)
	v_mfma_f32_32x32x16_bf16 v[222:237], v[206:209], v[160:163], v[222:237]
	ds_read_b64_tr_b16 v[206:207], v205
	ds_read_b64_tr_b16 v[208:209], v205 offset:4096
	v_sub_f32_e32 v132, v132, v190
	v_add_f32_e32 v254, v130, v254
	v_exp_f32_e32 v132, v132
	v_sub_f32_e32 v133, v133, v190
	v_add_f32_e32 v254, v131, v254
	s_waitcnt lgkmcnt(4)
	v_mfma_f32_32x32x16_bf16 v[222:237], v[210:213], v[164:167], v[222:237]
	ds_read_b64_tr_b16 v[210:211], v218
	ds_read_b64_tr_b16 v[212:213], v218 offset:4096
	v_exp_f32_e32 v133, v133
	v_sub_f32_e32 v134, v134, v190
	v_add_f32_e32 v254, v132, v254
	v_exp_f32_e32 v134, v134
	s_waitcnt lgkmcnt(5)
	v_mfma_f32_32x32x16_bf16 v[222:237], v[214:217], v[168:171], v[222:237]
	ds_read_b64_tr_b16 v[214:215], v219
	ds_read_b64_tr_b16 v[216:217], v219 offset:4096
	v_sub_f32_e32 v135, v135, v190
	v_add_f32_e32 v254, v133, v254
	v_exp_f32_e32 v135, v135
	s_nop 0
	s_waitcnt lgkmcnt(6)
	v_mfma_f32_32x32x16_bf16 v[222:237], v[238:241], v[172:175], v[222:237]
	ds_read_b64_tr_b16 v[238:239], v221
	ds_read_b64_tr_b16 v[240:241], v221 offset:4096
	v_cvt_pk_bf16_f32 v242, v128, v129
	v_cvt_pk_bf16_f32 v243, v130, v131
	v_cvt_pk_bf16_f32 v244, v132, v133
	v_cvt_pk_bf16_f32 v245, v134, v135
	s_nop 1
	s_waitcnt lgkmcnt(6)
	v_mfma_f32_32x32x16_bf16 v[112:127], v[206:209], v[242:245], v[112:127]
	ds_read_b64_tr_b16 v[206:207], v205 offset:256
	ds_read_b64_tr_b16 v[208:209], v205 offset:4352
	v_sub_f32_e32 v136, v136, v190
	v_add_f32_e32 v254, v134, v254
	v_exp_f32_e32 v136, v136
	v_sub_f32_e32 v137, v137, v190
	v_add_f32_e32 v254, v135, v254
	s_waitcnt lgkmcnt(6)
	v_mfma_f32_32x32x16_bf16 v[96:111], v[210:213], v[242:245], v[96:111]
	ds_read_b64_tr_b16 v[210:211], v218 offset:256
	ds_read_b64_tr_b16 v[212:213], v218 offset:4352
	v_exp_f32_e32 v137, v137
	v_sub_f32_e32 v138, v138, v190
	v_add_f32_e32 v254, v136, v254
	v_exp_f32_e32 v138, v138
	v_sub_f32_e32 v139, v139, v190
	s_waitcnt lgkmcnt(6)
	v_mfma_f32_32x32x16_bf16 v[80:95], v[214:217], v[242:245], v[80:95]
	ds_read_b64_tr_b16 v[214:215], v219 offset:256
	ds_read_b64_tr_b16 v[216:217], v219 offset:4352
	v_add_f32_e32 v254, v137, v254
	v_exp_f32_e32 v139, v139
	v_sub_f32_e32 v140, v140, v190
	v_add_f32_e32 v254, v138, v254
	s_waitcnt lgkmcnt(6)
	v_mfma_f32_32x32x16_bf16 v[64:79], v[238:241], v[242:245], v[64:79]
	ds_read_b64_tr_b16 v[238:239], v221 offset:256
	ds_read_b64_tr_b16 v[240:241], v221 offset:4352
	v_exp_f32_e32 v140, v140
	v_sub_f32_e32 v141, v141, v190
	v_add_f32_e32 v254, v139, v254
	v_exp_f32_e32 v141, v141
	s_waitcnt lgkmcnt(6)
	v_mfma_f32_32x32x16_bf16 v[48:63], v[206:209], v[242:245], v[48:63]
	ds_read_b64_tr_b16 v[206:207], v205 offset:8192
	ds_read_b64_tr_b16 v[208:209], v205 offset:12288
	v_sub_f32_e32 v142, v142, v190
	v_add_f32_e32 v254, v140, v254
	v_exp_f32_e32 v142, v142
	v_sub_f32_e32 v143, v143, v190
	s_waitcnt lgkmcnt(6)
	v_mfma_f32_32x32x16_bf16 v[32:47], v[210:213], v[242:245], v[32:47]
	ds_read_b64_tr_b16 v[210:211], v218 offset:8192
	ds_read_b64_tr_b16 v[212:213], v218 offset:12288
	v_add_f32_e32 v254, v141, v254
	v_exp_f32_e32 v143, v143
	v_add_f32_e32 v254, v142, v254
	v_add_f32_e32 v254, v143, v254
	s_waitcnt lgkmcnt(6)
	v_mfma_f32_32x32x16_bf16 v[16:31], v[214:217], v[242:245], v[16:31]
	ds_read_b64_tr_b16 v[214:215], v219 offset:8192
	ds_read_b64_tr_b16 v[216:217], v219 offset:12288
	v_cvt_pk_bf16_f32 v250, v136, v137
	v_cvt_pk_bf16_f32 v251, v138, v139
	v_cvt_pk_bf16_f32 v252, v140, v141
	v_cvt_pk_bf16_f32 v253, v142, v143
	v_add_f32_e32 v195, v195, v254
	s_waitcnt lgkmcnt(6)
	v_mfma_f32_32x32x16_bf16 v[0:15], v[238:241], v[242:245], v[0:15]
	ds_read_b64_tr_b16 v[238:239], v221 offset:8192
	ds_read_b64_tr_b16 v[240:241], v221 offset:12288
	ds_read_b64_tr_b16 v[128:129], v205 offset:8448
	ds_read_b64_tr_b16 v[130:131], v205 offset:12544
	s_waitcnt lgkmcnt(8)
	v_mfma_f32_32x32x16_bf16 v[112:127], v[206:209], v[250:253], v[112:127]
	ds_read_b64_tr_b16 v[206:207], v218 offset:8448
	ds_read_b64_tr_b16 v[208:209], v218 offset:12544
	v_max3_f32 v246, v222, v223, v224
	v_max3_f32 v247, v225, v226, v227
	v_max3_f32 v246, v246, v228, v229
	v_max3_f32 v247, v247, v230, v231
	v_max3_f32 v246, v246, v232, v233
	s_waitcnt lgkmcnt(8)
	v_mfma_f32_32x32x16_bf16 v[96:111], v[210:213], v[250:253], v[96:111]
	ds_read_b64_tr_b16 v[210:211], v219 offset:8448
	ds_read_b64_tr_b16 v[212:213], v219 offset:12544
	v_max3_f32 v247, v247, v234, v235
	v_max3_f32 v246, v246, v236, v237
	v_max_f32_e32 v246, v246, v247
	v_mov_b32_e32 v247, v246
	v_add_f32_e32 v249, 0x41000000, v190
	s_waitcnt lgkmcnt(8)
	v_mfma_f32_32x32x16_bf16 v[80:95], v[214:217], v[250:253], v[80:95]
	ds_read_b64_tr_b16 v[214:215], v221 offset:8448
	ds_read_b64_tr_b16 v[216:217], v221 offset:12544
	s_nop 1
	v_permlane32_swap_b32_e32 v246, v247
	v_max_f32_e32 v246, v246, v247
	v_cmp_gt_f32_e32 vcc, v246, v249
	s_cbranch_vccnz .Latt_rs1_5s1
	s_waitcnt lgkmcnt(8)
	v_mfma_f32_32x32x16_bf16 v[64:79], v[238:241], v[250:253], v[64:79]
	ds_read_b64_tr_b16 v[238:239], v205 offset:16384
	ds_read_b64_tr_b16 v[240:241], v205 offset:20480
	v_sub_f32_e32 v222, v222, v190
	v_exp_f32_e32 v222, v222
	v_sub_f32_e32 v223, v223, v190
	v_exp_f32_e32 v223, v223
	v_sub_f32_e32 v224, v224, v190
	v_add_f32_e32 v254, 0, v222
	s_waitcnt lgkmcnt(8)
	v_mfma_f32_32x32x16_bf16 v[48:63], v[128:131], v[250:253], v[48:63]
	ds_read_b64_tr_b16 v[128:129], v218 offset:16384
	ds_read_b64_tr_b16 v[130:131], v218 offset:20480
	v_exp_f32_e32 v224, v224
	v_sub_f32_e32 v225, v225, v190
	v_add_f32_e32 v254, v223, v254
	v_exp_f32_e32 v225, v225
	v_sub_f32_e32 v226, v226, v190
	v_add_f32_e32 v254, v224, v254
	s_waitcnt lgkmcnt(8)
	v_mfma_f32_32x32x16_bf16 v[32:47], v[206:209], v[250:253], v[32:47]
	ds_read_b64_tr_b16 v[206:207], v219 offset:16384
	ds_read_b64_tr_b16 v[208:209], v219 offset:20480
	v_exp_f32_e32 v226, v226
	v_sub_f32_e32 v227, v227, v190
	v_add_f32_e32 v254, v225, v254
	v_exp_f32_e32 v227, v227
	v_sub_f32_e32 v228, v228, v190
	s_waitcnt lgkmcnt(8)
	v_mfma_f32_32x32x16_bf16 v[16:31], v[210:213], v[250:253], v[16:31]
	ds_read_b64_tr_b16 v[210:211], v221 offset:16384
	ds_read_b64_tr_b16 v[212:213], v221 offset:20480
	v_add_f32_e32 v254, v226, v254
	v_exp_f32_e32 v228, v228
	v_sub_f32_e32 v229, v229, v190
	v_add_f32_e32 v254, v227, v254
	v_exp_f32_e32 v229, v229
	s_waitcnt lgkmcnt(8)
	v_mfma_f32_32x32x16_bf16 v[0:15], v[214:217], v[250:253], v[0:15]
	ds_read_b64_tr_b16 v[214:215], v205 offset:16640
	ds_read_b64_tr_b16 v[216:217], v205 offset:20736
	s_nop 0
	v_cvt_pk_bf16_f32 v242, v222, v223
	v_cvt_pk_bf16_f32 v243, v224, v225
	v_cvt_pk_bf16_f32 v244, v226, v227
	v_cvt_pk_bf16_f32 v245, v228, v229
	s_nop 1
	s_waitcnt lgkmcnt(8)
	v_mfma_f32_32x32x16_bf16 v[112:127], v[238:241], v[242:245], v[112:127]
	ds_read_b64_tr_b16 v[238:239], v218 offset:16640
	ds_read_b64_tr_b16 v[240:241], v218 offset:20736
	v_sub_f32_e32 v230, v230, v190
	v_add_f32_e32 v254, v228, v254
	v_exp_f32_e32 v230, v230
	v_sub_f32_e32 v231, v231, v190
	v_add_f32_e32 v254, v229, v254
	s_waitcnt lgkmcnt(8)
	v_mfma_f32_32x32x16_bf16 v[96:111], v[128:131], v[242:245], v[96:111]
	ds_read_b64_tr_b16 v[128:129], v219 offset:16640
	ds_read_b64_tr_b16 v[130:131], v219 offset:20736
	v_exp_f32_e32 v231, v231
	v_sub_f32_e32 v232, v232, v190
	v_add_f32_e32 v254, v230, v254
	v_exp_f32_e32 v232, v232
	v_sub_f32_e32 v233, v233, v190
	s_waitcnt lgkmcnt(8)
	v_mfma_f32_32x32x16_bf16 v[80:95], v[206:209], v[242:245], v[80:95]
	ds_read_b64_tr_b16 v[206:207], v221 offset:16640
	ds_read_b64_tr_b16 v[208:209], v221 offset:20736
	v_add_f32_e32 v254, v231, v254
	v_exp_f32_e32 v233, v233
	v_sub_f32_e32 v234, v234, v190
	v_add_f32_e32 v254, v232, v254
	s_waitcnt lgkmcnt(8)
	v_mfma_f32_32x32x16_bf16 v[64:79], v[210:213], v[242:245], v[64:79]
	ds_read_b64_tr_b16 v[210:211], v205 offset:24576
	ds_read_b64_tr_b16 v[212:213], v205 offset:28672
	v_exp_f32_e32 v234, v234
	v_sub_f32_e32 v235, v235, v190
	v_add_f32_e32 v254, v233, v254
	v_exp_f32_e32 v235, v235
	s_waitcnt lgkmcnt(8)
	v_mfma_f32_32x32x16_bf16 v[48:63], v[214:217], v[242:245], v[48:63]
	ds_read_b64_tr_b16 v[214:215], v218 offset:24576
	ds_read_b64_tr_b16 v[216:217], v218 offset:28672
	v_sub_f32_e32 v236, v236, v190
	v_add_f32_e32 v254, v234, v254
	v_exp_f32_e32 v236, v236
	v_sub_f32_e32 v237, v237, v190
	s_waitcnt lgkmcnt(8)
	v_mfma_f32_32x32x16_bf16 v[32:47], v[238:241], v[242:245], v[32:47]
	ds_read_b64_tr_b16 v[238:239], v219 offset:24576
	ds_read_b64_tr_b16 v[240:241], v219 offset:28672
	v_add_f32_e32 v254, v235, v254
	v_exp_f32_e32 v237, v237
	v_add_f32_e32 v254, v236, v254
	v_add_f32_e32 v254, v237, v254
	s_waitcnt lgkmcnt(8)
	v_mfma_f32_32x32x16_bf16 v[16:31], v[128:131], v[242:245], v[16:31]
	ds_read_b64_tr_b16 v[128:129], v221 offset:24576
	ds_read_b64_tr_b16 v[130:131], v221 offset:28672
	v_cvt_pk_bf16_f32 v250, v230, v231
	v_cvt_pk_bf16_f32 v251, v232, v233
	v_cvt_pk_bf16_f32 v252, v234, v235
	v_cvt_pk_bf16_f32 v253, v236, v237
	v_add_f32_e32 v195, v195, v254
	s_waitcnt lgkmcnt(8)
	v_mfma_f32_32x32x16_bf16 v[0:15], v[206:209], v[242:245], v[0:15]
	ds_read_b64_tr_b16 v[206:207], v205 offset:24832
	ds_read_b64_tr_b16 v[208:209], v205 offset:28928
	s_waitcnt lgkmcnt(8)
	v_mfma_f32_32x32x16_bf16 v[112:127], v[210:213], v[250:253], v[112:127]
	ds_read_b64_tr_b16 v[210:211], v218 offset:24832
	ds_read_b64_tr_b16 v[212:213], v218 offset:28928
	s_waitcnt lgkmcnt(8)
	v_mfma_f32_32x32x16_bf16 v[96:111], v[214:217], v[250:253], v[96:111]
	ds_read_b64_tr_b16 v[214:215], v219 offset:24832
	ds_read_b64_tr_b16 v[216:217], v219 offset:28928
	s_waitcnt lgkmcnt(8)
	v_mfma_f32_32x32x16_bf16 v[80:95], v[238:241], v[250:253], v[80:95]
	ds_read_b64_tr_b16 v[238:239], v221 offset:24832
	ds_read_b64_tr_b16 v[240:241], v221 offset:28928
	s_waitcnt lgkmcnt(8)
	v_mfma_f32_32x32x16_bf16 v[64:79], v[128:131], v[250:253], v[64:79]
	s_waitcnt lgkmcnt(6)
	v_mfma_f32_32x32x16_bf16 v[48:63], v[206:209], v[250:253], v[48:63]
	s_waitcnt lgkmcnt(4)
	v_mfma_f32_32x32x16_bf16 v[32:47], v[210:213], v[250:253], v[32:47]
	s_waitcnt lgkmcnt(2)
	v_mfma_f32_32x32x16_bf16 v[16:31], v[214:217], v[250:253], v[16:31]
	s_waitcnt lgkmcnt(0)
	v_mfma_f32_32x32x16_bf16 v[0:15], v[238:241], v[250:253], v[0:15]
	ds_read_b128 v[206:209], v196 offset:32768
	ds_read_b128 v[210:213], v197 offset:32768
	ds_read_b128 v[214:217], v198 offset:32768
	ds_read_b128 v[238:241], v199 offset:32768
	ds_read_b128 v[242:245], v200 offset:32768
	ds_read_b128 v[250:253], v201 offset:32768
	ds_read_b128 v[222:225], v202 offset:32768
	ds_read_b128 v[226:229], v203 offset:32768
	s_waitcnt vmcnt(0)
	s_add_i32 s18, s33, 1
	s_cmp_lg_u32 s33, 2
	s_cselect_b32 s33, s18, 0
	s_add_i32 s4, s4, 64
	s_add_u32 s12, s12, 0x100000
	s_addc_u32 s13, s13, 0
	s_add_i32 s76, s76, 1
	s_add_i32 s100, s4, 63
	s_cmp_le_i32 s100, s71
	s_cbranch_scc0 .Latt_latchb_5
	s_cmp_ge_u32 s76, s70
	s_cselect_b64 s[18:19], -1, 0
	v_mov_b32_e32 v204, v176
	s_barrier
	s_branch .Latt_cont_5s2
.Latt_rs1_5s1:
	s_waitcnt lgkmcnt(8)
	v_mfma_f32_32x32x16_bf16 v[64:79], v[238:241], v[250:253], v[64:79]
	ds_read_b64_tr_b16 v[238:239], v205 offset:16384
	ds_read_b64_tr_b16 v[240:241], v205 offset:20480
	s_waitcnt lgkmcnt(8)
	v_mfma_f32_32x32x16_bf16 v[48:63], v[128:131], v[250:253], v[48:63]
	ds_read_b64_tr_b16 v[128:129], v218 offset:16384
	ds_read_b64_tr_b16 v[130:131], v218 offset:20480
	s_waitcnt lgkmcnt(8)
	v_mfma_f32_32x32x16_bf16 v[32:47], v[206:209], v[250:253], v[32:47]
	ds_read_b64_tr_b16 v[206:207], v219 offset:16384
	ds_read_b64_tr_b16 v[208:209], v219 offset:20480
	s_waitcnt lgkmcnt(8)
	v_mfma_f32_32x32x16_bf16 v[16:31], v[210:213], v[250:253], v[16:31]
	ds_read_b64_tr_b16 v[210:211], v221 offset:16384
	ds_read_b64_tr_b16 v[212:213], v221 offset:20480
	s_waitcnt lgkmcnt(8)
	v_mfma_f32_32x32x16_bf16 v[0:15], v[214:217], v[250:253], v[0:15]
	ds_read_b64_tr_b16 v[214:215], v205 offset:16640
	ds_read_b64_tr_b16 v[216:217], v205 offset:20736
	s_nop 11
	v_max_f32_e32 v246, v190, v246
	v_sub_f32_e32 v190, v190, v246
	v_exp_f32_e32 v190, v190
	s_nop 0
	v_pk_mul_f32 v[126:127], v[126:127], v[190:191] op_sel_hi:[1,0]
	v_pk_mul_f32 v[124:125], v[124:125], v[190:191] op_sel_hi:[1,0]
	v_pk_mul_f32 v[122:123], v[122:123], v[190:191] op_sel_hi:[1,0]
	v_pk_mul_f32 v[120:121], v[120:121], v[190:191] op_sel_hi:[1,0]
	v_pk_mul_f32 v[118:119], v[118:119], v[190:191] op_sel_hi:[1,0]
	v_pk_mul_f32 v[116:117], v[116:117], v[190:191] op_sel_hi:[1,0]
	v_pk_mul_f32 v[114:115], v[114:115], v[190:191] op_sel_hi:[1,0]
	v_pk_mul_f32 v[112:113], v[112:113], v[190:191] op_sel_hi:[1,0]
	v_pk_mul_f32 v[110:111], v[110:111], v[190:191] op_sel_hi:[1,0]
	v_pk_mul_f32 v[108:109], v[108:109], v[190:191] op_sel_hi:[1,0]
	v_pk_mul_f32 v[106:107], v[106:107], v[190:191] op_sel_hi:[1,0]
	v_pk_mul_f32 v[104:105], v[104:105], v[190:191] op_sel_hi:[1,0]
	v_pk_mul_f32 v[102:103], v[102:103], v[190:191] op_sel_hi:[1,0]
	v_pk_mul_f32 v[100:101], v[100:101], v[190:191] op_sel_hi:[1,0]
	v_pk_mul_f32 v[98:99], v[98:99], v[190:191] op_sel_hi:[1,0]
	v_pk_mul_f32 v[96:97], v[96:97], v[190:191] op_sel_hi:[1,0]
	v_pk_mul_f32 v[94:95], v[94:95], v[190:191] op_sel_hi:[1,0]
	v_pk_mul_f32 v[92:93], v[92:93], v[190:191] op_sel_hi:[1,0]
	v_pk_mul_f32 v[90:91], v[90:91], v[190:191] op_sel_hi:[1,0]
	v_pk_mul_f32 v[88:89], v[88:89], v[190:191] op_sel_hi:[1,0]
	v_pk_mul_f32 v[86:87], v[86:87], v[190:191] op_sel_hi:[1,0]
	v_pk_mul_f32 v[84:85], v[84:85], v[190:191] op_sel_hi:[1,0]
	v_pk_mul_f32 v[82:83], v[82:83], v[190:191] op_sel_hi:[1,0]
	v_pk_mul_f32 v[80:81], v[80:81], v[190:191] op_sel_hi:[1,0]
	v_pk_mul_f32 v[78:79], v[78:79], v[190:191] op_sel_hi:[1,0]
	v_pk_mul_f32 v[76:77], v[76:77], v[190:191] op_sel_hi:[1,0]
	v_pk_mul_f32 v[74:75], v[74:75], v[190:191] op_sel_hi:[1,0]
	v_pk_mul_f32 v[72:73], v[72:73], v[190:191] op_sel_hi:[1,0]
	v_pk_mul_f32 v[70:71], v[70:71], v[190:191] op_sel_hi:[1,0]
	v_pk_mul_f32 v[68:69], v[68:69], v[190:191] op_sel_hi:[1,0]
	v_pk_mul_f32 v[66:67], v[66:67], v[190:191] op_sel_hi:[1,0]
	v_pk_mul_f32 v[64:65], v[64:65], v[190:191] op_sel_hi:[1,0]
	v_pk_mul_f32 v[62:63], v[62:63], v[190:191] op_sel_hi:[1,0]
	v_pk_mul_f32 v[60:61], v[60:61], v[190:191] op_sel_hi:[1,0]
	v_pk_mul_f32 v[58:59], v[58:59], v[190:191] op_sel_hi:[1,0]
	v_pk_mul_f32 v[56:57], v[56:57], v[190:191] op_sel_hi:[1,0]
	v_pk_mul_f32 v[54:55], v[54:55], v[190:191] op_sel_hi:[1,0]
	v_pk_mul_f32 v[52:53], v[52:53], v[190:191] op_sel_hi:[1,0]
	v_pk_mul_f32 v[50:51], v[50:51], v[190:191] op_sel_hi:[1,0]
	v_pk_mul_f32 v[48:49], v[48:49], v[190:191] op_sel_hi:[1,0]
	v_pk_mul_f32 v[46:47], v[46:47], v[190:191] op_sel_hi:[1,0]
	v_pk_mul_f32 v[44:45], v[44:45], v[190:191] op_sel_hi:[1,0]
	v_pk_mul_f32 v[42:43], v[42:43], v[190:191] op_sel_hi:[1,0]
	v_pk_mul_f32 v[40:41], v[40:41], v[190:191] op_sel_hi:[1,0]
	v_pk_mul_f32 v[38:39], v[38:39], v[190:191] op_sel_hi:[1,0]
	v_pk_mul_f32 v[36:37], v[36:37], v[190:191] op_sel_hi:[1,0]
	v_pk_mul_f32 v[34:35], v[34:35], v[190:191] op_sel_hi:[1,0]
	v_pk_mul_f32 v[32:33], v[32:33], v[190:191] op_sel_hi:[1,0]
	v_pk_mul_f32 v[30:31], v[30:31], v[190:191] op_sel_hi:[1,0]
	v_pk_mul_f32 v[28:29], v[28:29], v[190:191] op_sel_hi:[1,0]
	v_pk_mul_f32 v[26:27], v[26:27], v[190:191] op_sel_hi:[1,0]
	v_pk_mul_f32 v[24:25], v[24:25], v[190:191] op_sel_hi:[1,0]
	v_pk_mul_f32 v[22:23], v[22:23], v[190:191] op_sel_hi:[1,0]
	v_pk_mul_f32 v[20:21], v[20:21], v[190:191] op_sel_hi:[1,0]
	v_pk_mul_f32 v[18:19], v[18:19], v[190:191] op_sel_hi:[1,0]
	v_pk_mul_f32 v[16:17], v[16:17], v[190:191] op_sel_hi:[1,0]
	v_pk_mul_f32 v[14:15], v[14:15], v[190:191] op_sel_hi:[1,0]
	v_pk_mul_f32 v[12:13], v[12:13], v[190:191] op_sel_hi:[1,0]
	v_pk_mul_f32 v[10:11], v[10:11], v[190:191] op_sel_hi:[1,0]
	v_pk_mul_f32 v[8:9], v[8:9], v[190:191] op_sel_hi:[1,0]
	v_pk_mul_f32 v[6:7], v[6:7], v[190:191] op_sel_hi:[1,0]
	v_pk_mul_f32 v[4:5], v[4:5], v[190:191] op_sel_hi:[1,0]
	v_pk_mul_f32 v[2:3], v[2:3], v[190:191] op_sel_hi:[1,0]
	v_pk_mul_f32 v[0:1], v[0:1], v[190:191] op_sel_hi:[1,0]
	v_mul_f32_e32 v195, v195, v190
	v_mov_b32_e32 v190, v246
	v_sub_f32_e32 v222, v222, v190
	v_exp_f32_e32 v222, v222
	v_sub_f32_e32 v223, v223, v190
	v_exp_f32_e32 v223, v223
	v_sub_f32_e32 v224, v224, v190
	v_add_f32_e32 v254, 0, v222
	v_exp_f32_e32 v224, v224
	v_sub_f32_e32 v225, v225, v190
	v_add_f32_e32 v254, v223, v254
	v_exp_f32_e32 v225, v225
	v_sub_f32_e32 v226, v226, v190
	v_add_f32_e32 v254, v224, v254
	v_exp_f32_e32 v226, v226
	v_sub_f32_e32 v227, v227, v190
	v_add_f32_e32 v254, v225, v254
	v_exp_f32_e32 v227, v227
	v_sub_f32_e32 v228, v228, v190
	v_add_f32_e32 v254, v226, v254
	v_exp_f32_e32 v228, v228
	v_sub_f32_e32 v229, v229, v190
	v_add_f32_e32 v254, v227, v254
	v_exp_f32_e32 v229, v229
	v_sub_f32_e32 v230, v230, v190
	v_add_f32_e32 v254, v228, v254
	v_exp_f32_e32 v230, v230
	v_sub_f32_e32 v231, v231, v190
	v_add_f32_e32 v254, v229, v254
	v_exp_f32_e32 v231, v231
	v_sub_f32_e32 v232, v232, v190
	v_add_f32_e32 v254, v230, v254
	v_exp_f32_e32 v232, v232
	v_sub_f32_e32 v233, v233, v190
	v_add_f32_e32 v254, v231, v254
	v_exp_f32_e32 v233, v233
	v_sub_f32_e32 v234, v234, v190
	v_add_f32_e32 v254, v232, v254
	v_exp_f32_e32 v234, v234
	v_sub_f32_e32 v235, v235, v190
	v_add_f32_e32 v254, v233, v254
	v_exp_f32_e32 v235, v235
	v_sub_f32_e32 v236, v236, v190
	v_add_f32_e32 v254, v234, v254
	v_exp_f32_e32 v236, v236
	v_sub_f32_e32 v237, v237, v190
	v_add_f32_e32 v254, v235, v254
	v_exp_f32_e32 v237, v237
	v_add_f32_e32 v254, v236, v254
	v_add_f32_e32 v254, v237, v254
	v_cvt_pk_bf16_f32 v242, v222, v223
	v_cvt_pk_bf16_f32 v243, v224, v225
	v_cvt_pk_bf16_f32 v244, v226, v227
	v_cvt_pk_bf16_f32 v245, v228, v229
	v_cvt_pk_bf16_f32 v250, v230, v231
	v_cvt_pk_bf16_f32 v251, v232, v233
	v_cvt_pk_bf16_f32 v252, v234, v235
	v_cvt_pk_bf16_f32 v253, v236, v237
	v_add_f32_e32 v195, v195, v254
	s_nop 1
	s_waitcnt lgkmcnt(8)
	v_mfma_f32_32x32x16_bf16 v[112:127], v[238:241], v[242:245], v[112:127]
	ds_read_b64_tr_b16 v[238:239], v218 offset:16640
	ds_read_b64_tr_b16 v[240:241], v218 offset:20736
	s_waitcnt lgkmcnt(8)
	v_mfma_f32_32x32x16_bf16 v[96:111], v[128:131], v[242:245], v[96:111]
	ds_read_b64_tr_b16 v[222:223], v219 offset:16640
	ds_read_b64_tr_b16 v[224:225], v219 offset:20736
	s_waitcnt lgkmcnt(8)
	v_mfma_f32_32x32x16_bf16 v[80:95], v[206:209], v[242:245], v[80:95]
	ds_read_b64_tr_b16 v[206:207], v221 offset:16640
	ds_read_b64_tr_b16 v[208:209], v221 offset:20736
	s_waitcnt lgkmcnt(8)
	v_mfma_f32_32x32x16_bf16 v[64:79], v[210:213], v[242:245], v[64:79]
	ds_read_b64_tr_b16 v[210:211], v205 offset:24576
	ds_read_b64_tr_b16 v[212:213], v205 offset:28672
	s_waitcnt lgkmcnt(8)
	v_mfma_f32_32x32x16_bf16 v[48:63], v[214:217], v[242:245], v[48:63]
	ds_read_b64_tr_b16 v[214:215], v218 offset:24576
	ds_read_b64_tr_b16 v[216:217], v218 offset:28672
	s_waitcnt lgkmcnt(8)
	v_mfma_f32_32x32x16_bf16 v[32:47], v[238:241], v[242:245], v[32:47]
	ds_read_b64_tr_b16 v[238:239], v219 offset:24576
	ds_read_b64_tr_b16 v[240:241], v219 offset:28672
	s_waitcnt lgkmcnt(8)
	v_mfma_f32_32x32x16_bf16 v[16:31], v[222:225], v[242:245], v[16:31]
	ds_read_b64_tr_b16 v[222:223], v221 offset:24576
	ds_read_b64_tr_b16 v[224:225], v221 offset:28672
	s_waitcnt lgkmcnt(8)
	v_mfma_f32_32x32x16_bf16 v[0:15], v[206:209], v[242:245], v[0:15]
	ds_read_b64_tr_b16 v[206:207], v205 offset:24832
	ds_read_b64_tr_b16 v[208:209], v205 offset:28928
	s_waitcnt lgkmcnt(8)
	v_mfma_f32_32x32x16_bf16 v[112:127], v[210:213], v[250:253], v[112:127]
	ds_read_b64_tr_b16 v[210:211], v218 offset:24832
	ds_read_b64_tr_b16 v[212:213], v218 offset:28928
	s_waitcnt lgkmcnt(8)
	v_mfma_f32_32x32x16_bf16 v[96:111], v[214:217], v[250:253], v[96:111]
	ds_read_b64_tr_b16 v[214:215], v219 offset:24832
	ds_read_b64_tr_b16 v[216:217], v219 offset:28928
	s_waitcnt lgkmcnt(8)
	v_mfma_f32_32x32x16_bf16 v[80:95], v[238:241], v[250:253], v[80:95]
	ds_read_b64_tr_b16 v[238:239], v221 offset:24832
	ds_read_b64_tr_b16 v[240:241], v221 offset:28928
	s_waitcnt lgkmcnt(8)
	v_mfma_f32_32x32x16_bf16 v[64:79], v[222:225], v[250:253], v[64:79]
	s_waitcnt lgkmcnt(6)
	v_mfma_f32_32x32x16_bf16 v[48:63], v[206:209], v[250:253], v[48:63]
	s_waitcnt lgkmcnt(4)
	v_mfma_f32_32x32x16_bf16 v[32:47], v[210:213], v[250:253], v[32:47]
	s_waitcnt lgkmcnt(2)
	v_mfma_f32_32x32x16_bf16 v[16:31], v[214:217], v[250:253], v[16:31]
	s_waitcnt lgkmcnt(0)
	v_mfma_f32_32x32x16_bf16 v[0:15], v[238:241], v[250:253], v[0:15]
	ds_read_b128 v[206:209], v196 offset:32768
	ds_read_b128 v[210:213], v197 offset:32768
	ds_read_b128 v[214:217], v198 offset:32768
	ds_read_b128 v[238:241], v199 offset:32768
	ds_read_b128 v[242:245], v200 offset:32768
	ds_read_b128 v[250:253], v201 offset:32768
	ds_read_b128 v[222:225], v202 offset:32768
	ds_read_b128 v[226:229], v203 offset:32768
	s_waitcnt vmcnt(0)
	s_add_i32 s18, s33, 1
	s_cmp_lg_u32 s33, 2
	s_cselect_b32 s33, s18, 0
	s_add_i32 s4, s4, 64
	s_add_u32 s12, s12, 0x100000
	s_addc_u32 s13, s13, 0
	s_add_i32 s76, s76, 1
	s_add_i32 s100, s4, 63
	s_cmp_le_i32 s100, s71
	s_cbranch_scc0 .Latt_latchb_5
	s_cmp_ge_u32 s76, s70
	s_cselect_b64 s[18:19], -1, 0
	v_mov_b32_e32 v204, v176
	s_barrier
	s_branch .Latt_cont_5s2
.Latt_slow_5s1:
.Latt_slot2_5:
.Latt_cont_5s2:
	v_add_u32_e32 v205, 0x8000, v205
	v_add_u32_e32 v218, 0x8000, v218
	v_add_u32_e32 v219, 0x8000, v219
	v_add_u32_e32 v221, 0x8000, v221
	s_waitcnt lgkmcnt(7)
	v_mfma_f32_32x32x16_bf16 v[128:143], v[206:209], v[144:147], 0
	ds_read_b128 v[206:209], v196 offset:40960
	s_cmp_lg_u64 s[18:19], 0
	s_cbranch_scc1 .Latt_nd0_5s2
	s_sub_i32 s100, s33, 1
	s_cmp_eq_u32 s33, 0
	s_cselect_b32 s100, 2, s100
	s_lshl_b32 s101, s100, 14
	s_add_i32 m0, s73, s101
	s_nop 0
	global_load_lds_dwordx4 v178, s[12:13]

.Latt_nr0_5s2:
	s_waitcnt lgkmcnt(3)
	v_mfma_f32_32x32x16_bf16 v[222:237], v[214:217], v[152:155], v[222:237]
	ds_read_b128 v[214:217], v202 offset:40960
	v_sub_f32_e32 v128, v128, v190
	v_exp_f32_e32 v128, v128
	v_sub_f32_e32 v129, v129, v190
	v_exp_f32_e32 v129, v129
	v_sub_f32_e32 v130, v130, v190
	s_waitcnt lgkmcnt(3)
	v_mfma_f32_32x32x16_bf16 v[222:237], v[238:241], v[156:159], v[222:237]
	ds_read_b128 v[238:241], v203 offset:40960
	v_add_f32_e32 v254, 0, v128
	v_exp_f32_e32 v130, v130
	v_sub_f32_e32 v131, v131, v190
	v_add_f32_e32 v254, v129, v254
	v_exp_f32_e32 v131, v131
	s_waitcnt lgkmcnt(3)
	v_mfma_f32_32x32x16_bf16 v[222:237], v[206:209], v[160:163], v[222:237]
	ds_read_b64_tr_b16 v[206:207], v205
	ds_read_b64_tr_b16 v[208:209], v205 offset:4096
	v_sub_f32_e32 v132, v132, v190
	v_add_f32_e32 v254, v130, v254
	v_exp_f32_e32 v132, v132
	v_sub_f32_e32 v133, v133, v190
	v_add_f32_e32 v254, v131, v254
	s_waitcnt lgkmcnt(4)
	v_mfma_f32_32x32x16_bf16 v[222:237], v[210:213], v[164:167], v[222:237]
	ds_read_b64_tr_b16 v[210:211], v218
	ds_read_b64_tr_b16 v[212:213], v218 offset:4096
	v_exp_f32_e32 v133, v133
	v_sub_f32_e32 v134, v134, v190
	v_add_f32_e32 v254, v132, v254
	v_exp_f32_e32 v134, v134
	s_waitcnt lgkmcnt(5)
	v_mfma_f32_32x32x16_bf16 v[222:237], v[214:217], v[168:171], v[222:237]
	ds_read_b64_tr_b16 v[214:215], v219
	ds_read_b64_tr_b16 v[216:217], v219 offset:4096
	v_sub_f32_e32 v135, v135, v190
	v_add_f32_e32 v254, v133, v254
	v_exp_f32_e32 v135, v135
	s_nop 0
	s_waitcnt lgkmcnt(6)
	v_mfma_f32_32x32x16_bf16 v[222:237], v[238:241], v[172:175], v[222:237]
	ds_read_b64_tr_b16 v[238:239], v221
	ds_read_b64_tr_b16 v[240:241], v221 offset:4096
	v_cvt_pk_bf16_f32 v242, v128, v129
	v_cvt_pk_bf16_f32 v243, v130, v131
	v_cvt_pk_bf16_f32 v244, v132, v133
	v_cvt_pk_bf16_f32 v245, v134, v135
	s_nop 1
	s_waitcnt lgkmcnt(6)
	v_mfma_f32_32x32x16_bf16 v[112:127], v[206:209], v[242:245], v[112:127]
	ds_read_b64_tr_b16 v[206:207], v205 offset:256
	ds_read_b64_tr_b16 v[208:209], v205 offset:4352
	v_sub_f32_e32 v136, v136, v190
	v_add_f32_e32 v254, v134, v254
	v_exp_f32_e32 v136, v136
	v_sub_f32_e32 v137, v137, v190
	v_add_f32_e32 v254, v135, v254
	s_waitcnt lgkmcnt(6)
	v_mfma_f32_32x32x16_bf16 v[96:111], v[210:213], v[242:245], v[96:111]
	ds_read_b64_tr_b16 v[210:211], v218 offset:256
	ds_read_b64_tr_b16 v[212:213], v218 offset:4352
	v_exp_f32_e32 v137, v137
	v_sub_f32_e32 v138, v138, v190
	v_add_f32_e32 v254, v136, v254
	v_exp_f32_e32 v138, v138
	v_sub_f32_e32 v139, v139, v190
	s_waitcnt lgkmcnt(6)
	v_mfma_f32_32x32x16_bf16 v[80:95], v[214:217], v[242:245], v[80:95]
	ds_read_b64_tr_b16 v[214:215], v219 offset:256
	ds_read_b64_tr_b16 v[216:217], v219 offset:4352
	v_add_f32_e32 v254, v137, v254
	v_exp_f32_e32 v139, v139
	v_sub_f32_e32 v140, v140, v190
	v_add_f32_e32 v254, v138, v254
	s_waitcnt lgkmcnt(6)
	v_mfma_f32_32x32x16_bf16 v[64:79], v[238:241], v[242:245], v[64:79]
	ds_read_b64_tr_b16 v[238:239], v221 offset:256
	ds_read_b64_tr_b16 v[240:241], v221 offset:4352
	v_exp_f32_e32 v140, v140
	v_sub_f32_e32 v141, v141, v190
	v_add_f32_e32 v254, v139, v254
	v_exp_f32_e32 v141, v141
	s_waitcnt lgkmcnt(6)
	v_mfma_f32_32x32x16_bf16 v[48:63], v[206:209], v[242:245], v[48:63]
	ds_read_b64_tr_b16 v[206:207], v205 offset:8192
	ds_read_b64_tr_b16 v[208:209], v205 offset:12288
	v_sub_f32_e32 v142, v142, v190
	v_add_f32_e32 v254, v140, v254
	v_exp_f32_e32 v142, v142
	v_sub_f32_e32 v143, v143, v190
	s_waitcnt lgkmcnt(6)
	v_mfma_f32_32x32x16_bf16 v[32:47], v[210:213], v[242:245], v[32:47]
	ds_read_b64_tr_b16 v[210:211], v218 offset:8192
	ds_read_b64_tr_b16 v[212:213], v218 offset:12288
	v_add_f32_e32 v254, v141, v254
	v_exp_f32_e32 v143, v143
	v_add_f32_e32 v254, v142, v254
	v_add_f32_e32 v254, v143, v254
	s_waitcnt lgkmcnt(6)
	v_mfma_f32_32x32x16_bf16 v[16:31], v[214:217], v[242:245], v[16:31]
	ds_read_b64_tr_b16 v[214:215], v219 offset:8192
	ds_read_b64_tr_b16 v[216:217], v219 offset:12288
	v_cvt_pk_bf16_f32 v250, v136, v137
	v_cvt_pk_bf16_f32 v251, v138, v139
	v_cvt_pk_bf16_f32 v252, v140, v141
	v_cvt_pk_bf16_f32 v253, v142, v143
	v_add_f32_e32 v195, v195, v254
	s_waitcnt lgkmcnt(6)
	v_mfma_f32_32x32x16_bf16 v[0:15], v[238:241], v[242:245], v[0:15]
	ds_read_b64_tr_b16 v[238:239], v221 offset:8192
	ds_read_b64_tr_b16 v[240:241], v221 offset:12288
	ds_read_b64_tr_b16 v[128:129], v205 offset:8448
	ds_read_b64_tr_b16 v[130:131], v205 offset:12544
	s_waitcnt lgkmcnt(8)
	v_mfma_f32_32x32x16_bf16 v[112:127], v[206:209], v[250:253], v[112:127]
	ds_read_b64_tr_b16 v[206:207], v218 offset:8448
	ds_read_b64_tr_b16 v[208:209], v218 offset:12544
	v_max3_f32 v246, v222, v223, v224
	v_max3_f32 v247, v225, v226, v227
	v_max3_f32 v246, v246, v228, v229
	v_max3_f32 v247, v247, v230, v231
	v_max3_f32 v246, v246, v232, v233
	s_waitcnt lgkmcnt(8)
	v_mfma_f32_32x32x16_bf16 v[96:111], v[210:213], v[250:253], v[96:111]
	ds_read_b64_tr_b16 v[210:211], v219 offset:8448
	ds_read_b64_tr_b16 v[212:213], v219 offset:12544
	v_max3_f32 v247, v247, v234, v235
	v_max3_f32 v246, v246, v236, v237
	v_max_f32_e32 v246, v246, v247
	v_mov_b32_e32 v247, v246
	v_add_f32_e32 v249, 0x41000000, v190
	s_waitcnt lgkmcnt(8)
	v_mfma_f32_32x32x16_bf16 v[80:95], v[214:217], v[250:253], v[80:95]
	ds_read_b64_tr_b16 v[214:215], v221 offset:8448
	ds_read_b64_tr_b16 v[216:217], v221 offset:12544
	s_nop 1
	v_permlane32_swap_b32_e32 v246, v247
	v_max_f32_e32 v246, v246, v247
	v_cmp_gt_f32_e32 vcc, v246, v249
	s_cbranch_vccnz .Latt_rs1_5s2
	s_waitcnt lgkmcnt(8)
	v_mfma_f32_32x32x16_bf16 v[64:79], v[238:241], v[250:253], v[64:79]
	ds_read_b64_tr_b16 v[238:239], v205 offset:16384
	ds_read_b64_tr_b16 v[240:241], v205 offset:20480
	v_sub_f32_e32 v222, v222, v190
	v_exp_f32_e32 v222, v222
	v_sub_f32_e32 v223, v223, v190
	v_exp_f32_e32 v223, v223
	v_sub_f32_e32 v224, v224, v190
	v_add_f32_e32 v254, 0, v222
	s_waitcnt lgkmcnt(8)
	v_mfma_f32_32x32x16_bf16 v[48:63], v[128:131], v[250:253], v[48:63]
	ds_read_b64_tr_b16 v[128:129], v218 offset:16384
	ds_read_b64_tr_b16 v[130:131], v218 offset:20480
	v_exp_f32_e32 v224, v224
	v_sub_f32_e32 v225, v225, v190
	v_add_f32_e32 v254, v223, v254
	v_exp_f32_e32 v225, v225
	v_sub_f32_e32 v226, v226, v190
	v_add_f32_e32 v254, v224, v254
	s_waitcnt lgkmcnt(8)
	v_mfma_f32_32x32x16_bf16 v[32:47], v[206:209], v[250:253], v[32:47]
	ds_read_b64_tr_b16 v[206:207], v219 offset:16384
	ds_read_b64_tr_b16 v[208:209], v219 offset:20480
	v_exp_f32_e32 v226, v226
	v_sub_f32_e32 v227, v227, v190
	v_add_f32_e32 v254, v225, v254
	v_exp_f32_e32 v227, v227
	v_sub_f32_e32 v228, v228, v190
	s_waitcnt lgkmcnt(8)
	v_mfma_f32_32x32x16_bf16 v[16:31], v[210:213], v[250:253], v[16:31]
	ds_read_b64_tr_b16 v[210:211], v221 offset:16384
	ds_read_b64_tr_b16 v[212:213], v221 offset:20480
	v_add_f32_e32 v254, v226, v254
	v_exp_f32_e32 v228, v228
	v_sub_f32_e32 v229, v229, v190
	v_add_f32_e32 v254, v227, v254
	v_exp_f32_e32 v229, v229
	s_waitcnt lgkmcnt(8)
	v_mfma_f32_32x32x16_bf16 v[0:15], v[214:217], v[250:253], v[0:15]
	ds_read_b64_tr_b16 v[214:215], v205 offset:16640
	ds_read_b64_tr_b16 v[216:217], v205 offset:20736
	s_nop 0
	v_cvt_pk_bf16_f32 v242, v222, v223
	v_cvt_pk_bf16_f32 v243, v224, v225
	v_cvt_pk_bf16_f32 v244, v226, v227
	v_cvt_pk_bf16_f32 v245, v228, v229
	s_nop 1
	s_waitcnt lgkmcnt(8)
	v_mfma_f32_32x32x16_bf16 v[112:127], v[238:241], v[242:245], v[112:127]
	ds_read_b64_tr_b16 v[238:239], v218 offset:16640
	ds_read_b64_tr_b16 v[240:241], v218 offset:20736
	v_sub_f32_e32 v230, v230, v190
	v_add_f32_e32 v254, v228, v254
	v_exp_f32_e32 v230, v230
	v_sub_f32_e32 v231, v231, v190
	v_add_f32_e32 v254, v229, v254
	s_waitcnt lgkmcnt(8)
	v_mfma_f32_32x32x16_bf16 v[96:111], v[128:131], v[242:245], v[96:111]
	ds_read_b64_tr_b16 v[128:129], v219 offset:16640
	ds_read_b64_tr_b16 v[130:131], v219 offset:20736
	v_exp_f32_e32 v231, v231
	v_sub_f32_e32 v232, v232, v190
	v_add_f32_e32 v254, v230, v254
	v_exp_f32_e32 v232, v232
	v_sub_f32_e32 v233, v233, v190
	s_waitcnt lgkmcnt(8)
	v_mfma_f32_32x32x16_bf16 v[80:95], v[206:209], v[242:245], v[80:95]
	ds_read_b64_tr_b16 v[206:207], v221 offset:16640
	ds_read_b64_tr_b16 v[208:209], v221 offset:20736
	v_add_f32_e32 v254, v231, v254
	v_exp_f32_e32 v233, v233
	v_sub_f32_e32 v234, v234, v190
	v_add_f32_e32 v254, v232, v254
	s_waitcnt lgkmcnt(8)
	v_mfma_f32_32x32x16_bf16 v[64:79], v[210:213], v[242:245], v[64:79]
	ds_read_b64_tr_b16 v[210:211], v205 offset:24576
	ds_read_b64_tr_b16 v[212:213], v205 offset:28672
	v_exp_f32_e32 v234, v234
	v_sub_f32_e32 v235, v235, v190
	v_add_f32_e32 v254, v233, v254
	v_exp_f32_e32 v235, v235
	s_waitcnt lgkmcnt(8)
	v_mfma_f32_32x32x16_bf16 v[48:63], v[214:217], v[242:245], v[48:63]
	ds_read_b64_tr_b16 v[214:215], v218 offset:24576
	ds_read_b64_tr_b16 v[216:217], v218 offset:28672
	v_sub_f32_e32 v236, v236, v190
	v_add_f32_e32 v254, v234, v254
	v_exp_f32_e32 v236, v236
	v_sub_f32_e32 v237, v237, v190
	s_waitcnt lgkmcnt(8)
	v_mfma_f32_32x32x16_bf16 v[32:47], v[238:241], v[242:245], v[32:47]
	ds_read_b64_tr_b16 v[238:239], v219 offset:24576
	ds_read_b64_tr_b16 v[240:241], v219 offset:28672
	v_add_f32_e32 v254, v235, v254
	v_exp_f32_e32 v237, v237
	v_add_f32_e32 v254, v236, v254
	v_add_f32_e32 v254, v237, v254
	s_waitcnt lgkmcnt(8)
	v_mfma_f32_32x32x16_bf16 v[16:31], v[128:131], v[242:245], v[16:31]
	ds_read_b64_tr_b16 v[128:129], v221 offset:24576
	ds_read_b64_tr_b16 v[130:131], v221 offset:28672
	v_cvt_pk_bf16_f32 v250, v230, v231
	v_cvt_pk_bf16_f32 v251, v232, v233
	v_cvt_pk_bf16_f32 v252, v234, v235
	v_cvt_pk_bf16_f32 v253, v236, v237
	v_add_f32_e32 v195, v195, v254
	s_waitcnt lgkmcnt(8)
	v_mfma_f32_32x32x16_bf16 v[0:15], v[206:209], v[242:245], v[0:15]
	ds_read_b64_tr_b16 v[206:207], v205 offset:24832
	ds_read_b64_tr_b16 v[208:209], v205 offset:28928
	s_waitcnt lgkmcnt(8)
	v_mfma_f32_32x32x16_bf16 v[112:127], v[210:213], v[250:253], v[112:127]
	ds_read_b64_tr_b16 v[210:211], v218 offset:24832
	ds_read_b64_tr_b16 v[212:213], v218 offset:28928
	s_waitcnt lgkmcnt(8)
	v_mfma_f32_32x32x16_bf16 v[96:111], v[214:217], v[250:253], v[96:111]
	ds_read_b64_tr_b16 v[214:215], v219 offset:24832
	ds_read_b64_tr_b16 v[216:217], v219 offset:28928
	s_waitcnt lgkmcnt(8)
	v_mfma_f32_32x32x16_bf16 v[80:95], v[238:241], v[250:253], v[80:95]
	ds_read_b64_tr_b16 v[238:239], v221 offset:24832
	ds_read_b64_tr_b16 v[240:241], v221 offset:28928
	s_waitcnt lgkmcnt(8)
	v_mfma_f32_32x32x16_bf16 v[64:79], v[128:131], v[250:253], v[64:79]
	s_waitcnt lgkmcnt(6)
	v_mfma_f32_32x32x16_bf16 v[48:63], v[206:209], v[250:253], v[48:63]
	s_waitcnt lgkmcnt(4)
	v_mfma_f32_32x32x16_bf16 v[32:47], v[210:213], v[250:253], v[32:47]
	s_waitcnt lgkmcnt(2)
	v_mfma_f32_32x32x16_bf16 v[16:31], v[214:217], v[250:253], v[16:31]
	s_waitcnt lgkmcnt(0)
	v_mfma_f32_32x32x16_bf16 v[0:15], v[238:241], v[250:253], v[0:15]
	ds_read_b128 v[206:209], v196
	ds_read_b128 v[210:213], v197
	ds_read_b128 v[214:217], v198
	ds_read_b128 v[238:241], v199
	ds_read_b128 v[242:245], v200
	ds_read_b128 v[250:253], v201
	ds_read_b128 v[222:225], v202
	ds_read_b128 v[226:229], v203
	s_waitcnt vmcnt(0)
	s_add_i32 s18, s33, 1
	s_cmp_lg_u32 s33, 2
	s_cselect_b32 s33, s18, 0
	s_add_i32 s4, s4, 64
	s_add_u32 s12, s12, 0x100000
	s_addc_u32 s13, s13, 0
	s_add_i32 s76, s76, 1
	s_add_i32 s100, s4, 63
	s_cmp_le_i32 s100, s71
	s_cbranch_scc0 .Latt_latchb_5
	s_cmp_ge_u32 s76, s70
	s_cselect_b64 s[18:19], -1, 0
	v_mov_b32_e32 v204, v176
	s_barrier
	s_branch .Latt_cont_5s0
.Latt_rs1_5s2:
	s_waitcnt lgkmcnt(8)
	v_mfma_f32_32x32x16_bf16 v[64:79], v[238:241], v[250:253], v[64:79]
	ds_read_b64_tr_b16 v[238:239], v205 offset:16384
	ds_read_b64_tr_b16 v[240:241], v205 offset:20480
	s_waitcnt lgkmcnt(8)
	v_mfma_f32_32x32x16_bf16 v[48:63], v[128:131], v[250:253], v[48:63]
	ds_read_b64_tr_b16 v[128:129], v218 offset:16384
	ds_read_b64_tr_b16 v[130:131], v218 offset:20480
	s_waitcnt lgkmcnt(8)
	v_mfma_f32_32x32x16_bf16 v[32:47], v[206:209], v[250:253], v[32:47]
	ds_read_b64_tr_b16 v[206:207], v219 offset:16384
	ds_read_b64_tr_b16 v[208:209], v219 offset:20480
	s_waitcnt lgkmcnt(8)
	v_mfma_f32_32x32x16_bf16 v[16:31], v[210:213], v[250:253], v[16:31]
	ds_read_b64_tr_b16 v[210:211], v221 offset:16384
	ds_read_b64_tr_b16 v[212:213], v221 offset:20480
	s_waitcnt lgkmcnt(8)
	v_mfma_f32_32x32x16_bf16 v[0:15], v[214:217], v[250:253], v[0:15]
	ds_read_b64_tr_b16 v[214:215], v205 offset:16640
	ds_read_b64_tr_b16 v[216:217], v205 offset:20736
	s_nop 11
	v_max_f32_e32 v246, v190, v246
	v_sub_f32_e32 v190, v190, v246
	v_exp_f32_e32 v190, v190
	s_nop 0
	v_pk_mul_f32 v[126:127], v[126:127], v[190:191] op_sel_hi:[1,0]
	v_pk_mul_f32 v[124:125], v[124:125], v[190:191] op_sel_hi:[1,0]
	v_pk_mul_f32 v[122:123], v[122:123], v[190:191] op_sel_hi:[1,0]
	v_pk_mul_f32 v[120:121], v[120:121], v[190:191] op_sel_hi:[1,0]
	v_pk_mul_f32 v[118:119], v[118:119], v[190:191] op_sel_hi:[1,0]
	v_pk_mul_f32 v[116:117], v[116:117], v[190:191] op_sel_hi:[1,0]
	v_pk_mul_f32 v[114:115], v[114:115], v[190:191] op_sel_hi:[1,0]
	v_pk_mul_f32 v[112:113], v[112:113], v[190:191] op_sel_hi:[1,0]
	v_pk_mul_f32 v[110:111], v[110:111], v[190:191] op_sel_hi:[1,0]
	v_pk_mul_f32 v[108:109], v[108:109], v[190:191] op_sel_hi:[1,0]
	v_pk_mul_f32 v[106:107], v[106:107], v[190:191] op_sel_hi:[1,0]
	v_pk_mul_f32 v[104:105], v[104:105], v[190:191] op_sel_hi:[1,0]
	v_pk_mul_f32 v[102:103], v[102:103], v[190:191] op_sel_hi:[1,0]
	v_pk_mul_f32 v[100:101], v[100:101], v[190:191] op_sel_hi:[1,0]
	v_pk_mul_f32 v[98:99], v[98:99], v[190:191] op_sel_hi:[1,0]
	v_pk_mul_f32 v[96:97], v[96:97], v[190:191] op_sel_hi:[1,0]
	v_pk_mul_f32 v[94:95], v[94:95], v[190:191] op_sel_hi:[1,0]
	v_pk_mul_f32 v[92:93], v[92:93], v[190:191] op_sel_hi:[1,0]
	v_pk_mul_f32 v[90:91], v[90:91], v[190:191] op_sel_hi:[1,0]
	v_pk_mul_f32 v[88:89], v[88:89], v[190:191] op_sel_hi:[1,0]
	v_pk_mul_f32 v[86:87], v[86:87], v[190:191] op_sel_hi:[1,0]
	v_pk_mul_f32 v[84:85], v[84:85], v[190:191] op_sel_hi:[1,0]
	v_pk_mul_f32 v[82:83], v[82:83], v[190:191] op_sel_hi:[1,0]
	v_pk_mul_f32 v[80:81], v[80:81], v[190:191] op_sel_hi:[1,0]
	v_pk_mul_f32 v[78:79], v[78:79], v[190:191] op_sel_hi:[1,0]
	v_pk_mul_f32 v[76:77], v[76:77], v[190:191] op_sel_hi:[1,0]
	v_pk_mul_f32 v[74:75], v[74:75], v[190:191] op_sel_hi:[1,0]
	v_pk_mul_f32 v[72:73], v[72:73], v[190:191] op_sel_hi:[1,0]
	v_pk_mul_f32 v[70:71], v[70:71], v[190:191] op_sel_hi:[1,0]
	v_pk_mul_f32 v[68:69], v[68:69], v[190:191] op_sel_hi:[1,0]
	v_pk_mul_f32 v[66:67], v[66:67], v[190:191] op_sel_hi:[1,0]
	v_pk_mul_f32 v[64:65], v[64:65], v[190:191] op_sel_hi:[1,0]
	v_pk_mul_f32 v[62:63], v[62:63], v[190:191] op_sel_hi:[1,0]
	v_pk_mul_f32 v[60:61], v[60:61], v[190:191] op_sel_hi:[1,0]
	v_pk_mul_f32 v[58:59], v[58:59], v[190:191] op_sel_hi:[1,0]
	v_pk_mul_f32 v[56:57], v[56:57], v[190:191] op_sel_hi:[1,0]
	v_pk_mul_f32 v[54:55], v[54:55], v[190:191] op_sel_hi:[1,0]
	v_pk_mul_f32 v[52:53], v[52:53], v[190:191] op_sel_hi:[1,0]
	v_pk_mul_f32 v[50:51], v[50:51], v[190:191] op_sel_hi:[1,0]
	v_pk_mul_f32 v[48:49], v[48:49], v[190:191] op_sel_hi:[1,0]
	v_pk_mul_f32 v[46:47], v[46:47], v[190:191] op_sel_hi:[1,0]
	v_pk_mul_f32 v[44:45], v[44:45], v[190:191] op_sel_hi:[1,0]
	v_pk_mul_f32 v[42:43], v[42:43], v[190:191] op_sel_hi:[1,0]
	v_pk_mul_f32 v[40:41], v[40:41], v[190:191] op_sel_hi:[1,0]
	v_pk_mul_f32 v[38:39], v[38:39], v[190:191] op_sel_hi:[1,0]
	v_pk_mul_f32 v[36:37], v[36:37], v[190:191] op_sel_hi:[1,0]
	v_pk_mul_f32 v[34:35], v[34:35], v[190:191] op_sel_hi:[1,0]
	v_pk_mul_f32 v[32:33], v[32:33], v[190:191] op_sel_hi:[1,0]
	v_pk_mul_f32 v[30:31], v[30:31], v[190:191] op_sel_hi:[1,0]
	v_pk_mul_f32 v[28:29], v[28:29], v[190:191] op_sel_hi:[1,0]
	v_pk_mul_f32 v[26:27], v[26:27], v[190:191] op_sel_hi:[1,0]
	v_pk_mul_f32 v[24:25], v[24:25], v[190:191] op_sel_hi:[1,0]
	v_pk_mul_f32 v[22:23], v[22:23], v[190:191] op_sel_hi:[1,0]
	v_pk_mul_f32 v[20:21], v[20:21], v[190:191] op_sel_hi:[1,0]
	v_pk_mul_f32 v[18:19], v[18:19], v[190:191] op_sel_hi:[1,0]
	v_pk_mul_f32 v[16:17], v[16:17], v[190:191] op_sel_hi:[1,0]
	v_pk_mul_f32 v[14:15], v[14:15], v[190:191] op_sel_hi:[1,0]
	v_pk_mul_f32 v[12:13], v[12:13], v[190:191] op_sel_hi:[1,0]
	v_pk_mul_f32 v[10:11], v[10:11], v[190:191] op_sel_hi:[1,0]
	v_pk_mul_f32 v[8:9], v[8:9], v[190:191] op_sel_hi:[1,0]
	v_pk_mul_f32 v[6:7], v[6:7], v[190:191] op_sel_hi:[1,0]
	v_pk_mul_f32 v[4:5], v[4:5], v[190:191] op_sel_hi:[1,0]
	v_pk_mul_f32 v[2:3], v[2:3], v[190:191] op_sel_hi:[1,0]
	v_pk_mul_f32 v[0:1], v[0:1], v[190:191] op_sel_hi:[1,0]
	v_mul_f32_e32 v195, v195, v190
	v_mov_b32_e32 v190, v246
	v_sub_f32_e32 v222, v222, v190
	v_exp_f32_e32 v222, v222
	v_sub_f32_e32 v223, v223, v190
	v_exp_f32_e32 v223, v223
	v_sub_f32_e32 v224, v224, v190
	v_add_f32_e32 v254, 0, v222
	v_exp_f32_e32 v224, v224
	v_sub_f32_e32 v225, v225, v190
	v_add_f32_e32 v254, v223, v254
	v_exp_f32_e32 v225, v225
	v_sub_f32_e32 v226, v226, v190
	v_add_f32_e32 v254, v224, v254
	v_exp_f32_e32 v226, v226
	v_sub_f32_e32 v227, v227, v190
	v_add_f32_e32 v254, v225, v254
	v_exp_f32_e32 v227, v227
	v_sub_f32_e32 v228, v228, v190
	v_add_f32_e32 v254, v226, v254
	v_exp_f32_e32 v228, v228
	v_sub_f32_e32 v229, v229, v190
	v_add_f32_e32 v254, v227, v254
	v_exp_f32_e32 v229, v229
	v_sub_f32_e32 v230, v230, v190
	v_add_f32_e32 v254, v228, v254
	v_exp_f32_e32 v230, v230
	v_sub_f32_e32 v231, v231, v190
	v_add_f32_e32 v254, v229, v254
	v_exp_f32_e32 v231, v231
	v_sub_f32_e32 v232, v232, v190
	v_add_f32_e32 v254, v230, v254
	v_exp_f32_e32 v232, v232
	v_sub_f32_e32 v233, v233, v190
	v_add_f32_e32 v254, v231, v254
	v_exp_f32_e32 v233, v233
	v_sub_f32_e32 v234, v234, v190
	v_add_f32_e32 v254, v232, v254
	v_exp_f32_e32 v234, v234
	v_sub_f32_e32 v235, v235, v190
	v_add_f32_e32 v254, v233, v254
	v_exp_f32_e32 v235, v235
	v_sub_f32_e32 v236, v236, v190
	v_add_f32_e32 v254, v234, v254
	v_exp_f32_e32 v236, v236
	v_sub_f32_e32 v237, v237, v190
	v_add_f32_e32 v254, v235, v254
	v_exp_f32_e32 v237, v237
	v_add_f32_e32 v254, v236, v254
	v_add_f32_e32 v254, v237, v254
	v_cvt_pk_bf16_f32 v242, v222, v223
	v_cvt_pk_bf16_f32 v243, v224, v225
	v_cvt_pk_bf16_f32 v244, v226, v227
	v_cvt_pk_bf16_f32 v245, v228, v229
	v_cvt_pk_bf16_f32 v250, v230, v231
	v_cvt_pk_bf16_f32 v251, v232, v233
	v_cvt_pk_bf16_f32 v252, v234, v235
	v_cvt_pk_bf16_f32 v253, v236, v237
	v_add_f32_e32 v195, v195, v254
	s_nop 1
	s_waitcnt lgkmcnt(8)
	v_mfma_f32_32x32x16_bf16 v[112:127], v[238:241], v[242:245], v[112:127]
	ds_read_b64_tr_b16 v[238:239], v218 offset:16640
	ds_read_b64_tr_b16 v[240:241], v218 offset:20736
	s_waitcnt lgkmcnt(8)
	v_mfma_f32_32x32x16_bf16 v[96:111], v[128:131], v[242:245], v[96:111]
	ds_read_b64_tr_b16 v[222:223], v219 offset:16640
	ds_read_b64_tr_b16 v[224:225], v219 offset:20736
	s_waitcnt lgkmcnt(8)
	v_mfma_f32_32x32x16_bf16 v[80:95], v[206:209], v[242:245], v[80:95]
	ds_read_b64_tr_b16 v[206:207], v221 offset:16640
	ds_read_b64_tr_b16 v[208:209], v221 offset:20736
	s_waitcnt lgkmcnt(8)
	v_mfma_f32_32x32x16_bf16 v[64:79], v[210:213], v[242:245], v[64:79]
	ds_read_b64_tr_b16 v[210:211], v205 offset:24576
	ds_read_b64_tr_b16 v[212:213], v205 offset:28672
	s_waitcnt lgkmcnt(8)
	v_mfma_f32_32x32x16_bf16 v[48:63], v[214:217], v[242:245], v[48:63]
	ds_read_b64_tr_b16 v[214:215], v218 offset:24576
	ds_read_b64_tr_b16 v[216:217], v218 offset:28672
	s_waitcnt lgkmcnt(8)
	v_mfma_f32_32x32x16_bf16 v[32:47], v[238:241], v[242:245], v[32:47]
	ds_read_b64_tr_b16 v[238:239], v219 offset:24576
	ds_read_b64_tr_b16 v[240:241], v219 offset:28672
	s_waitcnt lgkmcnt(8)
	v_mfma_f32_32x32x16_bf16 v[16:31], v[222:225], v[242:245], v[16:31]
	ds_read_b64_tr_b16 v[222:223], v221 offset:24576
	ds_read_b64_tr_b16 v[224:225], v221 offset:28672
	s_waitcnt lgkmcnt(8)
	v_mfma_f32_32x32x16_bf16 v[0:15], v[206:209], v[242:245], v[0:15]
	ds_read_b64_tr_b16 v[206:207], v205 offset:24832
	ds_read_b64_tr_b16 v[208:209], v205 offset:28928
	s_waitcnt lgkmcnt(8)
	v_mfma_f32_32x32x16_bf16 v[112:127], v[210:213], v[250:253], v[112:127]
	ds_read_b64_tr_b16 v[210:211], v218 offset:24832
	ds_read_b64_tr_b16 v[212:213], v218 offset:28928
	s_waitcnt lgkmcnt(8)
	v_mfma_f32_32x32x16_bf16 v[96:111], v[214:217], v[250:253], v[96:111]
	ds_read_b64_tr_b16 v[214:215], v219 offset:24832
	ds_read_b64_tr_b16 v[216:217], v219 offset:28928
	s_waitcnt lgkmcnt(8)
	v_mfma_f32_32x32x16_bf16 v[80:95], v[238:241], v[250:253], v[80:95]
	ds_read_b64_tr_b16 v[238:239], v221 offset:24832
	ds_read_b64_tr_b16 v[240:241], v221 offset:28928
	s_waitcnt lgkmcnt(8)
	v_mfma_f32_32x32x16_bf16 v[64:79], v[222:225], v[250:253], v[64:79]
	s_waitcnt lgkmcnt(6)
	v_mfma_f32_32x32x16_bf16 v[48:63], v[206:209], v[250:253], v[48:63]
	s_waitcnt lgkmcnt(4)
	v_mfma_f32_32x32x16_bf16 v[32:47], v[210:213], v[250:253], v[32:47]
	s_waitcnt lgkmcnt(2)
	v_mfma_f32_32x32x16_bf16 v[16:31], v[214:217], v[250:253], v[16:31]
	s_waitcnt lgkmcnt(0)
	v_mfma_f32_32x32x16_bf16 v[0:15], v[238:241], v[250:253], v[0:15]
	ds_read_b128 v[206:209], v196
	ds_read_b128 v[210:213], v197
	ds_read_b128 v[214:217], v198
	ds_read_b128 v[238:241], v199
	ds_read_b128 v[242:245], v200
	ds_read_b128 v[250:253], v201
	ds_read_b128 v[222:225], v202
	ds_read_b128 v[226:229], v203
	s_waitcnt vmcnt(0)
	s_add_i32 s18, s33, 1
	s_cmp_lg_u32 s33, 2
	s_cselect_b32 s33, s18, 0
	s_add_i32 s4, s4, 64
	s_add_u32 s12, s12, 0x100000
	s_addc_u32 s13, s13, 0
	s_add_i32 s76, s76, 1
	s_add_i32 s100, s4, 63
	s_cmp_le_i32 s100, s71
	s_cbranch_scc0 .Latt_latchb_5
	s_cmp_ge_u32 s76, s70
	s_cselect_b64 s[18:19], -1, 0
	v_mov_b32_e32 v204, v176
	s_barrier
	s_branch .Latt_cont_5s0

.Latt_latchb_6:
	s_waitcnt lgkmcnt(0)
	s_cmp_eq_u32 s67, s72
	s_barrier
	s_cbranch_scc1 .LBB0_1854

.Latt_nr0_6s0:
	s_waitcnt lgkmcnt(3)
	v_mfma_f32_32x32x16_bf16 v[222:237], v[214:217], v[152:155], v[222:237]
	ds_read_b128 v[214:217], v201 offset:8192
	v_sub_f32_e32 v128, v128, v190
	v_exp_f32_e32 v128, v128
	v_sub_f32_e32 v129, v129, v190
	v_exp_f32_e32 v129, v129
	v_sub_f32_e32 v130, v130, v190
	s_waitcnt lgkmcnt(3)
	v_mfma_f32_32x32x16_bf16 v[222:237], v[238:241], v[156:159], v[222:237]
	ds_read_b128 v[238:241], v202 offset:8192
	v_add_f32_e32 v254, 0, v128
	v_exp_f32_e32 v130, v130
	v_sub_f32_e32 v131, v131, v190
	v_add_f32_e32 v254, v129, v254
	v_exp_f32_e32 v131, v131
	s_waitcnt lgkmcnt(3)
	v_mfma_f32_32x32x16_bf16 v[222:237], v[206:209], v[160:163], v[222:237]
	ds_read_b64_tr_b16 v[206:207], v205
	ds_read_b64_tr_b16 v[208:209], v205 offset:4096
	v_sub_f32_e32 v132, v132, v190
	v_add_f32_e32 v254, v130, v254
	v_exp_f32_e32 v132, v132
	v_sub_f32_e32 v133, v133, v190
	v_add_f32_e32 v254, v131, v254
	s_waitcnt lgkmcnt(4)
	v_mfma_f32_32x32x16_bf16 v[222:237], v[210:213], v[164:167], v[222:237]
	ds_read_b64_tr_b16 v[210:211], v218
	ds_read_b64_tr_b16 v[212:213], v218 offset:4096
	v_exp_f32_e32 v133, v133
	v_sub_f32_e32 v134, v134, v190
	v_add_f32_e32 v254, v132, v254
	v_exp_f32_e32 v134, v134
	s_waitcnt lgkmcnt(5)
	v_mfma_f32_32x32x16_bf16 v[222:237], v[214:217], v[168:171], v[222:237]
	ds_read_b64_tr_b16 v[214:215], v219
	ds_read_b64_tr_b16 v[216:217], v219 offset:4096
	v_sub_f32_e32 v135, v135, v190
	v_add_f32_e32 v254, v133, v254
	v_exp_f32_e32 v135, v135
	s_nop 0
	s_waitcnt lgkmcnt(6)
	v_mfma_f32_32x32x16_bf16 v[222:237], v[238:241], v[172:175], v[222:237]
	ds_read_b64_tr_b16 v[238:239], v221
	ds_read_b64_tr_b16 v[240:241], v221 offset:4096
	v_cvt_pk_bf16_f32 v242, v128, v129
	v_cvt_pk_bf16_f32 v243, v130, v131
	v_cvt_pk_bf16_f32 v244, v132, v133
	v_cvt_pk_bf16_f32 v245, v134, v135
	s_nop 1
	s_waitcnt lgkmcnt(6)
	v_mfma_f32_32x32x16_bf16 v[112:127], v[206:209], v[242:245], v[112:127]
	ds_read_b64_tr_b16 v[206:207], v205 offset:256
	ds_read_b64_tr_b16 v[208:209], v205 offset:4352
	v_sub_f32_e32 v136, v136, v190
	v_add_f32_e32 v254, v134, v254
	v_exp_f32_e32 v136, v136
	v_sub_f32_e32 v137, v137, v190
	v_add_f32_e32 v254, v135, v254
	s_waitcnt lgkmcnt(6)
	v_mfma_f32_32x32x16_bf16 v[96:111], v[210:213], v[242:245], v[96:111]
	ds_read_b64_tr_b16 v[210:211], v218 offset:256
	ds_read_b64_tr_b16 v[212:213], v218 offset:4352
	v_exp_f32_e32 v137, v137
	v_sub_f32_e32 v138, v138, v190
	v_add_f32_e32 v254, v136, v254
	v_exp_f32_e32 v138, v138
	v_sub_f32_e32 v139, v139, v190
	s_waitcnt lgkmcnt(6)
	v_mfma_f32_32x32x16_bf16 v[80:95], v[214:217], v[242:245], v[80:95]
	ds_read_b64_tr_b16 v[214:215], v219 offset:256
	ds_read_b64_tr_b16 v[216:217], v219 offset:4352
	v_add_f32_e32 v254, v137, v254
	v_exp_f32_e32 v139, v139
	v_sub_f32_e32 v140, v140, v190
	v_add_f32_e32 v254, v138, v254
	s_waitcnt lgkmcnt(6)
	v_mfma_f32_32x32x16_bf16 v[64:79], v[238:241], v[242:245], v[64:79]
	ds_read_b64_tr_b16 v[238:239], v221 offset:256
	ds_read_b64_tr_b16 v[240:241], v221 offset:4352
	v_exp_f32_e32 v140, v140
	v_sub_f32_e32 v141, v141, v190
	v_add_f32_e32 v254, v139, v254
	v_exp_f32_e32 v141, v141
	s_waitcnt lgkmcnt(6)
	v_mfma_f32_32x32x16_bf16 v[48:63], v[206:209], v[242:245], v[48:63]
	ds_read_b64_tr_b16 v[206:207], v205 offset:8192
	ds_read_b64_tr_b16 v[208:209], v205 offset:12288
	v_sub_f32_e32 v142, v142, v190
	v_add_f32_e32 v254, v140, v254
	v_exp_f32_e32 v142, v142
	v_sub_f32_e32 v143, v143, v190
	s_waitcnt lgkmcnt(6)
	v_mfma_f32_32x32x16_bf16 v[32:47], v[210:213], v[242:245], v[32:47]
	ds_read_b64_tr_b16 v[210:211], v218 offset:8192
	ds_read_b64_tr_b16 v[212:213], v218 offset:12288
	v_add_f32_e32 v254, v141, v254
	v_exp_f32_e32 v143, v143
	v_add_f32_e32 v254, v142, v254
	v_add_f32_e32 v254, v143, v254
	s_waitcnt lgkmcnt(6)
	v_mfma_f32_32x32x16_bf16 v[16:31], v[214:217], v[242:245], v[16:31]
	ds_read_b64_tr_b16 v[214:215], v219 offset:8192
	ds_read_b64_tr_b16 v[216:217], v219 offset:12288
	v_cvt_pk_bf16_f32 v250, v136, v137
	v_cvt_pk_bf16_f32 v251, v138, v139
	v_cvt_pk_bf16_f32 v252, v140, v141
	v_cvt_pk_bf16_f32 v253, v142, v143
	v_add_f32_e32 v203, v203, v254
	s_waitcnt lgkmcnt(6)
	v_mfma_f32_32x32x16_bf16 v[0:15], v[238:241], v[242:245], v[0:15]
	ds_read_b64_tr_b16 v[238:239], v221 offset:8192
	ds_read_b64_tr_b16 v[240:241], v221 offset:12288
	ds_read_b64_tr_b16 v[128:129], v205 offset:8448
	ds_read_b64_tr_b16 v[130:131], v205 offset:12544
	s_waitcnt lgkmcnt(8)
	v_mfma_f32_32x32x16_bf16 v[112:127], v[206:209], v[250:253], v[112:127]
	ds_read_b64_tr_b16 v[206:207], v218 offset:8448
	ds_read_b64_tr_b16 v[208:209], v218 offset:12544
	v_max3_f32 v246, v222, v223, v224
	v_max3_f32 v247, v225, v226, v227
	v_max3_f32 v246, v246, v228, v229
	v_max3_f32 v247, v247, v230, v231
	v_max3_f32 v246, v246, v232, v233
	s_waitcnt lgkmcnt(8)
	v_mfma_f32_32x32x16_bf16 v[96:111], v[210:213], v[250:253], v[96:111]
	ds_read_b64_tr_b16 v[210:211], v219 offset:8448
	ds_read_b64_tr_b16 v[212:213], v219 offset:12544
	v_max3_f32 v247, v247, v234, v235
	v_max3_f32 v246, v246, v236, v237
	v_max_f32_e32 v246, v246, v247
	v_mov_b32_e32 v247, v246
	v_add_f32_e32 v249, 0x41000000, v190
	s_waitcnt lgkmcnt(8)
	v_mfma_f32_32x32x16_bf16 v[80:95], v[214:217], v[250:253], v[80:95]
	ds_read_b64_tr_b16 v[214:215], v221 offset:8448
	ds_read_b64_tr_b16 v[216:217], v221 offset:12544
	s_nop 1
	v_permlane32_swap_b32_e32 v246, v247
	v_max_f32_e32 v246, v246, v247
	v_cmp_gt_f32_e32 vcc, v246, v249
	s_cbranch_vccnz .Latt_rs1_6s0
	s_waitcnt lgkmcnt(8)
	v_mfma_f32_32x32x16_bf16 v[64:79], v[238:241], v[250:253], v[64:79]
	ds_read_b64_tr_b16 v[238:239], v205 offset:16384
	ds_read_b64_tr_b16 v[240:241], v205 offset:20480
	v_sub_f32_e32 v222, v222, v190
	v_exp_f32_e32 v222, v222
	v_sub_f32_e32 v223, v223, v190
	v_exp_f32_e32 v223, v223
	v_sub_f32_e32 v224, v224, v190
	v_add_f32_e32 v254, 0, v222
	s_waitcnt lgkmcnt(8)
	v_mfma_f32_32x32x16_bf16 v[48:63], v[128:131], v[250:253], v[48:63]
	ds_read_b64_tr_b16 v[128:129], v218 offset:16384
	ds_read_b64_tr_b16 v[130:131], v218 offset:20480
	v_exp_f32_e32 v224, v224
	v_sub_f32_e32 v225, v225, v190
	v_add_f32_e32 v254, v223, v254
	v_exp_f32_e32 v225, v225
	v_sub_f32_e32 v226, v226, v190
	v_add_f32_e32 v254, v224, v254
	s_waitcnt lgkmcnt(8)
	v_mfma_f32_32x32x16_bf16 v[32:47], v[206:209], v[250:253], v[32:47]
	ds_read_b64_tr_b16 v[206:207], v219 offset:16384
	ds_read_b64_tr_b16 v[208:209], v219 offset:20480
	v_exp_f32_e32 v226, v226
	v_sub_f32_e32 v227, v227, v190
	v_add_f32_e32 v254, v225, v254
	v_exp_f32_e32 v227, v227
	v_sub_f32_e32 v228, v228, v190
	s_waitcnt lgkmcnt(8)
	v_mfma_f32_32x32x16_bf16 v[16:31], v[210:213], v[250:253], v[16:31]
	ds_read_b64_tr_b16 v[210:211], v221 offset:16384
	ds_read_b64_tr_b16 v[212:213], v221 offset:20480
	v_add_f32_e32 v254, v226, v254
	v_exp_f32_e32 v228, v228
	v_sub_f32_e32 v229, v229, v190
	v_add_f32_e32 v254, v227, v254
	v_exp_f32_e32 v229, v229
	s_waitcnt lgkmcnt(8)
	v_mfma_f32_32x32x16_bf16 v[0:15], v[214:217], v[250:253], v[0:15]
	ds_read_b64_tr_b16 v[214:215], v205 offset:16640
	ds_read_b64_tr_b16 v[216:217], v205 offset:20736
	s_nop 0
	v_cvt_pk_bf16_f32 v242, v222, v223
	v_cvt_pk_bf16_f32 v243, v224, v225
	v_cvt_pk_bf16_f32 v244, v226, v227
	v_cvt_pk_bf16_f32 v245, v228, v229
	s_nop 1
	s_waitcnt lgkmcnt(8)
	v_mfma_f32_32x32x16_bf16 v[112:127], v[238:241], v[242:245], v[112:127]
	ds_read_b64_tr_b16 v[238:239], v218 offset:16640
	ds_read_b64_tr_b16 v[240:241], v218 offset:20736
	v_sub_f32_e32 v230, v230, v190
	v_add_f32_e32 v254, v228, v254
	v_exp_f32_e32 v230, v230
	v_sub_f32_e32 v231, v231, v190
	v_add_f32_e32 v254, v229, v254
	s_waitcnt lgkmcnt(8)
	v_mfma_f32_32x32x16_bf16 v[96:111], v[128:131], v[242:245], v[96:111]
	ds_read_b64_tr_b16 v[128:129], v219 offset:16640
	ds_read_b64_tr_b16 v[130:131], v219 offset:20736
	v_exp_f32_e32 v231, v231
	v_sub_f32_e32 v232, v232, v190
	v_add_f32_e32 v254, v230, v254
	v_exp_f32_e32 v232, v232
	v_sub_f32_e32 v233, v233, v190
	s_waitcnt lgkmcnt(8)
	v_mfma_f32_32x32x16_bf16 v[80:95], v[206:209], v[242:245], v[80:95]
	ds_read_b64_tr_b16 v[206:207], v221 offset:16640
	ds_read_b64_tr_b16 v[208:209], v221 offset:20736
	v_add_f32_e32 v254, v231, v254
	v_exp_f32_e32 v233, v233
	v_sub_f32_e32 v234, v234, v190
	v_add_f32_e32 v254, v232, v254
	s_waitcnt lgkmcnt(8)
	v_mfma_f32_32x32x16_bf16 v[64:79], v[210:213], v[242:245], v[64:79]
	ds_read_b64_tr_b16 v[210:211], v205 offset:24576
	ds_read_b64_tr_b16 v[212:213], v205 offset:28672
	v_exp_f32_e32 v234, v234
	v_sub_f32_e32 v235, v235, v190
	v_add_f32_e32 v254, v233, v254
	v_exp_f32_e32 v235, v235
	s_waitcnt lgkmcnt(8)
	v_mfma_f32_32x32x16_bf16 v[48:63], v[214:217], v[242:245], v[48:63]
	ds_read_b64_tr_b16 v[214:215], v218 offset:24576
	ds_read_b64_tr_b16 v[216:217], v218 offset:28672
	v_sub_f32_e32 v236, v236, v190
	v_add_f32_e32 v254, v234, v254
	v_exp_f32_e32 v236, v236
	v_sub_f32_e32 v237, v237, v190
	s_waitcnt lgkmcnt(8)
	v_mfma_f32_32x32x16_bf16 v[32:47], v[238:241], v[242:245], v[32:47]
	ds_read_b64_tr_b16 v[238:239], v219 offset:24576
	ds_read_b64_tr_b16 v[240:241], v219 offset:28672
	v_add_f32_e32 v254, v235, v254
	v_exp_f32_e32 v237, v237
	v_add_f32_e32 v254, v236, v254
	v_add_f32_e32 v254, v237, v254
	s_waitcnt lgkmcnt(8)
	v_mfma_f32_32x32x16_bf16 v[16:31], v[128:131], v[242:245], v[16:31]
	ds_read_b64_tr_b16 v[128:129], v221 offset:24576
	ds_read_b64_tr_b16 v[130:131], v221 offset:28672
	v_cvt_pk_bf16_f32 v250, v230, v231
	v_cvt_pk_bf16_f32 v251, v232, v233
	v_cvt_pk_bf16_f32 v252, v234, v235
	v_cvt_pk_bf16_f32 v253, v236, v237
	v_add_f32_e32 v203, v203, v254
	s_waitcnt lgkmcnt(8)
	v_mfma_f32_32x32x16_bf16 v[0:15], v[206:209], v[242:245], v[0:15]
	ds_read_b64_tr_b16 v[206:207], v205 offset:24832
	ds_read_b64_tr_b16 v[208:209], v205 offset:28928
	s_waitcnt lgkmcnt(8)
	v_mfma_f32_32x32x16_bf16 v[112:127], v[210:213], v[250:253], v[112:127]
	ds_read_b64_tr_b16 v[210:211], v218 offset:24832
	ds_read_b64_tr_b16 v[212:213], v218 offset:28928
	s_waitcnt lgkmcnt(8)
	v_mfma_f32_32x32x16_bf16 v[96:111], v[214:217], v[250:253], v[96:111]
	ds_read_b64_tr_b16 v[214:215], v219 offset:24832
	ds_read_b64_tr_b16 v[216:217], v219 offset:28928
	s_waitcnt lgkmcnt(8)
	v_mfma_f32_32x32x16_bf16 v[80:95], v[238:241], v[250:253], v[80:95]
	ds_read_b64_tr_b16 v[238:239], v221 offset:24832
	ds_read_b64_tr_b16 v[240:241], v221 offset:28928
	s_waitcnt lgkmcnt(8)
	v_mfma_f32_32x32x16_bf16 v[64:79], v[128:131], v[250:253], v[64:79]
	s_waitcnt lgkmcnt(6)
	v_mfma_f32_32x32x16_bf16 v[48:63], v[206:209], v[250:253], v[48:63]
	s_waitcnt lgkmcnt(4)
	v_mfma_f32_32x32x16_bf16 v[32:47], v[210:213], v[250:253], v[32:47]
	s_waitcnt lgkmcnt(2)
	v_mfma_f32_32x32x16_bf16 v[16:31], v[214:217], v[250:253], v[16:31]
	s_waitcnt lgkmcnt(0)
	v_mfma_f32_32x32x16_bf16 v[0:15], v[238:241], v[250:253], v[0:15]
	ds_read_b128 v[206:209], v195 offset:16384
	ds_read_b128 v[210:213], v196 offset:16384
	ds_read_b128 v[214:217], v197 offset:16384
	ds_read_b128 v[238:241], v198 offset:16384
	ds_read_b128 v[242:245], v199 offset:16384
	ds_read_b128 v[250:253], v200 offset:16384
	ds_read_b128 v[222:225], v201 offset:16384
	ds_read_b128 v[226:229], v202 offset:16384
	s_waitcnt vmcnt(0)
	s_add_i32 s12, s34, 1
	s_cmp_lg_u32 s34, 2
	s_cselect_b32 s34, s12, 0
	s_add_i32 s72, s72, 64
	s_add_u32 s20, s20, 0x100000
	s_addc_u32 s21, s21, 0
	s_add_i32 s73, s73, 1
	s_add_i32 s100, s72, 63
	s_cmp_le_i32 s100, s68
	s_cbranch_scc0 .Latt_latchb_6
	s_cmp_ge_u32 s73, s66
	s_cselect_b64 s[12:13], -1, 0
	v_mov_b32_e32 v204, v176
	s_barrier
	s_branch .Latt_cont_6s1
.Latt_rs1_6s0:
	s_waitcnt lgkmcnt(8)
	v_mfma_f32_32x32x16_bf16 v[64:79], v[238:241], v[250:253], v[64:79]
	ds_read_b64_tr_b16 v[238:239], v205 offset:16384
	ds_read_b64_tr_b16 v[240:241], v205 offset:20480
	s_waitcnt lgkmcnt(8)
	v_mfma_f32_32x32x16_bf16 v[48:63], v[128:131], v[250:253], v[48:63]
	ds_read_b64_tr_b16 v[128:129], v218 offset:16384
	ds_read_b64_tr_b16 v[130:131], v218 offset:20480
	s_waitcnt lgkmcnt(8)
	v_mfma_f32_32x32x16_bf16 v[32:47], v[206:209], v[250:253], v[32:47]
	ds_read_b64_tr_b16 v[206:207], v219 offset:16384
	ds_read_b64_tr_b16 v[208:209], v219 offset:20480
	s_waitcnt lgkmcnt(8)
	v_mfma_f32_32x32x16_bf16 v[16:31], v[210:213], v[250:253], v[16:31]
	ds_read_b64_tr_b16 v[210:211], v221 offset:16384
	ds_read_b64_tr_b16 v[212:213], v221 offset:20480
	s_waitcnt lgkmcnt(8)
	v_mfma_f32_32x32x16_bf16 v[0:15], v[214:217], v[250:253], v[0:15]
	ds_read_b64_tr_b16 v[214:215], v205 offset:16640
	ds_read_b64_tr_b16 v[216:217], v205 offset:20736
	s_nop 11
	v_max_f32_e32 v246, v190, v246
	v_sub_f32_e32 v190, v190, v246
	v_exp_f32_e32 v190, v190
	s_nop 0
	v_pk_mul_f32 v[126:127], v[126:127], v[190:191] op_sel_hi:[1,0]
	v_pk_mul_f32 v[124:125], v[124:125], v[190:191] op_sel_hi:[1,0]
	v_pk_mul_f32 v[122:123], v[122:123], v[190:191] op_sel_hi:[1,0]
	v_pk_mul_f32 v[120:121], v[120:121], v[190:191] op_sel_hi:[1,0]
	v_pk_mul_f32 v[118:119], v[118:119], v[190:191] op_sel_hi:[1,0]
	v_pk_mul_f32 v[116:117], v[116:117], v[190:191] op_sel_hi:[1,0]
	v_pk_mul_f32 v[114:115], v[114:115], v[190:191] op_sel_hi:[1,0]
	v_pk_mul_f32 v[112:113], v[112:113], v[190:191] op_sel_hi:[1,0]
	v_pk_mul_f32 v[110:111], v[110:111], v[190:191] op_sel_hi:[1,0]
	v_pk_mul_f32 v[108:109], v[108:109], v[190:191] op_sel_hi:[1,0]
	v_pk_mul_f32 v[106:107], v[106:107], v[190:191] op_sel_hi:[1,0]
	v_pk_mul_f32 v[104:105], v[104:105], v[190:191] op_sel_hi:[1,0]
	v_pk_mul_f32 v[102:103], v[102:103], v[190:191] op_sel_hi:[1,0]
	v_pk_mul_f32 v[100:101], v[100:101], v[190:191] op_sel_hi:[1,0]
	v_pk_mul_f32 v[98:99], v[98:99], v[190:191] op_sel_hi:[1,0]
	v_pk_mul_f32 v[96:97], v[96:97], v[190:191] op_sel_hi:[1,0]
	v_pk_mul_f32 v[94:95], v[94:95], v[190:191] op_sel_hi:[1,0]
	v_pk_mul_f32 v[92:93], v[92:93], v[190:191] op_sel_hi:[1,0]
	v_pk_mul_f32 v[90:91], v[90:91], v[190:191] op_sel_hi:[1,0]
	v_pk_mul_f32 v[88:89], v[88:89], v[190:191] op_sel_hi:[1,0]
	v_pk_mul_f32 v[86:87], v[86:87], v[190:191] op_sel_hi:[1,0]
	v_pk_mul_f32 v[84:85], v[84:85], v[190:191] op_sel_hi:[1,0]
	v_pk_mul_f32 v[82:83], v[82:83], v[190:191] op_sel_hi:[1,0]
	v_pk_mul_f32 v[80:81], v[80:81], v[190:191] op_sel_hi:[1,0]
	v_pk_mul_f32 v[78:79], v[78:79], v[190:191] op_sel_hi:[1,0]
	v_pk_mul_f32 v[76:77], v[76:77], v[190:191] op_sel_hi:[1,0]
	v_pk_mul_f32 v[74:75], v[74:75], v[190:191] op_sel_hi:[1,0]
	v_pk_mul_f32 v[72:73], v[72:73], v[190:191] op_sel_hi:[1,0]
	v_pk_mul_f32 v[70:71], v[70:71], v[190:191] op_sel_hi:[1,0]
	v_pk_mul_f32 v[68:69], v[68:69], v[190:191] op_sel_hi:[1,0]
	v_pk_mul_f32 v[66:67], v[66:67], v[190:191] op_sel_hi:[1,0]
	v_pk_mul_f32 v[64:65], v[64:65], v[190:191] op_sel_hi:[1,0]
	v_pk_mul_f32 v[62:63], v[62:63], v[190:191] op_sel_hi:[1,0]
	v_pk_mul_f32 v[60:61], v[60:61], v[190:191] op_sel_hi:[1,0]
	v_pk_mul_f32 v[58:59], v[58:59], v[190:191] op_sel_hi:[1,0]
	v_pk_mul_f32 v[56:57], v[56:57], v[190:191] op_sel_hi:[1,0]
	v_pk_mul_f32 v[54:55], v[54:55], v[190:191] op_sel_hi:[1,0]
	v_pk_mul_f32 v[52:53], v[52:53], v[190:191] op_sel_hi:[1,0]
	v_pk_mul_f32 v[50:51], v[50:51], v[190:191] op_sel_hi:[1,0]
	v_pk_mul_f32 v[48:49], v[48:49], v[190:191] op_sel_hi:[1,0]
	v_pk_mul_f32 v[46:47], v[46:47], v[190:191] op_sel_hi:[1,0]
	v_pk_mul_f32 v[44:45], v[44:45], v[190:191] op_sel_hi:[1,0]
	v_pk_mul_f32 v[42:43], v[42:43], v[190:191] op_sel_hi:[1,0]
	v_pk_mul_f32 v[40:41], v[40:41], v[190:191] op_sel_hi:[1,0]
	v_pk_mul_f32 v[38:39], v[38:39], v[190:191] op_sel_hi:[1,0]
	v_pk_mul_f32 v[36:37], v[36:37], v[190:191] op_sel_hi:[1,0]
	v_pk_mul_f32 v[34:35], v[34:35], v[190:191] op_sel_hi:[1,0]
	v_pk_mul_f32 v[32:33], v[32:33], v[190:191] op_sel_hi:[1,0]
	v_pk_mul_f32 v[30:31], v[30:31], v[190:191] op_sel_hi:[1,0]
	v_pk_mul_f32 v[28:29], v[28:29], v[190:191] op_sel_hi:[1,0]
	v_pk_mul_f32 v[26:27], v[26:27], v[190:191] op_sel_hi:[1,0]
	v_pk_mul_f32 v[24:25], v[24:25], v[190:191] op_sel_hi:[1,0]
	v_pk_mul_f32 v[22:23], v[22:23], v[190:191] op_sel_hi:[1,0]
	v_pk_mul_f32 v[20:21], v[20:21], v[190:191] op_sel_hi:[1,0]
	v_pk_mul_f32 v[18:19], v[18:19], v[190:191] op_sel_hi:[1,0]
	v_pk_mul_f32 v[16:17], v[16:17], v[190:191] op_sel_hi:[1,0]
	v_pk_mul_f32 v[14:15], v[14:15], v[190:191] op_sel_hi:[1,0]
	v_pk_mul_f32 v[12:13], v[12:13], v[190:191] op_sel_hi:[1,0]
	v_pk_mul_f32 v[10:11], v[10:11], v[190:191] op_sel_hi:[1,0]
	v_pk_mul_f32 v[8:9], v[8:9], v[190:191] op_sel_hi:[1,0]
	v_pk_mul_f32 v[6:7], v[6:7], v[190:191] op_sel_hi:[1,0]
	v_pk_mul_f32 v[4:5], v[4:5], v[190:191] op_sel_hi:[1,0]
	v_pk_mul_f32 v[2:3], v[2:3], v[190:191] op_sel_hi:[1,0]
	v_pk_mul_f32 v[0:1], v[0:1], v[190:191] op_sel_hi:[1,0]
	v_mul_f32_e32 v203, v203, v190
	v_mov_b32_e32 v190, v246
	v_sub_f32_e32 v222, v222, v190
	v_exp_f32_e32 v222, v222
	v_sub_f32_e32 v223, v223, v190
	v_exp_f32_e32 v223, v223
	v_sub_f32_e32 v224, v224, v190
	v_add_f32_e32 v254, 0, v222
	v_exp_f32_e32 v224, v224
	v_sub_f32_e32 v225, v225, v190
	v_add_f32_e32 v254, v223, v254
	v_exp_f32_e32 v225, v225
	v_sub_f32_e32 v226, v226, v190
	v_add_f32_e32 v254, v224, v254
	v_exp_f32_e32 v226, v226
	v_sub_f32_e32 v227, v227, v190
	v_add_f32_e32 v254, v225, v254
	v_exp_f32_e32 v227, v227
	v_sub_f32_e32 v228, v228, v190
	v_add_f32_e32 v254, v226, v254
	v_exp_f32_e32 v228, v228
	v_sub_f32_e32 v229, v229, v190
	v_add_f32_e32 v254, v227, v254
	v_exp_f32_e32 v229, v229
	v_sub_f32_e32 v230, v230, v190
	v_add_f32_e32 v254, v228, v254
	v_exp_f32_e32 v230, v230
	v_sub_f32_e32 v231, v231, v190
	v_add_f32_e32 v254, v229, v254
	v_exp_f32_e32 v231, v231
	v_sub_f32_e32 v232, v232, v190
	v_add_f32_e32 v254, v230, v254
	v_exp_f32_e32 v232, v232
	v_sub_f32_e32 v233, v233, v190
	v_add_f32_e32 v254, v231, v254
	v_exp_f32_e32 v233, v233
	v_sub_f32_e32 v234, v234, v190
	v_add_f32_e32 v254, v232, v254
	v_exp_f32_e32 v234, v234
	v_sub_f32_e32 v235, v235, v190
	v_add_f32_e32 v254, v233, v254
	v_exp_f32_e32 v235, v235
	v_sub_f32_e32 v236, v236, v190
	v_add_f32_e32 v254, v234, v254
	v_exp_f32_e32 v236, v236
	v_sub_f32_e32 v237, v237, v190
	v_add_f32_e32 v254, v235, v254
	v_exp_f32_e32 v237, v237
	v_add_f32_e32 v254, v236, v254
	v_add_f32_e32 v254, v237, v254
	v_cvt_pk_bf16_f32 v242, v222, v223
	v_cvt_pk_bf16_f32 v243, v224, v225
	v_cvt_pk_bf16_f32 v244, v226, v227
	v_cvt_pk_bf16_f32 v245, v228, v229
	v_cvt_pk_bf16_f32 v250, v230, v231
	v_cvt_pk_bf16_f32 v251, v232, v233
	v_cvt_pk_bf16_f32 v252, v234, v235
	v_cvt_pk_bf16_f32 v253, v236, v237
	v_add_f32_e32 v203, v203, v254
	s_nop 1
	s_waitcnt lgkmcnt(8)
	v_mfma_f32_32x32x16_bf16 v[112:127], v[238:241], v[242:245], v[112:127]
	ds_read_b64_tr_b16 v[238:239], v218 offset:16640
	ds_read_b64_tr_b16 v[240:241], v218 offset:20736
	s_waitcnt lgkmcnt(8)
	v_mfma_f32_32x32x16_bf16 v[96:111], v[128:131], v[242:245], v[96:111]
	ds_read_b64_tr_b16 v[222:223], v219 offset:16640
	ds_read_b64_tr_b16 v[224:225], v219 offset:20736
	s_waitcnt lgkmcnt(8)
	v_mfma_f32_32x32x16_bf16 v[80:95], v[206:209], v[242:245], v[80:95]
	ds_read_b64_tr_b16 v[206:207], v221 offset:16640
	ds_read_b64_tr_b16 v[208:209], v221 offset:20736
	s_waitcnt lgkmcnt(8)
	v_mfma_f32_32x32x16_bf16 v[64:79], v[210:213], v[242:245], v[64:79]
	ds_read_b64_tr_b16 v[210:211], v205 offset:24576
	ds_read_b64_tr_b16 v[212:213], v205 offset:28672
	s_waitcnt lgkmcnt(8)
	v_mfma_f32_32x32x16_bf16 v[48:63], v[214:217], v[242:245], v[48:63]
	ds_read_b64_tr_b16 v[214:215], v218 offset:24576
	ds_read_b64_tr_b16 v[216:217], v218 offset:28672
	s_waitcnt lgkmcnt(8)
	v_mfma_f32_32x32x16_bf16 v[32:47], v[238:241], v[242:245], v[32:47]
	ds_read_b64_tr_b16 v[238:239], v219 offset:24576
	ds_read_b64_tr_b16 v[240:241], v219 offset:28672
	s_waitcnt lgkmcnt(8)
	v_mfma_f32_32x32x16_bf16 v[16:31], v[222:225], v[242:245], v[16:31]
	ds_read_b64_tr_b16 v[222:223], v221 offset:24576
	ds_read_b64_tr_b16 v[224:225], v221 offset:28672
	s_waitcnt lgkmcnt(8)
	v_mfma_f32_32x32x16_bf16 v[0:15], v[206:209], v[242:245], v[0:15]
	ds_read_b64_tr_b16 v[206:207], v205 offset:24832
	ds_read_b64_tr_b16 v[208:209], v205 offset:28928
	s_waitcnt lgkmcnt(8)
	v_mfma_f32_32x32x16_bf16 v[112:127], v[210:213], v[250:253], v[112:127]
	ds_read_b64_tr_b16 v[210:211], v218 offset:24832
	ds_read_b64_tr_b16 v[212:213], v218 offset:28928
	s_waitcnt lgkmcnt(8)
	v_mfma_f32_32x32x16_bf16 v[96:111], v[214:217], v[250:253], v[96:111]
	ds_read_b64_tr_b16 v[214:215], v219 offset:24832
	ds_read_b64_tr_b16 v[216:217], v219 offset:28928
	s_waitcnt lgkmcnt(8)
	v_mfma_f32_32x32x16_bf16 v[80:95], v[238:241], v[250:253], v[80:95]
	ds_read_b64_tr_b16 v[238:239], v221 offset:24832
	ds_read_b64_tr_b16 v[240:241], v221 offset:28928
	s_waitcnt lgkmcnt(8)
	v_mfma_f32_32x32x16_bf16 v[64:79], v[222:225], v[250:253], v[64:79]
	s_waitcnt lgkmcnt(6)
	v_mfma_f32_32x32x16_bf16 v[48:63], v[206:209], v[250:253], v[48:63]
	s_waitcnt lgkmcnt(4)
	v_mfma_f32_32x32x16_bf16 v[32:47], v[210:213], v[250:253], v[32:47]
	s_waitcnt lgkmcnt(2)
	v_mfma_f32_32x32x16_bf16 v[16:31], v[214:217], v[250:253], v[16:31]
	s_waitcnt lgkmcnt(0)
	v_mfma_f32_32x32x16_bf16 v[0:15], v[238:241], v[250:253], v[0:15]
	ds_read_b128 v[206:209], v195 offset:16384
	ds_read_b128 v[210:213], v196 offset:16384
	ds_read_b128 v[214:217], v197 offset:16384
	ds_read_b128 v[238:241], v198 offset:16384
	ds_read_b128 v[242:245], v199 offset:16384
	ds_read_b128 v[250:253], v200 offset:16384
	ds_read_b128 v[222:225], v201 offset:16384
	ds_read_b128 v[226:229], v202 offset:16384
	s_waitcnt vmcnt(0)
	s_add_i32 s12, s34, 1
	s_cmp_lg_u32 s34, 2
	s_cselect_b32 s34, s12, 0
	s_add_i32 s72, s72, 64
	s_add_u32 s20, s20, 0x100000
	s_addc_u32 s21, s21, 0
	s_add_i32 s73, s73, 1
	s_add_i32 s100, s72, 63
	s_cmp_le_i32 s100, s68
	s_cbranch_scc0 .Latt_latchb_6
	s_cmp_ge_u32 s73, s66
	s_cselect_b64 s[12:13], -1, 0
	v_mov_b32_e32 v204, v176
	s_barrier
	s_branch .Latt_cont_6s1
.Latt_slow_6s0:
.Latt_slot1_6:
.Latt_cont_6s1:
	v_add_u32_e32 v205, 0x8000, v205
	v_add_u32_e32 v218, 0x8000, v218
	v_add_u32_e32 v219, 0x8000, v219
	v_add_u32_e32 v221, 0x8000, v221
	s_waitcnt lgkmcnt(7)
	v_mfma_f32_32x32x16_bf16 v[128:143], v[206:209], v[144:147], 0
	ds_read_b128 v[206:209], v195 offset:24576
	s_cmp_lg_u64 s[12:13], 0
	s_cbranch_scc1 .Latt_nd0_6s1
	s_sub_i32 s100, s34, 1
	s_cmp_eq_u32 s34, 0
	s_cselect_b32 s100, 2, s100
	s_lshl_b32 s101, s100, 14
	s_add_i32 m0, s36, s101
	s_nop 0
	global_load_lds_dwordx4 v178, s[20:21]

.Latt_nr0_6s1:
	s_waitcnt lgkmcnt(3)
	v_mfma_f32_32x32x16_bf16 v[222:237], v[214:217], v[152:155], v[222:237]
	ds_read_b128 v[214:217], v201 offset:24576
	v_sub_f32_e32 v128, v128, v190
	v_exp_f32_e32 v128, v128
	v_sub_f32_e32 v129, v129, v190
	v_exp_f32_e32 v129, v129
	v_sub_f32_e32 v130, v130, v190
	s_waitcnt lgkmcnt(3)
	v_mfma_f32_32x32x16_bf16 v[222:237], v[238:241], v[156:159], v[222:237]
	ds_read_b128 v[238:241], v202 offset:24576
	v_add_f32_e32 v254, 0, v128
	v_exp_f32_e32 v130, v130
	v_sub_f32_e32 v131, v131, v190
	v_add_f32_e32 v254, v129, v254
	v_exp_f32_e32 v131, v131
	s_waitcnt lgkmcnt(3)
	v_mfma_f32_32x32x16_bf16 v[222:237], v[206:209], v[160:163], v[222:237]
	ds_read_b64_tr_b16 v[206:207], v205
	ds_read_b64_tr_b16 v[208:209], v205 offset:4096
	v_sub_f32_e32 v132, v132, v190
	v_add_f32_e32 v254, v130, v254
	v_exp_f32_e32 v132, v132
	v_sub_f32_e32 v133, v133, v190
	v_add_f32_e32 v254, v131, v254
	s_waitcnt lgkmcnt(4)
	v_mfma_f32_32x32x16_bf16 v[222:237], v[210:213], v[164:167], v[222:237]
	ds_read_b64_tr_b16 v[210:211], v218
	ds_read_b64_tr_b16 v[212:213], v218 offset:4096
	v_exp_f32_e32 v133, v133
	v_sub_f32_e32 v134, v134, v190
	v_add_f32_e32 v254, v132, v254
	v_exp_f32_e32 v134, v134
	s_waitcnt lgkmcnt(5)
	v_mfma_f32_32x32x16_bf16 v[222:237], v[214:217], v[168:171], v[222:237]
	ds_read_b64_tr_b16 v[214:215], v219
	ds_read_b64_tr_b16 v[216:217], v219 offset:4096
	v_sub_f32_e32 v135, v135, v190
	v_add_f32_e32 v254, v133, v254
	v_exp_f32_e32 v135, v135
	s_nop 0
	s_waitcnt lgkmcnt(6)
	v_mfma_f32_32x32x16_bf16 v[222:237], v[238:241], v[172:175], v[222:237]
	ds_read_b64_tr_b16 v[238:239], v221
	ds_read_b64_tr_b16 v[240:241], v221 offset:4096
	v_cvt_pk_bf16_f32 v242, v128, v129
	v_cvt_pk_bf16_f32 v243, v130, v131
	v_cvt_pk_bf16_f32 v244, v132, v133
	v_cvt_pk_bf16_f32 v245, v134, v135
	s_nop 1
	s_waitcnt lgkmcnt(6)
	v_mfma_f32_32x32x16_bf16 v[112:127], v[206:209], v[242:245], v[112:127]
	ds_read_b64_tr_b16 v[206:207], v205 offset:256
	ds_read_b64_tr_b16 v[208:209], v205 offset:4352
	v_sub_f32_e32 v136, v136, v190
	v_add_f32_e32 v254, v134, v254
	v_exp_f32_e32 v136, v136
	v_sub_f32_e32 v137, v137, v190
	v_add_f32_e32 v254, v135, v254
	s_waitcnt lgkmcnt(6)
	v_mfma_f32_32x32x16_bf16 v[96:111], v[210:213], v[242:245], v[96:111]
	ds_read_b64_tr_b16 v[210:211], v218 offset:256
	ds_read_b64_tr_b16 v[212:213], v218 offset:4352
	v_exp_f32_e32 v137, v137
	v_sub_f32_e32 v138, v138, v190
	v_add_f32_e32 v254, v136, v254
	v_exp_f32_e32 v138, v138
	v_sub_f32_e32 v139, v139, v190
	s_waitcnt lgkmcnt(6)
	v_mfma_f32_32x32x16_bf16 v[80:95], v[214:217], v[242:245], v[80:95]
	ds_read_b64_tr_b16 v[214:215], v219 offset:256
	ds_read_b64_tr_b16 v[216:217], v219 offset:4352
	v_add_f32_e32 v254, v137, v254
	v_exp_f32_e32 v139, v139
	v_sub_f32_e32 v140, v140, v190
	v_add_f32_e32 v254, v138, v254
	s_waitcnt lgkmcnt(6)
	v_mfma_f32_32x32x16_bf16 v[64:79], v[238:241], v[242:245], v[64:79]
	ds_read_b64_tr_b16 v[238:239], v221 offset:256
	ds_read_b64_tr_b16 v[240:241], v221 offset:4352
	v_exp_f32_e32 v140, v140
	v_sub_f32_e32 v141, v141, v190
	v_add_f32_e32 v254, v139, v254
	v_exp_f32_e32 v141, v141
	s_waitcnt lgkmcnt(6)
	v_mfma_f32_32x32x16_bf16 v[48:63], v[206:209], v[242:245], v[48:63]
	ds_read_b64_tr_b16 v[206:207], v205 offset:8192
	ds_read_b64_tr_b16 v[208:209], v205 offset:12288
	v_sub_f32_e32 v142, v142, v190
	v_add_f32_e32 v254, v140, v254
	v_exp_f32_e32 v142, v142
	v_sub_f32_e32 v143, v143, v190
	s_waitcnt lgkmcnt(6)
	v_mfma_f32_32x32x16_bf16 v[32:47], v[210:213], v[242:245], v[32:47]
	ds_read_b64_tr_b16 v[210:211], v218 offset:8192
	ds_read_b64_tr_b16 v[212:213], v218 offset:12288
	v_add_f32_e32 v254, v141, v254
	v_exp_f32_e32 v143, v143
	v_add_f32_e32 v254, v142, v254
	v_add_f32_e32 v254, v143, v254
	s_waitcnt lgkmcnt(6)
	v_mfma_f32_32x32x16_bf16 v[16:31], v[214:217], v[242:245], v[16:31]
	ds_read_b64_tr_b16 v[214:215], v219 offset:8192
	ds_read_b64_tr_b16 v[216:217], v219 offset:12288
	v_cvt_pk_bf16_f32 v250, v136, v137
	v_cvt_pk_bf16_f32 v251, v138, v139
	v_cvt_pk_bf16_f32 v252, v140, v141
	v_cvt_pk_bf16_f32 v253, v142, v143
	v_add_f32_e32 v203, v203, v254
	s_waitcnt lgkmcnt(6)
	v_mfma_f32_32x32x16_bf16 v[0:15], v[238:241], v[242:245], v[0:15]
	ds_read_b64_tr_b16 v[238:239], v221 offset:8192
	ds_read_b64_tr_b16 v[240:241], v221 offset:12288
	ds_read_b64_tr_b16 v[128:129], v205 offset:8448
	ds_read_b64_tr_b16 v[130:131], v205 offset:12544
	s_waitcnt lgkmcnt(8)
	v_mfma_f32_32x32x16_bf16 v[112:127], v[206:209], v[250:253], v[112:127]
	ds_read_b64_tr_b16 v[206:207], v218 offset:8448
	ds_read_b64_tr_b16 v[208:209], v218 offset:12544
	v_max3_f32 v246, v222, v223, v224
	v_max3_f32 v247, v225, v226, v227
	v_max3_f32 v246, v246, v228, v229
	v_max3_f32 v247, v247, v230, v231
	v_max3_f32 v246, v246, v232, v233
	s_waitcnt lgkmcnt(8)
	v_mfma_f32_32x32x16_bf16 v[96:111], v[210:213], v[250:253], v[96:111]
	ds_read_b64_tr_b16 v[210:211], v219 offset:8448
	ds_read_b64_tr_b16 v[212:213], v219 offset:12544
	v_max3_f32 v247, v247, v234, v235
	v_max3_f32 v246, v246, v236, v237
	v_max_f32_e32 v246, v246, v247
	v_mov_b32_e32 v247, v246
	v_add_f32_e32 v249, 0x41000000, v190
	s_waitcnt lgkmcnt(8)
	v_mfma_f32_32x32x16_bf16 v[80:95], v[214:217], v[250:253], v[80:95]
	ds_read_b64_tr_b16 v[214:215], v221 offset:8448
	ds_read_b64_tr_b16 v[216:217], v221 offset:12544
	s_nop 1
	v_permlane32_swap_b32_e32 v246, v247
	v_max_f32_e32 v246, v246, v247
	v_cmp_gt_f32_e32 vcc, v246, v249
	s_cbranch_vccnz .Latt_rs1_6s1
	s_waitcnt lgkmcnt(8)
	v_mfma_f32_32x32x16_bf16 v[64:79], v[238:241], v[250:253], v[64:79]
	ds_read_b64_tr_b16 v[238:239], v205 offset:16384
	ds_read_b64_tr_b16 v[240:241], v205 offset:20480
	v_sub_f32_e32 v222, v222, v190
	v_exp_f32_e32 v222, v222
	v_sub_f32_e32 v223, v223, v190
	v_exp_f32_e32 v223, v223
	v_sub_f32_e32 v224, v224, v190
	v_add_f32_e32 v254, 0, v222
	s_waitcnt lgkmcnt(8)
	v_mfma_f32_32x32x16_bf16 v[48:63], v[128:131], v[250:253], v[48:63]
	ds_read_b64_tr_b16 v[128:129], v218 offset:16384
	ds_read_b64_tr_b16 v[130:131], v218 offset:20480
	v_exp_f32_e32 v224, v224
	v_sub_f32_e32 v225, v225, v190
	v_add_f32_e32 v254, v223, v254
	v_exp_f32_e32 v225, v225
	v_sub_f32_e32 v226, v226, v190
	v_add_f32_e32 v254, v224, v254
	s_waitcnt lgkmcnt(8)
	v_mfma_f32_32x32x16_bf16 v[32:47], v[206:209], v[250:253], v[32:47]
	ds_read_b64_tr_b16 v[206:207], v219 offset:16384
	ds_read_b64_tr_b16 v[208:209], v219 offset:20480
	v_exp_f32_e32 v226, v226
	v_sub_f32_e32 v227, v227, v190
	v_add_f32_e32 v254, v225, v254
	v_exp_f32_e32 v227, v227
	v_sub_f32_e32 v228, v228, v190
	s_waitcnt lgkmcnt(8)
	v_mfma_f32_32x32x16_bf16 v[16:31], v[210:213], v[250:253], v[16:31]
	ds_read_b64_tr_b16 v[210:211], v221 offset:16384
	ds_read_b64_tr_b16 v[212:213], v221 offset:20480
	v_add_f32_e32 v254, v226, v254
	v_exp_f32_e32 v228, v228
	v_sub_f32_e32 v229, v229, v190
	v_add_f32_e32 v254, v227, v254
	v_exp_f32_e32 v229, v229
	s_waitcnt lgkmcnt(8)
	v_mfma_f32_32x32x16_bf16 v[0:15], v[214:217], v[250:253], v[0:15]
	ds_read_b64_tr_b16 v[214:215], v205 offset:16640
	ds_read_b64_tr_b16 v[216:217], v205 offset:20736
	s_nop 0
	v_cvt_pk_bf16_f32 v242, v222, v223
	v_cvt_pk_bf16_f32 v243, v224, v225
	v_cvt_pk_bf16_f32 v244, v226, v227
	v_cvt_pk_bf16_f32 v245, v228, v229
	s_nop 1
	s_waitcnt lgkmcnt(8)
	v_mfma_f32_32x32x16_bf16 v[112:127], v[238:241], v[242:245], v[112:127]
	ds_read_b64_tr_b16 v[238:239], v218 offset:16640
	ds_read_b64_tr_b16 v[240:241], v218 offset:20736
	v_sub_f32_e32 v230, v230, v190
	v_add_f32_e32 v254, v228, v254
	v_exp_f32_e32 v230, v230
	v_sub_f32_e32 v231, v231, v190
	v_add_f32_e32 v254, v229, v254
	s_waitcnt lgkmcnt(8)
	v_mfma_f32_32x32x16_bf16 v[96:111], v[128:131], v[242:245], v[96:111]
	ds_read_b64_tr_b16 v[128:129], v219 offset:16640
	ds_read_b64_tr_b16 v[130:131], v219 offset:20736
	v_exp_f32_e32 v231, v231
	v_sub_f32_e32 v232, v232, v190
	v_add_f32_e32 v254, v230, v254
	v_exp_f32_e32 v232, v232
	v_sub_f32_e32 v233, v233, v190
	s_waitcnt lgkmcnt(8)
	v_mfma_f32_32x32x16_bf16 v[80:95], v[206:209], v[242:245], v[80:95]
	ds_read_b64_tr_b16 v[206:207], v221 offset:16640
	ds_read_b64_tr_b16 v[208:209], v221 offset:20736
	v_add_f32_e32 v254, v231, v254
	v_exp_f32_e32 v233, v233
	v_sub_f32_e32 v234, v234, v190
	v_add_f32_e32 v254, v232, v254
	s_waitcnt lgkmcnt(8)
	v_mfma_f32_32x32x16_bf16 v[64:79], v[210:213], v[242:245], v[64:79]
	ds_read_b64_tr_b16 v[210:211], v205 offset:24576
	ds_read_b64_tr_b16 v[212:213], v205 offset:28672
	v_exp_f32_e32 v234, v234
	v_sub_f32_e32 v235, v235, v190
	v_add_f32_e32 v254, v233, v254
	v_exp_f32_e32 v235, v235
	s_waitcnt lgkmcnt(8)
	v_mfma_f32_32x32x16_bf16 v[48:63], v[214:217], v[242:245], v[48:63]
	ds_read_b64_tr_b16 v[214:215], v218 offset:24576
	ds_read_b64_tr_b16 v[216:217], v218 offset:28672
	v_sub_f32_e32 v236, v236, v190
	v_add_f32_e32 v254, v234, v254
	v_exp_f32_e32 v236, v236
	v_sub_f32_e32 v237, v237, v190
	s_waitcnt lgkmcnt(8)
	v_mfma_f32_32x32x16_bf16 v[32:47], v[238:241], v[242:245], v[32:47]
	ds_read_b64_tr_b16 v[238:239], v219 offset:24576
	ds_read_b64_tr_b16 v[240:241], v219 offset:28672
	v_add_f32_e32 v254, v235, v254
	v_exp_f32_e32 v237, v237
	v_add_f32_e32 v254, v236, v254
	v_add_f32_e32 v254, v237, v254
	s_waitcnt lgkmcnt(8)
	v_mfma_f32_32x32x16_bf16 v[16:31], v[128:131], v[242:245], v[16:31]
	ds_read_b64_tr_b16 v[128:129], v221 offset:24576
	ds_read_b64_tr_b16 v[130:131], v221 offset:28672
	v_cvt_pk_bf16_f32 v250, v230, v231
	v_cvt_pk_bf16_f32 v251, v232, v233
	v_cvt_pk_bf16_f32 v252, v234, v235
	v_cvt_pk_bf16_f32 v253, v236, v237
	v_add_f32_e32 v203, v203, v254
	s_waitcnt lgkmcnt(8)
	v_mfma_f32_32x32x16_bf16 v[0:15], v[206:209], v[242:245], v[0:15]
	ds_read_b64_tr_b16 v[206:207], v205 offset:24832
	ds_read_b64_tr_b16 v[208:209], v205 offset:28928
	s_waitcnt lgkmcnt(8)
	v_mfma_f32_32x32x16_bf16 v[112:127], v[210:213], v[250:253], v[112:127]
	ds_read_b64_tr_b16 v[210:211], v218 offset:24832
	ds_read_b64_tr_b16 v[212:213], v218 offset:28928
	s_waitcnt lgkmcnt(8)
	v_mfma_f32_32x32x16_bf16 v[96:111], v[214:217], v[250:253], v[96:111]
	ds_read_b64_tr_b16 v[214:215], v219 offset:24832
	ds_read_b64_tr_b16 v[216:217], v219 offset:28928
	s_waitcnt lgkmcnt(8)
	v_mfma_f32_32x32x16_bf16 v[80:95], v[238:241], v[250:253], v[80:95]
	ds_read_b64_tr_b16 v[238:239], v221 offset:24832
	ds_read_b64_tr_b16 v[240:241], v221 offset:28928
	s_waitcnt lgkmcnt(8)
	v_mfma_f32_32x32x16_bf16 v[64:79], v[128:131], v[250:253], v[64:79]
	s_waitcnt lgkmcnt(6)
	v_mfma_f32_32x32x16_bf16 v[48:63], v[206:209], v[250:253], v[48:63]
	s_waitcnt lgkmcnt(4)
	v_mfma_f32_32x32x16_bf16 v[32:47], v[210:213], v[250:253], v[32:47]
	s_waitcnt lgkmcnt(2)
	v_mfma_f32_32x32x16_bf16 v[16:31], v[214:217], v[250:253], v[16:31]
	s_waitcnt lgkmcnt(0)
	v_mfma_f32_32x32x16_bf16 v[0:15], v[238:241], v[250:253], v[0:15]
	ds_read_b128 v[206:209], v195 offset:32768
	ds_read_b128 v[210:213], v196 offset:32768
	ds_read_b128 v[214:217], v197 offset:32768
	ds_read_b128 v[238:241], v198 offset:32768
	ds_read_b128 v[242:245], v199 offset:32768
	ds_read_b128 v[250:253], v200 offset:32768
	ds_read_b128 v[222:225], v201 offset:32768
	ds_read_b128 v[226:229], v202 offset:32768
	s_waitcnt vmcnt(0)
	s_add_i32 s12, s34, 1
	s_cmp_lg_u32 s34, 2
	s_cselect_b32 s34, s12, 0
	s_add_i32 s72, s72, 64
	s_add_u32 s20, s20, 0x100000
	s_addc_u32 s21, s21, 0
	s_add_i32 s73, s73, 1
	s_add_i32 s100, s72, 63
	s_cmp_le_i32 s100, s68
	s_cbranch_scc0 .Latt_latchb_6
	s_cmp_ge_u32 s73, s66
	s_cselect_b64 s[12:13], -1, 0
	v_mov_b32_e32 v204, v176
	s_barrier
	s_branch .Latt_cont_6s2
.Latt_rs1_6s1:
	s_waitcnt lgkmcnt(8)
	v_mfma_f32_32x32x16_bf16 v[64:79], v[238:241], v[250:253], v[64:79]
	ds_read_b64_tr_b16 v[238:239], v205 offset:16384
	ds_read_b64_tr_b16 v[240:241], v205 offset:20480
	s_waitcnt lgkmcnt(8)
	v_mfma_f32_32x32x16_bf16 v[48:63], v[128:131], v[250:253], v[48:63]
	ds_read_b64_tr_b16 v[128:129], v218 offset:16384
	ds_read_b64_tr_b16 v[130:131], v218 offset:20480
	s_waitcnt lgkmcnt(8)
	v_mfma_f32_32x32x16_bf16 v[32:47], v[206:209], v[250:253], v[32:47]
	ds_read_b64_tr_b16 v[206:207], v219 offset:16384
	ds_read_b64_tr_b16 v[208:209], v219 offset:20480
	s_waitcnt lgkmcnt(8)
	v_mfma_f32_32x32x16_bf16 v[16:31], v[210:213], v[250:253], v[16:31]
	ds_read_b64_tr_b16 v[210:211], v221 offset:16384
	ds_read_b64_tr_b16 v[212:213], v221 offset:20480
	s_waitcnt lgkmcnt(8)
	v_mfma_f32_32x32x16_bf16 v[0:15], v[214:217], v[250:253], v[0:15]
	ds_read_b64_tr_b16 v[214:215], v205 offset:16640
	ds_read_b64_tr_b16 v[216:217], v205 offset:20736
	s_nop 11
	v_max_f32_e32 v246, v190, v246
	v_sub_f32_e32 v190, v190, v246
	v_exp_f32_e32 v190, v190
	s_nop 0
	v_pk_mul_f32 v[126:127], v[126:127], v[190:191] op_sel_hi:[1,0]
	v_pk_mul_f32 v[124:125], v[124:125], v[190:191] op_sel_hi:[1,0]
	v_pk_mul_f32 v[122:123], v[122:123], v[190:191] op_sel_hi:[1,0]
	v_pk_mul_f32 v[120:121], v[120:121], v[190:191] op_sel_hi:[1,0]
	v_pk_mul_f32 v[118:119], v[118:119], v[190:191] op_sel_hi:[1,0]
	v_pk_mul_f32 v[116:117], v[116:117], v[190:191] op_sel_hi:[1,0]
	v_pk_mul_f32 v[114:115], v[114:115], v[190:191] op_sel_hi:[1,0]
	v_pk_mul_f32 v[112:113], v[112:113], v[190:191] op_sel_hi:[1,0]
	v_pk_mul_f32 v[110:111], v[110:111], v[190:191] op_sel_hi:[1,0]
	v_pk_mul_f32 v[108:109], v[108:109], v[190:191] op_sel_hi:[1,0]
	v_pk_mul_f32 v[106:107], v[106:107], v[190:191] op_sel_hi:[1,0]
	v_pk_mul_f32 v[104:105], v[104:105], v[190:191] op_sel_hi:[1,0]
	v_pk_mul_f32 v[102:103], v[102:103], v[190:191] op_sel_hi:[1,0]
	v_pk_mul_f32 v[100:101], v[100:101], v[190:191] op_sel_hi:[1,0]
	v_pk_mul_f32 v[98:99], v[98:99], v[190:191] op_sel_hi:[1,0]
	v_pk_mul_f32 v[96:97], v[96:97], v[190:191] op_sel_hi:[1,0]
	v_pk_mul_f32 v[94:95], v[94:95], v[190:191] op_sel_hi:[1,0]
	v_pk_mul_f32 v[92:93], v[92:93], v[190:191] op_sel_hi:[1,0]
	v_pk_mul_f32 v[90:91], v[90:91], v[190:191] op_sel_hi:[1,0]
	v_pk_mul_f32 v[88:89], v[88:89], v[190:191] op_sel_hi:[1,0]
	v_pk_mul_f32 v[86:87], v[86:87], v[190:191] op_sel_hi:[1,0]
	v_pk_mul_f32 v[84:85], v[84:85], v[190:191] op_sel_hi:[1,0]
	v_pk_mul_f32 v[82:83], v[82:83], v[190:191] op_sel_hi:[1,0]
	v_pk_mul_f32 v[80:81], v[80:81], v[190:191] op_sel_hi:[1,0]
	v_pk_mul_f32 v[78:79], v[78:79], v[190:191] op_sel_hi:[1,0]
	v_pk_mul_f32 v[76:77], v[76:77], v[190:191] op_sel_hi:[1,0]
	v_pk_mul_f32 v[74:75], v[74:75], v[190:191] op_sel_hi:[1,0]
	v_pk_mul_f32 v[72:73], v[72:73], v[190:191] op_sel_hi:[1,0]
	v_pk_mul_f32 v[70:71], v[70:71], v[190:191] op_sel_hi:[1,0]
	v_pk_mul_f32 v[68:69], v[68:69], v[190:191] op_sel_hi:[1,0]
	v_pk_mul_f32 v[66:67], v[66:67], v[190:191] op_sel_hi:[1,0]
	v_pk_mul_f32 v[64:65], v[64:65], v[190:191] op_sel_hi:[1,0]
	v_pk_mul_f32 v[62:63], v[62:63], v[190:191] op_sel_hi:[1,0]
	v_pk_mul_f32 v[60:61], v[60:61], v[190:191] op_sel_hi:[1,0]
	v_pk_mul_f32 v[58:59], v[58:59], v[190:191] op_sel_hi:[1,0]
	v_pk_mul_f32 v[56:57], v[56:57], v[190:191] op_sel_hi:[1,0]
	v_pk_mul_f32 v[54:55], v[54:55], v[190:191] op_sel_hi:[1,0]
	v_pk_mul_f32 v[52:53], v[52:53], v[190:191] op_sel_hi:[1,0]
	v_pk_mul_f32 v[50:51], v[50:51], v[190:191] op_sel_hi:[1,0]
	v_pk_mul_f32 v[48:49], v[48:49], v[190:191] op_sel_hi:[1,0]
	v_pk_mul_f32 v[46:47], v[46:47], v[190:191] op_sel_hi:[1,0]
	v_pk_mul_f32 v[44:45], v[44:45], v[190:191] op_sel_hi:[1,0]
	v_pk_mul_f32 v[42:43], v[42:43], v[190:191] op_sel_hi:[1,0]
	v_pk_mul_f32 v[40:41], v[40:41], v[190:191] op_sel_hi:[1,0]
	v_pk_mul_f32 v[38:39], v[38:39], v[190:191] op_sel_hi:[1,0]
	v_pk_mul_f32 v[36:37], v[36:37], v[190:191] op_sel_hi:[1,0]
	v_pk_mul_f32 v[34:35], v[34:35], v[190:191] op_sel_hi:[1,0]
	v_pk_mul_f32 v[32:33], v[32:33], v[190:191] op_sel_hi:[1,0]
	v_pk_mul_f32 v[30:31], v[30:31], v[190:191] op_sel_hi:[1,0]
	v_pk_mul_f32 v[28:29], v[28:29], v[190:191] op_sel_hi:[1,0]
	v_pk_mul_f32 v[26:27], v[26:27], v[190:191] op_sel_hi:[1,0]
	v_pk_mul_f32 v[24:25], v[24:25], v[190:191] op_sel_hi:[1,0]
	v_pk_mul_f32 v[22:23], v[22:23], v[190:191] op_sel_hi:[1,0]
	v_pk_mul_f32 v[20:21], v[20:21], v[190:191] op_sel_hi:[1,0]
	v_pk_mul_f32 v[18:19], v[18:19], v[190:191] op_sel_hi:[1,0]
	v_pk_mul_f32 v[16:17], v[16:17], v[190:191] op_sel_hi:[1,0]
	v_pk_mul_f32 v[14:15], v[14:15], v[190:191] op_sel_hi:[1,0]
	v_pk_mul_f32 v[12:13], v[12:13], v[190:191] op_sel_hi:[1,0]
	v_pk_mul_f32 v[10:11], v[10:11], v[190:191] op_sel_hi:[1,0]
	v_pk_mul_f32 v[8:9], v[8:9], v[190:191] op_sel_hi:[1,0]
	v_pk_mul_f32 v[6:7], v[6:7], v[190:191] op_sel_hi:[1,0]
	v_pk_mul_f32 v[4:5], v[4:5], v[190:191] op_sel_hi:[1,0]
	v_pk_mul_f32 v[2:3], v[2:3], v[190:191] op_sel_hi:[1,0]
	v_pk_mul_f32 v[0:1], v[0:1], v[190:191] op_sel_hi:[1,0]
	v_mul_f32_e32 v203, v203, v190
	v_mov_b32_e32 v190, v246
	v_sub_f32_e32 v222, v222, v190
	v_exp_f32_e32 v222, v222
	v_sub_f32_e32 v223, v223, v190
	v_exp_f32_e32 v223, v223
	v_sub_f32_e32 v224, v224, v190
	v_add_f32_e32 v254, 0, v222
	v_exp_f32_e32 v224, v224
	v_sub_f32_e32 v225, v225, v190
	v_add_f32_e32 v254, v223, v254
	v_exp_f32_e32 v225, v225
	v_sub_f32_e32 v226, v226, v190
	v_add_f32_e32 v254, v224, v254
	v_exp_f32_e32 v226, v226
	v_sub_f32_e32 v227, v227, v190
	v_add_f32_e32 v254, v225, v254
	v_exp_f32_e32 v227, v227
	v_sub_f32_e32 v228, v228, v190
	v_add_f32_e32 v254, v226, v254
	v_exp_f32_e32 v228, v228
	v_sub_f32_e32 v229, v229, v190
	v_add_f32_e32 v254, v227, v254
	v_exp_f32_e32 v229, v229
	v_sub_f32_e32 v230, v230, v190
	v_add_f32_e32 v254, v228, v254
	v_exp_f32_e32 v230, v230
	v_sub_f32_e32 v231, v231, v190
	v_add_f32_e32 v254, v229, v254
	v_exp_f32_e32 v231, v231
	v_sub_f32_e32 v232, v232, v190
	v_add_f32_e32 v254, v230, v254
	v_exp_f32_e32 v232, v232
	v_sub_f32_e32 v233, v233, v190
	v_add_f32_e32 v254, v231, v254
	v_exp_f32_e32 v233, v233
	v_sub_f32_e32 v234, v234, v190
	v_add_f32_e32 v254, v232, v254
	v_exp_f32_e32 v234, v234
	v_sub_f32_e32 v235, v235, v190
	v_add_f32_e32 v254, v233, v254
	v_exp_f32_e32 v235, v235
	v_sub_f32_e32 v236, v236, v190
	v_add_f32_e32 v254, v234, v254
	v_exp_f32_e32 v236, v236
	v_sub_f32_e32 v237, v237, v190
	v_add_f32_e32 v254, v235, v254
	v_exp_f32_e32 v237, v237
	v_add_f32_e32 v254, v236, v254
	v_add_f32_e32 v254, v237, v254
	v_cvt_pk_bf16_f32 v242, v222, v223
	v_cvt_pk_bf16_f32 v243, v224, v225
	v_cvt_pk_bf16_f32 v244, v226, v227
	v_cvt_pk_bf16_f32 v245, v228, v229
	v_cvt_pk_bf16_f32 v250, v230, v231
	v_cvt_pk_bf16_f32 v251, v232, v233
	v_cvt_pk_bf16_f32 v252, v234, v235
	v_cvt_pk_bf16_f32 v253, v236, v237
	v_add_f32_e32 v203, v203, v254
	s_nop 1
	s_waitcnt lgkmcnt(8)
	v_mfma_f32_32x32x16_bf16 v[112:127], v[238:241], v[242:245], v[112:127]
	ds_read_b64_tr_b16 v[238:239], v218 offset:16640
	ds_read_b64_tr_b16 v[240:241], v218 offset:20736
	s_waitcnt lgkmcnt(8)
	v_mfma_f32_32x32x16_bf16 v[96:111], v[128:131], v[242:245], v[96:111]
	ds_read_b64_tr_b16 v[222:223], v219 offset:16640
	ds_read_b64_tr_b16 v[224:225], v219 offset:20736
	s_waitcnt lgkmcnt(8)
	v_mfma_f32_32x32x16_bf16 v[80:95], v[206:209], v[242:245], v[80:95]
	ds_read_b64_tr_b16 v[206:207], v221 offset:16640
	ds_read_b64_tr_b16 v[208:209], v221 offset:20736
	s_waitcnt lgkmcnt(8)
	v_mfma_f32_32x32x16_bf16 v[64:79], v[210:213], v[242:245], v[64:79]
	ds_read_b64_tr_b16 v[210:211], v205 offset:24576
	ds_read_b64_tr_b16 v[212:213], v205 offset:28672
	s_waitcnt lgkmcnt(8)
	v_mfma_f32_32x32x16_bf16 v[48:63], v[214:217], v[242:245], v[48:63]
	ds_read_b64_tr_b16 v[214:215], v218 offset:24576
	ds_read_b64_tr_b16 v[216:217], v218 offset:28672
	s_waitcnt lgkmcnt(8)
	v_mfma_f32_32x32x16_bf16 v[32:47], v[238:241], v[242:245], v[32:47]
	ds_read_b64_tr_b16 v[238:239], v219 offset:24576
	ds_read_b64_tr_b16 v[240:241], v219 offset:28672
	s_waitcnt lgkmcnt(8)
	v_mfma_f32_32x32x16_bf16 v[16:31], v[222:225], v[242:245], v[16:31]
	ds_read_b64_tr_b16 v[222:223], v221 offset:24576
	ds_read_b64_tr_b16 v[224:225], v221 offset:28672
	s_waitcnt lgkmcnt(8)
	v_mfma_f32_32x32x16_bf16 v[0:15], v[206:209], v[242:245], v[0:15]
	ds_read_b64_tr_b16 v[206:207], v205 offset:24832
	ds_read_b64_tr_b16 v[208:209], v205 offset:28928
	s_waitcnt lgkmcnt(8)
	v_mfma_f32_32x32x16_bf16 v[112:127], v[210:213], v[250:253], v[112:127]
	ds_read_b64_tr_b16 v[210:211], v218 offset:24832
	ds_read_b64_tr_b16 v[212:213], v218 offset:28928
	s_waitcnt lgkmcnt(8)
	v_mfma_f32_32x32x16_bf16 v[96:111], v[214:217], v[250:253], v[96:111]
	ds_read_b64_tr_b16 v[214:215], v219 offset:24832
	ds_read_b64_tr_b16 v[216:217], v219 offset:28928
	s_waitcnt lgkmcnt(8)
	v_mfma_f32_32x32x16_bf16 v[80:95], v[238:241], v[250:253], v[80:95]
	ds_read_b64_tr_b16 v[238:239], v221 offset:24832
	ds_read_b64_tr_b16 v[240:241], v221 offset:28928
	s_waitcnt lgkmcnt(8)
	v_mfma_f32_32x32x16_bf16 v[64:79], v[222:225], v[250:253], v[64:79]
	s_waitcnt lgkmcnt(6)
	v_mfma_f32_32x32x16_bf16 v[48:63], v[206:209], v[250:253], v[48:63]
	s_waitcnt lgkmcnt(4)
	v_mfma_f32_32x32x16_bf16 v[32:47], v[210:213], v[250:253], v[32:47]
	s_waitcnt lgkmcnt(2)
	v_mfma_f32_32x32x16_bf16 v[16:31], v[214:217], v[250:253], v[16:31]
	s_waitcnt lgkmcnt(0)
	v_mfma_f32_32x32x16_bf16 v[0:15], v[238:241], v[250:253], v[0:15]
	ds_read_b128 v[206:209], v195 offset:32768
	ds_read_b128 v[210:213], v196 offset:32768
	ds_read_b128 v[214:217], v197 offset:32768
	ds_read_b128 v[238:241], v198 offset:32768
	ds_read_b128 v[242:245], v199 offset:32768
	ds_read_b128 v[250:253], v200 offset:32768
	ds_read_b128 v[222:225], v201 offset:32768
	ds_read_b128 v[226:229], v202 offset:32768
	s_waitcnt vmcnt(0)
	s_add_i32 s12, s34, 1
	s_cmp_lg_u32 s34, 2
	s_cselect_b32 s34, s12, 0
	s_add_i32 s72, s72, 64
	s_add_u32 s20, s20, 0x100000
	s_addc_u32 s21, s21, 0
	s_add_i32 s73, s73, 1
	s_add_i32 s100, s72, 63
	s_cmp_le_i32 s100, s68
	s_cbranch_scc0 .Latt_latchb_6
	s_cmp_ge_u32 s73, s66
	s_cselect_b64 s[12:13], -1, 0
	v_mov_b32_e32 v204, v176
	s_barrier
	s_branch .Latt_cont_6s2
.Latt_slow_6s1:
.Latt_slot2_6:
.Latt_cont_6s2:
	v_add_u32_e32 v205, 0x8000, v205
	v_add_u32_e32 v218, 0x8000, v218
	v_add_u32_e32 v219, 0x8000, v219
	v_add_u32_e32 v221, 0x8000, v221
	s_waitcnt lgkmcnt(7)
	v_mfma_f32_32x32x16_bf16 v[128:143], v[206:209], v[144:147], 0
	ds_read_b128 v[206:209], v195 offset:40960
	s_cmp_lg_u64 s[12:13], 0
	s_cbranch_scc1 .Latt_nd0_6s2
	s_sub_i32 s100, s34, 1
	s_cmp_eq_u32 s34, 0
	s_cselect_b32 s100, 2, s100
	s_lshl_b32 s101, s100, 14
	s_add_i32 m0, s36, s101
	s_nop 0
	global_load_lds_dwordx4 v178, s[20:21]

.Latt_nr0_6s2:
	s_waitcnt lgkmcnt(3)
	v_mfma_f32_32x32x16_bf16 v[222:237], v[214:217], v[152:155], v[222:237]
	ds_read_b128 v[214:217], v201 offset:40960
	v_sub_f32_e32 v128, v128, v190
	v_exp_f32_e32 v128, v128
	v_sub_f32_e32 v129, v129, v190
	v_exp_f32_e32 v129, v129
	v_sub_f32_e32 v130, v130, v190
	s_waitcnt lgkmcnt(3)
	v_mfma_f32_32x32x16_bf16 v[222:237], v[238:241], v[156:159], v[222:237]
	ds_read_b128 v[238:241], v202 offset:40960
	v_add_f32_e32 v254, 0, v128
	v_exp_f32_e32 v130, v130
	v_sub_f32_e32 v131, v131, v190
	v_add_f32_e32 v254, v129, v254
	v_exp_f32_e32 v131, v131
	s_waitcnt lgkmcnt(3)
	v_mfma_f32_32x32x16_bf16 v[222:237], v[206:209], v[160:163], v[222:237]
	ds_read_b64_tr_b16 v[206:207], v205
	ds_read_b64_tr_b16 v[208:209], v205 offset:4096
	v_sub_f32_e32 v132, v132, v190
	v_add_f32_e32 v254, v130, v254
	v_exp_f32_e32 v132, v132
	v_sub_f32_e32 v133, v133, v190
	v_add_f32_e32 v254, v131, v254
	s_waitcnt lgkmcnt(4)
	v_mfma_f32_32x32x16_bf16 v[222:237], v[210:213], v[164:167], v[222:237]
	ds_read_b64_tr_b16 v[210:211], v218
	ds_read_b64_tr_b16 v[212:213], v218 offset:4096
	v_exp_f32_e32 v133, v133
	v_sub_f32_e32 v134, v134, v190
	v_add_f32_e32 v254, v132, v254
	v_exp_f32_e32 v134, v134
	s_waitcnt lgkmcnt(5)
	v_mfma_f32_32x32x16_bf16 v[222:237], v[214:217], v[168:171], v[222:237]
	ds_read_b64_tr_b16 v[214:215], v219
	ds_read_b64_tr_b16 v[216:217], v219 offset:4096
	v_sub_f32_e32 v135, v135, v190
	v_add_f32_e32 v254, v133, v254
	v_exp_f32_e32 v135, v135
	s_nop 0
	s_waitcnt lgkmcnt(6)
	v_mfma_f32_32x32x16_bf16 v[222:237], v[238:241], v[172:175], v[222:237]
	ds_read_b64_tr_b16 v[238:239], v221
	ds_read_b64_tr_b16 v[240:241], v221 offset:4096
	v_cvt_pk_bf16_f32 v242, v128, v129
	v_cvt_pk_bf16_f32 v243, v130, v131
	v_cvt_pk_bf16_f32 v244, v132, v133
	v_cvt_pk_bf16_f32 v245, v134, v135
	s_nop 1
	s_waitcnt lgkmcnt(6)
	v_mfma_f32_32x32x16_bf16 v[112:127], v[206:209], v[242:245], v[112:127]
	ds_read_b64_tr_b16 v[206:207], v205 offset:256
	ds_read_b64_tr_b16 v[208:209], v205 offset:4352
	v_sub_f32_e32 v136, v136, v190
	v_add_f32_e32 v254, v134, v254
	v_exp_f32_e32 v136, v136
	v_sub_f32_e32 v137, v137, v190
	v_add_f32_e32 v254, v135, v254
	s_waitcnt lgkmcnt(6)
	v_mfma_f32_32x32x16_bf16 v[96:111], v[210:213], v[242:245], v[96:111]
	ds_read_b64_tr_b16 v[210:211], v218 offset:256
	ds_read_b64_tr_b16 v[212:213], v218 offset:4352
	v_exp_f32_e32 v137, v137
	v_sub_f32_e32 v138, v138, v190
	v_add_f32_e32 v254, v136, v254
	v_exp_f32_e32 v138, v138
	v_sub_f32_e32 v139, v139, v190
	s_waitcnt lgkmcnt(6)
	v_mfma_f32_32x32x16_bf16 v[80:95], v[214:217], v[242:245], v[80:95]
	ds_read_b64_tr_b16 v[214:215], v219 offset:256
	ds_read_b64_tr_b16 v[216:217], v219 offset:4352
	v_add_f32_e32 v254, v137, v254
	v_exp_f32_e32 v139, v139
	v_sub_f32_e32 v140, v140, v190
	v_add_f32_e32 v254, v138, v254
	s_waitcnt lgkmcnt(6)
	v_mfma_f32_32x32x16_bf16 v[64:79], v[238:241], v[242:245], v[64:79]
	ds_read_b64_tr_b16 v[238:239], v221 offset:256
	ds_read_b64_tr_b16 v[240:241], v221 offset:4352
	v_exp_f32_e32 v140, v140
	v_sub_f32_e32 v141, v141, v190
	v_add_f32_e32 v254, v139, v254
	v_exp_f32_e32 v141, v141
	s_waitcnt lgkmcnt(6)
	v_mfma_f32_32x32x16_bf16 v[48:63], v[206:209], v[242:245], v[48:63]
	ds_read_b64_tr_b16 v[206:207], v205 offset:8192
	ds_read_b64_tr_b16 v[208:209], v205 offset:12288
	v_sub_f32_e32 v142, v142, v190
	v_add_f32_e32 v254, v140, v254
	v_exp_f32_e32 v142, v142
	v_sub_f32_e32 v143, v143, v190
	s_waitcnt lgkmcnt(6)
	v_mfma_f32_32x32x16_bf16 v[32:47], v[210:213], v[242:245], v[32:47]
	ds_read_b64_tr_b16 v[210:211], v218 offset:8192
	ds_read_b64_tr_b16 v[212:213], v218 offset:12288
	v_add_f32_e32 v254, v141, v254
	v_exp_f32_e32 v143, v143
	v_add_f32_e32 v254, v142, v254
	v_add_f32_e32 v254, v143, v254
	s_waitcnt lgkmcnt(6)
	v_mfma_f32_32x32x16_bf16 v[16:31], v[214:217], v[242:245], v[16:31]
	ds_read_b64_tr_b16 v[214:215], v219 offset:8192
	ds_read_b64_tr_b16 v[216:217], v219 offset:12288
	v_cvt_pk_bf16_f32 v250, v136, v137
	v_cvt_pk_bf16_f32 v251, v138, v139
	v_cvt_pk_bf16_f32 v252, v140, v141
	v_cvt_pk_bf16_f32 v253, v142, v143
	v_add_f32_e32 v203, v203, v254
	s_waitcnt lgkmcnt(6)
	v_mfma_f32_32x32x16_bf16 v[0:15], v[238:241], v[242:245], v[0:15]
	ds_read_b64_tr_b16 v[238:239], v221 offset:8192
	ds_read_b64_tr_b16 v[240:241], v221 offset:12288
	ds_read_b64_tr_b16 v[128:129], v205 offset:8448
	ds_read_b64_tr_b16 v[130:131], v205 offset:12544
	s_waitcnt lgkmcnt(8)
	v_mfma_f32_32x32x16_bf16 v[112:127], v[206:209], v[250:253], v[112:127]
	ds_read_b64_tr_b16 v[206:207], v218 offset:8448
	ds_read_b64_tr_b16 v[208:209], v218 offset:12544
	v_max3_f32 v246, v222, v223, v224
	v_max3_f32 v247, v225, v226, v227
	v_max3_f32 v246, v246, v228, v229
	v_max3_f32 v247, v247, v230, v231
	v_max3_f32 v246, v246, v232, v233
	s_waitcnt lgkmcnt(8)
	v_mfma_f32_32x32x16_bf16 v[96:111], v[210:213], v[250:253], v[96:111]
	ds_read_b64_tr_b16 v[210:211], v219 offset:8448
	ds_read_b64_tr_b16 v[212:213], v219 offset:12544
	v_max3_f32 v247, v247, v234, v235
	v_max3_f32 v246, v246, v236, v237
	v_max_f32_e32 v246, v246, v247
	v_mov_b32_e32 v247, v246
	v_add_f32_e32 v249, 0x41000000, v190
	s_waitcnt lgkmcnt(8)
	v_mfma_f32_32x32x16_bf16 v[80:95], v[214:217], v[250:253], v[80:95]
	ds_read_b64_tr_b16 v[214:215], v221 offset:8448
	ds_read_b64_tr_b16 v[216:217], v221 offset:12544
	s_nop 1
	v_permlane32_swap_b32_e32 v246, v247
	v_max_f32_e32 v246, v246, v247
	v_cmp_gt_f32_e32 vcc, v246, v249
	s_cbranch_vccnz .Latt_rs1_6s2
	s_waitcnt lgkmcnt(8)
	v_mfma_f32_32x32x16_bf16 v[64:79], v[238:241], v[250:253], v[64:79]
	ds_read_b64_tr_b16 v[238:239], v205 offset:16384
	ds_read_b64_tr_b16 v[240:241], v205 offset:20480
	v_sub_f32_e32 v222, v222, v190
	v_exp_f32_e32 v222, v222
	v_sub_f32_e32 v223, v223, v190
	v_exp_f32_e32 v223, v223
	v_sub_f32_e32 v224, v224, v190
	v_add_f32_e32 v254, 0, v222
	s_waitcnt lgkmcnt(8)
	v_mfma_f32_32x32x16_bf16 v[48:63], v[128:131], v[250:253], v[48:63]
	ds_read_b64_tr_b16 v[128:129], v218 offset:16384
	ds_read_b64_tr_b16 v[130:131], v218 offset:20480
	v_exp_f32_e32 v224, v224
	v_sub_f32_e32 v225, v225, v190
	v_add_f32_e32 v254, v223, v254
	v_exp_f32_e32 v225, v225
	v_sub_f32_e32 v226, v226, v190
	v_add_f32_e32 v254, v224, v254
	s_waitcnt lgkmcnt(8)
	v_mfma_f32_32x32x16_bf16 v[32:47], v[206:209], v[250:253], v[32:47]
	ds_read_b64_tr_b16 v[206:207], v219 offset:16384
	ds_read_b64_tr_b16 v[208:209], v219 offset:20480
	v_exp_f32_e32 v226, v226
	v_sub_f32_e32 v227, v227, v190
	v_add_f32_e32 v254, v225, v254
	v_exp_f32_e32 v227, v227
	v_sub_f32_e32 v228, v228, v190
	s_waitcnt lgkmcnt(8)
	v_mfma_f32_32x32x16_bf16 v[16:31], v[210:213], v[250:253], v[16:31]
	ds_read_b64_tr_b16 v[210:211], v221 offset:16384
	ds_read_b64_tr_b16 v[212:213], v221 offset:20480
	v_add_f32_e32 v254, v226, v254
	v_exp_f32_e32 v228, v228
	v_sub_f32_e32 v229, v229, v190
	v_add_f32_e32 v254, v227, v254
	v_exp_f32_e32 v229, v229
	s_waitcnt lgkmcnt(8)
	v_mfma_f32_32x32x16_bf16 v[0:15], v[214:217], v[250:253], v[0:15]
	ds_read_b64_tr_b16 v[214:215], v205 offset:16640
	ds_read_b64_tr_b16 v[216:217], v205 offset:20736
	s_nop 0
	v_cvt_pk_bf16_f32 v242, v222, v223
	v_cvt_pk_bf16_f32 v243, v224, v225
	v_cvt_pk_bf16_f32 v244, v226, v227
	v_cvt_pk_bf16_f32 v245, v228, v229
	s_nop 1
	s_waitcnt lgkmcnt(8)
	v_mfma_f32_32x32x16_bf16 v[112:127], v[238:241], v[242:245], v[112:127]
	ds_read_b64_tr_b16 v[238:239], v218 offset:16640
	ds_read_b64_tr_b16 v[240:241], v218 offset:20736
	v_sub_f32_e32 v230, v230, v190
	v_add_f32_e32 v254, v228, v254
	v_exp_f32_e32 v230, v230
	v_sub_f32_e32 v231, v231, v190
	v_add_f32_e32 v254, v229, v254
	s_waitcnt lgkmcnt(8)
	v_mfma_f32_32x32x16_bf16 v[96:111], v[128:131], v[242:245], v[96:111]
	ds_read_b64_tr_b16 v[128:129], v219 offset:16640
	ds_read_b64_tr_b16 v[130:131], v219 offset:20736
	v_exp_f32_e32 v231, v231
	v_sub_f32_e32 v232, v232, v190
	v_add_f32_e32 v254, v230, v254
	v_exp_f32_e32 v232, v232
	v_sub_f32_e32 v233, v233, v190
	s_waitcnt lgkmcnt(8)
	v_mfma_f32_32x32x16_bf16 v[80:95], v[206:209], v[242:245], v[80:95]
	ds_read_b64_tr_b16 v[206:207], v221 offset:16640
	ds_read_b64_tr_b16 v[208:209], v221 offset:20736
	v_add_f32_e32 v254, v231, v254
	v_exp_f32_e32 v233, v233
	v_sub_f32_e32 v234, v234, v190
	v_add_f32_e32 v254, v232, v254
	s_waitcnt lgkmcnt(8)
	v_mfma_f32_32x32x16_bf16 v[64:79], v[210:213], v[242:245], v[64:79]
	ds_read_b64_tr_b16 v[210:211], v205 offset:24576
	ds_read_b64_tr_b16 v[212:213], v205 offset:28672
	v_exp_f32_e32 v234, v234
	v_sub_f32_e32 v235, v235, v190
	v_add_f32_e32 v254, v233, v254
	v_exp_f32_e32 v235, v235
	s_waitcnt lgkmcnt(8)
	v_mfma_f32_32x32x16_bf16 v[48:63], v[214:217], v[242:245], v[48:63]
	ds_read_b64_tr_b16 v[214:215], v218 offset:24576
	ds_read_b64_tr_b16 v[216:217], v218 offset:28672
	v_sub_f32_e32 v236, v236, v190
	v_add_f32_e32 v254, v234, v254
	v_exp_f32_e32 v236, v236
	v_sub_f32_e32 v237, v237, v190
	s_waitcnt lgkmcnt(8)
	v_mfma_f32_32x32x16_bf16 v[32:47], v[238:241], v[242:245], v[32:47]
	ds_read_b64_tr_b16 v[238:239], v219 offset:24576
	ds_read_b64_tr_b16 v[240:241], v219 offset:28672
	v_add_f32_e32 v254, v235, v254
	v_exp_f32_e32 v237, v237
	v_add_f32_e32 v254, v236, v254
	v_add_f32_e32 v254, v237, v254
	s_waitcnt lgkmcnt(8)
	v_mfma_f32_32x32x16_bf16 v[16:31], v[128:131], v[242:245], v[16:31]
	ds_read_b64_tr_b16 v[128:129], v221 offset:24576
	ds_read_b64_tr_b16 v[130:131], v221 offset:28672
	v_cvt_pk_bf16_f32 v250, v230, v231
	v_cvt_pk_bf16_f32 v251, v232, v233
	v_cvt_pk_bf16_f32 v252, v234, v235
	v_cvt_pk_bf16_f32 v253, v236, v237
	v_add_f32_e32 v203, v203, v254
	s_waitcnt lgkmcnt(8)
	v_mfma_f32_32x32x16_bf16 v[0:15], v[206:209], v[242:245], v[0:15]
	ds_read_b64_tr_b16 v[206:207], v205 offset:24832
	ds_read_b64_tr_b16 v[208:209], v205 offset:28928
	s_waitcnt lgkmcnt(8)
	v_mfma_f32_32x32x16_bf16 v[112:127], v[210:213], v[250:253], v[112:127]
	ds_read_b64_tr_b16 v[210:211], v218 offset:24832
	ds_read_b64_tr_b16 v[212:213], v218 offset:28928
	s_waitcnt lgkmcnt(8)
	v_mfma_f32_32x32x16_bf16 v[96:111], v[214:217], v[250:253], v[96:111]
	ds_read_b64_tr_b16 v[214:215], v219 offset:24832
	ds_read_b64_tr_b16 v[216:217], v219 offset:28928
	s_waitcnt lgkmcnt(8)
	v_mfma_f32_32x32x16_bf16 v[80:95], v[238:241], v[250:253], v[80:95]
	ds_read_b64_tr_b16 v[238:239], v221 offset:24832
	ds_read_b64_tr_b16 v[240:241], v221 offset:28928
	s_waitcnt lgkmcnt(8)
	v_mfma_f32_32x32x16_bf16 v[64:79], v[128:131], v[250:253], v[64:79]
	s_waitcnt lgkmcnt(6)
	v_mfma_f32_32x32x16_bf16 v[48:63], v[206:209], v[250:253], v[48:63]
	s_waitcnt lgkmcnt(4)
	v_mfma_f32_32x32x16_bf16 v[32:47], v[210:213], v[250:253], v[32:47]
	s_waitcnt lgkmcnt(2)
	v_mfma_f32_32x32x16_bf16 v[16:31], v[214:217], v[250:253], v[16:31]
	s_waitcnt lgkmcnt(0)
	v_mfma_f32_32x32x16_bf16 v[0:15], v[238:241], v[250:253], v[0:15]
	ds_read_b128 v[206:209], v195
	ds_read_b128 v[210:213], v196
	ds_read_b128 v[214:217], v197
	ds_read_b128 v[238:241], v198
	ds_read_b128 v[242:245], v199
	ds_read_b128 v[250:253], v200
	ds_read_b128 v[222:225], v201
	ds_read_b128 v[226:229], v202
	s_waitcnt vmcnt(0)
	s_add_i32 s12, s34, 1
	s_cmp_lg_u32 s34, 2
	s_cselect_b32 s34, s12, 0
	s_add_i32 s72, s72, 64
	s_add_u32 s20, s20, 0x100000
	s_addc_u32 s21, s21, 0
	s_add_i32 s73, s73, 1
	s_add_i32 s100, s72, 63
	s_cmp_le_i32 s100, s68
	s_cbranch_scc0 .Latt_latchb_6
	s_cmp_ge_u32 s73, s66
	s_cselect_b64 s[12:13], -1, 0
	v_mov_b32_e32 v204, v176
	s_barrier
	s_branch .Latt_cont_6s0
.Latt_rs1_6s2:
	s_waitcnt lgkmcnt(8)
	v_mfma_f32_32x32x16_bf16 v[64:79], v[238:241], v[250:253], v[64:79]
	ds_read_b64_tr_b16 v[238:239], v205 offset:16384
	ds_read_b64_tr_b16 v[240:241], v205 offset:20480
	s_waitcnt lgkmcnt(8)
	v_mfma_f32_32x32x16_bf16 v[48:63], v[128:131], v[250:253], v[48:63]
	ds_read_b64_tr_b16 v[128:129], v218 offset:16384
	ds_read_b64_tr_b16 v[130:131], v218 offset:20480
	s_waitcnt lgkmcnt(8)
	v_mfma_f32_32x32x16_bf16 v[32:47], v[206:209], v[250:253], v[32:47]
	ds_read_b64_tr_b16 v[206:207], v219 offset:16384
	ds_read_b64_tr_b16 v[208:209], v219 offset:20480
	s_waitcnt lgkmcnt(8)
	v_mfma_f32_32x32x16_bf16 v[16:31], v[210:213], v[250:253], v[16:31]
	ds_read_b64_tr_b16 v[210:211], v221 offset:16384
	ds_read_b64_tr_b16 v[212:213], v221 offset:20480
	s_waitcnt lgkmcnt(8)
	v_mfma_f32_32x32x16_bf16 v[0:15], v[214:217], v[250:253], v[0:15]
	ds_read_b64_tr_b16 v[214:215], v205 offset:16640
	ds_read_b64_tr_b16 v[216:217], v205 offset:20736
	s_nop 11
	v_max_f32_e32 v246, v190, v246
	v_sub_f32_e32 v190, v190, v246
	v_exp_f32_e32 v190, v190
	s_nop 0
	v_pk_mul_f32 v[126:127], v[126:127], v[190:191] op_sel_hi:[1,0]
	v_pk_mul_f32 v[124:125], v[124:125], v[190:191] op_sel_hi:[1,0]
	v_pk_mul_f32 v[122:123], v[122:123], v[190:191] op_sel_hi:[1,0]
	v_pk_mul_f32 v[120:121], v[120:121], v[190:191] op_sel_hi:[1,0]
	v_pk_mul_f32 v[118:119], v[118:119], v[190:191] op_sel_hi:[1,0]
	v_pk_mul_f32 v[116:117], v[116:117], v[190:191] op_sel_hi:[1,0]
	v_pk_mul_f32 v[114:115], v[114:115], v[190:191] op_sel_hi:[1,0]
	v_pk_mul_f32 v[112:113], v[112:113], v[190:191] op_sel_hi:[1,0]
	v_pk_mul_f32 v[110:111], v[110:111], v[190:191] op_sel_hi:[1,0]
	v_pk_mul_f32 v[108:109], v[108:109], v[190:191] op_sel_hi:[1,0]
	v_pk_mul_f32 v[106:107], v[106:107], v[190:191] op_sel_hi:[1,0]
	v_pk_mul_f32 v[104:105], v[104:105], v[190:191] op_sel_hi:[1,0]
	v_pk_mul_f32 v[102:103], v[102:103], v[190:191] op_sel_hi:[1,0]
	v_pk_mul_f32 v[100:101], v[100:101], v[190:191] op_sel_hi:[1,0]
	v_pk_mul_f32 v[98:99], v[98:99], v[190:191] op_sel_hi:[1,0]
	v_pk_mul_f32 v[96:97], v[96:97], v[190:191] op_sel_hi:[1,0]
	v_pk_mul_f32 v[94:95], v[94:95], v[190:191] op_sel_hi:[1,0]
	v_pk_mul_f32 v[92:93], v[92:93], v[190:191] op_sel_hi:[1,0]
	v_pk_mul_f32 v[90:91], v[90:91], v[190:191] op_sel_hi:[1,0]
	v_pk_mul_f32 v[88:89], v[88:89], v[190:191] op_sel_hi:[1,0]
	v_pk_mul_f32 v[86:87], v[86:87], v[190:191] op_sel_hi:[1,0]
	v_pk_mul_f32 v[84:85], v[84:85], v[190:191] op_sel_hi:[1,0]
	v_pk_mul_f32 v[82:83], v[82:83], v[190:191] op_sel_hi:[1,0]
	v_pk_mul_f32 v[80:81], v[80:81], v[190:191] op_sel_hi:[1,0]
	v_pk_mul_f32 v[78:79], v[78:79], v[190:191] op_sel_hi:[1,0]
	v_pk_mul_f32 v[76:77], v[76:77], v[190:191] op_sel_hi:[1,0]
	v_pk_mul_f32 v[74:75], v[74:75], v[190:191] op_sel_hi:[1,0]
	v_pk_mul_f32 v[72:73], v[72:73], v[190:191] op_sel_hi:[1,0]
	v_pk_mul_f32 v[70:71], v[70:71], v[190:191] op_sel_hi:[1,0]
	v_pk_mul_f32 v[68:69], v[68:69], v[190:191] op_sel_hi:[1,0]
	v_pk_mul_f32 v[66:67], v[66:67], v[190:191] op_sel_hi:[1,0]
	v_pk_mul_f32 v[64:65], v[64:65], v[190:191] op_sel_hi:[1,0]
	v_pk_mul_f32 v[62:63], v[62:63], v[190:191] op_sel_hi:[1,0]
	v_pk_mul_f32 v[60:61], v[60:61], v[190:191] op_sel_hi:[1,0]
	v_pk_mul_f32 v[58:59], v[58:59], v[190:191] op_sel_hi:[1,0]
	v_pk_mul_f32 v[56:57], v[56:57], v[190:191] op_sel_hi:[1,0]
	v_pk_mul_f32 v[54:55], v[54:55], v[190:191] op_sel_hi:[1,0]
	v_pk_mul_f32 v[52:53], v[52:53], v[190:191] op_sel_hi:[1,0]
	v_pk_mul_f32 v[50:51], v[50:51], v[190:191] op_sel_hi:[1,0]
	v_pk_mul_f32 v[48:49], v[48:49], v[190:191] op_sel_hi:[1,0]
	v_pk_mul_f32 v[46:47], v[46:47], v[190:191] op_sel_hi:[1,0]
	v_pk_mul_f32 v[44:45], v[44:45], v[190:191] op_sel_hi:[1,0]
	v_pk_mul_f32 v[42:43], v[42:43], v[190:191] op_sel_hi:[1,0]
	v_pk_mul_f32 v[40:41], v[40:41], v[190:191] op_sel_hi:[1,0]
	v_pk_mul_f32 v[38:39], v[38:39], v[190:191] op_sel_hi:[1,0]
	v_pk_mul_f32 v[36:37], v[36:37], v[190:191] op_sel_hi:[1,0]
	v_pk_mul_f32 v[34:35], v[34:35], v[190:191] op_sel_hi:[1,0]
	v_pk_mul_f32 v[32:33], v[32:33], v[190:191] op_sel_hi:[1,0]
	v_pk_mul_f32 v[30:31], v[30:31], v[190:191] op_sel_hi:[1,0]
	v_pk_mul_f32 v[28:29], v[28:29], v[190:191] op_sel_hi:[1,0]
	v_pk_mul_f32 v[26:27], v[26:27], v[190:191] op_sel_hi:[1,0]
	v_pk_mul_f32 v[24:25], v[24:25], v[190:191] op_sel_hi:[1,0]
	v_pk_mul_f32 v[22:23], v[22:23], v[190:191] op_sel_hi:[1,0]
	v_pk_mul_f32 v[20:21], v[20:21], v[190:191] op_sel_hi:[1,0]
	v_pk_mul_f32 v[18:19], v[18:19], v[190:191] op_sel_hi:[1,0]
	v_pk_mul_f32 v[16:17], v[16:17], v[190:191] op_sel_hi:[1,0]
	v_pk_mul_f32 v[14:15], v[14:15], v[190:191] op_sel_hi:[1,0]
	v_pk_mul_f32 v[12:13], v[12:13], v[190:191] op_sel_hi:[1,0]
	v_pk_mul_f32 v[10:11], v[10:11], v[190:191] op_sel_hi:[1,0]
	v_pk_mul_f32 v[8:9], v[8:9], v[190:191] op_sel_hi:[1,0]
	v_pk_mul_f32 v[6:7], v[6:7], v[190:191] op_sel_hi:[1,0]
	v_pk_mul_f32 v[4:5], v[4:5], v[190:191] op_sel_hi:[1,0]
	v_pk_mul_f32 v[2:3], v[2:3], v[190:191] op_sel_hi:[1,0]
	v_pk_mul_f32 v[0:1], v[0:1], v[190:191] op_sel_hi:[1,0]
	v_mul_f32_e32 v203, v203, v190
	v_mov_b32_e32 v190, v246
	v_sub_f32_e32 v222, v222, v190
	v_exp_f32_e32 v222, v222
	v_sub_f32_e32 v223, v223, v190
	v_exp_f32_e32 v223, v223
	v_sub_f32_e32 v224, v224, v190
	v_add_f32_e32 v254, 0, v222
	v_exp_f32_e32 v224, v224
	v_sub_f32_e32 v225, v225, v190
	v_add_f32_e32 v254, v223, v254
	v_exp_f32_e32 v225, v225
	v_sub_f32_e32 v226, v226, v190
	v_add_f32_e32 v254, v224, v254
	v_exp_f32_e32 v226, v226
	v_sub_f32_e32 v227, v227, v190
	v_add_f32_e32 v254, v225, v254
	v_exp_f32_e32 v227, v227
	v_sub_f32_e32 v228, v228, v190
	v_add_f32_e32 v254, v226, v254
	v_exp_f32_e32 v228, v228
	v_sub_f32_e32 v229, v229, v190
	v_add_f32_e32 v254, v227, v254
	v_exp_f32_e32 v229, v229
	v_sub_f32_e32 v230, v230, v190
	v_add_f32_e32 v254, v228, v254
	v_exp_f32_e32 v230, v230
	v_sub_f32_e32 v231, v231, v190
	v_add_f32_e32 v254, v229, v254
	v_exp_f32_e32 v231, v231
	v_sub_f32_e32 v232, v232, v190
	v_add_f32_e32 v254, v230, v254
	v_exp_f32_e32 v232, v232
	v_sub_f32_e32 v233, v233, v190
	v_add_f32_e32 v254, v231, v254
	v_exp_f32_e32 v233, v233
	v_sub_f32_e32 v234, v234, v190
	v_add_f32_e32 v254, v232, v254
	v_exp_f32_e32 v234, v234
	v_sub_f32_e32 v235, v235, v190
	v_add_f32_e32 v254, v233, v254
	v_exp_f32_e32 v235, v235
	v_sub_f32_e32 v236, v236, v190
	v_add_f32_e32 v254, v234, v254
	v_exp_f32_e32 v236, v236
	v_sub_f32_e32 v237, v237, v190
	v_add_f32_e32 v254, v235, v254
	v_exp_f32_e32 v237, v237
	v_add_f32_e32 v254, v236, v254
	v_add_f32_e32 v254, v237, v254
	v_cvt_pk_bf16_f32 v242, v222, v223
	v_cvt_pk_bf16_f32 v243, v224, v225
	v_cvt_pk_bf16_f32 v244, v226, v227
	v_cvt_pk_bf16_f32 v245, v228, v229
	v_cvt_pk_bf16_f32 v250, v230, v231
	v_cvt_pk_bf16_f32 v251, v232, v233
	v_cvt_pk_bf16_f32 v252, v234, v235
	v_cvt_pk_bf16_f32 v253, v236, v237
	v_add_f32_e32 v203, v203, v254
	s_nop 1
	s_waitcnt lgkmcnt(8)
	v_mfma_f32_32x32x16_bf16 v[112:127], v[238:241], v[242:245], v[112:127]
	ds_read_b64_tr_b16 v[238:239], v218 offset:16640
	ds_read_b64_tr_b16 v[240:241], v218 offset:20736
	s_waitcnt lgkmcnt(8)
	v_mfma_f32_32x32x16_bf16 v[96:111], v[128:131], v[242:245], v[96:111]
	ds_read_b64_tr_b16 v[222:223], v219 offset:16640
	ds_read_b64_tr_b16 v[224:225], v219 offset:20736
	s_waitcnt lgkmcnt(8)
	v_mfma_f32_32x32x16_bf16 v[80:95], v[206:209], v[242:245], v[80:95]
	ds_read_b64_tr_b16 v[206:207], v221 offset:16640
	ds_read_b64_tr_b16 v[208:209], v221 offset:20736
	s_waitcnt lgkmcnt(8)
	v_mfma_f32_32x32x16_bf16 v[64:79], v[210:213], v[242:245], v[64:79]
	ds_read_b64_tr_b16 v[210:211], v205 offset:24576
	ds_read_b64_tr_b16 v[212:213], v205 offset:28672
	s_waitcnt lgkmcnt(8)
	v_mfma_f32_32x32x16_bf16 v[48:63], v[214:217], v[242:245], v[48:63]
	ds_read_b64_tr_b16 v[214:215], v218 offset:24576
	ds_read_b64_tr_b16 v[216:217], v218 offset:28672
	s_waitcnt lgkmcnt(8)
	v_mfma_f32_32x32x16_bf16 v[32:47], v[238:241], v[242:245], v[32:47]
	ds_read_b64_tr_b16 v[238:239], v219 offset:24576
	ds_read_b64_tr_b16 v[240:241], v219 offset:28672
	s_waitcnt lgkmcnt(8)
	v_mfma_f32_32x32x16_bf16 v[16:31], v[222:225], v[242:245], v[16:31]
	ds_read_b64_tr_b16 v[222:223], v221 offset:24576
	ds_read_b64_tr_b16 v[224:225], v221 offset:28672
	s_waitcnt lgkmcnt(8)
	v_mfma_f32_32x32x16_bf16 v[0:15], v[206:209], v[242:245], v[0:15]
	ds_read_b64_tr_b16 v[206:207], v205 offset:24832
	ds_read_b64_tr_b16 v[208:209], v205 offset:28928
	s_waitcnt lgkmcnt(8)
	v_mfma_f32_32x32x16_bf16 v[112:127], v[210:213], v[250:253], v[112:127]
	ds_read_b64_tr_b16 v[210:211], v218 offset:24832
	ds_read_b64_tr_b16 v[212:213], v218 offset:28928
	s_waitcnt lgkmcnt(8)
	v_mfma_f32_32x32x16_bf16 v[96:111], v[214:217], v[250:253], v[96:111]
	ds_read_b64_tr_b16 v[214:215], v219 offset:24832
	ds_read_b64_tr_b16 v[216:217], v219 offset:28928
	s_waitcnt lgkmcnt(8)
	v_mfma_f32_32x32x16_bf16 v[80:95], v[238:241], v[250:253], v[80:95]
	ds_read_b64_tr_b16 v[238:239], v221 offset:24832
	ds_read_b64_tr_b16 v[240:241], v221 offset:28928
	s_waitcnt lgkmcnt(8)
	v_mfma_f32_32x32x16_bf16 v[64:79], v[222:225], v[250:253], v[64:79]
	s_waitcnt lgkmcnt(6)
	v_mfma_f32_32x32x16_bf16 v[48:63], v[206:209], v[250:253], v[48:63]
	s_waitcnt lgkmcnt(4)
	v_mfma_f32_32x32x16_bf16 v[32:47], v[210:213], v[250:253], v[32:47]
	s_waitcnt lgkmcnt(2)
	v_mfma_f32_32x32x16_bf16 v[16:31], v[214:217], v[250:253], v[16:31]
	s_waitcnt lgkmcnt(0)
	v_mfma_f32_32x32x16_bf16 v[0:15], v[238:241], v[250:253], v[0:15]
	ds_read_b128 v[206:209], v195
	ds_read_b128 v[210:213], v196
	ds_read_b128 v[214:217], v197
	ds_read_b128 v[238:241], v198
	ds_read_b128 v[242:245], v199
	ds_read_b128 v[250:253], v200
	ds_read_b128 v[222:225], v201
	ds_read_b128 v[226:229], v202
	s_waitcnt vmcnt(0)
	s_add_i32 s12, s34, 1
	s_cmp_lg_u32 s34, 2
	s_cselect_b32 s34, s12, 0
	s_add_i32 s72, s72, 64
	s_add_u32 s20, s20, 0x100000
	s_addc_u32 s21, s21, 0
	s_add_i32 s73, s73, 1
	s_add_i32 s100, s72, 63
	s_cmp_le_i32 s100, s68
	s_cbranch_scc0 .Latt_latchb_6
	s_cmp_ge_u32 s73, s66
	s_cselect_b64 s[12:13], -1, 0
	v_mov_b32_e32 v204, v176
	s_barrier
	s_branch .Latt_cont_6s0

.Latt_latchb_7:
	s_waitcnt lgkmcnt(0)
	s_cmp_lg_u32 s67, s14
	s_barrier
	s_cbranch_scc0 .LBB0_1796

.Latt_nr0_7s0:
	s_waitcnt lgkmcnt(3)
	v_mfma_f32_32x32x16_bf16 v[222:237], v[214:217], v[152:155], v[222:237]
	ds_read_b128 v[214:217], v202 offset:8192
	v_sub_f32_e32 v128, v128, v190
	v_exp_f32_e32 v128, v128
	v_sub_f32_e32 v129, v129, v190
	v_exp_f32_e32 v129, v129
	v_sub_f32_e32 v130, v130, v190
	s_waitcnt lgkmcnt(3)
	v_mfma_f32_32x32x16_bf16 v[222:237], v[238:241], v[156:159], v[222:237]
	ds_read_b128 v[238:241], v203 offset:8192
	v_add_f32_e32 v254, 0, v128
	v_exp_f32_e32 v130, v130
	v_sub_f32_e32 v131, v131, v190
	v_add_f32_e32 v254, v129, v254
	v_exp_f32_e32 v131, v131
	s_waitcnt lgkmcnt(3)
	v_mfma_f32_32x32x16_bf16 v[222:237], v[206:209], v[160:163], v[222:237]
	ds_read_b64_tr_b16 v[206:207], v205
	ds_read_b64_tr_b16 v[208:209], v205 offset:4096
	v_sub_f32_e32 v132, v132, v190
	v_add_f32_e32 v254, v130, v254
	v_exp_f32_e32 v132, v132
	v_sub_f32_e32 v133, v133, v190
	v_add_f32_e32 v254, v131, v254
	s_waitcnt lgkmcnt(4)
	v_mfma_f32_32x32x16_bf16 v[222:237], v[210:213], v[164:167], v[222:237]
	ds_read_b64_tr_b16 v[210:211], v218
	ds_read_b64_tr_b16 v[212:213], v218 offset:4096
	v_exp_f32_e32 v133, v133
	v_sub_f32_e32 v134, v134, v190
	v_add_f32_e32 v254, v132, v254
	v_exp_f32_e32 v134, v134
	s_waitcnt lgkmcnt(5)
	v_mfma_f32_32x32x16_bf16 v[222:237], v[214:217], v[168:171], v[222:237]
	ds_read_b64_tr_b16 v[214:215], v219
	ds_read_b64_tr_b16 v[216:217], v219 offset:4096
	v_sub_f32_e32 v135, v135, v190
	v_add_f32_e32 v254, v133, v254
	v_exp_f32_e32 v135, v135
	s_nop 0
	s_waitcnt lgkmcnt(6)
	v_mfma_f32_32x32x16_bf16 v[222:237], v[238:241], v[172:175], v[222:237]
	ds_read_b64_tr_b16 v[238:239], v221
	ds_read_b64_tr_b16 v[240:241], v221 offset:4096
	v_cvt_pk_bf16_f32 v242, v128, v129
	v_cvt_pk_bf16_f32 v243, v130, v131
	v_cvt_pk_bf16_f32 v244, v132, v133
	v_cvt_pk_bf16_f32 v245, v134, v135
	s_nop 1
	s_waitcnt lgkmcnt(6)
	v_mfma_f32_32x32x16_bf16 v[112:127], v[206:209], v[242:245], v[112:127]
	ds_read_b64_tr_b16 v[206:207], v205 offset:256
	ds_read_b64_tr_b16 v[208:209], v205 offset:4352
	v_sub_f32_e32 v136, v136, v190
	v_add_f32_e32 v254, v134, v254
	v_exp_f32_e32 v136, v136
	v_sub_f32_e32 v137, v137, v190
	v_add_f32_e32 v254, v135, v254
	s_waitcnt lgkmcnt(6)
	v_mfma_f32_32x32x16_bf16 v[96:111], v[210:213], v[242:245], v[96:111]
	ds_read_b64_tr_b16 v[210:211], v218 offset:256
	ds_read_b64_tr_b16 v[212:213], v218 offset:4352
	v_exp_f32_e32 v137, v137
	v_sub_f32_e32 v138, v138, v190
	v_add_f32_e32 v254, v136, v254
	v_exp_f32_e32 v138, v138
	v_sub_f32_e32 v139, v139, v190
	s_waitcnt lgkmcnt(6)
	v_mfma_f32_32x32x16_bf16 v[80:95], v[214:217], v[242:245], v[80:95]
	ds_read_b64_tr_b16 v[214:215], v219 offset:256
	ds_read_b64_tr_b16 v[216:217], v219 offset:4352
	v_add_f32_e32 v254, v137, v254
	v_exp_f32_e32 v139, v139
	v_sub_f32_e32 v140, v140, v190
	v_add_f32_e32 v254, v138, v254
	s_waitcnt lgkmcnt(6)
	v_mfma_f32_32x32x16_bf16 v[64:79], v[238:241], v[242:245], v[64:79]
	ds_read_b64_tr_b16 v[238:239], v221 offset:256
	ds_read_b64_tr_b16 v[240:241], v221 offset:4352
	v_exp_f32_e32 v140, v140
	v_sub_f32_e32 v141, v141, v190
	v_add_f32_e32 v254, v139, v254
	v_exp_f32_e32 v141, v141
	s_waitcnt lgkmcnt(6)
	v_mfma_f32_32x32x16_bf16 v[48:63], v[206:209], v[242:245], v[48:63]
	ds_read_b64_tr_b16 v[206:207], v205 offset:8192
	ds_read_b64_tr_b16 v[208:209], v205 offset:12288
	v_sub_f32_e32 v142, v142, v190
	v_add_f32_e32 v254, v140, v254
	v_exp_f32_e32 v142, v142
	v_sub_f32_e32 v143, v143, v190
	s_waitcnt lgkmcnt(6)
	v_mfma_f32_32x32x16_bf16 v[32:47], v[210:213], v[242:245], v[32:47]
	ds_read_b64_tr_b16 v[210:211], v218 offset:8192
	ds_read_b64_tr_b16 v[212:213], v218 offset:12288
	v_add_f32_e32 v254, v141, v254
	v_exp_f32_e32 v143, v143
	v_add_f32_e32 v254, v142, v254
	v_add_f32_e32 v254, v143, v254
	s_waitcnt lgkmcnt(6)
	v_mfma_f32_32x32x16_bf16 v[16:31], v[214:217], v[242:245], v[16:31]
	ds_read_b64_tr_b16 v[214:215], v219 offset:8192
	ds_read_b64_tr_b16 v[216:217], v219 offset:12288
	v_cvt_pk_bf16_f32 v250, v136, v137
	v_cvt_pk_bf16_f32 v251, v138, v139
	v_cvt_pk_bf16_f32 v252, v140, v141
	v_cvt_pk_bf16_f32 v253, v142, v143
	v_add_f32_e32 v195, v195, v254
	s_waitcnt lgkmcnt(6)
	v_mfma_f32_32x32x16_bf16 v[0:15], v[238:241], v[242:245], v[0:15]
	ds_read_b64_tr_b16 v[238:239], v221 offset:8192
	ds_read_b64_tr_b16 v[240:241], v221 offset:12288
	ds_read_b64_tr_b16 v[128:129], v205 offset:8448
	ds_read_b64_tr_b16 v[130:131], v205 offset:12544
	s_waitcnt lgkmcnt(8)
	v_mfma_f32_32x32x16_bf16 v[112:127], v[206:209], v[250:253], v[112:127]
	ds_read_b64_tr_b16 v[206:207], v218 offset:8448
	ds_read_b64_tr_b16 v[208:209], v218 offset:12544
	v_max3_f32 v246, v222, v223, v224
	v_max3_f32 v247, v225, v226, v227
	v_max3_f32 v246, v246, v228, v229
	v_max3_f32 v247, v247, v230, v231
	v_max3_f32 v246, v246, v232, v233
	s_waitcnt lgkmcnt(8)
	v_mfma_f32_32x32x16_bf16 v[96:111], v[210:213], v[250:253], v[96:111]
	ds_read_b64_tr_b16 v[210:211], v219 offset:8448
	ds_read_b64_tr_b16 v[212:213], v219 offset:12544
	v_max3_f32 v247, v247, v234, v235
	v_max3_f32 v246, v246, v236, v237
	v_max_f32_e32 v246, v246, v247
	v_mov_b32_e32 v247, v246
	v_add_f32_e32 v249, 0x41000000, v190
	s_waitcnt lgkmcnt(8)
	v_mfma_f32_32x32x16_bf16 v[80:95], v[214:217], v[250:253], v[80:95]
	ds_read_b64_tr_b16 v[214:215], v221 offset:8448
	ds_read_b64_tr_b16 v[216:217], v221 offset:12544
	s_nop 1
	v_permlane32_swap_b32_e32 v246, v247
	v_max_f32_e32 v246, v246, v247
	v_cmp_gt_f32_e32 vcc, v246, v249
	s_cbranch_vccnz .Latt_rs1_7s0
	s_waitcnt lgkmcnt(8)
	v_mfma_f32_32x32x16_bf16 v[64:79], v[238:241], v[250:253], v[64:79]
	ds_read_b64_tr_b16 v[238:239], v205 offset:16384
	ds_read_b64_tr_b16 v[240:241], v205 offset:20480
	v_sub_f32_e32 v222, v222, v190
	v_exp_f32_e32 v222, v222
	v_sub_f32_e32 v223, v223, v190
	v_exp_f32_e32 v223, v223
	v_sub_f32_e32 v224, v224, v190
	v_add_f32_e32 v254, 0, v222
	s_waitcnt lgkmcnt(8)
	v_mfma_f32_32x32x16_bf16 v[48:63], v[128:131], v[250:253], v[48:63]
	ds_read_b64_tr_b16 v[128:129], v218 offset:16384
	ds_read_b64_tr_b16 v[130:131], v218 offset:20480
	v_exp_f32_e32 v224, v224
	v_sub_f32_e32 v225, v225, v190
	v_add_f32_e32 v254, v223, v254
	v_exp_f32_e32 v225, v225
	v_sub_f32_e32 v226, v226, v190
	v_add_f32_e32 v254, v224, v254
	s_waitcnt lgkmcnt(8)
	v_mfma_f32_32x32x16_bf16 v[32:47], v[206:209], v[250:253], v[32:47]
	ds_read_b64_tr_b16 v[206:207], v219 offset:16384
	ds_read_b64_tr_b16 v[208:209], v219 offset:20480
	v_exp_f32_e32 v226, v226
	v_sub_f32_e32 v227, v227, v190
	v_add_f32_e32 v254, v225, v254
	v_exp_f32_e32 v227, v227
	v_sub_f32_e32 v228, v228, v190
	s_waitcnt lgkmcnt(8)
	v_mfma_f32_32x32x16_bf16 v[16:31], v[210:213], v[250:253], v[16:31]
	ds_read_b64_tr_b16 v[210:211], v221 offset:16384
	ds_read_b64_tr_b16 v[212:213], v221 offset:20480
	v_add_f32_e32 v254, v226, v254
	v_exp_f32_e32 v228, v228
	v_sub_f32_e32 v229, v229, v190
	v_add_f32_e32 v254, v227, v254
	v_exp_f32_e32 v229, v229
	s_waitcnt lgkmcnt(8)
	v_mfma_f32_32x32x16_bf16 v[0:15], v[214:217], v[250:253], v[0:15]
	ds_read_b64_tr_b16 v[214:215], v205 offset:16640
	ds_read_b64_tr_b16 v[216:217], v205 offset:20736
	s_nop 0
	v_cvt_pk_bf16_f32 v242, v222, v223
	v_cvt_pk_bf16_f32 v243, v224, v225
	v_cvt_pk_bf16_f32 v244, v226, v227
	v_cvt_pk_bf16_f32 v245, v228, v229
	s_nop 1
	s_waitcnt lgkmcnt(8)
	v_mfma_f32_32x32x16_bf16 v[112:127], v[238:241], v[242:245], v[112:127]
	ds_read_b64_tr_b16 v[238:239], v218 offset:16640
	ds_read_b64_tr_b16 v[240:241], v218 offset:20736
	v_sub_f32_e32 v230, v230, v190
	v_add_f32_e32 v254, v228, v254
	v_exp_f32_e32 v230, v230
	v_sub_f32_e32 v231, v231, v190
	v_add_f32_e32 v254, v229, v254
	s_waitcnt lgkmcnt(8)
	v_mfma_f32_32x32x16_bf16 v[96:111], v[128:131], v[242:245], v[96:111]
	ds_read_b64_tr_b16 v[128:129], v219 offset:16640
	ds_read_b64_tr_b16 v[130:131], v219 offset:20736
	v_exp_f32_e32 v231, v231
	v_sub_f32_e32 v232, v232, v190
	v_add_f32_e32 v254, v230, v254
	v_exp_f32_e32 v232, v232
	v_sub_f32_e32 v233, v233, v190
	s_waitcnt lgkmcnt(8)
	v_mfma_f32_32x32x16_bf16 v[80:95], v[206:209], v[242:245], v[80:95]
	ds_read_b64_tr_b16 v[206:207], v221 offset:16640
	ds_read_b64_tr_b16 v[208:209], v221 offset:20736
	v_add_f32_e32 v254, v231, v254
	v_exp_f32_e32 v233, v233
	v_sub_f32_e32 v234, v234, v190
	v_add_f32_e32 v254, v232, v254
	s_waitcnt lgkmcnt(8)
	v_mfma_f32_32x32x16_bf16 v[64:79], v[210:213], v[242:245], v[64:79]
	ds_read_b64_tr_b16 v[210:211], v205 offset:24576
	ds_read_b64_tr_b16 v[212:213], v205 offset:28672
	v_exp_f32_e32 v234, v234
	v_sub_f32_e32 v235, v235, v190
	v_add_f32_e32 v254, v233, v254
	v_exp_f32_e32 v235, v235
	s_waitcnt lgkmcnt(8)
	v_mfma_f32_32x32x16_bf16 v[48:63], v[214:217], v[242:245], v[48:63]
	ds_read_b64_tr_b16 v[214:215], v218 offset:24576
	ds_read_b64_tr_b16 v[216:217], v218 offset:28672
	v_sub_f32_e32 v236, v236, v190
	v_add_f32_e32 v254, v234, v254
	v_exp_f32_e32 v236, v236
	v_sub_f32_e32 v237, v237, v190
	s_waitcnt lgkmcnt(8)
	v_mfma_f32_32x32x16_bf16 v[32:47], v[238:241], v[242:245], v[32:47]
	ds_read_b64_tr_b16 v[238:239], v219 offset:24576
	ds_read_b64_tr_b16 v[240:241], v219 offset:28672
	v_add_f32_e32 v254, v235, v254
	v_exp_f32_e32 v237, v237
	v_add_f32_e32 v254, v236, v254
	v_add_f32_e32 v254, v237, v254
	s_waitcnt lgkmcnt(8)
	v_mfma_f32_32x32x16_bf16 v[16:31], v[128:131], v[242:245], v[16:31]
	ds_read_b64_tr_b16 v[128:129], v221 offset:24576
	ds_read_b64_tr_b16 v[130:131], v221 offset:28672
	v_cvt_pk_bf16_f32 v250, v230, v231
	v_cvt_pk_bf16_f32 v251, v232, v233
	v_cvt_pk_bf16_f32 v252, v234, v235
	v_cvt_pk_bf16_f32 v253, v236, v237
	v_add_f32_e32 v195, v195, v254
	s_waitcnt lgkmcnt(8)
	v_mfma_f32_32x32x16_bf16 v[0:15], v[206:209], v[242:245], v[0:15]
	ds_read_b64_tr_b16 v[206:207], v205 offset:24832
	ds_read_b64_tr_b16 v[208:209], v205 offset:28928
	s_waitcnt lgkmcnt(8)
	v_mfma_f32_32x32x16_bf16 v[112:127], v[210:213], v[250:253], v[112:127]
	ds_read_b64_tr_b16 v[210:211], v218 offset:24832
	ds_read_b64_tr_b16 v[212:213], v218 offset:28928
	s_waitcnt lgkmcnt(8)
	v_mfma_f32_32x32x16_bf16 v[96:111], v[214:217], v[250:253], v[96:111]
	ds_read_b64_tr_b16 v[214:215], v219 offset:24832
	ds_read_b64_tr_b16 v[216:217], v219 offset:28928
	s_waitcnt lgkmcnt(8)
	v_mfma_f32_32x32x16_bf16 v[80:95], v[238:241], v[250:253], v[80:95]
	ds_read_b64_tr_b16 v[238:239], v221 offset:24832
	ds_read_b64_tr_b16 v[240:241], v221 offset:28928
	s_waitcnt lgkmcnt(8)
	v_mfma_f32_32x32x16_bf16 v[64:79], v[128:131], v[250:253], v[64:79]
	s_waitcnt lgkmcnt(6)
	v_mfma_f32_32x32x16_bf16 v[48:63], v[206:209], v[250:253], v[48:63]
	s_waitcnt lgkmcnt(4)
	v_mfma_f32_32x32x16_bf16 v[32:47], v[210:213], v[250:253], v[32:47]
	s_waitcnt lgkmcnt(2)
	v_mfma_f32_32x32x16_bf16 v[16:31], v[214:217], v[250:253], v[16:31]
	s_waitcnt lgkmcnt(0)
	v_mfma_f32_32x32x16_bf16 v[0:15], v[238:241], v[250:253], v[0:15]
	ds_read_b128 v[206:209], v196 offset:16384
	ds_read_b128 v[210:213], v197 offset:16384
	ds_read_b128 v[214:217], v198 offset:16384
	ds_read_b128 v[238:241], v199 offset:16384
	ds_read_b128 v[242:245], v200 offset:16384
	ds_read_b128 v[250:253], v201 offset:16384
	ds_read_b128 v[222:225], v202 offset:16384
	ds_read_b128 v[226:229], v203 offset:16384
	s_waitcnt vmcnt(0)
	s_add_i32 s8, s11, 1
	s_cmp_lg_u32 s11, 2
	s_cselect_b32 s11, s8, 0
	s_add_i32 s14, s14, 64
	s_add_u32 s22, s22, 0x100000
	s_addc_u32 s23, s23, 0
	s_add_i32 s10, s10, 1
	s_add_i32 s100, s14, 63
	s_cmp_le_i32 s100, s68
	s_cbranch_scc0 .Latt_latchb_7
	s_cmp_ge_u32 s10, s66
	s_cselect_b64 s[8:9], -1, 0
	v_mov_b32_e32 v204, v176
	s_barrier
	s_branch .Latt_cont_7s1
.Latt_rs1_7s0:
	s_waitcnt lgkmcnt(8)
	v_mfma_f32_32x32x16_bf16 v[64:79], v[238:241], v[250:253], v[64:79]
	ds_read_b64_tr_b16 v[238:239], v205 offset:16384
	ds_read_b64_tr_b16 v[240:241], v205 offset:20480
	s_waitcnt lgkmcnt(8)
	v_mfma_f32_32x32x16_bf16 v[48:63], v[128:131], v[250:253], v[48:63]
	ds_read_b64_tr_b16 v[128:129], v218 offset:16384
	ds_read_b64_tr_b16 v[130:131], v218 offset:20480
	s_waitcnt lgkmcnt(8)
	v_mfma_f32_32x32x16_bf16 v[32:47], v[206:209], v[250:253], v[32:47]
	ds_read_b64_tr_b16 v[206:207], v219 offset:16384
	ds_read_b64_tr_b16 v[208:209], v219 offset:20480
	s_waitcnt lgkmcnt(8)
	v_mfma_f32_32x32x16_bf16 v[16:31], v[210:213], v[250:253], v[16:31]
	ds_read_b64_tr_b16 v[210:211], v221 offset:16384
	ds_read_b64_tr_b16 v[212:213], v221 offset:20480
	s_waitcnt lgkmcnt(8)
	v_mfma_f32_32x32x16_bf16 v[0:15], v[214:217], v[250:253], v[0:15]
	ds_read_b64_tr_b16 v[214:215], v205 offset:16640
	ds_read_b64_tr_b16 v[216:217], v205 offset:20736
	s_nop 11
	v_max_f32_e32 v246, v190, v246
	v_sub_f32_e32 v190, v190, v246
	v_exp_f32_e32 v190, v190
	s_nop 0
	v_pk_mul_f32 v[126:127], v[126:127], v[190:191] op_sel_hi:[1,0]
	v_pk_mul_f32 v[124:125], v[124:125], v[190:191] op_sel_hi:[1,0]
	v_pk_mul_f32 v[122:123], v[122:123], v[190:191] op_sel_hi:[1,0]
	v_pk_mul_f32 v[120:121], v[120:121], v[190:191] op_sel_hi:[1,0]
	v_pk_mul_f32 v[118:119], v[118:119], v[190:191] op_sel_hi:[1,0]
	v_pk_mul_f32 v[116:117], v[116:117], v[190:191] op_sel_hi:[1,0]
	v_pk_mul_f32 v[114:115], v[114:115], v[190:191] op_sel_hi:[1,0]
	v_pk_mul_f32 v[112:113], v[112:113], v[190:191] op_sel_hi:[1,0]
	v_pk_mul_f32 v[110:111], v[110:111], v[190:191] op_sel_hi:[1,0]
	v_pk_mul_f32 v[108:109], v[108:109], v[190:191] op_sel_hi:[1,0]
	v_pk_mul_f32 v[106:107], v[106:107], v[190:191] op_sel_hi:[1,0]
	v_pk_mul_f32 v[104:105], v[104:105], v[190:191] op_sel_hi:[1,0]
	v_pk_mul_f32 v[102:103], v[102:103], v[190:191] op_sel_hi:[1,0]
	v_pk_mul_f32 v[100:101], v[100:101], v[190:191] op_sel_hi:[1,0]
	v_pk_mul_f32 v[98:99], v[98:99], v[190:191] op_sel_hi:[1,0]
	v_pk_mul_f32 v[96:97], v[96:97], v[190:191] op_sel_hi:[1,0]
	v_pk_mul_f32 v[94:95], v[94:95], v[190:191] op_sel_hi:[1,0]
	v_pk_mul_f32 v[92:93], v[92:93], v[190:191] op_sel_hi:[1,0]
	v_pk_mul_f32 v[90:91], v[90:91], v[190:191] op_sel_hi:[1,0]
	v_pk_mul_f32 v[88:89], v[88:89], v[190:191] op_sel_hi:[1,0]
	v_pk_mul_f32 v[86:87], v[86:87], v[190:191] op_sel_hi:[1,0]
	v_pk_mul_f32 v[84:85], v[84:85], v[190:191] op_sel_hi:[1,0]
	v_pk_mul_f32 v[82:83], v[82:83], v[190:191] op_sel_hi:[1,0]
	v_pk_mul_f32 v[80:81], v[80:81], v[190:191] op_sel_hi:[1,0]
	v_pk_mul_f32 v[78:79], v[78:79], v[190:191] op_sel_hi:[1,0]
	v_pk_mul_f32 v[76:77], v[76:77], v[190:191] op_sel_hi:[1,0]
	v_pk_mul_f32 v[74:75], v[74:75], v[190:191] op_sel_hi:[1,0]
	v_pk_mul_f32 v[72:73], v[72:73], v[190:191] op_sel_hi:[1,0]
	v_pk_mul_f32 v[70:71], v[70:71], v[190:191] op_sel_hi:[1,0]
	v_pk_mul_f32 v[68:69], v[68:69], v[190:191] op_sel_hi:[1,0]
	v_pk_mul_f32 v[66:67], v[66:67], v[190:191] op_sel_hi:[1,0]
	v_pk_mul_f32 v[64:65], v[64:65], v[190:191] op_sel_hi:[1,0]
	v_pk_mul_f32 v[62:63], v[62:63], v[190:191] op_sel_hi:[1,0]
	v_pk_mul_f32 v[60:61], v[60:61], v[190:191] op_sel_hi:[1,0]
	v_pk_mul_f32 v[58:59], v[58:59], v[190:191] op_sel_hi:[1,0]
	v_pk_mul_f32 v[56:57], v[56:57], v[190:191] op_sel_hi:[1,0]
	v_pk_mul_f32 v[54:55], v[54:55], v[190:191] op_sel_hi:[1,0]
	v_pk_mul_f32 v[52:53], v[52:53], v[190:191] op_sel_hi:[1,0]
	v_pk_mul_f32 v[50:51], v[50:51], v[190:191] op_sel_hi:[1,0]
	v_pk_mul_f32 v[48:49], v[48:49], v[190:191] op_sel_hi:[1,0]
	v_pk_mul_f32 v[46:47], v[46:47], v[190:191] op_sel_hi:[1,0]
	v_pk_mul_f32 v[44:45], v[44:45], v[190:191] op_sel_hi:[1,0]
	v_pk_mul_f32 v[42:43], v[42:43], v[190:191] op_sel_hi:[1,0]
	v_pk_mul_f32 v[40:41], v[40:41], v[190:191] op_sel_hi:[1,0]
	v_pk_mul_f32 v[38:39], v[38:39], v[190:191] op_sel_hi:[1,0]
	v_pk_mul_f32 v[36:37], v[36:37], v[190:191] op_sel_hi:[1,0]
	v_pk_mul_f32 v[34:35], v[34:35], v[190:191] op_sel_hi:[1,0]
	v_pk_mul_f32 v[32:33], v[32:33], v[190:191] op_sel_hi:[1,0]
	v_pk_mul_f32 v[30:31], v[30:31], v[190:191] op_sel_hi:[1,0]
	v_pk_mul_f32 v[28:29], v[28:29], v[190:191] op_sel_hi:[1,0]
	v_pk_mul_f32 v[26:27], v[26:27], v[190:191] op_sel_hi:[1,0]
	v_pk_mul_f32 v[24:25], v[24:25], v[190:191] op_sel_hi:[1,0]
	v_pk_mul_f32 v[22:23], v[22:23], v[190:191] op_sel_hi:[1,0]
	v_pk_mul_f32 v[20:21], v[20:21], v[190:191] op_sel_hi:[1,0]
	v_pk_mul_f32 v[18:19], v[18:19], v[190:191] op_sel_hi:[1,0]
	v_pk_mul_f32 v[16:17], v[16:17], v[190:191] op_sel_hi:[1,0]
	v_pk_mul_f32 v[14:15], v[14:15], v[190:191] op_sel_hi:[1,0]
	v_pk_mul_f32 v[12:13], v[12:13], v[190:191] op_sel_hi:[1,0]
	v_pk_mul_f32 v[10:11], v[10:11], v[190:191] op_sel_hi:[1,0]
	v_pk_mul_f32 v[8:9], v[8:9], v[190:191] op_sel_hi:[1,0]
	v_pk_mul_f32 v[6:7], v[6:7], v[190:191] op_sel_hi:[1,0]
	v_pk_mul_f32 v[4:5], v[4:5], v[190:191] op_sel_hi:[1,0]
	v_pk_mul_f32 v[2:3], v[2:3], v[190:191] op_sel_hi:[1,0]
	v_pk_mul_f32 v[0:1], v[0:1], v[190:191] op_sel_hi:[1,0]
	v_mul_f32_e32 v195, v195, v190
	v_mov_b32_e32 v190, v246
	v_sub_f32_e32 v222, v222, v190
	v_exp_f32_e32 v222, v222
	v_sub_f32_e32 v223, v223, v190
	v_exp_f32_e32 v223, v223
	v_sub_f32_e32 v224, v224, v190
	v_add_f32_e32 v254, 0, v222
	v_exp_f32_e32 v224, v224
	v_sub_f32_e32 v225, v225, v190
	v_add_f32_e32 v254, v223, v254
	v_exp_f32_e32 v225, v225
	v_sub_f32_e32 v226, v226, v190
	v_add_f32_e32 v254, v224, v254
	v_exp_f32_e32 v226, v226
	v_sub_f32_e32 v227, v227, v190
	v_add_f32_e32 v254, v225, v254
	v_exp_f32_e32 v227, v227
	v_sub_f32_e32 v228, v228, v190
	v_add_f32_e32 v254, v226, v254
	v_exp_f32_e32 v228, v228
	v_sub_f32_e32 v229, v229, v190
	v_add_f32_e32 v254, v227, v254
	v_exp_f32_e32 v229, v229
	v_sub_f32_e32 v230, v230, v190
	v_add_f32_e32 v254, v228, v254
	v_exp_f32_e32 v230, v230
	v_sub_f32_e32 v231, v231, v190
	v_add_f32_e32 v254, v229, v254
	v_exp_f32_e32 v231, v231
	v_sub_f32_e32 v232, v232, v190
	v_add_f32_e32 v254, v230, v254
	v_exp_f32_e32 v232, v232
	v_sub_f32_e32 v233, v233, v190
	v_add_f32_e32 v254, v231, v254
	v_exp_f32_e32 v233, v233
	v_sub_f32_e32 v234, v234, v190
	v_add_f32_e32 v254, v232, v254
	v_exp_f32_e32 v234, v234
	v_sub_f32_e32 v235, v235, v190
	v_add_f32_e32 v254, v233, v254
	v_exp_f32_e32 v235, v235
	v_sub_f32_e32 v236, v236, v190
	v_add_f32_e32 v254, v234, v254
	v_exp_f32_e32 v236, v236
	v_sub_f32_e32 v237, v237, v190
	v_add_f32_e32 v254, v235, v254
	v_exp_f32_e32 v237, v237
	v_add_f32_e32 v254, v236, v254
	v_add_f32_e32 v254, v237, v254
	v_cvt_pk_bf16_f32 v242, v222, v223
	v_cvt_pk_bf16_f32 v243, v224, v225
	v_cvt_pk_bf16_f32 v244, v226, v227
	v_cvt_pk_bf16_f32 v245, v228, v229
	v_cvt_pk_bf16_f32 v250, v230, v231
	v_cvt_pk_bf16_f32 v251, v232, v233
	v_cvt_pk_bf16_f32 v252, v234, v235
	v_cvt_pk_bf16_f32 v253, v236, v237
	v_add_f32_e32 v195, v195, v254
	s_nop 1
	s_waitcnt lgkmcnt(8)
	v_mfma_f32_32x32x16_bf16 v[112:127], v[238:241], v[242:245], v[112:127]
	ds_read_b64_tr_b16 v[238:239], v218 offset:16640
	ds_read_b64_tr_b16 v[240:241], v218 offset:20736
	s_waitcnt lgkmcnt(8)
	v_mfma_f32_32x32x16_bf16 v[96:111], v[128:131], v[242:245], v[96:111]
	ds_read_b64_tr_b16 v[222:223], v219 offset:16640
	ds_read_b64_tr_b16 v[224:225], v219 offset:20736
	s_waitcnt lgkmcnt(8)
	v_mfma_f32_32x32x16_bf16 v[80:95], v[206:209], v[242:245], v[80:95]
	ds_read_b64_tr_b16 v[206:207], v221 offset:16640
	ds_read_b64_tr_b16 v[208:209], v221 offset:20736
	s_waitcnt lgkmcnt(8)
	v_mfma_f32_32x32x16_bf16 v[64:79], v[210:213], v[242:245], v[64:79]
	ds_read_b64_tr_b16 v[210:211], v205 offset:24576
	ds_read_b64_tr_b16 v[212:213], v205 offset:28672
	s_waitcnt lgkmcnt(8)
	v_mfma_f32_32x32x16_bf16 v[48:63], v[214:217], v[242:245], v[48:63]
	ds_read_b64_tr_b16 v[214:215], v218 offset:24576
	ds_read_b64_tr_b16 v[216:217], v218 offset:28672
	s_waitcnt lgkmcnt(8)
	v_mfma_f32_32x32x16_bf16 v[32:47], v[238:241], v[242:245], v[32:47]
	ds_read_b64_tr_b16 v[238:239], v219 offset:24576
	ds_read_b64_tr_b16 v[240:241], v219 offset:28672
	s_waitcnt lgkmcnt(8)
	v_mfma_f32_32x32x16_bf16 v[16:31], v[222:225], v[242:245], v[16:31]
	ds_read_b64_tr_b16 v[222:223], v221 offset:24576
	ds_read_b64_tr_b16 v[224:225], v221 offset:28672
	s_waitcnt lgkmcnt(8)
	v_mfma_f32_32x32x16_bf16 v[0:15], v[206:209], v[242:245], v[0:15]
	ds_read_b64_tr_b16 v[206:207], v205 offset:24832
	ds_read_b64_tr_b16 v[208:209], v205 offset:28928
	s_waitcnt lgkmcnt(8)
	v_mfma_f32_32x32x16_bf16 v[112:127], v[210:213], v[250:253], v[112:127]
	ds_read_b64_tr_b16 v[210:211], v218 offset:24832
	ds_read_b64_tr_b16 v[212:213], v218 offset:28928
	s_waitcnt lgkmcnt(8)
	v_mfma_f32_32x32x16_bf16 v[96:111], v[214:217], v[250:253], v[96:111]
	ds_read_b64_tr_b16 v[214:215], v219 offset:24832
	ds_read_b64_tr_b16 v[216:217], v219 offset:28928
	s_waitcnt lgkmcnt(8)
	v_mfma_f32_32x32x16_bf16 v[80:95], v[238:241], v[250:253], v[80:95]
	ds_read_b64_tr_b16 v[238:239], v221 offset:24832
	ds_read_b64_tr_b16 v[240:241], v221 offset:28928
	s_waitcnt lgkmcnt(8)
	v_mfma_f32_32x32x16_bf16 v[64:79], v[222:225], v[250:253], v[64:79]
	s_waitcnt lgkmcnt(6)
	v_mfma_f32_32x32x16_bf16 v[48:63], v[206:209], v[250:253], v[48:63]
	s_waitcnt lgkmcnt(4)
	v_mfma_f32_32x32x16_bf16 v[32:47], v[210:213], v[250:253], v[32:47]
	s_waitcnt lgkmcnt(2)
	v_mfma_f32_32x32x16_bf16 v[16:31], v[214:217], v[250:253], v[16:31]
	s_waitcnt lgkmcnt(0)
	v_mfma_f32_32x32x16_bf16 v[0:15], v[238:241], v[250:253], v[0:15]
	ds_read_b128 v[206:209], v196 offset:16384
	ds_read_b128 v[210:213], v197 offset:16384
	ds_read_b128 v[214:217], v198 offset:16384
	ds_read_b128 v[238:241], v199 offset:16384
	ds_read_b128 v[242:245], v200 offset:16384
	ds_read_b128 v[250:253], v201 offset:16384
	ds_read_b128 v[222:225], v202 offset:16384
	ds_read_b128 v[226:229], v203 offset:16384
	s_waitcnt vmcnt(0)
	s_add_i32 s8, s11, 1
	s_cmp_lg_u32 s11, 2
	s_cselect_b32 s11, s8, 0
	s_add_i32 s14, s14, 64
	s_add_u32 s22, s22, 0x100000
	s_addc_u32 s23, s23, 0
	s_add_i32 s10, s10, 1
	s_add_i32 s100, s14, 63
	s_cmp_le_i32 s100, s68
	s_cbranch_scc0 .Latt_latchb_7
	s_cmp_ge_u32 s10, s66
	s_cselect_b64 s[8:9], -1, 0
	v_mov_b32_e32 v204, v176
	s_barrier
	s_branch .Latt_cont_7s1
.Latt_slow_7s0:
.Latt_slot1_7:
.Latt_cont_7s1:
	v_add_u32_e32 v205, 0x8000, v205
	v_add_u32_e32 v218, 0x8000, v218
	v_add_u32_e32 v219, 0x8000, v219
	v_add_u32_e32 v221, 0x8000, v221
	s_waitcnt lgkmcnt(7)
	v_mfma_f32_32x32x16_bf16 v[128:143], v[206:209], v[144:147], 0
	ds_read_b128 v[206:209], v196 offset:24576
	s_cmp_lg_u64 s[8:9], 0
	s_cbranch_scc1 .Latt_nd0_7s1
	s_sub_i32 s100, s11, 1
	s_cmp_eq_u32 s11, 0
	s_cselect_b32 s100, 2, s100
	s_lshl_b32 s101, s100, 14
	s_add_i32 m0, s36, s101
	s_nop 0
	global_load_lds_dwordx4 v178, s[22:23]

.Latt_nr0_7s1:
	s_waitcnt lgkmcnt(3)
	v_mfma_f32_32x32x16_bf16 v[222:237], v[214:217], v[152:155], v[222:237]
	ds_read_b128 v[214:217], v202 offset:24576
	v_sub_f32_e32 v128, v128, v190
	v_exp_f32_e32 v128, v128
	v_sub_f32_e32 v129, v129, v190
	v_exp_f32_e32 v129, v129
	v_sub_f32_e32 v130, v130, v190
	s_waitcnt lgkmcnt(3)
	v_mfma_f32_32x32x16_bf16 v[222:237], v[238:241], v[156:159], v[222:237]
	ds_read_b128 v[238:241], v203 offset:24576
	v_add_f32_e32 v254, 0, v128
	v_exp_f32_e32 v130, v130
	v_sub_f32_e32 v131, v131, v190
	v_add_f32_e32 v254, v129, v254
	v_exp_f32_e32 v131, v131
	s_waitcnt lgkmcnt(3)
	v_mfma_f32_32x32x16_bf16 v[222:237], v[206:209], v[160:163], v[222:237]
	ds_read_b64_tr_b16 v[206:207], v205
	ds_read_b64_tr_b16 v[208:209], v205 offset:4096
	v_sub_f32_e32 v132, v132, v190
	v_add_f32_e32 v254, v130, v254
	v_exp_f32_e32 v132, v132
	v_sub_f32_e32 v133, v133, v190
	v_add_f32_e32 v254, v131, v254
	s_waitcnt lgkmcnt(4)
	v_mfma_f32_32x32x16_bf16 v[222:237], v[210:213], v[164:167], v[222:237]
	ds_read_b64_tr_b16 v[210:211], v218
	ds_read_b64_tr_b16 v[212:213], v218 offset:4096
	v_exp_f32_e32 v133, v133
	v_sub_f32_e32 v134, v134, v190
	v_add_f32_e32 v254, v132, v254
	v_exp_f32_e32 v134, v134
	s_waitcnt lgkmcnt(5)
	v_mfma_f32_32x32x16_bf16 v[222:237], v[214:217], v[168:171], v[222:237]
	ds_read_b64_tr_b16 v[214:215], v219
	ds_read_b64_tr_b16 v[216:217], v219 offset:4096
	v_sub_f32_e32 v135, v135, v190
	v_add_f32_e32 v254, v133, v254
	v_exp_f32_e32 v135, v135
	s_nop 0
	s_waitcnt lgkmcnt(6)
	v_mfma_f32_32x32x16_bf16 v[222:237], v[238:241], v[172:175], v[222:237]
	ds_read_b64_tr_b16 v[238:239], v221
	ds_read_b64_tr_b16 v[240:241], v221 offset:4096
	v_cvt_pk_bf16_f32 v242, v128, v129
	v_cvt_pk_bf16_f32 v243, v130, v131
	v_cvt_pk_bf16_f32 v244, v132, v133
	v_cvt_pk_bf16_f32 v245, v134, v135
	s_nop 1
	s_waitcnt lgkmcnt(6)
	v_mfma_f32_32x32x16_bf16 v[112:127], v[206:209], v[242:245], v[112:127]
	ds_read_b64_tr_b16 v[206:207], v205 offset:256
	ds_read_b64_tr_b16 v[208:209], v205 offset:4352
	v_sub_f32_e32 v136, v136, v190
	v_add_f32_e32 v254, v134, v254
	v_exp_f32_e32 v136, v136
	v_sub_f32_e32 v137, v137, v190
	v_add_f32_e32 v254, v135, v254
	s_waitcnt lgkmcnt(6)
	v_mfma_f32_32x32x16_bf16 v[96:111], v[210:213], v[242:245], v[96:111]
	ds_read_b64_tr_b16 v[210:211], v218 offset:256
	ds_read_b64_tr_b16 v[212:213], v218 offset:4352
	v_exp_f32_e32 v137, v137
	v_sub_f32_e32 v138, v138, v190
	v_add_f32_e32 v254, v136, v254
	v_exp_f32_e32 v138, v138
	v_sub_f32_e32 v139, v139, v190
	s_waitcnt lgkmcnt(6)
	v_mfma_f32_32x32x16_bf16 v[80:95], v[214:217], v[242:245], v[80:95]
	ds_read_b64_tr_b16 v[214:215], v219 offset:256
	ds_read_b64_tr_b16 v[216:217], v219 offset:4352
	v_add_f32_e32 v254, v137, v254
	v_exp_f32_e32 v139, v139
	v_sub_f32_e32 v140, v140, v190
	v_add_f32_e32 v254, v138, v254
	s_waitcnt lgkmcnt(6)
	v_mfma_f32_32x32x16_bf16 v[64:79], v[238:241], v[242:245], v[64:79]
	ds_read_b64_tr_b16 v[238:239], v221 offset:256
	ds_read_b64_tr_b16 v[240:241], v221 offset:4352
	v_exp_f32_e32 v140, v140
	v_sub_f32_e32 v141, v141, v190
	v_add_f32_e32 v254, v139, v254
	v_exp_f32_e32 v141, v141
	s_waitcnt lgkmcnt(6)
	v_mfma_f32_32x32x16_bf16 v[48:63], v[206:209], v[242:245], v[48:63]
	ds_read_b64_tr_b16 v[206:207], v205 offset:8192
	ds_read_b64_tr_b16 v[208:209], v205 offset:12288
	v_sub_f32_e32 v142, v142, v190
	v_add_f32_e32 v254, v140, v254
	v_exp_f32_e32 v142, v142
	v_sub_f32_e32 v143, v143, v190
	s_waitcnt lgkmcnt(6)
	v_mfma_f32_32x32x16_bf16 v[32:47], v[210:213], v[242:245], v[32:47]
	ds_read_b64_tr_b16 v[210:211], v218 offset:8192
	ds_read_b64_tr_b16 v[212:213], v218 offset:12288
	v_add_f32_e32 v254, v141, v254
	v_exp_f32_e32 v143, v143
	v_add_f32_e32 v254, v142, v254
	v_add_f32_e32 v254, v143, v254
	s_waitcnt lgkmcnt(6)
	v_mfma_f32_32x32x16_bf16 v[16:31], v[214:217], v[242:245], v[16:31]
	ds_read_b64_tr_b16 v[214:215], v219 offset:8192
	ds_read_b64_tr_b16 v[216:217], v219 offset:12288
	v_cvt_pk_bf16_f32 v250, v136, v137
	v_cvt_pk_bf16_f32 v251, v138, v139
	v_cvt_pk_bf16_f32 v252, v140, v141
	v_cvt_pk_bf16_f32 v253, v142, v143
	v_add_f32_e32 v195, v195, v254
	s_waitcnt lgkmcnt(6)
	v_mfma_f32_32x32x16_bf16 v[0:15], v[238:241], v[242:245], v[0:15]
	ds_read_b64_tr_b16 v[238:239], v221 offset:8192
	ds_read_b64_tr_b16 v[240:241], v221 offset:12288
	ds_read_b64_tr_b16 v[128:129], v205 offset:8448
	ds_read_b64_tr_b16 v[130:131], v205 offset:12544
	s_waitcnt lgkmcnt(8)
	v_mfma_f32_32x32x16_bf16 v[112:127], v[206:209], v[250:253], v[112:127]
	ds_read_b64_tr_b16 v[206:207], v218 offset:8448
	ds_read_b64_tr_b16 v[208:209], v218 offset:12544
	v_max3_f32 v246, v222, v223, v224
	v_max3_f32 v247, v225, v226, v227
	v_max3_f32 v246, v246, v228, v229
	v_max3_f32 v247, v247, v230, v231
	v_max3_f32 v246, v246, v232, v233
	s_waitcnt lgkmcnt(8)
	v_mfma_f32_32x32x16_bf16 v[96:111], v[210:213], v[250:253], v[96:111]
	ds_read_b64_tr_b16 v[210:211], v219 offset:8448
	ds_read_b64_tr_b16 v[212:213], v219 offset:12544
	v_max3_f32 v247, v247, v234, v235
	v_max3_f32 v246, v246, v236, v237
	v_max_f32_e32 v246, v246, v247
	v_mov_b32_e32 v247, v246
	v_add_f32_e32 v249, 0x41000000, v190
	s_waitcnt lgkmcnt(8)
	v_mfma_f32_32x32x16_bf16 v[80:95], v[214:217], v[250:253], v[80:95]
	ds_read_b64_tr_b16 v[214:215], v221 offset:8448
	ds_read_b64_tr_b16 v[216:217], v221 offset:12544
	s_nop 1
	v_permlane32_swap_b32_e32 v246, v247
	v_max_f32_e32 v246, v246, v247
	v_cmp_gt_f32_e32 vcc, v246, v249
	s_cbranch_vccnz .Latt_rs1_7s1
	s_waitcnt lgkmcnt(8)
	v_mfma_f32_32x32x16_bf16 v[64:79], v[238:241], v[250:253], v[64:79]
	ds_read_b64_tr_b16 v[238:239], v205 offset:16384
	ds_read_b64_tr_b16 v[240:241], v205 offset:20480
	v_sub_f32_e32 v222, v222, v190
	v_exp_f32_e32 v222, v222
	v_sub_f32_e32 v223, v223, v190
	v_exp_f32_e32 v223, v223
	v_sub_f32_e32 v224, v224, v190
	v_add_f32_e32 v254, 0, v222
	s_waitcnt lgkmcnt(8)
	v_mfma_f32_32x32x16_bf16 v[48:63], v[128:131], v[250:253], v[48:63]
	ds_read_b64_tr_b16 v[128:129], v218 offset:16384
	ds_read_b64_tr_b16 v[130:131], v218 offset:20480
	v_exp_f32_e32 v224, v224
	v_sub_f32_e32 v225, v225, v190
	v_add_f32_e32 v254, v223, v254
	v_exp_f32_e32 v225, v225
	v_sub_f32_e32 v226, v226, v190
	v_add_f32_e32 v254, v224, v254
	s_waitcnt lgkmcnt(8)
	v_mfma_f32_32x32x16_bf16 v[32:47], v[206:209], v[250:253], v[32:47]
	ds_read_b64_tr_b16 v[206:207], v219 offset:16384
	ds_read_b64_tr_b16 v[208:209], v219 offset:20480
	v_exp_f32_e32 v226, v226
	v_sub_f32_e32 v227, v227, v190
	v_add_f32_e32 v254, v225, v254
	v_exp_f32_e32 v227, v227
	v_sub_f32_e32 v228, v228, v190
	s_waitcnt lgkmcnt(8)
	v_mfma_f32_32x32x16_bf16 v[16:31], v[210:213], v[250:253], v[16:31]
	ds_read_b64_tr_b16 v[210:211], v221 offset:16384
	ds_read_b64_tr_b16 v[212:213], v221 offset:20480
	v_add_f32_e32 v254, v226, v254
	v_exp_f32_e32 v228, v228
	v_sub_f32_e32 v229, v229, v190
	v_add_f32_e32 v254, v227, v254
	v_exp_f32_e32 v229, v229
	s_waitcnt lgkmcnt(8)
	v_mfma_f32_32x32x16_bf16 v[0:15], v[214:217], v[250:253], v[0:15]
	ds_read_b64_tr_b16 v[214:215], v205 offset:16640
	ds_read_b64_tr_b16 v[216:217], v205 offset:20736
	s_nop 0
	v_cvt_pk_bf16_f32 v242, v222, v223
	v_cvt_pk_bf16_f32 v243, v224, v225
	v_cvt_pk_bf16_f32 v244, v226, v227
	v_cvt_pk_bf16_f32 v245, v228, v229
	s_nop 1
	s_waitcnt lgkmcnt(8)
	v_mfma_f32_32x32x16_bf16 v[112:127], v[238:241], v[242:245], v[112:127]
	ds_read_b64_tr_b16 v[238:239], v218 offset:16640
	ds_read_b64_tr_b16 v[240:241], v218 offset:20736
	v_sub_f32_e32 v230, v230, v190
	v_add_f32_e32 v254, v228, v254
	v_exp_f32_e32 v230, v230
	v_sub_f32_e32 v231, v231, v190
	v_add_f32_e32 v254, v229, v254
	s_waitcnt lgkmcnt(8)
	v_mfma_f32_32x32x16_bf16 v[96:111], v[128:131], v[242:245], v[96:111]
	ds_read_b64_tr_b16 v[128:129], v219 offset:16640
	ds_read_b64_tr_b16 v[130:131], v219 offset:20736
	v_exp_f32_e32 v231, v231
	v_sub_f32_e32 v232, v232, v190
	v_add_f32_e32 v254, v230, v254
	v_exp_f32_e32 v232, v232
	v_sub_f32_e32 v233, v233, v190
	s_waitcnt lgkmcnt(8)
	v_mfma_f32_32x32x16_bf16 v[80:95], v[206:209], v[242:245], v[80:95]
	ds_read_b64_tr_b16 v[206:207], v221 offset:16640
	ds_read_b64_tr_b16 v[208:209], v221 offset:20736
	v_add_f32_e32 v254, v231, v254
	v_exp_f32_e32 v233, v233
	v_sub_f32_e32 v234, v234, v190
	v_add_f32_e32 v254, v232, v254
	s_waitcnt lgkmcnt(8)
	v_mfma_f32_32x32x16_bf16 v[64:79], v[210:213], v[242:245], v[64:79]
	ds_read_b64_tr_b16 v[210:211], v205 offset:24576
	ds_read_b64_tr_b16 v[212:213], v205 offset:28672
	v_exp_f32_e32 v234, v234
	v_sub_f32_e32 v235, v235, v190
	v_add_f32_e32 v254, v233, v254
	v_exp_f32_e32 v235, v235
	s_waitcnt lgkmcnt(8)
	v_mfma_f32_32x32x16_bf16 v[48:63], v[214:217], v[242:245], v[48:63]
	ds_read_b64_tr_b16 v[214:215], v218 offset:24576
	ds_read_b64_tr_b16 v[216:217], v218 offset:28672
	v_sub_f32_e32 v236, v236, v190
	v_add_f32_e32 v254, v234, v254
	v_exp_f32_e32 v236, v236
	v_sub_f32_e32 v237, v237, v190
	s_waitcnt lgkmcnt(8)
	v_mfma_f32_32x32x16_bf16 v[32:47], v[238:241], v[242:245], v[32:47]
	ds_read_b64_tr_b16 v[238:239], v219 offset:24576
	ds_read_b64_tr_b16 v[240:241], v219 offset:28672
	v_add_f32_e32 v254, v235, v254
	v_exp_f32_e32 v237, v237
	v_add_f32_e32 v254, v236, v254
	v_add_f32_e32 v254, v237, v254
	s_waitcnt lgkmcnt(8)
	v_mfma_f32_32x32x16_bf16 v[16:31], v[128:131], v[242:245], v[16:31]
	ds_read_b64_tr_b16 v[128:129], v221 offset:24576
	ds_read_b64_tr_b16 v[130:131], v221 offset:28672
	v_cvt_pk_bf16_f32 v250, v230, v231
	v_cvt_pk_bf16_f32 v251, v232, v233
	v_cvt_pk_bf16_f32 v252, v234, v235
	v_cvt_pk_bf16_f32 v253, v236, v237
	v_add_f32_e32 v195, v195, v254
	s_waitcnt lgkmcnt(8)
	v_mfma_f32_32x32x16_bf16 v[0:15], v[206:209], v[242:245], v[0:15]
	ds_read_b64_tr_b16 v[206:207], v205 offset:24832
	ds_read_b64_tr_b16 v[208:209], v205 offset:28928
	s_waitcnt lgkmcnt(8)
	v_mfma_f32_32x32x16_bf16 v[112:127], v[210:213], v[250:253], v[112:127]
	ds_read_b64_tr_b16 v[210:211], v218 offset:24832
	ds_read_b64_tr_b16 v[212:213], v218 offset:28928
	s_waitcnt lgkmcnt(8)
	v_mfma_f32_32x32x16_bf16 v[96:111], v[214:217], v[250:253], v[96:111]
	ds_read_b64_tr_b16 v[214:215], v219 offset:24832
	ds_read_b64_tr_b16 v[216:217], v219 offset:28928
	s_waitcnt lgkmcnt(8)
	v_mfma_f32_32x32x16_bf16 v[80:95], v[238:241], v[250:253], v[80:95]
	ds_read_b64_tr_b16 v[238:239], v221 offset:24832
	ds_read_b64_tr_b16 v[240:241], v221 offset:28928
	s_waitcnt lgkmcnt(8)
	v_mfma_f32_32x32x16_bf16 v[64:79], v[128:131], v[250:253], v[64:79]
	s_waitcnt lgkmcnt(6)
	v_mfma_f32_32x32x16_bf16 v[48:63], v[206:209], v[250:253], v[48:63]
	s_waitcnt lgkmcnt(4)
	v_mfma_f32_32x32x16_bf16 v[32:47], v[210:213], v[250:253], v[32:47]
	s_waitcnt lgkmcnt(2)
	v_mfma_f32_32x32x16_bf16 v[16:31], v[214:217], v[250:253], v[16:31]
	s_waitcnt lgkmcnt(0)
	v_mfma_f32_32x32x16_bf16 v[0:15], v[238:241], v[250:253], v[0:15]
	ds_read_b128 v[206:209], v196 offset:32768
	ds_read_b128 v[210:213], v197 offset:32768
	ds_read_b128 v[214:217], v198 offset:32768
	ds_read_b128 v[238:241], v199 offset:32768
	ds_read_b128 v[242:245], v200 offset:32768
	ds_read_b128 v[250:253], v201 offset:32768
	ds_read_b128 v[222:225], v202 offset:32768
	ds_read_b128 v[226:229], v203 offset:32768
	s_waitcnt vmcnt(0)
	s_add_i32 s8, s11, 1
	s_cmp_lg_u32 s11, 2
	s_cselect_b32 s11, s8, 0
	s_add_i32 s14, s14, 64
	s_add_u32 s22, s22, 0x100000
	s_addc_u32 s23, s23, 0
	s_add_i32 s10, s10, 1
	s_add_i32 s100, s14, 63
	s_cmp_le_i32 s100, s68
	s_cbranch_scc0 .Latt_latchb_7
	s_cmp_ge_u32 s10, s66
	s_cselect_b64 s[8:9], -1, 0
	v_mov_b32_e32 v204, v176
	s_barrier
	s_branch .Latt_cont_7s2
.Latt_rs1_7s1:
	s_waitcnt lgkmcnt(8)
	v_mfma_f32_32x32x16_bf16 v[64:79], v[238:241], v[250:253], v[64:79]
	ds_read_b64_tr_b16 v[238:239], v205 offset:16384
	ds_read_b64_tr_b16 v[240:241], v205 offset:20480
	s_waitcnt lgkmcnt(8)
	v_mfma_f32_32x32x16_bf16 v[48:63], v[128:131], v[250:253], v[48:63]
	ds_read_b64_tr_b16 v[128:129], v218 offset:16384
	ds_read_b64_tr_b16 v[130:131], v218 offset:20480
	s_waitcnt lgkmcnt(8)
	v_mfma_f32_32x32x16_bf16 v[32:47], v[206:209], v[250:253], v[32:47]
	ds_read_b64_tr_b16 v[206:207], v219 offset:16384
	ds_read_b64_tr_b16 v[208:209], v219 offset:20480
	s_waitcnt lgkmcnt(8)
	v_mfma_f32_32x32x16_bf16 v[16:31], v[210:213], v[250:253], v[16:31]
	ds_read_b64_tr_b16 v[210:211], v221 offset:16384
	ds_read_b64_tr_b16 v[212:213], v221 offset:20480
	s_waitcnt lgkmcnt(8)
	v_mfma_f32_32x32x16_bf16 v[0:15], v[214:217], v[250:253], v[0:15]
	ds_read_b64_tr_b16 v[214:215], v205 offset:16640
	ds_read_b64_tr_b16 v[216:217], v205 offset:20736
	s_nop 11
	v_max_f32_e32 v246, v190, v246
	v_sub_f32_e32 v190, v190, v246
	v_exp_f32_e32 v190, v190
	s_nop 0
	v_pk_mul_f32 v[126:127], v[126:127], v[190:191] op_sel_hi:[1,0]
	v_pk_mul_f32 v[124:125], v[124:125], v[190:191] op_sel_hi:[1,0]
	v_pk_mul_f32 v[122:123], v[122:123], v[190:191] op_sel_hi:[1,0]
	v_pk_mul_f32 v[120:121], v[120:121], v[190:191] op_sel_hi:[1,0]
	v_pk_mul_f32 v[118:119], v[118:119], v[190:191] op_sel_hi:[1,0]
	v_pk_mul_f32 v[116:117], v[116:117], v[190:191] op_sel_hi:[1,0]
	v_pk_mul_f32 v[114:115], v[114:115], v[190:191] op_sel_hi:[1,0]
	v_pk_mul_f32 v[112:113], v[112:113], v[190:191] op_sel_hi:[1,0]
	v_pk_mul_f32 v[110:111], v[110:111], v[190:191] op_sel_hi:[1,0]
	v_pk_mul_f32 v[108:109], v[108:109], v[190:191] op_sel_hi:[1,0]
	v_pk_mul_f32 v[106:107], v[106:107], v[190:191] op_sel_hi:[1,0]
	v_pk_mul_f32 v[104:105], v[104:105], v[190:191] op_sel_hi:[1,0]
	v_pk_mul_f32 v[102:103], v[102:103], v[190:191] op_sel_hi:[1,0]
	v_pk_mul_f32 v[100:101], v[100:101], v[190:191] op_sel_hi:[1,0]
	v_pk_mul_f32 v[98:99], v[98:99], v[190:191] op_sel_hi:[1,0]
	v_pk_mul_f32 v[96:97], v[96:97], v[190:191] op_sel_hi:[1,0]
	v_pk_mul_f32 v[94:95], v[94:95], v[190:191] op_sel_hi:[1,0]
	v_pk_mul_f32 v[92:93], v[92:93], v[190:191] op_sel_hi:[1,0]
	v_pk_mul_f32 v[90:91], v[90:91], v[190:191] op_sel_hi:[1,0]
	v_pk_mul_f32 v[88:89], v[88:89], v[190:191] op_sel_hi:[1,0]
	v_pk_mul_f32 v[86:87], v[86:87], v[190:191] op_sel_hi:[1,0]
	v_pk_mul_f32 v[84:85], v[84:85], v[190:191] op_sel_hi:[1,0]
	v_pk_mul_f32 v[82:83], v[82:83], v[190:191] op_sel_hi:[1,0]
	v_pk_mul_f32 v[80:81], v[80:81], v[190:191] op_sel_hi:[1,0]
	v_pk_mul_f32 v[78:79], v[78:79], v[190:191] op_sel_hi:[1,0]
	v_pk_mul_f32 v[76:77], v[76:77], v[190:191] op_sel_hi:[1,0]
	v_pk_mul_f32 v[74:75], v[74:75], v[190:191] op_sel_hi:[1,0]
	v_pk_mul_f32 v[72:73], v[72:73], v[190:191] op_sel_hi:[1,0]
	v_pk_mul_f32 v[70:71], v[70:71], v[190:191] op_sel_hi:[1,0]
	v_pk_mul_f32 v[68:69], v[68:69], v[190:191] op_sel_hi:[1,0]
	v_pk_mul_f32 v[66:67], v[66:67], v[190:191] op_sel_hi:[1,0]
	v_pk_mul_f32 v[64:65], v[64:65], v[190:191] op_sel_hi:[1,0]
	v_pk_mul_f32 v[62:63], v[62:63], v[190:191] op_sel_hi:[1,0]
	v_pk_mul_f32 v[60:61], v[60:61], v[190:191] op_sel_hi:[1,0]
	v_pk_mul_f32 v[58:59], v[58:59], v[190:191] op_sel_hi:[1,0]
	v_pk_mul_f32 v[56:57], v[56:57], v[190:191] op_sel_hi:[1,0]
	v_pk_mul_f32 v[54:55], v[54:55], v[190:191] op_sel_hi:[1,0]
	v_pk_mul_f32 v[52:53], v[52:53], v[190:191] op_sel_hi:[1,0]
	v_pk_mul_f32 v[50:51], v[50:51], v[190:191] op_sel_hi:[1,0]
	v_pk_mul_f32 v[48:49], v[48:49], v[190:191] op_sel_hi:[1,0]
	v_pk_mul_f32 v[46:47], v[46:47], v[190:191] op_sel_hi:[1,0]
	v_pk_mul_f32 v[44:45], v[44:45], v[190:191] op_sel_hi:[1,0]
	v_pk_mul_f32 v[42:43], v[42:43], v[190:191] op_sel_hi:[1,0]
	v_pk_mul_f32 v[40:41], v[40:41], v[190:191] op_sel_hi:[1,0]
	v_pk_mul_f32 v[38:39], v[38:39], v[190:191] op_sel_hi:[1,0]
	v_pk_mul_f32 v[36:37], v[36:37], v[190:191] op_sel_hi:[1,0]
	v_pk_mul_f32 v[34:35], v[34:35], v[190:191] op_sel_hi:[1,0]
	v_pk_mul_f32 v[32:33], v[32:33], v[190:191] op_sel_hi:[1,0]
	v_pk_mul_f32 v[30:31], v[30:31], v[190:191] op_sel_hi:[1,0]
	v_pk_mul_f32 v[28:29], v[28:29], v[190:191] op_sel_hi:[1,0]
	v_pk_mul_f32 v[26:27], v[26:27], v[190:191] op_sel_hi:[1,0]
	v_pk_mul_f32 v[24:25], v[24:25], v[190:191] op_sel_hi:[1,0]
	v_pk_mul_f32 v[22:23], v[22:23], v[190:191] op_sel_hi:[1,0]
	v_pk_mul_f32 v[20:21], v[20:21], v[190:191] op_sel_hi:[1,0]
	v_pk_mul_f32 v[18:19], v[18:19], v[190:191] op_sel_hi:[1,0]
	v_pk_mul_f32 v[16:17], v[16:17], v[190:191] op_sel_hi:[1,0]
	v_pk_mul_f32 v[14:15], v[14:15], v[190:191] op_sel_hi:[1,0]
	v_pk_mul_f32 v[12:13], v[12:13], v[190:191] op_sel_hi:[1,0]
	v_pk_mul_f32 v[10:11], v[10:11], v[190:191] op_sel_hi:[1,0]
	v_pk_mul_f32 v[8:9], v[8:9], v[190:191] op_sel_hi:[1,0]
	v_pk_mul_f32 v[6:7], v[6:7], v[190:191] op_sel_hi:[1,0]
	v_pk_mul_f32 v[4:5], v[4:5], v[190:191] op_sel_hi:[1,0]
	v_pk_mul_f32 v[2:3], v[2:3], v[190:191] op_sel_hi:[1,0]
	v_pk_mul_f32 v[0:1], v[0:1], v[190:191] op_sel_hi:[1,0]
	v_mul_f32_e32 v195, v195, v190
	v_mov_b32_e32 v190, v246
	v_sub_f32_e32 v222, v222, v190
	v_exp_f32_e32 v222, v222
	v_sub_f32_e32 v223, v223, v190
	v_exp_f32_e32 v223, v223
	v_sub_f32_e32 v224, v224, v190
	v_add_f32_e32 v254, 0, v222
	v_exp_f32_e32 v224, v224
	v_sub_f32_e32 v225, v225, v190
	v_add_f32_e32 v254, v223, v254
	v_exp_f32_e32 v225, v225
	v_sub_f32_e32 v226, v226, v190
	v_add_f32_e32 v254, v224, v254
	v_exp_f32_e32 v226, v226
	v_sub_f32_e32 v227, v227, v190
	v_add_f32_e32 v254, v225, v254
	v_exp_f32_e32 v227, v227
	v_sub_f32_e32 v228, v228, v190
	v_add_f32_e32 v254, v226, v254
	v_exp_f32_e32 v228, v228
	v_sub_f32_e32 v229, v229, v190
	v_add_f32_e32 v254, v227, v254
	v_exp_f32_e32 v229, v229
	v_sub_f32_e32 v230, v230, v190
	v_add_f32_e32 v254, v228, v254
	v_exp_f32_e32 v230, v230
	v_sub_f32_e32 v231, v231, v190
	v_add_f32_e32 v254, v229, v254
	v_exp_f32_e32 v231, v231
	v_sub_f32_e32 v232, v232, v190
	v_add_f32_e32 v254, v230, v254
	v_exp_f32_e32 v232, v232
	v_sub_f32_e32 v233, v233, v190
	v_add_f32_e32 v254, v231, v254
	v_exp_f32_e32 v233, v233
	v_sub_f32_e32 v234, v234, v190
	v_add_f32_e32 v254, v232, v254
	v_exp_f32_e32 v234, v234
	v_sub_f32_e32 v235, v235, v190
	v_add_f32_e32 v254, v233, v254
	v_exp_f32_e32 v235, v235
	v_sub_f32_e32 v236, v236, v190
	v_add_f32_e32 v254, v234, v254
	v_exp_f32_e32 v236, v236
	v_sub_f32_e32 v237, v237, v190
	v_add_f32_e32 v254, v235, v254
	v_exp_f32_e32 v237, v237
	v_add_f32_e32 v254, v236, v254
	v_add_f32_e32 v254, v237, v254
	v_cvt_pk_bf16_f32 v242, v222, v223
	v_cvt_pk_bf16_f32 v243, v224, v225
	v_cvt_pk_bf16_f32 v244, v226, v227
	v_cvt_pk_bf16_f32 v245, v228, v229
	v_cvt_pk_bf16_f32 v250, v230, v231
	v_cvt_pk_bf16_f32 v251, v232, v233
	v_cvt_pk_bf16_f32 v252, v234, v235
	v_cvt_pk_bf16_f32 v253, v236, v237
	v_add_f32_e32 v195, v195, v254
	s_nop 1
	s_waitcnt lgkmcnt(8)
	v_mfma_f32_32x32x16_bf16 v[112:127], v[238:241], v[242:245], v[112:127]
	ds_read_b64_tr_b16 v[238:239], v218 offset:16640
	ds_read_b64_tr_b16 v[240:241], v218 offset:20736
	s_waitcnt lgkmcnt(8)
	v_mfma_f32_32x32x16_bf16 v[96:111], v[128:131], v[242:245], v[96:111]
	ds_read_b64_tr_b16 v[222:223], v219 offset:16640
	ds_read_b64_tr_b16 v[224:225], v219 offset:20736
	s_waitcnt lgkmcnt(8)
	v_mfma_f32_32x32x16_bf16 v[80:95], v[206:209], v[242:245], v[80:95]
	ds_read_b64_tr_b16 v[206:207], v221 offset:16640
	ds_read_b64_tr_b16 v[208:209], v221 offset:20736
	s_waitcnt lgkmcnt(8)
	v_mfma_f32_32x32x16_bf16 v[64:79], v[210:213], v[242:245], v[64:79]
	ds_read_b64_tr_b16 v[210:211], v205 offset:24576
	ds_read_b64_tr_b16 v[212:213], v205 offset:28672
	s_waitcnt lgkmcnt(8)
	v_mfma_f32_32x32x16_bf16 v[48:63], v[214:217], v[242:245], v[48:63]
	ds_read_b64_tr_b16 v[214:215], v218 offset:24576
	ds_read_b64_tr_b16 v[216:217], v218 offset:28672
	s_waitcnt lgkmcnt(8)
	v_mfma_f32_32x32x16_bf16 v[32:47], v[238:241], v[242:245], v[32:47]
	ds_read_b64_tr_b16 v[238:239], v219 offset:24576
	ds_read_b64_tr_b16 v[240:241], v219 offset:28672
	s_waitcnt lgkmcnt(8)
	v_mfma_f32_32x32x16_bf16 v[16:31], v[222:225], v[242:245], v[16:31]
	ds_read_b64_tr_b16 v[222:223], v221 offset:24576
	ds_read_b64_tr_b16 v[224:225], v221 offset:28672
	s_waitcnt lgkmcnt(8)
	v_mfma_f32_32x32x16_bf16 v[0:15], v[206:209], v[242:245], v[0:15]
	ds_read_b64_tr_b16 v[206:207], v205 offset:24832
	ds_read_b64_tr_b16 v[208:209], v205 offset:28928
	s_waitcnt lgkmcnt(8)
	v_mfma_f32_32x32x16_bf16 v[112:127], v[210:213], v[250:253], v[112:127]
	ds_read_b64_tr_b16 v[210:211], v218 offset:24832
	ds_read_b64_tr_b16 v[212:213], v218 offset:28928
	s_waitcnt lgkmcnt(8)
	v_mfma_f32_32x32x16_bf16 v[96:111], v[214:217], v[250:253], v[96:111]
	ds_read_b64_tr_b16 v[214:215], v219 offset:24832
	ds_read_b64_tr_b16 v[216:217], v219 offset:28928
	s_waitcnt lgkmcnt(8)
	v_mfma_f32_32x32x16_bf16 v[80:95], v[238:241], v[250:253], v[80:95]
	ds_read_b64_tr_b16 v[238:239], v221 offset:24832
	ds_read_b64_tr_b16 v[240:241], v221 offset:28928
	s_waitcnt lgkmcnt(8)
	v_mfma_f32_32x32x16_bf16 v[64:79], v[222:225], v[250:253], v[64:79]
	s_waitcnt lgkmcnt(6)
	v_mfma_f32_32x32x16_bf16 v[48:63], v[206:209], v[250:253], v[48:63]
	s_waitcnt lgkmcnt(4)
	v_mfma_f32_32x32x16_bf16 v[32:47], v[210:213], v[250:253], v[32:47]
	s_waitcnt lgkmcnt(2)
	v_mfma_f32_32x32x16_bf16 v[16:31], v[214:217], v[250:253], v[16:31]
	s_waitcnt lgkmcnt(0)
	v_mfma_f32_32x32x16_bf16 v[0:15], v[238:241], v[250:253], v[0:15]
	ds_read_b128 v[206:209], v196 offset:32768
	ds_read_b128 v[210:213], v197 offset:32768
	ds_read_b128 v[214:217], v198 offset:32768
	ds_read_b128 v[238:241], v199 offset:32768
	ds_read_b128 v[242:245], v200 offset:32768
	ds_read_b128 v[250:253], v201 offset:32768
	ds_read_b128 v[222:225], v202 offset:32768
	ds_read_b128 v[226:229], v203 offset:32768
	s_waitcnt vmcnt(0)
	s_add_i32 s8, s11, 1
	s_cmp_lg_u32 s11, 2
	s_cselect_b32 s11, s8, 0
	s_add_i32 s14, s14, 64
	s_add_u32 s22, s22, 0x100000
	s_addc_u32 s23, s23, 0
	s_add_i32 s10, s10, 1
	s_add_i32 s100, s14, 63
	s_cmp_le_i32 s100, s68
	s_cbranch_scc0 .Latt_latchb_7
	s_cmp_ge_u32 s10, s66
	s_cselect_b64 s[8:9], -1, 0
	v_mov_b32_e32 v204, v176
	s_barrier
	s_branch .Latt_cont_7s2
.Latt_slow_7s1:
.Latt_slot2_7:
.Latt_cont_7s2:
	v_add_u32_e32 v205, 0x8000, v205
	v_add_u32_e32 v218, 0x8000, v218
	v_add_u32_e32 v219, 0x8000, v219
	v_add_u32_e32 v221, 0x8000, v221
	s_waitcnt lgkmcnt(7)
	v_mfma_f32_32x32x16_bf16 v[128:143], v[206:209], v[144:147], 0
	ds_read_b128 v[206:209], v196 offset:40960
	s_cmp_lg_u64 s[8:9], 0
	s_cbranch_scc1 .Latt_nd0_7s2
	s_sub_i32 s100, s11, 1
	s_cmp_eq_u32 s11, 0
	s_cselect_b32 s100, 2, s100
	s_lshl_b32 s101, s100, 14
	s_add_i32 m0, s36, s101
	s_nop 0
	global_load_lds_dwordx4 v178, s[22:23]

.Latt_nr0_7s2:
	s_waitcnt lgkmcnt(3)
	v_mfma_f32_32x32x16_bf16 v[222:237], v[214:217], v[152:155], v[222:237]
	ds_read_b128 v[214:217], v202 offset:40960
	v_sub_f32_e32 v128, v128, v190
	v_exp_f32_e32 v128, v128
	v_sub_f32_e32 v129, v129, v190
	v_exp_f32_e32 v129, v129
	v_sub_f32_e32 v130, v130, v190
	s_waitcnt lgkmcnt(3)
	v_mfma_f32_32x32x16_bf16 v[222:237], v[238:241], v[156:159], v[222:237]
	ds_read_b128 v[238:241], v203 offset:40960
	v_add_f32_e32 v254, 0, v128
	v_exp_f32_e32 v130, v130
	v_sub_f32_e32 v131, v131, v190
	v_add_f32_e32 v254, v129, v254
	v_exp_f32_e32 v131, v131
	s_waitcnt lgkmcnt(3)
	v_mfma_f32_32x32x16_bf16 v[222:237], v[206:209], v[160:163], v[222:237]
	ds_read_b64_tr_b16 v[206:207], v205
	ds_read_b64_tr_b16 v[208:209], v205 offset:4096
	v_sub_f32_e32 v132, v132, v190
	v_add_f32_e32 v254, v130, v254
	v_exp_f32_e32 v132, v132
	v_sub_f32_e32 v133, v133, v190
	v_add_f32_e32 v254, v131, v254
	s_waitcnt lgkmcnt(4)
	v_mfma_f32_32x32x16_bf16 v[222:237], v[210:213], v[164:167], v[222:237]
	ds_read_b64_tr_b16 v[210:211], v218
	ds_read_b64_tr_b16 v[212:213], v218 offset:4096
	v_exp_f32_e32 v133, v133
	v_sub_f32_e32 v134, v134, v190
	v_add_f32_e32 v254, v132, v254
	v_exp_f32_e32 v134, v134
	s_waitcnt lgkmcnt(5)
	v_mfma_f32_32x32x16_bf16 v[222:237], v[214:217], v[168:171], v[222:237]
	ds_read_b64_tr_b16 v[214:215], v219
	ds_read_b64_tr_b16 v[216:217], v219 offset:4096
	v_sub_f32_e32 v135, v135, v190
	v_add_f32_e32 v254, v133, v254
	v_exp_f32_e32 v135, v135
	s_nop 0
	s_waitcnt lgkmcnt(6)
	v_mfma_f32_32x32x16_bf16 v[222:237], v[238:241], v[172:175], v[222:237]
	ds_read_b64_tr_b16 v[238:239], v221
	ds_read_b64_tr_b16 v[240:241], v221 offset:4096
	v_cvt_pk_bf16_f32 v242, v128, v129
	v_cvt_pk_bf16_f32 v243, v130, v131
	v_cvt_pk_bf16_f32 v244, v132, v133
	v_cvt_pk_bf16_f32 v245, v134, v135
	s_nop 1
	s_waitcnt lgkmcnt(6)
	v_mfma_f32_32x32x16_bf16 v[112:127], v[206:209], v[242:245], v[112:127]
	ds_read_b64_tr_b16 v[206:207], v205 offset:256
	ds_read_b64_tr_b16 v[208:209], v205 offset:4352
	v_sub_f32_e32 v136, v136, v190
	v_add_f32_e32 v254, v134, v254
	v_exp_f32_e32 v136, v136
	v_sub_f32_e32 v137, v137, v190
	v_add_f32_e32 v254, v135, v254
	s_waitcnt lgkmcnt(6)
	v_mfma_f32_32x32x16_bf16 v[96:111], v[210:213], v[242:245], v[96:111]
	ds_read_b64_tr_b16 v[210:211], v218 offset:256
	ds_read_b64_tr_b16 v[212:213], v218 offset:4352
	v_exp_f32_e32 v137, v137
	v_sub_f32_e32 v138, v138, v190
	v_add_f32_e32 v254, v136, v254
	v_exp_f32_e32 v138, v138
	v_sub_f32_e32 v139, v139, v190
	s_waitcnt lgkmcnt(6)
	v_mfma_f32_32x32x16_bf16 v[80:95], v[214:217], v[242:245], v[80:95]
	ds_read_b64_tr_b16 v[214:215], v219 offset:256
	ds_read_b64_tr_b16 v[216:217], v219 offset:4352
	v_add_f32_e32 v254, v137, v254
	v_exp_f32_e32 v139, v139
	v_sub_f32_e32 v140, v140, v190
	v_add_f32_e32 v254, v138, v254
	s_waitcnt lgkmcnt(6)
	v_mfma_f32_32x32x16_bf16 v[64:79], v[238:241], v[242:245], v[64:79]
	ds_read_b64_tr_b16 v[238:239], v221 offset:256
	ds_read_b64_tr_b16 v[240:241], v221 offset:4352
	v_exp_f32_e32 v140, v140
	v_sub_f32_e32 v141, v141, v190
	v_add_f32_e32 v254, v139, v254
	v_exp_f32_e32 v141, v141
	s_waitcnt lgkmcnt(6)
	v_mfma_f32_32x32x16_bf16 v[48:63], v[206:209], v[242:245], v[48:63]
	ds_read_b64_tr_b16 v[206:207], v205 offset:8192
	ds_read_b64_tr_b16 v[208:209], v205 offset:12288
	v_sub_f32_e32 v142, v142, v190
	v_add_f32_e32 v254, v140, v254
	v_exp_f32_e32 v142, v142
	v_sub_f32_e32 v143, v143, v190
	s_waitcnt lgkmcnt(6)
	v_mfma_f32_32x32x16_bf16 v[32:47], v[210:213], v[242:245], v[32:47]
	ds_read_b64_tr_b16 v[210:211], v218 offset:8192
	ds_read_b64_tr_b16 v[212:213], v218 offset:12288
	v_add_f32_e32 v254, v141, v254
	v_exp_f32_e32 v143, v143
	v_add_f32_e32 v254, v142, v254
	v_add_f32_e32 v254, v143, v254
	s_waitcnt lgkmcnt(6)
	v_mfma_f32_32x32x16_bf16 v[16:31], v[214:217], v[242:245], v[16:31]
	ds_read_b64_tr_b16 v[214:215], v219 offset:8192
	ds_read_b64_tr_b16 v[216:217], v219 offset:12288
	v_cvt_pk_bf16_f32 v250, v136, v137
	v_cvt_pk_bf16_f32 v251, v138, v139
	v_cvt_pk_bf16_f32 v252, v140, v141
	v_cvt_pk_bf16_f32 v253, v142, v143
	v_add_f32_e32 v195, v195, v254
	s_waitcnt lgkmcnt(6)
	v_mfma_f32_32x32x16_bf16 v[0:15], v[238:241], v[242:245], v[0:15]
	ds_read_b64_tr_b16 v[238:239], v221 offset:8192
	ds_read_b64_tr_b16 v[240:241], v221 offset:12288
	ds_read_b64_tr_b16 v[128:129], v205 offset:8448
	ds_read_b64_tr_b16 v[130:131], v205 offset:12544
	s_waitcnt lgkmcnt(8)
	v_mfma_f32_32x32x16_bf16 v[112:127], v[206:209], v[250:253], v[112:127]
	ds_read_b64_tr_b16 v[206:207], v218 offset:8448
	ds_read_b64_tr_b16 v[208:209], v218 offset:12544
	v_max3_f32 v246, v222, v223, v224
	v_max3_f32 v247, v225, v226, v227
	v_max3_f32 v246, v246, v228, v229
	v_max3_f32 v247, v247, v230, v231
	v_max3_f32 v246, v246, v232, v233
	s_waitcnt lgkmcnt(8)
	v_mfma_f32_32x32x16_bf16 v[96:111], v[210:213], v[250:253], v[96:111]
	ds_read_b64_tr_b16 v[210:211], v219 offset:8448
	ds_read_b64_tr_b16 v[212:213], v219 offset:12544
	v_max3_f32 v247, v247, v234, v235
	v_max3_f32 v246, v246, v236, v237
	v_max_f32_e32 v246, v246, v247
	v_mov_b32_e32 v247, v246
	v_add_f32_e32 v249, 0x41000000, v190
	s_waitcnt lgkmcnt(8)
	v_mfma_f32_32x32x16_bf16 v[80:95], v[214:217], v[250:253], v[80:95]
	ds_read_b64_tr_b16 v[214:215], v221 offset:8448
	ds_read_b64_tr_b16 v[216:217], v221 offset:12544
	s_nop 1
	v_permlane32_swap_b32_e32 v246, v247
	v_max_f32_e32 v246, v246, v247
	v_cmp_gt_f32_e32 vcc, v246, v249
	s_cbranch_vccnz .Latt_rs1_7s2
	s_waitcnt lgkmcnt(8)
	v_mfma_f32_32x32x16_bf16 v[64:79], v[238:241], v[250:253], v[64:79]
	ds_read_b64_tr_b16 v[238:239], v205 offset:16384
	ds_read_b64_tr_b16 v[240:241], v205 offset:20480
	v_sub_f32_e32 v222, v222, v190
	v_exp_f32_e32 v222, v222
	v_sub_f32_e32 v223, v223, v190
	v_exp_f32_e32 v223, v223
	v_sub_f32_e32 v224, v224, v190
	v_add_f32_e32 v254, 0, v222
	s_waitcnt lgkmcnt(8)
	v_mfma_f32_32x32x16_bf16 v[48:63], v[128:131], v[250:253], v[48:63]
	ds_read_b64_tr_b16 v[128:129], v218 offset:16384
	ds_read_b64_tr_b16 v[130:131], v218 offset:20480
	v_exp_f32_e32 v224, v224
	v_sub_f32_e32 v225, v225, v190
	v_add_f32_e32 v254, v223, v254
	v_exp_f32_e32 v225, v225
	v_sub_f32_e32 v226, v226, v190
	v_add_f32_e32 v254, v224, v254
	s_waitcnt lgkmcnt(8)
	v_mfma_f32_32x32x16_bf16 v[32:47], v[206:209], v[250:253], v[32:47]
	ds_read_b64_tr_b16 v[206:207], v219 offset:16384
	ds_read_b64_tr_b16 v[208:209], v219 offset:20480
	v_exp_f32_e32 v226, v226
	v_sub_f32_e32 v227, v227, v190
	v_add_f32_e32 v254, v225, v254
	v_exp_f32_e32 v227, v227
	v_sub_f32_e32 v228, v228, v190
	s_waitcnt lgkmcnt(8)
	v_mfma_f32_32x32x16_bf16 v[16:31], v[210:213], v[250:253], v[16:31]
	ds_read_b64_tr_b16 v[210:211], v221 offset:16384
	ds_read_b64_tr_b16 v[212:213], v221 offset:20480
	v_add_f32_e32 v254, v226, v254
	v_exp_f32_e32 v228, v228
	v_sub_f32_e32 v229, v229, v190
	v_add_f32_e32 v254, v227, v254
	v_exp_f32_e32 v229, v229
	s_waitcnt lgkmcnt(8)
	v_mfma_f32_32x32x16_bf16 v[0:15], v[214:217], v[250:253], v[0:15]
	ds_read_b64_tr_b16 v[214:215], v205 offset:16640
	ds_read_b64_tr_b16 v[216:217], v205 offset:20736
	s_nop 0
	v_cvt_pk_bf16_f32 v242, v222, v223
	v_cvt_pk_bf16_f32 v243, v224, v225
	v_cvt_pk_bf16_f32 v244, v226, v227
	v_cvt_pk_bf16_f32 v245, v228, v229
	s_nop 1
	s_waitcnt lgkmcnt(8)
	v_mfma_f32_32x32x16_bf16 v[112:127], v[238:241], v[242:245], v[112:127]
	ds_read_b64_tr_b16 v[238:239], v218 offset:16640
	ds_read_b64_tr_b16 v[240:241], v218 offset:20736
	v_sub_f32_e32 v230, v230, v190
	v_add_f32_e32 v254, v228, v254
	v_exp_f32_e32 v230, v230
	v_sub_f32_e32 v231, v231, v190
	v_add_f32_e32 v254, v229, v254
	s_waitcnt lgkmcnt(8)
	v_mfma_f32_32x32x16_bf16 v[96:111], v[128:131], v[242:245], v[96:111]
	ds_read_b64_tr_b16 v[128:129], v219 offset:16640
	ds_read_b64_tr_b16 v[130:131], v219 offset:20736
	v_exp_f32_e32 v231, v231
	v_sub_f32_e32 v232, v232, v190
	v_add_f32_e32 v254, v230, v254
	v_exp_f32_e32 v232, v232
	v_sub_f32_e32 v233, v233, v190
	s_waitcnt lgkmcnt(8)
	v_mfma_f32_32x32x16_bf16 v[80:95], v[206:209], v[242:245], v[80:95]
	ds_read_b64_tr_b16 v[206:207], v221 offset:16640
	ds_read_b64_tr_b16 v[208:209], v221 offset:20736
	v_add_f32_e32 v254, v231, v254
	v_exp_f32_e32 v233, v233
	v_sub_f32_e32 v234, v234, v190
	v_add_f32_e32 v254, v232, v254
	s_waitcnt lgkmcnt(8)
	v_mfma_f32_32x32x16_bf16 v[64:79], v[210:213], v[242:245], v[64:79]
	ds_read_b64_tr_b16 v[210:211], v205 offset:24576
	ds_read_b64_tr_b16 v[212:213], v205 offset:28672
	v_exp_f32_e32 v234, v234
	v_sub_f32_e32 v235, v235, v190
	v_add_f32_e32 v254, v233, v254
	v_exp_f32_e32 v235, v235
	s_waitcnt lgkmcnt(8)
	v_mfma_f32_32x32x16_bf16 v[48:63], v[214:217], v[242:245], v[48:63]
	ds_read_b64_tr_b16 v[214:215], v218 offset:24576
	ds_read_b64_tr_b16 v[216:217], v218 offset:28672
	v_sub_f32_e32 v236, v236, v190
	v_add_f32_e32 v254, v234, v254
	v_exp_f32_e32 v236, v236
	v_sub_f32_e32 v237, v237, v190
	s_waitcnt lgkmcnt(8)
	v_mfma_f32_32x32x16_bf16 v[32:47], v[238:241], v[242:245], v[32:47]
	ds_read_b64_tr_b16 v[238:239], v219 offset:24576
	ds_read_b64_tr_b16 v[240:241], v219 offset:28672
	v_add_f32_e32 v254, v235, v254
	v_exp_f32_e32 v237, v237
	v_add_f32_e32 v254, v236, v254
	v_add_f32_e32 v254, v237, v254
	s_waitcnt lgkmcnt(8)
	v_mfma_f32_32x32x16_bf16 v[16:31], v[128:131], v[242:245], v[16:31]
	ds_read_b64_tr_b16 v[128:129], v221 offset:24576
	ds_read_b64_tr_b16 v[130:131], v221 offset:28672
	v_cvt_pk_bf16_f32 v250, v230, v231
	v_cvt_pk_bf16_f32 v251, v232, v233
	v_cvt_pk_bf16_f32 v252, v234, v235
	v_cvt_pk_bf16_f32 v253, v236, v237
	v_add_f32_e32 v195, v195, v254
	s_waitcnt lgkmcnt(8)
	v_mfma_f32_32x32x16_bf16 v[0:15], v[206:209], v[242:245], v[0:15]
	ds_read_b64_tr_b16 v[206:207], v205 offset:24832
	ds_read_b64_tr_b16 v[208:209], v205 offset:28928
	s_waitcnt lgkmcnt(8)
	v_mfma_f32_32x32x16_bf16 v[112:127], v[210:213], v[250:253], v[112:127]
	ds_read_b64_tr_b16 v[210:211], v218 offset:24832
	ds_read_b64_tr_b16 v[212:213], v218 offset:28928
	s_waitcnt lgkmcnt(8)
	v_mfma_f32_32x32x16_bf16 v[96:111], v[214:217], v[250:253], v[96:111]
	ds_read_b64_tr_b16 v[214:215], v219 offset:24832
	ds_read_b64_tr_b16 v[216:217], v219 offset:28928
	s_waitcnt lgkmcnt(8)
	v_mfma_f32_32x32x16_bf16 v[80:95], v[238:241], v[250:253], v[80:95]
	ds_read_b64_tr_b16 v[238:239], v221 offset:24832
	ds_read_b64_tr_b16 v[240:241], v221 offset:28928
	s_waitcnt lgkmcnt(8)
	v_mfma_f32_32x32x16_bf16 v[64:79], v[128:131], v[250:253], v[64:79]
	s_waitcnt lgkmcnt(6)
	v_mfma_f32_32x32x16_bf16 v[48:63], v[206:209], v[250:253], v[48:63]
	s_waitcnt lgkmcnt(4)
	v_mfma_f32_32x32x16_bf16 v[32:47], v[210:213], v[250:253], v[32:47]
	s_waitcnt lgkmcnt(2)
	v_mfma_f32_32x32x16_bf16 v[16:31], v[214:217], v[250:253], v[16:31]
	s_waitcnt lgkmcnt(0)
	v_mfma_f32_32x32x16_bf16 v[0:15], v[238:241], v[250:253], v[0:15]
	ds_read_b128 v[206:209], v196
	ds_read_b128 v[210:213], v197
	ds_read_b128 v[214:217], v198
	ds_read_b128 v[238:241], v199
	ds_read_b128 v[242:245], v200
	ds_read_b128 v[250:253], v201
	ds_read_b128 v[222:225], v202
	ds_read_b128 v[226:229], v203
	s_waitcnt vmcnt(0)
	s_add_i32 s8, s11, 1
	s_cmp_lg_u32 s11, 2
	s_cselect_b32 s11, s8, 0
	s_add_i32 s14, s14, 64
	s_add_u32 s22, s22, 0x100000
	s_addc_u32 s23, s23, 0
	s_add_i32 s10, s10, 1
	s_add_i32 s100, s14, 63
	s_cmp_le_i32 s100, s68
	s_cbranch_scc0 .Latt_latchb_7
	s_cmp_ge_u32 s10, s66
	s_cselect_b64 s[8:9], -1, 0
	v_mov_b32_e32 v204, v176
	s_barrier
	s_branch .Latt_cont_7s0
.Latt_rs1_7s2:
	s_waitcnt lgkmcnt(8)
	v_mfma_f32_32x32x16_bf16 v[64:79], v[238:241], v[250:253], v[64:79]
	ds_read_b64_tr_b16 v[238:239], v205 offset:16384
	ds_read_b64_tr_b16 v[240:241], v205 offset:20480
	s_waitcnt lgkmcnt(8)
	v_mfma_f32_32x32x16_bf16 v[48:63], v[128:131], v[250:253], v[48:63]
	ds_read_b64_tr_b16 v[128:129], v218 offset:16384
	ds_read_b64_tr_b16 v[130:131], v218 offset:20480
	s_waitcnt lgkmcnt(8)
	v_mfma_f32_32x32x16_bf16 v[32:47], v[206:209], v[250:253], v[32:47]
	ds_read_b64_tr_b16 v[206:207], v219 offset:16384
	ds_read_b64_tr_b16 v[208:209], v219 offset:20480
	s_waitcnt lgkmcnt(8)
	v_mfma_f32_32x32x16_bf16 v[16:31], v[210:213], v[250:253], v[16:31]
	ds_read_b64_tr_b16 v[210:211], v221 offset:16384
	ds_read_b64_tr_b16 v[212:213], v221 offset:20480
	s_waitcnt lgkmcnt(8)
	v_mfma_f32_32x32x16_bf16 v[0:15], v[214:217], v[250:253], v[0:15]
	ds_read_b64_tr_b16 v[214:215], v205 offset:16640
	ds_read_b64_tr_b16 v[216:217], v205 offset:20736
	s_nop 11
	v_max_f32_e32 v246, v190, v246
	v_sub_f32_e32 v190, v190, v246
	v_exp_f32_e32 v190, v190
	s_nop 0
	v_pk_mul_f32 v[126:127], v[126:127], v[190:191] op_sel_hi:[1,0]
	v_pk_mul_f32 v[124:125], v[124:125], v[190:191] op_sel_hi:[1,0]
	v_pk_mul_f32 v[122:123], v[122:123], v[190:191] op_sel_hi:[1,0]
	v_pk_mul_f32 v[120:121], v[120:121], v[190:191] op_sel_hi:[1,0]
	v_pk_mul_f32 v[118:119], v[118:119], v[190:191] op_sel_hi:[1,0]
	v_pk_mul_f32 v[116:117], v[116:117], v[190:191] op_sel_hi:[1,0]
	v_pk_mul_f32 v[114:115], v[114:115], v[190:191] op_sel_hi:[1,0]
	v_pk_mul_f32 v[112:113], v[112:113], v[190:191] op_sel_hi:[1,0]
	v_pk_mul_f32 v[110:111], v[110:111], v[190:191] op_sel_hi:[1,0]
	v_pk_mul_f32 v[108:109], v[108:109], v[190:191] op_sel_hi:[1,0]
	v_pk_mul_f32 v[106:107], v[106:107], v[190:191] op_sel_hi:[1,0]
	v_pk_mul_f32 v[104:105], v[104:105], v[190:191] op_sel_hi:[1,0]
	v_pk_mul_f32 v[102:103], v[102:103], v[190:191] op_sel_hi:[1,0]
	v_pk_mul_f32 v[100:101], v[100:101], v[190:191] op_sel_hi:[1,0]
	v_pk_mul_f32 v[98:99], v[98:99], v[190:191] op_sel_hi:[1,0]
	v_pk_mul_f32 v[96:97], v[96:97], v[190:191] op_sel_hi:[1,0]
	v_pk_mul_f32 v[94:95], v[94:95], v[190:191] op_sel_hi:[1,0]
	v_pk_mul_f32 v[92:93], v[92:93], v[190:191] op_sel_hi:[1,0]
	v_pk_mul_f32 v[90:91], v[90:91], v[190:191] op_sel_hi:[1,0]
	v_pk_mul_f32 v[88:89], v[88:89], v[190:191] op_sel_hi:[1,0]
	v_pk_mul_f32 v[86:87], v[86:87], v[190:191] op_sel_hi:[1,0]
	v_pk_mul_f32 v[84:85], v[84:85], v[190:191] op_sel_hi:[1,0]
	v_pk_mul_f32 v[82:83], v[82:83], v[190:191] op_sel_hi:[1,0]
	v_pk_mul_f32 v[80:81], v[80:81], v[190:191] op_sel_hi:[1,0]
	v_pk_mul_f32 v[78:79], v[78:79], v[190:191] op_sel_hi:[1,0]
	v_pk_mul_f32 v[76:77], v[76:77], v[190:191] op_sel_hi:[1,0]
	v_pk_mul_f32 v[74:75], v[74:75], v[190:191] op_sel_hi:[1,0]
	v_pk_mul_f32 v[72:73], v[72:73], v[190:191] op_sel_hi:[1,0]
	v_pk_mul_f32 v[70:71], v[70:71], v[190:191] op_sel_hi:[1,0]
	v_pk_mul_f32 v[68:69], v[68:69], v[190:191] op_sel_hi:[1,0]
	v_pk_mul_f32 v[66:67], v[66:67], v[190:191] op_sel_hi:[1,0]
	v_pk_mul_f32 v[64:65], v[64:65], v[190:191] op_sel_hi:[1,0]
	v_pk_mul_f32 v[62:63], v[62:63], v[190:191] op_sel_hi:[1,0]
	v_pk_mul_f32 v[60:61], v[60:61], v[190:191] op_sel_hi:[1,0]
	v_pk_mul_f32 v[58:59], v[58:59], v[190:191] op_sel_hi:[1,0]
	v_pk_mul_f32 v[56:57], v[56:57], v[190:191] op_sel_hi:[1,0]
	v_pk_mul_f32 v[54:55], v[54:55], v[190:191] op_sel_hi:[1,0]
	v_pk_mul_f32 v[52:53], v[52:53], v[190:191] op_sel_hi:[1,0]
	v_pk_mul_f32 v[50:51], v[50:51], v[190:191] op_sel_hi:[1,0]
	v_pk_mul_f32 v[48:49], v[48:49], v[190:191] op_sel_hi:[1,0]
	v_pk_mul_f32 v[46:47], v[46:47], v[190:191] op_sel_hi:[1,0]
	v_pk_mul_f32 v[44:45], v[44:45], v[190:191] op_sel_hi:[1,0]
	v_pk_mul_f32 v[42:43], v[42:43], v[190:191] op_sel_hi:[1,0]
	v_pk_mul_f32 v[40:41], v[40:41], v[190:191] op_sel_hi:[1,0]
	v_pk_mul_f32 v[38:39], v[38:39], v[190:191] op_sel_hi:[1,0]
	v_pk_mul_f32 v[36:37], v[36:37], v[190:191] op_sel_hi:[1,0]
	v_pk_mul_f32 v[34:35], v[34:35], v[190:191] op_sel_hi:[1,0]
	v_pk_mul_f32 v[32:33], v[32:33], v[190:191] op_sel_hi:[1,0]
	v_pk_mul_f32 v[30:31], v[30:31], v[190:191] op_sel_hi:[1,0]
	v_pk_mul_f32 v[28:29], v[28:29], v[190:191] op_sel_hi:[1,0]
	v_pk_mul_f32 v[26:27], v[26:27], v[190:191] op_sel_hi:[1,0]
	v_pk_mul_f32 v[24:25], v[24:25], v[190:191] op_sel_hi:[1,0]
	v_pk_mul_f32 v[22:23], v[22:23], v[190:191] op_sel_hi:[1,0]
	v_pk_mul_f32 v[20:21], v[20:21], v[190:191] op_sel_hi:[1,0]
	v_pk_mul_f32 v[18:19], v[18:19], v[190:191] op_sel_hi:[1,0]
	v_pk_mul_f32 v[16:17], v[16:17], v[190:191] op_sel_hi:[1,0]
	v_pk_mul_f32 v[14:15], v[14:15], v[190:191] op_sel_hi:[1,0]
	v_pk_mul_f32 v[12:13], v[12:13], v[190:191] op_sel_hi:[1,0]
	v_pk_mul_f32 v[10:11], v[10:11], v[190:191] op_sel_hi:[1,0]
	v_pk_mul_f32 v[8:9], v[8:9], v[190:191] op_sel_hi:[1,0]
	v_pk_mul_f32 v[6:7], v[6:7], v[190:191] op_sel_hi:[1,0]
	v_pk_mul_f32 v[4:5], v[4:5], v[190:191] op_sel_hi:[1,0]
	v_pk_mul_f32 v[2:3], v[2:3], v[190:191] op_sel_hi:[1,0]
	v_pk_mul_f32 v[0:1], v[0:1], v[190:191] op_sel_hi:[1,0]
	v_mul_f32_e32 v195, v195, v190
	v_mov_b32_e32 v190, v246
	v_sub_f32_e32 v222, v222, v190
	v_exp_f32_e32 v222, v222
	v_sub_f32_e32 v223, v223, v190
	v_exp_f32_e32 v223, v223
	v_sub_f32_e32 v224, v224, v190
	v_add_f32_e32 v254, 0, v222
	v_exp_f32_e32 v224, v224
	v_sub_f32_e32 v225, v225, v190
	v_add_f32_e32 v254, v223, v254
	v_exp_f32_e32 v225, v225
	v_sub_f32_e32 v226, v226, v190
	v_add_f32_e32 v254, v224, v254
	v_exp_f32_e32 v226, v226
	v_sub_f32_e32 v227, v227, v190
	v_add_f32_e32 v254, v225, v254
	v_exp_f32_e32 v227, v227
	v_sub_f32_e32 v228, v228, v190
	v_add_f32_e32 v254, v226, v254
	v_exp_f32_e32 v228, v228
	v_sub_f32_e32 v229, v229, v190
	v_add_f32_e32 v254, v227, v254
	v_exp_f32_e32 v229, v229
	v_sub_f32_e32 v230, v230, v190
	v_add_f32_e32 v254, v228, v254
	v_exp_f32_e32 v230, v230
	v_sub_f32_e32 v231, v231, v190
	v_add_f32_e32 v254, v229, v254
	v_exp_f32_e32 v231, v231
	v_sub_f32_e32 v232, v232, v190
	v_add_f32_e32 v254, v230, v254
	v_exp_f32_e32 v232, v232
	v_sub_f32_e32 v233, v233, v190
	v_add_f32_e32 v254, v231, v254
	v_exp_f32_e32 v233, v233
	v_sub_f32_e32 v234, v234, v190
	v_add_f32_e32 v254, v232, v254
	v_exp_f32_e32 v234, v234
	v_sub_f32_e32 v235, v235, v190
	v_add_f32_e32 v254, v233, v254
	v_exp_f32_e32 v235, v235
	v_sub_f32_e32 v236, v236, v190
	v_add_f32_e32 v254, v234, v254
	v_exp_f32_e32 v236, v236
	v_sub_f32_e32 v237, v237, v190
	v_add_f32_e32 v254, v235, v254
	v_exp_f32_e32 v237, v237
	v_add_f32_e32 v254, v236, v254
	v_add_f32_e32 v254, v237, v254
	v_cvt_pk_bf16_f32 v242, v222, v223
	v_cvt_pk_bf16_f32 v243, v224, v225
	v_cvt_pk_bf16_f32 v244, v226, v227
	v_cvt_pk_bf16_f32 v245, v228, v229
	v_cvt_pk_bf16_f32 v250, v230, v231
	v_cvt_pk_bf16_f32 v251, v232, v233
	v_cvt_pk_bf16_f32 v252, v234, v235
	v_cvt_pk_bf16_f32 v253, v236, v237
	v_add_f32_e32 v195, v195, v254
	s_nop 1
	s_waitcnt lgkmcnt(8)
	v_mfma_f32_32x32x16_bf16 v[112:127], v[238:241], v[242:245], v[112:127]
	ds_read_b64_tr_b16 v[238:239], v218 offset:16640
	ds_read_b64_tr_b16 v[240:241], v218 offset:20736
	s_waitcnt lgkmcnt(8)
	v_mfma_f32_32x32x16_bf16 v[96:111], v[128:131], v[242:245], v[96:111]
	ds_read_b64_tr_b16 v[222:223], v219 offset:16640
	ds_read_b64_tr_b16 v[224:225], v219 offset:20736
	s_waitcnt lgkmcnt(8)
	v_mfma_f32_32x32x16_bf16 v[80:95], v[206:209], v[242:245], v[80:95]
	ds_read_b64_tr_b16 v[206:207], v221 offset:16640
	ds_read_b64_tr_b16 v[208:209], v221 offset:20736
	s_waitcnt lgkmcnt(8)
	v_mfma_f32_32x32x16_bf16 v[64:79], v[210:213], v[242:245], v[64:79]
	ds_read_b64_tr_b16 v[210:211], v205 offset:24576
	ds_read_b64_tr_b16 v[212:213], v205 offset:28672
	s_waitcnt lgkmcnt(8)
	v_mfma_f32_32x32x16_bf16 v[48:63], v[214:217], v[242:245], v[48:63]
	ds_read_b64_tr_b16 v[214:215], v218 offset:24576
	ds_read_b64_tr_b16 v[216:217], v218 offset:28672
	s_waitcnt lgkmcnt(8)
	v_mfma_f32_32x32x16_bf16 v[32:47], v[238:241], v[242:245], v[32:47]
	ds_read_b64_tr_b16 v[238:239], v219 offset:24576
	ds_read_b64_tr_b16 v[240:241], v219 offset:28672
	s_waitcnt lgkmcnt(8)
	v_mfma_f32_32x32x16_bf16 v[16:31], v[222:225], v[242:245], v[16:31]
	ds_read_b64_tr_b16 v[222:223], v221 offset:24576
	ds_read_b64_tr_b16 v[224:225], v221 offset:28672
	s_waitcnt lgkmcnt(8)
	v_mfma_f32_32x32x16_bf16 v[0:15], v[206:209], v[242:245], v[0:15]
	ds_read_b64_tr_b16 v[206:207], v205 offset:24832
	ds_read_b64_tr_b16 v[208:209], v205 offset:28928
	s_waitcnt lgkmcnt(8)
	v_mfma_f32_32x32x16_bf16 v[112:127], v[210:213], v[250:253], v[112:127]
	ds_read_b64_tr_b16 v[210:211], v218 offset:24832
	ds_read_b64_tr_b16 v[212:213], v218 offset:28928
	s_waitcnt lgkmcnt(8)
	v_mfma_f32_32x32x16_bf16 v[96:111], v[214:217], v[250:253], v[96:111]
	ds_read_b64_tr_b16 v[214:215], v219 offset:24832
	ds_read_b64_tr_b16 v[216:217], v219 offset:28928
	s_waitcnt lgkmcnt(8)
	v_mfma_f32_32x32x16_bf16 v[80:95], v[238:241], v[250:253], v[80:95]
	ds_read_b64_tr_b16 v[238:239], v221 offset:24832
	ds_read_b64_tr_b16 v[240:241], v221 offset:28928
	s_waitcnt lgkmcnt(8)
	v_mfma_f32_32x32x16_bf16 v[64:79], v[222:225], v[250:253], v[64:79]
	s_waitcnt lgkmcnt(6)
	v_mfma_f32_32x32x16_bf16 v[48:63], v[206:209], v[250:253], v[48:63]
	s_waitcnt lgkmcnt(4)
	v_mfma_f32_32x32x16_bf16 v[32:47], v[210:213], v[250:253], v[32:47]
	s_waitcnt lgkmcnt(2)
	v_mfma_f32_32x32x16_bf16 v[16:31], v[214:217], v[250:253], v[16:31]
	s_waitcnt lgkmcnt(0)
	v_mfma_f32_32x32x16_bf16 v[0:15], v[238:241], v[250:253], v[0:15]
	ds_read_b128 v[206:209], v196
	ds_read_b128 v[210:213], v197
	ds_read_b128 v[214:217], v198
	ds_read_b128 v[238:241], v199
	ds_read_b128 v[242:245], v200
	ds_read_b128 v[250:253], v201
	ds_read_b128 v[222:225], v202
	ds_read_b128 v[226:229], v203
	s_waitcnt vmcnt(0)
	s_add_i32 s8, s11, 1
	s_cmp_lg_u32 s11, 2
	s_cselect_b32 s11, s8, 0
	s_add_i32 s14, s14, 64
	s_add_u32 s22, s22, 0x100000
	s_addc_u32 s23, s23, 0
	s_add_i32 s10, s10, 1
	s_add_i32 s100, s14, 63
	s_cmp_le_i32 s100, s68
	s_cbranch_scc0 .Latt_latchb_7
	s_cmp_ge_u32 s10, s66
	s_cselect_b64 s[8:9], -1, 0
	v_mov_b32_e32 v204, v176
	s_barrier
	s_branch .Latt_cont_7s0
